# placement: PEER act sub-phase moved 8 bytes (start at 60 mod 64), u- and v-phase placements kept
# baseline (speedup 1.0000x reference)
; #define LAS __attribute__((address_space(3)))
; __global__ void __launch_bounds__(NTHR, 2) k_main(Args a) {
;     ...
;             for (int it = 0; it < 8; ++it) {
;                 const int tl = it * 8 + wave, t = j * 64 + tl;
;                 const unsigned ew = *(const LAS unsigned*)(EL + tl * 128 + 2 * lane); const int e0 = (int)(ew & 0xffffu), e1 = (int)(ew >> 16);
;                 typedef int i2v __attribute__((ext_vector_type(2))); const i2v si = *(const LAS i2v*)(ACC + tl * 128 + 2 * lane);
;                 typedef float f2v __attribute__((ext_vector_type(2))); const f2v gt = *(const LAS f2v*)(GL + tl * 128 + 2 * lane); const float xs = XS[t];
;                 const int sx = ((const int*)(XS + T))[t];
;                 const float z0 = (float)(2 * si.x + sx) * SU[e0] * xs, z1 = (float)(2 * si.y + sx) * SU[e1] * xs;
;                 const float a0 = gt.x * gelu_as(z0) * SV[e0], a1 = gt.y * gelu_as(z1) * SV[e1];
.LBB0_674:
	s_nop 0
	s_nop 0
	s_ashr_i32 s41, s40, 31
	s_lshl_b64 s[10:11], s[40:41], 2
	s_add_u32 s14, s90, s10
	s_addc_u32 s15, s91, s11
	v_readlane_b32 s42, v235, 36
	v_readlane_b32 s43, v235, 37
	global_load_dword v78, v83, s[38:39] sc1
	v_add_u32_e32 v74, 0x16000, v91
	v_mov_b32_e32 v77, 3
	ds_read_b32 v18, v92
	ds_read_b32 v19, v92 offset:2048
	ds_read_b32 v20, v92 offset:4096
	ds_read_b32 v21, v92 offset:6144
	ds_read_b32 v22, v92 offset:8192
	ds_read_b32 v23, v92 offset:10240
	ds_read_b32 v24, v92 offset:12288
	ds_read_b32 v25, v92 offset:14336
	ds_read_b64 v[26:27], v91
	ds_read_b64 v[42:43], v74
	ds_read_b64 v[28:29], v91 offset:4096
	ds_read_b64 v[44:45], v74 offset:4096
	ds_read_b64 v[30:31], v91 offset:8192
	ds_read_b64 v[46:47], v74 offset:8192
	ds_read_b64 v[32:33], v91 offset:12288
	ds_read_b64 v[48:49], v74 offset:12288
	ds_read_b64 v[34:35], v91 offset:16384
	ds_read_b64 v[50:51], v74 offset:16384
	ds_read_b64 v[36:37], v91 offset:20480
	ds_read_b64 v[52:53], v74 offset:20480
	ds_read_b64 v[38:39], v91 offset:24576
	ds_read_b64 v[54:55], v74 offset:24576
	ds_read_b64 v[40:41], v91 offset:28672
	ds_read_b64 v[56:57], v74 offset:28672
	global_load_dword v58, v109, s[14:15]
	global_load_dword v66, v108, s[14:15]
	global_load_dword v59, v109, s[14:15] offset:32
	global_load_dword v67, v108, s[14:15] offset:32
	global_load_dword v60, v109, s[14:15] offset:64
	global_load_dword v68, v108, s[14:15] offset:64
	global_load_dword v61, v109, s[14:15] offset:96
	global_load_dword v69, v108, s[14:15] offset:96
	global_load_dword v62, v109, s[14:15] offset:128
	global_load_dword v70, v108, s[14:15] offset:128
	global_load_dword v63, v109, s[14:15] offset:160
	global_load_dword v71, v108, s[14:15] offset:160
	global_load_dword v64, v109, s[14:15] offset:192
	global_load_dword v72, v108, s[14:15] offset:192
	global_load_dword v65, v109, s[14:15] offset:224
	global_load_dword v73, v108, s[14:15] offset:224
	s_waitcnt lgkmcnt(0)
	v_lshlrev_b32_sdwa v75, v77, v18 dst_sel:DWORD dst_unused:UNUSED_PAD src0_sel:DWORD src1_sel:WORD_0
	v_lshlrev_b32_sdwa v76, v77, v18 dst_sel:DWORD dst_unused:UNUSED_PAD src0_sel:DWORD src1_sel:WORD_1
	s_nop 1
	global_load_dwordx2 v[122:123], v75, s[42:43]
	global_load_dwordx2 v[138:139], v76, s[42:43]
	v_lshlrev_b32_sdwa v75, v77, v19 dst_sel:DWORD dst_unused:UNUSED_PAD src0_sel:DWORD src1_sel:WORD_0
	v_lshlrev_b32_sdwa v76, v77, v19 dst_sel:DWORD dst_unused:UNUSED_PAD src0_sel:DWORD src1_sel:WORD_1
	s_nop 1
	global_load_dwordx2 v[124:125], v75, s[42:43]
	global_load_dwordx2 v[140:141], v76, s[42:43]
	v_lshlrev_b32_sdwa v75, v77, v20 dst_sel:DWORD dst_unused:UNUSED_PAD src0_sel:DWORD src1_sel:WORD_0
	v_lshlrev_b32_sdwa v76, v77, v20 dst_sel:DWORD dst_unused:UNUSED_PAD src0_sel:DWORD src1_sel:WORD_1
	s_nop 1
	global_load_dwordx2 v[126:127], v75, s[42:43]
	global_load_dwordx2 v[142:143], v76, s[42:43]
	v_lshlrev_b32_sdwa v75, v77, v21 dst_sel:DWORD dst_unused:UNUSED_PAD src0_sel:DWORD src1_sel:WORD_0
	v_lshlrev_b32_sdwa v76, v77, v21 dst_sel:DWORD dst_unused:UNUSED_PAD src0_sel:DWORD src1_sel:WORD_1
	s_nop 1
	global_load_dwordx2 v[128:129], v75, s[42:43]
	global_load_dwordx2 v[144:145], v76, s[42:43]
	v_lshlrev_b32_sdwa v75, v77, v22 dst_sel:DWORD dst_unused:UNUSED_PAD src0_sel:DWORD src1_sel:WORD_0
	v_lshlrev_b32_sdwa v76, v77, v22 dst_sel:DWORD dst_unused:UNUSED_PAD src0_sel:DWORD src1_sel:WORD_1
	s_nop 1
	global_load_dwordx2 v[130:131], v75, s[42:43]
	global_load_dwordx2 v[146:147], v76, s[42:43]
	v_lshlrev_b32_sdwa v75, v77, v23 dst_sel:DWORD dst_unused:UNUSED_PAD src0_sel:DWORD src1_sel:WORD_0
	v_lshlrev_b32_sdwa v76, v77, v23 dst_sel:DWORD dst_unused:UNUSED_PAD src0_sel:DWORD src1_sel:WORD_1
	s_nop 1
	global_load_dwordx2 v[132:133], v75, s[42:43]
	global_load_dwordx2 v[148:149], v76, s[42:43]
	v_lshlrev_b32_sdwa v75, v77, v24 dst_sel:DWORD dst_unused:UNUSED_PAD src0_sel:DWORD src1_sel:WORD_0
	v_lshlrev_b32_sdwa v76, v77, v24 dst_sel:DWORD dst_unused:UNUSED_PAD src0_sel:DWORD src1_sel:WORD_1
	s_nop 1
	global_load_dwordx2 v[134:135], v75, s[42:43]
	global_load_dwordx2 v[150:151], v76, s[42:43]
	v_lshlrev_b32_sdwa v75, v77, v25 dst_sel:DWORD dst_unused:UNUSED_PAD src0_sel:DWORD src1_sel:WORD_0
	v_lshlrev_b32_sdwa v76, v77, v25 dst_sel:DWORD dst_unused:UNUSED_PAD src0_sel:DWORD src1_sel:WORD_1
	s_nop 1
	global_load_dwordx2 v[136:137], v75, s[42:43]
	global_load_dwordx2 v[152:153], v76, s[42:43]
	s_waitcnt vmcnt(14)
; #define LAS __attribute__((address_space(3)))
; __device__ __forceinline__ float gelu_as(float z) {
;     const float ax = fabsf(z) * 0.70710678118654752f, t = __builtin_amdgcn_rcpf(1.f + 0.3275911f * ax);
;     const float poly = t * (0.254829592f + t * (-0.284496736f + t * (1.421413741f + t * (-1.453152027f + t * 1.061405429f))));
;     const float er = 1.f - poly * __expf(-ax * ax);
;     return 0.5f * z * (1.f + copysignf(er, z));
; }
; __global__ void __launch_bounds__(NTHR, 2) k_main(Args a) {
;     ...
;             for (int it = 0; it < 8; ++it) {
;                 const int tl = it * 8 + wave, t = j * 64 + tl;
;                 const unsigned ew = *(const LAS unsigned*)(EL + tl * 128 + 2 * lane); const int e0 = (int)(ew & 0xffffu), e1 = (int)(ew >> 16);
;                 typedef int i2v __attribute__((ext_vector_type(2))); const i2v si = *(const LAS i2v*)(ACC + tl * 128 + 2 * lane);
;                 typedef float f2v __attribute__((ext_vector_type(2))); const f2v gt = *(const LAS f2v*)(GL + tl * 128 + 2 * lane); const float xs = XS[t];
;                 const int sx = ((const int*)(XS + T))[t];
;                 const float z0 = (float)(2 * si.x + sx) * SU[e0] * xs, z1 = (float)(2 * si.y + sx) * SU[e1] * xs;
;                 const float a0 = gt.x * gelu_as(z0) * SV[e0], a1 = gt.y * gelu_as(z1) * SV[e1];
;                 const float mx = wave_max_dpp(fmaxf(fabsf(a0), fabsf(a1)));
;                 const float sc = mx > 0.f ? mx * (1.f / 119.f) : 1.f, inv = 1.f / sc;
;                 const int q0 = (int)rintf(a0 * inv), q1 = (int)rintf(a1 * inv);
;                 *(LAS unsigned short*)(AL + tl * 128 + 2 * lane) = (unsigned short)((q0 & 255) | ((q1 & 255) << 8));
;                 const int qs = wave_sum_dpp_i(q0 + q1);
;                 if (lane == 0) { ASC[tl] = sc; SAL[tl] = qs; }
	v_lshl_add_u32 v154, v26, 1, v58
	v_lshl_add_u32 v155, v27, 1, v58
	v_cvt_f32_i32_e32 v154, v154
	v_cvt_f32_i32_e32 v155, v155
	v_mul_f32_e32 v154, v122, v154
	v_mul_f32_e32 v155, v138, v155
	v_mul_f32_e32 v154, v66, v154
	v_mul_f32_e32 v155, v66, v155
	v_mul_f32_e64 v156, |v154|, s82
	v_mul_f32_e64 v157, |v155|, s82
	v_fma_f32 v158, v156, s83, 1.0
	v_fma_f32 v159, v157, s83, 1.0
	v_rcp_f32_e32 v158, v158
	v_rcp_f32_e32 v159, v159
	v_mul_f32_e64 v156, v156, -v156
	v_mul_f32_e64 v157, v157, -v157
	v_mul_f32_e32 v156, 0x3fb8aa3b, v156
	v_mul_f32_e32 v157, 0x3fb8aa3b, v157
	v_fmamk_f32 v160, v158, 0x3f87dc22, v110
	v_fmamk_f32 v161, v159, 0x3f87dc22, v110
	v_exp_f32_e32 v156, v156
	v_exp_f32_e32 v157, v157
	v_fmaak_f32 v160, v158, v160, 0x3fb5f0e3
	v_fmaak_f32 v161, v159, v161, 0x3fb5f0e3
	v_fmaak_f32 v160, v158, v160, 0xbe91a98e
	v_fmaak_f32 v161, v159, v161, 0xbe91a98e
	v_fmaak_f32 v160, v158, v160, 0x3e827906
	v_fmaak_f32 v161, v159, v161, 0x3e827906
	v_mul_f32_e32 v158, v158, v160
	v_mul_f32_e32 v159, v159, v161
	v_fma_f32 v156, -v156, v158, 1.0
	v_fma_f32 v157, -v157, v159, 1.0
	v_mul_f32_e32 v162, 0.5, v154
	v_mul_f32_e32 v163, 0.5, v155
	v_bfi_b32 v154, s84, v156, v154
	v_bfi_b32 v155, s84, v157, v155
	v_add_f32_e32 v154, 1.0, v154
	v_add_f32_e32 v155, 1.0, v155
	v_mul_f32_e32 v154, v162, v154
	v_mul_f32_e32 v155, v163, v155
	v_mul_f32_e32 v154, v42, v154
	v_mul_f32_e32 v155, v43, v155
	v_mul_f32_e32 v154, v123, v154
	v_mul_f32_e32 v155, v139, v155
	v_max_f32_e64 v164, |v154|, |v155|
	s_nop 1
	v_max_f32_dpp v164, v164, v164 quad_perm:[1,0,3,2] row_mask:0xf bank_mask:0xf
	s_nop 1
	v_max_f32_dpp v164, v164, v164 quad_perm:[2,3,0,1] row_mask:0xf bank_mask:0xf
	s_nop 1
	v_max_f32_dpp v164, v164, v164 row_half_mirror row_mask:0xf bank_mask:0xf
	s_nop 1
	v_max_f32_dpp v164, v164, v164 row_mirror row_mask:0xf bank_mask:0xf
	s_nop 1
	v_readlane_b32 s46, v164, 32
	v_readlane_b32 s47, v164, 48
	v_readlane_b32 s12, v164, 0
	v_readlane_b32 s13, v164, 16
	s_nop 1
	v_mov_b32_e32 v164, s47
	v_max_f32_e32 v164, s46, v164
	v_mov_b32_e32 v165, s13
	v_max3_f32 v164, s12, v165, v164
	v_mul_f32_e32 v165, 0x3c09ae41, v164
	v_cmp_lt_f32_e32 vcc, 0, v164
	s_nop 1
	v_cndmask_b32_e32 v164, 1.0, v165, vcc
	v_div_scale_f32 v166, s[12:13], v164, v164, 1.0
	v_rcp_f32_e32 v167, v166
	v_div_scale_f32 v168, vcc, 1.0, v164, 1.0
	v_fma_f32 v169, -v166, v167, 1.0
	v_fmac_f32_e32 v167, v169, v167
	v_mul_f32_e32 v169, v168, v167
	v_fma_f32 v170, -v166, v169, v168
	v_fmac_f32_e32 v169, v170, v167
	v_fma_f32 v166, -v166, v169, v168
	v_div_fmas_f32 v166, v166, v167, v169
	v_div_fixup_f32 v166, v166, v164, 1.0
	v_mul_f32_e32 v154, v166, v154
	v_mul_f32_e32 v155, v166, v155
	v_rndne_f32_e32 v154, v154
	v_rndne_f32_e32 v155, v155
	v_cvt_i32_f32_e32 v154, v154
	v_cvt_i32_f32_e32 v155, v155
	v_perm_b32 v167, v155, v154, s85
	v_add_u32_e32 v154, v154, v155
	ds_write_b16 v90, v167
	s_nop 1
	v_add_u32_dpp v154, v154, v154 quad_perm:[1,0,3,2] row_mask:0xf bank_mask:0xf bound_ctrl:1
	s_nop 1
	v_add_u32_dpp v154, v154, v154 quad_perm:[2,3,0,1] row_mask:0xf bank_mask:0xf bound_ctrl:1
	s_nop 1
	v_add_u32_dpp v154, v154, v154 row_half_mirror row_mask:0xf bank_mask:0xf bound_ctrl:1
	s_nop 1
	v_add_u32_dpp v154, v154, v154 row_mirror row_mask:0xf bank_mask:0xf bound_ctrl:1
	s_nop 1
	v_readlane_b32 s46, v154, 0
	v_readlane_b32 s47, v154, 16
	v_readlane_b32 s12, v154, 32
	v_readlane_b32 s13, v154, 48
	s_nop 1
	s_add_i32 s46, s47, s46
	s_add_i32 s46, s46, s12
	s_add_i32 s46, s46, s13
	s_mov_b32 s47, s67
	s_and_saveexec_b64 s[12:13], s[8:9]
	v_mov_b32_e32 v154, s47
	v_mov_b32_e32 v155, s46
	ds_write2st64_b32 v154, v164, v155 offset1:1
	s_or_b64 exec, exec, s[12:13]
	s_waitcnt vmcnt(12)
	v_lshl_add_u32 v154, v28, 1, v59
	v_lshl_add_u32 v155, v29, 1, v59
	v_cvt_f32_i32_e32 v154, v154
	v_cvt_f32_i32_e32 v155, v155
	v_mul_f32_e32 v154, v124, v154
	v_mul_f32_e32 v155, v140, v155
	v_mul_f32_e32 v154, v67, v154
	v_mul_f32_e32 v155, v67, v155
	v_mul_f32_e64 v156, |v154|, s82
	v_mul_f32_e64 v157, |v155|, s82
	v_fma_f32 v158, v156, s83, 1.0
	v_fma_f32 v159, v157, s83, 1.0
	v_rcp_f32_e32 v158, v158
	v_rcp_f32_e32 v159, v159
	v_mul_f32_e64 v156, v156, -v156
	v_mul_f32_e64 v157, v157, -v157
	v_mul_f32_e32 v156, 0x3fb8aa3b, v156
	v_mul_f32_e32 v157, 0x3fb8aa3b, v157
	v_fmamk_f32 v160, v158, 0x3f87dc22, v110
	v_fmamk_f32 v161, v159, 0x3f87dc22, v110
	v_exp_f32_e32 v156, v156
	v_exp_f32_e32 v157, v157
	v_fmaak_f32 v160, v158, v160, 0x3fb5f0e3
	v_fmaak_f32 v161, v159, v161, 0x3fb5f0e3
	v_fmaak_f32 v160, v158, v160, 0xbe91a98e
	v_fmaak_f32 v161, v159, v161, 0xbe91a98e
	v_fmaak_f32 v160, v158, v160, 0x3e827906
	v_fmaak_f32 v161, v159, v161, 0x3e827906
	v_mul_f32_e32 v158, v158, v160
	v_mul_f32_e32 v159, v159, v161
	v_fma_f32 v156, -v156, v158, 1.0
	v_fma_f32 v157, -v157, v159, 1.0
	v_mul_f32_e32 v162, 0.5, v154
	v_mul_f32_e32 v163, 0.5, v155
	v_bfi_b32 v154, s84, v156, v154
	v_bfi_b32 v155, s84, v157, v155
	v_add_f32_e32 v154, 1.0, v154
	v_add_f32_e32 v155, 1.0, v155
	v_mul_f32_e32 v154, v162, v154
	v_mul_f32_e32 v155, v163, v155
	v_mul_f32_e32 v154, v44, v154
	v_mul_f32_e32 v155, v45, v155
	v_mul_f32_e32 v154, v125, v154
	v_mul_f32_e32 v155, v141, v155
	v_max_f32_e64 v164, |v154|, |v155|
	s_nop 1
	v_max_f32_dpp v164, v164, v164 quad_perm:[1,0,3,2] row_mask:0xf bank_mask:0xf
	s_nop 1
	v_max_f32_dpp v164, v164, v164 quad_perm:[2,3,0,1] row_mask:0xf bank_mask:0xf
	s_nop 1
	v_max_f32_dpp v164, v164, v164 row_half_mirror row_mask:0xf bank_mask:0xf
	s_nop 1
	v_max_f32_dpp v164, v164, v164 row_mirror row_mask:0xf bank_mask:0xf
	s_nop 1
	v_readlane_b32 s46, v164, 32
	v_readlane_b32 s47, v164, 48
	v_readlane_b32 s12, v164, 0
; #define LAS __attribute__((address_space(3)))
; __device__ __forceinline__ float gelu_as(float z) {
;     const float ax = fabsf(z) * 0.70710678118654752f, t = __builtin_amdgcn_rcpf(1.f + 0.3275911f * ax);
;     const float poly = t * (0.254829592f + t * (-0.284496736f + t * (1.421413741f + t * (-1.453152027f + t * 1.061405429f))));
;     const float er = 1.f - poly * __expf(-ax * ax);
;     return 0.5f * z * (1.f + copysignf(er, z));
; }
; __global__ void __launch_bounds__(NTHR, 2) k_main(Args a) {
;     ...
;             for (int it = 0; it < 8; ++it) {
;                 const int tl = it * 8 + wave, t = j * 64 + tl;
;                 const unsigned ew = *(const LAS unsigned*)(EL + tl * 128 + 2 * lane); const int e0 = (int)(ew & 0xffffu), e1 = (int)(ew >> 16);
;                 typedef int i2v __attribute__((ext_vector_type(2))); const i2v si = *(const LAS i2v*)(ACC + tl * 128 + 2 * lane);
;                 typedef float f2v __attribute__((ext_vector_type(2))); const f2v gt = *(const LAS f2v*)(GL + tl * 128 + 2 * lane); const float xs = XS[t];
;                 const int sx = ((const int*)(XS + T))[t];
;                 const float z0 = (float)(2 * si.x + sx) * SU[e0] * xs, z1 = (float)(2 * si.y + sx) * SU[e1] * xs;
;                 const float a0 = gt.x * gelu_as(z0) * SV[e0], a1 = gt.y * gelu_as(z1) * SV[e1];
;                 const float mx = wave_max_dpp(fmaxf(fabsf(a0), fabsf(a1)));
;                 const float sc = mx > 0.f ? mx * (1.f / 119.f) : 1.f, inv = 1.f / sc;
;                 const int q0 = (int)rintf(a0 * inv), q1 = (int)rintf(a1 * inv);
;                 *(LAS unsigned short*)(AL + tl * 128 + 2 * lane) = (unsigned short)((q0 & 255) | ((q1 & 255) << 8));
;                 const int qs = wave_sum_dpp_i(q0 + q1);
;                 if (lane == 0) { ASC[tl] = sc; SAL[tl] = qs; }
	v_readlane_b32 s13, v164, 16
	s_nop 1
	v_mov_b32_e32 v164, s47
	v_max_f32_e32 v164, s46, v164
	v_mov_b32_e32 v165, s13
	v_max3_f32 v164, s12, v165, v164
	v_mul_f32_e32 v165, 0x3c09ae41, v164
	v_cmp_lt_f32_e32 vcc, 0, v164
	s_nop 1
	v_cndmask_b32_e32 v164, 1.0, v165, vcc
	v_div_scale_f32 v166, s[12:13], v164, v164, 1.0
	v_rcp_f32_e32 v167, v166
	v_div_scale_f32 v168, vcc, 1.0, v164, 1.0
	v_fma_f32 v169, -v166, v167, 1.0
	v_fmac_f32_e32 v167, v169, v167
	v_mul_f32_e32 v169, v168, v167
	v_fma_f32 v170, -v166, v169, v168
	v_fmac_f32_e32 v169, v170, v167
	v_fma_f32 v166, -v166, v169, v168
	v_div_fmas_f32 v166, v166, v167, v169
	v_div_fixup_f32 v166, v166, v164, 1.0
	v_mul_f32_e32 v154, v166, v154
	v_mul_f32_e32 v155, v166, v155
	v_rndne_f32_e32 v154, v154
	v_rndne_f32_e32 v155, v155
	v_cvt_i32_f32_e32 v154, v154
	v_cvt_i32_f32_e32 v155, v155
	v_perm_b32 v167, v155, v154, s85
	v_add_u32_e32 v154, v154, v155
	ds_write_b16 v90, v167 offset:1024
	s_nop 1
	v_add_u32_dpp v154, v154, v154 quad_perm:[1,0,3,2] row_mask:0xf bank_mask:0xf bound_ctrl:1
	s_nop 1
	v_add_u32_dpp v154, v154, v154 quad_perm:[2,3,0,1] row_mask:0xf bank_mask:0xf bound_ctrl:1
	s_nop 1
	v_add_u32_dpp v154, v154, v154 row_half_mirror row_mask:0xf bank_mask:0xf bound_ctrl:1
	s_nop 1
	v_add_u32_dpp v154, v154, v154 row_mirror row_mask:0xf bank_mask:0xf bound_ctrl:1
	s_nop 1
	v_readlane_b32 s46, v154, 0
	v_readlane_b32 s47, v154, 16
	v_readlane_b32 s12, v154, 32
	v_readlane_b32 s13, v154, 48
	s_nop 1
	s_add_i32 s46, s47, s46
	s_add_i32 s46, s46, s12
	s_add_i32 s46, s46, s13
	s_add_i32 s47, s67, 32
	s_and_saveexec_b64 s[12:13], s[8:9]
	v_mov_b32_e32 v154, s47
	v_mov_b32_e32 v155, s46
	ds_write2st64_b32 v154, v164, v155 offset1:1
	s_or_b64 exec, exec, s[12:13]
	s_waitcnt vmcnt(10)
	v_lshl_add_u32 v154, v30, 1, v60
	v_lshl_add_u32 v155, v31, 1, v60
	v_cvt_f32_i32_e32 v154, v154
	v_cvt_f32_i32_e32 v155, v155
	v_mul_f32_e32 v154, v126, v154
	v_mul_f32_e32 v155, v142, v155
	v_mul_f32_e32 v154, v68, v154
	v_mul_f32_e32 v155, v68, v155
	v_mul_f32_e64 v156, |v154|, s82
	v_mul_f32_e64 v157, |v155|, s82
	v_fma_f32 v158, v156, s83, 1.0
	v_fma_f32 v159, v157, s83, 1.0
	v_rcp_f32_e32 v158, v158
	v_rcp_f32_e32 v159, v159
	v_mul_f32_e64 v156, v156, -v156
	v_mul_f32_e64 v157, v157, -v157
	v_mul_f32_e32 v156, 0x3fb8aa3b, v156
	v_mul_f32_e32 v157, 0x3fb8aa3b, v157
	v_fmamk_f32 v160, v158, 0x3f87dc22, v110
	v_fmamk_f32 v161, v159, 0x3f87dc22, v110
	v_exp_f32_e32 v156, v156
	v_exp_f32_e32 v157, v157
	v_fmaak_f32 v160, v158, v160, 0x3fb5f0e3
	v_fmaak_f32 v161, v159, v161, 0x3fb5f0e3
	v_fmaak_f32 v160, v158, v160, 0xbe91a98e
	v_fmaak_f32 v161, v159, v161, 0xbe91a98e
	v_fmaak_f32 v160, v158, v160, 0x3e827906
	v_fmaak_f32 v161, v159, v161, 0x3e827906
	v_mul_f32_e32 v158, v158, v160
	v_mul_f32_e32 v159, v159, v161
	v_fma_f32 v156, -v156, v158, 1.0
	v_fma_f32 v157, -v157, v159, 1.0
	v_mul_f32_e32 v162, 0.5, v154
	v_mul_f32_e32 v163, 0.5, v155
	v_bfi_b32 v154, s84, v156, v154
	v_bfi_b32 v155, s84, v157, v155
	v_add_f32_e32 v154, 1.0, v154
	v_add_f32_e32 v155, 1.0, v155
	v_mul_f32_e32 v154, v162, v154
	v_mul_f32_e32 v155, v163, v155
	v_mul_f32_e32 v154, v46, v154
	v_mul_f32_e32 v155, v47, v155
	v_mul_f32_e32 v154, v127, v154
	v_mul_f32_e32 v155, v143, v155
	v_max_f32_e64 v164, |v154|, |v155|
	s_nop 1
	v_max_f32_dpp v164, v164, v164 quad_perm:[1,0,3,2] row_mask:0xf bank_mask:0xf
	s_nop 1
	v_max_f32_dpp v164, v164, v164 quad_perm:[2,3,0,1] row_mask:0xf bank_mask:0xf
	s_nop 1
	v_max_f32_dpp v164, v164, v164 row_half_mirror row_mask:0xf bank_mask:0xf
	s_nop 1
	v_max_f32_dpp v164, v164, v164 row_mirror row_mask:0xf bank_mask:0xf
	s_nop 1
	v_readlane_b32 s46, v164, 32
	v_readlane_b32 s47, v164, 48
	v_readlane_b32 s12, v164, 0
	v_readlane_b32 s13, v164, 16
	s_nop 1
	v_mov_b32_e32 v164, s47
	v_max_f32_e32 v164, s46, v164
	v_mov_b32_e32 v165, s13
	v_max3_f32 v164, s12, v165, v164
	v_mul_f32_e32 v165, 0x3c09ae41, v164
	v_cmp_lt_f32_e32 vcc, 0, v164
	s_nop 1
	v_cndmask_b32_e32 v164, 1.0, v165, vcc
	v_div_scale_f32 v166, s[12:13], v164, v164, 1.0
	v_rcp_f32_e32 v167, v166
	v_div_scale_f32 v168, vcc, 1.0, v164, 1.0
	v_fma_f32 v169, -v166, v167, 1.0
	v_fmac_f32_e32 v167, v169, v167
	v_mul_f32_e32 v169, v168, v167
	v_fma_f32 v170, -v166, v169, v168
	v_fmac_f32_e32 v169, v170, v167
	v_fma_f32 v166, -v166, v169, v168
	v_div_fmas_f32 v166, v166, v167, v169
	v_div_fixup_f32 v166, v166, v164, 1.0
	v_mul_f32_e32 v154, v166, v154
	v_mul_f32_e32 v155, v166, v155
	v_rndne_f32_e32 v154, v154
	v_rndne_f32_e32 v155, v155
	v_cvt_i32_f32_e32 v154, v154
	v_cvt_i32_f32_e32 v155, v155
	v_perm_b32 v167, v155, v154, s85
	v_add_u32_e32 v154, v154, v155
	ds_write_b16 v90, v167 offset:2048
	s_nop 1
	v_add_u32_dpp v154, v154, v154 quad_perm:[1,0,3,2] row_mask:0xf bank_mask:0xf bound_ctrl:1
	s_nop 1
	v_add_u32_dpp v154, v154, v154 quad_perm:[2,3,0,1] row_mask:0xf bank_mask:0xf bound_ctrl:1
	s_nop 1
	v_add_u32_dpp v154, v154, v154 row_half_mirror row_mask:0xf bank_mask:0xf bound_ctrl:1
	s_nop 1
	v_add_u32_dpp v154, v154, v154 row_mirror row_mask:0xf bank_mask:0xf bound_ctrl:1
	s_nop 1
	v_readlane_b32 s46, v154, 0
	v_readlane_b32 s47, v154, 16
	v_readlane_b32 s12, v154, 32
	v_readlane_b32 s13, v154, 48
	s_nop 1
	s_add_i32 s46, s47, s46
	s_add_i32 s46, s46, s12
	s_add_i32 s46, s46, s13
	s_add_i32 s47, s67, 64
	s_and_saveexec_b64 s[12:13], s[8:9]
	v_mov_b32_e32 v154, s47
	v_mov_b32_e32 v155, s46
	ds_write2st64_b32 v154, v164, v155 offset1:1
	s_or_b64 exec, exec, s[12:13]
	s_waitcnt vmcnt(8)
; #define LAS __attribute__((address_space(3)))
; __device__ __forceinline__ float gelu_as(float z) {
;     const float ax = fabsf(z) * 0.70710678118654752f, t = __builtin_amdgcn_rcpf(1.f + 0.3275911f * ax);
;     const float poly = t * (0.254829592f + t * (-0.284496736f + t * (1.421413741f + t * (-1.453152027f + t * 1.061405429f))));
;     const float er = 1.f - poly * __expf(-ax * ax);
;     return 0.5f * z * (1.f + copysignf(er, z));
; }
; __global__ void __launch_bounds__(NTHR, 2) k_main(Args a) {
;     ...
;             for (int it = 0; it < 8; ++it) {
;                 const int tl = it * 8 + wave, t = j * 64 + tl;
;                 const unsigned ew = *(const LAS unsigned*)(EL + tl * 128 + 2 * lane); const int e0 = (int)(ew & 0xffffu), e1 = (int)(ew >> 16);
;                 typedef int i2v __attribute__((ext_vector_type(2))); const i2v si = *(const LAS i2v*)(ACC + tl * 128 + 2 * lane);
;                 typedef float f2v __attribute__((ext_vector_type(2))); const f2v gt = *(const LAS f2v*)(GL + tl * 128 + 2 * lane); const float xs = XS[t];
;                 const int sx = ((const int*)(XS + T))[t];
;                 const float z0 = (float)(2 * si.x + sx) * SU[e0] * xs, z1 = (float)(2 * si.y + sx) * SU[e1] * xs;
;                 const float a0 = gt.x * gelu_as(z0) * SV[e0], a1 = gt.y * gelu_as(z1) * SV[e1];
;                 const float mx = wave_max_dpp(fmaxf(fabsf(a0), fabsf(a1)));
;                 const float sc = mx > 0.f ? mx * (1.f / 119.f) : 1.f, inv = 1.f / sc;
;                 const int q0 = (int)rintf(a0 * inv), q1 = (int)rintf(a1 * inv);
;                 *(LAS unsigned short*)(AL + tl * 128 + 2 * lane) = (unsigned short)((q0 & 255) | ((q1 & 255) << 8));
;                 const int qs = wave_sum_dpp_i(q0 + q1);
;                 if (lane == 0) { ASC[tl] = sc; SAL[tl] = qs; }
	v_lshl_add_u32 v154, v32, 1, v61
	v_lshl_add_u32 v155, v33, 1, v61
	v_cvt_f32_i32_e32 v154, v154
	v_cvt_f32_i32_e32 v155, v155
	v_mul_f32_e32 v154, v128, v154
	v_mul_f32_e32 v155, v144, v155
	v_mul_f32_e32 v154, v69, v154
	v_mul_f32_e32 v155, v69, v155
	v_mul_f32_e64 v156, |v154|, s82
	v_mul_f32_e64 v157, |v155|, s82
	v_fma_f32 v158, v156, s83, 1.0
	v_fma_f32 v159, v157, s83, 1.0
	v_rcp_f32_e32 v158, v158
	v_rcp_f32_e32 v159, v159
	v_mul_f32_e64 v156, v156, -v156
	v_mul_f32_e64 v157, v157, -v157
	v_mul_f32_e32 v156, 0x3fb8aa3b, v156
	v_mul_f32_e32 v157, 0x3fb8aa3b, v157
	v_fmamk_f32 v160, v158, 0x3f87dc22, v110
	v_fmamk_f32 v161, v159, 0x3f87dc22, v110
	v_exp_f32_e32 v156, v156
	v_exp_f32_e32 v157, v157
	v_fmaak_f32 v160, v158, v160, 0x3fb5f0e3
	v_fmaak_f32 v161, v159, v161, 0x3fb5f0e3
	v_fmaak_f32 v160, v158, v160, 0xbe91a98e
	v_fmaak_f32 v161, v159, v161, 0xbe91a98e
	v_fmaak_f32 v160, v158, v160, 0x3e827906
	v_fmaak_f32 v161, v159, v161, 0x3e827906
	v_mul_f32_e32 v158, v158, v160
	v_mul_f32_e32 v159, v159, v161
	v_fma_f32 v156, -v156, v158, 1.0
	v_fma_f32 v157, -v157, v159, 1.0
	v_mul_f32_e32 v162, 0.5, v154
	v_mul_f32_e32 v163, 0.5, v155
	v_bfi_b32 v154, s84, v156, v154
	v_bfi_b32 v155, s84, v157, v155
	v_add_f32_e32 v154, 1.0, v154
	v_add_f32_e32 v155, 1.0, v155
	v_mul_f32_e32 v154, v162, v154
	v_mul_f32_e32 v155, v163, v155
	v_mul_f32_e32 v154, v48, v154
	v_mul_f32_e32 v155, v49, v155
	v_mul_f32_e32 v154, v129, v154
	v_mul_f32_e32 v155, v145, v155
	v_max_f32_e64 v164, |v154|, |v155|
	s_nop 1
	v_max_f32_dpp v164, v164, v164 quad_perm:[1,0,3,2] row_mask:0xf bank_mask:0xf
	s_nop 1
	v_max_f32_dpp v164, v164, v164 quad_perm:[2,3,0,1] row_mask:0xf bank_mask:0xf
	s_nop 1
	v_max_f32_dpp v164, v164, v164 row_half_mirror row_mask:0xf bank_mask:0xf
	s_nop 1
	v_max_f32_dpp v164, v164, v164 row_mirror row_mask:0xf bank_mask:0xf
	s_nop 1
	v_readlane_b32 s46, v164, 32
	v_readlane_b32 s47, v164, 48
	v_readlane_b32 s12, v164, 0
	v_readlane_b32 s13, v164, 16
	s_nop 1
	v_mov_b32_e32 v164, s47
	v_max_f32_e32 v164, s46, v164
	v_mov_b32_e32 v165, s13
	v_max3_f32 v164, s12, v165, v164
	v_mul_f32_e32 v165, 0x3c09ae41, v164
	v_cmp_lt_f32_e32 vcc, 0, v164
	s_nop 1
	v_cndmask_b32_e32 v164, 1.0, v165, vcc
	v_div_scale_f32 v166, s[12:13], v164, v164, 1.0
	v_rcp_f32_e32 v167, v166
	v_div_scale_f32 v168, vcc, 1.0, v164, 1.0
	v_fma_f32 v169, -v166, v167, 1.0
	v_fmac_f32_e32 v167, v169, v167
	v_mul_f32_e32 v169, v168, v167
	v_fma_f32 v170, -v166, v169, v168
	v_fmac_f32_e32 v169, v170, v167
	v_fma_f32 v166, -v166, v169, v168
	v_div_fmas_f32 v166, v166, v167, v169
	v_div_fixup_f32 v166, v166, v164, 1.0
	v_mul_f32_e32 v154, v166, v154
	v_mul_f32_e32 v155, v166, v155
	v_rndne_f32_e32 v154, v154
	v_rndne_f32_e32 v155, v155
	v_cvt_i32_f32_e32 v154, v154
	v_cvt_i32_f32_e32 v155, v155
	v_perm_b32 v167, v155, v154, s85
	v_add_u32_e32 v154, v154, v155
	ds_write_b16 v90, v167 offset:3072
	s_nop 1
	v_add_u32_dpp v154, v154, v154 quad_perm:[1,0,3,2] row_mask:0xf bank_mask:0xf bound_ctrl:1
	s_nop 1
	v_add_u32_dpp v154, v154, v154 quad_perm:[2,3,0,1] row_mask:0xf bank_mask:0xf bound_ctrl:1
	s_nop 1
	v_add_u32_dpp v154, v154, v154 row_half_mirror row_mask:0xf bank_mask:0xf bound_ctrl:1
	s_nop 1
	v_add_u32_dpp v154, v154, v154 row_mirror row_mask:0xf bank_mask:0xf bound_ctrl:1
	s_nop 1
	v_readlane_b32 s46, v154, 0
	v_readlane_b32 s47, v154, 16
	v_readlane_b32 s12, v154, 32
	v_readlane_b32 s13, v154, 48
	s_nop 1
	s_add_i32 s46, s47, s46
	s_add_i32 s46, s46, s12
	s_add_i32 s46, s46, s13
	s_add_i32 s47, s67, 96
	s_and_saveexec_b64 s[12:13], s[8:9]
	v_mov_b32_e32 v154, s47
	v_mov_b32_e32 v155, s46
	ds_write2st64_b32 v154, v164, v155 offset1:1
	s_or_b64 exec, exec, s[12:13]
	s_waitcnt vmcnt(6)
	v_lshl_add_u32 v154, v34, 1, v62
	v_lshl_add_u32 v155, v35, 1, v62
	v_cvt_f32_i32_e32 v154, v154
	v_cvt_f32_i32_e32 v155, v155
	v_mul_f32_e32 v154, v130, v154
	v_mul_f32_e32 v155, v146, v155
	v_mul_f32_e32 v154, v70, v154
	v_mul_f32_e32 v155, v70, v155
	v_mul_f32_e64 v156, |v154|, s82
	v_mul_f32_e64 v157, |v155|, s82
	v_fma_f32 v158, v156, s83, 1.0
	v_fma_f32 v159, v157, s83, 1.0
	v_rcp_f32_e32 v158, v158
	v_rcp_f32_e32 v159, v159
	v_mul_f32_e64 v156, v156, -v156
	v_mul_f32_e64 v157, v157, -v157
	v_mul_f32_e32 v156, 0x3fb8aa3b, v156
	v_mul_f32_e32 v157, 0x3fb8aa3b, v157
	v_fmamk_f32 v160, v158, 0x3f87dc22, v110
	v_fmamk_f32 v161, v159, 0x3f87dc22, v110
	v_exp_f32_e32 v156, v156
	v_exp_f32_e32 v157, v157
	v_fmaak_f32 v160, v158, v160, 0x3fb5f0e3
	v_fmaak_f32 v161, v159, v161, 0x3fb5f0e3
	v_fmaak_f32 v160, v158, v160, 0xbe91a98e
	v_fmaak_f32 v161, v159, v161, 0xbe91a98e
	v_fmaak_f32 v160, v158, v160, 0x3e827906
	v_fmaak_f32 v161, v159, v161, 0x3e827906
	v_mul_f32_e32 v158, v158, v160
	v_mul_f32_e32 v159, v159, v161
	v_fma_f32 v156, -v156, v158, 1.0
	v_fma_f32 v157, -v157, v159, 1.0
	v_mul_f32_e32 v162, 0.5, v154
	v_mul_f32_e32 v163, 0.5, v155
	v_bfi_b32 v154, s84, v156, v154
	v_bfi_b32 v155, s84, v157, v155
	v_add_f32_e32 v154, 1.0, v154
	v_add_f32_e32 v155, 1.0, v155
	v_mul_f32_e32 v154, v162, v154
	v_mul_f32_e32 v155, v163, v155
	v_mul_f32_e32 v154, v50, v154
	v_mul_f32_e32 v155, v51, v155
	v_mul_f32_e32 v154, v131, v154
	v_mul_f32_e32 v155, v147, v155
	v_max_f32_e64 v164, |v154|, |v155|
	s_nop 1
	v_max_f32_dpp v164, v164, v164 quad_perm:[1,0,3,2] row_mask:0xf bank_mask:0xf
	s_nop 1
	v_max_f32_dpp v164, v164, v164 quad_perm:[2,3,0,1] row_mask:0xf bank_mask:0xf
	s_nop 1
	v_max_f32_dpp v164, v164, v164 row_half_mirror row_mask:0xf bank_mask:0xf
	s_nop 1
	v_max_f32_dpp v164, v164, v164 row_mirror row_mask:0xf bank_mask:0xf
	s_nop 1
	v_readlane_b32 s46, v164, 32
	v_readlane_b32 s47, v164, 48
; #define LAS __attribute__((address_space(3)))
; __global__ void __launch_bounds__(NTHR, 2) k_main(Args a) {
;     ...
;                 const float z0 = (float)(2 * si.x + sx) * SU[e0] * xs, z1 = (float)(2 * si.y + sx) * SU[e1] * xs;
;                 const float a0 = gt.x * gelu_as(z0) * SV[e0], a1 = gt.y * gelu_as(z1) * SV[e1];
;                 const float mx = wave_max_dpp(fmaxf(fabsf(a0), fabsf(a1)));
;                 const float sc = mx > 0.f ? mx * (1.f / 119.f) : 1.f, inv = 1.f / sc;
;                 const int q0 = (int)rintf(a0 * inv), q1 = (int)rintf(a1 * inv);
;                 *(LAS unsigned short*)(AL + tl * 128 + 2 * lane) = (unsigned short)((q0 & 255) | ((q1 & 255) << 8));
;                 const int qs = wave_sum_dpp_i(q0 + q1);
;                 if (lane == 0) { ASC[tl] = sc; SAL[tl] = qs; }
	v_readlane_b32 s12, v164, 0
	v_readlane_b32 s13, v164, 16
	s_nop 1
	v_mov_b32_e32 v164, s47
	v_max_f32_e32 v164, s46, v164
	v_mov_b32_e32 v165, s13
	v_max3_f32 v164, s12, v165, v164
	v_mul_f32_e32 v165, 0x3c09ae41, v164
	v_cmp_lt_f32_e32 vcc, 0, v164
	s_nop 1
	v_cndmask_b32_e32 v164, 1.0, v165, vcc
	v_div_scale_f32 v166, s[12:13], v164, v164, 1.0
	v_rcp_f32_e32 v167, v166
	v_div_scale_f32 v168, vcc, 1.0, v164, 1.0
	v_fma_f32 v169, -v166, v167, 1.0
	v_fmac_f32_e32 v167, v169, v167
	v_mul_f32_e32 v169, v168, v167
	v_fma_f32 v170, -v166, v169, v168
	v_fmac_f32_e32 v169, v170, v167
	v_fma_f32 v166, -v166, v169, v168
	v_div_fmas_f32 v166, v166, v167, v169
	v_div_fixup_f32 v166, v166, v164, 1.0
	v_mul_f32_e32 v154, v166, v154
	v_mul_f32_e32 v155, v166, v155
	v_rndne_f32_e32 v154, v154
	v_rndne_f32_e32 v155, v155
	v_cvt_i32_f32_e32 v154, v154
	v_cvt_i32_f32_e32 v155, v155
	v_perm_b32 v167, v155, v154, s85
	v_add_u32_e32 v154, v154, v155
	ds_write_b16 v90, v167 offset:4096
	s_nop 1
	v_add_u32_dpp v154, v154, v154 quad_perm:[1,0,3,2] row_mask:0xf bank_mask:0xf bound_ctrl:1
	s_nop 1
	v_add_u32_dpp v154, v154, v154 quad_perm:[2,3,0,1] row_mask:0xf bank_mask:0xf bound_ctrl:1
	s_nop 1
	v_add_u32_dpp v154, v154, v154 row_half_mirror row_mask:0xf bank_mask:0xf bound_ctrl:1
	s_nop 1
	v_add_u32_dpp v154, v154, v154 row_mirror row_mask:0xf bank_mask:0xf bound_ctrl:1
	s_nop 1
	v_readlane_b32 s46, v154, 0
	v_readlane_b32 s47, v154, 16
	v_readlane_b32 s12, v154, 32
	v_readlane_b32 s13, v154, 48
	s_nop 1
	s_add_i32 s46, s47, s46
	s_add_i32 s46, s46, s12
	s_add_i32 s46, s46, s13
	s_add_i32 s47, s67, 128
	s_and_saveexec_b64 s[12:13], s[8:9]
	v_mov_b32_e32 v154, s47
	v_mov_b32_e32 v155, s46
	ds_write2st64_b32 v154, v164, v155 offset1:1
	s_or_b64 exec, exec, s[12:13]
	s_waitcnt vmcnt(4)
	v_lshl_add_u32 v154, v36, 1, v63
	v_lshl_add_u32 v155, v37, 1, v63
	v_cvt_f32_i32_e32 v154, v154
	v_cvt_f32_i32_e32 v155, v155
	v_mul_f32_e32 v154, v132, v154
	v_mul_f32_e32 v155, v148, v155
	v_mul_f32_e32 v154, v71, v154
	v_mul_f32_e32 v155, v71, v155
	v_mul_f32_e64 v156, |v154|, s82
	v_mul_f32_e64 v157, |v155|, s82
	v_fma_f32 v158, v156, s83, 1.0
	v_fma_f32 v159, v157, s83, 1.0
	v_rcp_f32_e32 v158, v158
	v_rcp_f32_e32 v159, v159
	v_mul_f32_e64 v156, v156, -v156
	v_mul_f32_e64 v157, v157, -v157
	v_mul_f32_e32 v156, 0x3fb8aa3b, v156
	v_mul_f32_e32 v157, 0x3fb8aa3b, v157
	v_fmamk_f32 v160, v158, 0x3f87dc22, v110
	v_fmamk_f32 v161, v159, 0x3f87dc22, v110
	v_exp_f32_e32 v156, v156
	v_exp_f32_e32 v157, v157
	v_fmaak_f32 v160, v158, v160, 0x3fb5f0e3
	v_fmaak_f32 v161, v159, v161, 0x3fb5f0e3
	v_fmaak_f32 v160, v158, v160, 0xbe91a98e
	v_fmaak_f32 v161, v159, v161, 0xbe91a98e
	v_fmaak_f32 v160, v158, v160, 0x3e827906
	v_fmaak_f32 v161, v159, v161, 0x3e827906
	v_mul_f32_e32 v158, v158, v160
	v_mul_f32_e32 v159, v159, v161
	v_fma_f32 v156, -v156, v158, 1.0
	v_fma_f32 v157, -v157, v159, 1.0
	v_mul_f32_e32 v162, 0.5, v154
	v_mul_f32_e32 v163, 0.5, v155
	v_bfi_b32 v154, s84, v156, v154
	v_bfi_b32 v155, s84, v157, v155
	v_add_f32_e32 v154, 1.0, v154
	v_add_f32_e32 v155, 1.0, v155
	v_mul_f32_e32 v154, v162, v154
	v_mul_f32_e32 v155, v163, v155
	v_mul_f32_e32 v154, v52, v154
	v_mul_f32_e32 v155, v53, v155
	v_mul_f32_e32 v154, v133, v154
	v_mul_f32_e32 v155, v149, v155
	v_max_f32_e64 v164, |v154|, |v155|
	s_nop 1
	v_max_f32_dpp v164, v164, v164 quad_perm:[1,0,3,2] row_mask:0xf bank_mask:0xf
	s_nop 1
	v_max_f32_dpp v164, v164, v164 quad_perm:[2,3,0,1] row_mask:0xf bank_mask:0xf
	s_nop 1
	v_max_f32_dpp v164, v164, v164 row_half_mirror row_mask:0xf bank_mask:0xf
	s_nop 1
	v_max_f32_dpp v164, v164, v164 row_mirror row_mask:0xf bank_mask:0xf
	s_nop 1
	v_readlane_b32 s46, v164, 32
	v_readlane_b32 s47, v164, 48
	v_readlane_b32 s12, v164, 0
	v_readlane_b32 s13, v164, 16
	s_nop 1
	v_mov_b32_e32 v164, s47
	v_max_f32_e32 v164, s46, v164
	v_mov_b32_e32 v165, s13
	v_max3_f32 v164, s12, v165, v164
	v_mul_f32_e32 v165, 0x3c09ae41, v164
	v_cmp_lt_f32_e32 vcc, 0, v164
	s_nop 1
	v_cndmask_b32_e32 v164, 1.0, v165, vcc
	v_div_scale_f32 v166, s[12:13], v164, v164, 1.0
	v_rcp_f32_e32 v167, v166
	v_div_scale_f32 v168, vcc, 1.0, v164, 1.0
	v_fma_f32 v169, -v166, v167, 1.0
	v_fmac_f32_e32 v167, v169, v167
	v_mul_f32_e32 v169, v168, v167
	v_fma_f32 v170, -v166, v169, v168
	v_fmac_f32_e32 v169, v170, v167
	v_fma_f32 v166, -v166, v169, v168
	v_div_fmas_f32 v166, v166, v167, v169
	v_div_fixup_f32 v166, v166, v164, 1.0
	v_mul_f32_e32 v154, v166, v154
	v_mul_f32_e32 v155, v166, v155
	v_rndne_f32_e32 v154, v154
	v_rndne_f32_e32 v155, v155
	v_cvt_i32_f32_e32 v154, v154
	v_cvt_i32_f32_e32 v155, v155
	v_perm_b32 v167, v155, v154, s85
	v_add_u32_e32 v154, v154, v155
	ds_write_b16 v90, v167 offset:5120
	s_nop 1
	v_add_u32_dpp v154, v154, v154 quad_perm:[1,0,3,2] row_mask:0xf bank_mask:0xf bound_ctrl:1
	s_nop 1
	v_add_u32_dpp v154, v154, v154 quad_perm:[2,3,0,1] row_mask:0xf bank_mask:0xf bound_ctrl:1
	s_nop 1
	v_add_u32_dpp v154, v154, v154 row_half_mirror row_mask:0xf bank_mask:0xf bound_ctrl:1
	s_nop 1
	v_add_u32_dpp v154, v154, v154 row_mirror row_mask:0xf bank_mask:0xf bound_ctrl:1
	s_nop 1
	v_readlane_b32 s46, v154, 0
	v_readlane_b32 s47, v154, 16
	v_readlane_b32 s12, v154, 32
	v_readlane_b32 s13, v154, 48
	s_nop 1
	s_add_i32 s46, s47, s46
	s_add_i32 s46, s46, s12
	s_add_i32 s46, s46, s13
	s_add_i32 s47, s67, 160
	s_and_saveexec_b64 s[12:13], s[8:9]
	v_mov_b32_e32 v154, s47
	v_mov_b32_e32 v155, s46
	ds_write2st64_b32 v154, v164, v155 offset1:1
	s_or_b64 exec, exec, s[12:13]
	s_waitcnt vmcnt(2)
; #define LAS __attribute__((address_space(3)))
; __global__ void __launch_bounds__(NTHR, 2) k_main(Args a) {
;     ...
;                 const float z0 = (float)(2 * si.x + sx) * SU[e0] * xs, z1 = (float)(2 * si.y + sx) * SU[e1] * xs;
;                 const float a0 = gt.x * gelu_as(z0) * SV[e0], a1 = gt.y * gelu_as(z1) * SV[e1];
;                 const float mx = wave_max_dpp(fmaxf(fabsf(a0), fabsf(a1)));
;                 const float sc = mx > 0.f ? mx * (1.f / 119.f) : 1.f, inv = 1.f / sc;
;                 const int q0 = (int)rintf(a0 * inv), q1 = (int)rintf(a1 * inv);
;                 *(LAS unsigned short*)(AL + tl * 128 + 2 * lane) = (unsigned short)((q0 & 255) | ((q1 & 255) << 8));
;                 const int qs = wave_sum_dpp_i(q0 + q1);
;                 if (lane == 0) { ASC[tl] = sc; SAL[tl] = qs; }
	v_lshl_add_u32 v154, v38, 1, v64
	v_lshl_add_u32 v155, v39, 1, v64
	v_cvt_f32_i32_e32 v154, v154
	v_cvt_f32_i32_e32 v155, v155
	v_mul_f32_e32 v154, v134, v154
	v_mul_f32_e32 v155, v150, v155
	v_mul_f32_e32 v154, v72, v154
	v_mul_f32_e32 v155, v72, v155
	v_mul_f32_e64 v156, |v154|, s82
	v_mul_f32_e64 v157, |v155|, s82
	v_fma_f32 v158, v156, s83, 1.0
	v_fma_f32 v159, v157, s83, 1.0
	v_rcp_f32_e32 v158, v158
	v_rcp_f32_e32 v159, v159
	v_mul_f32_e64 v156, v156, -v156
	v_mul_f32_e64 v157, v157, -v157
	v_mul_f32_e32 v156, 0x3fb8aa3b, v156
	v_mul_f32_e32 v157, 0x3fb8aa3b, v157
	v_fmamk_f32 v160, v158, 0x3f87dc22, v110
	v_fmamk_f32 v161, v159, 0x3f87dc22, v110
	v_exp_f32_e32 v156, v156
	v_exp_f32_e32 v157, v157
	v_fmaak_f32 v160, v158, v160, 0x3fb5f0e3
	v_fmaak_f32 v161, v159, v161, 0x3fb5f0e3
	v_fmaak_f32 v160, v158, v160, 0xbe91a98e
	v_fmaak_f32 v161, v159, v161, 0xbe91a98e
	v_fmaak_f32 v160, v158, v160, 0x3e827906
	v_fmaak_f32 v161, v159, v161, 0x3e827906
	v_mul_f32_e32 v158, v158, v160
	v_mul_f32_e32 v159, v159, v161
	v_fma_f32 v156, -v156, v158, 1.0
	v_fma_f32 v157, -v157, v159, 1.0
	v_mul_f32_e32 v162, 0.5, v154
	v_mul_f32_e32 v163, 0.5, v155
	v_bfi_b32 v154, s84, v156, v154
	v_bfi_b32 v155, s84, v157, v155
	v_add_f32_e32 v154, 1.0, v154
	v_add_f32_e32 v155, 1.0, v155
	v_mul_f32_e32 v154, v162, v154
	v_mul_f32_e32 v155, v163, v155
	v_mul_f32_e32 v154, v54, v154
	v_mul_f32_e32 v155, v55, v155
	v_mul_f32_e32 v154, v135, v154
	v_mul_f32_e32 v155, v151, v155
	v_max_f32_e64 v164, |v154|, |v155|
	s_nop 1
	v_max_f32_dpp v164, v164, v164 quad_perm:[1,0,3,2] row_mask:0xf bank_mask:0xf
	s_nop 1
	v_max_f32_dpp v164, v164, v164 quad_perm:[2,3,0,1] row_mask:0xf bank_mask:0xf
	s_nop 1
	v_max_f32_dpp v164, v164, v164 row_half_mirror row_mask:0xf bank_mask:0xf
	s_nop 1
	v_max_f32_dpp v164, v164, v164 row_mirror row_mask:0xf bank_mask:0xf
	s_nop 1
	v_readlane_b32 s46, v164, 32
	v_readlane_b32 s47, v164, 48
	v_readlane_b32 s12, v164, 0
	v_readlane_b32 s13, v164, 16
	s_nop 1
	v_mov_b32_e32 v164, s47
	v_max_f32_e32 v164, s46, v164
	v_mov_b32_e32 v165, s13
	v_max3_f32 v164, s12, v165, v164
	v_mul_f32_e32 v165, 0x3c09ae41, v164
	v_cmp_lt_f32_e32 vcc, 0, v164
	s_nop 1
	v_cndmask_b32_e32 v164, 1.0, v165, vcc
	v_div_scale_f32 v166, s[12:13], v164, v164, 1.0
	v_rcp_f32_e32 v167, v166
	v_div_scale_f32 v168, vcc, 1.0, v164, 1.0
	v_fma_f32 v169, -v166, v167, 1.0
	v_fmac_f32_e32 v167, v169, v167
	v_mul_f32_e32 v169, v168, v167
	v_fma_f32 v170, -v166, v169, v168
	v_fmac_f32_e32 v169, v170, v167
	v_fma_f32 v166, -v166, v169, v168
	v_div_fmas_f32 v166, v166, v167, v169
	v_div_fixup_f32 v166, v166, v164, 1.0
	v_mul_f32_e32 v154, v166, v154
	v_mul_f32_e32 v155, v166, v155
	v_rndne_f32_e32 v154, v154
	v_rndne_f32_e32 v155, v155
	v_cvt_i32_f32_e32 v154, v154
	v_cvt_i32_f32_e32 v155, v155
	v_perm_b32 v167, v155, v154, s85
	v_add_u32_e32 v154, v154, v155
	ds_write_b16 v90, v167 offset:6144
	s_nop 1
	v_add_u32_dpp v154, v154, v154 quad_perm:[1,0,3,2] row_mask:0xf bank_mask:0xf bound_ctrl:1
	s_nop 1
	v_add_u32_dpp v154, v154, v154 quad_perm:[2,3,0,1] row_mask:0xf bank_mask:0xf bound_ctrl:1
	s_nop 1
	v_add_u32_dpp v154, v154, v154 row_half_mirror row_mask:0xf bank_mask:0xf bound_ctrl:1
	s_nop 1
	v_add_u32_dpp v154, v154, v154 row_mirror row_mask:0xf bank_mask:0xf bound_ctrl:1
	s_nop 1
	v_readlane_b32 s46, v154, 0
	v_readlane_b32 s47, v154, 16
	v_readlane_b32 s12, v154, 32
	v_readlane_b32 s13, v154, 48
	s_nop 1
	s_add_i32 s46, s47, s46
	s_add_i32 s46, s46, s12
	s_add_i32 s46, s46, s13
	s_add_i32 s47, s67, 192
	s_and_saveexec_b64 s[12:13], s[8:9]
	v_mov_b32_e32 v154, s47
	v_mov_b32_e32 v155, s46
	ds_write2st64_b32 v154, v164, v155 offset1:1
	s_or_b64 exec, exec, s[12:13]
	s_waitcnt vmcnt(0)
; #define LAS __attribute__((address_space(3)))
; __global__ void __launch_bounds__(NTHR, 2) k_main(Args a) {
;     ...
;                 const float z0 = (float)(2 * si.x + sx) * SU[e0] * xs, z1 = (float)(2 * si.y + sx) * SU[e1] * xs;
;                 const float a0 = gt.x * gelu_as(z0) * SV[e0], a1 = gt.y * gelu_as(z1) * SV[e1];
;                 const float mx = wave_max_dpp(fmaxf(fabsf(a0), fabsf(a1)));
;                 const float sc = mx > 0.f ? mx * (1.f / 119.f) : 1.f, inv = 1.f / sc;
;                 const int q0 = (int)rintf(a0 * inv), q1 = (int)rintf(a1 * inv);
;                 *(LAS unsigned short*)(AL + tl * 128 + 2 * lane) = (unsigned short)((q0 & 255) | ((q1 & 255) << 8));
;                 const int qs = wave_sum_dpp_i(q0 + q1);
;                 if (lane == 0) { ASC[tl] = sc; SAL[tl] = qs; }
	v_lshl_add_u32 v154, v40, 1, v65
	v_lshl_add_u32 v155, v41, 1, v65
	v_cvt_f32_i32_e32 v154, v154
	v_cvt_f32_i32_e32 v155, v155
	v_mul_f32_e32 v154, v136, v154
	v_mul_f32_e32 v155, v152, v155
	v_mul_f32_e32 v154, v73, v154
	v_mul_f32_e32 v155, v73, v155
	v_mul_f32_e64 v156, |v154|, s82
	v_mul_f32_e64 v157, |v155|, s82
	v_fma_f32 v158, v156, s83, 1.0
	v_fma_f32 v159, v157, s83, 1.0
	v_rcp_f32_e32 v158, v158
	v_rcp_f32_e32 v159, v159
	v_mul_f32_e64 v156, v156, -v156
	v_mul_f32_e64 v157, v157, -v157
	v_mul_f32_e32 v156, 0x3fb8aa3b, v156
	v_mul_f32_e32 v157, 0x3fb8aa3b, v157
	v_fmamk_f32 v160, v158, 0x3f87dc22, v110
	v_fmamk_f32 v161, v159, 0x3f87dc22, v110
	v_exp_f32_e32 v156, v156
	v_exp_f32_e32 v157, v157
	v_fmaak_f32 v160, v158, v160, 0x3fb5f0e3
	v_fmaak_f32 v161, v159, v161, 0x3fb5f0e3
	v_fmaak_f32 v160, v158, v160, 0xbe91a98e
	v_fmaak_f32 v161, v159, v161, 0xbe91a98e
	v_fmaak_f32 v160, v158, v160, 0x3e827906
	v_fmaak_f32 v161, v159, v161, 0x3e827906
	v_mul_f32_e32 v158, v158, v160
	v_mul_f32_e32 v159, v159, v161
	v_fma_f32 v156, -v156, v158, 1.0
	v_fma_f32 v157, -v157, v159, 1.0
	v_mul_f32_e32 v162, 0.5, v154
	v_mul_f32_e32 v163, 0.5, v155
	v_bfi_b32 v154, s84, v156, v154
	v_bfi_b32 v155, s84, v157, v155
	v_add_f32_e32 v154, 1.0, v154
	v_add_f32_e32 v155, 1.0, v155
	v_mul_f32_e32 v154, v162, v154
	v_mul_f32_e32 v155, v163, v155
	v_mul_f32_e32 v154, v56, v154
	v_mul_f32_e32 v155, v57, v155
	v_mul_f32_e32 v154, v137, v154
	v_mul_f32_e32 v155, v153, v155
	v_max_f32_e64 v164, |v154|, |v155|
	s_nop 1
	v_max_f32_dpp v164, v164, v164 quad_perm:[1,0,3,2] row_mask:0xf bank_mask:0xf
	s_nop 1
	v_max_f32_dpp v164, v164, v164 quad_perm:[2,3,0,1] row_mask:0xf bank_mask:0xf
	s_nop 1
	v_max_f32_dpp v164, v164, v164 row_half_mirror row_mask:0xf bank_mask:0xf
	s_nop 1
	v_max_f32_dpp v164, v164, v164 row_mirror row_mask:0xf bank_mask:0xf
	s_nop 1
	v_readlane_b32 s46, v164, 32
	v_readlane_b32 s47, v164, 48
	v_readlane_b32 s12, v164, 0
	v_readlane_b32 s13, v164, 16
	s_nop 1
	v_mov_b32_e32 v164, s47
	v_max_f32_e32 v164, s46, v164
	v_mov_b32_e32 v165, s13
	v_max3_f32 v164, s12, v165, v164
	v_mul_f32_e32 v165, 0x3c09ae41, v164
	v_cmp_lt_f32_e32 vcc, 0, v164
	s_nop 1
	v_cndmask_b32_e32 v164, 1.0, v165, vcc
	v_div_scale_f32 v166, s[12:13], v164, v164, 1.0
	v_rcp_f32_e32 v167, v166
	v_div_scale_f32 v168, vcc, 1.0, v164, 1.0
	v_fma_f32 v169, -v166, v167, 1.0
	v_fmac_f32_e32 v167, v169, v167
	v_mul_f32_e32 v169, v168, v167
	v_fma_f32 v170, -v166, v169, v168
	v_fmac_f32_e32 v169, v170, v167
	v_fma_f32 v166, -v166, v169, v168
	v_div_fmas_f32 v166, v166, v167, v169
	v_div_fixup_f32 v166, v166, v164, 1.0
	v_mul_f32_e32 v154, v166, v154
	v_mul_f32_e32 v155, v166, v155
	v_rndne_f32_e32 v154, v154
	v_rndne_f32_e32 v155, v155
	v_cvt_i32_f32_e32 v154, v154
	v_cvt_i32_f32_e32 v155, v155
	v_perm_b32 v167, v155, v154, s85
	v_add_u32_e32 v154, v154, v155
	ds_write_b16 v90, v167 offset:7168
	s_nop 1
	v_add_u32_dpp v154, v154, v154 quad_perm:[1,0,3,2] row_mask:0xf bank_mask:0xf bound_ctrl:1
	s_nop 1
	v_add_u32_dpp v154, v154, v154 quad_perm:[2,3,0,1] row_mask:0xf bank_mask:0xf bound_ctrl:1
	s_nop 1
	v_add_u32_dpp v154, v154, v154 row_half_mirror row_mask:0xf bank_mask:0xf bound_ctrl:1
	s_nop 1
	v_add_u32_dpp v154, v154, v154 row_mirror row_mask:0xf bank_mask:0xf bound_ctrl:1
	s_nop 1
	v_readlane_b32 s46, v154, 0
	v_readlane_b32 s47, v154, 16
	v_readlane_b32 s12, v154, 32
	v_readlane_b32 s13, v154, 48
	s_nop 1
	s_add_i32 s46, s47, s46
	s_add_i32 s46, s46, s12
	s_add_i32 s46, s46, s13
	s_add_i32 s47, s67, 224
	s_and_saveexec_b64 s[12:13], s[8:9]
	v_mov_b32_e32 v154, s47
	v_mov_b32_e32 v155, s46
	ds_write2st64_b32 v154, v164, v155 offset1:1
	s_or_b64 exec, exec, s[12:13]

; #define LAS __attribute__((address_space(3)))
; #define TR4(p_) __builtin_amdgcn_ds_read_tr4_b64_v2i32((LAS v2i*)(p_))
; __device__ __forceinline__ void peer_v_tokens(int j, const LAS unsigned short* EL, const LAS unsigned char* AL  , const LAS float* ASC  , const LAS int* SAL  , ...
;     ...
;     const int BUF[3] = {vslot(3 * wave), vslot(3 * wave + 1), vslot(3 * wave + 2)};
;     const int g = lane >> 3, j8 = lane & 7, s16 = lane & 15, grp = lane >> 4;
;     *(LAS unsigned long long*)(ldsb + BUF[0] + 8 * s16) = 0xFEDCBA9876543210ull;
;     CFENCE();
;     const v2i cal = TR4(ldsb + BUF[0] + 8 * s16);
;     const int pc = cal.x & 15;
;     asm volatile("s_waitcnt lgkmcnt(0)" ::: "memory");
;     const unsigned cx0 = 16u * (unsigned)(j8 ^ (g >> 1)), cx1 = 16u * (unsigned)(j8 ^ (4 + (g >> 1)));
;     const int fr = (4 * (s16 >> 3) + ((s16 & 7) >> 1)) & 7;
;     int roff[4];
; #pragma unroll
;     for (int r = 0; r < 4; ++r) roff[r] = 128 * s16 + 16 * ((((grp >> 1) + 2 * r)) ^ fr) + 8 * (grp & 1);
;     ...
; #pragma unroll 1
;     for (int it = 0; it < 8; ++it) {
;         const int tl = it * 8 + wave, t = j * 64 + tl;
;         unsigned E[8];
;         { const LAS v4u* ep = (const LAS v4u*)(EL + tl * 128 + 16 * g); const v4u e0 = ep[0], e1 = ep[1];
;           E[0] = e0.x; E[1] = e0.y; E[2] = e0.z; E[3] = e0.w; E[4] = e1.x; E[5] = e1.y; E[6] = e1.z; E[7] = e1.w; }
;         uint2 hv[4]; float4 gv[4];
;         { unsigned ho = (unsigned)t * (D / 4) + (unsigned)lane; asm volatile("" : "+v"(ho)); const uint2* hp = (const uint2*)HB + ho; const float4* gp = (const float4*)fng + lane;
; #pragma unroll
;           for (int jq = 0; jq < 4; ++jq) { hv[jq] = hp[64 * jq]; gv[jq] = gp[64 * jq]; } }
;         VDMA(0, 0); VDMA(1, 1);
; #pragma unroll
;         for (int m = 0; m < 2; ++m) {
;             const int idx = lane + 64 * m, tau = idx >> 4, sr = idx & 15, k = 16 * (sr & 7) + 2 * tau + (sr >> 3);
;             const int aq = (int)*(const LAS signed char*)(AL + tl * 128 + k); const int tq = aq + 8;
;             const unsigned lo = (((unsigned)tq & 15u) ^ 8u) * 0x11111111u, hi = ((unsigned)(tq >> 4) & 15u) * 0x11111111u;
;             typedef unsigned u2v __attribute__((ext_vector_type(2)));
;             u2v l2; l2.x = lo; l2.y = lo; u2v h2; h2.x = hi; h2.y = hi;
;             *(LAS u2v*)(ATL + 8 * idx) = l2; *(LAS u2v*)(ATL + 1024 + 8 * idx) = h2;
;         }
.LBB0_691:
	s_or_b64 exec, exec, s[10:11]
	v_mov_b32_e32 v18, v1
	s_waitcnt lgkmcnt(0)
	s_barrier
	v_readlane_b32 s70, v235, 50
	v_and_b32_e32 v19, 15, v18
	v_lshlrev_b32_e32 v58, 3, v19
	v_add_u32_e32 v20, s60, v58
	ds_write_b64 v20, v[84:85]
	v_lshrrev_b32_e32 v23, 1, v18
	v_ashrrev_i32_e32 v24, 5, v18
	v_and_b32_e32 v25, 8, v23
	ds_read_b64_tr_b4 v[20:21], v20
	v_lshl_or_b32 v19, v19, 7, v25
	v_bitop3_b32 v25, v23, v24, 7 bitop3:0x6c
	v_lshl_add_u32 v59, v25, 4, v19
	v_add_u32_e32 v25, 2, v24
	v_bitop3_b32 v25, v25, v23, 7 bitop3:0x78
	v_lshl_add_u32 v60, v25, 4, v19
	v_add_u32_e32 v25, 4, v24
	v_add_u32_e32 v24, 6, v24
	s_waitcnt lgkmcnt(0)
	v_ashrrev_i32_e32 v21, 4, v18
	v_bitop3_b32 v25, v25, v23, 7 bitop3:0x78
	v_bitop3_b32 v23, v24, v23, 7 bitop3:0x78
	v_bitop3_b32 v22, v18, v21, 7 bitop3:0x6c
	v_add_u32_e32 v21, 4, v21
	v_lshl_add_u32 v61, v25, 4, v19
	v_lshl_add_u32 v62, v23, 4, v19
	v_and_b32_e32 v19, 15, v20
	v_bitop3_b32 v21, v21, v18, 7 bitop3:0x78
	v_lshlrev_b32_e32 v63, 4, v22
	v_lshlrev_b32_e32 v22, 1, v19
	v_ashrrev_i32_e32 v19, 31, v18
	v_lshlrev_b32_e32 v64, 4, v21
	v_lshlrev_b64 v[20:21], 4, v[18:19]
	v_and_b32_e32 v25, 0x7ffffff0, v18
	v_lshl_add_u64 v[34:35], s[86:87], 0, v[20:21]
	v_lshlrev_b32_e32 v19, 4, v18
	v_lshlrev_b32_e32 v25, 1, v25
	v_lshl_add_u64 v[36:37], s[88:89], 0, v[20:21]
	v_add_u32_e32 v21, 64, v18
	s_waitcnt lgkmcnt(0)
	v_and_b32_e32 v19, 0x70, v19
	v_add3_u32 v65, s58, v22, v25
	v_ashrrev_i32_e32 v20, 3, v18
	v_ashrrev_i32_e32 v22, 3, v21
	v_lshrrev_b32_e32 v23, 3, v18
	v_bfe_u32 v24, v18, 3, 1
	v_and_b32_e32 v20, -2, v20
	v_and_b32_e32 v22, -2, v22
	v_lshlrev_b32_e32 v21, 3, v21
	v_add_u32_e32 v19, s72, v19
	v_lshlrev_b32_e32 v66, 3, v18
	v_add_u32_e32 v67, 0x200000, v63
	v_add_u32_e32 v68, 0x200000, v64
	v_add_u32_e32 v69, 0x400000, v63
	v_add_u32_e32 v70, 0x400000, v64
	v_add_u32_e32 v71, 0x600000, v63
	v_add_u32_e32 v72, 0x600000, v64
	v_add3_u32 v73, v19, v22, v24
	v_add3_u32 v74, v19, v20, v24
	v_lshl_add_u32 v75, v23, 5, s65
	v_add_u32_e32 v76, s73, v18
	s_mov_b32 s12, 0
	v_add_u32_e32 v77, s59, v21
	s_mov_b32 s13, s67
	v_readlane_b32 s71, v235, 51
	s_nop 0
	s_nop 0
	s_nop 0
	s_nop 0
	s_nop 0
	s_nop 0
	s_nop 0
	s_nop 0
	s_nop 0
	s_nop 0
	s_nop 0
	s_nop 0
	s_nop 0
	s_nop 0
	s_mov_b32 s76, s60
	s_add_i32 s77, s60, 0x800
	s_mov_b32 s78, s61
	s_add_i32 s79, s61, 0x800
	s_mov_b32 s98, s62
	s_add_i32 s99, s62, 0x800
	v_add_u32_e32 v159, s59, v66
	v_add_u32_e32 v160, s59, v58
	v_add_u32_e32 v154, s58, v66
	v_add_u32_e32 v227, 0x12000, v75
	v_lshlrev_b32_e32 v138, 1, v66
	v_add_u32_e32 v155, 0x11200, v138
	v_add_u32_e32 v156, 0x27400, v138
	global_load_dwordx4 v[210:213], v[34:35], off
	global_load_dwordx4 v[214:217], v[34:35], off offset:1024
	global_load_dwordx4 v[218:221], v[34:35], off offset:2048
	global_load_dwordx4 v[222:225], v[34:35], off offset:3072
	ds_read_b128 v[18:21], v227
	ds_read_b128 v[22:25], v227 offset:16
	v_mov_b32_e32 v138, v74
	ds_read_u8 v139, v138
	v_mov_b32_e32 v141, v73
	ds_read_u8 v140, v141
	v_mov_b32_e32 v150, v63
	v_mov_b32_e32 v151, v64
	s_waitcnt lgkmcnt(0)
	v_and_b32_e32 v78, 0xffff, v18
	v_lshrrev_b32_e32 v79, 16, v18
	v_lshl_add_u32 v78, v78, 7, v150
	v_lshl_add_u32 v79, v79, 7, v151
	s_mov_b32 m0, s76
	s_add_i32 s43, s76, 0x400
	global_load_lds_dwordx4 v78, s[50:51]
	s_mov_b32 m0, s43
	s_nop 0
	global_load_lds_dwordx4 v79, s[50:51]
	v_and_b32_e32 v78, 0xffff, v19
	v_lshrrev_b32_e32 v79, 16, v19
	v_lshl_add_u32 v78, v78, 7, v150
	v_lshl_add_u32 v79, v79, 7, v151
	s_mov_b32 m0, s77
	s_add_i32 s43, s77, 0x400
	global_load_lds_dwordx4 v78, s[50:51]
	s_mov_b32 m0, s43
	s_nop 0
	global_load_lds_dwordx4 v79, s[50:51]
	v_and_b32_e32 v78, 0xffff, v20
	v_lshrrev_b32_e32 v79, 16, v20
	v_lshl_add_u32 v78, v78, 7, v150
	v_lshl_add_u32 v79, v79, 7, v151
	s_mov_b32 m0, s78
	s_add_i32 s43, s78, 0x400
	global_load_lds_dwordx4 v78, s[50:51]
	s_mov_b32 m0, s43
	s_nop 0
	global_load_lds_dwordx4 v79, s[50:51]
	v_and_b32_e32 v78, 0xffff, v21
	v_lshrrev_b32_e32 v79, 16, v21
	v_lshl_add_u32 v78, v78, 7, v150
	v_lshl_add_u32 v79, v79, 7, v151
	s_mov_b32 m0, s79
	s_add_i32 s43, s79, 0x400
	global_load_lds_dwordx4 v78, s[50:51]
	s_mov_b32 m0, s43
	s_nop 0
	global_load_lds_dwordx4 v79, s[50:51]
	v_and_b32_e32 v78, 0xffff, v22
	v_lshrrev_b32_e32 v79, 16, v22
	v_lshl_add_u32 v78, v78, 7, v150
	v_lshl_add_u32 v79, v79, 7, v151
	s_mov_b32 m0, s98
	s_add_i32 s43, s98, 0x400
	global_load_lds_dwordx4 v78, s[50:51]
	s_mov_b32 m0, s43
	s_nop 0
	global_load_lds_dwordx4 v79, s[50:51]
	v_add_u32_e32 v143, 8, v139
	v_and_b32_e32 v142, 15, v143
	v_xor_b32_e32 v142, 8, v142
	v_bfe_u32 v144, v143, 4, 4
	v_mul_lo_u32 v142, v142, s92
	v_mul_lo_u32 v144, v144, s92
	v_mov_b32_e32 v143, v142
	v_mov_b32_e32 v145, v144
	ds_write2st64_b64 v159, v[142:143], v[144:145] offset1:2
	s_waitcnt vmcnt(10)
	ds_write_b128 v155, v[210:213]
	ds_write_b128 v155, v[214:217] offset:1024
	ds_write_b128 v156, v[218:221]
	ds_write_b128 v156, v[222:225] offset:1024
	s_waitcnt vmcnt(8)
; #define LAS __attribute__((address_space(3)))
; #define TR4(p_) __builtin_amdgcn_ds_read_tr4_b64_v2i32((LAS v2i*)(p_))
; #define CFENCE() asm volatile("" ::: "memory")
; __device__ __forceinline__ void peer_v_tokens(int j, const LAS unsigned short* EL, const LAS unsigned char* AL  , const LAS float* ASC  , const LAS int* SAL  , ...
;     ...
;         VDMA(0, 0); VDMA(1, 1);
; #pragma unroll
;         for (int m = 0; m < 2; ++m) {
;             const int idx = lane + 64 * m, tau = idx >> 4, sr = idx & 15, k = 16 * (sr & 7) + 2 * tau + (sr >> 3);
;             const int aq = (int)*(const LAS signed char*)(AL + tl * 128 + k); const int tq = aq + 8;
;             const unsigned lo = (((unsigned)tq & 15u) ^ 8u) * 0x11111111u, hi = ((unsigned)(tq >> 4) & 15u) * 0x11111111u;
;             typedef unsigned u2v __attribute__((ext_vector_type(2)));
;             u2v l2; l2.x = lo; l2.y = lo; u2v h2; h2.x = hi; h2.y = hi;
;             *(LAS u2v*)(ATL + 8 * idx) = l2; *(LAS u2v*)(ATL + 1024 + 8 * idx) = h2;
;         }
;         const float asc = ASC[tl]; const int sa = SAL[tl];
;         CFENCE();
;         int accH[4], accL[4];
; #pragma unroll
;         for (int st = 0; st < 16; ++st) {
;             const int p = st >> 2, q = st & 3;
;             if (st < 14) VDMA(st + 2, (st + 2) % 3);
;             if (st < 14) asm volatile("s_waitcnt vmcnt(8)" ::: "memory");
;             else if (st == 14) asm volatile("s_waitcnt vmcnt(4)" ::: "memory");
;             else asm volatile("s_waitcnt vmcnt(0)" ::: "memory");
;             if (q == 0) {
; #pragma unroll
;                 for (int r = 0; r < 4; ++r) { accH[r] = 0; accL[r] = 0; } }
; #pragma unroll
;             for (int tp = 0; tp < 2; ++tp) {
;                 const v2i ao = TR4(ATL + (2 * q + tp) * 128 + 8 * s16), ah = TR4(ATL + 1024 + (2 * q + tp) * 128 + 8 * s16);
; #pragma unroll
;                 for (int r = 0; r < 4; ++r) {
;                     const v2i d = TR4(ldsb + BUF[st % 3] + 2048 * tp + roff[r]);
;                     accH[r] = __builtin_amdgcn_sdot8(d.x, ah.x, accH[r], false); accH[r] = __builtin_amdgcn_sdot8(d.y, ah.y, accH[r], false);
;                     accL[r] = __builtin_amdgcn_sdot8(d.x, ao.x, accL[r], false); accL[r] = __builtin_amdgcn_sdot8(d.y, ao.y, accL[r], false);
;                 }
;             }
	v_add_u32_e32 v54, s76, v59
	v_add_u32_e32 v55, s76, v60
	v_add_u32_e32 v56, s76, v61
	v_add_u32_e32 v57, s76, v62
	ds_read_b64_tr_b4 v[46:47], v160
	ds_read_b64_tr_b4 v[48:49], v160 offset:1024
	ds_read_b64_tr_b4 v[122:123], v54
	ds_read_b64_tr_b4 v[124:125], v55
	ds_read_b64_tr_b4 v[126:127], v56
	ds_read_b64_tr_b4 v[128:129], v57
	v_add_u32_e32 v147, 8, v140
	v_and_b32_e32 v146, 15, v147
	v_xor_b32_e32 v146, 8, v146
	v_bfe_u32 v148, v147, 4, 4
	v_mul_lo_u32 v146, v146, s92
	v_mul_lo_u32 v148, v148, s92
	v_mov_b32_e32 v147, v146
	v_mov_b32_e32 v149, v148
	ds_write2st64_b64 v77, v[146:147], v[148:149] offset1:2
	v_add_u32_e32 v138, 0x400, v74
	ds_read_u8 v139, v138
	v_add_u32_e32 v141, 0x400, v73
	ds_read_u8 v140, v141
	s_mov_b32 s43, s67
	v_mov_b32_e32 v138, s43
	ds_read2st64_b32 v[228:229], v138 offset1:1
	ds_read_b128 v[26:29], v227 offset:2048
	ds_read_b128 v[30:33], v227 offset:2064
	v_mov_b32_e32 v38, 0
	v_mov_b32_e32 v39, 0
	v_mov_b32_e32 v40, 0
	v_mov_b32_e32 v41, 0
	v_mov_b32_e32 v42, 0
	v_mov_b32_e32 v43, 0
	v_mov_b32_e32 v44, 0
	v_mov_b32_e32 v45, 0
	v_and_b32_e32 v78, 0xffff, v23
	v_lshrrev_b32_e32 v79, 16, v23
	v_lshl_add_u32 v78, v78, 7, v150
	v_lshl_add_u32 v79, v79, 7, v151
	s_mov_b32 m0, s99
	s_add_i32 s43, s99, 0x400
	global_load_lds_dwordx4 v78, s[50:51]
	s_mov_b32 m0, s43
	s_nop 0
	global_load_lds_dwordx4 v79, s[50:51]
	s_waitcnt vmcnt(8)
	v_add_u32_e32 v54, s77, v59
	v_add_u32_e32 v55, s77, v60
	v_add_u32_e32 v56, s77, v61
	v_add_u32_e32 v57, s77, v62
	ds_read_b64_tr_b4 v[50:51], v160 offset:128
	ds_read_b64_tr_b4 v[52:53], v160 offset:1152
	ds_read_b64_tr_b4 v[130:131], v54
	ds_read_b64_tr_b4 v[132:133], v55
	ds_read_b64_tr_b4 v[134:135], v56
	ds_read_b64_tr_b4 v[136:137], v57
	s_waitcnt lgkmcnt(12)
	v_dot8c_i32_i4_e32 v38, v122, v48
	v_dot8c_i32_i4_e32 v39, v122, v46
	v_dot8c_i32_i4_e32 v40, v124, v48
	v_dot8c_i32_i4_e32 v41, v124, v46
	v_dot8c_i32_i4_e32 v42, v126, v48
	v_dot8c_i32_i4_e32 v43, v126, v46
	v_dot8c_i32_i4_e32 v44, v128, v48
	v_dot8c_i32_i4_e32 v45, v128, v46
	v_dot8c_i32_i4_e32 v38, v123, v49
	v_dot8c_i32_i4_e32 v39, v123, v47
	v_dot8c_i32_i4_e32 v40, v125, v49
	v_dot8c_i32_i4_e32 v41, v125, v47
	v_dot8c_i32_i4_e32 v42, v127, v49
	v_dot8c_i32_i4_e32 v43, v127, v47
	v_dot8c_i32_i4_e32 v44, v129, v49
	v_dot8c_i32_i4_e32 v45, v129, v47
	v_and_b32_e32 v78, 0xffff, v24
	v_lshrrev_b32_e32 v79, 16, v24
	v_lshl_add_u32 v78, v78, 7, v150
	v_lshl_add_u32 v79, v79, 7, v151
	s_mov_b32 m0, s76
	s_add_i32 s43, s76, 0x400
	global_load_lds_dwordx4 v78, s[50:51]
	s_mov_b32 m0, s43
	s_nop 0
	global_load_lds_dwordx4 v79, s[50:51]
	s_waitcnt vmcnt(8)
	v_add_u32_e32 v54, s78, v59
	v_add_u32_e32 v55, s78, v60
	v_add_u32_e32 v56, s78, v61
	v_add_u32_e32 v57, s78, v62
	ds_read_b64_tr_b4 v[46:47], v160 offset:256
	ds_read_b64_tr_b4 v[48:49], v160 offset:1280
	ds_read_b64_tr_b4 v[122:123], v54
	ds_read_b64_tr_b4 v[124:125], v55
	ds_read_b64_tr_b4 v[126:127], v56
	ds_read_b64_tr_b4 v[128:129], v57
	s_waitcnt lgkmcnt(6)
	v_dot8c_i32_i4_e32 v38, v130, v52
	v_dot8c_i32_i4_e32 v39, v130, v50
	v_dot8c_i32_i4_e32 v40, v132, v52
	v_dot8c_i32_i4_e32 v41, v132, v50
	v_dot8c_i32_i4_e32 v42, v134, v52
	v_dot8c_i32_i4_e32 v43, v134, v50
	v_dot8c_i32_i4_e32 v44, v136, v52
	v_dot8c_i32_i4_e32 v45, v136, v50
	v_dot8c_i32_i4_e32 v38, v131, v53
	v_dot8c_i32_i4_e32 v39, v131, v51
	v_dot8c_i32_i4_e32 v40, v133, v53
	v_dot8c_i32_i4_e32 v41, v133, v51
	v_dot8c_i32_i4_e32 v42, v135, v53
	v_dot8c_i32_i4_e32 v43, v135, v51
	v_dot8c_i32_i4_e32 v44, v137, v53
	v_dot8c_i32_i4_e32 v45, v137, v51
	v_and_b32_e32 v78, 0xffff, v25
	v_lshrrev_b32_e32 v79, 16, v25
	v_lshl_add_u32 v78, v78, 7, v150
	v_lshl_add_u32 v79, v79, 7, v151
	s_mov_b32 m0, s77
	s_add_i32 s43, s77, 0x400
	global_load_lds_dwordx4 v78, s[50:51]
	s_mov_b32 m0, s43
	s_nop 0
	global_load_lds_dwordx4 v79, s[50:51]
	s_waitcnt vmcnt(8)
	v_add_u32_e32 v54, s79, v59
	v_add_u32_e32 v55, s79, v60
	v_add_u32_e32 v56, s79, v61
	v_add_u32_e32 v57, s79, v62
	ds_read_b64_tr_b4 v[50:51], v160 offset:384
	ds_read_b64_tr_b4 v[52:53], v160 offset:1408
	ds_read_b64_tr_b4 v[130:131], v54
	ds_read_b64_tr_b4 v[132:133], v55
	ds_read_b64_tr_b4 v[134:135], v56
	ds_read_b64_tr_b4 v[136:137], v57
	s_waitcnt lgkmcnt(6)
	v_dot8c_i32_i4_e32 v38, v122, v48
	v_dot8c_i32_i4_e32 v39, v122, v46
	v_dot8c_i32_i4_e32 v40, v124, v48
	v_dot8c_i32_i4_e32 v41, v124, v46
	v_dot8c_i32_i4_e32 v42, v126, v48
	v_dot8c_i32_i4_e32 v43, v126, v46
	v_dot8c_i32_i4_e32 v44, v128, v48
	v_dot8c_i32_i4_e32 v45, v128, v46
	v_dot8c_i32_i4_e32 v38, v123, v49
	v_dot8c_i32_i4_e32 v39, v123, v47
	v_dot8c_i32_i4_e32 v40, v125, v49
	v_dot8c_i32_i4_e32 v41, v125, v47
	v_dot8c_i32_i4_e32 v42, v127, v49
	v_dot8c_i32_i4_e32 v43, v127, v47
	v_dot8c_i32_i4_e32 v44, v129, v49
	v_dot8c_i32_i4_e32 v45, v129, v47
	s_waitcnt lgkmcnt(15)
	v_and_b32_e32 v78, 0xffff, v26
	v_lshrrev_b32_e32 v79, 16, v26
	v_lshl_add_u32 v78, v78, 7, v150
	v_lshl_add_u32 v79, v79, 7, v151
	s_mov_b32 m0, s78
	s_add_i32 s43, s78, 0x400
	global_load_lds_dwordx4 v78, s[50:51]
	s_mov_b32 m0, s43
	s_nop 0
	global_load_lds_dwordx4 v79, s[50:51]
	s_waitcnt vmcnt(8)
	v_add_u32_e32 v54, s98, v59
	v_add_u32_e32 v55, s98, v60
	v_add_u32_e32 v56, s98, v61
	v_add_u32_e32 v57, s98, v62
	ds_read_b64_tr_b4 v[46:47], v160 offset:512
	ds_read_b64_tr_b4 v[48:49], v160 offset:1536
	ds_read_b64_tr_b4 v[122:123], v54
	ds_read_b64_tr_b4 v[124:125], v55
	ds_read_b64_tr_b4 v[126:127], v56
	ds_read_b64_tr_b4 v[128:129], v57
	s_waitcnt lgkmcnt(6)
; #define TR4(p_) __builtin_amdgcn_ds_read_tr4_b64_v2i32((LAS v2i*)(p_))
; #define VDMA(st_, k_) do { _Pragma("unroll") for (int i_ = 0; i_ < 4; ++i_) { \
;         const unsigned off_ = (unsigned)((st_) >> 2) * (16384u * 128u) + (PE_ID(E, 4 * ((st_) & 3) + i_) << 7) + ((i_ & 1) ? cx1 : cx0); \
;         __builtin_amdgcn_global_load_lds((const unsigned*)(V4 + off_), (LAS unsigned*)(ldsb + BUF[k_] + 1024 * i_), 16, 0, 0); } } while (0)
; __device__ __forceinline__ void peer_v_tokens(int j, const LAS unsigned short* EL, const LAS unsigned char* AL  , const LAS float* ASC  , const LAS int* SAL  , ...
;     ...
;         for (int st = 0; st < 16; ++st) {
;             const int p = st >> 2, q = st & 3;
;             if (st < 14) VDMA(st + 2, (st + 2) % 3);
;             if (st < 14) asm volatile("s_waitcnt vmcnt(8)" ::: "memory");
;             else if (st == 14) asm volatile("s_waitcnt vmcnt(4)" ::: "memory");
;             else asm volatile("s_waitcnt vmcnt(0)" ::: "memory");
;             if (q == 0) {
; #pragma unroll
;                 for (int r = 0; r < 4; ++r) { accH[r] = 0; accL[r] = 0; } }
; #pragma unroll
;             for (int tp = 0; tp < 2; ++tp) {
;                 const v2i ao = TR4(ATL + (2 * q + tp) * 128 + 8 * s16), ah = TR4(ATL + 1024 + (2 * q + tp) * 128 + 8 * s16);
; #pragma unroll
;                 for (int r = 0; r < 4; ++r) {
;                     const v2i d = TR4(ldsb + BUF[st % 3] + 2048 * tp + roff[r]);
;                     accH[r] = __builtin_amdgcn_sdot8(d.x, ah.x, accH[r], false); accH[r] = __builtin_amdgcn_sdot8(d.y, ah.y, accH[r], false);
;                     accL[r] = __builtin_amdgcn_sdot8(d.x, ao.x, accL[r], false); accL[r] = __builtin_amdgcn_sdot8(d.y, ao.y, accL[r], false);
;                 }
;             }
	v_dot8c_i32_i4_e32 v38, v130, v52
	v_dot8c_i32_i4_e32 v39, v130, v50
	v_dot8c_i32_i4_e32 v40, v132, v52
	v_dot8c_i32_i4_e32 v41, v132, v50
	v_dot8c_i32_i4_e32 v42, v134, v52
	v_dot8c_i32_i4_e32 v43, v134, v50
	v_dot8c_i32_i4_e32 v44, v136, v52
	v_dot8c_i32_i4_e32 v45, v136, v50
	v_dot8c_i32_i4_e32 v38, v131, v53
	v_dot8c_i32_i4_e32 v39, v131, v51
	v_dot8c_i32_i4_e32 v40, v133, v53
	v_dot8c_i32_i4_e32 v41, v133, v51
	v_dot8c_i32_i4_e32 v42, v135, v53
	v_dot8c_i32_i4_e32 v43, v135, v51
	v_dot8c_i32_i4_e32 v44, v137, v53
	v_dot8c_i32_i4_e32 v45, v137, v51
	v_and_b32_e32 v78, 0xffff, v27
	v_lshrrev_b32_e32 v79, 16, v27
	v_lshl_add_u32 v78, v78, 7, v150
	v_lshl_add_u32 v79, v79, 7, v151
	s_mov_b32 m0, s79
	s_add_i32 s43, s79, 0x400
	global_load_lds_dwordx4 v78, s[50:51]
	s_mov_b32 m0, s43
	s_nop 0
	global_load_lds_dwordx4 v79, s[50:51]
	s_waitcnt vmcnt(8)
	v_add_u32_e32 v54, s99, v59
	v_add_u32_e32 v55, s99, v60
	v_add_u32_e32 v56, s99, v61
	v_add_u32_e32 v57, s99, v62
	ds_read_b64_tr_b4 v[50:51], v160 offset:640
	ds_read_b64_tr_b4 v[52:53], v160 offset:1664
	ds_read_b64_tr_b4 v[130:131], v54
	ds_read_b64_tr_b4 v[132:133], v55
	ds_read_b64_tr_b4 v[134:135], v56
	ds_read_b64_tr_b4 v[136:137], v57
	s_waitcnt lgkmcnt(6)
	v_dot8c_i32_i4_e32 v38, v122, v48
	v_dot8c_i32_i4_e32 v39, v122, v46
	v_dot8c_i32_i4_e32 v40, v124, v48
	v_dot8c_i32_i4_e32 v41, v124, v46
	v_dot8c_i32_i4_e32 v42, v126, v48
	v_dot8c_i32_i4_e32 v43, v126, v46
	v_dot8c_i32_i4_e32 v44, v128, v48
	v_dot8c_i32_i4_e32 v45, v128, v46
	v_dot8c_i32_i4_e32 v38, v123, v49
	v_dot8c_i32_i4_e32 v39, v123, v47
	v_dot8c_i32_i4_e32 v40, v125, v49
	v_dot8c_i32_i4_e32 v41, v125, v47
	v_dot8c_i32_i4_e32 v42, v127, v49
	v_dot8c_i32_i4_e32 v43, v127, v47
	v_dot8c_i32_i4_e32 v44, v129, v49
	v_dot8c_i32_i4_e32 v45, v129, v47
	s_waitcnt lgkmcnt(15)
	v_add_u32_e32 v143, 8, v139
	v_and_b32_e32 v142, 15, v143
	v_xor_b32_e32 v142, 8, v142
	v_bfe_u32 v144, v143, 4, 4
	v_mul_lo_u32 v142, v142, s92
	v_mul_lo_u32 v144, v144, s92
	v_mov_b32_e32 v143, v142
	v_mov_b32_e32 v145, v144
	ds_write2st64_b64 v159, v[142:143], v[144:145] offset1:2
	v_and_b32_e32 v78, 0xffff, v28
	v_lshrrev_b32_e32 v79, 16, v28
	v_lshl_add_u32 v78, v78, 7, v150
	v_lshl_add_u32 v79, v79, 7, v151
	s_mov_b32 m0, s98
	s_add_i32 s43, s98, 0x400
	global_load_lds_dwordx4 v78, s[50:51]
	s_mov_b32 m0, s43
	s_nop 0
	global_load_lds_dwordx4 v79, s[50:51]
	s_waitcnt vmcnt(8)
	v_add_u32_e32 v54, s76, v59
	v_add_u32_e32 v55, s76, v60
	v_add_u32_e32 v56, s76, v61
	v_add_u32_e32 v57, s76, v62
	ds_read_b64_tr_b4 v[46:47], v160 offset:768
	ds_read_b64_tr_b4 v[48:49], v160 offset:1792
	ds_read_b64_tr_b4 v[122:123], v54
	ds_read_b64_tr_b4 v[124:125], v55
	ds_read_b64_tr_b4 v[126:127], v56
	ds_read_b64_tr_b4 v[128:129], v57
	s_waitcnt lgkmcnt(7)
	v_dot8c_i32_i4_e32 v38, v130, v52
	v_dot8c_i32_i4_e32 v39, v130, v50
	v_dot8c_i32_i4_e32 v40, v132, v52
	v_dot8c_i32_i4_e32 v41, v132, v50
	v_dot8c_i32_i4_e32 v42, v134, v52
	v_dot8c_i32_i4_e32 v43, v134, v50
	v_dot8c_i32_i4_e32 v44, v136, v52
	v_dot8c_i32_i4_e32 v45, v136, v50
	v_dot8c_i32_i4_e32 v38, v131, v53
	v_dot8c_i32_i4_e32 v39, v131, v51
	v_dot8c_i32_i4_e32 v40, v133, v53
	v_dot8c_i32_i4_e32 v41, v133, v51
	v_dot8c_i32_i4_e32 v42, v135, v53
	v_dot8c_i32_i4_e32 v43, v135, v51
	v_dot8c_i32_i4_e32 v44, v137, v53
	v_dot8c_i32_i4_e32 v45, v137, v51
	v_and_b32_e32 v78, 0xffff, v29
	v_lshrrev_b32_e32 v79, 16, v29
	v_lshl_add_u32 v78, v78, 7, v150
	v_lshl_add_u32 v79, v79, 7, v151
	s_mov_b32 m0, s99
	s_add_i32 s43, s99, 0x400
	global_load_lds_dwordx4 v78, s[50:51]
	s_mov_b32 m0, s43
	s_nop 0
	global_load_lds_dwordx4 v79, s[50:51]
	s_waitcnt vmcnt(8)
	v_add_u32_e32 v54, s77, v59
	v_add_u32_e32 v55, s77, v60
	v_add_u32_e32 v56, s77, v61
	v_add_u32_e32 v57, s77, v62
	ds_read_b64_tr_b4 v[50:51], v160 offset:896
	ds_read_b64_tr_b4 v[52:53], v160 offset:1920
	ds_read_b64_tr_b4 v[130:131], v54
	ds_read_b64_tr_b4 v[132:133], v55
	ds_read_b64_tr_b4 v[134:135], v56
	ds_read_b64_tr_b4 v[136:137], v57
	s_waitcnt lgkmcnt(6)
	v_dot8c_i32_i4_e32 v38, v122, v48
	v_dot8c_i32_i4_e32 v39, v122, v46
	v_dot8c_i32_i4_e32 v40, v124, v48
	v_dot8c_i32_i4_e32 v41, v124, v46
	v_dot8c_i32_i4_e32 v42, v126, v48
	v_dot8c_i32_i4_e32 v43, v126, v46
	v_dot8c_i32_i4_e32 v44, v128, v48
	v_dot8c_i32_i4_e32 v45, v128, v46
	v_dot8c_i32_i4_e32 v38, v123, v49
	v_dot8c_i32_i4_e32 v39, v123, v47
	v_dot8c_i32_i4_e32 v40, v125, v49
	v_dot8c_i32_i4_e32 v41, v125, v47
	v_dot8c_i32_i4_e32 v42, v127, v49
	v_dot8c_i32_i4_e32 v43, v127, v47
	v_dot8c_i32_i4_e32 v44, v129, v49
	v_dot8c_i32_i4_e32 v45, v129, v47
	v_and_b32_e32 v78, 0xffff, v30
	v_lshrrev_b32_e32 v79, 16, v30
	v_lshl_add_u32 v78, v78, 7, v150
	v_lshl_add_u32 v79, v79, 7, v151
	s_mov_b32 m0, s76
	s_add_i32 s43, s76, 0x400
	global_load_lds_dwordx4 v78, s[50:51]
	s_mov_b32 m0, s43
	s_nop 0
	global_load_lds_dwordx4 v79, s[50:51]
	s_waitcnt vmcnt(8)
	v_add_u32_e32 v54, s78, v59
	v_add_u32_e32 v55, s78, v60
	v_add_u32_e32 v56, s78, v61
	v_add_u32_e32 v57, s78, v62
	ds_read_b64_tr_b4 v[46:47], v160
	ds_read_b64_tr_b4 v[48:49], v160 offset:1024
	ds_read_b64_tr_b4 v[122:123], v54
	ds_read_b64_tr_b4 v[124:125], v55
	ds_read_b64_tr_b4 v[126:127], v56
	ds_read_b64_tr_b4 v[128:129], v57
	s_waitcnt lgkmcnt(6)
	v_dot8c_i32_i4_e32 v38, v130, v52
	v_dot8c_i32_i4_e32 v39, v130, v50
	v_dot8c_i32_i4_e32 v40, v132, v52
	v_dot8c_i32_i4_e32 v41, v132, v50
	v_dot8c_i32_i4_e32 v42, v134, v52
	v_dot8c_i32_i4_e32 v43, v134, v50
	v_dot8c_i32_i4_e32 v44, v136, v52
	v_dot8c_i32_i4_e32 v45, v136, v50
	v_dot8c_i32_i4_e32 v38, v131, v53
	v_dot8c_i32_i4_e32 v39, v131, v51
	v_dot8c_i32_i4_e32 v40, v133, v53
	v_dot8c_i32_i4_e32 v41, v133, v51
	v_dot8c_i32_i4_e32 v42, v135, v53
	v_dot8c_i32_i4_e32 v43, v135, v51
	v_dot8c_i32_i4_e32 v44, v137, v53
	v_dot8c_i32_i4_e32 v45, v137, v51
	s_nop 3
	s_waitcnt lgkmcnt(15)
; __device__ __forceinline__ bf16 f2bf(float f) { return (bf16)f2bfu(f); }
; #define TR4(p_) __builtin_amdgcn_ds_read_tr4_b64_v2i32((LAS v2i*)(p_))
; #define VDMA(st_, k_) do { _Pragma("unroll") for (int i_ = 0; i_ < 4; ++i_) { \
;         const unsigned off_ = (unsigned)((st_) >> 2) * (16384u * 128u) + (PE_ID(E, 4 * ((st_) & 3) + i_) << 7) + ((i_ & 1) ? cx1 : cx0); \
;         __builtin_amdgcn_global_load_lds((const unsigned*)(V4 + off_), (LAS unsigned*)(ldsb + BUF[k_] + 1024 * i_), 16, 0, 0); } } while (0)
; __device__ __forceinline__ void peer_v_tokens(int j, const LAS unsigned short* EL, const LAS unsigned char* AL  , const LAS float* ASC  , const LAS int* SAL  , ...
;     ...
;         for (int st = 0; st < 16; ++st) {
;             const int p = st >> 2, q = st & 3;
;             if (st < 14) VDMA(st + 2, (st + 2) % 3);
;             if (st < 14) asm volatile("s_waitcnt vmcnt(8)" ::: "memory");
;             else if (st == 14) asm volatile("s_waitcnt vmcnt(4)" ::: "memory");
;             else asm volatile("s_waitcnt vmcnt(0)" ::: "memory");
;             if (q == 0) {
; #pragma unroll
;                 for (int r = 0; r < 4; ++r) { accH[r] = 0; accL[r] = 0; } }
; #pragma unroll
;             for (int tp = 0; tp < 2; ++tp) {
;                 const v2i ao = TR4(ATL + (2 * q + tp) * 128 + 8 * s16), ah = TR4(ATL + 1024 + (2 * q + tp) * 128 + 8 * s16);
; #pragma unroll
;                 for (int r = 0; r < 4; ++r) {
;                     const v2i d = TR4(ldsb + BUF[st % 3] + 2048 * tp + roff[r]);
;                     accH[r] = __builtin_amdgcn_sdot8(d.x, ah.x, accH[r], false); accH[r] = __builtin_amdgcn_sdot8(d.y, ah.y, accH[r], false);
;                     accL[r] = __builtin_amdgcn_sdot8(d.x, ao.x, accL[r], false); accL[r] = __builtin_amdgcn_sdot8(d.y, ao.y, accL[r], false);
;                 }
;             }
;             asm volatile("s_waitcnt lgkmcnt(0)" ::: "memory");
;             if (q == 3) {
; #pragma unroll
;                 for (int r = 0; r < 4; ++r) STASH[256 * p + 16 * (grp + 4 * r) + pc] = f2bf(asc * (float)(2 * ((accH[r] << 4) + accL[r]) + sa));
	v_lshlrev_b32_e32 v38, 5, v38
	v_lshlrev_b32_e32 v39, 1, v39
	v_add3_u32 v38, v39, v229, v38
	v_cvt_f32_i32_e32 v38, v38
	v_mul_f32_e32 v38, v228, v38
	v_lshlrev_b32_e32 v40, 5, v40
	v_lshlrev_b32_e32 v41, 1, v41
	v_add3_u32 v40, v41, v229, v40
	v_cvt_f32_i32_e32 v40, v40
	v_mul_f32_e32 v40, v228, v40
	v_lshlrev_b32_e32 v42, 5, v42
	v_lshlrev_b32_e32 v43, 1, v43
	v_add3_u32 v42, v43, v229, v42
	v_cvt_f32_i32_e32 v42, v42
	v_mul_f32_e32 v42, v228, v42
	v_lshlrev_b32_e32 v44, 5, v44
	v_lshlrev_b32_e32 v45, 1, v45
	v_add3_u32 v44, v45, v229, v44
	v_cvt_f32_i32_e32 v44, v44
	v_mul_f32_e32 v44, v228, v44
	v_cvt_pk_bf16_f32 v162, v38, v40
	v_cvt_pk_bf16_f32 v163, v42, v44
	v_add_u32_e32 v147, 8, v140
	v_and_b32_e32 v146, 15, v147
	v_xor_b32_e32 v146, 8, v146
	v_bfe_u32 v148, v147, 4, 4
	v_mul_lo_u32 v146, v146, s92
	v_mul_lo_u32 v148, v148, s92
	v_mov_b32_e32 v147, v146
	v_mov_b32_e32 v149, v148
	ds_write2st64_b64 v77, v[146:147], v[148:149] offset1:2
	v_mov_b32_e32 v138, v74
	ds_read_u8 v139, v138
	v_mov_b32_e32 v141, v73
	ds_read_u8 v140, v141
	s_add_i32 s43, s67, 32
	v_mov_b32_e32 v138, s43
	ds_read2st64_b32 v[228:229], v138 offset1:1
	ds_read_b128 v[18:21], v227
	ds_read_b128 v[22:25], v227 offset:16
	v_add_u32_e32 v152, 0x200000, v63
	v_add_u32_e32 v153, 0x200000, v64
	v_mov_b32_e32 v38, 0
	v_mov_b32_e32 v39, 0
	v_mov_b32_e32 v40, 0
	v_mov_b32_e32 v41, 0
	v_mov_b32_e32 v42, 0
	v_mov_b32_e32 v43, 0
	v_mov_b32_e32 v44, 0
	v_mov_b32_e32 v45, 0
	v_and_b32_e32 v78, 0xffff, v31
	v_lshrrev_b32_e32 v79, 16, v31
	v_lshl_add_u32 v78, v78, 7, v150
	v_lshl_add_u32 v79, v79, 7, v151
	s_mov_b32 m0, s77
	s_add_i32 s43, s77, 0x400
	global_load_lds_dwordx4 v78, s[50:51]
	s_mov_b32 m0, s43
	s_nop 0
	global_load_lds_dwordx4 v79, s[50:51]
	s_waitcnt vmcnt(8)
	v_add_u32_e32 v54, s79, v59
	v_add_u32_e32 v55, s79, v60
	v_add_u32_e32 v56, s79, v61
	v_add_u32_e32 v57, s79, v62
	ds_read_b64_tr_b4 v[50:51], v160 offset:128
	ds_read_b64_tr_b4 v[52:53], v160 offset:1152
	ds_read_b64_tr_b4 v[130:131], v54
	ds_read_b64_tr_b4 v[132:133], v55
	ds_read_b64_tr_b4 v[134:135], v56
	ds_read_b64_tr_b4 v[136:137], v57
	s_waitcnt lgkmcnt(12)
	v_dot8c_i32_i4_e32 v38, v122, v48
	v_dot8c_i32_i4_e32 v39, v122, v46
	v_dot8c_i32_i4_e32 v40, v124, v48
	v_dot8c_i32_i4_e32 v41, v124, v46
	v_dot8c_i32_i4_e32 v42, v126, v48
	v_dot8c_i32_i4_e32 v43, v126, v46
	v_dot8c_i32_i4_e32 v44, v128, v48
	v_dot8c_i32_i4_e32 v45, v128, v46
	v_dot8c_i32_i4_e32 v38, v123, v49
	v_dot8c_i32_i4_e32 v39, v123, v47
	v_dot8c_i32_i4_e32 v40, v125, v49
	v_dot8c_i32_i4_e32 v41, v125, v47
	v_dot8c_i32_i4_e32 v42, v127, v49
	v_dot8c_i32_i4_e32 v43, v127, v47
	v_dot8c_i32_i4_e32 v44, v129, v49
	v_dot8c_i32_i4_e32 v45, v129, v47
	v_and_b32_e32 v78, 0xffff, v32
	v_lshrrev_b32_e32 v79, 16, v32
	v_lshl_add_u32 v78, v78, 7, v150
	v_lshl_add_u32 v79, v79, 7, v151
	s_mov_b32 m0, s78
	s_add_i32 s43, s78, 0x400
	global_load_lds_dwordx4 v78, s[50:51]
	s_mov_b32 m0, s43
	s_nop 0
	global_load_lds_dwordx4 v79, s[50:51]
	s_waitcnt vmcnt(8)
	v_add_u32_e32 v54, s98, v59
	v_add_u32_e32 v55, s98, v60
	v_add_u32_e32 v56, s98, v61
	v_add_u32_e32 v57, s98, v62
	ds_read_b64_tr_b4 v[46:47], v160 offset:256
	ds_read_b64_tr_b4 v[48:49], v160 offset:1280
	ds_read_b64_tr_b4 v[122:123], v54
	ds_read_b64_tr_b4 v[124:125], v55
	ds_read_b64_tr_b4 v[126:127], v56
	ds_read_b64_tr_b4 v[128:129], v57
	s_waitcnt lgkmcnt(6)
	v_dot8c_i32_i4_e32 v38, v130, v52
	v_dot8c_i32_i4_e32 v39, v130, v50
	v_dot8c_i32_i4_e32 v40, v132, v52
	v_dot8c_i32_i4_e32 v41, v132, v50
	v_dot8c_i32_i4_e32 v42, v134, v52
	v_dot8c_i32_i4_e32 v43, v134, v50
	v_dot8c_i32_i4_e32 v44, v136, v52
	v_dot8c_i32_i4_e32 v45, v136, v50
	v_dot8c_i32_i4_e32 v38, v131, v53
	v_dot8c_i32_i4_e32 v39, v131, v51
	v_dot8c_i32_i4_e32 v40, v133, v53
	v_dot8c_i32_i4_e32 v41, v133, v51
	v_dot8c_i32_i4_e32 v42, v135, v53
	v_dot8c_i32_i4_e32 v43, v135, v51
	v_dot8c_i32_i4_e32 v44, v137, v53
	v_dot8c_i32_i4_e32 v45, v137, v51
	v_and_b32_e32 v78, 0xffff, v33
	v_lshrrev_b32_e32 v79, 16, v33
	v_lshl_add_u32 v78, v78, 7, v150
	v_lshl_add_u32 v79, v79, 7, v151
	s_mov_b32 m0, s79
	s_add_i32 s43, s79, 0x400
	global_load_lds_dwordx4 v78, s[50:51]
	s_mov_b32 m0, s43
	s_nop 0
	global_load_lds_dwordx4 v79, s[50:51]
	s_waitcnt vmcnt(8)
	v_add_u32_e32 v54, s99, v59
	v_add_u32_e32 v55, s99, v60
	v_add_u32_e32 v56, s99, v61
	v_add_u32_e32 v57, s99, v62
	ds_read_b64_tr_b4 v[50:51], v160 offset:384
	ds_read_b64_tr_b4 v[52:53], v160 offset:1408
	ds_read_b64_tr_b4 v[130:131], v54
	ds_read_b64_tr_b4 v[132:133], v55
	ds_read_b64_tr_b4 v[134:135], v56
	ds_read_b64_tr_b4 v[136:137], v57
	s_waitcnt lgkmcnt(6)
	v_dot8c_i32_i4_e32 v38, v122, v48
	v_dot8c_i32_i4_e32 v39, v122, v46
	v_dot8c_i32_i4_e32 v40, v124, v48
	v_dot8c_i32_i4_e32 v41, v124, v46
	v_dot8c_i32_i4_e32 v42, v126, v48
	v_dot8c_i32_i4_e32 v43, v126, v46
	v_dot8c_i32_i4_e32 v44, v128, v48
	v_dot8c_i32_i4_e32 v45, v128, v46
	v_dot8c_i32_i4_e32 v38, v123, v49
	v_dot8c_i32_i4_e32 v39, v123, v47
	v_dot8c_i32_i4_e32 v40, v125, v49
	v_dot8c_i32_i4_e32 v41, v125, v47
	v_dot8c_i32_i4_e32 v42, v127, v49
	v_dot8c_i32_i4_e32 v43, v127, v47
	v_dot8c_i32_i4_e32 v44, v129, v49
	v_dot8c_i32_i4_e32 v45, v129, v47
	s_waitcnt lgkmcnt(15)
	v_and_b32_e32 v78, 0xffff, v18
	v_lshrrev_b32_e32 v79, 16, v18
	v_lshl_add_u32 v78, v78, 7, v152
	v_lshl_add_u32 v79, v79, 7, v153
	s_mov_b32 m0, s98
	s_add_i32 s43, s98, 0x400
	global_load_lds_dwordx4 v78, s[50:51]
	s_mov_b32 m0, s43
	s_nop 0
	global_load_lds_dwordx4 v79, s[50:51]
	s_waitcnt vmcnt(8)
; #define TR4(p_) __builtin_amdgcn_ds_read_tr4_b64_v2i32((LAS v2i*)(p_))
; #define VDMA(st_, k_) do { _Pragma("unroll") for (int i_ = 0; i_ < 4; ++i_) { \
;         const unsigned off_ = (unsigned)((st_) >> 2) * (16384u * 128u) + (PE_ID(E, 4 * ((st_) & 3) + i_) << 7) + ((i_ & 1) ? cx1 : cx0); \
;         __builtin_amdgcn_global_load_lds((const unsigned*)(V4 + off_), (LAS unsigned*)(ldsb + BUF[k_] + 1024 * i_), 16, 0, 0); } } while (0)
; __device__ __forceinline__ void peer_v_tokens(int j, const LAS unsigned short* EL, const LAS unsigned char* AL  , const LAS float* ASC  , const LAS int* SAL  , ...
;     ...
;         for (int st = 0; st < 16; ++st) {
;             const int p = st >> 2, q = st & 3;
;             if (st < 14) VDMA(st + 2, (st + 2) % 3);
;             if (st < 14) asm volatile("s_waitcnt vmcnt(8)" ::: "memory");
;             else if (st == 14) asm volatile("s_waitcnt vmcnt(4)" ::: "memory");
;             else asm volatile("s_waitcnt vmcnt(0)" ::: "memory");
;             if (q == 0) {
; #pragma unroll
;                 for (int r = 0; r < 4; ++r) { accH[r] = 0; accL[r] = 0; } }
; #pragma unroll
;             for (int tp = 0; tp < 2; ++tp) {
;                 const v2i ao = TR4(ATL + (2 * q + tp) * 128 + 8 * s16), ah = TR4(ATL + 1024 + (2 * q + tp) * 128 + 8 * s16);
; #pragma unroll
;                 for (int r = 0; r < 4; ++r) {
;                     const v2i d = TR4(ldsb + BUF[st % 3] + 2048 * tp + roff[r]);
;                     accH[r] = __builtin_amdgcn_sdot8(d.x, ah.x, accH[r], false); accH[r] = __builtin_amdgcn_sdot8(d.y, ah.y, accH[r], false);
;                     accL[r] = __builtin_amdgcn_sdot8(d.x, ao.x, accL[r], false); accL[r] = __builtin_amdgcn_sdot8(d.y, ao.y, accL[r], false);
;                 }
;             }
	v_add_u32_e32 v54, s76, v59
	v_add_u32_e32 v55, s76, v60
	v_add_u32_e32 v56, s76, v61
	v_add_u32_e32 v57, s76, v62
	ds_read_b64_tr_b4 v[46:47], v160 offset:512
	ds_read_b64_tr_b4 v[48:49], v160 offset:1536
	ds_read_b64_tr_b4 v[122:123], v54
	ds_read_b64_tr_b4 v[124:125], v55
	ds_read_b64_tr_b4 v[126:127], v56
	ds_read_b64_tr_b4 v[128:129], v57
	s_waitcnt lgkmcnt(6)
	v_dot8c_i32_i4_e32 v38, v130, v52
	v_dot8c_i32_i4_e32 v39, v130, v50
	v_dot8c_i32_i4_e32 v40, v132, v52
	v_dot8c_i32_i4_e32 v41, v132, v50
	v_dot8c_i32_i4_e32 v42, v134, v52
	v_dot8c_i32_i4_e32 v43, v134, v50
	v_dot8c_i32_i4_e32 v44, v136, v52
	v_dot8c_i32_i4_e32 v45, v136, v50
	v_dot8c_i32_i4_e32 v38, v131, v53
	v_dot8c_i32_i4_e32 v39, v131, v51
	v_dot8c_i32_i4_e32 v40, v133, v53
	v_dot8c_i32_i4_e32 v41, v133, v51
	v_dot8c_i32_i4_e32 v42, v135, v53
	v_dot8c_i32_i4_e32 v43, v135, v51
	v_dot8c_i32_i4_e32 v44, v137, v53
	v_dot8c_i32_i4_e32 v45, v137, v51
	v_and_b32_e32 v78, 0xffff, v19
	v_lshrrev_b32_e32 v79, 16, v19
	v_lshl_add_u32 v78, v78, 7, v152
	v_lshl_add_u32 v79, v79, 7, v153
	s_mov_b32 m0, s99
	s_add_i32 s43, s99, 0x400
	global_load_lds_dwordx4 v78, s[50:51]
	s_mov_b32 m0, s43
	s_nop 0
	global_load_lds_dwordx4 v79, s[50:51]
	s_waitcnt vmcnt(8)
	v_add_u32_e32 v54, s77, v59
	v_add_u32_e32 v55, s77, v60
	v_add_u32_e32 v56, s77, v61
	v_add_u32_e32 v57, s77, v62
	ds_read_b64_tr_b4 v[50:51], v160 offset:640
	ds_read_b64_tr_b4 v[52:53], v160 offset:1664
	ds_read_b64_tr_b4 v[130:131], v54
	ds_read_b64_tr_b4 v[132:133], v55
	ds_read_b64_tr_b4 v[134:135], v56
	ds_read_b64_tr_b4 v[136:137], v57
	s_waitcnt lgkmcnt(6)
	v_dot8c_i32_i4_e32 v38, v122, v48
	v_dot8c_i32_i4_e32 v39, v122, v46
	v_dot8c_i32_i4_e32 v40, v124, v48
	v_dot8c_i32_i4_e32 v41, v124, v46
	v_dot8c_i32_i4_e32 v42, v126, v48
	v_dot8c_i32_i4_e32 v43, v126, v46
	v_dot8c_i32_i4_e32 v44, v128, v48
	v_dot8c_i32_i4_e32 v45, v128, v46
	v_dot8c_i32_i4_e32 v38, v123, v49
	v_dot8c_i32_i4_e32 v39, v123, v47
	v_dot8c_i32_i4_e32 v40, v125, v49
	v_dot8c_i32_i4_e32 v41, v125, v47
	v_dot8c_i32_i4_e32 v42, v127, v49
	v_dot8c_i32_i4_e32 v43, v127, v47
	v_dot8c_i32_i4_e32 v44, v129, v49
	v_dot8c_i32_i4_e32 v45, v129, v47
	s_waitcnt lgkmcnt(15)
	v_add_u32_e32 v143, 8, v139
	v_and_b32_e32 v142, 15, v143
	v_xor_b32_e32 v142, 8, v142
	v_bfe_u32 v144, v143, 4, 4
	v_mul_lo_u32 v142, v142, s92
	v_mul_lo_u32 v144, v144, s92
	v_mov_b32_e32 v143, v142
	v_mov_b32_e32 v145, v144
	ds_write2st64_b64 v159, v[142:143], v[144:145] offset1:2
	v_and_b32_e32 v78, 0xffff, v20
	v_lshrrev_b32_e32 v79, 16, v20
	v_lshl_add_u32 v78, v78, 7, v152
	v_lshl_add_u32 v79, v79, 7, v153
	s_mov_b32 m0, s76
	s_add_i32 s43, s76, 0x400
	global_load_lds_dwordx4 v78, s[50:51]
	s_mov_b32 m0, s43
	s_nop 0
	global_load_lds_dwordx4 v79, s[50:51]
	s_waitcnt vmcnt(8)
	v_add_u32_e32 v54, s78, v59
	v_add_u32_e32 v55, s78, v60
	v_add_u32_e32 v56, s78, v61
	v_add_u32_e32 v57, s78, v62
	ds_read_b64_tr_b4 v[46:47], v160 offset:768
	ds_read_b64_tr_b4 v[48:49], v160 offset:1792
	ds_read_b64_tr_b4 v[122:123], v54
	ds_read_b64_tr_b4 v[124:125], v55
	ds_read_b64_tr_b4 v[126:127], v56
	ds_read_b64_tr_b4 v[128:129], v57
	s_waitcnt lgkmcnt(7)
	v_dot8c_i32_i4_e32 v38, v130, v52
	v_dot8c_i32_i4_e32 v39, v130, v50
	v_dot8c_i32_i4_e32 v40, v132, v52
	v_dot8c_i32_i4_e32 v41, v132, v50
	v_dot8c_i32_i4_e32 v42, v134, v52
	v_dot8c_i32_i4_e32 v43, v134, v50
	v_dot8c_i32_i4_e32 v44, v136, v52
	v_dot8c_i32_i4_e32 v45, v136, v50
	v_dot8c_i32_i4_e32 v38, v131, v53
	v_dot8c_i32_i4_e32 v39, v131, v51
	v_dot8c_i32_i4_e32 v40, v133, v53
	v_dot8c_i32_i4_e32 v41, v133, v51
	v_dot8c_i32_i4_e32 v42, v135, v53
	v_dot8c_i32_i4_e32 v43, v135, v51
	v_dot8c_i32_i4_e32 v44, v137, v53
	v_dot8c_i32_i4_e32 v45, v137, v51
	v_and_b32_e32 v78, 0xffff, v21
	v_lshrrev_b32_e32 v79, 16, v21
	v_lshl_add_u32 v78, v78, 7, v152
	v_lshl_add_u32 v79, v79, 7, v153
	s_mov_b32 m0, s77
	s_add_i32 s43, s77, 0x400
	global_load_lds_dwordx4 v78, s[50:51]
	s_mov_b32 m0, s43
	s_nop 0
	global_load_lds_dwordx4 v79, s[50:51]
	s_waitcnt vmcnt(8)
	v_add_u32_e32 v54, s79, v59
	v_add_u32_e32 v55, s79, v60
	v_add_u32_e32 v56, s79, v61
	v_add_u32_e32 v57, s79, v62
	ds_read_b64_tr_b4 v[50:51], v160 offset:896
	ds_read_b64_tr_b4 v[52:53], v160 offset:1920
	ds_read_b64_tr_b4 v[130:131], v54
	ds_read_b64_tr_b4 v[132:133], v55
	ds_read_b64_tr_b4 v[134:135], v56
	ds_read_b64_tr_b4 v[136:137], v57
	s_waitcnt lgkmcnt(6)
	v_dot8c_i32_i4_e32 v38, v122, v48
	v_dot8c_i32_i4_e32 v39, v122, v46
	v_dot8c_i32_i4_e32 v40, v124, v48
	v_dot8c_i32_i4_e32 v41, v124, v46
	v_dot8c_i32_i4_e32 v42, v126, v48
	v_dot8c_i32_i4_e32 v43, v126, v46
	v_dot8c_i32_i4_e32 v44, v128, v48
	v_dot8c_i32_i4_e32 v45, v128, v46
	v_dot8c_i32_i4_e32 v38, v123, v49
	v_dot8c_i32_i4_e32 v39, v123, v47
	v_dot8c_i32_i4_e32 v40, v125, v49
	v_dot8c_i32_i4_e32 v41, v125, v47
	v_dot8c_i32_i4_e32 v42, v127, v49
	v_dot8c_i32_i4_e32 v43, v127, v47
	v_dot8c_i32_i4_e32 v44, v129, v49
	v_dot8c_i32_i4_e32 v45, v129, v47
	v_and_b32_e32 v78, 0xffff, v22
	v_lshrrev_b32_e32 v79, 16, v22
	v_lshl_add_u32 v78, v78, 7, v152
	v_lshl_add_u32 v79, v79, 7, v153
	s_mov_b32 m0, s78
	s_add_i32 s43, s78, 0x400
	global_load_lds_dwordx4 v78, s[50:51]
	s_mov_b32 m0, s43
	s_nop 0
	global_load_lds_dwordx4 v79, s[50:51]
	s_waitcnt vmcnt(8)
	v_add_u32_e32 v54, s98, v59
	v_add_u32_e32 v55, s98, v60
	v_add_u32_e32 v56, s98, v61
	v_add_u32_e32 v57, s98, v62
	ds_read_b64_tr_b4 v[46:47], v160
	ds_read_b64_tr_b4 v[48:49], v160 offset:1024
	ds_read_b64_tr_b4 v[122:123], v54
	ds_read_b64_tr_b4 v[124:125], v55
	ds_read_b64_tr_b4 v[126:127], v56
	ds_read_b64_tr_b4 v[128:129], v57
	s_waitcnt lgkmcnt(6)
; __device__ __forceinline__ bf16 f2bf(float f) { return (bf16)f2bfu(f); }
; #define TR4(p_) __builtin_amdgcn_ds_read_tr4_b64_v2i32((LAS v2i*)(p_))
; #define VDMA(st_, k_) do { _Pragma("unroll") for (int i_ = 0; i_ < 4; ++i_) { \
;         const unsigned off_ = (unsigned)((st_) >> 2) * (16384u * 128u) + (PE_ID(E, 4 * ((st_) & 3) + i_) << 7) + ((i_ & 1) ? cx1 : cx0); \
;         __builtin_amdgcn_global_load_lds((const unsigned*)(V4 + off_), (LAS unsigned*)(ldsb + BUF[k_] + 1024 * i_), 16, 0, 0); } } while (0)
; __device__ __forceinline__ void peer_v_tokens(int j, const LAS unsigned short* EL, const LAS unsigned char* AL  , const LAS float* ASC  , const LAS int* SAL  , ...
;     ...
;         for (int st = 0; st < 16; ++st) {
;             const int p = st >> 2, q = st & 3;
;             if (st < 14) VDMA(st + 2, (st + 2) % 3);
;             if (st < 14) asm volatile("s_waitcnt vmcnt(8)" ::: "memory");
;             else if (st == 14) asm volatile("s_waitcnt vmcnt(4)" ::: "memory");
;             else asm volatile("s_waitcnt vmcnt(0)" ::: "memory");
;             if (q == 0) {
; #pragma unroll
;                 for (int r = 0; r < 4; ++r) { accH[r] = 0; accL[r] = 0; } }
; #pragma unroll
;             for (int tp = 0; tp < 2; ++tp) {
;                 const v2i ao = TR4(ATL + (2 * q + tp) * 128 + 8 * s16), ah = TR4(ATL + 1024 + (2 * q + tp) * 128 + 8 * s16);
; #pragma unroll
;                 for (int r = 0; r < 4; ++r) {
;                     const v2i d = TR4(ldsb + BUF[st % 3] + 2048 * tp + roff[r]);
;                     accH[r] = __builtin_amdgcn_sdot8(d.x, ah.x, accH[r], false); accH[r] = __builtin_amdgcn_sdot8(d.y, ah.y, accH[r], false);
;                     accL[r] = __builtin_amdgcn_sdot8(d.x, ao.x, accL[r], false); accL[r] = __builtin_amdgcn_sdot8(d.y, ao.y, accL[r], false);
;                 }
;             }
;             asm volatile("s_waitcnt lgkmcnt(0)" ::: "memory");
;             if (q == 3) {
; #pragma unroll
;                 for (int r = 0; r < 4; ++r) STASH[256 * p + 16 * (grp + 4 * r) + pc] = f2bf(asc * (float)(2 * ((accH[r] << 4) + accL[r]) + sa));
	v_dot8c_i32_i4_e32 v38, v130, v52
	v_dot8c_i32_i4_e32 v39, v130, v50
	v_dot8c_i32_i4_e32 v40, v132, v52
	v_dot8c_i32_i4_e32 v41, v132, v50
	v_dot8c_i32_i4_e32 v42, v134, v52
	v_dot8c_i32_i4_e32 v43, v134, v50
	v_dot8c_i32_i4_e32 v44, v136, v52
	v_dot8c_i32_i4_e32 v45, v136, v50
	v_dot8c_i32_i4_e32 v38, v131, v53
	v_dot8c_i32_i4_e32 v39, v131, v51
	v_dot8c_i32_i4_e32 v40, v133, v53
	v_dot8c_i32_i4_e32 v41, v133, v51
	v_dot8c_i32_i4_e32 v42, v135, v53
	v_dot8c_i32_i4_e32 v43, v135, v51
	v_dot8c_i32_i4_e32 v44, v137, v53
	v_dot8c_i32_i4_e32 v45, v137, v51
	s_nop 3
	s_waitcnt lgkmcnt(15)
	v_lshlrev_b32_e32 v38, 5, v38
	v_lshlrev_b32_e32 v39, 1, v39
	v_add3_u32 v38, v39, v229, v38
	v_cvt_f32_i32_e32 v38, v38
	v_mul_f32_e32 v38, v228, v38
	v_lshlrev_b32_e32 v40, 5, v40
	v_lshlrev_b32_e32 v41, 1, v41
	v_add3_u32 v40, v41, v229, v40
	v_cvt_f32_i32_e32 v40, v40
	v_mul_f32_e32 v40, v228, v40
	v_lshlrev_b32_e32 v42, 5, v42
	v_lshlrev_b32_e32 v43, 1, v43
	v_add3_u32 v42, v43, v229, v42
	v_cvt_f32_i32_e32 v42, v42
	v_mul_f32_e32 v42, v228, v42
	v_lshlrev_b32_e32 v44, 5, v44
	v_lshlrev_b32_e32 v45, 1, v45
	v_add3_u32 v44, v45, v229, v44
	v_cvt_f32_i32_e32 v44, v44
	v_mul_f32_e32 v44, v228, v44
	v_cvt_pk_bf16_f32 v170, v38, v40
	v_cvt_pk_bf16_f32 v171, v42, v44
	v_add_u32_e32 v147, 8, v140
	v_and_b32_e32 v146, 15, v147
	v_xor_b32_e32 v146, 8, v146
	v_bfe_u32 v148, v147, 4, 4
	v_mul_lo_u32 v146, v146, s92
	v_mul_lo_u32 v148, v148, s92
	v_mov_b32_e32 v147, v146
	v_mov_b32_e32 v149, v148
	ds_write2st64_b64 v77, v[146:147], v[148:149] offset1:2
	v_add_u32_e32 v138, 0x400, v74
	ds_read_u8 v139, v138
	v_add_u32_e32 v141, 0x400, v73
	ds_read_u8 v140, v141
	s_mov_b32 s43, s67
	v_mov_b32_e32 v138, s43
	ds_read2st64_b32 v[228:229], v138 offset1:1
	ds_read_b128 v[26:29], v227 offset:2048
	ds_read_b128 v[30:33], v227 offset:2064
	v_mov_b32_e32 v38, 0
	v_mov_b32_e32 v39, 0
	v_mov_b32_e32 v40, 0
	v_mov_b32_e32 v41, 0
	v_mov_b32_e32 v42, 0
	v_mov_b32_e32 v43, 0
	v_mov_b32_e32 v44, 0
	v_mov_b32_e32 v45, 0
	v_and_b32_e32 v78, 0xffff, v23
	v_lshrrev_b32_e32 v79, 16, v23
	v_lshl_add_u32 v78, v78, 7, v152
	v_lshl_add_u32 v79, v79, 7, v153
	s_mov_b32 m0, s79
	s_add_i32 s43, s79, 0x400
	global_load_lds_dwordx4 v78, s[50:51]
	s_mov_b32 m0, s43
	s_nop 0
	global_load_lds_dwordx4 v79, s[50:51]
	s_waitcnt vmcnt(8)
	v_add_u32_e32 v54, s99, v59
	v_add_u32_e32 v55, s99, v60
	v_add_u32_e32 v56, s99, v61
	v_add_u32_e32 v57, s99, v62
	ds_read_b64_tr_b4 v[50:51], v160 offset:128
	ds_read_b64_tr_b4 v[52:53], v160 offset:1152
	ds_read_b64_tr_b4 v[130:131], v54
	ds_read_b64_tr_b4 v[132:133], v55
	ds_read_b64_tr_b4 v[134:135], v56
	ds_read_b64_tr_b4 v[136:137], v57
	s_waitcnt lgkmcnt(12)
	v_dot8c_i32_i4_e32 v38, v122, v48
	v_dot8c_i32_i4_e32 v39, v122, v46
	v_dot8c_i32_i4_e32 v40, v124, v48
	v_dot8c_i32_i4_e32 v41, v124, v46
	v_dot8c_i32_i4_e32 v42, v126, v48
	v_dot8c_i32_i4_e32 v43, v126, v46
	v_dot8c_i32_i4_e32 v44, v128, v48
	v_dot8c_i32_i4_e32 v45, v128, v46
	v_dot8c_i32_i4_e32 v38, v123, v49
	v_dot8c_i32_i4_e32 v39, v123, v47
	v_dot8c_i32_i4_e32 v40, v125, v49
	v_dot8c_i32_i4_e32 v41, v125, v47
	v_dot8c_i32_i4_e32 v42, v127, v49
	v_dot8c_i32_i4_e32 v43, v127, v47
	v_dot8c_i32_i4_e32 v44, v129, v49
	v_dot8c_i32_i4_e32 v45, v129, v47
	v_and_b32_e32 v78, 0xffff, v24
	v_lshrrev_b32_e32 v79, 16, v24
	v_lshl_add_u32 v78, v78, 7, v152
	v_lshl_add_u32 v79, v79, 7, v153
	s_mov_b32 m0, s98
	s_add_i32 s43, s98, 0x400
	global_load_lds_dwordx4 v78, s[50:51]
	s_mov_b32 m0, s43
	s_nop 0
	global_load_lds_dwordx4 v79, s[50:51]
	s_waitcnt vmcnt(8)
	v_add_u32_e32 v54, s76, v59
	v_add_u32_e32 v55, s76, v60
	v_add_u32_e32 v56, s76, v61
	v_add_u32_e32 v57, s76, v62
	ds_read_b64_tr_b4 v[46:47], v160 offset:256
	ds_read_b64_tr_b4 v[48:49], v160 offset:1280
	ds_read_b64_tr_b4 v[122:123], v54
	ds_read_b64_tr_b4 v[124:125], v55
	ds_read_b64_tr_b4 v[126:127], v56
	ds_read_b64_tr_b4 v[128:129], v57
	s_waitcnt lgkmcnt(6)
	v_dot8c_i32_i4_e32 v38, v130, v52
	v_dot8c_i32_i4_e32 v39, v130, v50
	v_dot8c_i32_i4_e32 v40, v132, v52
	v_dot8c_i32_i4_e32 v41, v132, v50
	v_dot8c_i32_i4_e32 v42, v134, v52
	v_dot8c_i32_i4_e32 v43, v134, v50
	v_dot8c_i32_i4_e32 v44, v136, v52
	v_dot8c_i32_i4_e32 v45, v136, v50
	v_dot8c_i32_i4_e32 v38, v131, v53
	v_dot8c_i32_i4_e32 v39, v131, v51
	v_dot8c_i32_i4_e32 v40, v133, v53
	v_dot8c_i32_i4_e32 v41, v133, v51
	v_dot8c_i32_i4_e32 v42, v135, v53
	v_dot8c_i32_i4_e32 v43, v135, v51
	v_dot8c_i32_i4_e32 v44, v137, v53
	v_dot8c_i32_i4_e32 v45, v137, v51
	v_and_b32_e32 v78, 0xffff, v25
	v_lshrrev_b32_e32 v79, 16, v25
	v_lshl_add_u32 v78, v78, 7, v152
	v_lshl_add_u32 v79, v79, 7, v153
	s_mov_b32 m0, s99
	s_add_i32 s43, s99, 0x400
	global_load_lds_dwordx4 v78, s[50:51]
	s_mov_b32 m0, s43
	s_nop 0
	global_load_lds_dwordx4 v79, s[50:51]
	s_waitcnt vmcnt(8)
	v_add_u32_e32 v54, s77, v59
	v_add_u32_e32 v55, s77, v60
	v_add_u32_e32 v56, s77, v61
	v_add_u32_e32 v57, s77, v62
	ds_read_b64_tr_b4 v[50:51], v160 offset:384
	ds_read_b64_tr_b4 v[52:53], v160 offset:1408
	ds_read_b64_tr_b4 v[130:131], v54
	ds_read_b64_tr_b4 v[132:133], v55
	ds_read_b64_tr_b4 v[134:135], v56
	ds_read_b64_tr_b4 v[136:137], v57
	s_waitcnt lgkmcnt(6)
	v_dot8c_i32_i4_e32 v38, v122, v48
	v_dot8c_i32_i4_e32 v39, v122, v46
	v_dot8c_i32_i4_e32 v40, v124, v48
	v_dot8c_i32_i4_e32 v41, v124, v46
	v_dot8c_i32_i4_e32 v42, v126, v48
	v_dot8c_i32_i4_e32 v43, v126, v46
	v_dot8c_i32_i4_e32 v44, v128, v48
	v_dot8c_i32_i4_e32 v45, v128, v46
	v_dot8c_i32_i4_e32 v38, v123, v49
	v_dot8c_i32_i4_e32 v39, v123, v47
	v_dot8c_i32_i4_e32 v40, v125, v49
	v_dot8c_i32_i4_e32 v41, v125, v47
	v_dot8c_i32_i4_e32 v42, v127, v49
	v_dot8c_i32_i4_e32 v43, v127, v47
	v_dot8c_i32_i4_e32 v44, v129, v49
	v_dot8c_i32_i4_e32 v45, v129, v47
	s_waitcnt lgkmcnt(15)
; #define TR4(p_) __builtin_amdgcn_ds_read_tr4_b64_v2i32((LAS v2i*)(p_))
; #define VDMA(st_, k_) do { _Pragma("unroll") for (int i_ = 0; i_ < 4; ++i_) { \
;         const unsigned off_ = (unsigned)((st_) >> 2) * (16384u * 128u) + (PE_ID(E, 4 * ((st_) & 3) + i_) << 7) + ((i_ & 1) ? cx1 : cx0); \
;         __builtin_amdgcn_global_load_lds((const unsigned*)(V4 + off_), (LAS unsigned*)(ldsb + BUF[k_] + 1024 * i_), 16, 0, 0); } } while (0)
; __device__ __forceinline__ void peer_v_tokens(int j, const LAS unsigned short* EL, const LAS unsigned char* AL  , const LAS float* ASC  , const LAS int* SAL  , ...
;     ...
;         for (int st = 0; st < 16; ++st) {
;             const int p = st >> 2, q = st & 3;
;             if (st < 14) VDMA(st + 2, (st + 2) % 3);
;             if (st < 14) asm volatile("s_waitcnt vmcnt(8)" ::: "memory");
;             else if (st == 14) asm volatile("s_waitcnt vmcnt(4)" ::: "memory");
;             else asm volatile("s_waitcnt vmcnt(0)" ::: "memory");
;             if (q == 0) {
; #pragma unroll
;                 for (int r = 0; r < 4; ++r) { accH[r] = 0; accL[r] = 0; } }
; #pragma unroll
;             for (int tp = 0; tp < 2; ++tp) {
;                 const v2i ao = TR4(ATL + (2 * q + tp) * 128 + 8 * s16), ah = TR4(ATL + 1024 + (2 * q + tp) * 128 + 8 * s16);
; #pragma unroll
;                 for (int r = 0; r < 4; ++r) {
;                     const v2i d = TR4(ldsb + BUF[st % 3] + 2048 * tp + roff[r]);
;                     accH[r] = __builtin_amdgcn_sdot8(d.x, ah.x, accH[r], false); accH[r] = __builtin_amdgcn_sdot8(d.y, ah.y, accH[r], false);
;                     accL[r] = __builtin_amdgcn_sdot8(d.x, ao.x, accL[r], false); accL[r] = __builtin_amdgcn_sdot8(d.y, ao.y, accL[r], false);
;                 }
;             }
	v_and_b32_e32 v78, 0xffff, v26
	v_lshrrev_b32_e32 v79, 16, v26
	v_lshl_add_u32 v78, v78, 7, v152
	v_lshl_add_u32 v79, v79, 7, v153
	s_mov_b32 m0, s76
	s_add_i32 s43, s76, 0x400
	global_load_lds_dwordx4 v78, s[50:51]
	s_mov_b32 m0, s43
	s_nop 0
	global_load_lds_dwordx4 v79, s[50:51]
	s_waitcnt vmcnt(8)
	v_add_u32_e32 v54, s78, v59
	v_add_u32_e32 v55, s78, v60
	v_add_u32_e32 v56, s78, v61
	v_add_u32_e32 v57, s78, v62
	ds_read_b64_tr_b4 v[46:47], v160 offset:512
	ds_read_b64_tr_b4 v[48:49], v160 offset:1536
	ds_read_b64_tr_b4 v[122:123], v54
	ds_read_b64_tr_b4 v[124:125], v55
	ds_read_b64_tr_b4 v[126:127], v56
	ds_read_b64_tr_b4 v[128:129], v57
	s_waitcnt lgkmcnt(6)
	v_dot8c_i32_i4_e32 v38, v130, v52
	v_dot8c_i32_i4_e32 v39, v130, v50
	v_dot8c_i32_i4_e32 v40, v132, v52
	v_dot8c_i32_i4_e32 v41, v132, v50
	v_dot8c_i32_i4_e32 v42, v134, v52
	v_dot8c_i32_i4_e32 v43, v134, v50
	v_dot8c_i32_i4_e32 v44, v136, v52
	v_dot8c_i32_i4_e32 v45, v136, v50
	v_dot8c_i32_i4_e32 v38, v131, v53
	v_dot8c_i32_i4_e32 v39, v131, v51
	v_dot8c_i32_i4_e32 v40, v133, v53
	v_dot8c_i32_i4_e32 v41, v133, v51
	v_dot8c_i32_i4_e32 v42, v135, v53
	v_dot8c_i32_i4_e32 v43, v135, v51
	v_dot8c_i32_i4_e32 v44, v137, v53
	v_dot8c_i32_i4_e32 v45, v137, v51
	v_and_b32_e32 v78, 0xffff, v27
	v_lshrrev_b32_e32 v79, 16, v27
	v_lshl_add_u32 v78, v78, 7, v152
	v_lshl_add_u32 v79, v79, 7, v153
	s_mov_b32 m0, s77
	s_add_i32 s43, s77, 0x400
	global_load_lds_dwordx4 v78, s[50:51]
	s_mov_b32 m0, s43
	s_nop 0
	global_load_lds_dwordx4 v79, s[50:51]
	s_waitcnt vmcnt(8)
	v_add_u32_e32 v54, s79, v59
	v_add_u32_e32 v55, s79, v60
	v_add_u32_e32 v56, s79, v61
	v_add_u32_e32 v57, s79, v62
	ds_read_b64_tr_b4 v[50:51], v160 offset:640
	ds_read_b64_tr_b4 v[52:53], v160 offset:1664
	ds_read_b64_tr_b4 v[130:131], v54
	ds_read_b64_tr_b4 v[132:133], v55
	ds_read_b64_tr_b4 v[134:135], v56
	ds_read_b64_tr_b4 v[136:137], v57
	s_waitcnt lgkmcnt(6)
	v_dot8c_i32_i4_e32 v38, v122, v48
	v_dot8c_i32_i4_e32 v39, v122, v46
	v_dot8c_i32_i4_e32 v40, v124, v48
	v_dot8c_i32_i4_e32 v41, v124, v46
	v_dot8c_i32_i4_e32 v42, v126, v48
	v_dot8c_i32_i4_e32 v43, v126, v46
	v_dot8c_i32_i4_e32 v44, v128, v48
	v_dot8c_i32_i4_e32 v45, v128, v46
	v_dot8c_i32_i4_e32 v38, v123, v49
	v_dot8c_i32_i4_e32 v39, v123, v47
	v_dot8c_i32_i4_e32 v40, v125, v49
	v_dot8c_i32_i4_e32 v41, v125, v47
	v_dot8c_i32_i4_e32 v42, v127, v49
	v_dot8c_i32_i4_e32 v43, v127, v47
	v_dot8c_i32_i4_e32 v44, v129, v49
	v_dot8c_i32_i4_e32 v45, v129, v47
	s_waitcnt lgkmcnt(15)
	v_add_u32_e32 v143, 8, v139
	v_and_b32_e32 v142, 15, v143
	v_xor_b32_e32 v142, 8, v142
	v_bfe_u32 v144, v143, 4, 4
	v_mul_lo_u32 v142, v142, s92
	v_mul_lo_u32 v144, v144, s92
	v_mov_b32_e32 v143, v142
	v_mov_b32_e32 v145, v144
	ds_write2st64_b64 v159, v[142:143], v[144:145] offset1:2
	v_and_b32_e32 v78, 0xffff, v28
	v_lshrrev_b32_e32 v79, 16, v28
	v_lshl_add_u32 v78, v78, 7, v152
	v_lshl_add_u32 v79, v79, 7, v153
	s_mov_b32 m0, s78
	s_add_i32 s43, s78, 0x400
	global_load_lds_dwordx4 v78, s[50:51]
	s_mov_b32 m0, s43
	s_nop 0
	global_load_lds_dwordx4 v79, s[50:51]
	s_waitcnt vmcnt(8)
	v_add_u32_e32 v54, s98, v59
	v_add_u32_e32 v55, s98, v60
	v_add_u32_e32 v56, s98, v61
	v_add_u32_e32 v57, s98, v62
	ds_read_b64_tr_b4 v[46:47], v160 offset:768
	ds_read_b64_tr_b4 v[48:49], v160 offset:1792
	ds_read_b64_tr_b4 v[122:123], v54
	ds_read_b64_tr_b4 v[124:125], v55
	ds_read_b64_tr_b4 v[126:127], v56
	ds_read_b64_tr_b4 v[128:129], v57
	s_waitcnt lgkmcnt(7)
	v_dot8c_i32_i4_e32 v38, v130, v52
	v_dot8c_i32_i4_e32 v39, v130, v50
	v_dot8c_i32_i4_e32 v40, v132, v52
	v_dot8c_i32_i4_e32 v41, v132, v50
	v_dot8c_i32_i4_e32 v42, v134, v52
	v_dot8c_i32_i4_e32 v43, v134, v50
	v_dot8c_i32_i4_e32 v44, v136, v52
	v_dot8c_i32_i4_e32 v45, v136, v50
	v_dot8c_i32_i4_e32 v38, v131, v53
	v_dot8c_i32_i4_e32 v39, v131, v51
	v_dot8c_i32_i4_e32 v40, v133, v53
	v_dot8c_i32_i4_e32 v41, v133, v51
	v_dot8c_i32_i4_e32 v42, v135, v53
	v_dot8c_i32_i4_e32 v43, v135, v51
	v_dot8c_i32_i4_e32 v44, v137, v53
	v_dot8c_i32_i4_e32 v45, v137, v51
	v_and_b32_e32 v78, 0xffff, v29
	v_lshrrev_b32_e32 v79, 16, v29
	v_lshl_add_u32 v78, v78, 7, v152
	v_lshl_add_u32 v79, v79, 7, v153
	s_mov_b32 m0, s79
	s_add_i32 s43, s79, 0x400
	global_load_lds_dwordx4 v78, s[50:51]
	s_mov_b32 m0, s43
	s_nop 0
	global_load_lds_dwordx4 v79, s[50:51]
	s_waitcnt vmcnt(8)
	v_add_u32_e32 v54, s99, v59
	v_add_u32_e32 v55, s99, v60
	v_add_u32_e32 v56, s99, v61
	v_add_u32_e32 v57, s99, v62
	ds_read_b64_tr_b4 v[50:51], v160 offset:896
	ds_read_b64_tr_b4 v[52:53], v160 offset:1920
	ds_read_b64_tr_b4 v[130:131], v54
	ds_read_b64_tr_b4 v[132:133], v55
	ds_read_b64_tr_b4 v[134:135], v56
	ds_read_b64_tr_b4 v[136:137], v57
	s_waitcnt lgkmcnt(6)
	v_dot8c_i32_i4_e32 v38, v122, v48
	v_dot8c_i32_i4_e32 v39, v122, v46
	v_dot8c_i32_i4_e32 v40, v124, v48
	v_dot8c_i32_i4_e32 v41, v124, v46
	v_dot8c_i32_i4_e32 v42, v126, v48
	v_dot8c_i32_i4_e32 v43, v126, v46
	v_dot8c_i32_i4_e32 v44, v128, v48
	v_dot8c_i32_i4_e32 v45, v128, v46
	v_dot8c_i32_i4_e32 v38, v123, v49
	v_dot8c_i32_i4_e32 v39, v123, v47
	v_dot8c_i32_i4_e32 v40, v125, v49
	v_dot8c_i32_i4_e32 v41, v125, v47
	v_dot8c_i32_i4_e32 v42, v127, v49
	v_dot8c_i32_i4_e32 v43, v127, v47
	v_dot8c_i32_i4_e32 v44, v129, v49
	v_dot8c_i32_i4_e32 v45, v129, v47
	v_and_b32_e32 v78, 0xffff, v30
	v_lshrrev_b32_e32 v79, 16, v30
	v_lshl_add_u32 v78, v78, 7, v152
	v_lshl_add_u32 v79, v79, 7, v153
	s_mov_b32 m0, s98
	s_add_i32 s43, s98, 0x400
	global_load_lds_dwordx4 v78, s[50:51]
	s_mov_b32 m0, s43
	s_nop 0
	global_load_lds_dwordx4 v79, s[50:51]
	s_waitcnt vmcnt(8)
; __device__ __forceinline__ bf16 f2bf(float f) { return (bf16)f2bfu(f); }
; #define TR4(p_) __builtin_amdgcn_ds_read_tr4_b64_v2i32((LAS v2i*)(p_))
; #define VDMA(st_, k_) do { _Pragma("unroll") for (int i_ = 0; i_ < 4; ++i_) { \
;         const unsigned off_ = (unsigned)((st_) >> 2) * (16384u * 128u) + (PE_ID(E, 4 * ((st_) & 3) + i_) << 7) + ((i_ & 1) ? cx1 : cx0); \
;         __builtin_amdgcn_global_load_lds((const unsigned*)(V4 + off_), (LAS unsigned*)(ldsb + BUF[k_] + 1024 * i_), 16, 0, 0); } } while (0)
; __device__ __forceinline__ void peer_v_tokens(int j, const LAS unsigned short* EL, const LAS unsigned char* AL  , const LAS float* ASC  , const LAS int* SAL  , ...
;     ...
;         for (int st = 0; st < 16; ++st) {
;             const int p = st >> 2, q = st & 3;
;             if (st < 14) VDMA(st + 2, (st + 2) % 3);
;             if (st < 14) asm volatile("s_waitcnt vmcnt(8)" ::: "memory");
;             else if (st == 14) asm volatile("s_waitcnt vmcnt(4)" ::: "memory");
;             else asm volatile("s_waitcnt vmcnt(0)" ::: "memory");
;             if (q == 0) {
; #pragma unroll
;                 for (int r = 0; r < 4; ++r) { accH[r] = 0; accL[r] = 0; } }
; #pragma unroll
;             for (int tp = 0; tp < 2; ++tp) {
;                 const v2i ao = TR4(ATL + (2 * q + tp) * 128 + 8 * s16), ah = TR4(ATL + 1024 + (2 * q + tp) * 128 + 8 * s16);
; #pragma unroll
;                 for (int r = 0; r < 4; ++r) {
;                     const v2i d = TR4(ldsb + BUF[st % 3] + 2048 * tp + roff[r]);
;                     accH[r] = __builtin_amdgcn_sdot8(d.x, ah.x, accH[r], false); accH[r] = __builtin_amdgcn_sdot8(d.y, ah.y, accH[r], false);
;                     accL[r] = __builtin_amdgcn_sdot8(d.x, ao.x, accL[r], false); accL[r] = __builtin_amdgcn_sdot8(d.y, ao.y, accL[r], false);
;                 }
;             }
;             asm volatile("s_waitcnt lgkmcnt(0)" ::: "memory");
;             if (q == 3) {
; #pragma unroll
;                 for (int r = 0; r < 4; ++r) STASH[256 * p + 16 * (grp + 4 * r) + pc] = f2bf(asc * (float)(2 * ((accH[r] << 4) + accL[r]) + sa));
	v_add_u32_e32 v54, s76, v59
	v_add_u32_e32 v55, s76, v60
	v_add_u32_e32 v56, s76, v61
	v_add_u32_e32 v57, s76, v62
	ds_read_b64_tr_b4 v[46:47], v160
	ds_read_b64_tr_b4 v[48:49], v160 offset:1024
	ds_read_b64_tr_b4 v[122:123], v54
	ds_read_b64_tr_b4 v[124:125], v55
	ds_read_b64_tr_b4 v[126:127], v56
	ds_read_b64_tr_b4 v[128:129], v57
	s_waitcnt lgkmcnt(6)
	v_dot8c_i32_i4_e32 v38, v130, v52
	v_dot8c_i32_i4_e32 v39, v130, v50
	v_dot8c_i32_i4_e32 v40, v132, v52
	v_dot8c_i32_i4_e32 v41, v132, v50
	v_dot8c_i32_i4_e32 v42, v134, v52
	v_dot8c_i32_i4_e32 v43, v134, v50
	v_dot8c_i32_i4_e32 v44, v136, v52
	v_dot8c_i32_i4_e32 v45, v136, v50
	v_dot8c_i32_i4_e32 v38, v131, v53
	v_dot8c_i32_i4_e32 v39, v131, v51
	v_dot8c_i32_i4_e32 v40, v133, v53
	v_dot8c_i32_i4_e32 v41, v133, v51
	v_dot8c_i32_i4_e32 v42, v135, v53
	v_dot8c_i32_i4_e32 v43, v135, v51
	v_dot8c_i32_i4_e32 v44, v137, v53
	v_dot8c_i32_i4_e32 v45, v137, v51
	s_nop 3
	s_waitcnt lgkmcnt(15)
	v_lshlrev_b32_e32 v38, 5, v38
	v_lshlrev_b32_e32 v39, 1, v39
	v_add3_u32 v38, v39, v229, v38
	v_cvt_f32_i32_e32 v38, v38
	v_mul_f32_e32 v38, v228, v38
	v_lshlrev_b32_e32 v40, 5, v40
	v_lshlrev_b32_e32 v41, 1, v41
	v_add3_u32 v40, v41, v229, v40
	v_cvt_f32_i32_e32 v40, v40
	v_mul_f32_e32 v40, v228, v40
	v_lshlrev_b32_e32 v42, 5, v42
	v_lshlrev_b32_e32 v43, 1, v43
	v_add3_u32 v42, v43, v229, v42
	v_cvt_f32_i32_e32 v42, v42
	v_mul_f32_e32 v42, v228, v42
	v_lshlrev_b32_e32 v44, 5, v44
	v_lshlrev_b32_e32 v45, 1, v45
	v_add3_u32 v44, v45, v229, v44
	v_cvt_f32_i32_e32 v44, v44
	v_mul_f32_e32 v44, v228, v44
	v_cvt_pk_bf16_f32 v164, v38, v40
	v_cvt_pk_bf16_f32 v165, v42, v44
	v_add_u32_e32 v147, 8, v140
	v_and_b32_e32 v146, 15, v147
	v_xor_b32_e32 v146, 8, v146
	v_bfe_u32 v148, v147, 4, 4
	v_mul_lo_u32 v146, v146, s92
	v_mul_lo_u32 v148, v148, s92
	v_mov_b32_e32 v147, v146
	v_mov_b32_e32 v149, v148
	ds_write2st64_b64 v77, v[146:147], v[148:149] offset1:2
	v_mov_b32_e32 v138, v74
	ds_read_u8 v139, v138
	v_mov_b32_e32 v141, v73
	ds_read_u8 v140, v141
	s_add_i32 s43, s67, 32
	v_mov_b32_e32 v138, s43
	ds_read2st64_b32 v[228:229], v138 offset1:1
	ds_read_b128 v[18:21], v227
	ds_read_b128 v[22:25], v227 offset:16
	v_add_u32_e32 v150, 0x400000, v63
	v_add_u32_e32 v151, 0x400000, v64
	v_mov_b32_e32 v38, 0
	v_mov_b32_e32 v39, 0
	v_mov_b32_e32 v40, 0
	v_mov_b32_e32 v41, 0
	v_mov_b32_e32 v42, 0
	v_mov_b32_e32 v43, 0
	v_mov_b32_e32 v44, 0
	v_mov_b32_e32 v45, 0
	v_and_b32_e32 v78, 0xffff, v31
	v_lshrrev_b32_e32 v79, 16, v31
	v_lshl_add_u32 v78, v78, 7, v152
	v_lshl_add_u32 v79, v79, 7, v153
	s_mov_b32 m0, s99
	s_add_i32 s43, s99, 0x400
	global_load_lds_dwordx4 v78, s[50:51]
	s_mov_b32 m0, s43
	s_nop 0
	global_load_lds_dwordx4 v79, s[50:51]
	s_waitcnt vmcnt(8)
	v_add_u32_e32 v54, s77, v59
	v_add_u32_e32 v55, s77, v60
	v_add_u32_e32 v56, s77, v61
	v_add_u32_e32 v57, s77, v62
	ds_read_b64_tr_b4 v[50:51], v160 offset:128
	ds_read_b64_tr_b4 v[52:53], v160 offset:1152
	ds_read_b64_tr_b4 v[130:131], v54
	ds_read_b64_tr_b4 v[132:133], v55
	ds_read_b64_tr_b4 v[134:135], v56
	ds_read_b64_tr_b4 v[136:137], v57
	s_waitcnt lgkmcnt(12)
	v_dot8c_i32_i4_e32 v38, v122, v48
	v_dot8c_i32_i4_e32 v39, v122, v46
	v_dot8c_i32_i4_e32 v40, v124, v48
	v_dot8c_i32_i4_e32 v41, v124, v46
	v_dot8c_i32_i4_e32 v42, v126, v48
	v_dot8c_i32_i4_e32 v43, v126, v46
	v_dot8c_i32_i4_e32 v44, v128, v48
	v_dot8c_i32_i4_e32 v45, v128, v46
	v_dot8c_i32_i4_e32 v38, v123, v49
	v_dot8c_i32_i4_e32 v39, v123, v47
	v_dot8c_i32_i4_e32 v40, v125, v49
	v_dot8c_i32_i4_e32 v41, v125, v47
	v_dot8c_i32_i4_e32 v42, v127, v49
	v_dot8c_i32_i4_e32 v43, v127, v47
	v_dot8c_i32_i4_e32 v44, v129, v49
	v_dot8c_i32_i4_e32 v45, v129, v47
	v_and_b32_e32 v78, 0xffff, v32
	v_lshrrev_b32_e32 v79, 16, v32
	v_lshl_add_u32 v78, v78, 7, v152
	v_lshl_add_u32 v79, v79, 7, v153
	s_mov_b32 m0, s76
	s_add_i32 s43, s76, 0x400
	global_load_lds_dwordx4 v78, s[50:51]
	s_mov_b32 m0, s43
	s_nop 0
	global_load_lds_dwordx4 v79, s[50:51]
	s_waitcnt vmcnt(8)
	v_add_u32_e32 v54, s78, v59
	v_add_u32_e32 v55, s78, v60
	v_add_u32_e32 v56, s78, v61
	v_add_u32_e32 v57, s78, v62
	ds_read_b64_tr_b4 v[46:47], v160 offset:256
	ds_read_b64_tr_b4 v[48:49], v160 offset:1280
	ds_read_b64_tr_b4 v[122:123], v54
	ds_read_b64_tr_b4 v[124:125], v55
	ds_read_b64_tr_b4 v[126:127], v56
	ds_read_b64_tr_b4 v[128:129], v57
	s_waitcnt lgkmcnt(6)
	v_dot8c_i32_i4_e32 v38, v130, v52
	v_dot8c_i32_i4_e32 v39, v130, v50
	v_dot8c_i32_i4_e32 v40, v132, v52
	v_dot8c_i32_i4_e32 v41, v132, v50
	v_dot8c_i32_i4_e32 v42, v134, v52
	v_dot8c_i32_i4_e32 v43, v134, v50
	v_dot8c_i32_i4_e32 v44, v136, v52
	v_dot8c_i32_i4_e32 v45, v136, v50
	v_dot8c_i32_i4_e32 v38, v131, v53
	v_dot8c_i32_i4_e32 v39, v131, v51
	v_dot8c_i32_i4_e32 v40, v133, v53
	v_dot8c_i32_i4_e32 v41, v133, v51
	v_dot8c_i32_i4_e32 v42, v135, v53
	v_dot8c_i32_i4_e32 v43, v135, v51
	v_dot8c_i32_i4_e32 v44, v137, v53
	v_dot8c_i32_i4_e32 v45, v137, v51
	v_and_b32_e32 v78, 0xffff, v33
	v_lshrrev_b32_e32 v79, 16, v33
	v_lshl_add_u32 v78, v78, 7, v152
	v_lshl_add_u32 v79, v79, 7, v153
	s_mov_b32 m0, s77
	s_add_i32 s43, s77, 0x400
	global_load_lds_dwordx4 v78, s[50:51]
	s_mov_b32 m0, s43
	s_nop 0
	global_load_lds_dwordx4 v79, s[50:51]
	s_waitcnt vmcnt(8)
	v_add_u32_e32 v54, s79, v59
	v_add_u32_e32 v55, s79, v60
	v_add_u32_e32 v56, s79, v61
	v_add_u32_e32 v57, s79, v62
	ds_read_b64_tr_b4 v[50:51], v160 offset:384
	ds_read_b64_tr_b4 v[52:53], v160 offset:1408
	ds_read_b64_tr_b4 v[130:131], v54
	ds_read_b64_tr_b4 v[132:133], v55
	ds_read_b64_tr_b4 v[134:135], v56
	ds_read_b64_tr_b4 v[136:137], v57
	s_waitcnt lgkmcnt(6)
; #define TR4(p_) __builtin_amdgcn_ds_read_tr4_b64_v2i32((LAS v2i*)(p_))
; #define VDMA(st_, k_) do { _Pragma("unroll") for (int i_ = 0; i_ < 4; ++i_) { \
;         const unsigned off_ = (unsigned)((st_) >> 2) * (16384u * 128u) + (PE_ID(E, 4 * ((st_) & 3) + i_) << 7) + ((i_ & 1) ? cx1 : cx0); \
;         __builtin_amdgcn_global_load_lds((const unsigned*)(V4 + off_), (LAS unsigned*)(ldsb + BUF[k_] + 1024 * i_), 16, 0, 0); } } while (0)
; __device__ __forceinline__ void peer_v_tokens(int j, const LAS unsigned short* EL, const LAS unsigned char* AL  , const LAS float* ASC  , const LAS int* SAL  , ...
;     ...
;         for (int st = 0; st < 16; ++st) {
;             const int p = st >> 2, q = st & 3;
;             if (st < 14) VDMA(st + 2, (st + 2) % 3);
;             if (st < 14) asm volatile("s_waitcnt vmcnt(8)" ::: "memory");
;             else if (st == 14) asm volatile("s_waitcnt vmcnt(4)" ::: "memory");
;             else asm volatile("s_waitcnt vmcnt(0)" ::: "memory");
;             if (q == 0) {
; #pragma unroll
;                 for (int r = 0; r < 4; ++r) { accH[r] = 0; accL[r] = 0; } }
; #pragma unroll
;             for (int tp = 0; tp < 2; ++tp) {
;                 const v2i ao = TR4(ATL + (2 * q + tp) * 128 + 8 * s16), ah = TR4(ATL + 1024 + (2 * q + tp) * 128 + 8 * s16);
; #pragma unroll
;                 for (int r = 0; r < 4; ++r) {
;                     const v2i d = TR4(ldsb + BUF[st % 3] + 2048 * tp + roff[r]);
;                     accH[r] = __builtin_amdgcn_sdot8(d.x, ah.x, accH[r], false); accH[r] = __builtin_amdgcn_sdot8(d.y, ah.y, accH[r], false);
;                     accL[r] = __builtin_amdgcn_sdot8(d.x, ao.x, accL[r], false); accL[r] = __builtin_amdgcn_sdot8(d.y, ao.y, accL[r], false);
;                 }
;             }
	v_dot8c_i32_i4_e32 v38, v122, v48
	v_dot8c_i32_i4_e32 v39, v122, v46
	v_dot8c_i32_i4_e32 v40, v124, v48
	v_dot8c_i32_i4_e32 v41, v124, v46
	v_dot8c_i32_i4_e32 v42, v126, v48
	v_dot8c_i32_i4_e32 v43, v126, v46
	v_dot8c_i32_i4_e32 v44, v128, v48
	v_dot8c_i32_i4_e32 v45, v128, v46
	v_dot8c_i32_i4_e32 v38, v123, v49
	v_dot8c_i32_i4_e32 v39, v123, v47
	v_dot8c_i32_i4_e32 v40, v125, v49
	v_dot8c_i32_i4_e32 v41, v125, v47
	v_dot8c_i32_i4_e32 v42, v127, v49
	v_dot8c_i32_i4_e32 v43, v127, v47
	v_dot8c_i32_i4_e32 v44, v129, v49
	v_dot8c_i32_i4_e32 v45, v129, v47
	s_waitcnt lgkmcnt(15)
	v_and_b32_e32 v78, 0xffff, v18
	v_lshrrev_b32_e32 v79, 16, v18
	v_lshl_add_u32 v78, v78, 7, v150
	v_lshl_add_u32 v79, v79, 7, v151
	s_mov_b32 m0, s78
	s_add_i32 s43, s78, 0x400
	global_load_lds_dwordx4 v78, s[50:51]
	s_mov_b32 m0, s43
	s_nop 0
	global_load_lds_dwordx4 v79, s[50:51]
	s_waitcnt vmcnt(8)
	v_add_u32_e32 v54, s98, v59
	v_add_u32_e32 v55, s98, v60
	v_add_u32_e32 v56, s98, v61
	v_add_u32_e32 v57, s98, v62
	ds_read_b64_tr_b4 v[46:47], v160 offset:512
	ds_read_b64_tr_b4 v[48:49], v160 offset:1536
	ds_read_b64_tr_b4 v[122:123], v54
	ds_read_b64_tr_b4 v[124:125], v55
	ds_read_b64_tr_b4 v[126:127], v56
	ds_read_b64_tr_b4 v[128:129], v57
	s_waitcnt lgkmcnt(6)
	v_dot8c_i32_i4_e32 v38, v130, v52
	v_dot8c_i32_i4_e32 v39, v130, v50
	v_dot8c_i32_i4_e32 v40, v132, v52
	v_dot8c_i32_i4_e32 v41, v132, v50
	v_dot8c_i32_i4_e32 v42, v134, v52
	v_dot8c_i32_i4_e32 v43, v134, v50
	v_dot8c_i32_i4_e32 v44, v136, v52
	v_dot8c_i32_i4_e32 v45, v136, v50
	v_dot8c_i32_i4_e32 v38, v131, v53
	v_dot8c_i32_i4_e32 v39, v131, v51
	v_dot8c_i32_i4_e32 v40, v133, v53
	v_dot8c_i32_i4_e32 v41, v133, v51
	v_dot8c_i32_i4_e32 v42, v135, v53
	v_dot8c_i32_i4_e32 v43, v135, v51
	v_dot8c_i32_i4_e32 v44, v137, v53
	v_dot8c_i32_i4_e32 v45, v137, v51
	v_and_b32_e32 v78, 0xffff, v19
	v_lshrrev_b32_e32 v79, 16, v19
	v_lshl_add_u32 v78, v78, 7, v150
	v_lshl_add_u32 v79, v79, 7, v151
	s_mov_b32 m0, s79
	s_add_i32 s43, s79, 0x400
	global_load_lds_dwordx4 v78, s[50:51]
	s_mov_b32 m0, s43
	s_nop 0
	global_load_lds_dwordx4 v79, s[50:51]
	s_waitcnt vmcnt(8)
	v_add_u32_e32 v54, s99, v59
	v_add_u32_e32 v55, s99, v60
	v_add_u32_e32 v56, s99, v61
	v_add_u32_e32 v57, s99, v62
	ds_read_b64_tr_b4 v[50:51], v160 offset:640
	ds_read_b64_tr_b4 v[52:53], v160 offset:1664
	ds_read_b64_tr_b4 v[130:131], v54
	ds_read_b64_tr_b4 v[132:133], v55
	ds_read_b64_tr_b4 v[134:135], v56
	ds_read_b64_tr_b4 v[136:137], v57
	s_waitcnt lgkmcnt(6)
	v_dot8c_i32_i4_e32 v38, v122, v48
	v_dot8c_i32_i4_e32 v39, v122, v46
	v_dot8c_i32_i4_e32 v40, v124, v48
	v_dot8c_i32_i4_e32 v41, v124, v46
	v_dot8c_i32_i4_e32 v42, v126, v48
	v_dot8c_i32_i4_e32 v43, v126, v46
	v_dot8c_i32_i4_e32 v44, v128, v48
	v_dot8c_i32_i4_e32 v45, v128, v46
	v_dot8c_i32_i4_e32 v38, v123, v49
	v_dot8c_i32_i4_e32 v39, v123, v47
	v_dot8c_i32_i4_e32 v40, v125, v49
	v_dot8c_i32_i4_e32 v41, v125, v47
	v_dot8c_i32_i4_e32 v42, v127, v49
	v_dot8c_i32_i4_e32 v43, v127, v47
	v_dot8c_i32_i4_e32 v44, v129, v49
	v_dot8c_i32_i4_e32 v45, v129, v47
	s_waitcnt lgkmcnt(15)
	v_add_u32_e32 v143, 8, v139
	v_and_b32_e32 v142, 15, v143
	v_xor_b32_e32 v142, 8, v142
	v_bfe_u32 v144, v143, 4, 4
	v_mul_lo_u32 v142, v142, s92
	v_mul_lo_u32 v144, v144, s92
	v_mov_b32_e32 v143, v142
	v_mov_b32_e32 v145, v144
	ds_write2st64_b64 v159, v[142:143], v[144:145] offset1:2
	v_and_b32_e32 v78, 0xffff, v20
	v_lshrrev_b32_e32 v79, 16, v20
	v_lshl_add_u32 v78, v78, 7, v150
	v_lshl_add_u32 v79, v79, 7, v151
	s_mov_b32 m0, s98
	s_add_i32 s43, s98, 0x400
	global_load_lds_dwordx4 v78, s[50:51]
	s_mov_b32 m0, s43
	s_nop 0
	global_load_lds_dwordx4 v79, s[50:51]
	s_waitcnt vmcnt(8)
	v_add_u32_e32 v54, s76, v59
	v_add_u32_e32 v55, s76, v60
	v_add_u32_e32 v56, s76, v61
	v_add_u32_e32 v57, s76, v62
	ds_read_b64_tr_b4 v[46:47], v160 offset:768
	ds_read_b64_tr_b4 v[48:49], v160 offset:1792
	ds_read_b64_tr_b4 v[122:123], v54
	ds_read_b64_tr_b4 v[124:125], v55
	ds_read_b64_tr_b4 v[126:127], v56
	ds_read_b64_tr_b4 v[128:129], v57
	s_waitcnt lgkmcnt(7)
	v_dot8c_i32_i4_e32 v38, v130, v52
	v_dot8c_i32_i4_e32 v39, v130, v50
	v_dot8c_i32_i4_e32 v40, v132, v52
	v_dot8c_i32_i4_e32 v41, v132, v50
	v_dot8c_i32_i4_e32 v42, v134, v52
	v_dot8c_i32_i4_e32 v43, v134, v50
	v_dot8c_i32_i4_e32 v44, v136, v52
	v_dot8c_i32_i4_e32 v45, v136, v50
	v_dot8c_i32_i4_e32 v38, v131, v53
	v_dot8c_i32_i4_e32 v39, v131, v51
	v_dot8c_i32_i4_e32 v40, v133, v53
	v_dot8c_i32_i4_e32 v41, v133, v51
	v_dot8c_i32_i4_e32 v42, v135, v53
	v_dot8c_i32_i4_e32 v43, v135, v51
	v_dot8c_i32_i4_e32 v44, v137, v53
	v_dot8c_i32_i4_e32 v45, v137, v51
	v_and_b32_e32 v78, 0xffff, v21
	v_lshrrev_b32_e32 v79, 16, v21
	v_lshl_add_u32 v78, v78, 7, v150
	v_lshl_add_u32 v79, v79, 7, v151
	s_mov_b32 m0, s99
	s_add_i32 s43, s99, 0x400
	global_load_lds_dwordx4 v78, s[50:51]
	s_mov_b32 m0, s43
	s_nop 0
	global_load_lds_dwordx4 v79, s[50:51]
	s_waitcnt vmcnt(8)
	v_add_u32_e32 v54, s77, v59
	v_add_u32_e32 v55, s77, v60
	v_add_u32_e32 v56, s77, v61
	v_add_u32_e32 v57, s77, v62
	ds_read_b64_tr_b4 v[50:51], v160 offset:896
	ds_read_b64_tr_b4 v[52:53], v160 offset:1920
	ds_read_b64_tr_b4 v[130:131], v54
	ds_read_b64_tr_b4 v[132:133], v55
	ds_read_b64_tr_b4 v[134:135], v56
	ds_read_b64_tr_b4 v[136:137], v57
	s_waitcnt lgkmcnt(6)
; __device__ __forceinline__ bf16 f2bf(float f) { return (bf16)f2bfu(f); }
; #define TR4(p_) __builtin_amdgcn_ds_read_tr4_b64_v2i32((LAS v2i*)(p_))
; #define VDMA(st_, k_) do { _Pragma("unroll") for (int i_ = 0; i_ < 4; ++i_) { \
;         const unsigned off_ = (unsigned)((st_) >> 2) * (16384u * 128u) + (PE_ID(E, 4 * ((st_) & 3) + i_) << 7) + ((i_ & 1) ? cx1 : cx0); \
;         __builtin_amdgcn_global_load_lds((const unsigned*)(V4 + off_), (LAS unsigned*)(ldsb + BUF[k_] + 1024 * i_), 16, 0, 0); } } while (0)
; __device__ __forceinline__ void peer_v_tokens(int j, const LAS unsigned short* EL, const LAS unsigned char* AL  , const LAS float* ASC  , const LAS int* SAL  , ...
;     ...
;         for (int st = 0; st < 16; ++st) {
;             const int p = st >> 2, q = st & 3;
;             if (st < 14) VDMA(st + 2, (st + 2) % 3);
;             if (st < 14) asm volatile("s_waitcnt vmcnt(8)" ::: "memory");
;             else if (st == 14) asm volatile("s_waitcnt vmcnt(4)" ::: "memory");
;             else asm volatile("s_waitcnt vmcnt(0)" ::: "memory");
;             if (q == 0) {
; #pragma unroll
;                 for (int r = 0; r < 4; ++r) { accH[r] = 0; accL[r] = 0; } }
; #pragma unroll
;             for (int tp = 0; tp < 2; ++tp) {
;                 const v2i ao = TR4(ATL + (2 * q + tp) * 128 + 8 * s16), ah = TR4(ATL + 1024 + (2 * q + tp) * 128 + 8 * s16);
; #pragma unroll
;                 for (int r = 0; r < 4; ++r) {
;                     const v2i d = TR4(ldsb + BUF[st % 3] + 2048 * tp + roff[r]);
;                     accH[r] = __builtin_amdgcn_sdot8(d.x, ah.x, accH[r], false); accH[r] = __builtin_amdgcn_sdot8(d.y, ah.y, accH[r], false);
;                     accL[r] = __builtin_amdgcn_sdot8(d.x, ao.x, accL[r], false); accL[r] = __builtin_amdgcn_sdot8(d.y, ao.y, accL[r], false);
;                 }
;             }
;             asm volatile("s_waitcnt lgkmcnt(0)" ::: "memory");
;             if (q == 3) {
; #pragma unroll
;                 for (int r = 0; r < 4; ++r) STASH[256 * p + 16 * (grp + 4 * r) + pc] = f2bf(asc * (float)(2 * ((accH[r] << 4) + accL[r]) + sa));
	v_dot8c_i32_i4_e32 v38, v122, v48
	v_dot8c_i32_i4_e32 v39, v122, v46
	v_dot8c_i32_i4_e32 v40, v124, v48
	v_dot8c_i32_i4_e32 v41, v124, v46
	v_dot8c_i32_i4_e32 v42, v126, v48
	v_dot8c_i32_i4_e32 v43, v126, v46
	v_dot8c_i32_i4_e32 v44, v128, v48
	v_dot8c_i32_i4_e32 v45, v128, v46
	v_dot8c_i32_i4_e32 v38, v123, v49
	v_dot8c_i32_i4_e32 v39, v123, v47
	v_dot8c_i32_i4_e32 v40, v125, v49
	v_dot8c_i32_i4_e32 v41, v125, v47
	v_dot8c_i32_i4_e32 v42, v127, v49
	v_dot8c_i32_i4_e32 v43, v127, v47
	v_dot8c_i32_i4_e32 v44, v129, v49
	v_dot8c_i32_i4_e32 v45, v129, v47
	v_and_b32_e32 v78, 0xffff, v22
	v_lshrrev_b32_e32 v79, 16, v22
	v_lshl_add_u32 v78, v78, 7, v150
	v_lshl_add_u32 v79, v79, 7, v151
	s_mov_b32 m0, s76
	s_add_i32 s43, s76, 0x400
	global_load_lds_dwordx4 v78, s[50:51]
	s_mov_b32 m0, s43
	s_nop 0
	global_load_lds_dwordx4 v79, s[50:51]
	s_waitcnt vmcnt(8)
	v_add_u32_e32 v54, s78, v59
	v_add_u32_e32 v55, s78, v60
	v_add_u32_e32 v56, s78, v61
	v_add_u32_e32 v57, s78, v62
	ds_read_b64_tr_b4 v[46:47], v160
	ds_read_b64_tr_b4 v[48:49], v160 offset:1024
	ds_read_b64_tr_b4 v[122:123], v54
	ds_read_b64_tr_b4 v[124:125], v55
	ds_read_b64_tr_b4 v[126:127], v56
	ds_read_b64_tr_b4 v[128:129], v57
	s_waitcnt lgkmcnt(6)
	v_dot8c_i32_i4_e32 v38, v130, v52
	v_dot8c_i32_i4_e32 v39, v130, v50
	v_dot8c_i32_i4_e32 v40, v132, v52
	v_dot8c_i32_i4_e32 v41, v132, v50
	v_dot8c_i32_i4_e32 v42, v134, v52
	v_dot8c_i32_i4_e32 v43, v134, v50
	v_dot8c_i32_i4_e32 v44, v136, v52
	v_dot8c_i32_i4_e32 v45, v136, v50
	v_dot8c_i32_i4_e32 v38, v131, v53
	v_dot8c_i32_i4_e32 v39, v131, v51
	v_dot8c_i32_i4_e32 v40, v133, v53
	v_dot8c_i32_i4_e32 v41, v133, v51
	v_dot8c_i32_i4_e32 v42, v135, v53
	v_dot8c_i32_i4_e32 v43, v135, v51
	v_dot8c_i32_i4_e32 v44, v137, v53
	v_dot8c_i32_i4_e32 v45, v137, v51
	s_nop 3
	s_waitcnt lgkmcnt(15)
	v_lshlrev_b32_e32 v38, 5, v38
	v_lshlrev_b32_e32 v39, 1, v39
	v_add3_u32 v38, v39, v229, v38
	v_cvt_f32_i32_e32 v38, v38
	v_mul_f32_e32 v38, v228, v38
	v_lshlrev_b32_e32 v40, 5, v40
	v_lshlrev_b32_e32 v41, 1, v41
	v_add3_u32 v40, v41, v229, v40
	v_cvt_f32_i32_e32 v40, v40
	v_mul_f32_e32 v40, v228, v40
	v_lshlrev_b32_e32 v42, 5, v42
	v_lshlrev_b32_e32 v43, 1, v43
	v_add3_u32 v42, v43, v229, v42
	v_cvt_f32_i32_e32 v42, v42
	v_mul_f32_e32 v42, v228, v42
	v_lshlrev_b32_e32 v44, 5, v44
	v_lshlrev_b32_e32 v45, 1, v45
	v_add3_u32 v44, v45, v229, v44
	v_cvt_f32_i32_e32 v44, v44
	v_mul_f32_e32 v44, v228, v44
	v_cvt_pk_bf16_f32 v172, v38, v40
	v_cvt_pk_bf16_f32 v173, v42, v44
	v_add_u32_e32 v147, 8, v140
	v_and_b32_e32 v146, 15, v147
	v_xor_b32_e32 v146, 8, v146
	v_bfe_u32 v148, v147, 4, 4
	v_mul_lo_u32 v146, v146, s92
	v_mul_lo_u32 v148, v148, s92
	v_mov_b32_e32 v147, v146
	v_mov_b32_e32 v149, v148
	ds_write2st64_b64 v77, v[146:147], v[148:149] offset1:2
	v_add_u32_e32 v138, 0x400, v74
	ds_read_u8 v139, v138
	v_add_u32_e32 v141, 0x400, v73
	ds_read_u8 v140, v141
	s_mov_b32 s43, s67
	v_mov_b32_e32 v138, s43
	ds_read2st64_b32 v[228:229], v138 offset1:1
	ds_read_b128 v[26:29], v227 offset:2048
	ds_read_b128 v[30:33], v227 offset:2064
	v_mov_b32_e32 v38, 0
	v_mov_b32_e32 v39, 0
	v_mov_b32_e32 v40, 0
	v_mov_b32_e32 v41, 0
	v_mov_b32_e32 v42, 0
	v_mov_b32_e32 v43, 0
	v_mov_b32_e32 v44, 0
	v_mov_b32_e32 v45, 0
	v_and_b32_e32 v78, 0xffff, v23
	v_lshrrev_b32_e32 v79, 16, v23
	v_lshl_add_u32 v78, v78, 7, v150
	v_lshl_add_u32 v79, v79, 7, v151
	s_mov_b32 m0, s77
	s_add_i32 s43, s77, 0x400
	global_load_lds_dwordx4 v78, s[50:51]
	s_mov_b32 m0, s43
	s_nop 0
	global_load_lds_dwordx4 v79, s[50:51]
	s_waitcnt vmcnt(8)
	v_add_u32_e32 v54, s79, v59
	v_add_u32_e32 v55, s79, v60
	v_add_u32_e32 v56, s79, v61
	v_add_u32_e32 v57, s79, v62
	ds_read_b64_tr_b4 v[50:51], v160 offset:128
	ds_read_b64_tr_b4 v[52:53], v160 offset:1152
	ds_read_b64_tr_b4 v[130:131], v54
	ds_read_b64_tr_b4 v[132:133], v55
	ds_read_b64_tr_b4 v[134:135], v56
	ds_read_b64_tr_b4 v[136:137], v57
	s_waitcnt lgkmcnt(12)
	v_dot8c_i32_i4_e32 v38, v122, v48
	v_dot8c_i32_i4_e32 v39, v122, v46
	v_dot8c_i32_i4_e32 v40, v124, v48
	v_dot8c_i32_i4_e32 v41, v124, v46
	v_dot8c_i32_i4_e32 v42, v126, v48
	v_dot8c_i32_i4_e32 v43, v126, v46
	v_dot8c_i32_i4_e32 v44, v128, v48
	v_dot8c_i32_i4_e32 v45, v128, v46
	v_dot8c_i32_i4_e32 v38, v123, v49
	v_dot8c_i32_i4_e32 v39, v123, v47
	v_dot8c_i32_i4_e32 v40, v125, v49
	v_dot8c_i32_i4_e32 v41, v125, v47
	v_dot8c_i32_i4_e32 v42, v127, v49
	v_dot8c_i32_i4_e32 v43, v127, v47
	v_dot8c_i32_i4_e32 v44, v129, v49
	v_dot8c_i32_i4_e32 v45, v129, v47
	v_and_b32_e32 v78, 0xffff, v24
	v_lshrrev_b32_e32 v79, 16, v24
	v_lshl_add_u32 v78, v78, 7, v150
	v_lshl_add_u32 v79, v79, 7, v151
	s_mov_b32 m0, s78
	s_add_i32 s43, s78, 0x400
	global_load_lds_dwordx4 v78, s[50:51]
	s_mov_b32 m0, s43
	s_nop 0
	global_load_lds_dwordx4 v79, s[50:51]
	s_waitcnt vmcnt(8)
	v_add_u32_e32 v54, s98, v59
	v_add_u32_e32 v55, s98, v60
	v_add_u32_e32 v56, s98, v61
	v_add_u32_e32 v57, s98, v62
	ds_read_b64_tr_b4 v[46:47], v160 offset:256
	ds_read_b64_tr_b4 v[48:49], v160 offset:1280
	ds_read_b64_tr_b4 v[122:123], v54
	ds_read_b64_tr_b4 v[124:125], v55
	ds_read_b64_tr_b4 v[126:127], v56
	ds_read_b64_tr_b4 v[128:129], v57
	s_waitcnt lgkmcnt(6)
	v_dot8c_i32_i4_e32 v38, v130, v52
	v_dot8c_i32_i4_e32 v39, v130, v50
	v_dot8c_i32_i4_e32 v40, v132, v52
	v_dot8c_i32_i4_e32 v41, v132, v50
	v_dot8c_i32_i4_e32 v42, v134, v52
	v_dot8c_i32_i4_e32 v43, v134, v50
	v_dot8c_i32_i4_e32 v44, v136, v52
	v_dot8c_i32_i4_e32 v45, v136, v50
	v_dot8c_i32_i4_e32 v38, v131, v53
	v_dot8c_i32_i4_e32 v39, v131, v51
	v_dot8c_i32_i4_e32 v40, v133, v53
	v_dot8c_i32_i4_e32 v41, v133, v51
	v_dot8c_i32_i4_e32 v42, v135, v53
	v_dot8c_i32_i4_e32 v43, v135, v51
	v_dot8c_i32_i4_e32 v44, v137, v53
	v_dot8c_i32_i4_e32 v45, v137, v51
	v_and_b32_e32 v78, 0xffff, v25
	v_lshrrev_b32_e32 v79, 16, v25
	v_lshl_add_u32 v78, v78, 7, v150
	v_lshl_add_u32 v79, v79, 7, v151
	s_mov_b32 m0, s79
	s_add_i32 s43, s79, 0x400
	global_load_lds_dwordx4 v78, s[50:51]
	s_mov_b32 m0, s43
	s_nop 0
	global_load_lds_dwordx4 v79, s[50:51]
	s_waitcnt vmcnt(8)
; #define TR4(p_) __builtin_amdgcn_ds_read_tr4_b64_v2i32((LAS v2i*)(p_))
; #define VDMA(st_, k_) do { _Pragma("unroll") for (int i_ = 0; i_ < 4; ++i_) { \
;         const unsigned off_ = (unsigned)((st_) >> 2) * (16384u * 128u) + (PE_ID(E, 4 * ((st_) & 3) + i_) << 7) + ((i_ & 1) ? cx1 : cx0); \
;         __builtin_amdgcn_global_load_lds((const unsigned*)(V4 + off_), (LAS unsigned*)(ldsb + BUF[k_] + 1024 * i_), 16, 0, 0); } } while (0)
; __device__ __forceinline__ void peer_v_tokens(int j, const LAS unsigned short* EL, const LAS unsigned char* AL  , const LAS float* ASC  , const LAS int* SAL  , ...
;     ...
;         for (int st = 0; st < 16; ++st) {
;             const int p = st >> 2, q = st & 3;
;             if (st < 14) VDMA(st + 2, (st + 2) % 3);
;             if (st < 14) asm volatile("s_waitcnt vmcnt(8)" ::: "memory");
;             else if (st == 14) asm volatile("s_waitcnt vmcnt(4)" ::: "memory");
;             else asm volatile("s_waitcnt vmcnt(0)" ::: "memory");
;             if (q == 0) {
; #pragma unroll
;                 for (int r = 0; r < 4; ++r) { accH[r] = 0; accL[r] = 0; } }
; #pragma unroll
;             for (int tp = 0; tp < 2; ++tp) {
;                 const v2i ao = TR4(ATL + (2 * q + tp) * 128 + 8 * s16), ah = TR4(ATL + 1024 + (2 * q + tp) * 128 + 8 * s16);
; #pragma unroll
;                 for (int r = 0; r < 4; ++r) {
;                     const v2i d = TR4(ldsb + BUF[st % 3] + 2048 * tp + roff[r]);
;                     accH[r] = __builtin_amdgcn_sdot8(d.x, ah.x, accH[r], false); accH[r] = __builtin_amdgcn_sdot8(d.y, ah.y, accH[r], false);
;                     accL[r] = __builtin_amdgcn_sdot8(d.x, ao.x, accL[r], false); accL[r] = __builtin_amdgcn_sdot8(d.y, ao.y, accL[r], false);
;                 }
;             }
	v_add_u32_e32 v54, s99, v59
	v_add_u32_e32 v55, s99, v60
	v_add_u32_e32 v56, s99, v61
	v_add_u32_e32 v57, s99, v62
	ds_read_b64_tr_b4 v[50:51], v160 offset:384
	ds_read_b64_tr_b4 v[52:53], v160 offset:1408
	ds_read_b64_tr_b4 v[130:131], v54
	ds_read_b64_tr_b4 v[132:133], v55
	ds_read_b64_tr_b4 v[134:135], v56
	ds_read_b64_tr_b4 v[136:137], v57
	s_waitcnt lgkmcnt(6)
	v_dot8c_i32_i4_e32 v38, v122, v48
	v_dot8c_i32_i4_e32 v39, v122, v46
	v_dot8c_i32_i4_e32 v40, v124, v48
	v_dot8c_i32_i4_e32 v41, v124, v46
	v_dot8c_i32_i4_e32 v42, v126, v48
	v_dot8c_i32_i4_e32 v43, v126, v46
	v_dot8c_i32_i4_e32 v44, v128, v48
	v_dot8c_i32_i4_e32 v45, v128, v46
	v_dot8c_i32_i4_e32 v38, v123, v49
	v_dot8c_i32_i4_e32 v39, v123, v47
	v_dot8c_i32_i4_e32 v40, v125, v49
	v_dot8c_i32_i4_e32 v41, v125, v47
	v_dot8c_i32_i4_e32 v42, v127, v49
	v_dot8c_i32_i4_e32 v43, v127, v47
	v_dot8c_i32_i4_e32 v44, v129, v49
	v_dot8c_i32_i4_e32 v45, v129, v47
	s_waitcnt lgkmcnt(15)
	v_and_b32_e32 v78, 0xffff, v26
	v_lshrrev_b32_e32 v79, 16, v26
	v_lshl_add_u32 v78, v78, 7, v150
	v_lshl_add_u32 v79, v79, 7, v151
	s_mov_b32 m0, s98
	s_add_i32 s43, s98, 0x400
	global_load_lds_dwordx4 v78, s[50:51]
	s_mov_b32 m0, s43
	s_nop 0
	global_load_lds_dwordx4 v79, s[50:51]
	s_waitcnt vmcnt(8)
	v_add_u32_e32 v54, s76, v59
	v_add_u32_e32 v55, s76, v60
	v_add_u32_e32 v56, s76, v61
	v_add_u32_e32 v57, s76, v62
	ds_read_b64_tr_b4 v[46:47], v160 offset:512
	ds_read_b64_tr_b4 v[48:49], v160 offset:1536
	ds_read_b64_tr_b4 v[122:123], v54
	ds_read_b64_tr_b4 v[124:125], v55
	ds_read_b64_tr_b4 v[126:127], v56
	ds_read_b64_tr_b4 v[128:129], v57
	s_waitcnt lgkmcnt(6)
	v_dot8c_i32_i4_e32 v38, v130, v52
	v_dot8c_i32_i4_e32 v39, v130, v50
	v_dot8c_i32_i4_e32 v40, v132, v52
	v_dot8c_i32_i4_e32 v41, v132, v50
	v_dot8c_i32_i4_e32 v42, v134, v52
	v_dot8c_i32_i4_e32 v43, v134, v50
	v_dot8c_i32_i4_e32 v44, v136, v52
	v_dot8c_i32_i4_e32 v45, v136, v50
	v_dot8c_i32_i4_e32 v38, v131, v53
	v_dot8c_i32_i4_e32 v39, v131, v51
	v_dot8c_i32_i4_e32 v40, v133, v53
	v_dot8c_i32_i4_e32 v41, v133, v51
	v_dot8c_i32_i4_e32 v42, v135, v53
	v_dot8c_i32_i4_e32 v43, v135, v51
	v_dot8c_i32_i4_e32 v44, v137, v53
	v_dot8c_i32_i4_e32 v45, v137, v51
	v_and_b32_e32 v78, 0xffff, v27
	v_lshrrev_b32_e32 v79, 16, v27
	v_lshl_add_u32 v78, v78, 7, v150
	v_lshl_add_u32 v79, v79, 7, v151
	s_mov_b32 m0, s99
	s_add_i32 s43, s99, 0x400
	global_load_lds_dwordx4 v78, s[50:51]
	s_mov_b32 m0, s43
	s_nop 0
	global_load_lds_dwordx4 v79, s[50:51]
	s_waitcnt vmcnt(8)
	v_add_u32_e32 v54, s77, v59
	v_add_u32_e32 v55, s77, v60
	v_add_u32_e32 v56, s77, v61
	v_add_u32_e32 v57, s77, v62
	ds_read_b64_tr_b4 v[50:51], v160 offset:640
	ds_read_b64_tr_b4 v[52:53], v160 offset:1664
	ds_read_b64_tr_b4 v[130:131], v54
	ds_read_b64_tr_b4 v[132:133], v55
	ds_read_b64_tr_b4 v[134:135], v56
	ds_read_b64_tr_b4 v[136:137], v57
	s_waitcnt lgkmcnt(6)
	v_dot8c_i32_i4_e32 v38, v122, v48
	v_dot8c_i32_i4_e32 v39, v122, v46
	v_dot8c_i32_i4_e32 v40, v124, v48
	v_dot8c_i32_i4_e32 v41, v124, v46
	v_dot8c_i32_i4_e32 v42, v126, v48
	v_dot8c_i32_i4_e32 v43, v126, v46
	v_dot8c_i32_i4_e32 v44, v128, v48
	v_dot8c_i32_i4_e32 v45, v128, v46
	v_dot8c_i32_i4_e32 v38, v123, v49
	v_dot8c_i32_i4_e32 v39, v123, v47
	v_dot8c_i32_i4_e32 v40, v125, v49
	v_dot8c_i32_i4_e32 v41, v125, v47
	v_dot8c_i32_i4_e32 v42, v127, v49
	v_dot8c_i32_i4_e32 v43, v127, v47
	v_dot8c_i32_i4_e32 v44, v129, v49
	v_dot8c_i32_i4_e32 v45, v129, v47
	s_waitcnt lgkmcnt(15)
	v_add_u32_e32 v143, 8, v139
	v_and_b32_e32 v142, 15, v143
	v_xor_b32_e32 v142, 8, v142
	v_bfe_u32 v144, v143, 4, 4
	v_mul_lo_u32 v142, v142, s92
	v_mul_lo_u32 v144, v144, s92
	v_mov_b32_e32 v143, v142
	v_mov_b32_e32 v145, v144
	ds_write2st64_b64 v159, v[142:143], v[144:145] offset1:2
	v_and_b32_e32 v78, 0xffff, v28
	v_lshrrev_b32_e32 v79, 16, v28
	v_lshl_add_u32 v78, v78, 7, v150
	v_lshl_add_u32 v79, v79, 7, v151
	s_mov_b32 m0, s76
	s_add_i32 s43, s76, 0x400
	global_load_lds_dwordx4 v78, s[50:51]
	s_mov_b32 m0, s43
	s_nop 0
	global_load_lds_dwordx4 v79, s[50:51]
	s_waitcnt vmcnt(8)
	v_add_u32_e32 v54, s78, v59
	v_add_u32_e32 v55, s78, v60
	v_add_u32_e32 v56, s78, v61
	v_add_u32_e32 v57, s78, v62
	ds_read_b64_tr_b4 v[46:47], v160 offset:768
	ds_read_b64_tr_b4 v[48:49], v160 offset:1792
	ds_read_b64_tr_b4 v[122:123], v54
	ds_read_b64_tr_b4 v[124:125], v55
	ds_read_b64_tr_b4 v[126:127], v56
	ds_read_b64_tr_b4 v[128:129], v57
	s_waitcnt lgkmcnt(7)
	v_dot8c_i32_i4_e32 v38, v130, v52
	v_dot8c_i32_i4_e32 v39, v130, v50
	v_dot8c_i32_i4_e32 v40, v132, v52
	v_dot8c_i32_i4_e32 v41, v132, v50
	v_dot8c_i32_i4_e32 v42, v134, v52
	v_dot8c_i32_i4_e32 v43, v134, v50
	v_dot8c_i32_i4_e32 v44, v136, v52
	v_dot8c_i32_i4_e32 v45, v136, v50
	v_dot8c_i32_i4_e32 v38, v131, v53
	v_dot8c_i32_i4_e32 v39, v131, v51
	v_dot8c_i32_i4_e32 v40, v133, v53
	v_dot8c_i32_i4_e32 v41, v133, v51
	v_dot8c_i32_i4_e32 v42, v135, v53
	v_dot8c_i32_i4_e32 v43, v135, v51
	v_dot8c_i32_i4_e32 v44, v137, v53
	v_dot8c_i32_i4_e32 v45, v137, v51
	v_and_b32_e32 v78, 0xffff, v29
	v_lshrrev_b32_e32 v79, 16, v29
	v_lshl_add_u32 v78, v78, 7, v150
	v_lshl_add_u32 v79, v79, 7, v151
	s_mov_b32 m0, s77
	s_add_i32 s43, s77, 0x400
	global_load_lds_dwordx4 v78, s[50:51]
	s_mov_b32 m0, s43
	s_nop 0
	global_load_lds_dwordx4 v79, s[50:51]
	s_waitcnt vmcnt(8)
	v_add_u32_e32 v54, s79, v59
	v_add_u32_e32 v55, s79, v60
	v_add_u32_e32 v56, s79, v61
	v_add_u32_e32 v57, s79, v62
	ds_read_b64_tr_b4 v[50:51], v160 offset:896
	ds_read_b64_tr_b4 v[52:53], v160 offset:1920
	ds_read_b64_tr_b4 v[130:131], v54
	ds_read_b64_tr_b4 v[132:133], v55
	ds_read_b64_tr_b4 v[134:135], v56
	ds_read_b64_tr_b4 v[136:137], v57
	s_waitcnt lgkmcnt(6)
; __device__ __forceinline__ bf16 f2bf(float f) { return (bf16)f2bfu(f); }
; #define TR4(p_) __builtin_amdgcn_ds_read_tr4_b64_v2i32((LAS v2i*)(p_))
; #define VDMA(st_, k_) do { _Pragma("unroll") for (int i_ = 0; i_ < 4; ++i_) { \
;         const unsigned off_ = (unsigned)((st_) >> 2) * (16384u * 128u) + (PE_ID(E, 4 * ((st_) & 3) + i_) << 7) + ((i_ & 1) ? cx1 : cx0); \
;         __builtin_amdgcn_global_load_lds((const unsigned*)(V4 + off_), (LAS unsigned*)(ldsb + BUF[k_] + 1024 * i_), 16, 0, 0); } } while (0)
; __device__ __forceinline__ void peer_v_tokens(int j, const LAS unsigned short* EL, const LAS unsigned char* AL  , const LAS float* ASC  , const LAS int* SAL  , ...
;     ...
;         for (int st = 0; st < 16; ++st) {
;             const int p = st >> 2, q = st & 3;
;             if (st < 14) VDMA(st + 2, (st + 2) % 3);
;             if (st < 14) asm volatile("s_waitcnt vmcnt(8)" ::: "memory");
;             else if (st == 14) asm volatile("s_waitcnt vmcnt(4)" ::: "memory");
;             else asm volatile("s_waitcnt vmcnt(0)" ::: "memory");
;             if (q == 0) {
; #pragma unroll
;                 for (int r = 0; r < 4; ++r) { accH[r] = 0; accL[r] = 0; } }
; #pragma unroll
;             for (int tp = 0; tp < 2; ++tp) {
;                 const v2i ao = TR4(ATL + (2 * q + tp) * 128 + 8 * s16), ah = TR4(ATL + 1024 + (2 * q + tp) * 128 + 8 * s16);
; #pragma unroll
;                 for (int r = 0; r < 4; ++r) {
;                     const v2i d = TR4(ldsb + BUF[st % 3] + 2048 * tp + roff[r]);
;                     accH[r] = __builtin_amdgcn_sdot8(d.x, ah.x, accH[r], false); accH[r] = __builtin_amdgcn_sdot8(d.y, ah.y, accH[r], false);
;                     accL[r] = __builtin_amdgcn_sdot8(d.x, ao.x, accL[r], false); accL[r] = __builtin_amdgcn_sdot8(d.y, ao.y, accL[r], false);
;                 }
;             }
;             asm volatile("s_waitcnt lgkmcnt(0)" ::: "memory");
;             if (q == 3) {
; #pragma unroll
;                 for (int r = 0; r < 4; ++r) STASH[256 * p + 16 * (grp + 4 * r) + pc] = f2bf(asc * (float)(2 * ((accH[r] << 4) + accL[r]) + sa));
	v_dot8c_i32_i4_e32 v38, v122, v48
	v_dot8c_i32_i4_e32 v39, v122, v46
	v_dot8c_i32_i4_e32 v40, v124, v48
	v_dot8c_i32_i4_e32 v41, v124, v46
	v_dot8c_i32_i4_e32 v42, v126, v48
	v_dot8c_i32_i4_e32 v43, v126, v46
	v_dot8c_i32_i4_e32 v44, v128, v48
	v_dot8c_i32_i4_e32 v45, v128, v46
	v_dot8c_i32_i4_e32 v38, v123, v49
	v_dot8c_i32_i4_e32 v39, v123, v47
	v_dot8c_i32_i4_e32 v40, v125, v49
	v_dot8c_i32_i4_e32 v41, v125, v47
	v_dot8c_i32_i4_e32 v42, v127, v49
	v_dot8c_i32_i4_e32 v43, v127, v47
	v_dot8c_i32_i4_e32 v44, v129, v49
	v_dot8c_i32_i4_e32 v45, v129, v47
	v_and_b32_e32 v78, 0xffff, v30
	v_lshrrev_b32_e32 v79, 16, v30
	v_lshl_add_u32 v78, v78, 7, v150
	v_lshl_add_u32 v79, v79, 7, v151
	s_mov_b32 m0, s78
	s_add_i32 s43, s78, 0x400
	global_load_lds_dwordx4 v78, s[50:51]
	s_mov_b32 m0, s43
	s_nop 0
	global_load_lds_dwordx4 v79, s[50:51]
	s_waitcnt vmcnt(8)
	v_add_u32_e32 v54, s98, v59
	v_add_u32_e32 v55, s98, v60
	v_add_u32_e32 v56, s98, v61
	v_add_u32_e32 v57, s98, v62
	ds_read_b64_tr_b4 v[46:47], v160
	ds_read_b64_tr_b4 v[48:49], v160 offset:1024
	ds_read_b64_tr_b4 v[122:123], v54
	ds_read_b64_tr_b4 v[124:125], v55
	ds_read_b64_tr_b4 v[126:127], v56
	ds_read_b64_tr_b4 v[128:129], v57
	s_waitcnt lgkmcnt(6)
	v_dot8c_i32_i4_e32 v38, v130, v52
	v_dot8c_i32_i4_e32 v39, v130, v50
	v_dot8c_i32_i4_e32 v40, v132, v52
	v_dot8c_i32_i4_e32 v41, v132, v50
	v_dot8c_i32_i4_e32 v42, v134, v52
	v_dot8c_i32_i4_e32 v43, v134, v50
	v_dot8c_i32_i4_e32 v44, v136, v52
	v_dot8c_i32_i4_e32 v45, v136, v50
	v_dot8c_i32_i4_e32 v38, v131, v53
	v_dot8c_i32_i4_e32 v39, v131, v51
	v_dot8c_i32_i4_e32 v40, v133, v53
	v_dot8c_i32_i4_e32 v41, v133, v51
	v_dot8c_i32_i4_e32 v42, v135, v53
	v_dot8c_i32_i4_e32 v43, v135, v51
	v_dot8c_i32_i4_e32 v44, v137, v53
	v_dot8c_i32_i4_e32 v45, v137, v51
	s_nop 3
	s_waitcnt lgkmcnt(15)
	v_lshlrev_b32_e32 v38, 5, v38
	v_lshlrev_b32_e32 v39, 1, v39
	v_add3_u32 v38, v39, v229, v38
	v_cvt_f32_i32_e32 v38, v38
	v_mul_f32_e32 v38, v228, v38
	v_lshlrev_b32_e32 v40, 5, v40
	v_lshlrev_b32_e32 v41, 1, v41
	v_add3_u32 v40, v41, v229, v40
	v_cvt_f32_i32_e32 v40, v40
	v_mul_f32_e32 v40, v228, v40
	v_lshlrev_b32_e32 v42, 5, v42
	v_lshlrev_b32_e32 v43, 1, v43
	v_add3_u32 v42, v43, v229, v42
	v_cvt_f32_i32_e32 v42, v42
	v_mul_f32_e32 v42, v228, v42
	v_lshlrev_b32_e32 v44, 5, v44
	v_lshlrev_b32_e32 v45, 1, v45
	v_add3_u32 v44, v45, v229, v44
	v_cvt_f32_i32_e32 v44, v44
	v_mul_f32_e32 v44, v228, v44
	v_cvt_pk_bf16_f32 v166, v38, v40
	v_cvt_pk_bf16_f32 v167, v42, v44
	v_add_u32_e32 v147, 8, v140
	v_and_b32_e32 v146, 15, v147
	v_xor_b32_e32 v146, 8, v146
	v_bfe_u32 v148, v147, 4, 4
	v_mul_lo_u32 v146, v146, s92
	v_mul_lo_u32 v148, v148, s92
	v_mov_b32_e32 v147, v146
	v_mov_b32_e32 v149, v148
	ds_write2st64_b64 v77, v[146:147], v[148:149] offset1:2
	v_mov_b32_e32 v138, v74
	ds_read_u8 v139, v138
	v_mov_b32_e32 v141, v73
	ds_read_u8 v140, v141
	s_add_i32 s43, s67, 32
	v_mov_b32_e32 v138, s43
	ds_read2st64_b32 v[228:229], v138 offset1:1
	ds_read_b128 v[18:21], v227
	ds_read_b128 v[22:25], v227 offset:16
	v_add_u32_e32 v152, 0x600000, v63
	v_add_u32_e32 v153, 0x600000, v64
	v_mov_b32_e32 v38, 0
	v_mov_b32_e32 v39, 0
	v_mov_b32_e32 v40, 0
	v_mov_b32_e32 v41, 0
	v_mov_b32_e32 v42, 0
	v_mov_b32_e32 v43, 0
	v_mov_b32_e32 v44, 0
	v_mov_b32_e32 v45, 0
	v_and_b32_e32 v78, 0xffff, v31
	v_lshrrev_b32_e32 v79, 16, v31
	v_lshl_add_u32 v78, v78, 7, v150
	v_lshl_add_u32 v79, v79, 7, v151
	s_mov_b32 m0, s79
	s_add_i32 s43, s79, 0x400
	global_load_lds_dwordx4 v78, s[50:51]
	s_mov_b32 m0, s43
	s_nop 0
	global_load_lds_dwordx4 v79, s[50:51]
	s_waitcnt vmcnt(8)
	v_add_u32_e32 v54, s99, v59
	v_add_u32_e32 v55, s99, v60
	v_add_u32_e32 v56, s99, v61
	v_add_u32_e32 v57, s99, v62
	ds_read_b64_tr_b4 v[50:51], v160 offset:128
	ds_read_b64_tr_b4 v[52:53], v160 offset:1152
	ds_read_b64_tr_b4 v[130:131], v54
	ds_read_b64_tr_b4 v[132:133], v55
	ds_read_b64_tr_b4 v[134:135], v56
	ds_read_b64_tr_b4 v[136:137], v57
	s_waitcnt lgkmcnt(12)
	v_dot8c_i32_i4_e32 v38, v122, v48
	v_dot8c_i32_i4_e32 v39, v122, v46
	v_dot8c_i32_i4_e32 v40, v124, v48
	v_dot8c_i32_i4_e32 v41, v124, v46
	v_dot8c_i32_i4_e32 v42, v126, v48
	v_dot8c_i32_i4_e32 v43, v126, v46
	v_dot8c_i32_i4_e32 v44, v128, v48
	v_dot8c_i32_i4_e32 v45, v128, v46
	v_dot8c_i32_i4_e32 v38, v123, v49
	v_dot8c_i32_i4_e32 v39, v123, v47
	v_dot8c_i32_i4_e32 v40, v125, v49
	v_dot8c_i32_i4_e32 v41, v125, v47
	v_dot8c_i32_i4_e32 v42, v127, v49
	v_dot8c_i32_i4_e32 v43, v127, v47
	v_dot8c_i32_i4_e32 v44, v129, v49
	v_dot8c_i32_i4_e32 v45, v129, v47
	v_and_b32_e32 v78, 0xffff, v32
	v_lshrrev_b32_e32 v79, 16, v32
	v_lshl_add_u32 v78, v78, 7, v150
	v_lshl_add_u32 v79, v79, 7, v151
	s_mov_b32 m0, s98
	s_add_i32 s43, s98, 0x400
	global_load_lds_dwordx4 v78, s[50:51]
	s_mov_b32 m0, s43
	s_nop 0
	global_load_lds_dwordx4 v79, s[50:51]
	s_waitcnt vmcnt(8)
	v_add_u32_e32 v54, s76, v59
	v_add_u32_e32 v55, s76, v60
	v_add_u32_e32 v56, s76, v61
	v_add_u32_e32 v57, s76, v62
	ds_read_b64_tr_b4 v[46:47], v160 offset:256
	ds_read_b64_tr_b4 v[48:49], v160 offset:1280
	ds_read_b64_tr_b4 v[122:123], v54
	ds_read_b64_tr_b4 v[124:125], v55
	ds_read_b64_tr_b4 v[126:127], v56
	ds_read_b64_tr_b4 v[128:129], v57
	s_waitcnt lgkmcnt(6)
	v_dot8c_i32_i4_e32 v38, v130, v52
	v_dot8c_i32_i4_e32 v39, v130, v50
	v_dot8c_i32_i4_e32 v40, v132, v52
	v_dot8c_i32_i4_e32 v41, v132, v50
	v_dot8c_i32_i4_e32 v42, v134, v52
	v_dot8c_i32_i4_e32 v43, v134, v50
	v_dot8c_i32_i4_e32 v44, v136, v52
	v_dot8c_i32_i4_e32 v45, v136, v50
	v_dot8c_i32_i4_e32 v38, v131, v53
	v_dot8c_i32_i4_e32 v39, v131, v51
	v_dot8c_i32_i4_e32 v40, v133, v53
	v_dot8c_i32_i4_e32 v41, v133, v51
	v_dot8c_i32_i4_e32 v42, v135, v53
	v_dot8c_i32_i4_e32 v43, v135, v51
	v_dot8c_i32_i4_e32 v44, v137, v53
	v_dot8c_i32_i4_e32 v45, v137, v51
	v_and_b32_e32 v78, 0xffff, v33
	v_lshrrev_b32_e32 v79, 16, v33
	v_lshl_add_u32 v78, v78, 7, v150
	v_lshl_add_u32 v79, v79, 7, v151
	s_mov_b32 m0, s99
	s_add_i32 s43, s99, 0x400
	global_load_lds_dwordx4 v78, s[50:51]
	s_mov_b32 m0, s43
	s_nop 0
	global_load_lds_dwordx4 v79, s[50:51]
	s_waitcnt vmcnt(8)
; #define TR4(p_) __builtin_amdgcn_ds_read_tr4_b64_v2i32((LAS v2i*)(p_))
; #define VDMA(st_, k_) do { _Pragma("unroll") for (int i_ = 0; i_ < 4; ++i_) { \
;         const unsigned off_ = (unsigned)((st_) >> 2) * (16384u * 128u) + (PE_ID(E, 4 * ((st_) & 3) + i_) << 7) + ((i_ & 1) ? cx1 : cx0); \
;         __builtin_amdgcn_global_load_lds((const unsigned*)(V4 + off_), (LAS unsigned*)(ldsb + BUF[k_] + 1024 * i_), 16, 0, 0); } } while (0)
; __device__ __forceinline__ void peer_v_tokens(int j, const LAS unsigned short* EL, const LAS unsigned char* AL  , const LAS float* ASC  , const LAS int* SAL  , ...
;     ...
;         for (int st = 0; st < 16; ++st) {
;             const int p = st >> 2, q = st & 3;
;             if (st < 14) VDMA(st + 2, (st + 2) % 3);
;             if (st < 14) asm volatile("s_waitcnt vmcnt(8)" ::: "memory");
;             else if (st == 14) asm volatile("s_waitcnt vmcnt(4)" ::: "memory");
;             else asm volatile("s_waitcnt vmcnt(0)" ::: "memory");
;             if (q == 0) {
; #pragma unroll
;                 for (int r = 0; r < 4; ++r) { accH[r] = 0; accL[r] = 0; } }
; #pragma unroll
;             for (int tp = 0; tp < 2; ++tp) {
;                 const v2i ao = TR4(ATL + (2 * q + tp) * 128 + 8 * s16), ah = TR4(ATL + 1024 + (2 * q + tp) * 128 + 8 * s16);
; #pragma unroll
;                 for (int r = 0; r < 4; ++r) {
;                     const v2i d = TR4(ldsb + BUF[st % 3] + 2048 * tp + roff[r]);
;                     accH[r] = __builtin_amdgcn_sdot8(d.x, ah.x, accH[r], false); accH[r] = __builtin_amdgcn_sdot8(d.y, ah.y, accH[r], false);
;                     accL[r] = __builtin_amdgcn_sdot8(d.x, ao.x, accL[r], false); accL[r] = __builtin_amdgcn_sdot8(d.y, ao.y, accL[r], false);
;                 }
;             }
	v_add_u32_e32 v54, s77, v59
	v_add_u32_e32 v55, s77, v60
	v_add_u32_e32 v56, s77, v61
	v_add_u32_e32 v57, s77, v62
	ds_read_b64_tr_b4 v[50:51], v160 offset:384
	ds_read_b64_tr_b4 v[52:53], v160 offset:1408
	ds_read_b64_tr_b4 v[130:131], v54
	ds_read_b64_tr_b4 v[132:133], v55
	ds_read_b64_tr_b4 v[134:135], v56
	ds_read_b64_tr_b4 v[136:137], v57
	s_waitcnt lgkmcnt(6)
	v_dot8c_i32_i4_e32 v38, v122, v48
	v_dot8c_i32_i4_e32 v39, v122, v46
	v_dot8c_i32_i4_e32 v40, v124, v48
	v_dot8c_i32_i4_e32 v41, v124, v46
	v_dot8c_i32_i4_e32 v42, v126, v48
	v_dot8c_i32_i4_e32 v43, v126, v46
	v_dot8c_i32_i4_e32 v44, v128, v48
	v_dot8c_i32_i4_e32 v45, v128, v46
	v_dot8c_i32_i4_e32 v38, v123, v49
	v_dot8c_i32_i4_e32 v39, v123, v47
	v_dot8c_i32_i4_e32 v40, v125, v49
	v_dot8c_i32_i4_e32 v41, v125, v47
	v_dot8c_i32_i4_e32 v42, v127, v49
	v_dot8c_i32_i4_e32 v43, v127, v47
	v_dot8c_i32_i4_e32 v44, v129, v49
	v_dot8c_i32_i4_e32 v45, v129, v47
	s_waitcnt lgkmcnt(15)
	v_and_b32_e32 v78, 0xffff, v18
	v_lshrrev_b32_e32 v79, 16, v18
	v_lshl_add_u32 v78, v78, 7, v152
	v_lshl_add_u32 v79, v79, 7, v153
	s_mov_b32 m0, s76
	s_add_i32 s43, s76, 0x400
	global_load_lds_dwordx4 v78, s[50:51]
	s_mov_b32 m0, s43
	s_nop 0
	global_load_lds_dwordx4 v79, s[50:51]
	s_waitcnt vmcnt(8)
	v_add_u32_e32 v54, s78, v59
	v_add_u32_e32 v55, s78, v60
	v_add_u32_e32 v56, s78, v61
	v_add_u32_e32 v57, s78, v62
	ds_read_b64_tr_b4 v[46:47], v160 offset:512
	ds_read_b64_tr_b4 v[48:49], v160 offset:1536
	ds_read_b64_tr_b4 v[122:123], v54
	ds_read_b64_tr_b4 v[124:125], v55
	ds_read_b64_tr_b4 v[126:127], v56
	ds_read_b64_tr_b4 v[128:129], v57
	s_waitcnt lgkmcnt(6)
	v_dot8c_i32_i4_e32 v38, v130, v52
	v_dot8c_i32_i4_e32 v39, v130, v50
	v_dot8c_i32_i4_e32 v40, v132, v52
	v_dot8c_i32_i4_e32 v41, v132, v50
	v_dot8c_i32_i4_e32 v42, v134, v52
	v_dot8c_i32_i4_e32 v43, v134, v50
	v_dot8c_i32_i4_e32 v44, v136, v52
	v_dot8c_i32_i4_e32 v45, v136, v50
	v_dot8c_i32_i4_e32 v38, v131, v53
	v_dot8c_i32_i4_e32 v39, v131, v51
	v_dot8c_i32_i4_e32 v40, v133, v53
	v_dot8c_i32_i4_e32 v41, v133, v51
	v_dot8c_i32_i4_e32 v42, v135, v53
	v_dot8c_i32_i4_e32 v43, v135, v51
	v_dot8c_i32_i4_e32 v44, v137, v53
	v_dot8c_i32_i4_e32 v45, v137, v51
	v_and_b32_e32 v78, 0xffff, v19
	v_lshrrev_b32_e32 v79, 16, v19
	v_lshl_add_u32 v78, v78, 7, v152
	v_lshl_add_u32 v79, v79, 7, v153
	s_mov_b32 m0, s77
	s_add_i32 s43, s77, 0x400
	global_load_lds_dwordx4 v78, s[50:51]
	s_mov_b32 m0, s43
	s_nop 0
	global_load_lds_dwordx4 v79, s[50:51]
	s_waitcnt vmcnt(8)
	v_add_u32_e32 v54, s79, v59
	v_add_u32_e32 v55, s79, v60
	v_add_u32_e32 v56, s79, v61
	v_add_u32_e32 v57, s79, v62
	ds_read_b64_tr_b4 v[50:51], v160 offset:640
	ds_read_b64_tr_b4 v[52:53], v160 offset:1664
	ds_read_b64_tr_b4 v[130:131], v54
	ds_read_b64_tr_b4 v[132:133], v55
	ds_read_b64_tr_b4 v[134:135], v56
	ds_read_b64_tr_b4 v[136:137], v57
	s_waitcnt lgkmcnt(6)
	v_dot8c_i32_i4_e32 v38, v122, v48
	v_dot8c_i32_i4_e32 v39, v122, v46
	v_dot8c_i32_i4_e32 v40, v124, v48
	v_dot8c_i32_i4_e32 v41, v124, v46
	v_dot8c_i32_i4_e32 v42, v126, v48
	v_dot8c_i32_i4_e32 v43, v126, v46
	v_dot8c_i32_i4_e32 v44, v128, v48
	v_dot8c_i32_i4_e32 v45, v128, v46
	v_dot8c_i32_i4_e32 v38, v123, v49
	v_dot8c_i32_i4_e32 v39, v123, v47
	v_dot8c_i32_i4_e32 v40, v125, v49
	v_dot8c_i32_i4_e32 v41, v125, v47
	v_dot8c_i32_i4_e32 v42, v127, v49
	v_dot8c_i32_i4_e32 v43, v127, v47
	v_dot8c_i32_i4_e32 v44, v129, v49
	v_dot8c_i32_i4_e32 v45, v129, v47
	s_waitcnt lgkmcnt(15)
	v_add_u32_e32 v143, 8, v139
	v_and_b32_e32 v142, 15, v143
	v_xor_b32_e32 v142, 8, v142
	v_bfe_u32 v144, v143, 4, 4
	v_mul_lo_u32 v142, v142, s92
	v_mul_lo_u32 v144, v144, s92
	v_mov_b32_e32 v143, v142
	v_mov_b32_e32 v145, v144
	ds_write2st64_b64 v159, v[142:143], v[144:145] offset1:2
	v_and_b32_e32 v78, 0xffff, v20
	v_lshrrev_b32_e32 v79, 16, v20
	v_lshl_add_u32 v78, v78, 7, v152
	v_lshl_add_u32 v79, v79, 7, v153
	s_mov_b32 m0, s78
	s_add_i32 s43, s78, 0x400
	global_load_lds_dwordx4 v78, s[50:51]
	s_mov_b32 m0, s43
	s_nop 0
	global_load_lds_dwordx4 v79, s[50:51]
	s_waitcnt vmcnt(8)
	v_add_u32_e32 v54, s98, v59
	v_add_u32_e32 v55, s98, v60
	v_add_u32_e32 v56, s98, v61
	v_add_u32_e32 v57, s98, v62
	ds_read_b64_tr_b4 v[46:47], v160 offset:768
	ds_read_b64_tr_b4 v[48:49], v160 offset:1792
	ds_read_b64_tr_b4 v[122:123], v54
	ds_read_b64_tr_b4 v[124:125], v55
	ds_read_b64_tr_b4 v[126:127], v56
	ds_read_b64_tr_b4 v[128:129], v57
	s_waitcnt lgkmcnt(7)
	v_dot8c_i32_i4_e32 v38, v130, v52
	v_dot8c_i32_i4_e32 v39, v130, v50
	v_dot8c_i32_i4_e32 v40, v132, v52
	v_dot8c_i32_i4_e32 v41, v132, v50
	v_dot8c_i32_i4_e32 v42, v134, v52
	v_dot8c_i32_i4_e32 v43, v134, v50
	v_dot8c_i32_i4_e32 v44, v136, v52
	v_dot8c_i32_i4_e32 v45, v136, v50
	v_dot8c_i32_i4_e32 v38, v131, v53
	v_dot8c_i32_i4_e32 v39, v131, v51
	v_dot8c_i32_i4_e32 v40, v133, v53
	v_dot8c_i32_i4_e32 v41, v133, v51
	v_dot8c_i32_i4_e32 v42, v135, v53
	v_dot8c_i32_i4_e32 v43, v135, v51
	v_dot8c_i32_i4_e32 v44, v137, v53
	v_dot8c_i32_i4_e32 v45, v137, v51
	v_and_b32_e32 v78, 0xffff, v21
	v_lshrrev_b32_e32 v79, 16, v21
	v_lshl_add_u32 v78, v78, 7, v152
	v_lshl_add_u32 v79, v79, 7, v153
	s_mov_b32 m0, s79
	s_add_i32 s43, s79, 0x400
	global_load_lds_dwordx4 v78, s[50:51]
	s_mov_b32 m0, s43
	s_nop 0
	global_load_lds_dwordx4 v79, s[50:51]
	s_waitcnt vmcnt(8)
	v_add_u32_e32 v54, s99, v59
	v_add_u32_e32 v55, s99, v60
	v_add_u32_e32 v56, s99, v61
	v_add_u32_e32 v57, s99, v62
	ds_read_b64_tr_b4 v[50:51], v160 offset:896
	ds_read_b64_tr_b4 v[52:53], v160 offset:1920
	ds_read_b64_tr_b4 v[130:131], v54
	ds_read_b64_tr_b4 v[132:133], v55
	ds_read_b64_tr_b4 v[134:135], v56
	ds_read_b64_tr_b4 v[136:137], v57
	s_waitcnt lgkmcnt(6)
; __device__ __forceinline__ bf16 f2bf(float f) { return (bf16)f2bfu(f); }
; #define TR4(p_) __builtin_amdgcn_ds_read_tr4_b64_v2i32((LAS v2i*)(p_))
; #define VDMA(st_, k_) do { _Pragma("unroll") for (int i_ = 0; i_ < 4; ++i_) { \
;         const unsigned off_ = (unsigned)((st_) >> 2) * (16384u * 128u) + (PE_ID(E, 4 * ((st_) & 3) + i_) << 7) + ((i_ & 1) ? cx1 : cx0); \
;         __builtin_amdgcn_global_load_lds((const unsigned*)(V4 + off_), (LAS unsigned*)(ldsb + BUF[k_] + 1024 * i_), 16, 0, 0); } } while (0)
; __device__ __forceinline__ void peer_v_tokens(int j, const LAS unsigned short* EL, const LAS unsigned char* AL  , const LAS float* ASC  , const LAS int* SAL  , ...
;     ...
;         for (int st = 0; st < 16; ++st) {
;             const int p = st >> 2, q = st & 3;
;             if (st < 14) VDMA(st + 2, (st + 2) % 3);
;             if (st < 14) asm volatile("s_waitcnt vmcnt(8)" ::: "memory");
;             else if (st == 14) asm volatile("s_waitcnt vmcnt(4)" ::: "memory");
;             else asm volatile("s_waitcnt vmcnt(0)" ::: "memory");
;             if (q == 0) {
; #pragma unroll
;                 for (int r = 0; r < 4; ++r) { accH[r] = 0; accL[r] = 0; } }
; #pragma unroll
;             for (int tp = 0; tp < 2; ++tp) {
;                 const v2i ao = TR4(ATL + (2 * q + tp) * 128 + 8 * s16), ah = TR4(ATL + 1024 + (2 * q + tp) * 128 + 8 * s16);
; #pragma unroll
;                 for (int r = 0; r < 4; ++r) {
;                     const v2i d = TR4(ldsb + BUF[st % 3] + 2048 * tp + roff[r]);
;                     accH[r] = __builtin_amdgcn_sdot8(d.x, ah.x, accH[r], false); accH[r] = __builtin_amdgcn_sdot8(d.y, ah.y, accH[r], false);
;                     accL[r] = __builtin_amdgcn_sdot8(d.x, ao.x, accL[r], false); accL[r] = __builtin_amdgcn_sdot8(d.y, ao.y, accL[r], false);
;                 }
;             }
;             asm volatile("s_waitcnt lgkmcnt(0)" ::: "memory");
;             if (q == 3) {
; #pragma unroll
;                 for (int r = 0; r < 4; ++r) STASH[256 * p + 16 * (grp + 4 * r) + pc] = f2bf(asc * (float)(2 * ((accH[r] << 4) + accL[r]) + sa));
	v_dot8c_i32_i4_e32 v38, v122, v48
	v_dot8c_i32_i4_e32 v39, v122, v46
	v_dot8c_i32_i4_e32 v40, v124, v48
	v_dot8c_i32_i4_e32 v41, v124, v46
	v_dot8c_i32_i4_e32 v42, v126, v48
	v_dot8c_i32_i4_e32 v43, v126, v46
	v_dot8c_i32_i4_e32 v44, v128, v48
	v_dot8c_i32_i4_e32 v45, v128, v46
	v_dot8c_i32_i4_e32 v38, v123, v49
	v_dot8c_i32_i4_e32 v39, v123, v47
	v_dot8c_i32_i4_e32 v40, v125, v49
	v_dot8c_i32_i4_e32 v41, v125, v47
	v_dot8c_i32_i4_e32 v42, v127, v49
	v_dot8c_i32_i4_e32 v43, v127, v47
	v_dot8c_i32_i4_e32 v44, v129, v49
	v_dot8c_i32_i4_e32 v45, v129, v47
	v_and_b32_e32 v78, 0xffff, v22
	v_lshrrev_b32_e32 v79, 16, v22
	v_lshl_add_u32 v78, v78, 7, v152
	v_lshl_add_u32 v79, v79, 7, v153
	s_mov_b32 m0, s98
	s_add_i32 s43, s98, 0x400
	global_load_lds_dwordx4 v78, s[50:51]
	s_mov_b32 m0, s43
	s_nop 0
	global_load_lds_dwordx4 v79, s[50:51]
	s_waitcnt vmcnt(8)
	v_add_u32_e32 v54, s76, v59
	v_add_u32_e32 v55, s76, v60
	v_add_u32_e32 v56, s76, v61
	v_add_u32_e32 v57, s76, v62
	ds_read_b64_tr_b4 v[46:47], v160
	ds_read_b64_tr_b4 v[48:49], v160 offset:1024
	ds_read_b64_tr_b4 v[122:123], v54
	ds_read_b64_tr_b4 v[124:125], v55
	ds_read_b64_tr_b4 v[126:127], v56
	ds_read_b64_tr_b4 v[128:129], v57
	s_waitcnt lgkmcnt(6)
	v_dot8c_i32_i4_e32 v38, v130, v52
	v_dot8c_i32_i4_e32 v39, v130, v50
	v_dot8c_i32_i4_e32 v40, v132, v52
	v_dot8c_i32_i4_e32 v41, v132, v50
	v_dot8c_i32_i4_e32 v42, v134, v52
	v_dot8c_i32_i4_e32 v43, v134, v50
	v_dot8c_i32_i4_e32 v44, v136, v52
	v_dot8c_i32_i4_e32 v45, v136, v50
	v_dot8c_i32_i4_e32 v38, v131, v53
	v_dot8c_i32_i4_e32 v39, v131, v51
	v_dot8c_i32_i4_e32 v40, v133, v53
	v_dot8c_i32_i4_e32 v41, v133, v51
	v_dot8c_i32_i4_e32 v42, v135, v53
	v_dot8c_i32_i4_e32 v43, v135, v51
	v_dot8c_i32_i4_e32 v44, v137, v53
	v_dot8c_i32_i4_e32 v45, v137, v51
	s_nop 3
	s_waitcnt lgkmcnt(15)
	v_lshlrev_b32_e32 v38, 5, v38
	v_lshlrev_b32_e32 v39, 1, v39
	v_add3_u32 v38, v39, v229, v38
	v_cvt_f32_i32_e32 v38, v38
	v_mul_f32_e32 v38, v228, v38
	v_lshlrev_b32_e32 v40, 5, v40
	v_lshlrev_b32_e32 v41, 1, v41
	v_add3_u32 v40, v41, v229, v40
	v_cvt_f32_i32_e32 v40, v40
	v_mul_f32_e32 v40, v228, v40
	v_lshlrev_b32_e32 v42, 5, v42
	v_lshlrev_b32_e32 v43, 1, v43
	v_add3_u32 v42, v43, v229, v42
	v_cvt_f32_i32_e32 v42, v42
	v_mul_f32_e32 v42, v228, v42
	v_lshlrev_b32_e32 v44, 5, v44
	v_lshlrev_b32_e32 v45, 1, v45
	v_add3_u32 v44, v45, v229, v44
	v_cvt_f32_i32_e32 v44, v44
	v_mul_f32_e32 v44, v228, v44
	v_cvt_pk_bf16_f32 v174, v38, v40
	v_cvt_pk_bf16_f32 v175, v42, v44
	v_add_u32_e32 v147, 8, v140
	v_and_b32_e32 v146, 15, v147
	v_xor_b32_e32 v146, 8, v146
	v_bfe_u32 v148, v147, 4, 4
	v_mul_lo_u32 v146, v146, s92
	v_mul_lo_u32 v148, v148, s92
	v_mov_b32_e32 v147, v146
	v_mov_b32_e32 v149, v148
	ds_write2st64_b64 v77, v[146:147], v[148:149] offset1:2
	v_add_u32_e32 v138, 0x400, v74
	ds_read_u8 v139, v138
	v_add_u32_e32 v141, 0x400, v73
	ds_read_u8 v140, v141
	s_mov_b32 s43, s67
	v_mov_b32_e32 v138, s43
	ds_read2st64_b32 v[228:229], v138 offset1:1
	ds_read_b128 v[26:29], v227 offset:2048
	ds_read_b128 v[30:33], v227 offset:2064
	v_mov_b32_e32 v38, 0
	v_mov_b32_e32 v39, 0
	v_mov_b32_e32 v40, 0
	v_mov_b32_e32 v41, 0
	v_mov_b32_e32 v42, 0
	v_mov_b32_e32 v43, 0
	v_mov_b32_e32 v44, 0
	v_mov_b32_e32 v45, 0
	v_and_b32_e32 v78, 0xffff, v23
	v_lshrrev_b32_e32 v79, 16, v23
	v_lshl_add_u32 v78, v78, 7, v152
	v_lshl_add_u32 v79, v79, 7, v153
	s_mov_b32 m0, s99
	s_add_i32 s43, s99, 0x400
	global_load_lds_dwordx4 v78, s[50:51]
	s_mov_b32 m0, s43
	s_nop 0
	global_load_lds_dwordx4 v79, s[50:51]
	s_waitcnt vmcnt(8)
	v_add_u32_e32 v54, s77, v59
	v_add_u32_e32 v55, s77, v60
	v_add_u32_e32 v56, s77, v61
	v_add_u32_e32 v57, s77, v62
	ds_read_b64_tr_b4 v[50:51], v160 offset:128
	ds_read_b64_tr_b4 v[52:53], v160 offset:1152
	ds_read_b64_tr_b4 v[130:131], v54
	ds_read_b64_tr_b4 v[132:133], v55
	ds_read_b64_tr_b4 v[134:135], v56
	ds_read_b64_tr_b4 v[136:137], v57
	s_waitcnt lgkmcnt(12)
	v_dot8c_i32_i4_e32 v38, v122, v48
	v_dot8c_i32_i4_e32 v39, v122, v46
	v_dot8c_i32_i4_e32 v40, v124, v48
	v_dot8c_i32_i4_e32 v41, v124, v46
	v_dot8c_i32_i4_e32 v42, v126, v48
	v_dot8c_i32_i4_e32 v43, v126, v46
	v_dot8c_i32_i4_e32 v44, v128, v48
	v_dot8c_i32_i4_e32 v45, v128, v46
	v_dot8c_i32_i4_e32 v38, v123, v49
	v_dot8c_i32_i4_e32 v39, v123, v47
	v_dot8c_i32_i4_e32 v40, v125, v49
	v_dot8c_i32_i4_e32 v41, v125, v47
	v_dot8c_i32_i4_e32 v42, v127, v49
	v_dot8c_i32_i4_e32 v43, v127, v47
	v_dot8c_i32_i4_e32 v44, v129, v49
	v_dot8c_i32_i4_e32 v45, v129, v47
	v_and_b32_e32 v78, 0xffff, v24
	v_lshrrev_b32_e32 v79, 16, v24
	v_lshl_add_u32 v78, v78, 7, v152
	v_lshl_add_u32 v79, v79, 7, v153
	s_mov_b32 m0, s76
	s_add_i32 s43, s76, 0x400
	global_load_lds_dwordx4 v78, s[50:51]
	s_mov_b32 m0, s43
	s_nop 0
	global_load_lds_dwordx4 v79, s[50:51]
	s_waitcnt vmcnt(8)
	v_add_u32_e32 v54, s78, v59
	v_add_u32_e32 v55, s78, v60
	v_add_u32_e32 v56, s78, v61
	v_add_u32_e32 v57, s78, v62
	ds_read_b64_tr_b4 v[46:47], v160 offset:256
	ds_read_b64_tr_b4 v[48:49], v160 offset:1280
	ds_read_b64_tr_b4 v[122:123], v54
	ds_read_b64_tr_b4 v[124:125], v55
	ds_read_b64_tr_b4 v[126:127], v56
	ds_read_b64_tr_b4 v[128:129], v57
	s_waitcnt lgkmcnt(6)
	v_dot8c_i32_i4_e32 v38, v130, v52
	v_dot8c_i32_i4_e32 v39, v130, v50
	v_dot8c_i32_i4_e32 v40, v132, v52
	v_dot8c_i32_i4_e32 v41, v132, v50
	v_dot8c_i32_i4_e32 v42, v134, v52
	v_dot8c_i32_i4_e32 v43, v134, v50
	v_dot8c_i32_i4_e32 v44, v136, v52
	v_dot8c_i32_i4_e32 v45, v136, v50
	v_dot8c_i32_i4_e32 v38, v131, v53
	v_dot8c_i32_i4_e32 v39, v131, v51
	v_dot8c_i32_i4_e32 v40, v133, v53
	v_dot8c_i32_i4_e32 v41, v133, v51
	v_dot8c_i32_i4_e32 v42, v135, v53
	v_dot8c_i32_i4_e32 v43, v135, v51
	v_dot8c_i32_i4_e32 v44, v137, v53
	v_dot8c_i32_i4_e32 v45, v137, v51
	v_and_b32_e32 v78, 0xffff, v25
	v_lshrrev_b32_e32 v79, 16, v25
	v_lshl_add_u32 v78, v78, 7, v152
	v_lshl_add_u32 v79, v79, 7, v153
	s_mov_b32 m0, s77
	s_add_i32 s43, s77, 0x400
	global_load_lds_dwordx4 v78, s[50:51]
	s_mov_b32 m0, s43
	s_nop 0
	global_load_lds_dwordx4 v79, s[50:51]
	s_waitcnt vmcnt(8)
; #define TR4(p_) __builtin_amdgcn_ds_read_tr4_b64_v2i32((LAS v2i*)(p_))
; #define VDMA(st_, k_) do { _Pragma("unroll") for (int i_ = 0; i_ < 4; ++i_) { \
;         const unsigned off_ = (unsigned)((st_) >> 2) * (16384u * 128u) + (PE_ID(E, 4 * ((st_) & 3) + i_) << 7) + ((i_ & 1) ? cx1 : cx0); \
;         __builtin_amdgcn_global_load_lds((const unsigned*)(V4 + off_), (LAS unsigned*)(ldsb + BUF[k_] + 1024 * i_), 16, 0, 0); } } while (0)
; __device__ __forceinline__ void peer_v_tokens(int j, const LAS unsigned short* EL, const LAS unsigned char* AL  , const LAS float* ASC  , const LAS int* SAL  , ...
;     ...
;         for (int st = 0; st < 16; ++st) {
;             const int p = st >> 2, q = st & 3;
;             if (st < 14) VDMA(st + 2, (st + 2) % 3);
;             if (st < 14) asm volatile("s_waitcnt vmcnt(8)" ::: "memory");
;             else if (st == 14) asm volatile("s_waitcnt vmcnt(4)" ::: "memory");
;             else asm volatile("s_waitcnt vmcnt(0)" ::: "memory");
;             if (q == 0) {
; #pragma unroll
;                 for (int r = 0; r < 4; ++r) { accH[r] = 0; accL[r] = 0; } }
; #pragma unroll
;             for (int tp = 0; tp < 2; ++tp) {
;                 const v2i ao = TR4(ATL + (2 * q + tp) * 128 + 8 * s16), ah = TR4(ATL + 1024 + (2 * q + tp) * 128 + 8 * s16);
; #pragma unroll
;                 for (int r = 0; r < 4; ++r) {
;                     const v2i d = TR4(ldsb + BUF[st % 3] + 2048 * tp + roff[r]);
;                     accH[r] = __builtin_amdgcn_sdot8(d.x, ah.x, accH[r], false); accH[r] = __builtin_amdgcn_sdot8(d.y, ah.y, accH[r], false);
;                     accL[r] = __builtin_amdgcn_sdot8(d.x, ao.x, accL[r], false); accL[r] = __builtin_amdgcn_sdot8(d.y, ao.y, accL[r], false);
;                 }
;             }
	v_add_u32_e32 v54, s79, v59
	v_add_u32_e32 v55, s79, v60
	v_add_u32_e32 v56, s79, v61
	v_add_u32_e32 v57, s79, v62
	ds_read_b64_tr_b4 v[50:51], v160 offset:384
	ds_read_b64_tr_b4 v[52:53], v160 offset:1408
	ds_read_b64_tr_b4 v[130:131], v54
	ds_read_b64_tr_b4 v[132:133], v55
	ds_read_b64_tr_b4 v[134:135], v56
	ds_read_b64_tr_b4 v[136:137], v57
	s_waitcnt lgkmcnt(6)
	v_dot8c_i32_i4_e32 v38, v122, v48
	v_dot8c_i32_i4_e32 v39, v122, v46
	v_dot8c_i32_i4_e32 v40, v124, v48
	v_dot8c_i32_i4_e32 v41, v124, v46
	v_dot8c_i32_i4_e32 v42, v126, v48
	v_dot8c_i32_i4_e32 v43, v126, v46
	v_dot8c_i32_i4_e32 v44, v128, v48
	v_dot8c_i32_i4_e32 v45, v128, v46
	v_dot8c_i32_i4_e32 v38, v123, v49
	v_dot8c_i32_i4_e32 v39, v123, v47
	v_dot8c_i32_i4_e32 v40, v125, v49
	v_dot8c_i32_i4_e32 v41, v125, v47
	v_dot8c_i32_i4_e32 v42, v127, v49
	v_dot8c_i32_i4_e32 v43, v127, v47
	v_dot8c_i32_i4_e32 v44, v129, v49
	v_dot8c_i32_i4_e32 v45, v129, v47
	s_waitcnt lgkmcnt(15)
	v_and_b32_e32 v78, 0xffff, v26
	v_lshrrev_b32_e32 v79, 16, v26
	v_lshl_add_u32 v78, v78, 7, v152
	v_lshl_add_u32 v79, v79, 7, v153
	s_mov_b32 m0, s78
	s_add_i32 s43, s78, 0x400
	global_load_lds_dwordx4 v78, s[50:51]
	s_mov_b32 m0, s43
	s_nop 0
	global_load_lds_dwordx4 v79, s[50:51]
	s_waitcnt vmcnt(8)
	v_add_u32_e32 v54, s98, v59
	v_add_u32_e32 v55, s98, v60
	v_add_u32_e32 v56, s98, v61
	v_add_u32_e32 v57, s98, v62
	ds_read_b64_tr_b4 v[46:47], v160 offset:512
	ds_read_b64_tr_b4 v[48:49], v160 offset:1536
	ds_read_b64_tr_b4 v[122:123], v54
	ds_read_b64_tr_b4 v[124:125], v55
	ds_read_b64_tr_b4 v[126:127], v56
	ds_read_b64_tr_b4 v[128:129], v57
	s_waitcnt lgkmcnt(6)
	v_dot8c_i32_i4_e32 v38, v130, v52
	v_dot8c_i32_i4_e32 v39, v130, v50
	v_dot8c_i32_i4_e32 v40, v132, v52
	v_dot8c_i32_i4_e32 v41, v132, v50
	v_dot8c_i32_i4_e32 v42, v134, v52
	v_dot8c_i32_i4_e32 v43, v134, v50
	v_dot8c_i32_i4_e32 v44, v136, v52
	v_dot8c_i32_i4_e32 v45, v136, v50
	v_dot8c_i32_i4_e32 v38, v131, v53
	v_dot8c_i32_i4_e32 v39, v131, v51
	v_dot8c_i32_i4_e32 v40, v133, v53
	v_dot8c_i32_i4_e32 v41, v133, v51
	v_dot8c_i32_i4_e32 v42, v135, v53
	v_dot8c_i32_i4_e32 v43, v135, v51
	v_dot8c_i32_i4_e32 v44, v137, v53
	v_dot8c_i32_i4_e32 v45, v137, v51
	v_and_b32_e32 v78, 0xffff, v27
	v_lshrrev_b32_e32 v79, 16, v27
	v_lshl_add_u32 v78, v78, 7, v152
	v_lshl_add_u32 v79, v79, 7, v153
	s_mov_b32 m0, s79
	s_add_i32 s43, s79, 0x400
	global_load_lds_dwordx4 v78, s[50:51]
	s_mov_b32 m0, s43
	s_nop 0
	global_load_lds_dwordx4 v79, s[50:51]
	s_waitcnt vmcnt(8)
	v_add_u32_e32 v54, s99, v59
	v_add_u32_e32 v55, s99, v60
	v_add_u32_e32 v56, s99, v61
	v_add_u32_e32 v57, s99, v62
	ds_read_b64_tr_b4 v[50:51], v160 offset:640
	ds_read_b64_tr_b4 v[52:53], v160 offset:1664
	ds_read_b64_tr_b4 v[130:131], v54
	ds_read_b64_tr_b4 v[132:133], v55
	ds_read_b64_tr_b4 v[134:135], v56
	ds_read_b64_tr_b4 v[136:137], v57
	s_waitcnt lgkmcnt(6)
	v_dot8c_i32_i4_e32 v38, v122, v48
	v_dot8c_i32_i4_e32 v39, v122, v46
	v_dot8c_i32_i4_e32 v40, v124, v48
	v_dot8c_i32_i4_e32 v41, v124, v46
	v_dot8c_i32_i4_e32 v42, v126, v48
	v_dot8c_i32_i4_e32 v43, v126, v46
	v_dot8c_i32_i4_e32 v44, v128, v48
	v_dot8c_i32_i4_e32 v45, v128, v46
	v_dot8c_i32_i4_e32 v38, v123, v49
	v_dot8c_i32_i4_e32 v39, v123, v47
	v_dot8c_i32_i4_e32 v40, v125, v49
	v_dot8c_i32_i4_e32 v41, v125, v47
	v_dot8c_i32_i4_e32 v42, v127, v49
	v_dot8c_i32_i4_e32 v43, v127, v47
	v_dot8c_i32_i4_e32 v44, v129, v49
	v_dot8c_i32_i4_e32 v45, v129, v47
	s_waitcnt lgkmcnt(15)
	v_add_u32_e32 v143, 8, v139
	v_and_b32_e32 v142, 15, v143
	v_xor_b32_e32 v142, 8, v142
	v_bfe_u32 v144, v143, 4, 4
	v_mul_lo_u32 v142, v142, s92
	v_mul_lo_u32 v144, v144, s92
	v_mov_b32_e32 v143, v142
	v_mov_b32_e32 v145, v144
	ds_write2st64_b64 v159, v[142:143], v[144:145] offset1:2
	v_and_b32_e32 v78, 0xffff, v28
	v_lshrrev_b32_e32 v79, 16, v28
	v_lshl_add_u32 v78, v78, 7, v152
	v_lshl_add_u32 v79, v79, 7, v153
	s_mov_b32 m0, s98
	s_add_i32 s43, s98, 0x400
	global_load_lds_dwordx4 v78, s[50:51]
	s_mov_b32 m0, s43
	s_nop 0
	global_load_lds_dwordx4 v79, s[50:51]
	s_waitcnt vmcnt(8)
	v_add_u32_e32 v54, s76, v59
	v_add_u32_e32 v55, s76, v60
	v_add_u32_e32 v56, s76, v61
	v_add_u32_e32 v57, s76, v62
	ds_read_b64_tr_b4 v[46:47], v160 offset:768
	ds_read_b64_tr_b4 v[48:49], v160 offset:1792
	ds_read_b64_tr_b4 v[122:123], v54
	ds_read_b64_tr_b4 v[124:125], v55
	ds_read_b64_tr_b4 v[126:127], v56
	ds_read_b64_tr_b4 v[128:129], v57
	s_waitcnt lgkmcnt(7)
	v_dot8c_i32_i4_e32 v38, v130, v52
	v_dot8c_i32_i4_e32 v39, v130, v50
	v_dot8c_i32_i4_e32 v40, v132, v52
	v_dot8c_i32_i4_e32 v41, v132, v50
	v_dot8c_i32_i4_e32 v42, v134, v52
	v_dot8c_i32_i4_e32 v43, v134, v50
	v_dot8c_i32_i4_e32 v44, v136, v52
	v_dot8c_i32_i4_e32 v45, v136, v50
	v_dot8c_i32_i4_e32 v38, v131, v53
	v_dot8c_i32_i4_e32 v39, v131, v51
	v_dot8c_i32_i4_e32 v40, v133, v53
	v_dot8c_i32_i4_e32 v41, v133, v51
	v_dot8c_i32_i4_e32 v42, v135, v53
	v_dot8c_i32_i4_e32 v43, v135, v51
	v_dot8c_i32_i4_e32 v44, v137, v53
	v_dot8c_i32_i4_e32 v45, v137, v51
	v_and_b32_e32 v78, 0xffff, v29
	v_lshrrev_b32_e32 v79, 16, v29
	v_lshl_add_u32 v78, v78, 7, v152
	v_lshl_add_u32 v79, v79, 7, v153
	s_mov_b32 m0, s99
	s_add_i32 s43, s99, 0x400
	global_load_lds_dwordx4 v78, s[50:51]
	s_mov_b32 m0, s43
	s_nop 0
	global_load_lds_dwordx4 v79, s[50:51]
	s_waitcnt vmcnt(8)
	v_add_u32_e32 v54, s77, v59
	v_add_u32_e32 v55, s77, v60
	v_add_u32_e32 v56, s77, v61
	v_add_u32_e32 v57, s77, v62
	ds_read_b64_tr_b4 v[50:51], v160 offset:896
	ds_read_b64_tr_b4 v[52:53], v160 offset:1920
	ds_read_b64_tr_b4 v[130:131], v54
	ds_read_b64_tr_b4 v[132:133], v55
	ds_read_b64_tr_b4 v[134:135], v56
	ds_read_b64_tr_b4 v[136:137], v57
	s_waitcnt lgkmcnt(6)
; __device__ __forceinline__ bf16 f2bf(float f) { return (bf16)f2bfu(f); }
; #define TR4(p_) __builtin_amdgcn_ds_read_tr4_b64_v2i32((LAS v2i*)(p_))
; #define VDMA(st_, k_) do { _Pragma("unroll") for (int i_ = 0; i_ < 4; ++i_) { \
;         const unsigned off_ = (unsigned)((st_) >> 2) * (16384u * 128u) + (PE_ID(E, 4 * ((st_) & 3) + i_) << 7) + ((i_ & 1) ? cx1 : cx0); \
;         __builtin_amdgcn_global_load_lds((const unsigned*)(V4 + off_), (LAS unsigned*)(ldsb + BUF[k_] + 1024 * i_), 16, 0, 0); } } while (0)
; __device__ __forceinline__ void peer_v_tokens(int j, const LAS unsigned short* EL, const LAS unsigned char* AL  , const LAS float* ASC  , const LAS int* SAL  , ...
;     ...
;         { unsigned ho = (unsigned)t * (D / 4) + (unsigned)lane; asm volatile("" : "+v"(ho)); const uint2* hp = (const uint2*)HB + ho; const float4* gp = (const float4*)fng + lane;
; #pragma unroll
;           for (int jq = 0; jq < 4; ++jq) { hv[jq] = hp[64 * jq]; gv[jq] = gp[64 * jq]; } }
;     ...
;         for (int st = 0; st < 16; ++st) {
;             const int p = st >> 2, q = st & 3;
;             if (st < 14) VDMA(st + 2, (st + 2) % 3);
;             if (st < 14) asm volatile("s_waitcnt vmcnt(8)" ::: "memory");
;             else if (st == 14) asm volatile("s_waitcnt vmcnt(4)" ::: "memory");
;             else asm volatile("s_waitcnt vmcnt(0)" ::: "memory");
;             if (q == 0) {
; #pragma unroll
;                 for (int r = 0; r < 4; ++r) { accH[r] = 0; accL[r] = 0; } }
; #pragma unroll
;             for (int tp = 0; tp < 2; ++tp) {
;                 const v2i ao = TR4(ATL + (2 * q + tp) * 128 + 8 * s16), ah = TR4(ATL + 1024 + (2 * q + tp) * 128 + 8 * s16);
; #pragma unroll
;                 for (int r = 0; r < 4; ++r) {
;                     const v2i d = TR4(ldsb + BUF[st % 3] + 2048 * tp + roff[r]);
;                     accH[r] = __builtin_amdgcn_sdot8(d.x, ah.x, accH[r], false); accH[r] = __builtin_amdgcn_sdot8(d.y, ah.y, accH[r], false);
;                     accL[r] = __builtin_amdgcn_sdot8(d.x, ao.x, accL[r], false); accL[r] = __builtin_amdgcn_sdot8(d.y, ao.y, accL[r], false);
;                 }
;             }
;             asm volatile("s_waitcnt lgkmcnt(0)" ::: "memory");
;             if (q == 3) {
; #pragma unroll
;                 for (int r = 0; r < 4; ++r) STASH[256 * p + 16 * (grp + 4 * r) + pc] = f2bf(asc * (float)(2 * ((accH[r] << 4) + accL[r]) + sa));
	v_dot8c_i32_i4_e32 v38, v122, v48
	v_dot8c_i32_i4_e32 v39, v122, v46
	v_dot8c_i32_i4_e32 v40, v124, v48
	v_dot8c_i32_i4_e32 v41, v124, v46
	v_dot8c_i32_i4_e32 v42, v126, v48
	v_dot8c_i32_i4_e32 v43, v126, v46
	v_dot8c_i32_i4_e32 v44, v128, v48
	v_dot8c_i32_i4_e32 v45, v128, v46
	v_dot8c_i32_i4_e32 v38, v123, v49
	v_dot8c_i32_i4_e32 v39, v123, v47
	v_dot8c_i32_i4_e32 v40, v125, v49
	v_dot8c_i32_i4_e32 v41, v125, v47
	v_dot8c_i32_i4_e32 v42, v127, v49
	v_dot8c_i32_i4_e32 v43, v127, v47
	v_dot8c_i32_i4_e32 v44, v129, v49
	v_dot8c_i32_i4_e32 v45, v129, v47
	v_and_b32_e32 v78, 0xffff, v30
	v_lshrrev_b32_e32 v79, 16, v30
	v_lshl_add_u32 v78, v78, 7, v152
	v_lshl_add_u32 v79, v79, 7, v153
	s_mov_b32 m0, s76
	s_add_i32 s43, s76, 0x400
	global_load_lds_dwordx4 v78, s[50:51]
	s_mov_b32 m0, s43
	s_nop 0
	global_load_lds_dwordx4 v79, s[50:51]
	s_waitcnt vmcnt(8)
	v_add_u32_e32 v54, s78, v59
	v_add_u32_e32 v55, s78, v60
	v_add_u32_e32 v56, s78, v61
	v_add_u32_e32 v57, s78, v62
	ds_read_b64_tr_b4 v[46:47], v160
	ds_read_b64_tr_b4 v[48:49], v160 offset:1024
	ds_read_b64_tr_b4 v[122:123], v54
	ds_read_b64_tr_b4 v[124:125], v55
	ds_read_b64_tr_b4 v[126:127], v56
	ds_read_b64_tr_b4 v[128:129], v57
	s_waitcnt lgkmcnt(6)
	v_dot8c_i32_i4_e32 v38, v130, v52
	v_dot8c_i32_i4_e32 v39, v130, v50
	v_dot8c_i32_i4_e32 v40, v132, v52
	v_dot8c_i32_i4_e32 v41, v132, v50
	v_dot8c_i32_i4_e32 v42, v134, v52
	v_dot8c_i32_i4_e32 v43, v134, v50
	v_dot8c_i32_i4_e32 v44, v136, v52
	v_dot8c_i32_i4_e32 v45, v136, v50
	v_dot8c_i32_i4_e32 v38, v131, v53
	v_dot8c_i32_i4_e32 v39, v131, v51
	v_dot8c_i32_i4_e32 v40, v133, v53
	v_dot8c_i32_i4_e32 v41, v133, v51
	v_dot8c_i32_i4_e32 v42, v135, v53
	v_dot8c_i32_i4_e32 v43, v135, v51
	v_dot8c_i32_i4_e32 v44, v137, v53
	v_dot8c_i32_i4_e32 v45, v137, v51
	s_nop 3
	s_waitcnt lgkmcnt(15)
	v_lshlrev_b32_e32 v38, 5, v38
	v_lshlrev_b32_e32 v39, 1, v39
	v_add3_u32 v38, v39, v229, v38
	v_cvt_f32_i32_e32 v38, v38
	v_mul_f32_e32 v38, v228, v38
	v_lshlrev_b32_e32 v40, 5, v40
	v_lshlrev_b32_e32 v41, 1, v41
	v_add3_u32 v40, v41, v229, v40
	v_cvt_f32_i32_e32 v40, v40
	v_mul_f32_e32 v40, v228, v40
	v_lshlrev_b32_e32 v42, 5, v42
	v_lshlrev_b32_e32 v43, 1, v43
	v_add3_u32 v42, v43, v229, v42
	v_cvt_f32_i32_e32 v42, v42
	v_mul_f32_e32 v42, v228, v42
	v_lshlrev_b32_e32 v44, 5, v44
	v_lshlrev_b32_e32 v45, 1, v45
	v_add3_u32 v44, v45, v229, v44
	v_cvt_f32_i32_e32 v44, v44
	v_mul_f32_e32 v44, v228, v44
	v_cvt_pk_bf16_f32 v168, v38, v40
	v_cvt_pk_bf16_f32 v169, v42, v44
	s_add_i32 s43, s40, 0
	s_lshl_b32 s43, s43, 11
	v_add_u32_e32 v138, s43, v66
	global_load_dwordx2 v[194:195], v138, s[70:71]
	global_load_dwordx2 v[196:197], v138, s[70:71] offset:512
	global_load_dwordx2 v[198:199], v138, s[70:71] offset:1024
	global_load_dwordx2 v[200:201], v138, s[70:71] offset:1536
	v_add_u32_e32 v147, 8, v140
	v_and_b32_e32 v146, 15, v147
	v_xor_b32_e32 v146, 8, v146
	v_bfe_u32 v148, v147, 4, 4
	v_mul_lo_u32 v146, v146, s92
	v_mul_lo_u32 v148, v148, s92
	v_mov_b32_e32 v147, v146
	v_mov_b32_e32 v149, v148
	ds_write2st64_b64 v77, v[146:147], v[148:149] offset1:2
	v_add_u32_e32 v138, 0x800, v74
	ds_read_u8 v139, v138
	v_add_u32_e32 v141, 0x800, v73
	ds_read_u8 v140, v141
	s_add_i32 s43, s67, 32
	v_mov_b32_e32 v138, s43
	ds_read2st64_b32 v[228:229], v138 offset1:1
	ds_read_b128 v[18:21], v227 offset:4096
	ds_read_b128 v[22:25], v227 offset:4112
	v_mov_b32_e32 v150, v63
	v_mov_b32_e32 v151, v64
	v_mov_b32_e32 v38, 0
	v_mov_b32_e32 v39, 0
	v_mov_b32_e32 v40, 0
	v_mov_b32_e32 v41, 0
	v_mov_b32_e32 v42, 0
	v_mov_b32_e32 v43, 0
	v_mov_b32_e32 v44, 0
	v_mov_b32_e32 v45, 0
	v_and_b32_e32 v78, 0xffff, v31
	v_lshrrev_b32_e32 v79, 16, v31
	v_lshl_add_u32 v78, v78, 7, v152
	v_lshl_add_u32 v79, v79, 7, v153
	s_mov_b32 m0, s77
	s_add_i32 s43, s77, 0x400
	global_load_lds_dwordx4 v78, s[50:51]
	s_mov_b32 m0, s43
	s_nop 0
	global_load_lds_dwordx4 v79, s[50:51]
	s_waitcnt vmcnt(12)
	v_add_u32_e32 v54, s79, v59
	v_add_u32_e32 v55, s79, v60
	v_add_u32_e32 v56, s79, v61
	v_add_u32_e32 v57, s79, v62
	ds_read_b64_tr_b4 v[50:51], v160 offset:128
	ds_read_b64_tr_b4 v[52:53], v160 offset:1152
	ds_read_b64_tr_b4 v[130:131], v54
	ds_read_b64_tr_b4 v[132:133], v55
	ds_read_b64_tr_b4 v[134:135], v56
	ds_read_b64_tr_b4 v[136:137], v57
	s_waitcnt lgkmcnt(12)
	v_dot8c_i32_i4_e32 v38, v122, v48
	v_dot8c_i32_i4_e32 v39, v122, v46
	v_dot8c_i32_i4_e32 v40, v124, v48
	v_dot8c_i32_i4_e32 v41, v124, v46
	v_dot8c_i32_i4_e32 v42, v126, v48
	v_dot8c_i32_i4_e32 v43, v126, v46
	v_dot8c_i32_i4_e32 v44, v128, v48
	v_dot8c_i32_i4_e32 v45, v128, v46
	v_dot8c_i32_i4_e32 v38, v123, v49
	v_dot8c_i32_i4_e32 v39, v123, v47
	v_dot8c_i32_i4_e32 v40, v125, v49
	v_dot8c_i32_i4_e32 v41, v125, v47
	v_dot8c_i32_i4_e32 v42, v127, v49
	v_dot8c_i32_i4_e32 v43, v127, v47
	v_dot8c_i32_i4_e32 v44, v129, v49
	v_dot8c_i32_i4_e32 v45, v129, v47
	v_and_b32_e32 v78, 0xffff, v32
	v_lshrrev_b32_e32 v79, 16, v32
	v_lshl_add_u32 v78, v78, 7, v152
	v_lshl_add_u32 v79, v79, 7, v153
	s_mov_b32 m0, s78
	s_add_i32 s43, s78, 0x400
	global_load_lds_dwordx4 v78, s[50:51]
	s_mov_b32 m0, s43
	s_nop 0
	global_load_lds_dwordx4 v79, s[50:51]
	s_waitcnt vmcnt(12)
	v_add_u32_e32 v54, s98, v59
	v_add_u32_e32 v55, s98, v60
	v_add_u32_e32 v56, s98, v61
	v_add_u32_e32 v57, s98, v62
	ds_read_b64_tr_b4 v[46:47], v160 offset:256
	ds_read_b64_tr_b4 v[48:49], v160 offset:1280
	ds_read_b64_tr_b4 v[122:123], v54
	ds_read_b64_tr_b4 v[124:125], v55
	ds_read_b64_tr_b4 v[126:127], v56
	ds_read_b64_tr_b4 v[128:129], v57
	s_waitcnt lgkmcnt(6)
; #define TR4(p_) __builtin_amdgcn_ds_read_tr4_b64_v2i32((LAS v2i*)(p_))
; #define VDMA(st_, k_) do { _Pragma("unroll") for (int i_ = 0; i_ < 4; ++i_) { \
;         const unsigned off_ = (unsigned)((st_) >> 2) * (16384u * 128u) + (PE_ID(E, 4 * ((st_) & 3) + i_) << 7) + ((i_ & 1) ? cx1 : cx0); \
;         __builtin_amdgcn_global_load_lds((const unsigned*)(V4 + off_), (LAS unsigned*)(ldsb + BUF[k_] + 1024 * i_), 16, 0, 0); } } while (0)
; __device__ __forceinline__ void peer_v_tokens(int j, const LAS unsigned short* EL, const LAS unsigned char* AL  , const LAS float* ASC  , const LAS int* SAL  , ...
;     ...
;         for (int st = 0; st < 16; ++st) {
;             const int p = st >> 2, q = st & 3;
;             if (st < 14) VDMA(st + 2, (st + 2) % 3);
;             if (st < 14) asm volatile("s_waitcnt vmcnt(8)" ::: "memory");
;             else if (st == 14) asm volatile("s_waitcnt vmcnt(4)" ::: "memory");
;             else asm volatile("s_waitcnt vmcnt(0)" ::: "memory");
;             if (q == 0) {
; #pragma unroll
;                 for (int r = 0; r < 4; ++r) { accH[r] = 0; accL[r] = 0; } }
; #pragma unroll
;             for (int tp = 0; tp < 2; ++tp) {
;                 const v2i ao = TR4(ATL + (2 * q + tp) * 128 + 8 * s16), ah = TR4(ATL + 1024 + (2 * q + tp) * 128 + 8 * s16);
; #pragma unroll
;                 for (int r = 0; r < 4; ++r) {
;                     const v2i d = TR4(ldsb + BUF[st % 3] + 2048 * tp + roff[r]);
;                     accH[r] = __builtin_amdgcn_sdot8(d.x, ah.x, accH[r], false); accH[r] = __builtin_amdgcn_sdot8(d.y, ah.y, accH[r], false);
;                     accL[r] = __builtin_amdgcn_sdot8(d.x, ao.x, accL[r], false); accL[r] = __builtin_amdgcn_sdot8(d.y, ao.y, accL[r], false);
;                 }
;             }
	v_dot8c_i32_i4_e32 v38, v130, v52
	v_dot8c_i32_i4_e32 v39, v130, v50
	v_dot8c_i32_i4_e32 v40, v132, v52
	v_dot8c_i32_i4_e32 v41, v132, v50
	v_dot8c_i32_i4_e32 v42, v134, v52
	v_dot8c_i32_i4_e32 v43, v134, v50
	v_dot8c_i32_i4_e32 v44, v136, v52
	v_dot8c_i32_i4_e32 v45, v136, v50
	v_dot8c_i32_i4_e32 v38, v131, v53
	v_dot8c_i32_i4_e32 v39, v131, v51
	v_dot8c_i32_i4_e32 v40, v133, v53
	v_dot8c_i32_i4_e32 v41, v133, v51
	v_dot8c_i32_i4_e32 v42, v135, v53
	v_dot8c_i32_i4_e32 v43, v135, v51
	v_dot8c_i32_i4_e32 v44, v137, v53
	v_dot8c_i32_i4_e32 v45, v137, v51
	v_and_b32_e32 v78, 0xffff, v33
	v_lshrrev_b32_e32 v79, 16, v33
	v_lshl_add_u32 v78, v78, 7, v152
	v_lshl_add_u32 v79, v79, 7, v153
	s_mov_b32 m0, s79
	s_add_i32 s43, s79, 0x400
	global_load_lds_dwordx4 v78, s[50:51]
	s_mov_b32 m0, s43
	s_nop 0
	global_load_lds_dwordx4 v79, s[50:51]
	s_waitcnt vmcnt(12)
	v_add_u32_e32 v54, s99, v59
	v_add_u32_e32 v55, s99, v60
	v_add_u32_e32 v56, s99, v61
	v_add_u32_e32 v57, s99, v62
	ds_read_b64_tr_b4 v[50:51], v160 offset:384
	ds_read_b64_tr_b4 v[52:53], v160 offset:1408
	ds_read_b64_tr_b4 v[130:131], v54
	ds_read_b64_tr_b4 v[132:133], v55
	ds_read_b64_tr_b4 v[134:135], v56
	ds_read_b64_tr_b4 v[136:137], v57
	s_waitcnt lgkmcnt(6)
	v_dot8c_i32_i4_e32 v38, v122, v48
	v_dot8c_i32_i4_e32 v39, v122, v46
	v_dot8c_i32_i4_e32 v40, v124, v48
	v_dot8c_i32_i4_e32 v41, v124, v46
	v_dot8c_i32_i4_e32 v42, v126, v48
	v_dot8c_i32_i4_e32 v43, v126, v46
	v_dot8c_i32_i4_e32 v44, v128, v48
	v_dot8c_i32_i4_e32 v45, v128, v46
	v_dot8c_i32_i4_e32 v38, v123, v49
	v_dot8c_i32_i4_e32 v39, v123, v47
	v_dot8c_i32_i4_e32 v40, v125, v49
	v_dot8c_i32_i4_e32 v41, v125, v47
	v_dot8c_i32_i4_e32 v42, v127, v49
	v_dot8c_i32_i4_e32 v43, v127, v47
	v_dot8c_i32_i4_e32 v44, v129, v49
	v_dot8c_i32_i4_e32 v45, v129, v47
	s_waitcnt lgkmcnt(15)
	v_and_b32_e32 v78, 0xffff, v18
	v_lshrrev_b32_e32 v79, 16, v18
	v_lshl_add_u32 v78, v78, 7, v150
	v_lshl_add_u32 v79, v79, 7, v151
	s_mov_b32 m0, s98
	s_add_i32 s43, s98, 0x400
	global_load_lds_dwordx4 v78, s[50:51]
	s_mov_b32 m0, s43
	s_nop 0
	global_load_lds_dwordx4 v79, s[50:51]
	s_waitcnt vmcnt(12)
	v_add_u32_e32 v54, s76, v59
	v_add_u32_e32 v55, s76, v60
	v_add_u32_e32 v56, s76, v61
	v_add_u32_e32 v57, s76, v62
	ds_read_b64_tr_b4 v[46:47], v160 offset:512
	ds_read_b64_tr_b4 v[48:49], v160 offset:1536
	ds_read_b64_tr_b4 v[122:123], v54
	ds_read_b64_tr_b4 v[124:125], v55
	ds_read_b64_tr_b4 v[126:127], v56
	ds_read_b64_tr_b4 v[128:129], v57
	s_waitcnt lgkmcnt(6)
	v_dot8c_i32_i4_e32 v38, v130, v52
	v_dot8c_i32_i4_e32 v39, v130, v50
	v_dot8c_i32_i4_e32 v40, v132, v52
	v_dot8c_i32_i4_e32 v41, v132, v50
	v_dot8c_i32_i4_e32 v42, v134, v52
	v_dot8c_i32_i4_e32 v43, v134, v50
	v_dot8c_i32_i4_e32 v44, v136, v52
	v_dot8c_i32_i4_e32 v45, v136, v50
	v_dot8c_i32_i4_e32 v38, v131, v53
	v_dot8c_i32_i4_e32 v39, v131, v51
	v_dot8c_i32_i4_e32 v40, v133, v53
	v_dot8c_i32_i4_e32 v41, v133, v51
	v_dot8c_i32_i4_e32 v42, v135, v53
	v_dot8c_i32_i4_e32 v43, v135, v51
	v_dot8c_i32_i4_e32 v44, v137, v53
	v_dot8c_i32_i4_e32 v45, v137, v51
	v_and_b32_e32 v78, 0xffff, v19
	v_lshrrev_b32_e32 v79, 16, v19
	v_lshl_add_u32 v78, v78, 7, v150
	v_lshl_add_u32 v79, v79, 7, v151
	s_mov_b32 m0, s99
	s_add_i32 s43, s99, 0x400
	global_load_lds_dwordx4 v78, s[50:51]
	s_mov_b32 m0, s43
	s_nop 0
	global_load_lds_dwordx4 v79, s[50:51]
	s_waitcnt vmcnt(8)
	v_add_u32_e32 v54, s77, v59
	v_add_u32_e32 v55, s77, v60
	v_add_u32_e32 v56, s77, v61
	v_add_u32_e32 v57, s77, v62
	ds_read_b64_tr_b4 v[50:51], v160 offset:640
	ds_read_b64_tr_b4 v[52:53], v160 offset:1664
	ds_read_b64_tr_b4 v[130:131], v54
	ds_read_b64_tr_b4 v[132:133], v55
	ds_read_b64_tr_b4 v[134:135], v56
	ds_read_b64_tr_b4 v[136:137], v57
	s_waitcnt lgkmcnt(6)
	v_dot8c_i32_i4_e32 v38, v122, v48
	v_dot8c_i32_i4_e32 v39, v122, v46
	v_dot8c_i32_i4_e32 v40, v124, v48
	v_dot8c_i32_i4_e32 v41, v124, v46
	v_dot8c_i32_i4_e32 v42, v126, v48
	v_dot8c_i32_i4_e32 v43, v126, v46
	v_dot8c_i32_i4_e32 v44, v128, v48
	v_dot8c_i32_i4_e32 v45, v128, v46
	v_dot8c_i32_i4_e32 v38, v123, v49
	v_dot8c_i32_i4_e32 v39, v123, v47
	v_dot8c_i32_i4_e32 v40, v125, v49
	v_dot8c_i32_i4_e32 v41, v125, v47
	v_dot8c_i32_i4_e32 v42, v127, v49
	v_dot8c_i32_i4_e32 v43, v127, v47
	v_dot8c_i32_i4_e32 v44, v129, v49
	v_dot8c_i32_i4_e32 v45, v129, v47
	s_waitcnt lgkmcnt(15)
	v_add_u32_e32 v143, 8, v139
	v_and_b32_e32 v142, 15, v143
	v_xor_b32_e32 v142, 8, v142
	v_bfe_u32 v144, v143, 4, 4
	v_mul_lo_u32 v142, v142, s92
	v_mul_lo_u32 v144, v144, s92
	v_mov_b32_e32 v143, v142
	v_mov_b32_e32 v145, v144
	ds_write2st64_b64 v159, v[142:143], v[144:145] offset1:2
	v_and_b32_e32 v78, 0xffff, v20
	v_lshrrev_b32_e32 v79, 16, v20
	v_lshl_add_u32 v78, v78, 7, v150
	v_lshl_add_u32 v79, v79, 7, v151
	s_mov_b32 m0, s76
	s_add_i32 s43, s76, 0x400
	global_load_lds_dwordx4 v78, s[50:51]
	s_mov_b32 m0, s43
	s_nop 0
	global_load_lds_dwordx4 v79, s[50:51]
	s_waitcnt vmcnt(8)
	v_add_u32_e32 v54, s78, v59
	v_add_u32_e32 v55, s78, v60
	v_add_u32_e32 v56, s78, v61
	v_add_u32_e32 v57, s78, v62
	ds_read_b64_tr_b4 v[46:47], v160 offset:768
	ds_read_b64_tr_b4 v[48:49], v160 offset:1792
	ds_read_b64_tr_b4 v[122:123], v54
	ds_read_b64_tr_b4 v[124:125], v55
	ds_read_b64_tr_b4 v[126:127], v56
	ds_read_b64_tr_b4 v[128:129], v57
	s_waitcnt lgkmcnt(7)
; __device__ __forceinline__ bf16 f2bf(float f) { return (bf16)f2bfu(f); }
; #define TR4(p_) __builtin_amdgcn_ds_read_tr4_b64_v2i32((LAS v2i*)(p_))
; #define VDMA(st_, k_) do { _Pragma("unroll") for (int i_ = 0; i_ < 4; ++i_) { \
;         const unsigned off_ = (unsigned)((st_) >> 2) * (16384u * 128u) + (PE_ID(E, 4 * ((st_) & 3) + i_) << 7) + ((i_ & 1) ? cx1 : cx0); \
;         __builtin_amdgcn_global_load_lds((const unsigned*)(V4 + off_), (LAS unsigned*)(ldsb + BUF[k_] + 1024 * i_), 16, 0, 0); } } while (0)
; __device__ __forceinline__ void peer_v_tokens(int j, const LAS unsigned short* EL, const LAS unsigned char* AL  , const LAS float* ASC  , const LAS int* SAL  , ...
;     ...
;         for (int st = 0; st < 16; ++st) {
;             const int p = st >> 2, q = st & 3;
;             if (st < 14) VDMA(st + 2, (st + 2) % 3);
;             if (st < 14) asm volatile("s_waitcnt vmcnt(8)" ::: "memory");
;             else if (st == 14) asm volatile("s_waitcnt vmcnt(4)" ::: "memory");
;             else asm volatile("s_waitcnt vmcnt(0)" ::: "memory");
;             if (q == 0) {
; #pragma unroll
;                 for (int r = 0; r < 4; ++r) { accH[r] = 0; accL[r] = 0; } }
; #pragma unroll
;             for (int tp = 0; tp < 2; ++tp) {
;                 const v2i ao = TR4(ATL + (2 * q + tp) * 128 + 8 * s16), ah = TR4(ATL + 1024 + (2 * q + tp) * 128 + 8 * s16);
; #pragma unroll
;                 for (int r = 0; r < 4; ++r) {
;                     const v2i d = TR4(ldsb + BUF[st % 3] + 2048 * tp + roff[r]);
;                     accH[r] = __builtin_amdgcn_sdot8(d.x, ah.x, accH[r], false); accH[r] = __builtin_amdgcn_sdot8(d.y, ah.y, accH[r], false);
;                     accL[r] = __builtin_amdgcn_sdot8(d.x, ao.x, accL[r], false); accL[r] = __builtin_amdgcn_sdot8(d.y, ao.y, accL[r], false);
;                 }
;             }
;             asm volatile("s_waitcnt lgkmcnt(0)" ::: "memory");
;             if (q == 3) {
; #pragma unroll
;                 for (int r = 0; r < 4; ++r) STASH[256 * p + 16 * (grp + 4 * r) + pc] = f2bf(asc * (float)(2 * ((accH[r] << 4) + accL[r]) + sa));
	v_dot8c_i32_i4_e32 v38, v130, v52
	v_dot8c_i32_i4_e32 v39, v130, v50
	v_dot8c_i32_i4_e32 v40, v132, v52
	v_dot8c_i32_i4_e32 v41, v132, v50
	v_dot8c_i32_i4_e32 v42, v134, v52
	v_dot8c_i32_i4_e32 v43, v134, v50
	v_dot8c_i32_i4_e32 v44, v136, v52
	v_dot8c_i32_i4_e32 v45, v136, v50
	v_dot8c_i32_i4_e32 v38, v131, v53
	v_dot8c_i32_i4_e32 v39, v131, v51
	v_dot8c_i32_i4_e32 v40, v133, v53
	v_dot8c_i32_i4_e32 v41, v133, v51
	v_dot8c_i32_i4_e32 v42, v135, v53
	v_dot8c_i32_i4_e32 v43, v135, v51
	v_dot8c_i32_i4_e32 v44, v137, v53
	v_dot8c_i32_i4_e32 v45, v137, v51
	v_and_b32_e32 v78, 0xffff, v21
	v_lshrrev_b32_e32 v79, 16, v21
	v_lshl_add_u32 v78, v78, 7, v150
	v_lshl_add_u32 v79, v79, 7, v151
	s_mov_b32 m0, s77
	s_add_i32 s43, s77, 0x400
	global_load_lds_dwordx4 v78, s[50:51]
	s_mov_b32 m0, s43
	s_nop 0
	global_load_lds_dwordx4 v79, s[50:51]
	s_waitcnt vmcnt(8)
	v_add_u32_e32 v54, s79, v59
	v_add_u32_e32 v55, s79, v60
	v_add_u32_e32 v56, s79, v61
	v_add_u32_e32 v57, s79, v62
	ds_read_b64_tr_b4 v[50:51], v160 offset:896
	ds_read_b64_tr_b4 v[52:53], v160 offset:1920
	ds_read_b64_tr_b4 v[130:131], v54
	ds_read_b64_tr_b4 v[132:133], v55
	ds_read_b64_tr_b4 v[134:135], v56
	ds_read_b64_tr_b4 v[136:137], v57
	s_waitcnt lgkmcnt(6)
	v_dot8c_i32_i4_e32 v38, v122, v48
	v_dot8c_i32_i4_e32 v39, v122, v46
	v_dot8c_i32_i4_e32 v40, v124, v48
	v_dot8c_i32_i4_e32 v41, v124, v46
	v_dot8c_i32_i4_e32 v42, v126, v48
	v_dot8c_i32_i4_e32 v43, v126, v46
	v_dot8c_i32_i4_e32 v44, v128, v48
	v_dot8c_i32_i4_e32 v45, v128, v46
	v_dot8c_i32_i4_e32 v38, v123, v49
	v_dot8c_i32_i4_e32 v39, v123, v47
	v_dot8c_i32_i4_e32 v40, v125, v49
	v_dot8c_i32_i4_e32 v41, v125, v47
	v_dot8c_i32_i4_e32 v42, v127, v49
	v_dot8c_i32_i4_e32 v43, v127, v47
	v_dot8c_i32_i4_e32 v44, v129, v49
	v_dot8c_i32_i4_e32 v45, v129, v47
	v_and_b32_e32 v78, 0xffff, v22
	v_lshrrev_b32_e32 v79, 16, v22
	v_lshl_add_u32 v78, v78, 7, v150
	v_lshl_add_u32 v79, v79, 7, v151
	s_mov_b32 m0, s78
	s_add_i32 s43, s78, 0x400
	global_load_lds_dwordx4 v78, s[50:51]
	s_mov_b32 m0, s43
	s_nop 0
	global_load_lds_dwordx4 v79, s[50:51]
	s_waitcnt vmcnt(8)
	v_add_u32_e32 v54, s98, v59
	v_add_u32_e32 v55, s98, v60
	v_add_u32_e32 v56, s98, v61
	v_add_u32_e32 v57, s98, v62
	ds_read_b64_tr_b4 v[46:47], v160
	ds_read_b64_tr_b4 v[48:49], v160 offset:1024
	ds_read_b64_tr_b4 v[122:123], v54
	ds_read_b64_tr_b4 v[124:125], v55
	ds_read_b64_tr_b4 v[126:127], v56
	ds_read_b64_tr_b4 v[128:129], v57
	s_waitcnt lgkmcnt(6)
	v_dot8c_i32_i4_e32 v38, v130, v52
	v_dot8c_i32_i4_e32 v39, v130, v50
	v_dot8c_i32_i4_e32 v40, v132, v52
	v_dot8c_i32_i4_e32 v41, v132, v50
	v_dot8c_i32_i4_e32 v42, v134, v52
	v_dot8c_i32_i4_e32 v43, v134, v50
	v_dot8c_i32_i4_e32 v44, v136, v52
	v_dot8c_i32_i4_e32 v45, v136, v50
	v_dot8c_i32_i4_e32 v38, v131, v53
	v_dot8c_i32_i4_e32 v39, v131, v51
	v_dot8c_i32_i4_e32 v40, v133, v53
	v_dot8c_i32_i4_e32 v41, v133, v51
	v_dot8c_i32_i4_e32 v42, v135, v53
	v_dot8c_i32_i4_e32 v43, v135, v51
	v_dot8c_i32_i4_e32 v44, v137, v53
	v_dot8c_i32_i4_e32 v45, v137, v51
	s_nop 3
	s_waitcnt lgkmcnt(15)
	v_lshlrev_b32_e32 v38, 5, v38
	v_lshlrev_b32_e32 v39, 1, v39
	v_add3_u32 v38, v39, v229, v38
	v_cvt_f32_i32_e32 v38, v38
	v_mul_f32_e32 v38, v228, v38
	v_lshlrev_b32_e32 v40, 5, v40
	v_lshlrev_b32_e32 v41, 1, v41
	v_add3_u32 v40, v41, v229, v40
	v_cvt_f32_i32_e32 v40, v40
	v_mul_f32_e32 v40, v228, v40
	v_lshlrev_b32_e32 v42, 5, v42
	v_lshlrev_b32_e32 v43, 1, v43
	v_add3_u32 v42, v43, v229, v42
	v_cvt_f32_i32_e32 v42, v42
	v_mul_f32_e32 v42, v228, v42
	v_lshlrev_b32_e32 v44, 5, v44
	v_lshlrev_b32_e32 v45, 1, v45
	v_add3_u32 v44, v45, v229, v44
	v_cvt_f32_i32_e32 v44, v44
	v_mul_f32_e32 v44, v228, v44
	v_cvt_pk_bf16_f32 v176, v38, v40
	v_cvt_pk_bf16_f32 v177, v42, v44
	v_add_u32_e32 v147, 8, v140
	v_and_b32_e32 v146, 15, v147
	v_xor_b32_e32 v146, 8, v146
	v_bfe_u32 v148, v147, 4, 4
	v_mul_lo_u32 v146, v146, s92
	v_mul_lo_u32 v148, v148, s92
	v_mov_b32_e32 v147, v146
	v_mov_b32_e32 v149, v148
	ds_write2st64_b64 v77, v[146:147], v[148:149] offset1:2
	v_add_u32_e32 v138, 0xc00, v74
	ds_read_u8 v139, v138
	v_add_u32_e32 v141, 0xc00, v73
	ds_read_u8 v140, v141
	s_add_i32 s43, s67, 64
	v_mov_b32_e32 v138, s43
	ds_read2st64_b32 v[228:229], v138 offset1:1
	ds_read_b128 v[26:29], v227 offset:6144
	ds_read_b128 v[30:33], v227 offset:6160
	v_mov_b32_e32 v38, 0
	v_mov_b32_e32 v39, 0
	v_mov_b32_e32 v40, 0
	v_mov_b32_e32 v41, 0
	v_mov_b32_e32 v42, 0
	v_mov_b32_e32 v43, 0
	v_mov_b32_e32 v44, 0
	v_mov_b32_e32 v45, 0
	v_and_b32_e32 v78, 0xffff, v23
	v_lshrrev_b32_e32 v79, 16, v23
	v_lshl_add_u32 v78, v78, 7, v150
	v_lshl_add_u32 v79, v79, 7, v151
	s_mov_b32 m0, s79
	s_add_i32 s43, s79, 0x400
	global_load_lds_dwordx4 v78, s[50:51]
	s_mov_b32 m0, s43
	s_nop 0
	global_load_lds_dwordx4 v79, s[50:51]
	s_waitcnt vmcnt(8)
	v_add_u32_e32 v54, s99, v59
	v_add_u32_e32 v55, s99, v60
	v_add_u32_e32 v56, s99, v61
	v_add_u32_e32 v57, s99, v62
	ds_read_b64_tr_b4 v[50:51], v160 offset:128
	ds_read_b64_tr_b4 v[52:53], v160 offset:1152
	ds_read_b64_tr_b4 v[130:131], v54
	ds_read_b64_tr_b4 v[132:133], v55
	ds_read_b64_tr_b4 v[134:135], v56
	ds_read_b64_tr_b4 v[136:137], v57
	s_waitcnt lgkmcnt(12)
	v_dot8c_i32_i4_e32 v38, v122, v48
	v_dot8c_i32_i4_e32 v39, v122, v46
	v_dot8c_i32_i4_e32 v40, v124, v48
	v_dot8c_i32_i4_e32 v41, v124, v46
	v_dot8c_i32_i4_e32 v42, v126, v48
	v_dot8c_i32_i4_e32 v43, v126, v46
	v_dot8c_i32_i4_e32 v44, v128, v48
	v_dot8c_i32_i4_e32 v45, v128, v46
	v_dot8c_i32_i4_e32 v38, v123, v49
	v_dot8c_i32_i4_e32 v39, v123, v47
	v_dot8c_i32_i4_e32 v40, v125, v49
	v_dot8c_i32_i4_e32 v41, v125, v47
	v_dot8c_i32_i4_e32 v42, v127, v49
	v_dot8c_i32_i4_e32 v43, v127, v47
	v_dot8c_i32_i4_e32 v44, v129, v49
	v_dot8c_i32_i4_e32 v45, v129, v47
	v_and_b32_e32 v78, 0xffff, v24
	v_lshrrev_b32_e32 v79, 16, v24
	v_lshl_add_u32 v78, v78, 7, v150
	v_lshl_add_u32 v79, v79, 7, v151
	s_mov_b32 m0, s98
	s_add_i32 s43, s98, 0x400
	global_load_lds_dwordx4 v78, s[50:51]
	s_mov_b32 m0, s43
	s_nop 0
	global_load_lds_dwordx4 v79, s[50:51]
	s_waitcnt vmcnt(8)
; #define LAS __attribute__((address_space(3)))
; __device__ __forceinline__ bf16 f2bf(float f) { return (bf16)f2bfu(f); }
; #define TR4(p_) __builtin_amdgcn_ds_read_tr4_b64_v2i32((LAS v2i*)(p_))
; #define CFENCE() asm volatile("" ::: "memory")
; __device__ __forceinline__ void peer_v_tokens(int j, const LAS unsigned short* EL, const LAS unsigned char* AL  , const LAS float* ASC  , const LAS int* SAL  , ...
;     ...
;             for (int tp = 0; tp < 2; ++tp) {
;                 const v2i ao = TR4(ATL + (2 * q + tp) * 128 + 8 * s16), ah = TR4(ATL + 1024 + (2 * q + tp) * 128 + 8 * s16);
; #pragma unroll
;                 for (int r = 0; r < 4; ++r) {
;                     const v2i d = TR4(ldsb + BUF[st % 3] + 2048 * tp + roff[r]);
;                     accH[r] = __builtin_amdgcn_sdot8(d.x, ah.x, accH[r], false); accH[r] = __builtin_amdgcn_sdot8(d.y, ah.y, accH[r], false);
;                     accL[r] = __builtin_amdgcn_sdot8(d.x, ao.x, accL[r], false); accL[r] = __builtin_amdgcn_sdot8(d.y, ao.y, accL[r], false);
;                 }
;             }
;             asm volatile("s_waitcnt lgkmcnt(0)" ::: "memory");
;             if (q == 3) {
; #pragma unroll
;                 for (int r = 0; r < 4; ++r) STASH[256 * p + 16 * (grp + 4 * r) + pc] = f2bf(asc * (float)(2 * ((accH[r] << 4) + accL[r]) + sa));
;             }
;         }
;         CFENCE();
;         {
;             float4 v[4]; float ss = 0.f;
; #pragma unroll
;             for (int jq = 0; jq < 4; ++jq) { typedef unsigned u2v __attribute__((ext_vector_type(2))); const u2v pw = *(const LAS u2v*)(STASH + 4 * lane + 256 * jq); const uint2 hw = hv[jq];
	v_add_u32_e32 v54, s76, v59
	v_add_u32_e32 v55, s76, v60
	v_add_u32_e32 v56, s76, v61
	v_add_u32_e32 v57, s76, v62
	ds_read_b64_tr_b4 v[46:47], v160 offset:256
	ds_read_b64_tr_b4 v[48:49], v160 offset:1280
	ds_read_b64_tr_b4 v[122:123], v54
	ds_read_b64_tr_b4 v[124:125], v55
	ds_read_b64_tr_b4 v[126:127], v56
	ds_read_b64_tr_b4 v[128:129], v57
	s_waitcnt lgkmcnt(6)
	v_dot8c_i32_i4_e32 v38, v130, v52
	v_dot8c_i32_i4_e32 v39, v130, v50
	v_dot8c_i32_i4_e32 v40, v132, v52
	v_dot8c_i32_i4_e32 v41, v132, v50
	v_dot8c_i32_i4_e32 v42, v134, v52
	v_dot8c_i32_i4_e32 v43, v134, v50
	v_dot8c_i32_i4_e32 v44, v136, v52
	v_dot8c_i32_i4_e32 v45, v136, v50
	v_dot8c_i32_i4_e32 v38, v131, v53
	v_dot8c_i32_i4_e32 v39, v131, v51
	v_dot8c_i32_i4_e32 v40, v133, v53
	v_dot8c_i32_i4_e32 v41, v133, v51
	v_dot8c_i32_i4_e32 v42, v135, v53
	v_dot8c_i32_i4_e32 v43, v135, v51
	v_dot8c_i32_i4_e32 v44, v137, v53
	v_dot8c_i32_i4_e32 v45, v137, v51
	ds_write_b16 v65, v162
	ds_write_b16_d16_hi v65, v162 offset:128
	ds_write_b16 v65, v163 offset:256
	ds_write_b16_d16_hi v65, v163 offset:384
	ds_write_b16 v65, v164 offset:512
	ds_write_b16_d16_hi v65, v164 offset:640
	ds_write_b16 v65, v165 offset:768
	ds_write_b16_d16_hi v65, v165 offset:896
	ds_write_b16 v65, v166 offset:1024
	ds_write_b16_d16_hi v65, v166 offset:1152
	ds_write_b16 v65, v167 offset:1280
	ds_write_b16_d16_hi v65, v167 offset:1408
	ds_write_b16 v65, v168 offset:1536
	ds_write_b16_d16_hi v65, v168 offset:1664
	ds_write_b16 v65, v169 offset:1792
	ds_write_b16_d16_hi v65, v169 offset:1920
	ds_read_b64 v[202:203], v154
	ds_read_b64 v[204:205], v154 offset:512
	ds_read_b64 v[206:207], v154 offset:1024
	ds_read_b64 v[208:209], v154 offset:1536
	v_and_b32_e32 v78, 0xffff, v25
	v_lshrrev_b32_e32 v79, 16, v25
	v_lshl_add_u32 v78, v78, 7, v150
	v_lshl_add_u32 v79, v79, 7, v151
	s_mov_b32 m0, s99
	s_add_i32 s43, s99, 0x400
	global_load_lds_dwordx4 v78, s[50:51]
	s_mov_b32 m0, s43
	s_nop 0
	global_load_lds_dwordx4 v79, s[50:51]
	s_waitcnt vmcnt(8)
	v_add_u32_e32 v54, s77, v59
	v_add_u32_e32 v55, s77, v60
	v_add_u32_e32 v56, s77, v61
	v_add_u32_e32 v57, s77, v62
	ds_read_b64_tr_b4 v[50:51], v160 offset:384
	ds_read_b64_tr_b4 v[52:53], v160 offset:1408
	ds_read_b64_tr_b4 v[130:131], v54
	ds_read_b64_tr_b4 v[132:133], v55
	ds_read_b64_tr_b4 v[134:135], v56
	ds_read_b64_tr_b4 v[136:137], v57
	s_waitcnt lgkmcnt(15)
	v_dot8c_i32_i4_e32 v38, v122, v48
	v_dot8c_i32_i4_e32 v39, v122, v46
	v_dot8c_i32_i4_e32 v40, v124, v48
	v_dot8c_i32_i4_e32 v41, v124, v46
	v_dot8c_i32_i4_e32 v42, v126, v48
	v_dot8c_i32_i4_e32 v43, v126, v46
	v_dot8c_i32_i4_e32 v44, v128, v48
	v_dot8c_i32_i4_e32 v45, v128, v46
	v_dot8c_i32_i4_e32 v38, v123, v49
	v_dot8c_i32_i4_e32 v39, v123, v47
	v_dot8c_i32_i4_e32 v40, v125, v49
	v_dot8c_i32_i4_e32 v41, v125, v47
	v_dot8c_i32_i4_e32 v42, v127, v49
	v_dot8c_i32_i4_e32 v43, v127, v47
	v_dot8c_i32_i4_e32 v44, v129, v49
	v_dot8c_i32_i4_e32 v45, v129, v47
	s_waitcnt lgkmcnt(15)
	v_and_b32_e32 v78, 0xffff, v26
	v_lshrrev_b32_e32 v79, 16, v26
	v_lshl_add_u32 v78, v78, 7, v150
	v_lshl_add_u32 v79, v79, 7, v151
	s_mov_b32 m0, s76
	s_add_i32 s43, s76, 0x400
	global_load_lds_dwordx4 v78, s[50:51]
	s_mov_b32 m0, s43
	s_nop 0
	global_load_lds_dwordx4 v79, s[50:51]
	s_waitcnt vmcnt(8)
	v_add_u32_e32 v54, s78, v59
	v_add_u32_e32 v55, s78, v60
	v_add_u32_e32 v56, s78, v61
	v_add_u32_e32 v57, s78, v62
	ds_read_b64_tr_b4 v[46:47], v160 offset:512
	ds_read_b64_tr_b4 v[48:49], v160 offset:1536
	ds_read_b64_tr_b4 v[122:123], v54
	ds_read_b64_tr_b4 v[124:125], v55
	ds_read_b64_tr_b4 v[126:127], v56
	ds_read_b64_tr_b4 v[128:129], v57
	s_waitcnt lgkmcnt(6)
	v_dot8c_i32_i4_e32 v38, v130, v52
	v_dot8c_i32_i4_e32 v39, v130, v50
	v_dot8c_i32_i4_e32 v40, v132, v52
	v_dot8c_i32_i4_e32 v41, v132, v50
	v_dot8c_i32_i4_e32 v42, v134, v52
	v_dot8c_i32_i4_e32 v43, v134, v50
	v_dot8c_i32_i4_e32 v44, v136, v52
	v_dot8c_i32_i4_e32 v45, v136, v50
	v_dot8c_i32_i4_e32 v38, v131, v53
	v_dot8c_i32_i4_e32 v39, v131, v51
	v_dot8c_i32_i4_e32 v40, v133, v53
	v_dot8c_i32_i4_e32 v41, v133, v51
	v_dot8c_i32_i4_e32 v42, v135, v53
	v_dot8c_i32_i4_e32 v43, v135, v51
	v_dot8c_i32_i4_e32 v44, v137, v53
	v_dot8c_i32_i4_e32 v45, v137, v51
	v_and_b32_e32 v78, 0xffff, v27
	v_lshrrev_b32_e32 v79, 16, v27
	v_lshl_add_u32 v78, v78, 7, v150
	v_lshl_add_u32 v79, v79, 7, v151
	s_mov_b32 m0, s77
	s_add_i32 s43, s77, 0x400
	global_load_lds_dwordx4 v78, s[50:51]
	s_mov_b32 m0, s43
	s_nop 0
	global_load_lds_dwordx4 v79, s[50:51]
	s_waitcnt vmcnt(8)
	v_add_u32_e32 v54, s79, v59
	v_add_u32_e32 v55, s79, v60
	v_add_u32_e32 v56, s79, v61
	v_add_u32_e32 v57, s79, v62
	ds_read_b64_tr_b4 v[50:51], v160 offset:640
	ds_read_b64_tr_b4 v[52:53], v160 offset:1664
	ds_read_b64_tr_b4 v[130:131], v54
	ds_read_b64_tr_b4 v[132:133], v55
	ds_read_b64_tr_b4 v[134:135], v56
	ds_read_b64_tr_b4 v[136:137], v57
	s_waitcnt lgkmcnt(6)
	v_dot8c_i32_i4_e32 v38, v122, v48
	v_dot8c_i32_i4_e32 v39, v122, v46
	v_dot8c_i32_i4_e32 v40, v124, v48
	v_dot8c_i32_i4_e32 v41, v124, v46
	v_dot8c_i32_i4_e32 v42, v126, v48
	v_dot8c_i32_i4_e32 v43, v126, v46
	v_dot8c_i32_i4_e32 v44, v128, v48
	v_dot8c_i32_i4_e32 v45, v128, v46
	v_dot8c_i32_i4_e32 v38, v123, v49
	v_dot8c_i32_i4_e32 v39, v123, v47
	v_dot8c_i32_i4_e32 v40, v125, v49
	v_dot8c_i32_i4_e32 v41, v125, v47
	v_dot8c_i32_i4_e32 v42, v127, v49
	v_dot8c_i32_i4_e32 v43, v127, v47
	v_dot8c_i32_i4_e32 v44, v129, v49
	v_dot8c_i32_i4_e32 v45, v129, v47
	s_waitcnt lgkmcnt(15)
; #define LAS __attribute__((address_space(3)))
; __device__ __forceinline__ void peer_v_tokens(int j, const LAS unsigned short* EL, const LAS unsigned char* AL  , const LAS float* ASC  , const LAS int* SAL  , ...
;     ...
;         for (int m = 0; m < 2; ++m) {
;             const int idx = lane + 64 * m, tau = idx >> 4, sr = idx & 15, k = 16 * (sr & 7) + 2 * tau + (sr >> 3);
;             const int aq = (int)*(const LAS signed char*)(AL + tl * 128 + k); const int tq = aq + 8;
;             const unsigned lo = (((unsigned)tq & 15u) ^ 8u) * 0x11111111u, hi = ((unsigned)(tq >> 4) & 15u) * 0x11111111u;
;             typedef unsigned u2v __attribute__((ext_vector_type(2)));
;             u2v l2; l2.x = lo; l2.y = lo; u2v h2; h2.x = hi; h2.y = hi;
;             *(LAS u2v*)(ATL + 8 * idx) = l2; *(LAS u2v*)(ATL + 1024 + 8 * idx) = h2;
;         }
;         const float asc = ASC[tl]; const int sa = SAL[tl];
;         CFENCE();
;         int accH[4], accL[4];
; #pragma unroll
;         for (int st = 0; st < 16; ++st) {
;             const int p = st >> 2, q = st & 3;
;             if (st < 14) VDMA(st + 2, (st + 2) % 3);
;             if (st < 14) asm volatile("s_waitcnt vmcnt(8)" ::: "memory");
;             else if (st == 14) asm volatile("s_waitcnt vmcnt(4)" ::: "memory");
;             else asm volatile("s_waitcnt vmcnt(0)" ::: "memory");
;             if (q == 0) {
; #pragma unroll
;                 for (int r = 0; r < 4; ++r) { accH[r] = 0; accL[r] = 0; } }
; #pragma unroll
;             for (int tp = 0; tp < 2; ++tp) {
;                 const v2i ao = TR4(ATL + (2 * q + tp) * 128 + 8 * s16), ah = TR4(ATL + 1024 + (2 * q + tp) * 128 + 8 * s16);
; #pragma unroll
;                 for (int r = 0; r < 4; ++r) {
;                     const v2i d = TR4(ldsb + BUF[st % 3] + 2048 * tp + roff[r]);
;                     accH[r] = __builtin_amdgcn_sdot8(d.x, ah.x, accH[r], false); accH[r] = __builtin_amdgcn_sdot8(d.y, ah.y, accH[r], false);
;                     accL[r] = __builtin_amdgcn_sdot8(d.x, ao.x, accL[r], false); accL[r] = __builtin_amdgcn_sdot8(d.y, ao.y, accL[r], false);
;                 }
;             }
;             asm volatile("s_waitcnt lgkmcnt(0)" ::: "memory");
;             if (q == 3) {
; #pragma unroll
;                 for (int r = 0; r < 4; ++r) STASH[256 * p + 16 * (grp + 4 * r) + pc] = f2bf(asc * (float)(2 * ((accH[r] << 4) + accL[r]) + sa));
	v_add_u32_e32 v143, 8, v139
	v_and_b32_e32 v142, 15, v143
	v_xor_b32_e32 v142, 8, v142
	v_bfe_u32 v144, v143, 4, 4
	v_mul_lo_u32 v142, v142, s92
	v_mul_lo_u32 v144, v144, s92
	v_mov_b32_e32 v143, v142
	v_mov_b32_e32 v145, v144
	ds_write2st64_b64 v159, v[142:143], v[144:145] offset1:2
	v_and_b32_e32 v78, 0xffff, v28
	v_lshrrev_b32_e32 v79, 16, v28
	v_lshl_add_u32 v78, v78, 7, v150
	v_lshl_add_u32 v79, v79, 7, v151
	s_mov_b32 m0, s78
	s_add_i32 s43, s78, 0x400
	global_load_lds_dwordx4 v78, s[50:51]
	s_mov_b32 m0, s43
	s_nop 0
	global_load_lds_dwordx4 v79, s[50:51]
	s_waitcnt vmcnt(8)
	v_add_u32_e32 v54, s98, v59
	v_add_u32_e32 v55, s98, v60
	v_add_u32_e32 v56, s98, v61
	v_add_u32_e32 v57, s98, v62
	ds_read_b64_tr_b4 v[46:47], v160 offset:768
	ds_read_b64_tr_b4 v[48:49], v160 offset:1792
	ds_read_b64_tr_b4 v[122:123], v54
	ds_read_b64_tr_b4 v[124:125], v55
	ds_read_b64_tr_b4 v[126:127], v56
	ds_read_b64_tr_b4 v[128:129], v57
	s_waitcnt lgkmcnt(7)
	v_dot8c_i32_i4_e32 v38, v130, v52
	v_dot8c_i32_i4_e32 v39, v130, v50
	v_dot8c_i32_i4_e32 v40, v132, v52
	v_dot8c_i32_i4_e32 v41, v132, v50
	v_dot8c_i32_i4_e32 v42, v134, v52
	v_dot8c_i32_i4_e32 v43, v134, v50
	v_dot8c_i32_i4_e32 v44, v136, v52
	v_dot8c_i32_i4_e32 v45, v136, v50
	v_dot8c_i32_i4_e32 v38, v131, v53
	v_dot8c_i32_i4_e32 v39, v131, v51
	v_dot8c_i32_i4_e32 v40, v133, v53
	v_dot8c_i32_i4_e32 v41, v133, v51
	v_dot8c_i32_i4_e32 v42, v135, v53
	v_dot8c_i32_i4_e32 v43, v135, v51
	v_dot8c_i32_i4_e32 v44, v137, v53
	v_dot8c_i32_i4_e32 v45, v137, v51
	v_and_b32_e32 v78, 0xffff, v29
	v_lshrrev_b32_e32 v79, 16, v29
	v_lshl_add_u32 v78, v78, 7, v150
	v_lshl_add_u32 v79, v79, 7, v151
	s_mov_b32 m0, s79
	s_add_i32 s43, s79, 0x400
	global_load_lds_dwordx4 v78, s[50:51]
	s_mov_b32 m0, s43
	s_nop 0
	global_load_lds_dwordx4 v79, s[50:51]
	s_waitcnt vmcnt(8)
	v_add_u32_e32 v54, s99, v59
	v_add_u32_e32 v55, s99, v60
	v_add_u32_e32 v56, s99, v61
	v_add_u32_e32 v57, s99, v62
	ds_read_b64_tr_b4 v[50:51], v160 offset:896
	ds_read_b64_tr_b4 v[52:53], v160 offset:1920
	ds_read_b64_tr_b4 v[130:131], v54
	ds_read_b64_tr_b4 v[132:133], v55
	ds_read_b64_tr_b4 v[134:135], v56
	ds_read_b64_tr_b4 v[136:137], v57
	s_waitcnt lgkmcnt(6)
	v_dot8c_i32_i4_e32 v38, v122, v48
	v_dot8c_i32_i4_e32 v39, v122, v46
	v_dot8c_i32_i4_e32 v40, v124, v48
	v_dot8c_i32_i4_e32 v41, v124, v46
	v_dot8c_i32_i4_e32 v42, v126, v48
	v_dot8c_i32_i4_e32 v43, v126, v46
	v_dot8c_i32_i4_e32 v44, v128, v48
	v_dot8c_i32_i4_e32 v45, v128, v46
	v_dot8c_i32_i4_e32 v38, v123, v49
	v_dot8c_i32_i4_e32 v39, v123, v47
	v_dot8c_i32_i4_e32 v40, v125, v49
	v_dot8c_i32_i4_e32 v41, v125, v47
	v_dot8c_i32_i4_e32 v42, v127, v49
	v_dot8c_i32_i4_e32 v43, v127, v47
	v_dot8c_i32_i4_e32 v44, v129, v49
	v_dot8c_i32_i4_e32 v45, v129, v47
	v_and_b32_e32 v78, 0xffff, v30
	v_lshrrev_b32_e32 v79, 16, v30
	v_lshl_add_u32 v78, v78, 7, v150
	v_lshl_add_u32 v79, v79, 7, v151
	s_mov_b32 m0, s98
	s_add_i32 s43, s98, 0x400
	global_load_lds_dwordx4 v78, s[50:51]
	s_mov_b32 m0, s43
	s_nop 0
	global_load_lds_dwordx4 v79, s[50:51]
	s_waitcnt vmcnt(8)
	v_add_u32_e32 v54, s76, v59
	v_add_u32_e32 v55, s76, v60
	v_add_u32_e32 v56, s76, v61
	v_add_u32_e32 v57, s76, v62
	ds_read_b64_tr_b4 v[46:47], v160
	ds_read_b64_tr_b4 v[48:49], v160 offset:1024
	ds_read_b64_tr_b4 v[122:123], v54
	ds_read_b64_tr_b4 v[124:125], v55
	ds_read_b64_tr_b4 v[126:127], v56
	ds_read_b64_tr_b4 v[128:129], v57
	s_waitcnt lgkmcnt(6)
	v_dot8c_i32_i4_e32 v38, v130, v52
	v_dot8c_i32_i4_e32 v39, v130, v50
	v_dot8c_i32_i4_e32 v40, v132, v52
	v_dot8c_i32_i4_e32 v41, v132, v50
	v_dot8c_i32_i4_e32 v42, v134, v52
	v_dot8c_i32_i4_e32 v43, v134, v50
	v_dot8c_i32_i4_e32 v44, v136, v52
	v_dot8c_i32_i4_e32 v45, v136, v50
	v_dot8c_i32_i4_e32 v38, v131, v53
	v_dot8c_i32_i4_e32 v39, v131, v51
	v_dot8c_i32_i4_e32 v40, v133, v53
	v_dot8c_i32_i4_e32 v41, v133, v51
	v_dot8c_i32_i4_e32 v42, v135, v53
	v_dot8c_i32_i4_e32 v43, v135, v51
	v_dot8c_i32_i4_e32 v44, v137, v53
	v_dot8c_i32_i4_e32 v45, v137, v51
	s_nop 3
	s_waitcnt lgkmcnt(15)
	v_lshlrev_b32_e32 v38, 5, v38
	v_lshlrev_b32_e32 v39, 1, v39
	v_add3_u32 v38, v39, v229, v38
	v_cvt_f32_i32_e32 v38, v38
	v_mul_f32_e32 v38, v228, v38
	v_lshlrev_b32_e32 v40, 5, v40
	v_lshlrev_b32_e32 v41, 1, v41
	v_add3_u32 v40, v41, v229, v40
	v_cvt_f32_i32_e32 v40, v40
	v_mul_f32_e32 v40, v228, v40
	v_lshlrev_b32_e32 v42, 5, v42
	v_lshlrev_b32_e32 v43, 1, v43
	v_add3_u32 v42, v43, v229, v42
	v_cvt_f32_i32_e32 v42, v42
	v_mul_f32_e32 v42, v228, v42
	v_lshlrev_b32_e32 v44, 5, v44
	v_lshlrev_b32_e32 v45, 1, v45
	v_add3_u32 v44, v45, v229, v44
	v_cvt_f32_i32_e32 v44, v44
	v_mul_f32_e32 v44, v228, v44
	v_cvt_pk_bf16_f32 v178, v38, v40
	v_cvt_pk_bf16_f32 v179, v42, v44
	v_add_u32_e32 v147, 8, v140
	v_and_b32_e32 v146, 15, v147
	v_xor_b32_e32 v146, 8, v146
	v_bfe_u32 v148, v147, 4, 4
	v_mul_lo_u32 v146, v146, s92
	v_mul_lo_u32 v148, v148, s92
	v_mov_b32_e32 v147, v146
	v_mov_b32_e32 v149, v148
	ds_write2st64_b64 v77, v[146:147], v[148:149] offset1:2
	v_add_u32_e32 v138, 0x800, v74
	ds_read_u8 v139, v138
	v_add_u32_e32 v141, 0x800, v73
	ds_read_u8 v140, v141
	s_add_i32 s43, s67, 96
	v_mov_b32_e32 v138, s43
	ds_read2st64_b32 v[228:229], v138 offset1:1
	ds_read_b128 v[18:21], v227 offset:4096
	ds_read_b128 v[22:25], v227 offset:4112
	v_add_u32_e32 v152, 0x200000, v63
	v_add_u32_e32 v153, 0x200000, v64
	v_mov_b32_e32 v38, 0
	v_mov_b32_e32 v39, 0
	v_mov_b32_e32 v40, 0
	v_mov_b32_e32 v41, 0
	v_mov_b32_e32 v42, 0
	v_mov_b32_e32 v43, 0
	v_mov_b32_e32 v44, 0
	v_mov_b32_e32 v45, 0
	v_and_b32_e32 v78, 0xffff, v31
	v_lshrrev_b32_e32 v79, 16, v31
	v_lshl_add_u32 v78, v78, 7, v150
	v_lshl_add_u32 v79, v79, 7, v151
	s_mov_b32 m0, s99
	s_add_i32 s43, s99, 0x400
	global_load_lds_dwordx4 v78, s[50:51]
	s_mov_b32 m0, s43
	s_nop 0
	global_load_lds_dwordx4 v79, s[50:51]
	s_waitcnt vmcnt(8)
; #define LAS __attribute__((address_space(3)))
; #define TR4(p_) __builtin_amdgcn_ds_read_tr4_b64_v2i32((LAS v2i*)(p_))
; __device__ __forceinline__ void peer_v_tokens(int j, const LAS unsigned short* EL, const LAS unsigned char* AL  , const LAS float* ASC  , const LAS int* SAL  , ...
;     ...
; #pragma unroll
;         for (int st = 0; st < 16; ++st) {
;             const int p = st >> 2, q = st & 3;
;             if (st < 14) VDMA(st + 2, (st + 2) % 3);
;             if (st < 14) asm volatile("s_waitcnt vmcnt(8)" ::: "memory");
;             else if (st == 14) asm volatile("s_waitcnt vmcnt(4)" ::: "memory");
;             else asm volatile("s_waitcnt vmcnt(0)" ::: "memory");
;             if (q == 0) {
; #pragma unroll
;                 for (int r = 0; r < 4; ++r) { accH[r] = 0; accL[r] = 0; } }
; #pragma unroll
;             for (int tp = 0; tp < 2; ++tp) {
;                 const v2i ao = TR4(ATL + (2 * q + tp) * 128 + 8 * s16), ah = TR4(ATL + 1024 + (2 * q + tp) * 128 + 8 * s16);
; #pragma unroll
;                 for (int r = 0; r < 4; ++r) {
;                     const v2i d = TR4(ldsb + BUF[st % 3] + 2048 * tp + roff[r]);
;                     accH[r] = __builtin_amdgcn_sdot8(d.x, ah.x, accH[r], false); accH[r] = __builtin_amdgcn_sdot8(d.y, ah.y, accH[r], false);
;                     accL[r] = __builtin_amdgcn_sdot8(d.x, ao.x, accL[r], false); accL[r] = __builtin_amdgcn_sdot8(d.y, ao.y, accL[r], false);
;                 }
;     ...
;         {
;             float4 v[4]; float ss = 0.f;
; #pragma unroll
;             for (int jq = 0; jq < 4; ++jq) { typedef unsigned u2v __attribute__((ext_vector_type(2))); const u2v pw = *(const LAS u2v*)(STASH + 4 * lane + 256 * jq); const uint2 hw = hv[jq];
;                 v[jq] = make_float4(__uint_as_float(hw.x << 16) + __uint_as_float(pw.x << 16), __uint_as_float(hw.x & 0xffff0000u) + __uint_as_float(pw.x & 0xffff0000u),
;                                     __uint_as_float(hw.y << 16) + __uint_as_float(pw.y << 16), __uint_as_float(hw.y & 0xffff0000u) + __uint_as_float(pw.y & 0xffff0000u));
;                 ss += v[jq].x * v[jq].x + v[jq].y * v[jq].y + v[jq].z * v[jq].z + v[jq].w * v[jq].w; }
;             ss = wave_sum(ss);
;             const float r3 = rsqrtf(ss * (1.f / D) + EPS);
	v_add_u32_e32 v54, s77, v59
	v_add_u32_e32 v55, s77, v60
	v_add_u32_e32 v56, s77, v61
	v_add_u32_e32 v57, s77, v62
	ds_read_b64_tr_b4 v[50:51], v160 offset:128
	ds_read_b64_tr_b4 v[52:53], v160 offset:1152
	ds_read_b64_tr_b4 v[130:131], v54
	ds_read_b64_tr_b4 v[132:133], v55
	ds_read_b64_tr_b4 v[134:135], v56
	ds_read_b64_tr_b4 v[136:137], v57
	s_waitcnt lgkmcnt(12)
	s_waitcnt vmcnt(34) lgkmcnt(15)
	v_lshlrev_b32_e32 v210, 16, v194
	v_and_b32_e32 v211, 0xffff0000, v194
	v_lshlrev_b32_e32 v142, 16, v202
	v_and_b32_e32 v143, 0xffff0000, v202
	v_add_f32_e32 v210, v210, v142
	v_add_f32_e32 v211, v211, v143
	v_lshlrev_b32_e32 v212, 16, v195
	v_and_b32_e32 v213, 0xffff0000, v195
	v_lshlrev_b32_e32 v142, 16, v203
	v_and_b32_e32 v143, 0xffff0000, v203
	v_add_f32_e32 v212, v212, v142
	v_add_f32_e32 v213, v213, v143
	v_lshlrev_b32_e32 v214, 16, v196
	v_and_b32_e32 v215, 0xffff0000, v196
	v_lshlrev_b32_e32 v142, 16, v204
	v_and_b32_e32 v143, 0xffff0000, v204
	v_add_f32_e32 v214, v214, v142
	v_add_f32_e32 v215, v215, v143
	v_lshlrev_b32_e32 v216, 16, v197
	v_and_b32_e32 v217, 0xffff0000, v197
	v_lshlrev_b32_e32 v142, 16, v205
	v_and_b32_e32 v143, 0xffff0000, v205
	v_add_f32_e32 v216, v216, v142
	v_add_f32_e32 v217, v217, v143
	v_lshlrev_b32_e32 v218, 16, v198
	v_and_b32_e32 v219, 0xffff0000, v198
	v_lshlrev_b32_e32 v142, 16, v206
	v_and_b32_e32 v143, 0xffff0000, v206
	v_add_f32_e32 v218, v218, v142
	v_add_f32_e32 v219, v219, v143
	v_lshlrev_b32_e32 v220, 16, v199
	v_and_b32_e32 v221, 0xffff0000, v199
	v_lshlrev_b32_e32 v142, 16, v207
	v_and_b32_e32 v143, 0xffff0000, v207
	v_add_f32_e32 v220, v220, v142
	v_add_f32_e32 v221, v221, v143
	v_lshlrev_b32_e32 v222, 16, v200
	v_and_b32_e32 v223, 0xffff0000, v200
	v_lshlrev_b32_e32 v142, 16, v208
	v_and_b32_e32 v143, 0xffff0000, v208
	v_add_f32_e32 v222, v222, v142
	v_add_f32_e32 v223, v223, v143
	v_lshlrev_b32_e32 v224, 16, v201
	v_and_b32_e32 v225, 0xffff0000, v201
	v_lshlrev_b32_e32 v142, 16, v209
	v_and_b32_e32 v143, 0xffff0000, v209
	v_add_f32_e32 v224, v224, v142
	v_add_f32_e32 v225, v225, v143
	v_mov_b32_e32 v144, 0
	v_mul_f32_e32 v145, v210, v210
	v_fmac_f32_e32 v145, v211, v211
	v_fmac_f32_e32 v145, v212, v212
	v_fmac_f32_e32 v145, v213, v213
	v_add_f32_e32 v144, v144, v145
	v_mul_f32_e32 v145, v214, v214
	v_fmac_f32_e32 v145, v215, v215
	v_fmac_f32_e32 v145, v216, v216
	v_fmac_f32_e32 v145, v217, v217
	v_add_f32_e32 v144, v144, v145
	v_mul_f32_e32 v145, v218, v218
	v_fmac_f32_e32 v145, v219, v219
	v_fmac_f32_e32 v145, v220, v220
	v_fmac_f32_e32 v145, v221, v221
	v_add_f32_e32 v144, v144, v145
	v_mul_f32_e32 v145, v222, v222
	v_fmac_f32_e32 v145, v223, v223
	v_fmac_f32_e32 v145, v224, v224
	v_fmac_f32_e32 v145, v225, v225
	v_add_f32_e32 v144, v144, v145
	s_nop 1
	v_add_f32_dpp v144, v144, v144 quad_perm:[1,0,3,2] row_mask:0xf bank_mask:0xf bound_ctrl:1
	s_nop 1
	v_add_f32_dpp v144, v144, v144 quad_perm:[2,3,0,1] row_mask:0xf bank_mask:0xf bound_ctrl:1
	s_nop 1
	v_add_f32_dpp v144, v144, v144 row_half_mirror row_mask:0xf bank_mask:0xf bound_ctrl:1
	s_nop 1
	v_add_f32_dpp v144, v144, v144 row_mirror row_mask:0xf bank_mask:0xf bound_ctrl:1
	s_nop 1
	v_readlane_b32 s10, v144, 0
	v_readlane_b32 s11, v144, 16
	v_readlane_b32 s14, v144, 32
	v_readlane_b32 s15, v144, 48
	s_nop 3
	v_mov_b32_e32 v144, s11
	v_mov_b32_e32 v145, s15
	v_add_f32_e32 v144, s10, v144
	v_add_f32_e32 v145, s14, v145
	v_add_f32_e32 v144, v144, v145
	v_fmamk_f32 v144, v144, 0x3a800000, v111
	v_rsq_f32_e32 v144, v144
	s_nop 0
	v_mul_f32_e32 v210, v210, v144
	v_mul_f32_e32 v211, v211, v144
	v_mul_f32_e32 v212, v212, v144
	v_mul_f32_e32 v213, v213, v144
	v_mul_f32_e32 v214, v214, v144
	v_mul_f32_e32 v215, v215, v144
	v_mul_f32_e32 v216, v216, v144
	v_mul_f32_e32 v217, v217, v144
	v_mul_f32_e32 v218, v218, v144
	v_mul_f32_e32 v219, v219, v144
	v_mul_f32_e32 v220, v220, v144
	v_mul_f32_e32 v221, v221, v144
	v_mul_f32_e32 v222, v222, v144
	v_mul_f32_e32 v223, v223, v144
	v_mul_f32_e32 v224, v224, v144
	v_mul_f32_e32 v225, v225, v144
	v_dot8c_i32_i4_e32 v38, v122, v48
	v_dot8c_i32_i4_e32 v39, v122, v46
	v_dot8c_i32_i4_e32 v40, v124, v48
	v_dot8c_i32_i4_e32 v41, v124, v46
	v_dot8c_i32_i4_e32 v42, v126, v48
	v_dot8c_i32_i4_e32 v43, v126, v46
	v_dot8c_i32_i4_e32 v44, v128, v48
	v_dot8c_i32_i4_e32 v45, v128, v46
	v_dot8c_i32_i4_e32 v38, v123, v49
	v_dot8c_i32_i4_e32 v39, v123, v47
	v_dot8c_i32_i4_e32 v40, v125, v49
	v_dot8c_i32_i4_e32 v41, v125, v47
	v_dot8c_i32_i4_e32 v42, v127, v49
	v_dot8c_i32_i4_e32 v43, v127, v47
	v_dot8c_i32_i4_e32 v44, v129, v49
	v_dot8c_i32_i4_e32 v45, v129, v47
	v_and_b32_e32 v78, 0xffff, v32
	v_lshrrev_b32_e32 v79, 16, v32
	v_lshl_add_u32 v78, v78, 7, v150
	v_lshl_add_u32 v79, v79, 7, v151
	s_mov_b32 m0, s76
	s_add_i32 s43, s76, 0x400
	global_load_lds_dwordx4 v78, s[50:51]
	s_mov_b32 m0, s43
	s_nop 0
	global_load_lds_dwordx4 v79, s[50:51]
	s_waitcnt vmcnt(8)
	v_add_u32_e32 v54, s78, v59
	v_add_u32_e32 v55, s78, v60
	v_add_u32_e32 v56, s78, v61
	v_add_u32_e32 v57, s78, v62
	ds_read_b64_tr_b4 v[46:47], v160 offset:256
	ds_read_b64_tr_b4 v[48:49], v160 offset:1280
	ds_read_b64_tr_b4 v[122:123], v54
	ds_read_b64_tr_b4 v[124:125], v55
	ds_read_b64_tr_b4 v[126:127], v56
	ds_read_b64_tr_b4 v[128:129], v57
	s_waitcnt lgkmcnt(6)
; #define TR4(p_) __builtin_amdgcn_ds_read_tr4_b64_v2i32((LAS v2i*)(p_))
; #define VDMA(st_, k_) do { _Pragma("unroll") for (int i_ = 0; i_ < 4; ++i_) { \
;         const unsigned off_ = (unsigned)((st_) >> 2) * (16384u * 128u) + (PE_ID(E, 4 * ((st_) & 3) + i_) << 7) + ((i_ & 1) ? cx1 : cx0); \
;         __builtin_amdgcn_global_load_lds((const unsigned*)(V4 + off_), (LAS unsigned*)(ldsb + BUF[k_] + 1024 * i_), 16, 0, 0); } } while (0)
; __device__ __forceinline__ void peer_v_tokens(int j, const LAS unsigned short* EL, const LAS unsigned char* AL  , const LAS float* ASC  , const LAS int* SAL  , ...
;     ...
; #pragma unroll
;         for (int st = 0; st < 16; ++st) {
;             const int p = st >> 2, q = st & 3;
;             if (st < 14) VDMA(st + 2, (st + 2) % 3);
;             if (st < 14) asm volatile("s_waitcnt vmcnt(8)" ::: "memory");
;             else if (st == 14) asm volatile("s_waitcnt vmcnt(4)" ::: "memory");
;             else asm volatile("s_waitcnt vmcnt(0)" ::: "memory");
;             if (q == 0) {
; #pragma unroll
;                 for (int r = 0; r < 4; ++r) { accH[r] = 0; accL[r] = 0; } }
; #pragma unroll
;             for (int tp = 0; tp < 2; ++tp) {
;                 const v2i ao = TR4(ATL + (2 * q + tp) * 128 + 8 * s16), ah = TR4(ATL + 1024 + (2 * q + tp) * 128 + 8 * s16);
; #pragma unroll
;                 for (int r = 0; r < 4; ++r) {
;                     const v2i d = TR4(ldsb + BUF[st % 3] + 2048 * tp + roff[r]);
;                     accH[r] = __builtin_amdgcn_sdot8(d.x, ah.x, accH[r], false); accH[r] = __builtin_amdgcn_sdot8(d.y, ah.y, accH[r], false);
;                     accL[r] = __builtin_amdgcn_sdot8(d.x, ao.x, accL[r], false); accL[r] = __builtin_amdgcn_sdot8(d.y, ao.y, accL[r], false);
;                 }
	v_dot8c_i32_i4_e32 v38, v130, v52
	v_dot8c_i32_i4_e32 v39, v130, v50
	v_dot8c_i32_i4_e32 v40, v132, v52
	v_dot8c_i32_i4_e32 v41, v132, v50
	v_dot8c_i32_i4_e32 v42, v134, v52
	v_dot8c_i32_i4_e32 v43, v134, v50
	v_dot8c_i32_i4_e32 v44, v136, v52
	v_dot8c_i32_i4_e32 v45, v136, v50
	v_dot8c_i32_i4_e32 v38, v131, v53
	v_dot8c_i32_i4_e32 v39, v131, v51
	v_dot8c_i32_i4_e32 v40, v133, v53
	v_dot8c_i32_i4_e32 v41, v133, v51
	v_dot8c_i32_i4_e32 v42, v135, v53
	v_dot8c_i32_i4_e32 v43, v135, v51
	v_dot8c_i32_i4_e32 v44, v137, v53
	v_dot8c_i32_i4_e32 v45, v137, v51
	v_and_b32_e32 v78, 0xffff, v33
	v_lshrrev_b32_e32 v79, 16, v33
	v_lshl_add_u32 v78, v78, 7, v150
	v_lshl_add_u32 v79, v79, 7, v151
	s_mov_b32 m0, s77
	s_add_i32 s43, s77, 0x400
	global_load_lds_dwordx4 v78, s[50:51]
	s_mov_b32 m0, s43
	s_nop 0
	global_load_lds_dwordx4 v79, s[50:51]
	s_waitcnt vmcnt(8)
	v_add_u32_e32 v54, s79, v59
	v_add_u32_e32 v55, s79, v60
	v_add_u32_e32 v56, s79, v61
	v_add_u32_e32 v57, s79, v62
	ds_read_b64_tr_b4 v[50:51], v160 offset:384
	ds_read_b64_tr_b4 v[52:53], v160 offset:1408
	ds_read_b64_tr_b4 v[130:131], v54
	ds_read_b64_tr_b4 v[132:133], v55
	ds_read_b64_tr_b4 v[134:135], v56
	ds_read_b64_tr_b4 v[136:137], v57
	s_waitcnt lgkmcnt(6)
	v_dot8c_i32_i4_e32 v38, v122, v48
	v_dot8c_i32_i4_e32 v39, v122, v46
	v_dot8c_i32_i4_e32 v40, v124, v48
	v_dot8c_i32_i4_e32 v41, v124, v46
	v_dot8c_i32_i4_e32 v42, v126, v48
	v_dot8c_i32_i4_e32 v43, v126, v46
	v_dot8c_i32_i4_e32 v44, v128, v48
	v_dot8c_i32_i4_e32 v45, v128, v46
	v_dot8c_i32_i4_e32 v38, v123, v49
	v_dot8c_i32_i4_e32 v39, v123, v47
	v_dot8c_i32_i4_e32 v40, v125, v49
	v_dot8c_i32_i4_e32 v41, v125, v47
	v_dot8c_i32_i4_e32 v42, v127, v49
	v_dot8c_i32_i4_e32 v43, v127, v47
	v_dot8c_i32_i4_e32 v44, v129, v49
	v_dot8c_i32_i4_e32 v45, v129, v47
	s_waitcnt lgkmcnt(15)
	v_and_b32_e32 v78, 0xffff, v18
	v_lshrrev_b32_e32 v79, 16, v18
	v_lshl_add_u32 v78, v78, 7, v152
	v_lshl_add_u32 v79, v79, 7, v153
	s_mov_b32 m0, s78
	s_add_i32 s43, s78, 0x400
	global_load_lds_dwordx4 v78, s[50:51]
	s_mov_b32 m0, s43
	s_nop 0
	global_load_lds_dwordx4 v79, s[50:51]
	s_waitcnt vmcnt(8)
	v_add_u32_e32 v54, s98, v59
	v_add_u32_e32 v55, s98, v60
	v_add_u32_e32 v56, s98, v61
	v_add_u32_e32 v57, s98, v62
	ds_read_b64_tr_b4 v[46:47], v160 offset:512
	ds_read_b64_tr_b4 v[48:49], v160 offset:1536
	ds_read_b64_tr_b4 v[122:123], v54
	ds_read_b64_tr_b4 v[124:125], v55
	ds_read_b64_tr_b4 v[126:127], v56
	ds_read_b64_tr_b4 v[128:129], v57
	s_waitcnt lgkmcnt(6)
	v_dot8c_i32_i4_e32 v38, v130, v52
	v_dot8c_i32_i4_e32 v39, v130, v50
	v_dot8c_i32_i4_e32 v40, v132, v52
	v_dot8c_i32_i4_e32 v41, v132, v50
	v_dot8c_i32_i4_e32 v42, v134, v52
	v_dot8c_i32_i4_e32 v43, v134, v50
	v_dot8c_i32_i4_e32 v44, v136, v52
	v_dot8c_i32_i4_e32 v45, v136, v50
	v_dot8c_i32_i4_e32 v38, v131, v53
	v_dot8c_i32_i4_e32 v39, v131, v51
	v_dot8c_i32_i4_e32 v40, v133, v53
	v_dot8c_i32_i4_e32 v41, v133, v51
	v_dot8c_i32_i4_e32 v42, v135, v53
	v_dot8c_i32_i4_e32 v43, v135, v51
	v_dot8c_i32_i4_e32 v44, v137, v53
	v_dot8c_i32_i4_e32 v45, v137, v51
	v_and_b32_e32 v78, 0xffff, v19
	v_lshrrev_b32_e32 v79, 16, v19
	v_lshl_add_u32 v78, v78, 7, v152
	v_lshl_add_u32 v79, v79, 7, v153
	s_mov_b32 m0, s79
	s_add_i32 s43, s79, 0x400
	global_load_lds_dwordx4 v78, s[50:51]
	s_mov_b32 m0, s43
	s_nop 0
	global_load_lds_dwordx4 v79, s[50:51]
	s_waitcnt vmcnt(8)
	v_add_u32_e32 v54, s99, v59
	v_add_u32_e32 v55, s99, v60
	v_add_u32_e32 v56, s99, v61
	v_add_u32_e32 v57, s99, v62
	ds_read_b64_tr_b4 v[50:51], v160 offset:640
	ds_read_b64_tr_b4 v[52:53], v160 offset:1664
	ds_read_b64_tr_b4 v[130:131], v54
	ds_read_b64_tr_b4 v[132:133], v55
	ds_read_b64_tr_b4 v[134:135], v56
	ds_read_b64_tr_b4 v[136:137], v57
	s_waitcnt lgkmcnt(6)
	v_dot8c_i32_i4_e32 v38, v122, v48
	v_dot8c_i32_i4_e32 v39, v122, v46
	v_dot8c_i32_i4_e32 v40, v124, v48
	v_dot8c_i32_i4_e32 v41, v124, v46
	v_dot8c_i32_i4_e32 v42, v126, v48
	v_dot8c_i32_i4_e32 v43, v126, v46
	v_dot8c_i32_i4_e32 v44, v128, v48
	v_dot8c_i32_i4_e32 v45, v128, v46
	v_dot8c_i32_i4_e32 v38, v123, v49
	v_dot8c_i32_i4_e32 v39, v123, v47
	v_dot8c_i32_i4_e32 v40, v125, v49
	v_dot8c_i32_i4_e32 v41, v125, v47
	v_dot8c_i32_i4_e32 v42, v127, v49
	v_dot8c_i32_i4_e32 v43, v127, v47
	v_dot8c_i32_i4_e32 v44, v129, v49
	v_dot8c_i32_i4_e32 v45, v129, v47
	s_waitcnt lgkmcnt(15)
	v_add_u32_e32 v143, 8, v139
	v_and_b32_e32 v142, 15, v143
	v_xor_b32_e32 v142, 8, v142
	v_bfe_u32 v144, v143, 4, 4
	v_mul_lo_u32 v142, v142, s92
	v_mul_lo_u32 v144, v144, s92
	v_mov_b32_e32 v143, v142
	v_mov_b32_e32 v145, v144
	ds_write2st64_b64 v159, v[142:143], v[144:145] offset1:2
	v_and_b32_e32 v78, 0xffff, v20
	v_lshrrev_b32_e32 v79, 16, v20
	v_lshl_add_u32 v78, v78, 7, v152
	v_lshl_add_u32 v79, v79, 7, v153
	s_mov_b32 m0, s98
	s_add_i32 s43, s98, 0x400
	global_load_lds_dwordx4 v78, s[50:51]
	s_mov_b32 m0, s43
	s_nop 0
	global_load_lds_dwordx4 v79, s[50:51]
	s_waitcnt vmcnt(8)
	v_add_u32_e32 v54, s76, v59
	v_add_u32_e32 v55, s76, v60
	v_add_u32_e32 v56, s76, v61
	v_add_u32_e32 v57, s76, v62
	ds_read_b64_tr_b4 v[46:47], v160 offset:768
	ds_read_b64_tr_b4 v[48:49], v160 offset:1792
	ds_read_b64_tr_b4 v[122:123], v54
	ds_read_b64_tr_b4 v[124:125], v55
	ds_read_b64_tr_b4 v[126:127], v56
	ds_read_b64_tr_b4 v[128:129], v57
	s_waitcnt lgkmcnt(7)
; __device__ __forceinline__ void peer_v_tokens(int j, const LAS unsigned short* EL, const LAS unsigned char* AL  , const LAS float* ASC  , const LAS int* SAL  , ...
;     ...
;         { unsigned ho = (unsigned)t * (D / 4) + (unsigned)lane; asm volatile("" : "+v"(ho)); const uint2* hp = (const uint2*)HB + ho; const float4* gp = (const float4*)fng + lane;
; #pragma unroll
;           for (int jq = 0; jq < 4; ++jq) { hv[jq] = hp[64 * jq]; gv[jq] = gp[64 * jq]; } }
;         VDMA(0, 0); VDMA(1, 1);
; #pragma unroll
;         for (int m = 0; m < 2; ++m) {
;             const int idx = lane + 64 * m, tau = idx >> 4, sr = idx & 15, k = 16 * (sr & 7) + 2 * tau + (sr >> 3);
;             const int aq = (int)*(const LAS signed char*)(AL + tl * 128 + k); const int tq = aq + 8;
;             const unsigned lo = (((unsigned)tq & 15u) ^ 8u) * 0x11111111u, hi = ((unsigned)(tq >> 4) & 15u) * 0x11111111u;
;             typedef unsigned u2v __attribute__((ext_vector_type(2)));
;             u2v l2; l2.x = lo; l2.y = lo; u2v h2; h2.x = hi; h2.y = hi;
;             *(LAS u2v*)(ATL + 8 * idx) = l2; *(LAS u2v*)(ATL + 1024 + 8 * idx) = h2;
;         }
;         const float asc = ASC[tl]; const int sa = SAL[tl];
;         CFENCE();
;         int accH[4], accL[4];
; #pragma unroll
;         for (int st = 0; st < 16; ++st) {
;             const int p = st >> 2, q = st & 3;
;             if (st < 14) VDMA(st + 2, (st + 2) % 3);
;             if (st < 14) asm volatile("s_waitcnt vmcnt(8)" ::: "memory");
;             else if (st == 14) asm volatile("s_waitcnt vmcnt(4)" ::: "memory");
;             else asm volatile("s_waitcnt vmcnt(0)" ::: "memory");
;             if (q == 0) {
; #pragma unroll
;                 for (int r = 0; r < 4; ++r) { accH[r] = 0; accL[r] = 0; } }
; #pragma unroll
;             for (int tp = 0; tp < 2; ++tp) {
;                 const v2i ao = TR4(ATL + (2 * q + tp) * 128 + 8 * s16), ah = TR4(ATL + 1024 + (2 * q + tp) * 128 + 8 * s16);
; #pragma unroll
;                 for (int r = 0; r < 4; ++r) {
;                     const v2i d = TR4(ldsb + BUF[st % 3] + 2048 * tp + roff[r]);
;                     accH[r] = __builtin_amdgcn_sdot8(d.x, ah.x, accH[r], false); accH[r] = __builtin_amdgcn_sdot8(d.y, ah.y, accH[r], false);
;                     accL[r] = __builtin_amdgcn_sdot8(d.x, ao.x, accL[r], false); accL[r] = __builtin_amdgcn_sdot8(d.y, ao.y, accL[r], false);
	v_dot8c_i32_i4_e32 v38, v130, v52
	v_dot8c_i32_i4_e32 v39, v130, v50
	v_dot8c_i32_i4_e32 v40, v132, v52
	v_dot8c_i32_i4_e32 v41, v132, v50
	v_dot8c_i32_i4_e32 v42, v134, v52
	v_dot8c_i32_i4_e32 v43, v134, v50
	v_dot8c_i32_i4_e32 v44, v136, v52
	v_dot8c_i32_i4_e32 v45, v136, v50
	v_dot8c_i32_i4_e32 v38, v131, v53
	v_dot8c_i32_i4_e32 v39, v131, v51
	v_dot8c_i32_i4_e32 v40, v133, v53
	v_dot8c_i32_i4_e32 v41, v133, v51
	v_dot8c_i32_i4_e32 v42, v135, v53
	v_dot8c_i32_i4_e32 v43, v135, v51
	v_dot8c_i32_i4_e32 v44, v137, v53
	v_dot8c_i32_i4_e32 v45, v137, v51
	v_and_b32_e32 v78, 0xffff, v21
	v_lshrrev_b32_e32 v79, 16, v21
	v_lshl_add_u32 v78, v78, 7, v152
	v_lshl_add_u32 v79, v79, 7, v153
	s_mov_b32 m0, s99
	s_add_i32 s43, s99, 0x400
	global_load_lds_dwordx4 v78, s[50:51]
	s_mov_b32 m0, s43
	s_nop 0
	global_load_lds_dwordx4 v79, s[50:51]
	s_waitcnt vmcnt(8)
	v_add_u32_e32 v54, s77, v59
	v_add_u32_e32 v55, s77, v60
	v_add_u32_e32 v56, s77, v61
	v_add_u32_e32 v57, s77, v62
	ds_read_b64_tr_b4 v[50:51], v160 offset:896
	ds_read_b64_tr_b4 v[52:53], v160 offset:1920
	ds_read_b64_tr_b4 v[130:131], v54
	ds_read_b64_tr_b4 v[132:133], v55
	ds_read_b64_tr_b4 v[134:135], v56
	ds_read_b64_tr_b4 v[136:137], v57
	s_waitcnt lgkmcnt(6)
	v_dot8c_i32_i4_e32 v38, v122, v48
	v_dot8c_i32_i4_e32 v39, v122, v46
	v_dot8c_i32_i4_e32 v40, v124, v48
	v_dot8c_i32_i4_e32 v41, v124, v46
	v_dot8c_i32_i4_e32 v42, v126, v48
	v_dot8c_i32_i4_e32 v43, v126, v46
	v_dot8c_i32_i4_e32 v44, v128, v48
	v_dot8c_i32_i4_e32 v45, v128, v46
	v_dot8c_i32_i4_e32 v38, v123, v49
	v_dot8c_i32_i4_e32 v39, v123, v47
	v_dot8c_i32_i4_e32 v40, v125, v49
	v_dot8c_i32_i4_e32 v41, v125, v47
	v_dot8c_i32_i4_e32 v42, v127, v49
	v_dot8c_i32_i4_e32 v43, v127, v47
	v_dot8c_i32_i4_e32 v44, v129, v49
	v_dot8c_i32_i4_e32 v45, v129, v47
	v_and_b32_e32 v78, 0xffff, v22
	v_lshrrev_b32_e32 v79, 16, v22
	v_lshl_add_u32 v78, v78, 7, v152
	v_lshl_add_u32 v79, v79, 7, v153
	s_mov_b32 m0, s76
	s_add_i32 s43, s76, 0x400
	global_load_lds_dwordx4 v78, s[50:51]
	s_mov_b32 m0, s43
	s_nop 0
	global_load_lds_dwordx4 v79, s[50:51]
	s_waitcnt vmcnt(8)
	v_add_u32_e32 v54, s78, v59
	v_add_u32_e32 v55, s78, v60
	v_add_u32_e32 v56, s78, v61
	v_add_u32_e32 v57, s78, v62
	ds_read_b64_tr_b4 v[46:47], v160
	ds_read_b64_tr_b4 v[48:49], v160 offset:1024
	ds_read_b64_tr_b4 v[122:123], v54
	ds_read_b64_tr_b4 v[124:125], v55
	ds_read_b64_tr_b4 v[126:127], v56
	ds_read_b64_tr_b4 v[128:129], v57
	s_waitcnt lgkmcnt(6)
	v_dot8c_i32_i4_e32 v38, v130, v52
	v_dot8c_i32_i4_e32 v39, v130, v50
	v_dot8c_i32_i4_e32 v40, v132, v52
	v_dot8c_i32_i4_e32 v41, v132, v50
	v_dot8c_i32_i4_e32 v42, v134, v52
	v_dot8c_i32_i4_e32 v43, v134, v50
	v_dot8c_i32_i4_e32 v44, v136, v52
	v_dot8c_i32_i4_e32 v45, v136, v50
	v_dot8c_i32_i4_e32 v38, v131, v53
	v_dot8c_i32_i4_e32 v39, v131, v51
	v_dot8c_i32_i4_e32 v40, v133, v53
	v_dot8c_i32_i4_e32 v41, v133, v51
	v_dot8c_i32_i4_e32 v42, v135, v53
	v_dot8c_i32_i4_e32 v43, v135, v51
	v_dot8c_i32_i4_e32 v44, v137, v53
	v_dot8c_i32_i4_e32 v45, v137, v51
	s_nop 3
	s_waitcnt lgkmcnt(15)
	v_lshlrev_b32_e32 v38, 5, v38
	v_lshlrev_b32_e32 v39, 1, v39
	v_add3_u32 v38, v39, v229, v38
	v_cvt_f32_i32_e32 v38, v38
	v_mul_f32_e32 v38, v228, v38
	v_lshlrev_b32_e32 v40, 5, v40
	v_lshlrev_b32_e32 v41, 1, v41
	v_add3_u32 v40, v41, v229, v40
	v_cvt_f32_i32_e32 v40, v40
	v_mul_f32_e32 v40, v228, v40
	v_lshlrev_b32_e32 v42, 5, v42
	v_lshlrev_b32_e32 v43, 1, v43
	v_add3_u32 v42, v43, v229, v42
	v_cvt_f32_i32_e32 v42, v42
	v_mul_f32_e32 v42, v228, v42
	v_lshlrev_b32_e32 v44, 5, v44
	v_lshlrev_b32_e32 v45, 1, v45
	v_add3_u32 v44, v45, v229, v44
	v_cvt_f32_i32_e32 v44, v44
	v_mul_f32_e32 v44, v228, v44
	v_cvt_pk_bf16_f32 v186, v38, v40
	v_cvt_pk_bf16_f32 v187, v42, v44
	ds_read_b128 v[252:255], v155
	s_add_i32 s44, s40, 0
	s_ashr_i32 s45, s44, 31
	s_lshl_b64 s[44:45], s[44:45], 12
	v_lshl_add_u64 v[80:81], v[36:37], 0, s[44:45]
	s_waitcnt lgkmcnt(0)
	v_mul_f32_e32 v210, v210, v252
	v_mul_f32_e32 v211, v211, v253
	v_mul_f32_e32 v212, v212, v254
	v_mul_f32_e32 v213, v213, v255
	global_store_dwordx4 v[80:81], v[210:213], off nt
	s_add_i32 s43, s40, 8
	s_lshl_b32 s43, s43, 11
	v_add_u32_e32 v138, s43, v66
	global_load_dwordx2 v[194:195], v138, s[70:71]
	global_load_dwordx2 v[196:197], v138, s[70:71] offset:512
	global_load_dwordx2 v[198:199], v138, s[70:71] offset:1024
	global_load_dwordx2 v[200:201], v138, s[70:71] offset:1536
	v_add_u32_e32 v147, 8, v140
	v_and_b32_e32 v146, 15, v147
	v_xor_b32_e32 v146, 8, v146
	v_bfe_u32 v148, v147, 4, 4
	v_mul_lo_u32 v146, v146, s92
	v_mul_lo_u32 v148, v148, s92
	v_mov_b32_e32 v147, v146
	v_mov_b32_e32 v149, v148
	ds_write2st64_b64 v77, v[146:147], v[148:149] offset1:2
	v_add_u32_e32 v138, 0xc00, v74
	ds_read_u8 v139, v138
	v_add_u32_e32 v141, 0xc00, v73
	ds_read_u8 v140, v141
	s_add_i32 s43, s67, 64
	v_mov_b32_e32 v138, s43
	ds_read2st64_b32 v[228:229], v138 offset1:1
	ds_read_b128 v[26:29], v227 offset:6144
	ds_read_b128 v[30:33], v227 offset:6160
	v_mov_b32_e32 v38, 0
	v_mov_b32_e32 v39, 0
	v_mov_b32_e32 v40, 0
	v_mov_b32_e32 v41, 0
	v_mov_b32_e32 v42, 0
	v_mov_b32_e32 v43, 0
	v_mov_b32_e32 v44, 0
	v_mov_b32_e32 v45, 0
	v_and_b32_e32 v78, 0xffff, v23
	v_lshrrev_b32_e32 v79, 16, v23
	v_lshl_add_u32 v78, v78, 7, v152
	v_lshl_add_u32 v79, v79, 7, v153
	s_mov_b32 m0, s77
	s_add_i32 s43, s77, 0x400
	global_load_lds_dwordx4 v78, s[50:51]
	s_mov_b32 m0, s43
	s_nop 0
	global_load_lds_dwordx4 v79, s[50:51]
	s_waitcnt vmcnt(13)
	v_add_u32_e32 v54, s79, v59
	v_add_u32_e32 v55, s79, v60
	v_add_u32_e32 v56, s79, v61
	v_add_u32_e32 v57, s79, v62
	ds_read_b64_tr_b4 v[50:51], v160 offset:128
	ds_read_b64_tr_b4 v[52:53], v160 offset:1152
	ds_read_b64_tr_b4 v[130:131], v54
	ds_read_b64_tr_b4 v[132:133], v55
	ds_read_b64_tr_b4 v[134:135], v56
	ds_read_b64_tr_b4 v[136:137], v57
	s_waitcnt lgkmcnt(13)
; #define TR4(p_) __builtin_amdgcn_ds_read_tr4_b64_v2i32((LAS v2i*)(p_))
; #define VDMA(st_, k_) do { _Pragma("unroll") for (int i_ = 0; i_ < 4; ++i_) { \
;         const unsigned off_ = (unsigned)((st_) >> 2) * (16384u * 128u) + (PE_ID(E, 4 * ((st_) & 3) + i_) << 7) + ((i_ & 1) ? cx1 : cx0); \
;         __builtin_amdgcn_global_load_lds((const unsigned*)(V4 + off_), (LAS unsigned*)(ldsb + BUF[k_] + 1024 * i_), 16, 0, 0); } } while (0)
; __device__ __forceinline__ void peer_v_tokens(int j, const LAS unsigned short* EL, const LAS unsigned char* AL  , const LAS float* ASC  , const LAS int* SAL  , ...
;     ...
; #pragma unroll
;         for (int st = 0; st < 16; ++st) {
;             const int p = st >> 2, q = st & 3;
;             if (st < 14) VDMA(st + 2, (st + 2) % 3);
;             if (st < 14) asm volatile("s_waitcnt vmcnt(8)" ::: "memory");
;             else if (st == 14) asm volatile("s_waitcnt vmcnt(4)" ::: "memory");
;             else asm volatile("s_waitcnt vmcnt(0)" ::: "memory");
;             if (q == 0) {
; #pragma unroll
;                 for (int r = 0; r < 4; ++r) { accH[r] = 0; accL[r] = 0; } }
; #pragma unroll
;             for (int tp = 0; tp < 2; ++tp) {
;                 const v2i ao = TR4(ATL + (2 * q + tp) * 128 + 8 * s16), ah = TR4(ATL + 1024 + (2 * q + tp) * 128 + 8 * s16);
; #pragma unroll
;                 for (int r = 0; r < 4; ++r) {
;                     const v2i d = TR4(ldsb + BUF[st % 3] + 2048 * tp + roff[r]);
;                     accH[r] = __builtin_amdgcn_sdot8(d.x, ah.x, accH[r], false); accH[r] = __builtin_amdgcn_sdot8(d.y, ah.y, accH[r], false);
;                     accL[r] = __builtin_amdgcn_sdot8(d.x, ao.x, accL[r], false); accL[r] = __builtin_amdgcn_sdot8(d.y, ao.y, accL[r], false);
;                 }
	v_dot8c_i32_i4_e32 v38, v122, v48
	v_dot8c_i32_i4_e32 v39, v122, v46
	v_dot8c_i32_i4_e32 v40, v124, v48
	v_dot8c_i32_i4_e32 v41, v124, v46
	v_dot8c_i32_i4_e32 v42, v126, v48
	v_dot8c_i32_i4_e32 v43, v126, v46
	v_dot8c_i32_i4_e32 v44, v128, v48
	v_dot8c_i32_i4_e32 v45, v128, v46
	v_dot8c_i32_i4_e32 v38, v123, v49
	v_dot8c_i32_i4_e32 v39, v123, v47
	v_dot8c_i32_i4_e32 v40, v125, v49
	v_dot8c_i32_i4_e32 v41, v125, v47
	v_dot8c_i32_i4_e32 v42, v127, v49
	v_dot8c_i32_i4_e32 v43, v127, v47
	v_dot8c_i32_i4_e32 v44, v129, v49
	v_dot8c_i32_i4_e32 v45, v129, v47
	v_and_b32_e32 v78, 0xffff, v24
	v_lshrrev_b32_e32 v79, 16, v24
	v_lshl_add_u32 v78, v78, 7, v152
	v_lshl_add_u32 v79, v79, 7, v153
	s_mov_b32 m0, s78
	s_add_i32 s43, s78, 0x400
	global_load_lds_dwordx4 v78, s[50:51]
	s_mov_b32 m0, s43
	s_nop 0
	global_load_lds_dwordx4 v79, s[50:51]
	s_waitcnt vmcnt(13)
	v_add_u32_e32 v54, s98, v59
	v_add_u32_e32 v55, s98, v60
	v_add_u32_e32 v56, s98, v61
	v_add_u32_e32 v57, s98, v62
	ds_read_b64_tr_b4 v[46:47], v160 offset:256
	ds_read_b64_tr_b4 v[48:49], v160 offset:1280
	ds_read_b64_tr_b4 v[122:123], v54
	ds_read_b64_tr_b4 v[124:125], v55
	ds_read_b64_tr_b4 v[126:127], v56
	ds_read_b64_tr_b4 v[128:129], v57
	s_waitcnt lgkmcnt(6)
	v_dot8c_i32_i4_e32 v38, v130, v52
	v_dot8c_i32_i4_e32 v39, v130, v50
	v_dot8c_i32_i4_e32 v40, v132, v52
	v_dot8c_i32_i4_e32 v41, v132, v50
	v_dot8c_i32_i4_e32 v42, v134, v52
	v_dot8c_i32_i4_e32 v43, v134, v50
	v_dot8c_i32_i4_e32 v44, v136, v52
	v_dot8c_i32_i4_e32 v45, v136, v50
	v_dot8c_i32_i4_e32 v38, v131, v53
	v_dot8c_i32_i4_e32 v39, v131, v51
	v_dot8c_i32_i4_e32 v40, v133, v53
	v_dot8c_i32_i4_e32 v41, v133, v51
	v_dot8c_i32_i4_e32 v42, v135, v53
	v_dot8c_i32_i4_e32 v43, v135, v51
	v_dot8c_i32_i4_e32 v44, v137, v53
	v_dot8c_i32_i4_e32 v45, v137, v51
	v_and_b32_e32 v78, 0xffff, v25
	v_lshrrev_b32_e32 v79, 16, v25
	v_lshl_add_u32 v78, v78, 7, v152
	v_lshl_add_u32 v79, v79, 7, v153
	s_mov_b32 m0, s79
	s_add_i32 s43, s79, 0x400
	global_load_lds_dwordx4 v78, s[50:51]
	s_mov_b32 m0, s43
	s_nop 0
	global_load_lds_dwordx4 v79, s[50:51]
	s_waitcnt vmcnt(13)
	v_add_u32_e32 v54, s99, v59
	v_add_u32_e32 v55, s99, v60
	v_add_u32_e32 v56, s99, v61
	v_add_u32_e32 v57, s99, v62
	ds_read_b64_tr_b4 v[50:51], v160 offset:384
	ds_read_b64_tr_b4 v[52:53], v160 offset:1408
	ds_read_b64_tr_b4 v[130:131], v54
	ds_read_b64_tr_b4 v[132:133], v55
	ds_read_b64_tr_b4 v[134:135], v56
	ds_read_b64_tr_b4 v[136:137], v57
	s_waitcnt lgkmcnt(6)
	v_dot8c_i32_i4_e32 v38, v122, v48
	v_dot8c_i32_i4_e32 v39, v122, v46
	v_dot8c_i32_i4_e32 v40, v124, v48
	v_dot8c_i32_i4_e32 v41, v124, v46
	v_dot8c_i32_i4_e32 v42, v126, v48
	v_dot8c_i32_i4_e32 v43, v126, v46
	v_dot8c_i32_i4_e32 v44, v128, v48
	v_dot8c_i32_i4_e32 v45, v128, v46
	v_dot8c_i32_i4_e32 v38, v123, v49
	v_dot8c_i32_i4_e32 v39, v123, v47
	v_dot8c_i32_i4_e32 v40, v125, v49
	v_dot8c_i32_i4_e32 v41, v125, v47
	v_dot8c_i32_i4_e32 v42, v127, v49
	v_dot8c_i32_i4_e32 v43, v127, v47
	v_dot8c_i32_i4_e32 v44, v129, v49
	v_dot8c_i32_i4_e32 v45, v129, v47
	s_waitcnt lgkmcnt(15)
	v_and_b32_e32 v78, 0xffff, v26
	v_lshrrev_b32_e32 v79, 16, v26
	v_lshl_add_u32 v78, v78, 7, v152
	v_lshl_add_u32 v79, v79, 7, v153
	s_mov_b32 m0, s98
	s_add_i32 s43, s98, 0x400
	global_load_lds_dwordx4 v78, s[50:51]
	s_mov_b32 m0, s43
	s_nop 0
	global_load_lds_dwordx4 v79, s[50:51]
	s_waitcnt vmcnt(13)
	v_add_u32_e32 v54, s76, v59
	v_add_u32_e32 v55, s76, v60
	v_add_u32_e32 v56, s76, v61
	v_add_u32_e32 v57, s76, v62
	ds_read_b64_tr_b4 v[46:47], v160 offset:512
	ds_read_b64_tr_b4 v[48:49], v160 offset:1536
	ds_read_b64_tr_b4 v[122:123], v54
	ds_read_b64_tr_b4 v[124:125], v55
	ds_read_b64_tr_b4 v[126:127], v56
	ds_read_b64_tr_b4 v[128:129], v57
	s_waitcnt lgkmcnt(6)
	v_dot8c_i32_i4_e32 v38, v130, v52
	v_dot8c_i32_i4_e32 v39, v130, v50
	v_dot8c_i32_i4_e32 v40, v132, v52
	v_dot8c_i32_i4_e32 v41, v132, v50
	v_dot8c_i32_i4_e32 v42, v134, v52
	v_dot8c_i32_i4_e32 v43, v134, v50
	v_dot8c_i32_i4_e32 v44, v136, v52
	v_dot8c_i32_i4_e32 v45, v136, v50
	v_dot8c_i32_i4_e32 v38, v131, v53
	v_dot8c_i32_i4_e32 v39, v131, v51
	v_dot8c_i32_i4_e32 v40, v133, v53
	v_dot8c_i32_i4_e32 v41, v133, v51
	v_dot8c_i32_i4_e32 v42, v135, v53
	v_dot8c_i32_i4_e32 v43, v135, v51
	v_dot8c_i32_i4_e32 v44, v137, v53
	v_dot8c_i32_i4_e32 v45, v137, v51
	v_and_b32_e32 v78, 0xffff, v27
	v_lshrrev_b32_e32 v79, 16, v27
	v_lshl_add_u32 v78, v78, 7, v152
	v_lshl_add_u32 v79, v79, 7, v153
	s_mov_b32 m0, s99
	s_add_i32 s43, s99, 0x400
	global_load_lds_dwordx4 v78, s[50:51]
	s_mov_b32 m0, s43
	s_nop 0
	global_load_lds_dwordx4 v79, s[50:51]
	s_waitcnt vmcnt(8)
	v_add_u32_e32 v54, s77, v59
	v_add_u32_e32 v55, s77, v60
	v_add_u32_e32 v56, s77, v61
	v_add_u32_e32 v57, s77, v62
	ds_read_b64_tr_b4 v[50:51], v160 offset:640
	ds_read_b64_tr_b4 v[52:53], v160 offset:1664
	ds_read_b64_tr_b4 v[130:131], v54
	ds_read_b64_tr_b4 v[132:133], v55
	ds_read_b64_tr_b4 v[134:135], v56
	ds_read_b64_tr_b4 v[136:137], v57
	s_waitcnt lgkmcnt(6)
	v_dot8c_i32_i4_e32 v38, v122, v48
	v_dot8c_i32_i4_e32 v39, v122, v46
	v_dot8c_i32_i4_e32 v40, v124, v48
	v_dot8c_i32_i4_e32 v41, v124, v46
	v_dot8c_i32_i4_e32 v42, v126, v48
	v_dot8c_i32_i4_e32 v43, v126, v46
	v_dot8c_i32_i4_e32 v44, v128, v48
	v_dot8c_i32_i4_e32 v45, v128, v46
	v_dot8c_i32_i4_e32 v38, v123, v49
	v_dot8c_i32_i4_e32 v39, v123, v47
	v_dot8c_i32_i4_e32 v40, v125, v49
	v_dot8c_i32_i4_e32 v41, v125, v47
	v_dot8c_i32_i4_e32 v42, v127, v49
	v_dot8c_i32_i4_e32 v43, v127, v47
	v_dot8c_i32_i4_e32 v44, v129, v49
	v_dot8c_i32_i4_e32 v45, v129, v47
	s_waitcnt lgkmcnt(15)
; __device__ __forceinline__ void peer_v_tokens(int j, const LAS unsigned short* EL, const LAS unsigned char* AL  , const LAS float* ASC  , const LAS int* SAL  , ...
;     ...
; #pragma unroll
;         for (int st = 0; st < 16; ++st) {
;             const int p = st >> 2, q = st & 3;
;             if (st < 14) VDMA(st + 2, (st + 2) % 3);
;             if (st < 14) asm volatile("s_waitcnt vmcnt(8)" ::: "memory");
;             else if (st == 14) asm volatile("s_waitcnt vmcnt(4)" ::: "memory");
;             else asm volatile("s_waitcnt vmcnt(0)" ::: "memory");
;             if (q == 0) {
; #pragma unroll
;                 for (int r = 0; r < 4; ++r) { accH[r] = 0; accL[r] = 0; } }
; #pragma unroll
;             for (int tp = 0; tp < 2; ++tp) {
;                 const v2i ao = TR4(ATL + (2 * q + tp) * 128 + 8 * s16), ah = TR4(ATL + 1024 + (2 * q + tp) * 128 + 8 * s16);
; #pragma unroll
;                 for (int r = 0; r < 4; ++r) {
;                     const v2i d = TR4(ldsb + BUF[st % 3] + 2048 * tp + roff[r]);
;                     accH[r] = __builtin_amdgcn_sdot8(d.x, ah.x, accH[r], false); accH[r] = __builtin_amdgcn_sdot8(d.y, ah.y, accH[r], false);
;                     accL[r] = __builtin_amdgcn_sdot8(d.x, ao.x, accL[r], false); accL[r] = __builtin_amdgcn_sdot8(d.y, ao.y, accL[r], false);
;                 }
;             }
;             asm volatile("s_waitcnt lgkmcnt(0)" ::: "memory");
;             if (q == 3) {
; #pragma unroll
;                 for (int r = 0; r < 4; ++r) STASH[256 * p + 16 * (grp + 4 * r) + pc] = f2bf(asc * (float)(2 * ((accH[r] << 4) + accL[r]) + sa));
;             }
;         }
;         CFENCE();
;         {
;             float4 v[4]; float ss = 0.f;
; #pragma unroll
;             for (int jq = 0; jq < 4; ++jq) { typedef unsigned u2v __attribute__((ext_vector_type(2))); const u2v pw = *(const LAS u2v*)(STASH + 4 * lane + 256 * jq); const uint2 hw = hv[jq];
;                 v[jq] = make_float4(__uint_as_float(hw.x << 16) + __uint_as_float(pw.x << 16), __uint_as_float(hw.x & 0xffff0000u) + __uint_as_float(pw.x & 0xffff0000u),
;                                     __uint_as_float(hw.y << 16) + __uint_as_float(pw.y << 16), __uint_as_float(hw.y & 0xffff0000u) + __uint_as_float(pw.y & 0xffff0000u));
;                 ss += v[jq].x * v[jq].x + v[jq].y * v[jq].y + v[jq].z * v[jq].z + v[jq].w * v[jq].w; }
;             ss = wave_sum(ss);
	v_add_u32_e32 v143, 8, v139
	v_and_b32_e32 v142, 15, v143
	v_xor_b32_e32 v142, 8, v142
	v_bfe_u32 v144, v143, 4, 4
	v_mul_lo_u32 v142, v142, s92
	v_mul_lo_u32 v144, v144, s92
	v_mov_b32_e32 v143, v142
	v_mov_b32_e32 v145, v144
	ds_write2st64_b64 v159, v[142:143], v[144:145] offset1:2
	v_and_b32_e32 v78, 0xffff, v28
	v_lshrrev_b32_e32 v79, 16, v28
	v_lshl_add_u32 v78, v78, 7, v152
	v_lshl_add_u32 v79, v79, 7, v153
	s_mov_b32 m0, s76
	s_add_i32 s43, s76, 0x400
	global_load_lds_dwordx4 v78, s[50:51]
	s_mov_b32 m0, s43
	s_nop 0
	global_load_lds_dwordx4 v79, s[50:51]
	s_waitcnt vmcnt(8)
	v_add_u32_e32 v54, s78, v59
	v_add_u32_e32 v55, s78, v60
	v_add_u32_e32 v56, s78, v61
	v_add_u32_e32 v57, s78, v62
	ds_read_b64_tr_b4 v[46:47], v160 offset:768
	ds_read_b64_tr_b4 v[48:49], v160 offset:1792
	ds_read_b64_tr_b4 v[122:123], v54
	ds_read_b64_tr_b4 v[124:125], v55
	ds_read_b64_tr_b4 v[126:127], v56
	ds_read_b64_tr_b4 v[128:129], v57
	s_waitcnt lgkmcnt(7)
	v_dot8c_i32_i4_e32 v38, v130, v52
	v_dot8c_i32_i4_e32 v39, v130, v50
	v_dot8c_i32_i4_e32 v40, v132, v52
	v_dot8c_i32_i4_e32 v41, v132, v50
	v_dot8c_i32_i4_e32 v42, v134, v52
	v_dot8c_i32_i4_e32 v43, v134, v50
	v_dot8c_i32_i4_e32 v44, v136, v52
	v_dot8c_i32_i4_e32 v45, v136, v50
	v_dot8c_i32_i4_e32 v38, v131, v53
	v_dot8c_i32_i4_e32 v39, v131, v51
	v_dot8c_i32_i4_e32 v40, v133, v53
	v_dot8c_i32_i4_e32 v41, v133, v51
	v_dot8c_i32_i4_e32 v42, v135, v53
	v_dot8c_i32_i4_e32 v43, v135, v51
	v_dot8c_i32_i4_e32 v44, v137, v53
	v_dot8c_i32_i4_e32 v45, v137, v51
	v_and_b32_e32 v78, 0xffff, v29
	v_lshrrev_b32_e32 v79, 16, v29
	v_lshl_add_u32 v78, v78, 7, v152
	v_lshl_add_u32 v79, v79, 7, v153
	s_mov_b32 m0, s77
	s_add_i32 s43, s77, 0x400
	global_load_lds_dwordx4 v78, s[50:51]
	s_mov_b32 m0, s43
	s_nop 0
	global_load_lds_dwordx4 v79, s[50:51]
	s_waitcnt vmcnt(8)
	v_add_u32_e32 v54, s79, v59
	v_add_u32_e32 v55, s79, v60
	v_add_u32_e32 v56, s79, v61
	v_add_u32_e32 v57, s79, v62
	ds_read_b64_tr_b4 v[50:51], v160 offset:896
	ds_read_b64_tr_b4 v[52:53], v160 offset:1920
	ds_read_b64_tr_b4 v[130:131], v54
	ds_read_b64_tr_b4 v[132:133], v55
	ds_read_b64_tr_b4 v[134:135], v56
	ds_read_b64_tr_b4 v[136:137], v57
	s_waitcnt lgkmcnt(6)
	v_dot8c_i32_i4_e32 v38, v122, v48
	v_dot8c_i32_i4_e32 v39, v122, v46
	v_dot8c_i32_i4_e32 v40, v124, v48
	v_dot8c_i32_i4_e32 v41, v124, v46
	v_dot8c_i32_i4_e32 v42, v126, v48
	v_dot8c_i32_i4_e32 v43, v126, v46
	v_dot8c_i32_i4_e32 v44, v128, v48
	v_dot8c_i32_i4_e32 v45, v128, v46
	v_dot8c_i32_i4_e32 v38, v123, v49
	v_dot8c_i32_i4_e32 v39, v123, v47
	v_dot8c_i32_i4_e32 v40, v125, v49
	v_dot8c_i32_i4_e32 v41, v125, v47
	v_dot8c_i32_i4_e32 v42, v127, v49
	v_dot8c_i32_i4_e32 v43, v127, v47
	v_dot8c_i32_i4_e32 v44, v129, v49
	v_dot8c_i32_i4_e32 v45, v129, v47
	v_and_b32_e32 v78, 0xffff, v30
	v_lshrrev_b32_e32 v79, 16, v30
	v_lshl_add_u32 v78, v78, 7, v152
	v_lshl_add_u32 v79, v79, 7, v153
	s_mov_b32 m0, s78
	s_add_i32 s43, s78, 0x400
	global_load_lds_dwordx4 v78, s[50:51]
	s_mov_b32 m0, s43
	s_nop 0
	global_load_lds_dwordx4 v79, s[50:51]
	s_waitcnt vmcnt(8)
	v_add_u32_e32 v54, s98, v59
	v_add_u32_e32 v55, s98, v60
	v_add_u32_e32 v56, s98, v61
	v_add_u32_e32 v57, s98, v62
	ds_read_b64_tr_b4 v[46:47], v160
	ds_read_b64_tr_b4 v[48:49], v160 offset:1024
	ds_read_b64_tr_b4 v[122:123], v54
	ds_read_b64_tr_b4 v[124:125], v55
	ds_read_b64_tr_b4 v[126:127], v56
	ds_read_b64_tr_b4 v[128:129], v57
	s_waitcnt lgkmcnt(6)
	v_dot8c_i32_i4_e32 v38, v130, v52
	v_dot8c_i32_i4_e32 v39, v130, v50
	v_dot8c_i32_i4_e32 v40, v132, v52
	v_dot8c_i32_i4_e32 v41, v132, v50
	v_dot8c_i32_i4_e32 v42, v134, v52
	v_dot8c_i32_i4_e32 v43, v134, v50
	v_dot8c_i32_i4_e32 v44, v136, v52
	v_dot8c_i32_i4_e32 v45, v136, v50
	v_dot8c_i32_i4_e32 v38, v131, v53
	v_dot8c_i32_i4_e32 v39, v131, v51
	v_dot8c_i32_i4_e32 v40, v133, v53
	v_dot8c_i32_i4_e32 v41, v133, v51
	v_dot8c_i32_i4_e32 v42, v135, v53
	v_dot8c_i32_i4_e32 v43, v135, v51
	v_dot8c_i32_i4_e32 v44, v137, v53
	v_dot8c_i32_i4_e32 v45, v137, v51
	s_nop 3
	s_waitcnt lgkmcnt(15)
	v_lshlrev_b32_e32 v38, 5, v38
	v_lshlrev_b32_e32 v39, 1, v39
	v_add3_u32 v38, v39, v229, v38
	v_cvt_f32_i32_e32 v38, v38
	v_mul_f32_e32 v38, v228, v38
	v_lshlrev_b32_e32 v40, 5, v40
	v_lshlrev_b32_e32 v41, 1, v41
	v_add3_u32 v40, v41, v229, v40
	v_cvt_f32_i32_e32 v40, v40
	v_mul_f32_e32 v40, v228, v40
	v_lshlrev_b32_e32 v42, 5, v42
	v_lshlrev_b32_e32 v43, 1, v43
	v_add3_u32 v42, v43, v229, v42
	v_cvt_f32_i32_e32 v42, v42
	v_mul_f32_e32 v42, v228, v42
	v_lshlrev_b32_e32 v44, 5, v44
	v_lshlrev_b32_e32 v45, 1, v45
	v_add3_u32 v44, v45, v229, v44
	v_cvt_f32_i32_e32 v44, v44
	v_mul_f32_e32 v44, v228, v44
	v_cvt_pk_bf16_f32 v180, v38, v40
	v_cvt_pk_bf16_f32 v181, v42, v44
	ds_read_b128 v[252:255], v155 offset:1024
	s_add_i32 s44, s40, 0
	s_ashr_i32 s45, s44, 31
	s_lshl_b64 s[44:45], s[44:45], 12
	v_lshl_add_u64 v[80:81], v[36:37], 0, s[44:45]
	s_waitcnt lgkmcnt(0)
	v_mul_f32_e32 v214, v214, v252
	v_mul_f32_e32 v215, v215, v253
	v_mul_f32_e32 v216, v216, v254
	v_mul_f32_e32 v217, v217, v255
	global_store_dwordx4 v[80:81], v[214:217], off offset:1024 nt
	v_add_u32_e32 v147, 8, v140
	v_and_b32_e32 v146, 15, v147
	v_xor_b32_e32 v146, 8, v146
	v_bfe_u32 v148, v147, 4, 4
	v_mul_lo_u32 v146, v146, s92
	v_mul_lo_u32 v148, v148, s92
	v_mov_b32_e32 v147, v146
	v_mov_b32_e32 v149, v148
	ds_write2st64_b64 v77, v[146:147], v[148:149] offset1:2
	v_add_u32_e32 v138, 0x800, v74
	ds_read_u8 v139, v138
	v_add_u32_e32 v141, 0x800, v73
	ds_read_u8 v140, v141
	s_add_i32 s43, s67, 96
	v_mov_b32_e32 v138, s43
	ds_read2st64_b32 v[228:229], v138 offset1:1
	ds_read_b128 v[18:21], v227 offset:4096
	ds_read_b128 v[22:25], v227 offset:4112
	v_add_u32_e32 v150, 0x400000, v63
	v_add_u32_e32 v151, 0x400000, v64
	v_mov_b32_e32 v38, 0
	v_mov_b32_e32 v39, 0
	v_mov_b32_e32 v40, 0
	v_mov_b32_e32 v41, 0
	v_mov_b32_e32 v42, 0
	v_mov_b32_e32 v43, 0
	v_mov_b32_e32 v44, 0
	v_mov_b32_e32 v45, 0
	v_and_b32_e32 v78, 0xffff, v31
	v_lshrrev_b32_e32 v79, 16, v31
	v_lshl_add_u32 v78, v78, 7, v152
	v_lshl_add_u32 v79, v79, 7, v153
	s_mov_b32 m0, s79
	s_add_i32 s43, s79, 0x400
	global_load_lds_dwordx4 v78, s[50:51]
	s_mov_b32 m0, s43
	s_nop 0
	global_load_lds_dwordx4 v79, s[50:51]
	s_waitcnt vmcnt(9)
; #define LAS __attribute__((address_space(3)))
; __device__ __forceinline__ bf16 f2bf(float f) { return (bf16)f2bfu(f); }
; #define TR4(p_) __builtin_amdgcn_ds_read_tr4_b64_v2i32((LAS v2i*)(p_))
; #define CFENCE() asm volatile("" ::: "memory")
; __device__ __forceinline__ void peer_v_tokens(int j, const LAS unsigned short* EL, const LAS unsigned char* AL  , const LAS float* ASC  , const LAS int* SAL  , ...
;     ...
; #pragma unroll
;         for (int st = 0; st < 16; ++st) {
;             const int p = st >> 2, q = st & 3;
;             if (st < 14) VDMA(st + 2, (st + 2) % 3);
;             if (st < 14) asm volatile("s_waitcnt vmcnt(8)" ::: "memory");
;             else if (st == 14) asm volatile("s_waitcnt vmcnt(4)" ::: "memory");
;             else asm volatile("s_waitcnt vmcnt(0)" ::: "memory");
;             if (q == 0) {
; #pragma unroll
;                 for (int r = 0; r < 4; ++r) { accH[r] = 0; accL[r] = 0; } }
; #pragma unroll
;             for (int tp = 0; tp < 2; ++tp) {
;                 const v2i ao = TR4(ATL + (2 * q + tp) * 128 + 8 * s16), ah = TR4(ATL + 1024 + (2 * q + tp) * 128 + 8 * s16);
; #pragma unroll
;                 for (int r = 0; r < 4; ++r) {
;                     const v2i d = TR4(ldsb + BUF[st % 3] + 2048 * tp + roff[r]);
;                     accH[r] = __builtin_amdgcn_sdot8(d.x, ah.x, accH[r], false); accH[r] = __builtin_amdgcn_sdot8(d.y, ah.y, accH[r], false);
;                     accL[r] = __builtin_amdgcn_sdot8(d.x, ao.x, accL[r], false); accL[r] = __builtin_amdgcn_sdot8(d.y, ao.y, accL[r], false);
;                 }
;             }
;             asm volatile("s_waitcnt lgkmcnt(0)" ::: "memory");
;             if (q == 3) {
; #pragma unroll
;                 for (int r = 0; r < 4; ++r) STASH[256 * p + 16 * (grp + 4 * r) + pc] = f2bf(asc * (float)(2 * ((accH[r] << 4) + accL[r]) + sa));
;             }
;         }
;         CFENCE();
;         {
;             float4 v[4]; float ss = 0.f;
; #pragma unroll
;             for (int jq = 0; jq < 4; ++jq) { typedef unsigned u2v __attribute__((ext_vector_type(2))); const u2v pw = *(const LAS u2v*)(STASH + 4 * lane + 256 * jq); const uint2 hw = hv[jq];
	v_add_u32_e32 v54, s99, v59
	v_add_u32_e32 v55, s99, v60
	v_add_u32_e32 v56, s99, v61
	v_add_u32_e32 v57, s99, v62
	ds_read_b64_tr_b4 v[50:51], v160 offset:128
	ds_read_b64_tr_b4 v[52:53], v160 offset:1152
	ds_read_b64_tr_b4 v[130:131], v54
	ds_read_b64_tr_b4 v[132:133], v55
	ds_read_b64_tr_b4 v[134:135], v56
	ds_read_b64_tr_b4 v[136:137], v57
	s_waitcnt lgkmcnt(13)
	v_dot8c_i32_i4_e32 v38, v122, v48
	v_dot8c_i32_i4_e32 v39, v122, v46
	v_dot8c_i32_i4_e32 v40, v124, v48
	v_dot8c_i32_i4_e32 v41, v124, v46
	v_dot8c_i32_i4_e32 v42, v126, v48
	v_dot8c_i32_i4_e32 v43, v126, v46
	v_dot8c_i32_i4_e32 v44, v128, v48
	v_dot8c_i32_i4_e32 v45, v128, v46
	v_dot8c_i32_i4_e32 v38, v123, v49
	v_dot8c_i32_i4_e32 v39, v123, v47
	v_dot8c_i32_i4_e32 v40, v125, v49
	v_dot8c_i32_i4_e32 v41, v125, v47
	v_dot8c_i32_i4_e32 v42, v127, v49
	v_dot8c_i32_i4_e32 v43, v127, v47
	v_dot8c_i32_i4_e32 v44, v129, v49
	v_dot8c_i32_i4_e32 v45, v129, v47
	v_and_b32_e32 v78, 0xffff, v32
	v_lshrrev_b32_e32 v79, 16, v32
	v_lshl_add_u32 v78, v78, 7, v152
	v_lshl_add_u32 v79, v79, 7, v153
	s_mov_b32 m0, s98
	s_add_i32 s43, s98, 0x400
	global_load_lds_dwordx4 v78, s[50:51]
	s_mov_b32 m0, s43
	s_nop 0
	global_load_lds_dwordx4 v79, s[50:51]
	s_waitcnt vmcnt(9)
	v_add_u32_e32 v54, s76, v59
	v_add_u32_e32 v55, s76, v60
	v_add_u32_e32 v56, s76, v61
	v_add_u32_e32 v57, s76, v62
	ds_read_b64_tr_b4 v[46:47], v160 offset:256
	ds_read_b64_tr_b4 v[48:49], v160 offset:1280
	ds_read_b64_tr_b4 v[122:123], v54
	ds_read_b64_tr_b4 v[124:125], v55
	ds_read_b64_tr_b4 v[126:127], v56
	ds_read_b64_tr_b4 v[128:129], v57
	s_waitcnt lgkmcnt(6)
	v_dot8c_i32_i4_e32 v38, v130, v52
	v_dot8c_i32_i4_e32 v39, v130, v50
	v_dot8c_i32_i4_e32 v40, v132, v52
	v_dot8c_i32_i4_e32 v41, v132, v50
	v_dot8c_i32_i4_e32 v42, v134, v52
	v_dot8c_i32_i4_e32 v43, v134, v50
	v_dot8c_i32_i4_e32 v44, v136, v52
	v_dot8c_i32_i4_e32 v45, v136, v50
	v_dot8c_i32_i4_e32 v38, v131, v53
	v_dot8c_i32_i4_e32 v39, v131, v51
	v_dot8c_i32_i4_e32 v40, v133, v53
	v_dot8c_i32_i4_e32 v41, v133, v51
	v_dot8c_i32_i4_e32 v42, v135, v53
	v_dot8c_i32_i4_e32 v43, v135, v51
	v_dot8c_i32_i4_e32 v44, v137, v53
	v_dot8c_i32_i4_e32 v45, v137, v51
	ds_write_b16 v65, v170
	ds_write_b16_d16_hi v65, v170 offset:128
	ds_write_b16 v65, v171 offset:256
	ds_write_b16_d16_hi v65, v171 offset:384
	ds_write_b16 v65, v172 offset:512
	ds_write_b16_d16_hi v65, v172 offset:640
	ds_write_b16 v65, v173 offset:768
	ds_write_b16_d16_hi v65, v173 offset:896
	ds_write_b16 v65, v174 offset:1024
	ds_write_b16_d16_hi v65, v174 offset:1152
	ds_write_b16 v65, v175 offset:1280
	ds_write_b16_d16_hi v65, v175 offset:1408
	ds_write_b16 v65, v176 offset:1536
	ds_write_b16_d16_hi v65, v176 offset:1664
	ds_write_b16 v65, v177 offset:1792
	ds_write_b16_d16_hi v65, v177 offset:1920
	ds_read_b64 v[202:203], v154
	ds_read_b64 v[204:205], v154 offset:512
	ds_read_b64 v[206:207], v154 offset:1024
	ds_read_b64 v[208:209], v154 offset:1536
	v_and_b32_e32 v78, 0xffff, v33
	v_lshrrev_b32_e32 v79, 16, v33
	v_lshl_add_u32 v78, v78, 7, v152
	v_lshl_add_u32 v79, v79, 7, v153
	s_mov_b32 m0, s99
	s_add_i32 s43, s99, 0x400
	global_load_lds_dwordx4 v78, s[50:51]
	s_mov_b32 m0, s43
	s_nop 0
	global_load_lds_dwordx4 v79, s[50:51]
	s_waitcnt vmcnt(9)
	v_add_u32_e32 v54, s77, v59
	v_add_u32_e32 v55, s77, v60
	v_add_u32_e32 v56, s77, v61
	v_add_u32_e32 v57, s77, v62
	ds_read_b64_tr_b4 v[50:51], v160 offset:384
	ds_read_b64_tr_b4 v[52:53], v160 offset:1408
	ds_read_b64_tr_b4 v[130:131], v54
	ds_read_b64_tr_b4 v[132:133], v55
	ds_read_b64_tr_b4 v[134:135], v56
	ds_read_b64_tr_b4 v[136:137], v57
	s_waitcnt lgkmcnt(15)
	v_dot8c_i32_i4_e32 v38, v122, v48
	v_dot8c_i32_i4_e32 v39, v122, v46
	v_dot8c_i32_i4_e32 v40, v124, v48
	v_dot8c_i32_i4_e32 v41, v124, v46
	v_dot8c_i32_i4_e32 v42, v126, v48
	v_dot8c_i32_i4_e32 v43, v126, v46
	v_dot8c_i32_i4_e32 v44, v128, v48
	v_dot8c_i32_i4_e32 v45, v128, v46
	v_dot8c_i32_i4_e32 v38, v123, v49
	v_dot8c_i32_i4_e32 v39, v123, v47
	v_dot8c_i32_i4_e32 v40, v125, v49
	v_dot8c_i32_i4_e32 v41, v125, v47
	v_dot8c_i32_i4_e32 v42, v127, v49
	v_dot8c_i32_i4_e32 v43, v127, v47
	v_dot8c_i32_i4_e32 v44, v129, v49
	v_dot8c_i32_i4_e32 v45, v129, v47
	s_waitcnt lgkmcnt(15)
	v_and_b32_e32 v78, 0xffff, v18
	v_lshrrev_b32_e32 v79, 16, v18
	v_lshl_add_u32 v78, v78, 7, v150
	v_lshl_add_u32 v79, v79, 7, v151
	s_mov_b32 m0, s76
	s_add_i32 s43, s76, 0x400
	global_load_lds_dwordx4 v78, s[50:51]
	s_mov_b32 m0, s43
	s_nop 0
	global_load_lds_dwordx4 v79, s[50:51]
	s_waitcnt vmcnt(9)
	v_add_u32_e32 v54, s78, v59
	v_add_u32_e32 v55, s78, v60
	v_add_u32_e32 v56, s78, v61
	v_add_u32_e32 v57, s78, v62
	ds_read_b64_tr_b4 v[46:47], v160 offset:512
	ds_read_b64_tr_b4 v[48:49], v160 offset:1536
	ds_read_b64_tr_b4 v[122:123], v54
	ds_read_b64_tr_b4 v[124:125], v55
	ds_read_b64_tr_b4 v[126:127], v56
	ds_read_b64_tr_b4 v[128:129], v57
	s_waitcnt lgkmcnt(6)
	v_dot8c_i32_i4_e32 v38, v130, v52
	v_dot8c_i32_i4_e32 v39, v130, v50
	v_dot8c_i32_i4_e32 v40, v132, v52
	v_dot8c_i32_i4_e32 v41, v132, v50
	v_dot8c_i32_i4_e32 v42, v134, v52
	v_dot8c_i32_i4_e32 v43, v134, v50
	v_dot8c_i32_i4_e32 v44, v136, v52
	v_dot8c_i32_i4_e32 v45, v136, v50
	v_dot8c_i32_i4_e32 v38, v131, v53
	v_dot8c_i32_i4_e32 v39, v131, v51
	v_dot8c_i32_i4_e32 v40, v133, v53
	v_dot8c_i32_i4_e32 v41, v133, v51
	v_dot8c_i32_i4_e32 v42, v135, v53
	v_dot8c_i32_i4_e32 v43, v135, v51
	v_dot8c_i32_i4_e32 v44, v137, v53
	v_dot8c_i32_i4_e32 v45, v137, v51
	v_and_b32_e32 v78, 0xffff, v19
	v_lshrrev_b32_e32 v79, 16, v19
	v_lshl_add_u32 v78, v78, 7, v150
	v_lshl_add_u32 v79, v79, 7, v151
	s_mov_b32 m0, s77
	s_add_i32 s43, s77, 0x400
	global_load_lds_dwordx4 v78, s[50:51]
	s_mov_b32 m0, s43
	s_nop 0
	global_load_lds_dwordx4 v79, s[50:51]
	s_waitcnt vmcnt(8)
; __device__ __forceinline__ bf16 f2bf(float f) { return (bf16)f2bfu(f); }
; #define TR4(p_) __builtin_amdgcn_ds_read_tr4_b64_v2i32((LAS v2i*)(p_))
; #define VDMA(st_, k_) do { _Pragma("unroll") for (int i_ = 0; i_ < 4; ++i_) { \
;         const unsigned off_ = (unsigned)((st_) >> 2) * (16384u * 128u) + (PE_ID(E, 4 * ((st_) & 3) + i_) << 7) + ((i_ & 1) ? cx1 : cx0); \
;         __builtin_amdgcn_global_load_lds((const unsigned*)(V4 + off_), (LAS unsigned*)(ldsb + BUF[k_] + 1024 * i_), 16, 0, 0); } } while (0)
; __device__ __forceinline__ void peer_v_tokens(int j, const LAS unsigned short* EL, const LAS unsigned char* AL  , const LAS float* ASC  , const LAS int* SAL  , ...
;     ...
; #pragma unroll
;         for (int st = 0; st < 16; ++st) {
;             const int p = st >> 2, q = st & 3;
;             if (st < 14) VDMA(st + 2, (st + 2) % 3);
;             if (st < 14) asm volatile("s_waitcnt vmcnt(8)" ::: "memory");
;             else if (st == 14) asm volatile("s_waitcnt vmcnt(4)" ::: "memory");
;             else asm volatile("s_waitcnt vmcnt(0)" ::: "memory");
;             if (q == 0) {
; #pragma unroll
;                 for (int r = 0; r < 4; ++r) { accH[r] = 0; accL[r] = 0; } }
; #pragma unroll
;             for (int tp = 0; tp < 2; ++tp) {
;                 const v2i ao = TR4(ATL + (2 * q + tp) * 128 + 8 * s16), ah = TR4(ATL + 1024 + (2 * q + tp) * 128 + 8 * s16);
; #pragma unroll
;                 for (int r = 0; r < 4; ++r) {
;                     const v2i d = TR4(ldsb + BUF[st % 3] + 2048 * tp + roff[r]);
;                     accH[r] = __builtin_amdgcn_sdot8(d.x, ah.x, accH[r], false); accH[r] = __builtin_amdgcn_sdot8(d.y, ah.y, accH[r], false);
;                     accL[r] = __builtin_amdgcn_sdot8(d.x, ao.x, accL[r], false); accL[r] = __builtin_amdgcn_sdot8(d.y, ao.y, accL[r], false);
;                 }
;             }
;             asm volatile("s_waitcnt lgkmcnt(0)" ::: "memory");
;             if (q == 3) {
; #pragma unroll
;                 for (int r = 0; r < 4; ++r) STASH[256 * p + 16 * (grp + 4 * r) + pc] = f2bf(asc * (float)(2 * ((accH[r] << 4) + accL[r]) + sa));
	v_add_u32_e32 v54, s79, v59
	v_add_u32_e32 v55, s79, v60
	v_add_u32_e32 v56, s79, v61
	v_add_u32_e32 v57, s79, v62
	ds_read_b64_tr_b4 v[50:51], v160 offset:640
	ds_read_b64_tr_b4 v[52:53], v160 offset:1664
	ds_read_b64_tr_b4 v[130:131], v54
	ds_read_b64_tr_b4 v[132:133], v55
	ds_read_b64_tr_b4 v[134:135], v56
	ds_read_b64_tr_b4 v[136:137], v57
	s_waitcnt lgkmcnt(6)
	v_dot8c_i32_i4_e32 v38, v122, v48
	v_dot8c_i32_i4_e32 v39, v122, v46
	v_dot8c_i32_i4_e32 v40, v124, v48
	v_dot8c_i32_i4_e32 v41, v124, v46
	v_dot8c_i32_i4_e32 v42, v126, v48
	v_dot8c_i32_i4_e32 v43, v126, v46
	v_dot8c_i32_i4_e32 v44, v128, v48
	v_dot8c_i32_i4_e32 v45, v128, v46
	v_dot8c_i32_i4_e32 v38, v123, v49
	v_dot8c_i32_i4_e32 v39, v123, v47
	v_dot8c_i32_i4_e32 v40, v125, v49
	v_dot8c_i32_i4_e32 v41, v125, v47
	v_dot8c_i32_i4_e32 v42, v127, v49
	v_dot8c_i32_i4_e32 v43, v127, v47
	v_dot8c_i32_i4_e32 v44, v129, v49
	v_dot8c_i32_i4_e32 v45, v129, v47
	s_waitcnt lgkmcnt(15)
	v_add_u32_e32 v143, 8, v139
	v_and_b32_e32 v142, 15, v143
	v_xor_b32_e32 v142, 8, v142
	v_bfe_u32 v144, v143, 4, 4
	v_mul_lo_u32 v142, v142, s92
	v_mul_lo_u32 v144, v144, s92
	v_mov_b32_e32 v143, v142
	v_mov_b32_e32 v145, v144
	ds_write2st64_b64 v159, v[142:143], v[144:145] offset1:2
	v_and_b32_e32 v78, 0xffff, v20
	v_lshrrev_b32_e32 v79, 16, v20
	v_lshl_add_u32 v78, v78, 7, v150
	v_lshl_add_u32 v79, v79, 7, v151
	s_mov_b32 m0, s78
	s_add_i32 s43, s78, 0x400
	global_load_lds_dwordx4 v78, s[50:51]
	s_mov_b32 m0, s43
	s_nop 0
	global_load_lds_dwordx4 v79, s[50:51]
	s_waitcnt vmcnt(8)
	v_add_u32_e32 v54, s98, v59
	v_add_u32_e32 v55, s98, v60
	v_add_u32_e32 v56, s98, v61
	v_add_u32_e32 v57, s98, v62
	ds_read_b64_tr_b4 v[46:47], v160 offset:768
	ds_read_b64_tr_b4 v[48:49], v160 offset:1792
	ds_read_b64_tr_b4 v[122:123], v54
	ds_read_b64_tr_b4 v[124:125], v55
	ds_read_b64_tr_b4 v[126:127], v56
	ds_read_b64_tr_b4 v[128:129], v57
	s_waitcnt lgkmcnt(7)
	v_dot8c_i32_i4_e32 v38, v130, v52
	v_dot8c_i32_i4_e32 v39, v130, v50
	v_dot8c_i32_i4_e32 v40, v132, v52
	v_dot8c_i32_i4_e32 v41, v132, v50
	v_dot8c_i32_i4_e32 v42, v134, v52
	v_dot8c_i32_i4_e32 v43, v134, v50
	v_dot8c_i32_i4_e32 v44, v136, v52
	v_dot8c_i32_i4_e32 v45, v136, v50
	v_dot8c_i32_i4_e32 v38, v131, v53
	v_dot8c_i32_i4_e32 v39, v131, v51
	v_dot8c_i32_i4_e32 v40, v133, v53
	v_dot8c_i32_i4_e32 v41, v133, v51
	v_dot8c_i32_i4_e32 v42, v135, v53
	v_dot8c_i32_i4_e32 v43, v135, v51
	v_dot8c_i32_i4_e32 v44, v137, v53
	v_dot8c_i32_i4_e32 v45, v137, v51
	v_and_b32_e32 v78, 0xffff, v21
	v_lshrrev_b32_e32 v79, 16, v21
	v_lshl_add_u32 v78, v78, 7, v150
	v_lshl_add_u32 v79, v79, 7, v151
	s_mov_b32 m0, s79
	s_add_i32 s43, s79, 0x400
	global_load_lds_dwordx4 v78, s[50:51]
	s_mov_b32 m0, s43
	s_nop 0
	global_load_lds_dwordx4 v79, s[50:51]
	s_waitcnt vmcnt(8)
	v_add_u32_e32 v54, s99, v59
	v_add_u32_e32 v55, s99, v60
	v_add_u32_e32 v56, s99, v61
	v_add_u32_e32 v57, s99, v62
	ds_read_b64_tr_b4 v[50:51], v160 offset:896
	ds_read_b64_tr_b4 v[52:53], v160 offset:1920
	ds_read_b64_tr_b4 v[130:131], v54
	ds_read_b64_tr_b4 v[132:133], v55
	ds_read_b64_tr_b4 v[134:135], v56
	ds_read_b64_tr_b4 v[136:137], v57
	s_waitcnt lgkmcnt(6)
	v_dot8c_i32_i4_e32 v38, v122, v48
	v_dot8c_i32_i4_e32 v39, v122, v46
	v_dot8c_i32_i4_e32 v40, v124, v48
	v_dot8c_i32_i4_e32 v41, v124, v46
	v_dot8c_i32_i4_e32 v42, v126, v48
	v_dot8c_i32_i4_e32 v43, v126, v46
	v_dot8c_i32_i4_e32 v44, v128, v48
	v_dot8c_i32_i4_e32 v45, v128, v46
	v_dot8c_i32_i4_e32 v38, v123, v49
	v_dot8c_i32_i4_e32 v39, v123, v47
	v_dot8c_i32_i4_e32 v40, v125, v49
	v_dot8c_i32_i4_e32 v41, v125, v47
	v_dot8c_i32_i4_e32 v42, v127, v49
	v_dot8c_i32_i4_e32 v43, v127, v47
	v_dot8c_i32_i4_e32 v44, v129, v49
	v_dot8c_i32_i4_e32 v45, v129, v47
	v_and_b32_e32 v78, 0xffff, v22
	v_lshrrev_b32_e32 v79, 16, v22
	v_lshl_add_u32 v78, v78, 7, v150
	v_lshl_add_u32 v79, v79, 7, v151
	s_mov_b32 m0, s98
	s_add_i32 s43, s98, 0x400
	global_load_lds_dwordx4 v78, s[50:51]
	s_mov_b32 m0, s43
	s_nop 0
	global_load_lds_dwordx4 v79, s[50:51]
	s_waitcnt vmcnt(8)
	v_add_u32_e32 v54, s76, v59
	v_add_u32_e32 v55, s76, v60
	v_add_u32_e32 v56, s76, v61
	v_add_u32_e32 v57, s76, v62
	ds_read_b64_tr_b4 v[46:47], v160
	ds_read_b64_tr_b4 v[48:49], v160 offset:1024
	ds_read_b64_tr_b4 v[122:123], v54
	ds_read_b64_tr_b4 v[124:125], v55
	ds_read_b64_tr_b4 v[126:127], v56
	ds_read_b64_tr_b4 v[128:129], v57
	s_waitcnt lgkmcnt(6)
	v_dot8c_i32_i4_e32 v38, v130, v52
	v_dot8c_i32_i4_e32 v39, v130, v50
	v_dot8c_i32_i4_e32 v40, v132, v52
	v_dot8c_i32_i4_e32 v41, v132, v50
	v_dot8c_i32_i4_e32 v42, v134, v52
	v_dot8c_i32_i4_e32 v43, v134, v50
	v_dot8c_i32_i4_e32 v44, v136, v52
	v_dot8c_i32_i4_e32 v45, v136, v50
	v_dot8c_i32_i4_e32 v38, v131, v53
	v_dot8c_i32_i4_e32 v39, v131, v51
	v_dot8c_i32_i4_e32 v40, v133, v53
	v_dot8c_i32_i4_e32 v41, v133, v51
	v_dot8c_i32_i4_e32 v42, v135, v53
	v_dot8c_i32_i4_e32 v43, v135, v51
	v_dot8c_i32_i4_e32 v44, v137, v53
	v_dot8c_i32_i4_e32 v45, v137, v51
	s_nop 3
	s_waitcnt lgkmcnt(15)
	v_lshlrev_b32_e32 v38, 5, v38
	v_lshlrev_b32_e32 v39, 1, v39
	v_add3_u32 v38, v39, v229, v38
	v_cvt_f32_i32_e32 v38, v38
	v_mul_f32_e32 v38, v228, v38
	v_lshlrev_b32_e32 v40, 5, v40
	v_lshlrev_b32_e32 v41, 1, v41
	v_add3_u32 v40, v41, v229, v40
	v_cvt_f32_i32_e32 v40, v40
	v_mul_f32_e32 v40, v228, v40
	v_lshlrev_b32_e32 v42, 5, v42
	v_lshlrev_b32_e32 v43, 1, v43
	v_add3_u32 v42, v43, v229, v42
	v_cvt_f32_i32_e32 v42, v42
	v_mul_f32_e32 v42, v228, v42
	v_lshlrev_b32_e32 v44, 5, v44
	v_lshlrev_b32_e32 v45, 1, v45
	v_add3_u32 v44, v45, v229, v44
	v_cvt_f32_i32_e32 v44, v44
	v_mul_f32_e32 v44, v228, v44
	v_cvt_pk_bf16_f32 v188, v38, v40
	v_cvt_pk_bf16_f32 v189, v42, v44
	ds_read_b128 v[252:255], v156
	s_add_i32 s44, s40, 0
	s_ashr_i32 s45, s44, 31
	s_lshl_b64 s[44:45], s[44:45], 12
	v_lshl_add_u64 v[80:81], v[36:37], 0, s[44:45]
	s_waitcnt lgkmcnt(0)
; #define LAS __attribute__((address_space(3)))
; __device__ __forceinline__ void peer_v_tokens(int j, const LAS unsigned short* EL, const LAS unsigned char* AL  , const LAS float* ASC  , const LAS int* SAL  , ...
;     ...
;         {
;             float4 v[4]; float ss = 0.f;
; #pragma unroll
;             for (int jq = 0; jq < 4; ++jq) { typedef unsigned u2v __attribute__((ext_vector_type(2))); const u2v pw = *(const LAS u2v*)(STASH + 4 * lane + 256 * jq); const uint2 hw = hv[jq];
;                 v[jq] = make_float4(__uint_as_float(hw.x << 16) + __uint_as_float(pw.x << 16), __uint_as_float(hw.x & 0xffff0000u) + __uint_as_float(pw.x & 0xffff0000u),
;                                     __uint_as_float(hw.y << 16) + __uint_as_float(pw.y << 16), __uint_as_float(hw.y & 0xffff0000u) + __uint_as_float(pw.y & 0xffff0000u));
;                 ss += v[jq].x * v[jq].x + v[jq].y * v[jq].y + v[jq].z * v[jq].z + v[jq].w * v[jq].w; }
;             ss = wave_sum(ss);
;             const float r3 = rsqrtf(ss * (1.f / D) + EPS);
;             float4* op = (float4*)(outp + (size_t)t * D) + lane;
; #pragma unroll
;             for (int jq = 0; jq < 4; ++jq) { typedef float f4v __attribute__((ext_vector_type(4))); f4v o4; o4.x = v[jq].x * r3 * gv[jq].x; o4.y = v[jq].y * r3 * gv[jq].y; o4.z = v[jq].z * r3 * gv[jq].z; o4.w = v[jq].w * r3 * gv[jq].w;
;                 __builtin_nontemporal_store(o4, (f4v*)op + 64 * jq); }
	v_mul_f32_e32 v218, v218, v252
	v_mul_f32_e32 v219, v219, v253
	v_mul_f32_e32 v220, v220, v254
	v_mul_f32_e32 v221, v221, v255
	global_store_dwordx4 v[80:81], v[218:221], off offset:2048 nt
	v_add_u32_e32 v147, 8, v140
	v_and_b32_e32 v146, 15, v147
	v_xor_b32_e32 v146, 8, v146
	v_bfe_u32 v148, v147, 4, 4
	v_mul_lo_u32 v146, v146, s92
	v_mul_lo_u32 v148, v148, s92
	v_mov_b32_e32 v147, v146
	v_mov_b32_e32 v149, v148
	ds_write2st64_b64 v77, v[146:147], v[148:149] offset1:2
	v_add_u32_e32 v138, 0xc00, v74
	ds_read_u8 v139, v138
	v_add_u32_e32 v141, 0xc00, v73
	ds_read_u8 v140, v141
	s_add_i32 s43, s67, 64
	v_mov_b32_e32 v138, s43
	ds_read2st64_b32 v[228:229], v138 offset1:1
	ds_read_b128 v[26:29], v227 offset:6144
	ds_read_b128 v[30:33], v227 offset:6160
	v_mov_b32_e32 v38, 0
	v_mov_b32_e32 v39, 0
	v_mov_b32_e32 v40, 0
	v_mov_b32_e32 v41, 0
	v_mov_b32_e32 v42, 0
	v_mov_b32_e32 v43, 0
	v_mov_b32_e32 v44, 0
	v_mov_b32_e32 v45, 0
	v_and_b32_e32 v78, 0xffff, v23
	v_lshrrev_b32_e32 v79, 16, v23
	v_lshl_add_u32 v78, v78, 7, v150
	v_lshl_add_u32 v79, v79, 7, v151
	s_mov_b32 m0, s99
	s_add_i32 s43, s99, 0x400
	global_load_lds_dwordx4 v78, s[50:51]
	s_mov_b32 m0, s43
	s_nop 0
	global_load_lds_dwordx4 v79, s[50:51]
	s_waitcnt vmcnt(9)
	v_add_u32_e32 v54, s77, v59
	v_add_u32_e32 v55, s77, v60
	v_add_u32_e32 v56, s77, v61
	v_add_u32_e32 v57, s77, v62
	ds_read_b64_tr_b4 v[50:51], v160 offset:128
	ds_read_b64_tr_b4 v[52:53], v160 offset:1152
	ds_read_b64_tr_b4 v[130:131], v54
	ds_read_b64_tr_b4 v[132:133], v55
	ds_read_b64_tr_b4 v[134:135], v56
	ds_read_b64_tr_b4 v[136:137], v57
	s_waitcnt lgkmcnt(13)
	s_waitcnt vmcnt(36) lgkmcnt(15)
	v_lshlrev_b32_e32 v236, 16, v194
	v_and_b32_e32 v237, 0xffff0000, v194
	v_lshlrev_b32_e32 v142, 16, v202
	v_and_b32_e32 v143, 0xffff0000, v202
	v_add_f32_e32 v236, v236, v142
	v_add_f32_e32 v237, v237, v143
	v_lshlrev_b32_e32 v238, 16, v195
	v_and_b32_e32 v239, 0xffff0000, v195
	v_lshlrev_b32_e32 v142, 16, v203
	v_and_b32_e32 v143, 0xffff0000, v203
	v_add_f32_e32 v238, v238, v142
	v_add_f32_e32 v239, v239, v143
	v_lshlrev_b32_e32 v240, 16, v196
	v_and_b32_e32 v241, 0xffff0000, v196
	v_lshlrev_b32_e32 v142, 16, v204
	v_and_b32_e32 v143, 0xffff0000, v204
	v_add_f32_e32 v240, v240, v142
	v_add_f32_e32 v241, v241, v143
	v_lshlrev_b32_e32 v242, 16, v197
	v_and_b32_e32 v243, 0xffff0000, v197
	v_lshlrev_b32_e32 v142, 16, v205
	v_and_b32_e32 v143, 0xffff0000, v205
	v_add_f32_e32 v242, v242, v142
	v_add_f32_e32 v243, v243, v143
	v_lshlrev_b32_e32 v244, 16, v198
	v_and_b32_e32 v245, 0xffff0000, v198
	v_lshlrev_b32_e32 v142, 16, v206
	v_and_b32_e32 v143, 0xffff0000, v206
	v_add_f32_e32 v244, v244, v142
	v_add_f32_e32 v245, v245, v143
	v_lshlrev_b32_e32 v246, 16, v199
	v_and_b32_e32 v247, 0xffff0000, v199
	v_lshlrev_b32_e32 v142, 16, v207
	v_and_b32_e32 v143, 0xffff0000, v207
	v_add_f32_e32 v246, v246, v142
	v_add_f32_e32 v247, v247, v143
	v_lshlrev_b32_e32 v248, 16, v200
	v_and_b32_e32 v249, 0xffff0000, v200
	v_lshlrev_b32_e32 v142, 16, v208
	v_and_b32_e32 v143, 0xffff0000, v208
	v_add_f32_e32 v248, v248, v142
	v_add_f32_e32 v249, v249, v143
	v_lshlrev_b32_e32 v250, 16, v201
	v_and_b32_e32 v251, 0xffff0000, v201
	v_lshlrev_b32_e32 v142, 16, v209
	v_and_b32_e32 v143, 0xffff0000, v209
	v_add_f32_e32 v250, v250, v142
	v_add_f32_e32 v251, v251, v143
	v_mov_b32_e32 v144, 0
	v_mul_f32_e32 v145, v236, v236
	v_fmac_f32_e32 v145, v237, v237
	v_fmac_f32_e32 v145, v238, v238
	v_fmac_f32_e32 v145, v239, v239
	v_add_f32_e32 v144, v144, v145
	v_mul_f32_e32 v145, v240, v240
	v_fmac_f32_e32 v145, v241, v241
	v_fmac_f32_e32 v145, v242, v242
	v_fmac_f32_e32 v145, v243, v243
	v_add_f32_e32 v144, v144, v145
	v_mul_f32_e32 v145, v244, v244
	v_fmac_f32_e32 v145, v245, v245
	v_fmac_f32_e32 v145, v246, v246
	v_fmac_f32_e32 v145, v247, v247
	v_add_f32_e32 v144, v144, v145
	v_mul_f32_e32 v145, v248, v248
	v_fmac_f32_e32 v145, v249, v249
	v_fmac_f32_e32 v145, v250, v250
	v_fmac_f32_e32 v145, v251, v251
	v_add_f32_e32 v144, v144, v145
	s_nop 1
	v_add_f32_dpp v144, v144, v144 quad_perm:[1,0,3,2] row_mask:0xf bank_mask:0xf bound_ctrl:1
	s_nop 1
	v_add_f32_dpp v144, v144, v144 quad_perm:[2,3,0,1] row_mask:0xf bank_mask:0xf bound_ctrl:1
	s_nop 1
	v_add_f32_dpp v144, v144, v144 row_half_mirror row_mask:0xf bank_mask:0xf bound_ctrl:1
	s_nop 1
	v_add_f32_dpp v144, v144, v144 row_mirror row_mask:0xf bank_mask:0xf bound_ctrl:1
	s_nop 1
	v_readlane_b32 s10, v144, 0
	v_readlane_b32 s11, v144, 16
	v_readlane_b32 s14, v144, 32
	v_readlane_b32 s15, v144, 48
	s_nop 3
	v_mov_b32_e32 v144, s11
	v_mov_b32_e32 v145, s15
	v_add_f32_e32 v144, s10, v144
	v_add_f32_e32 v145, s14, v145
	v_add_f32_e32 v144, v144, v145
	v_fmamk_f32 v144, v144, 0x3a800000, v111
	v_rsq_f32_e32 v144, v144
	s_nop 0
	v_mul_f32_e32 v236, v236, v144
	v_mul_f32_e32 v237, v237, v144
	v_mul_f32_e32 v238, v238, v144
	v_mul_f32_e32 v239, v239, v144
	v_mul_f32_e32 v240, v240, v144
	v_mul_f32_e32 v241, v241, v144
	v_mul_f32_e32 v242, v242, v144
	v_mul_f32_e32 v243, v243, v144
	v_mul_f32_e32 v244, v244, v144
	v_mul_f32_e32 v245, v245, v144
	v_mul_f32_e32 v246, v246, v144
	v_mul_f32_e32 v247, v247, v144
	v_mul_f32_e32 v248, v248, v144
	v_mul_f32_e32 v249, v249, v144
	v_mul_f32_e32 v250, v250, v144
	v_mul_f32_e32 v251, v251, v144
	v_dot8c_i32_i4_e32 v38, v122, v48
	v_dot8c_i32_i4_e32 v39, v122, v46
	v_dot8c_i32_i4_e32 v40, v124, v48
	v_dot8c_i32_i4_e32 v41, v124, v46
	v_dot8c_i32_i4_e32 v42, v126, v48
	v_dot8c_i32_i4_e32 v43, v126, v46
	v_dot8c_i32_i4_e32 v44, v128, v48
	v_dot8c_i32_i4_e32 v45, v128, v46
	v_dot8c_i32_i4_e32 v38, v123, v49
	v_dot8c_i32_i4_e32 v39, v123, v47
	v_dot8c_i32_i4_e32 v40, v125, v49
	v_dot8c_i32_i4_e32 v41, v125, v47
	v_dot8c_i32_i4_e32 v42, v127, v49
	v_dot8c_i32_i4_e32 v43, v127, v47
	v_dot8c_i32_i4_e32 v44, v129, v49
	v_dot8c_i32_i4_e32 v45, v129, v47
	v_and_b32_e32 v78, 0xffff, v24
	v_lshrrev_b32_e32 v79, 16, v24
	v_lshl_add_u32 v78, v78, 7, v150
	v_lshl_add_u32 v79, v79, 7, v151
	s_mov_b32 m0, s76
	s_add_i32 s43, s76, 0x400
	global_load_lds_dwordx4 v78, s[50:51]
	s_mov_b32 m0, s43
	s_nop 0
	global_load_lds_dwordx4 v79, s[50:51]
	s_waitcnt vmcnt(9)
; #define TR4(p_) __builtin_amdgcn_ds_read_tr4_b64_v2i32((LAS v2i*)(p_))
; #define VDMA(st_, k_) do { _Pragma("unroll") for (int i_ = 0; i_ < 4; ++i_) { \
;         const unsigned off_ = (unsigned)((st_) >> 2) * (16384u * 128u) + (PE_ID(E, 4 * ((st_) & 3) + i_) << 7) + ((i_ & 1) ? cx1 : cx0); \
;         __builtin_amdgcn_global_load_lds((const unsigned*)(V4 + off_), (LAS unsigned*)(ldsb + BUF[k_] + 1024 * i_), 16, 0, 0); } } while (0)
; __device__ __forceinline__ void peer_v_tokens(int j, const LAS unsigned short* EL, const LAS unsigned char* AL  , const LAS float* ASC  , const LAS int* SAL  , ...
;     ...
; #pragma unroll
;         for (int st = 0; st < 16; ++st) {
;             const int p = st >> 2, q = st & 3;
;             if (st < 14) VDMA(st + 2, (st + 2) % 3);
;             if (st < 14) asm volatile("s_waitcnt vmcnt(8)" ::: "memory");
;             else if (st == 14) asm volatile("s_waitcnt vmcnt(4)" ::: "memory");
;             else asm volatile("s_waitcnt vmcnt(0)" ::: "memory");
;             if (q == 0) {
; #pragma unroll
;                 for (int r = 0; r < 4; ++r) { accH[r] = 0; accL[r] = 0; } }
; #pragma unroll
;             for (int tp = 0; tp < 2; ++tp) {
;                 const v2i ao = TR4(ATL + (2 * q + tp) * 128 + 8 * s16), ah = TR4(ATL + 1024 + (2 * q + tp) * 128 + 8 * s16);
; #pragma unroll
;                 for (int r = 0; r < 4; ++r) {
;                     const v2i d = TR4(ldsb + BUF[st % 3] + 2048 * tp + roff[r]);
;                     accH[r] = __builtin_amdgcn_sdot8(d.x, ah.x, accH[r], false); accH[r] = __builtin_amdgcn_sdot8(d.y, ah.y, accH[r], false);
;                     accL[r] = __builtin_amdgcn_sdot8(d.x, ao.x, accL[r], false); accL[r] = __builtin_amdgcn_sdot8(d.y, ao.y, accL[r], false);
;                 }
	v_add_u32_e32 v54, s78, v59
	v_add_u32_e32 v55, s78, v60
	v_add_u32_e32 v56, s78, v61
	v_add_u32_e32 v57, s78, v62
	ds_read_b64_tr_b4 v[46:47], v160 offset:256
	ds_read_b64_tr_b4 v[48:49], v160 offset:1280
	ds_read_b64_tr_b4 v[122:123], v54
	ds_read_b64_tr_b4 v[124:125], v55
	ds_read_b64_tr_b4 v[126:127], v56
	ds_read_b64_tr_b4 v[128:129], v57
	s_waitcnt lgkmcnt(6)
	v_dot8c_i32_i4_e32 v38, v130, v52
	v_dot8c_i32_i4_e32 v39, v130, v50
	v_dot8c_i32_i4_e32 v40, v132, v52
	v_dot8c_i32_i4_e32 v41, v132, v50
	v_dot8c_i32_i4_e32 v42, v134, v52
	v_dot8c_i32_i4_e32 v43, v134, v50
	v_dot8c_i32_i4_e32 v44, v136, v52
	v_dot8c_i32_i4_e32 v45, v136, v50
	v_dot8c_i32_i4_e32 v38, v131, v53
	v_dot8c_i32_i4_e32 v39, v131, v51
	v_dot8c_i32_i4_e32 v40, v133, v53
	v_dot8c_i32_i4_e32 v41, v133, v51
	v_dot8c_i32_i4_e32 v42, v135, v53
	v_dot8c_i32_i4_e32 v43, v135, v51
	v_dot8c_i32_i4_e32 v44, v137, v53
	v_dot8c_i32_i4_e32 v45, v137, v51
	v_and_b32_e32 v78, 0xffff, v25
	v_lshrrev_b32_e32 v79, 16, v25
	v_lshl_add_u32 v78, v78, 7, v150
	v_lshl_add_u32 v79, v79, 7, v151
	s_mov_b32 m0, s77
	s_add_i32 s43, s77, 0x400
	global_load_lds_dwordx4 v78, s[50:51]
	s_mov_b32 m0, s43
	s_nop 0
	global_load_lds_dwordx4 v79, s[50:51]
	s_waitcnt vmcnt(9)
	v_add_u32_e32 v54, s79, v59
	v_add_u32_e32 v55, s79, v60
	v_add_u32_e32 v56, s79, v61
	v_add_u32_e32 v57, s79, v62
	ds_read_b64_tr_b4 v[50:51], v160 offset:384
	ds_read_b64_tr_b4 v[52:53], v160 offset:1408
	ds_read_b64_tr_b4 v[130:131], v54
	ds_read_b64_tr_b4 v[132:133], v55
	ds_read_b64_tr_b4 v[134:135], v56
	ds_read_b64_tr_b4 v[136:137], v57
	s_waitcnt lgkmcnt(6)
	v_dot8c_i32_i4_e32 v38, v122, v48
	v_dot8c_i32_i4_e32 v39, v122, v46
	v_dot8c_i32_i4_e32 v40, v124, v48
	v_dot8c_i32_i4_e32 v41, v124, v46
	v_dot8c_i32_i4_e32 v42, v126, v48
	v_dot8c_i32_i4_e32 v43, v126, v46
	v_dot8c_i32_i4_e32 v44, v128, v48
	v_dot8c_i32_i4_e32 v45, v128, v46
	v_dot8c_i32_i4_e32 v38, v123, v49
	v_dot8c_i32_i4_e32 v39, v123, v47
	v_dot8c_i32_i4_e32 v40, v125, v49
	v_dot8c_i32_i4_e32 v41, v125, v47
	v_dot8c_i32_i4_e32 v42, v127, v49
	v_dot8c_i32_i4_e32 v43, v127, v47
	v_dot8c_i32_i4_e32 v44, v129, v49
	v_dot8c_i32_i4_e32 v45, v129, v47
	s_waitcnt lgkmcnt(15)
	v_and_b32_e32 v78, 0xffff, v26
	v_lshrrev_b32_e32 v79, 16, v26
	v_lshl_add_u32 v78, v78, 7, v150
	v_lshl_add_u32 v79, v79, 7, v151
	s_mov_b32 m0, s78
	s_add_i32 s43, s78, 0x400
	global_load_lds_dwordx4 v78, s[50:51]
	s_mov_b32 m0, s43
	s_nop 0
	global_load_lds_dwordx4 v79, s[50:51]
	s_waitcnt vmcnt(9)
	v_add_u32_e32 v54, s98, v59
	v_add_u32_e32 v55, s98, v60
	v_add_u32_e32 v56, s98, v61
	v_add_u32_e32 v57, s98, v62
	ds_read_b64_tr_b4 v[46:47], v160 offset:512
	ds_read_b64_tr_b4 v[48:49], v160 offset:1536
	ds_read_b64_tr_b4 v[122:123], v54
	ds_read_b64_tr_b4 v[124:125], v55
	ds_read_b64_tr_b4 v[126:127], v56
	ds_read_b64_tr_b4 v[128:129], v57
	s_waitcnt lgkmcnt(6)
	v_dot8c_i32_i4_e32 v38, v130, v52
	v_dot8c_i32_i4_e32 v39, v130, v50
	v_dot8c_i32_i4_e32 v40, v132, v52
	v_dot8c_i32_i4_e32 v41, v132, v50
	v_dot8c_i32_i4_e32 v42, v134, v52
	v_dot8c_i32_i4_e32 v43, v134, v50
	v_dot8c_i32_i4_e32 v44, v136, v52
	v_dot8c_i32_i4_e32 v45, v136, v50
	v_dot8c_i32_i4_e32 v38, v131, v53
	v_dot8c_i32_i4_e32 v39, v131, v51
	v_dot8c_i32_i4_e32 v40, v133, v53
	v_dot8c_i32_i4_e32 v41, v133, v51
	v_dot8c_i32_i4_e32 v42, v135, v53
	v_dot8c_i32_i4_e32 v43, v135, v51
	v_dot8c_i32_i4_e32 v44, v137, v53
	v_dot8c_i32_i4_e32 v45, v137, v51
	v_and_b32_e32 v78, 0xffff, v27
	v_lshrrev_b32_e32 v79, 16, v27
	v_lshl_add_u32 v78, v78, 7, v150
	v_lshl_add_u32 v79, v79, 7, v151
	s_mov_b32 m0, s79
	s_add_i32 s43, s79, 0x400
	global_load_lds_dwordx4 v78, s[50:51]
	s_mov_b32 m0, s43
	s_nop 0
	global_load_lds_dwordx4 v79, s[50:51]
	s_waitcnt vmcnt(8)
	v_add_u32_e32 v54, s99, v59
	v_add_u32_e32 v55, s99, v60
	v_add_u32_e32 v56, s99, v61
	v_add_u32_e32 v57, s99, v62
	ds_read_b64_tr_b4 v[50:51], v160 offset:640
	ds_read_b64_tr_b4 v[52:53], v160 offset:1664
	ds_read_b64_tr_b4 v[130:131], v54
	ds_read_b64_tr_b4 v[132:133], v55
	ds_read_b64_tr_b4 v[134:135], v56
	ds_read_b64_tr_b4 v[136:137], v57
	s_waitcnt lgkmcnt(6)
	v_dot8c_i32_i4_e32 v38, v122, v48
	v_dot8c_i32_i4_e32 v39, v122, v46
	v_dot8c_i32_i4_e32 v40, v124, v48
	v_dot8c_i32_i4_e32 v41, v124, v46
	v_dot8c_i32_i4_e32 v42, v126, v48
	v_dot8c_i32_i4_e32 v43, v126, v46
	v_dot8c_i32_i4_e32 v44, v128, v48
	v_dot8c_i32_i4_e32 v45, v128, v46
	v_dot8c_i32_i4_e32 v38, v123, v49
	v_dot8c_i32_i4_e32 v39, v123, v47
	v_dot8c_i32_i4_e32 v40, v125, v49
	v_dot8c_i32_i4_e32 v41, v125, v47
	v_dot8c_i32_i4_e32 v42, v127, v49
	v_dot8c_i32_i4_e32 v43, v127, v47
	v_dot8c_i32_i4_e32 v44, v129, v49
	v_dot8c_i32_i4_e32 v45, v129, v47
	s_waitcnt lgkmcnt(15)
	v_add_u32_e32 v143, 8, v139
	v_and_b32_e32 v142, 15, v143
	v_xor_b32_e32 v142, 8, v142
	v_bfe_u32 v144, v143, 4, 4
	v_mul_lo_u32 v142, v142, s92
	v_mul_lo_u32 v144, v144, s92
	v_mov_b32_e32 v143, v142
	v_mov_b32_e32 v145, v144
	ds_write2st64_b64 v159, v[142:143], v[144:145] offset1:2
	v_and_b32_e32 v78, 0xffff, v28
	v_lshrrev_b32_e32 v79, 16, v28
	v_lshl_add_u32 v78, v78, 7, v150
	v_lshl_add_u32 v79, v79, 7, v151
	s_mov_b32 m0, s98
	s_add_i32 s43, s98, 0x400
	global_load_lds_dwordx4 v78, s[50:51]
	s_mov_b32 m0, s43
	s_nop 0
	global_load_lds_dwordx4 v79, s[50:51]
	s_waitcnt vmcnt(8)
	v_add_u32_e32 v54, s76, v59
	v_add_u32_e32 v55, s76, v60
	v_add_u32_e32 v56, s76, v61
	v_add_u32_e32 v57, s76, v62
	ds_read_b64_tr_b4 v[46:47], v160 offset:768
	ds_read_b64_tr_b4 v[48:49], v160 offset:1792
	ds_read_b64_tr_b4 v[122:123], v54
	ds_read_b64_tr_b4 v[124:125], v55
	ds_read_b64_tr_b4 v[126:127], v56
	ds_read_b64_tr_b4 v[128:129], v57
	s_waitcnt lgkmcnt(7)
; __device__ __forceinline__ void peer_v_tokens(int j, const LAS unsigned short* EL, const LAS unsigned char* AL  , const LAS float* ASC  , const LAS int* SAL  , ...
;     ...
;         { const LAS v4u* ep = (const LAS v4u*)(EL + tl * 128 + 16 * g); const v4u e0 = ep[0], e1 = ep[1];
;           E[0] = e0.x; E[1] = e0.y; E[2] = e0.z; E[3] = e0.w; E[4] = e1.x; E[5] = e1.y; E[6] = e1.z; E[7] = e1.w; }
;         uint2 hv[4]; float4 gv[4];
;         { unsigned ho = (unsigned)t * (D / 4) + (unsigned)lane; asm volatile("" : "+v"(ho)); const uint2* hp = (const uint2*)HB + ho; const float4* gp = (const float4*)fng + lane;
; #pragma unroll
;           for (int jq = 0; jq < 4; ++jq) { hv[jq] = hp[64 * jq]; gv[jq] = gp[64 * jq]; } }
;         VDMA(0, 0); VDMA(1, 1);
; #pragma unroll
;         for (int m = 0; m < 2; ++m) {
;             const int idx = lane + 64 * m, tau = idx >> 4, sr = idx & 15, k = 16 * (sr & 7) + 2 * tau + (sr >> 3);
;             const int aq = (int)*(const LAS signed char*)(AL + tl * 128 + k); const int tq = aq + 8;
;             const unsigned lo = (((unsigned)tq & 15u) ^ 8u) * 0x11111111u, hi = ((unsigned)(tq >> 4) & 15u) * 0x11111111u;
;             typedef unsigned u2v __attribute__((ext_vector_type(2)));
;             u2v l2; l2.x = lo; l2.y = lo; u2v h2; h2.x = hi; h2.y = hi;
;             *(LAS u2v*)(ATL + 8 * idx) = l2; *(LAS u2v*)(ATL + 1024 + 8 * idx) = h2;
;         }
;         const float asc = ASC[tl]; const int sa = SAL[tl];
;         CFENCE();
;         int accH[4], accL[4];
; #pragma unroll
;         for (int st = 0; st < 16; ++st) {
;             const int p = st >> 2, q = st & 3;
;             if (st < 14) VDMA(st + 2, (st + 2) % 3);
;             if (st < 14) asm volatile("s_waitcnt vmcnt(8)" ::: "memory");
;             else if (st == 14) asm volatile("s_waitcnt vmcnt(4)" ::: "memory");
;             else asm volatile("s_waitcnt vmcnt(0)" ::: "memory");
;             if (q == 0) {
; #pragma unroll
;                 for (int r = 0; r < 4; ++r) { accH[r] = 0; accL[r] = 0; } }
; #pragma unroll
;             for (int tp = 0; tp < 2; ++tp) {
;                 const v2i ao = TR4(ATL + (2 * q + tp) * 128 + 8 * s16), ah = TR4(ATL + 1024 + (2 * q + tp) * 128 + 8 * s16);
; #pragma unroll
;                 for (int r = 0; r < 4; ++r) {
;                     const v2i d = TR4(ldsb + BUF[st % 3] + 2048 * tp + roff[r]);
	v_dot8c_i32_i4_e32 v38, v130, v52
	v_dot8c_i32_i4_e32 v39, v130, v50
	v_dot8c_i32_i4_e32 v40, v132, v52
	v_dot8c_i32_i4_e32 v41, v132, v50
	v_dot8c_i32_i4_e32 v42, v134, v52
	v_dot8c_i32_i4_e32 v43, v134, v50
	v_dot8c_i32_i4_e32 v44, v136, v52
	v_dot8c_i32_i4_e32 v45, v136, v50
	v_dot8c_i32_i4_e32 v38, v131, v53
	v_dot8c_i32_i4_e32 v39, v131, v51
	v_dot8c_i32_i4_e32 v40, v133, v53
	v_dot8c_i32_i4_e32 v41, v133, v51
	v_dot8c_i32_i4_e32 v42, v135, v53
	v_dot8c_i32_i4_e32 v43, v135, v51
	v_dot8c_i32_i4_e32 v44, v137, v53
	v_dot8c_i32_i4_e32 v45, v137, v51
	v_and_b32_e32 v78, 0xffff, v29
	v_lshrrev_b32_e32 v79, 16, v29
	v_lshl_add_u32 v78, v78, 7, v150
	v_lshl_add_u32 v79, v79, 7, v151
	s_mov_b32 m0, s99
	s_add_i32 s43, s99, 0x400
	global_load_lds_dwordx4 v78, s[50:51]
	s_mov_b32 m0, s43
	s_nop 0
	global_load_lds_dwordx4 v79, s[50:51]
	s_waitcnt vmcnt(8)
	v_add_u32_e32 v54, s77, v59
	v_add_u32_e32 v55, s77, v60
	v_add_u32_e32 v56, s77, v61
	v_add_u32_e32 v57, s77, v62
	ds_read_b64_tr_b4 v[50:51], v160 offset:896
	ds_read_b64_tr_b4 v[52:53], v160 offset:1920
	ds_read_b64_tr_b4 v[130:131], v54
	ds_read_b64_tr_b4 v[132:133], v55
	ds_read_b64_tr_b4 v[134:135], v56
	ds_read_b64_tr_b4 v[136:137], v57
	s_waitcnt lgkmcnt(6)
	v_dot8c_i32_i4_e32 v38, v122, v48
	v_dot8c_i32_i4_e32 v39, v122, v46
	v_dot8c_i32_i4_e32 v40, v124, v48
	v_dot8c_i32_i4_e32 v41, v124, v46
	v_dot8c_i32_i4_e32 v42, v126, v48
	v_dot8c_i32_i4_e32 v43, v126, v46
	v_dot8c_i32_i4_e32 v44, v128, v48
	v_dot8c_i32_i4_e32 v45, v128, v46
	v_dot8c_i32_i4_e32 v38, v123, v49
	v_dot8c_i32_i4_e32 v39, v123, v47
	v_dot8c_i32_i4_e32 v40, v125, v49
	v_dot8c_i32_i4_e32 v41, v125, v47
	v_dot8c_i32_i4_e32 v42, v127, v49
	v_dot8c_i32_i4_e32 v43, v127, v47
	v_dot8c_i32_i4_e32 v44, v129, v49
	v_dot8c_i32_i4_e32 v45, v129, v47
	v_and_b32_e32 v78, 0xffff, v30
	v_lshrrev_b32_e32 v79, 16, v30
	v_lshl_add_u32 v78, v78, 7, v150
	v_lshl_add_u32 v79, v79, 7, v151
	s_mov_b32 m0, s76
	s_add_i32 s43, s76, 0x400
	global_load_lds_dwordx4 v78, s[50:51]
	s_mov_b32 m0, s43
	s_nop 0
	global_load_lds_dwordx4 v79, s[50:51]
	s_waitcnt vmcnt(8)
	v_add_u32_e32 v54, s78, v59
	v_add_u32_e32 v55, s78, v60
	v_add_u32_e32 v56, s78, v61
	v_add_u32_e32 v57, s78, v62
	ds_read_b64_tr_b4 v[46:47], v160
	ds_read_b64_tr_b4 v[48:49], v160 offset:1024
	ds_read_b64_tr_b4 v[122:123], v54
	ds_read_b64_tr_b4 v[124:125], v55
	ds_read_b64_tr_b4 v[126:127], v56
	ds_read_b64_tr_b4 v[128:129], v57
	s_waitcnt lgkmcnt(6)
	v_dot8c_i32_i4_e32 v38, v130, v52
	v_dot8c_i32_i4_e32 v39, v130, v50
	v_dot8c_i32_i4_e32 v40, v132, v52
	v_dot8c_i32_i4_e32 v41, v132, v50
	v_dot8c_i32_i4_e32 v42, v134, v52
	v_dot8c_i32_i4_e32 v43, v134, v50
	v_dot8c_i32_i4_e32 v44, v136, v52
	v_dot8c_i32_i4_e32 v45, v136, v50
	v_dot8c_i32_i4_e32 v38, v131, v53
	v_dot8c_i32_i4_e32 v39, v131, v51
	v_dot8c_i32_i4_e32 v40, v133, v53
	v_dot8c_i32_i4_e32 v41, v133, v51
	v_dot8c_i32_i4_e32 v42, v135, v53
	v_dot8c_i32_i4_e32 v43, v135, v51
	v_dot8c_i32_i4_e32 v44, v137, v53
	v_dot8c_i32_i4_e32 v45, v137, v51
	s_nop 3
	s_waitcnt lgkmcnt(15)
	v_lshlrev_b32_e32 v38, 5, v38
	v_lshlrev_b32_e32 v39, 1, v39
	v_add3_u32 v38, v39, v229, v38
	v_cvt_f32_i32_e32 v38, v38
	v_mul_f32_e32 v38, v228, v38
	v_lshlrev_b32_e32 v40, 5, v40
	v_lshlrev_b32_e32 v41, 1, v41
	v_add3_u32 v40, v41, v229, v40
	v_cvt_f32_i32_e32 v40, v40
	v_mul_f32_e32 v40, v228, v40
	v_lshlrev_b32_e32 v42, 5, v42
	v_lshlrev_b32_e32 v43, 1, v43
	v_add3_u32 v42, v43, v229, v42
	v_cvt_f32_i32_e32 v42, v42
	v_mul_f32_e32 v42, v228, v42
	v_lshlrev_b32_e32 v44, 5, v44
	v_lshlrev_b32_e32 v45, 1, v45
	v_add3_u32 v44, v45, v229, v44
	v_cvt_f32_i32_e32 v44, v44
	v_mul_f32_e32 v44, v228, v44
	v_cvt_pk_bf16_f32 v182, v38, v40
	v_cvt_pk_bf16_f32 v183, v42, v44
	ds_read_b128 v[252:255], v156 offset:1024
	s_add_i32 s44, s40, 0
	s_ashr_i32 s45, s44, 31
	s_lshl_b64 s[44:45], s[44:45], 12
	v_lshl_add_u64 v[80:81], v[36:37], 0, s[44:45]
	s_waitcnt lgkmcnt(0)
	v_mul_f32_e32 v222, v222, v252
	v_mul_f32_e32 v223, v223, v253
	v_mul_f32_e32 v224, v224, v254
	v_mul_f32_e32 v225, v225, v255
	global_store_dwordx4 v[80:81], v[222:225], off offset:3072 nt
	ds_read_b128 v[252:255], v155
	s_add_i32 s44, s40, 8
	s_ashr_i32 s45, s44, 31
	s_lshl_b64 s[44:45], s[44:45], 12
	v_lshl_add_u64 v[80:81], v[36:37], 0, s[44:45]
	s_waitcnt lgkmcnt(0)
	v_mul_f32_e32 v236, v236, v252
	v_mul_f32_e32 v237, v237, v253
	v_mul_f32_e32 v238, v238, v254
	v_mul_f32_e32 v239, v239, v255
	global_store_dwordx4 v[80:81], v[236:239], off nt
	v_add_u32_e32 v147, 8, v140
	v_and_b32_e32 v146, 15, v147
	v_xor_b32_e32 v146, 8, v146
	v_bfe_u32 v148, v147, 4, 4
	v_mul_lo_u32 v146, v146, s92
	v_mul_lo_u32 v148, v148, s92
	v_mov_b32_e32 v147, v146
	v_mov_b32_e32 v149, v148
	ds_write2st64_b64 v77, v[146:147], v[148:149] offset1:2
	v_add_u32_e32 v138, 0x800, v74
	ds_read_u8 v139, v138
	v_add_u32_e32 v141, 0x800, v73
	ds_read_u8 v140, v141
	s_add_i32 s43, s67, 96
	v_mov_b32_e32 v138, s43
	ds_read2st64_b32 v[228:229], v138 offset1:1
	ds_read_b128 v[18:21], v227 offset:4096
	ds_read_b128 v[22:25], v227 offset:4112
	v_add_u32_e32 v152, 0x600000, v63
	v_add_u32_e32 v153, 0x600000, v64
	v_mov_b32_e32 v38, 0
	v_mov_b32_e32 v39, 0
	v_mov_b32_e32 v40, 0
	v_mov_b32_e32 v41, 0
	v_mov_b32_e32 v42, 0
	v_mov_b32_e32 v43, 0
	v_mov_b32_e32 v44, 0
	v_mov_b32_e32 v45, 0
	v_and_b32_e32 v78, 0xffff, v31
	v_lshrrev_b32_e32 v79, 16, v31
	v_lshl_add_u32 v78, v78, 7, v150
	v_lshl_add_u32 v79, v79, 7, v151
	s_mov_b32 m0, s77
	s_add_i32 s43, s77, 0x400
	global_load_lds_dwordx4 v78, s[50:51]
	s_mov_b32 m0, s43
	s_nop 0
	global_load_lds_dwordx4 v79, s[50:51]
	s_waitcnt vmcnt(10)
; #define TR4(p_) __builtin_amdgcn_ds_read_tr4_b64_v2i32((LAS v2i*)(p_))
; #define VDMA(st_, k_) do { _Pragma("unroll") for (int i_ = 0; i_ < 4; ++i_) { \
;         const unsigned off_ = (unsigned)((st_) >> 2) * (16384u * 128u) + (PE_ID(E, 4 * ((st_) & 3) + i_) << 7) + ((i_ & 1) ? cx1 : cx0); \
;         __builtin_amdgcn_global_load_lds((const unsigned*)(V4 + off_), (LAS unsigned*)(ldsb + BUF[k_] + 1024 * i_), 16, 0, 0); } } while (0)
; __device__ __forceinline__ void peer_v_tokens(int j, const LAS unsigned short* EL, const LAS unsigned char* AL  , const LAS float* ASC  , const LAS int* SAL  , ...
;     ...
; #pragma unroll
;         for (int st = 0; st < 16; ++st) {
;             const int p = st >> 2, q = st & 3;
;             if (st < 14) VDMA(st + 2, (st + 2) % 3);
;             if (st < 14) asm volatile("s_waitcnt vmcnt(8)" ::: "memory");
;             else if (st == 14) asm volatile("s_waitcnt vmcnt(4)" ::: "memory");
;             else asm volatile("s_waitcnt vmcnt(0)" ::: "memory");
;             if (q == 0) {
; #pragma unroll
;                 for (int r = 0; r < 4; ++r) { accH[r] = 0; accL[r] = 0; } }
; #pragma unroll
;             for (int tp = 0; tp < 2; ++tp) {
;                 const v2i ao = TR4(ATL + (2 * q + tp) * 128 + 8 * s16), ah = TR4(ATL + 1024 + (2 * q + tp) * 128 + 8 * s16);
; #pragma unroll
;                 for (int r = 0; r < 4; ++r) {
;                     const v2i d = TR4(ldsb + BUF[st % 3] + 2048 * tp + roff[r]);
;                     accH[r] = __builtin_amdgcn_sdot8(d.x, ah.x, accH[r], false); accH[r] = __builtin_amdgcn_sdot8(d.y, ah.y, accH[r], false);
;                     accL[r] = __builtin_amdgcn_sdot8(d.x, ao.x, accL[r], false); accL[r] = __builtin_amdgcn_sdot8(d.y, ao.y, accL[r], false);
;                 }
	v_add_u32_e32 v54, s79, v59
	v_add_u32_e32 v55, s79, v60
	v_add_u32_e32 v56, s79, v61
	v_add_u32_e32 v57, s79, v62
	ds_read_b64_tr_b4 v[50:51], v160 offset:128
	ds_read_b64_tr_b4 v[52:53], v160 offset:1152
	ds_read_b64_tr_b4 v[130:131], v54
	ds_read_b64_tr_b4 v[132:133], v55
	ds_read_b64_tr_b4 v[134:135], v56
	ds_read_b64_tr_b4 v[136:137], v57
	s_waitcnt lgkmcnt(14)
	v_dot8c_i32_i4_e32 v38, v122, v48
	v_dot8c_i32_i4_e32 v39, v122, v46
	v_dot8c_i32_i4_e32 v40, v124, v48
	v_dot8c_i32_i4_e32 v41, v124, v46
	v_dot8c_i32_i4_e32 v42, v126, v48
	v_dot8c_i32_i4_e32 v43, v126, v46
	v_dot8c_i32_i4_e32 v44, v128, v48
	v_dot8c_i32_i4_e32 v45, v128, v46
	v_dot8c_i32_i4_e32 v38, v123, v49
	v_dot8c_i32_i4_e32 v39, v123, v47
	v_dot8c_i32_i4_e32 v40, v125, v49
	v_dot8c_i32_i4_e32 v41, v125, v47
	v_dot8c_i32_i4_e32 v42, v127, v49
	v_dot8c_i32_i4_e32 v43, v127, v47
	v_dot8c_i32_i4_e32 v44, v129, v49
	v_dot8c_i32_i4_e32 v45, v129, v47
	v_and_b32_e32 v78, 0xffff, v32
	v_lshrrev_b32_e32 v79, 16, v32
	v_lshl_add_u32 v78, v78, 7, v150
	v_lshl_add_u32 v79, v79, 7, v151
	s_mov_b32 m0, s78
	s_add_i32 s43, s78, 0x400
	global_load_lds_dwordx4 v78, s[50:51]
	s_mov_b32 m0, s43
	s_nop 0
	global_load_lds_dwordx4 v79, s[50:51]
	s_waitcnt vmcnt(10)
	v_add_u32_e32 v54, s98, v59
	v_add_u32_e32 v55, s98, v60
	v_add_u32_e32 v56, s98, v61
	v_add_u32_e32 v57, s98, v62
	ds_read_b64_tr_b4 v[46:47], v160 offset:256
	ds_read_b64_tr_b4 v[48:49], v160 offset:1280
	ds_read_b64_tr_b4 v[122:123], v54
	ds_read_b64_tr_b4 v[124:125], v55
	ds_read_b64_tr_b4 v[126:127], v56
	ds_read_b64_tr_b4 v[128:129], v57
	s_waitcnt lgkmcnt(6)
	v_dot8c_i32_i4_e32 v38, v130, v52
	v_dot8c_i32_i4_e32 v39, v130, v50
	v_dot8c_i32_i4_e32 v40, v132, v52
	v_dot8c_i32_i4_e32 v41, v132, v50
	v_dot8c_i32_i4_e32 v42, v134, v52
	v_dot8c_i32_i4_e32 v43, v134, v50
	v_dot8c_i32_i4_e32 v44, v136, v52
	v_dot8c_i32_i4_e32 v45, v136, v50
	v_dot8c_i32_i4_e32 v38, v131, v53
	v_dot8c_i32_i4_e32 v39, v131, v51
	v_dot8c_i32_i4_e32 v40, v133, v53
	v_dot8c_i32_i4_e32 v41, v133, v51
	v_dot8c_i32_i4_e32 v42, v135, v53
	v_dot8c_i32_i4_e32 v43, v135, v51
	v_dot8c_i32_i4_e32 v44, v137, v53
	v_dot8c_i32_i4_e32 v45, v137, v51
	v_and_b32_e32 v78, 0xffff, v33
	v_lshrrev_b32_e32 v79, 16, v33
	v_lshl_add_u32 v78, v78, 7, v150
	v_lshl_add_u32 v79, v79, 7, v151
	s_mov_b32 m0, s79
	s_add_i32 s43, s79, 0x400
	global_load_lds_dwordx4 v78, s[50:51]
	s_mov_b32 m0, s43
	s_nop 0
	global_load_lds_dwordx4 v79, s[50:51]
	s_waitcnt vmcnt(10)
	v_add_u32_e32 v54, s99, v59
	v_add_u32_e32 v55, s99, v60
	v_add_u32_e32 v56, s99, v61
	v_add_u32_e32 v57, s99, v62
	ds_read_b64_tr_b4 v[50:51], v160 offset:384
	ds_read_b64_tr_b4 v[52:53], v160 offset:1408
	ds_read_b64_tr_b4 v[130:131], v54
	ds_read_b64_tr_b4 v[132:133], v55
	ds_read_b64_tr_b4 v[134:135], v56
	ds_read_b64_tr_b4 v[136:137], v57
	s_waitcnt lgkmcnt(6)
	v_dot8c_i32_i4_e32 v38, v122, v48
	v_dot8c_i32_i4_e32 v39, v122, v46
	v_dot8c_i32_i4_e32 v40, v124, v48
	v_dot8c_i32_i4_e32 v41, v124, v46
	v_dot8c_i32_i4_e32 v42, v126, v48
	v_dot8c_i32_i4_e32 v43, v126, v46
	v_dot8c_i32_i4_e32 v44, v128, v48
	v_dot8c_i32_i4_e32 v45, v128, v46
	v_dot8c_i32_i4_e32 v38, v123, v49
	v_dot8c_i32_i4_e32 v39, v123, v47
	v_dot8c_i32_i4_e32 v40, v125, v49
	v_dot8c_i32_i4_e32 v41, v125, v47
	v_dot8c_i32_i4_e32 v42, v127, v49
	v_dot8c_i32_i4_e32 v43, v127, v47
	v_dot8c_i32_i4_e32 v44, v129, v49
	v_dot8c_i32_i4_e32 v45, v129, v47
	s_waitcnt lgkmcnt(15)
	v_and_b32_e32 v78, 0xffff, v18
	v_lshrrev_b32_e32 v79, 16, v18
	v_lshl_add_u32 v78, v78, 7, v152
	v_lshl_add_u32 v79, v79, 7, v153
	s_mov_b32 m0, s98
	s_add_i32 s43, s98, 0x400
	global_load_lds_dwordx4 v78, s[50:51]
	s_mov_b32 m0, s43
	s_nop 0
	global_load_lds_dwordx4 v79, s[50:51]
	s_waitcnt vmcnt(10)
	v_add_u32_e32 v54, s76, v59
	v_add_u32_e32 v55, s76, v60
	v_add_u32_e32 v56, s76, v61
	v_add_u32_e32 v57, s76, v62
	ds_read_b64_tr_b4 v[46:47], v160 offset:512
	ds_read_b64_tr_b4 v[48:49], v160 offset:1536
	ds_read_b64_tr_b4 v[122:123], v54
	ds_read_b64_tr_b4 v[124:125], v55
	ds_read_b64_tr_b4 v[126:127], v56
	ds_read_b64_tr_b4 v[128:129], v57
	s_waitcnt lgkmcnt(6)
	v_dot8c_i32_i4_e32 v38, v130, v52
	v_dot8c_i32_i4_e32 v39, v130, v50
	v_dot8c_i32_i4_e32 v40, v132, v52
	v_dot8c_i32_i4_e32 v41, v132, v50
	v_dot8c_i32_i4_e32 v42, v134, v52
	v_dot8c_i32_i4_e32 v43, v134, v50
	v_dot8c_i32_i4_e32 v44, v136, v52
	v_dot8c_i32_i4_e32 v45, v136, v50
	v_dot8c_i32_i4_e32 v38, v131, v53
	v_dot8c_i32_i4_e32 v39, v131, v51
	v_dot8c_i32_i4_e32 v40, v133, v53
	v_dot8c_i32_i4_e32 v41, v133, v51
	v_dot8c_i32_i4_e32 v42, v135, v53
	v_dot8c_i32_i4_e32 v43, v135, v51
	v_dot8c_i32_i4_e32 v44, v137, v53
	v_dot8c_i32_i4_e32 v45, v137, v51
	v_and_b32_e32 v78, 0xffff, v19
	v_lshrrev_b32_e32 v79, 16, v19
	v_lshl_add_u32 v78, v78, 7, v152
	v_lshl_add_u32 v79, v79, 7, v153
	s_mov_b32 m0, s99
	s_add_i32 s43, s99, 0x400
	global_load_lds_dwordx4 v78, s[50:51]
	s_mov_b32 m0, s43
	s_nop 0
	global_load_lds_dwordx4 v79, s[50:51]
	s_waitcnt vmcnt(8)
	v_add_u32_e32 v54, s77, v59
	v_add_u32_e32 v55, s77, v60
	v_add_u32_e32 v56, s77, v61
	v_add_u32_e32 v57, s77, v62
	ds_read_b64_tr_b4 v[50:51], v160 offset:640
	ds_read_b64_tr_b4 v[52:53], v160 offset:1664
	ds_read_b64_tr_b4 v[130:131], v54
	ds_read_b64_tr_b4 v[132:133], v55
	ds_read_b64_tr_b4 v[134:135], v56
	ds_read_b64_tr_b4 v[136:137], v57
	s_waitcnt lgkmcnt(6)
	v_dot8c_i32_i4_e32 v38, v122, v48
	v_dot8c_i32_i4_e32 v39, v122, v46
	v_dot8c_i32_i4_e32 v40, v124, v48
	v_dot8c_i32_i4_e32 v41, v124, v46
	v_dot8c_i32_i4_e32 v42, v126, v48
	v_dot8c_i32_i4_e32 v43, v126, v46
	v_dot8c_i32_i4_e32 v44, v128, v48
	v_dot8c_i32_i4_e32 v45, v128, v46
	v_dot8c_i32_i4_e32 v38, v123, v49
	v_dot8c_i32_i4_e32 v39, v123, v47
	v_dot8c_i32_i4_e32 v40, v125, v49
	v_dot8c_i32_i4_e32 v41, v125, v47
	v_dot8c_i32_i4_e32 v42, v127, v49
	v_dot8c_i32_i4_e32 v43, v127, v47
	v_dot8c_i32_i4_e32 v44, v129, v49
	v_dot8c_i32_i4_e32 v45, v129, v47
	s_waitcnt lgkmcnt(15)
; __device__ __forceinline__ void peer_v_tokens(int j, const LAS unsigned short* EL, const LAS unsigned char* AL  , const LAS float* ASC  , const LAS int* SAL  , ...
;     ...
; #pragma unroll
;         for (int st = 0; st < 16; ++st) {
;             const int p = st >> 2, q = st & 3;
;             if (st < 14) VDMA(st + 2, (st + 2) % 3);
;             if (st < 14) asm volatile("s_waitcnt vmcnt(8)" ::: "memory");
;             else if (st == 14) asm volatile("s_waitcnt vmcnt(4)" ::: "memory");
;             else asm volatile("s_waitcnt vmcnt(0)" ::: "memory");
;             if (q == 0) {
; #pragma unroll
;                 for (int r = 0; r < 4; ++r) { accH[r] = 0; accL[r] = 0; } }
; #pragma unroll
;             for (int tp = 0; tp < 2; ++tp) {
;                 const v2i ao = TR4(ATL + (2 * q + tp) * 128 + 8 * s16), ah = TR4(ATL + 1024 + (2 * q + tp) * 128 + 8 * s16);
; #pragma unroll
;                 for (int r = 0; r < 4; ++r) {
;                     const v2i d = TR4(ldsb + BUF[st % 3] + 2048 * tp + roff[r]);
;                     accH[r] = __builtin_amdgcn_sdot8(d.x, ah.x, accH[r], false); accH[r] = __builtin_amdgcn_sdot8(d.y, ah.y, accH[r], false);
;                     accL[r] = __builtin_amdgcn_sdot8(d.x, ao.x, accL[r], false); accL[r] = __builtin_amdgcn_sdot8(d.y, ao.y, accL[r], false);
;                 }
;             }
;             asm volatile("s_waitcnt lgkmcnt(0)" ::: "memory");
;             if (q == 3) {
; #pragma unroll
;                 for (int r = 0; r < 4; ++r) STASH[256 * p + 16 * (grp + 4 * r) + pc] = f2bf(asc * (float)(2 * ((accH[r] << 4) + accL[r]) + sa));
;             }
;         }
;         CFENCE();
;         {
;             float4 v[4]; float ss = 0.f;
; #pragma unroll
;             for (int jq = 0; jq < 4; ++jq) { typedef unsigned u2v __attribute__((ext_vector_type(2))); const u2v pw = *(const LAS u2v*)(STASH + 4 * lane + 256 * jq); const uint2 hw = hv[jq];
;                 v[jq] = make_float4(__uint_as_float(hw.x << 16) + __uint_as_float(pw.x << 16), __uint_as_float(hw.x & 0xffff0000u) + __uint_as_float(pw.x & 0xffff0000u),
;                                     __uint_as_float(hw.y << 16) + __uint_as_float(pw.y << 16), __uint_as_float(hw.y & 0xffff0000u) + __uint_as_float(pw.y & 0xffff0000u));
;                 ss += v[jq].x * v[jq].x + v[jq].y * v[jq].y + v[jq].z * v[jq].z + v[jq].w * v[jq].w; }
;             ss = wave_sum(ss);
	v_add_u32_e32 v143, 8, v139
	v_and_b32_e32 v142, 15, v143
	v_xor_b32_e32 v142, 8, v142
	v_bfe_u32 v144, v143, 4, 4
	v_mul_lo_u32 v142, v142, s92
	v_mul_lo_u32 v144, v144, s92
	v_mov_b32_e32 v143, v142
	v_mov_b32_e32 v145, v144
	ds_write2st64_b64 v159, v[142:143], v[144:145] offset1:2
	v_and_b32_e32 v78, 0xffff, v20
	v_lshrrev_b32_e32 v79, 16, v20
	v_lshl_add_u32 v78, v78, 7, v152
	v_lshl_add_u32 v79, v79, 7, v153
	s_mov_b32 m0, s76
	s_add_i32 s43, s76, 0x400
	global_load_lds_dwordx4 v78, s[50:51]
	s_mov_b32 m0, s43
	s_nop 0
	global_load_lds_dwordx4 v79, s[50:51]
	s_waitcnt vmcnt(8)
	v_add_u32_e32 v54, s78, v59
	v_add_u32_e32 v55, s78, v60
	v_add_u32_e32 v56, s78, v61
	v_add_u32_e32 v57, s78, v62
	ds_read_b64_tr_b4 v[46:47], v160 offset:768
	ds_read_b64_tr_b4 v[48:49], v160 offset:1792
	ds_read_b64_tr_b4 v[122:123], v54
	ds_read_b64_tr_b4 v[124:125], v55
	ds_read_b64_tr_b4 v[126:127], v56
	ds_read_b64_tr_b4 v[128:129], v57
	s_waitcnt lgkmcnt(7)
	v_dot8c_i32_i4_e32 v38, v130, v52
	v_dot8c_i32_i4_e32 v39, v130, v50
	v_dot8c_i32_i4_e32 v40, v132, v52
	v_dot8c_i32_i4_e32 v41, v132, v50
	v_dot8c_i32_i4_e32 v42, v134, v52
	v_dot8c_i32_i4_e32 v43, v134, v50
	v_dot8c_i32_i4_e32 v44, v136, v52
	v_dot8c_i32_i4_e32 v45, v136, v50
	v_dot8c_i32_i4_e32 v38, v131, v53
	v_dot8c_i32_i4_e32 v39, v131, v51
	v_dot8c_i32_i4_e32 v40, v133, v53
	v_dot8c_i32_i4_e32 v41, v133, v51
	v_dot8c_i32_i4_e32 v42, v135, v53
	v_dot8c_i32_i4_e32 v43, v135, v51
	v_dot8c_i32_i4_e32 v44, v137, v53
	v_dot8c_i32_i4_e32 v45, v137, v51
	v_and_b32_e32 v78, 0xffff, v21
	v_lshrrev_b32_e32 v79, 16, v21
	v_lshl_add_u32 v78, v78, 7, v152
	v_lshl_add_u32 v79, v79, 7, v153
	s_mov_b32 m0, s77
	s_add_i32 s43, s77, 0x400
	global_load_lds_dwordx4 v78, s[50:51]
	s_mov_b32 m0, s43
	s_nop 0
	global_load_lds_dwordx4 v79, s[50:51]
	s_waitcnt vmcnt(8)
	v_add_u32_e32 v54, s79, v59
	v_add_u32_e32 v55, s79, v60
	v_add_u32_e32 v56, s79, v61
	v_add_u32_e32 v57, s79, v62
	ds_read_b64_tr_b4 v[50:51], v160 offset:896
	ds_read_b64_tr_b4 v[52:53], v160 offset:1920
	ds_read_b64_tr_b4 v[130:131], v54
	ds_read_b64_tr_b4 v[132:133], v55
	ds_read_b64_tr_b4 v[134:135], v56
	ds_read_b64_tr_b4 v[136:137], v57
	s_waitcnt lgkmcnt(6)
	v_dot8c_i32_i4_e32 v38, v122, v48
	v_dot8c_i32_i4_e32 v39, v122, v46
	v_dot8c_i32_i4_e32 v40, v124, v48
	v_dot8c_i32_i4_e32 v41, v124, v46
	v_dot8c_i32_i4_e32 v42, v126, v48
	v_dot8c_i32_i4_e32 v43, v126, v46
	v_dot8c_i32_i4_e32 v44, v128, v48
	v_dot8c_i32_i4_e32 v45, v128, v46
	v_dot8c_i32_i4_e32 v38, v123, v49
	v_dot8c_i32_i4_e32 v39, v123, v47
	v_dot8c_i32_i4_e32 v40, v125, v49
	v_dot8c_i32_i4_e32 v41, v125, v47
	v_dot8c_i32_i4_e32 v42, v127, v49
	v_dot8c_i32_i4_e32 v43, v127, v47
	v_dot8c_i32_i4_e32 v44, v129, v49
	v_dot8c_i32_i4_e32 v45, v129, v47
	v_and_b32_e32 v78, 0xffff, v22
	v_lshrrev_b32_e32 v79, 16, v22
	v_lshl_add_u32 v78, v78, 7, v152
	v_lshl_add_u32 v79, v79, 7, v153
	s_mov_b32 m0, s78
	s_add_i32 s43, s78, 0x400
	global_load_lds_dwordx4 v78, s[50:51]
	s_mov_b32 m0, s43
	s_nop 0
	global_load_lds_dwordx4 v79, s[50:51]
	s_waitcnt vmcnt(8)
	v_add_u32_e32 v54, s98, v59
	v_add_u32_e32 v55, s98, v60
	v_add_u32_e32 v56, s98, v61
	v_add_u32_e32 v57, s98, v62
	ds_read_b64_tr_b4 v[46:47], v160
	ds_read_b64_tr_b4 v[48:49], v160 offset:1024
	ds_read_b64_tr_b4 v[122:123], v54
	ds_read_b64_tr_b4 v[124:125], v55
	ds_read_b64_tr_b4 v[126:127], v56
	ds_read_b64_tr_b4 v[128:129], v57
	s_waitcnt lgkmcnt(6)
	v_dot8c_i32_i4_e32 v38, v130, v52
	v_dot8c_i32_i4_e32 v39, v130, v50
	v_dot8c_i32_i4_e32 v40, v132, v52
	v_dot8c_i32_i4_e32 v41, v132, v50
	v_dot8c_i32_i4_e32 v42, v134, v52
	v_dot8c_i32_i4_e32 v43, v134, v50
	v_dot8c_i32_i4_e32 v44, v136, v52
	v_dot8c_i32_i4_e32 v45, v136, v50
	v_dot8c_i32_i4_e32 v38, v131, v53
	v_dot8c_i32_i4_e32 v39, v131, v51
	v_dot8c_i32_i4_e32 v40, v133, v53
	v_dot8c_i32_i4_e32 v41, v133, v51
	v_dot8c_i32_i4_e32 v42, v135, v53
	v_dot8c_i32_i4_e32 v43, v135, v51
	v_dot8c_i32_i4_e32 v44, v137, v53
	v_dot8c_i32_i4_e32 v45, v137, v51
	s_nop 3
	s_waitcnt lgkmcnt(15)
	v_lshlrev_b32_e32 v38, 5, v38
	v_lshlrev_b32_e32 v39, 1, v39
	v_add3_u32 v38, v39, v229, v38
	v_cvt_f32_i32_e32 v38, v38
	v_mul_f32_e32 v38, v228, v38
	v_lshlrev_b32_e32 v40, 5, v40
	v_lshlrev_b32_e32 v41, 1, v41
	v_add3_u32 v40, v41, v229, v40
	v_cvt_f32_i32_e32 v40, v40
	v_mul_f32_e32 v40, v228, v40
	v_lshlrev_b32_e32 v42, 5, v42
	v_lshlrev_b32_e32 v43, 1, v43
	v_add3_u32 v42, v43, v229, v42
	v_cvt_f32_i32_e32 v42, v42
	v_mul_f32_e32 v42, v228, v42
	v_lshlrev_b32_e32 v44, 5, v44
	v_lshlrev_b32_e32 v45, 1, v45
	v_add3_u32 v44, v45, v229, v44
	v_cvt_f32_i32_e32 v44, v44
	v_mul_f32_e32 v44, v228, v44
	v_cvt_pk_bf16_f32 v190, v38, v40
	v_cvt_pk_bf16_f32 v191, v42, v44
	ds_read_b128 v[252:255], v155 offset:1024
	s_add_i32 s44, s40, 8
	s_ashr_i32 s45, s44, 31
	s_lshl_b64 s[44:45], s[44:45], 12
	v_lshl_add_u64 v[80:81], v[36:37], 0, s[44:45]
	s_waitcnt lgkmcnt(0)
	v_mul_f32_e32 v240, v240, v252
	v_mul_f32_e32 v241, v241, v253
	v_mul_f32_e32 v242, v242, v254
	v_mul_f32_e32 v243, v243, v255
	global_store_dwordx4 v[80:81], v[240:243], off offset:1024 nt
	v_add_u32_e32 v147, 8, v140
	v_and_b32_e32 v146, 15, v147
	v_xor_b32_e32 v146, 8, v146
	v_bfe_u32 v148, v147, 4, 4
	v_mul_lo_u32 v146, v146, s92
	v_mul_lo_u32 v148, v148, s92
	v_mov_b32_e32 v147, v146
	v_mov_b32_e32 v149, v148
	ds_write2st64_b64 v77, v[146:147], v[148:149] offset1:2
	v_add_u32_e32 v138, 0xc00, v74
	ds_read_u8 v139, v138
	v_add_u32_e32 v141, 0xc00, v73
	ds_read_u8 v140, v141
	s_add_i32 s43, s67, 64
	v_mov_b32_e32 v138, s43
	ds_read2st64_b32 v[228:229], v138 offset1:1
	ds_read_b128 v[26:29], v227 offset:6144
	ds_read_b128 v[30:33], v227 offset:6160
	v_mov_b32_e32 v38, 0
	v_mov_b32_e32 v39, 0
	v_mov_b32_e32 v40, 0
	v_mov_b32_e32 v41, 0
	v_mov_b32_e32 v42, 0
	v_mov_b32_e32 v43, 0
	v_mov_b32_e32 v44, 0
	v_mov_b32_e32 v45, 0
	v_and_b32_e32 v78, 0xffff, v23
	v_lshrrev_b32_e32 v79, 16, v23
	v_lshl_add_u32 v78, v78, 7, v152
	v_lshl_add_u32 v79, v79, 7, v153
	s_mov_b32 m0, s79
	s_add_i32 s43, s79, 0x400
	global_load_lds_dwordx4 v78, s[50:51]
	s_mov_b32 m0, s43
	s_nop 0
	global_load_lds_dwordx4 v79, s[50:51]
	s_waitcnt vmcnt(9)
; #define TR4(p_) __builtin_amdgcn_ds_read_tr4_b64_v2i32((LAS v2i*)(p_))
; #define VDMA(st_, k_) do { _Pragma("unroll") for (int i_ = 0; i_ < 4; ++i_) { \
;         const unsigned off_ = (unsigned)((st_) >> 2) * (16384u * 128u) + (PE_ID(E, 4 * ((st_) & 3) + i_) << 7) + ((i_ & 1) ? cx1 : cx0); \
;         __builtin_amdgcn_global_load_lds((const unsigned*)(V4 + off_), (LAS unsigned*)(ldsb + BUF[k_] + 1024 * i_), 16, 0, 0); } } while (0)
; __device__ __forceinline__ void peer_v_tokens(int j, const LAS unsigned short* EL, const LAS unsigned char* AL  , const LAS float* ASC  , const LAS int* SAL  , ...
;     ...
; #pragma unroll
;         for (int st = 0; st < 16; ++st) {
;             const int p = st >> 2, q = st & 3;
;             if (st < 14) VDMA(st + 2, (st + 2) % 3);
;             if (st < 14) asm volatile("s_waitcnt vmcnt(8)" ::: "memory");
;             else if (st == 14) asm volatile("s_waitcnt vmcnt(4)" ::: "memory");
;             else asm volatile("s_waitcnt vmcnt(0)" ::: "memory");
;             if (q == 0) {
; #pragma unroll
;                 for (int r = 0; r < 4; ++r) { accH[r] = 0; accL[r] = 0; } }
; #pragma unroll
;             for (int tp = 0; tp < 2; ++tp) {
;                 const v2i ao = TR4(ATL + (2 * q + tp) * 128 + 8 * s16), ah = TR4(ATL + 1024 + (2 * q + tp) * 128 + 8 * s16);
; #pragma unroll
;                 for (int r = 0; r < 4; ++r) {
;                     const v2i d = TR4(ldsb + BUF[st % 3] + 2048 * tp + roff[r]);
;                     accH[r] = __builtin_amdgcn_sdot8(d.x, ah.x, accH[r], false); accH[r] = __builtin_amdgcn_sdot8(d.y, ah.y, accH[r], false);
;                     accL[r] = __builtin_amdgcn_sdot8(d.x, ao.x, accL[r], false); accL[r] = __builtin_amdgcn_sdot8(d.y, ao.y, accL[r], false);
;                 }
	v_add_u32_e32 v54, s99, v59
	v_add_u32_e32 v55, s99, v60
	v_add_u32_e32 v56, s99, v61
	v_add_u32_e32 v57, s99, v62
	ds_read_b64_tr_b4 v[50:51], v160 offset:128
	ds_read_b64_tr_b4 v[52:53], v160 offset:1152
	ds_read_b64_tr_b4 v[130:131], v54
	ds_read_b64_tr_b4 v[132:133], v55
	ds_read_b64_tr_b4 v[134:135], v56
	ds_read_b64_tr_b4 v[136:137], v57
	s_waitcnt lgkmcnt(13)
	v_dot8c_i32_i4_e32 v38, v122, v48
	v_dot8c_i32_i4_e32 v39, v122, v46
	v_dot8c_i32_i4_e32 v40, v124, v48
	v_dot8c_i32_i4_e32 v41, v124, v46
	v_dot8c_i32_i4_e32 v42, v126, v48
	v_dot8c_i32_i4_e32 v43, v126, v46
	v_dot8c_i32_i4_e32 v44, v128, v48
	v_dot8c_i32_i4_e32 v45, v128, v46
	v_dot8c_i32_i4_e32 v38, v123, v49
	v_dot8c_i32_i4_e32 v39, v123, v47
	v_dot8c_i32_i4_e32 v40, v125, v49
	v_dot8c_i32_i4_e32 v41, v125, v47
	v_dot8c_i32_i4_e32 v42, v127, v49
	v_dot8c_i32_i4_e32 v43, v127, v47
	v_dot8c_i32_i4_e32 v44, v129, v49
	v_dot8c_i32_i4_e32 v45, v129, v47
	v_and_b32_e32 v78, 0xffff, v24
	v_lshrrev_b32_e32 v79, 16, v24
	v_lshl_add_u32 v78, v78, 7, v152
	v_lshl_add_u32 v79, v79, 7, v153
	s_mov_b32 m0, s98
	s_add_i32 s43, s98, 0x400
	global_load_lds_dwordx4 v78, s[50:51]
	s_mov_b32 m0, s43
	s_nop 0
	global_load_lds_dwordx4 v79, s[50:51]
	s_waitcnt vmcnt(9)
	v_add_u32_e32 v54, s76, v59
	v_add_u32_e32 v55, s76, v60
	v_add_u32_e32 v56, s76, v61
	v_add_u32_e32 v57, s76, v62
	ds_read_b64_tr_b4 v[46:47], v160 offset:256
	ds_read_b64_tr_b4 v[48:49], v160 offset:1280
	ds_read_b64_tr_b4 v[122:123], v54
	ds_read_b64_tr_b4 v[124:125], v55
	ds_read_b64_tr_b4 v[126:127], v56
	ds_read_b64_tr_b4 v[128:129], v57
	s_waitcnt lgkmcnt(6)
	v_dot8c_i32_i4_e32 v38, v130, v52
	v_dot8c_i32_i4_e32 v39, v130, v50
	v_dot8c_i32_i4_e32 v40, v132, v52
	v_dot8c_i32_i4_e32 v41, v132, v50
	v_dot8c_i32_i4_e32 v42, v134, v52
	v_dot8c_i32_i4_e32 v43, v134, v50
	v_dot8c_i32_i4_e32 v44, v136, v52
	v_dot8c_i32_i4_e32 v45, v136, v50
	v_dot8c_i32_i4_e32 v38, v131, v53
	v_dot8c_i32_i4_e32 v39, v131, v51
	v_dot8c_i32_i4_e32 v40, v133, v53
	v_dot8c_i32_i4_e32 v41, v133, v51
	v_dot8c_i32_i4_e32 v42, v135, v53
	v_dot8c_i32_i4_e32 v43, v135, v51
	v_dot8c_i32_i4_e32 v44, v137, v53
	v_dot8c_i32_i4_e32 v45, v137, v51
	v_and_b32_e32 v78, 0xffff, v25
	v_lshrrev_b32_e32 v79, 16, v25
	v_lshl_add_u32 v78, v78, 7, v152
	v_lshl_add_u32 v79, v79, 7, v153
	s_mov_b32 m0, s99
	s_add_i32 s43, s99, 0x400
	global_load_lds_dwordx4 v78, s[50:51]
	s_mov_b32 m0, s43
	s_nop 0
	global_load_lds_dwordx4 v79, s[50:51]
	s_waitcnt vmcnt(9)
	v_add_u32_e32 v54, s77, v59
	v_add_u32_e32 v55, s77, v60
	v_add_u32_e32 v56, s77, v61
	v_add_u32_e32 v57, s77, v62
	ds_read_b64_tr_b4 v[50:51], v160 offset:384
	ds_read_b64_tr_b4 v[52:53], v160 offset:1408
	ds_read_b64_tr_b4 v[130:131], v54
	ds_read_b64_tr_b4 v[132:133], v55
	ds_read_b64_tr_b4 v[134:135], v56
	ds_read_b64_tr_b4 v[136:137], v57
	s_waitcnt lgkmcnt(6)
	v_dot8c_i32_i4_e32 v38, v122, v48
	v_dot8c_i32_i4_e32 v39, v122, v46
	v_dot8c_i32_i4_e32 v40, v124, v48
	v_dot8c_i32_i4_e32 v41, v124, v46
	v_dot8c_i32_i4_e32 v42, v126, v48
	v_dot8c_i32_i4_e32 v43, v126, v46
	v_dot8c_i32_i4_e32 v44, v128, v48
	v_dot8c_i32_i4_e32 v45, v128, v46
	v_dot8c_i32_i4_e32 v38, v123, v49
	v_dot8c_i32_i4_e32 v39, v123, v47
	v_dot8c_i32_i4_e32 v40, v125, v49
	v_dot8c_i32_i4_e32 v41, v125, v47
	v_dot8c_i32_i4_e32 v42, v127, v49
	v_dot8c_i32_i4_e32 v43, v127, v47
	v_dot8c_i32_i4_e32 v44, v129, v49
	v_dot8c_i32_i4_e32 v45, v129, v47
	s_waitcnt lgkmcnt(15)
	v_and_b32_e32 v78, 0xffff, v26
	v_lshrrev_b32_e32 v79, 16, v26
	v_lshl_add_u32 v78, v78, 7, v152
	v_lshl_add_u32 v79, v79, 7, v153
	s_mov_b32 m0, s76
	s_add_i32 s43, s76, 0x400
	global_load_lds_dwordx4 v78, s[50:51]
	s_mov_b32 m0, s43
	s_nop 0
	global_load_lds_dwordx4 v79, s[50:51]
	s_waitcnt vmcnt(9)
	v_add_u32_e32 v54, s78, v59
	v_add_u32_e32 v55, s78, v60
	v_add_u32_e32 v56, s78, v61
	v_add_u32_e32 v57, s78, v62
	ds_read_b64_tr_b4 v[46:47], v160 offset:512
	ds_read_b64_tr_b4 v[48:49], v160 offset:1536
	ds_read_b64_tr_b4 v[122:123], v54
	ds_read_b64_tr_b4 v[124:125], v55
	ds_read_b64_tr_b4 v[126:127], v56
	ds_read_b64_tr_b4 v[128:129], v57
	s_waitcnt lgkmcnt(6)
	v_dot8c_i32_i4_e32 v38, v130, v52
	v_dot8c_i32_i4_e32 v39, v130, v50
	v_dot8c_i32_i4_e32 v40, v132, v52
	v_dot8c_i32_i4_e32 v41, v132, v50
	v_dot8c_i32_i4_e32 v42, v134, v52
	v_dot8c_i32_i4_e32 v43, v134, v50
	v_dot8c_i32_i4_e32 v44, v136, v52
	v_dot8c_i32_i4_e32 v45, v136, v50
	v_dot8c_i32_i4_e32 v38, v131, v53
	v_dot8c_i32_i4_e32 v39, v131, v51
	v_dot8c_i32_i4_e32 v40, v133, v53
	v_dot8c_i32_i4_e32 v41, v133, v51
	v_dot8c_i32_i4_e32 v42, v135, v53
	v_dot8c_i32_i4_e32 v43, v135, v51
	v_dot8c_i32_i4_e32 v44, v137, v53
	v_dot8c_i32_i4_e32 v45, v137, v51
	v_and_b32_e32 v78, 0xffff, v27
	v_lshrrev_b32_e32 v79, 16, v27
	v_lshl_add_u32 v78, v78, 7, v152
	v_lshl_add_u32 v79, v79, 7, v153
	s_mov_b32 m0, s77
	s_add_i32 s43, s77, 0x400
	global_load_lds_dwordx4 v78, s[50:51]
	s_mov_b32 m0, s43
	s_nop 0
	global_load_lds_dwordx4 v79, s[50:51]
	s_waitcnt vmcnt(8)
	v_add_u32_e32 v54, s79, v59
	v_add_u32_e32 v55, s79, v60
	v_add_u32_e32 v56, s79, v61
	v_add_u32_e32 v57, s79, v62
	ds_read_b64_tr_b4 v[50:51], v160 offset:640
	ds_read_b64_tr_b4 v[52:53], v160 offset:1664
	ds_read_b64_tr_b4 v[130:131], v54
	ds_read_b64_tr_b4 v[132:133], v55
	ds_read_b64_tr_b4 v[134:135], v56
	ds_read_b64_tr_b4 v[136:137], v57
	s_waitcnt lgkmcnt(6)
	v_dot8c_i32_i4_e32 v38, v122, v48
	v_dot8c_i32_i4_e32 v39, v122, v46
	v_dot8c_i32_i4_e32 v40, v124, v48
	v_dot8c_i32_i4_e32 v41, v124, v46
	v_dot8c_i32_i4_e32 v42, v126, v48
	v_dot8c_i32_i4_e32 v43, v126, v46
	v_dot8c_i32_i4_e32 v44, v128, v48
	v_dot8c_i32_i4_e32 v45, v128, v46
	v_dot8c_i32_i4_e32 v38, v123, v49
	v_dot8c_i32_i4_e32 v39, v123, v47
	v_dot8c_i32_i4_e32 v40, v125, v49
	v_dot8c_i32_i4_e32 v41, v125, v47
	v_dot8c_i32_i4_e32 v42, v127, v49
	v_dot8c_i32_i4_e32 v43, v127, v47
	v_dot8c_i32_i4_e32 v44, v129, v49
	v_dot8c_i32_i4_e32 v45, v129, v47
	s_waitcnt lgkmcnt(15)
; __device__ __forceinline__ bf16 f2bf(float f) { return (bf16)f2bfu(f); }
; #define TR4(p_) __builtin_amdgcn_ds_read_tr4_b64_v2i32((LAS v2i*)(p_))
; #define VDMA(st_, k_) do { _Pragma("unroll") for (int i_ = 0; i_ < 4; ++i_) { \
;         const unsigned off_ = (unsigned)((st_) >> 2) * (16384u * 128u) + (PE_ID(E, 4 * ((st_) & 3) + i_) << 7) + ((i_ & 1) ? cx1 : cx0); \
;         __builtin_amdgcn_global_load_lds((const unsigned*)(V4 + off_), (LAS unsigned*)(ldsb + BUF[k_] + 1024 * i_), 16, 0, 0); } } while (0)
; __device__ __forceinline__ void peer_v_tokens(int j, const LAS unsigned short* EL, const LAS unsigned char* AL  , const LAS float* ASC  , const LAS int* SAL  , ...
;     ...
; #pragma unroll
;         for (int st = 0; st < 16; ++st) {
;             const int p = st >> 2, q = st & 3;
;             if (st < 14) VDMA(st + 2, (st + 2) % 3);
;             if (st < 14) asm volatile("s_waitcnt vmcnt(8)" ::: "memory");
;             else if (st == 14) asm volatile("s_waitcnt vmcnt(4)" ::: "memory");
;             else asm volatile("s_waitcnt vmcnt(0)" ::: "memory");
;             if (q == 0) {
; #pragma unroll
;                 for (int r = 0; r < 4; ++r) { accH[r] = 0; accL[r] = 0; } }
; #pragma unroll
;             for (int tp = 0; tp < 2; ++tp) {
;                 const v2i ao = TR4(ATL + (2 * q + tp) * 128 + 8 * s16), ah = TR4(ATL + 1024 + (2 * q + tp) * 128 + 8 * s16);
; #pragma unroll
;                 for (int r = 0; r < 4; ++r) {
;                     const v2i d = TR4(ldsb + BUF[st % 3] + 2048 * tp + roff[r]);
;                     accH[r] = __builtin_amdgcn_sdot8(d.x, ah.x, accH[r], false); accH[r] = __builtin_amdgcn_sdot8(d.y, ah.y, accH[r], false);
;                     accL[r] = __builtin_amdgcn_sdot8(d.x, ao.x, accL[r], false); accL[r] = __builtin_amdgcn_sdot8(d.y, ao.y, accL[r], false);
;                 }
;             }
;             asm volatile("s_waitcnt lgkmcnt(0)" ::: "memory");
;             if (q == 3) {
; #pragma unroll
;                 for (int r = 0; r < 4; ++r) STASH[256 * p + 16 * (grp + 4 * r) + pc] = f2bf(asc * (float)(2 * ((accH[r] << 4) + accL[r]) + sa));
	v_add_u32_e32 v143, 8, v139
	v_and_b32_e32 v142, 15, v143
	v_xor_b32_e32 v142, 8, v142
	v_bfe_u32 v144, v143, 4, 4
	v_mul_lo_u32 v142, v142, s92
	v_mul_lo_u32 v144, v144, s92
	v_mov_b32_e32 v143, v142
	v_mov_b32_e32 v145, v144
	ds_write2st64_b64 v159, v[142:143], v[144:145] offset1:2
	v_and_b32_e32 v78, 0xffff, v28
	v_lshrrev_b32_e32 v79, 16, v28
	v_lshl_add_u32 v78, v78, 7, v152
	v_lshl_add_u32 v79, v79, 7, v153
	s_mov_b32 m0, s78
	s_add_i32 s43, s78, 0x400
	global_load_lds_dwordx4 v78, s[50:51]
	s_mov_b32 m0, s43
	s_nop 0
	global_load_lds_dwordx4 v79, s[50:51]
	s_waitcnt vmcnt(8)
	v_add_u32_e32 v54, s98, v59
	v_add_u32_e32 v55, s98, v60
	v_add_u32_e32 v56, s98, v61
	v_add_u32_e32 v57, s98, v62
	ds_read_b64_tr_b4 v[46:47], v160 offset:768
	ds_read_b64_tr_b4 v[48:49], v160 offset:1792
	ds_read_b64_tr_b4 v[122:123], v54
	ds_read_b64_tr_b4 v[124:125], v55
	ds_read_b64_tr_b4 v[126:127], v56
	ds_read_b64_tr_b4 v[128:129], v57
	s_waitcnt lgkmcnt(7)
	v_dot8c_i32_i4_e32 v38, v130, v52
	v_dot8c_i32_i4_e32 v39, v130, v50
	v_dot8c_i32_i4_e32 v40, v132, v52
	v_dot8c_i32_i4_e32 v41, v132, v50
	v_dot8c_i32_i4_e32 v42, v134, v52
	v_dot8c_i32_i4_e32 v43, v134, v50
	v_dot8c_i32_i4_e32 v44, v136, v52
	v_dot8c_i32_i4_e32 v45, v136, v50
	v_dot8c_i32_i4_e32 v38, v131, v53
	v_dot8c_i32_i4_e32 v39, v131, v51
	v_dot8c_i32_i4_e32 v40, v133, v53
	v_dot8c_i32_i4_e32 v41, v133, v51
	v_dot8c_i32_i4_e32 v42, v135, v53
	v_dot8c_i32_i4_e32 v43, v135, v51
	v_dot8c_i32_i4_e32 v44, v137, v53
	v_dot8c_i32_i4_e32 v45, v137, v51
	v_and_b32_e32 v78, 0xffff, v29
	v_lshrrev_b32_e32 v79, 16, v29
	v_lshl_add_u32 v78, v78, 7, v152
	v_lshl_add_u32 v79, v79, 7, v153
	s_mov_b32 m0, s79
	s_add_i32 s43, s79, 0x400
	global_load_lds_dwordx4 v78, s[50:51]
	s_mov_b32 m0, s43
	s_nop 0
	global_load_lds_dwordx4 v79, s[50:51]
	s_waitcnt vmcnt(8)
	v_add_u32_e32 v54, s99, v59
	v_add_u32_e32 v55, s99, v60
	v_add_u32_e32 v56, s99, v61
	v_add_u32_e32 v57, s99, v62
	ds_read_b64_tr_b4 v[50:51], v160 offset:896
	ds_read_b64_tr_b4 v[52:53], v160 offset:1920
	ds_read_b64_tr_b4 v[130:131], v54
	ds_read_b64_tr_b4 v[132:133], v55
	ds_read_b64_tr_b4 v[134:135], v56
	ds_read_b64_tr_b4 v[136:137], v57
	s_waitcnt lgkmcnt(6)
	v_dot8c_i32_i4_e32 v38, v122, v48
	v_dot8c_i32_i4_e32 v39, v122, v46
	v_dot8c_i32_i4_e32 v40, v124, v48
	v_dot8c_i32_i4_e32 v41, v124, v46
	v_dot8c_i32_i4_e32 v42, v126, v48
	v_dot8c_i32_i4_e32 v43, v126, v46
	v_dot8c_i32_i4_e32 v44, v128, v48
	v_dot8c_i32_i4_e32 v45, v128, v46
	v_dot8c_i32_i4_e32 v38, v123, v49
	v_dot8c_i32_i4_e32 v39, v123, v47
	v_dot8c_i32_i4_e32 v40, v125, v49
	v_dot8c_i32_i4_e32 v41, v125, v47
	v_dot8c_i32_i4_e32 v42, v127, v49
	v_dot8c_i32_i4_e32 v43, v127, v47
	v_dot8c_i32_i4_e32 v44, v129, v49
	v_dot8c_i32_i4_e32 v45, v129, v47
	v_and_b32_e32 v78, 0xffff, v30
	v_lshrrev_b32_e32 v79, 16, v30
	v_lshl_add_u32 v78, v78, 7, v152
	v_lshl_add_u32 v79, v79, 7, v153
	s_mov_b32 m0, s98
	s_add_i32 s43, s98, 0x400
	global_load_lds_dwordx4 v78, s[50:51]
	s_mov_b32 m0, s43
	s_nop 0
	global_load_lds_dwordx4 v79, s[50:51]
	s_waitcnt vmcnt(8)
	v_add_u32_e32 v54, s76, v59
	v_add_u32_e32 v55, s76, v60
	v_add_u32_e32 v56, s76, v61
	v_add_u32_e32 v57, s76, v62
	ds_read_b64_tr_b4 v[46:47], v160
	ds_read_b64_tr_b4 v[48:49], v160 offset:1024
	ds_read_b64_tr_b4 v[122:123], v54
	ds_read_b64_tr_b4 v[124:125], v55
	ds_read_b64_tr_b4 v[126:127], v56
	ds_read_b64_tr_b4 v[128:129], v57
	s_waitcnt lgkmcnt(6)
	v_dot8c_i32_i4_e32 v38, v130, v52
	v_dot8c_i32_i4_e32 v39, v130, v50
	v_dot8c_i32_i4_e32 v40, v132, v52
	v_dot8c_i32_i4_e32 v41, v132, v50
	v_dot8c_i32_i4_e32 v42, v134, v52
	v_dot8c_i32_i4_e32 v43, v134, v50
	v_dot8c_i32_i4_e32 v44, v136, v52
	v_dot8c_i32_i4_e32 v45, v136, v50
	v_dot8c_i32_i4_e32 v38, v131, v53
	v_dot8c_i32_i4_e32 v39, v131, v51
	v_dot8c_i32_i4_e32 v40, v133, v53
	v_dot8c_i32_i4_e32 v41, v133, v51
	v_dot8c_i32_i4_e32 v42, v135, v53
	v_dot8c_i32_i4_e32 v43, v135, v51
	v_dot8c_i32_i4_e32 v44, v137, v53
	v_dot8c_i32_i4_e32 v45, v137, v51
	s_nop 3
	s_waitcnt lgkmcnt(15)
	v_lshlrev_b32_e32 v38, 5, v38
	v_lshlrev_b32_e32 v39, 1, v39
	v_add3_u32 v38, v39, v229, v38
	v_cvt_f32_i32_e32 v38, v38
	v_mul_f32_e32 v38, v228, v38
	v_lshlrev_b32_e32 v40, 5, v40
	v_lshlrev_b32_e32 v41, 1, v41
	v_add3_u32 v40, v41, v229, v40
	v_cvt_f32_i32_e32 v40, v40
	v_mul_f32_e32 v40, v228, v40
	v_lshlrev_b32_e32 v42, 5, v42
	v_lshlrev_b32_e32 v43, 1, v43
	v_add3_u32 v42, v43, v229, v42
	v_cvt_f32_i32_e32 v42, v42
	v_mul_f32_e32 v42, v228, v42
	v_lshlrev_b32_e32 v44, 5, v44
	v_lshlrev_b32_e32 v45, 1, v45
	v_add3_u32 v44, v45, v229, v44
	v_cvt_f32_i32_e32 v44, v44
	v_mul_f32_e32 v44, v228, v44
	v_cvt_pk_bf16_f32 v184, v38, v40
	v_cvt_pk_bf16_f32 v185, v42, v44
	ds_read_b128 v[252:255], v156
	s_add_i32 s44, s40, 8
	s_ashr_i32 s45, s44, 31
	s_lshl_b64 s[44:45], s[44:45], 12
	v_lshl_add_u64 v[80:81], v[36:37], 0, s[44:45]
	s_waitcnt lgkmcnt(0)
; __device__ __forceinline__ void peer_v_tokens(int j, const LAS unsigned short* EL, const LAS unsigned char* AL  , const LAS float* ASC  , const LAS int* SAL  , ...
;     ...
;         { const LAS v4u* ep = (const LAS v4u*)(EL + tl * 128 + 16 * g); const v4u e0 = ep[0], e1 = ep[1];
;           E[0] = e0.x; E[1] = e0.y; E[2] = e0.z; E[3] = e0.w; E[4] = e1.x; E[5] = e1.y; E[6] = e1.z; E[7] = e1.w; }
;         uint2 hv[4]; float4 gv[4];
;         { unsigned ho = (unsigned)t * (D / 4) + (unsigned)lane; asm volatile("" : "+v"(ho)); const uint2* hp = (const uint2*)HB + ho; const float4* gp = (const float4*)fng + lane;
; #pragma unroll
;           for (int jq = 0; jq < 4; ++jq) { hv[jq] = hp[64 * jq]; gv[jq] = gp[64 * jq]; } }
;         VDMA(0, 0); VDMA(1, 1);
; #pragma unroll
;         for (int m = 0; m < 2; ++m) {
;             const int idx = lane + 64 * m, tau = idx >> 4, sr = idx & 15, k = 16 * (sr & 7) + 2 * tau + (sr >> 3);
;             const int aq = (int)*(const LAS signed char*)(AL + tl * 128 + k); const int tq = aq + 8;
;             const unsigned lo = (((unsigned)tq & 15u) ^ 8u) * 0x11111111u, hi = ((unsigned)(tq >> 4) & 15u) * 0x11111111u;
;             typedef unsigned u2v __attribute__((ext_vector_type(2)));
;             u2v l2; l2.x = lo; l2.y = lo; u2v h2; h2.x = hi; h2.y = hi;
;             *(LAS u2v*)(ATL + 8 * idx) = l2; *(LAS u2v*)(ATL + 1024 + 8 * idx) = h2;
;         }
;         const float asc = ASC[tl]; const int sa = SAL[tl];
;         CFENCE();
;         int accH[4], accL[4];
; #pragma unroll
;         for (int st = 0; st < 16; ++st) {
;             const int p = st >> 2, q = st & 3;
;             if (st < 14) VDMA(st + 2, (st + 2) % 3);
;             if (st < 14) asm volatile("s_waitcnt vmcnt(8)" ::: "memory");
;             else if (st == 14) asm volatile("s_waitcnt vmcnt(4)" ::: "memory");
;             else asm volatile("s_waitcnt vmcnt(0)" ::: "memory");
;             if (q == 0) {
; #pragma unroll
;                 for (int r = 0; r < 4; ++r) { accH[r] = 0; accL[r] = 0; } }
; #pragma unroll
;             for (int tp = 0; tp < 2; ++tp) {
;                 const v2i ao = TR4(ATL + (2 * q + tp) * 128 + 8 * s16), ah = TR4(ATL + 1024 + (2 * q + tp) * 128 + 8 * s16);
; #pragma unroll
;                 for (int r = 0; r < 4; ++r) {
;                     const v2i d = TR4(ldsb + BUF[st % 3] + 2048 * tp + roff[r]);
	v_mul_f32_e32 v244, v244, v252
	v_mul_f32_e32 v245, v245, v253
	v_mul_f32_e32 v246, v246, v254
	v_mul_f32_e32 v247, v247, v255
	global_store_dwordx4 v[80:81], v[244:247], off offset:2048 nt
	s_add_i32 s43, s40, 16
	s_lshl_b32 s43, s43, 11
	v_add_u32_e32 v138, s43, v66
	global_load_dwordx2 v[194:195], v138, s[70:71]
	global_load_dwordx2 v[196:197], v138, s[70:71] offset:512
	global_load_dwordx2 v[198:199], v138, s[70:71] offset:1024
	global_load_dwordx2 v[200:201], v138, s[70:71] offset:1536
	v_add_u32_e32 v147, 8, v140
	v_and_b32_e32 v146, 15, v147
	v_xor_b32_e32 v146, 8, v146
	v_bfe_u32 v148, v147, 4, 4
	v_mul_lo_u32 v146, v146, s92
	v_mul_lo_u32 v148, v148, s92
	v_mov_b32_e32 v147, v146
	v_mov_b32_e32 v149, v148
	ds_write2st64_b64 v77, v[146:147], v[148:149] offset1:2
	v_add_u32_e32 v138, 0x1000, v74
	ds_read_u8 v139, v138
	v_add_u32_e32 v141, 0x1000, v73
	ds_read_u8 v140, v141
	s_add_i32 s43, s67, 96
	v_mov_b32_e32 v138, s43
	ds_read2st64_b32 v[228:229], v138 offset1:1
	ds_read_b128 v[18:21], v227 offset:8192
	ds_read_b128 v[22:25], v227 offset:8208
	v_mov_b32_e32 v150, v63
	v_mov_b32_e32 v151, v64
	v_mov_b32_e32 v38, 0
	v_mov_b32_e32 v39, 0
	v_mov_b32_e32 v40, 0
	v_mov_b32_e32 v41, 0
	v_mov_b32_e32 v42, 0
	v_mov_b32_e32 v43, 0
	v_mov_b32_e32 v44, 0
	v_mov_b32_e32 v45, 0
	v_and_b32_e32 v78, 0xffff, v31
	v_lshrrev_b32_e32 v79, 16, v31
	v_lshl_add_u32 v78, v78, 7, v152
	v_lshl_add_u32 v79, v79, 7, v153
	s_mov_b32 m0, s99
	s_add_i32 s43, s99, 0x400
	global_load_lds_dwordx4 v78, s[50:51]
	s_mov_b32 m0, s43
	s_nop 0
	global_load_lds_dwordx4 v79, s[50:51]
	s_waitcnt vmcnt(13)
	v_add_u32_e32 v54, s77, v59
	v_add_u32_e32 v55, s77, v60
	v_add_u32_e32 v56, s77, v61
	v_add_u32_e32 v57, s77, v62
	ds_read_b64_tr_b4 v[50:51], v160 offset:128
	ds_read_b64_tr_b4 v[52:53], v160 offset:1152
	ds_read_b64_tr_b4 v[130:131], v54
	ds_read_b64_tr_b4 v[132:133], v55
	ds_read_b64_tr_b4 v[134:135], v56
	ds_read_b64_tr_b4 v[136:137], v57
	s_waitcnt lgkmcnt(13)
	v_dot8c_i32_i4_e32 v38, v122, v48
	v_dot8c_i32_i4_e32 v39, v122, v46
	v_dot8c_i32_i4_e32 v40, v124, v48
	v_dot8c_i32_i4_e32 v41, v124, v46
	v_dot8c_i32_i4_e32 v42, v126, v48
	v_dot8c_i32_i4_e32 v43, v126, v46
	v_dot8c_i32_i4_e32 v44, v128, v48
	v_dot8c_i32_i4_e32 v45, v128, v46
	v_dot8c_i32_i4_e32 v38, v123, v49
	v_dot8c_i32_i4_e32 v39, v123, v47
	v_dot8c_i32_i4_e32 v40, v125, v49
	v_dot8c_i32_i4_e32 v41, v125, v47
	v_dot8c_i32_i4_e32 v42, v127, v49
	v_dot8c_i32_i4_e32 v43, v127, v47
	v_dot8c_i32_i4_e32 v44, v129, v49
	v_dot8c_i32_i4_e32 v45, v129, v47
	v_and_b32_e32 v78, 0xffff, v32
	v_lshrrev_b32_e32 v79, 16, v32
	v_lshl_add_u32 v78, v78, 7, v152
	v_lshl_add_u32 v79, v79, 7, v153
	s_mov_b32 m0, s76
	s_add_i32 s43, s76, 0x400
	global_load_lds_dwordx4 v78, s[50:51]
	s_mov_b32 m0, s43
	s_nop 0
	global_load_lds_dwordx4 v79, s[50:51]
	s_waitcnt vmcnt(13)
	v_add_u32_e32 v54, s78, v59
	v_add_u32_e32 v55, s78, v60
	v_add_u32_e32 v56, s78, v61
	v_add_u32_e32 v57, s78, v62
	ds_read_b64_tr_b4 v[46:47], v160 offset:256
	ds_read_b64_tr_b4 v[48:49], v160 offset:1280
	ds_read_b64_tr_b4 v[122:123], v54
	ds_read_b64_tr_b4 v[124:125], v55
	ds_read_b64_tr_b4 v[126:127], v56
	ds_read_b64_tr_b4 v[128:129], v57
	s_waitcnt lgkmcnt(6)
	v_dot8c_i32_i4_e32 v38, v130, v52
	v_dot8c_i32_i4_e32 v39, v130, v50
	v_dot8c_i32_i4_e32 v40, v132, v52
	v_dot8c_i32_i4_e32 v41, v132, v50
	v_dot8c_i32_i4_e32 v42, v134, v52
	v_dot8c_i32_i4_e32 v43, v134, v50
	v_dot8c_i32_i4_e32 v44, v136, v52
	v_dot8c_i32_i4_e32 v45, v136, v50
	v_dot8c_i32_i4_e32 v38, v131, v53
	v_dot8c_i32_i4_e32 v39, v131, v51
	v_dot8c_i32_i4_e32 v40, v133, v53
	v_dot8c_i32_i4_e32 v41, v133, v51
	v_dot8c_i32_i4_e32 v42, v135, v53
	v_dot8c_i32_i4_e32 v43, v135, v51
	v_dot8c_i32_i4_e32 v44, v137, v53
	v_dot8c_i32_i4_e32 v45, v137, v51
	v_and_b32_e32 v78, 0xffff, v33
	v_lshrrev_b32_e32 v79, 16, v33
	v_lshl_add_u32 v78, v78, 7, v152
	v_lshl_add_u32 v79, v79, 7, v153
	s_mov_b32 m0, s77
	s_add_i32 s43, s77, 0x400
	global_load_lds_dwordx4 v78, s[50:51]
	s_mov_b32 m0, s43
	s_nop 0
	global_load_lds_dwordx4 v79, s[50:51]
	s_waitcnt vmcnt(13)
	v_add_u32_e32 v54, s79, v59
	v_add_u32_e32 v55, s79, v60
	v_add_u32_e32 v56, s79, v61
	v_add_u32_e32 v57, s79, v62
	ds_read_b64_tr_b4 v[50:51], v160 offset:384
	ds_read_b64_tr_b4 v[52:53], v160 offset:1408
	ds_read_b64_tr_b4 v[130:131], v54
	ds_read_b64_tr_b4 v[132:133], v55
	ds_read_b64_tr_b4 v[134:135], v56
	ds_read_b64_tr_b4 v[136:137], v57
	s_waitcnt lgkmcnt(6)
	v_dot8c_i32_i4_e32 v38, v122, v48
	v_dot8c_i32_i4_e32 v39, v122, v46
	v_dot8c_i32_i4_e32 v40, v124, v48
	v_dot8c_i32_i4_e32 v41, v124, v46
	v_dot8c_i32_i4_e32 v42, v126, v48
	v_dot8c_i32_i4_e32 v43, v126, v46
	v_dot8c_i32_i4_e32 v44, v128, v48
	v_dot8c_i32_i4_e32 v45, v128, v46
	v_dot8c_i32_i4_e32 v38, v123, v49
	v_dot8c_i32_i4_e32 v39, v123, v47
	v_dot8c_i32_i4_e32 v40, v125, v49
	v_dot8c_i32_i4_e32 v41, v125, v47
	v_dot8c_i32_i4_e32 v42, v127, v49
	v_dot8c_i32_i4_e32 v43, v127, v47
	v_dot8c_i32_i4_e32 v44, v129, v49
	v_dot8c_i32_i4_e32 v45, v129, v47
	s_waitcnt lgkmcnt(15)
	v_and_b32_e32 v78, 0xffff, v18
	v_lshrrev_b32_e32 v79, 16, v18
	v_lshl_add_u32 v78, v78, 7, v150
	v_lshl_add_u32 v79, v79, 7, v151
	s_mov_b32 m0, s78
	s_add_i32 s43, s78, 0x400
	global_load_lds_dwordx4 v78, s[50:51]
	s_mov_b32 m0, s43
	s_nop 0
	global_load_lds_dwordx4 v79, s[50:51]
	s_waitcnt vmcnt(13)
	v_add_u32_e32 v54, s98, v59
	v_add_u32_e32 v55, s98, v60
	v_add_u32_e32 v56, s98, v61
	v_add_u32_e32 v57, s98, v62
	ds_read_b64_tr_b4 v[46:47], v160 offset:512
	ds_read_b64_tr_b4 v[48:49], v160 offset:1536
	ds_read_b64_tr_b4 v[122:123], v54
	ds_read_b64_tr_b4 v[124:125], v55
	ds_read_b64_tr_b4 v[126:127], v56
	ds_read_b64_tr_b4 v[128:129], v57
	s_waitcnt lgkmcnt(6)
; #define TR4(p_) __builtin_amdgcn_ds_read_tr4_b64_v2i32((LAS v2i*)(p_))
; #define VDMA(st_, k_) do { _Pragma("unroll") for (int i_ = 0; i_ < 4; ++i_) { \
;         const unsigned off_ = (unsigned)((st_) >> 2) * (16384u * 128u) + (PE_ID(E, 4 * ((st_) & 3) + i_) << 7) + ((i_ & 1) ? cx1 : cx0); \
;         __builtin_amdgcn_global_load_lds((const unsigned*)(V4 + off_), (LAS unsigned*)(ldsb + BUF[k_] + 1024 * i_), 16, 0, 0); } } while (0)
; __device__ __forceinline__ void peer_v_tokens(int j, const LAS unsigned short* EL, const LAS unsigned char* AL  , const LAS float* ASC  , const LAS int* SAL  , ...
;     ...
; #pragma unroll
;         for (int st = 0; st < 16; ++st) {
;             const int p = st >> 2, q = st & 3;
;             if (st < 14) VDMA(st + 2, (st + 2) % 3);
;             if (st < 14) asm volatile("s_waitcnt vmcnt(8)" ::: "memory");
;             else if (st == 14) asm volatile("s_waitcnt vmcnt(4)" ::: "memory");
;             else asm volatile("s_waitcnt vmcnt(0)" ::: "memory");
;             if (q == 0) {
; #pragma unroll
;                 for (int r = 0; r < 4; ++r) { accH[r] = 0; accL[r] = 0; } }
; #pragma unroll
;             for (int tp = 0; tp < 2; ++tp) {
;                 const v2i ao = TR4(ATL + (2 * q + tp) * 128 + 8 * s16), ah = TR4(ATL + 1024 + (2 * q + tp) * 128 + 8 * s16);
; #pragma unroll
;                 for (int r = 0; r < 4; ++r) {
;                     const v2i d = TR4(ldsb + BUF[st % 3] + 2048 * tp + roff[r]);
;                     accH[r] = __builtin_amdgcn_sdot8(d.x, ah.x, accH[r], false); accH[r] = __builtin_amdgcn_sdot8(d.y, ah.y, accH[r], false);
;                     accL[r] = __builtin_amdgcn_sdot8(d.x, ao.x, accL[r], false); accL[r] = __builtin_amdgcn_sdot8(d.y, ao.y, accL[r], false);
;                 }
	v_dot8c_i32_i4_e32 v38, v130, v52
	v_dot8c_i32_i4_e32 v39, v130, v50
	v_dot8c_i32_i4_e32 v40, v132, v52
	v_dot8c_i32_i4_e32 v41, v132, v50
	v_dot8c_i32_i4_e32 v42, v134, v52
	v_dot8c_i32_i4_e32 v43, v134, v50
	v_dot8c_i32_i4_e32 v44, v136, v52
	v_dot8c_i32_i4_e32 v45, v136, v50
	v_dot8c_i32_i4_e32 v38, v131, v53
	v_dot8c_i32_i4_e32 v39, v131, v51
	v_dot8c_i32_i4_e32 v40, v133, v53
	v_dot8c_i32_i4_e32 v41, v133, v51
	v_dot8c_i32_i4_e32 v42, v135, v53
	v_dot8c_i32_i4_e32 v43, v135, v51
	v_dot8c_i32_i4_e32 v44, v137, v53
	v_dot8c_i32_i4_e32 v45, v137, v51
	v_and_b32_e32 v78, 0xffff, v19
	v_lshrrev_b32_e32 v79, 16, v19
	v_lshl_add_u32 v78, v78, 7, v150
	v_lshl_add_u32 v79, v79, 7, v151
	s_mov_b32 m0, s79
	s_add_i32 s43, s79, 0x400
	global_load_lds_dwordx4 v78, s[50:51]
	s_mov_b32 m0, s43
	s_nop 0
	global_load_lds_dwordx4 v79, s[50:51]
	s_waitcnt vmcnt(8)
	v_add_u32_e32 v54, s99, v59
	v_add_u32_e32 v55, s99, v60
	v_add_u32_e32 v56, s99, v61
	v_add_u32_e32 v57, s99, v62
	ds_read_b64_tr_b4 v[50:51], v160 offset:640
	ds_read_b64_tr_b4 v[52:53], v160 offset:1664
	ds_read_b64_tr_b4 v[130:131], v54
	ds_read_b64_tr_b4 v[132:133], v55
	ds_read_b64_tr_b4 v[134:135], v56
	ds_read_b64_tr_b4 v[136:137], v57
	s_waitcnt lgkmcnt(6)
	v_dot8c_i32_i4_e32 v38, v122, v48
	v_dot8c_i32_i4_e32 v39, v122, v46
	v_dot8c_i32_i4_e32 v40, v124, v48
	v_dot8c_i32_i4_e32 v41, v124, v46
	v_dot8c_i32_i4_e32 v42, v126, v48
	v_dot8c_i32_i4_e32 v43, v126, v46
	v_dot8c_i32_i4_e32 v44, v128, v48
	v_dot8c_i32_i4_e32 v45, v128, v46
	v_dot8c_i32_i4_e32 v38, v123, v49
	v_dot8c_i32_i4_e32 v39, v123, v47
	v_dot8c_i32_i4_e32 v40, v125, v49
	v_dot8c_i32_i4_e32 v41, v125, v47
	v_dot8c_i32_i4_e32 v42, v127, v49
	v_dot8c_i32_i4_e32 v43, v127, v47
	v_dot8c_i32_i4_e32 v44, v129, v49
	v_dot8c_i32_i4_e32 v45, v129, v47
	s_waitcnt lgkmcnt(15)
	v_add_u32_e32 v143, 8, v139
	v_and_b32_e32 v142, 15, v143
	v_xor_b32_e32 v142, 8, v142
	v_bfe_u32 v144, v143, 4, 4
	v_mul_lo_u32 v142, v142, s92
	v_mul_lo_u32 v144, v144, s92
	v_mov_b32_e32 v143, v142
	v_mov_b32_e32 v145, v144
	ds_write2st64_b64 v159, v[142:143], v[144:145] offset1:2
	v_and_b32_e32 v78, 0xffff, v20
	v_lshrrev_b32_e32 v79, 16, v20
	v_lshl_add_u32 v78, v78, 7, v150
	v_lshl_add_u32 v79, v79, 7, v151
	s_mov_b32 m0, s98
	s_add_i32 s43, s98, 0x400
	global_load_lds_dwordx4 v78, s[50:51]
	s_mov_b32 m0, s43
	s_nop 0
	global_load_lds_dwordx4 v79, s[50:51]
	s_waitcnt vmcnt(8)
	v_add_u32_e32 v54, s76, v59
	v_add_u32_e32 v55, s76, v60
	v_add_u32_e32 v56, s76, v61
	v_add_u32_e32 v57, s76, v62
	ds_read_b64_tr_b4 v[46:47], v160 offset:768
	ds_read_b64_tr_b4 v[48:49], v160 offset:1792
	ds_read_b64_tr_b4 v[122:123], v54
	ds_read_b64_tr_b4 v[124:125], v55
	ds_read_b64_tr_b4 v[126:127], v56
	ds_read_b64_tr_b4 v[128:129], v57
	s_waitcnt lgkmcnt(7)
	v_dot8c_i32_i4_e32 v38, v130, v52
	v_dot8c_i32_i4_e32 v39, v130, v50
	v_dot8c_i32_i4_e32 v40, v132, v52
	v_dot8c_i32_i4_e32 v41, v132, v50
	v_dot8c_i32_i4_e32 v42, v134, v52
	v_dot8c_i32_i4_e32 v43, v134, v50
	v_dot8c_i32_i4_e32 v44, v136, v52
	v_dot8c_i32_i4_e32 v45, v136, v50
	v_dot8c_i32_i4_e32 v38, v131, v53
	v_dot8c_i32_i4_e32 v39, v131, v51
	v_dot8c_i32_i4_e32 v40, v133, v53
	v_dot8c_i32_i4_e32 v41, v133, v51
	v_dot8c_i32_i4_e32 v42, v135, v53
	v_dot8c_i32_i4_e32 v43, v135, v51
	v_dot8c_i32_i4_e32 v44, v137, v53
	v_dot8c_i32_i4_e32 v45, v137, v51
	v_and_b32_e32 v78, 0xffff, v21
	v_lshrrev_b32_e32 v79, 16, v21
	v_lshl_add_u32 v78, v78, 7, v150
	v_lshl_add_u32 v79, v79, 7, v151
	s_mov_b32 m0, s99
	s_add_i32 s43, s99, 0x400
	global_load_lds_dwordx4 v78, s[50:51]
	s_mov_b32 m0, s43
	s_nop 0
	global_load_lds_dwordx4 v79, s[50:51]
	s_waitcnt vmcnt(8)
	v_add_u32_e32 v54, s77, v59
	v_add_u32_e32 v55, s77, v60
	v_add_u32_e32 v56, s77, v61
	v_add_u32_e32 v57, s77, v62
	ds_read_b64_tr_b4 v[50:51], v160 offset:896
	ds_read_b64_tr_b4 v[52:53], v160 offset:1920
	ds_read_b64_tr_b4 v[130:131], v54
	ds_read_b64_tr_b4 v[132:133], v55
	ds_read_b64_tr_b4 v[134:135], v56
	ds_read_b64_tr_b4 v[136:137], v57
	s_waitcnt lgkmcnt(6)
	v_dot8c_i32_i4_e32 v38, v122, v48
	v_dot8c_i32_i4_e32 v39, v122, v46
	v_dot8c_i32_i4_e32 v40, v124, v48
	v_dot8c_i32_i4_e32 v41, v124, v46
	v_dot8c_i32_i4_e32 v42, v126, v48
	v_dot8c_i32_i4_e32 v43, v126, v46
	v_dot8c_i32_i4_e32 v44, v128, v48
	v_dot8c_i32_i4_e32 v45, v128, v46
	v_dot8c_i32_i4_e32 v38, v123, v49
	v_dot8c_i32_i4_e32 v39, v123, v47
	v_dot8c_i32_i4_e32 v40, v125, v49
	v_dot8c_i32_i4_e32 v41, v125, v47
	v_dot8c_i32_i4_e32 v42, v127, v49
	v_dot8c_i32_i4_e32 v43, v127, v47
	v_dot8c_i32_i4_e32 v44, v129, v49
	v_dot8c_i32_i4_e32 v45, v129, v47
	v_and_b32_e32 v78, 0xffff, v22
	v_lshrrev_b32_e32 v79, 16, v22
	v_lshl_add_u32 v78, v78, 7, v150
	v_lshl_add_u32 v79, v79, 7, v151
	s_mov_b32 m0, s76
	s_add_i32 s43, s76, 0x400
	global_load_lds_dwordx4 v78, s[50:51]
	s_mov_b32 m0, s43
	s_nop 0
	global_load_lds_dwordx4 v79, s[50:51]
	s_waitcnt vmcnt(8)
	v_add_u32_e32 v54, s78, v59
	v_add_u32_e32 v55, s78, v60
	v_add_u32_e32 v56, s78, v61
	v_add_u32_e32 v57, s78, v62
	ds_read_b64_tr_b4 v[46:47], v160
	ds_read_b64_tr_b4 v[48:49], v160 offset:1024
	ds_read_b64_tr_b4 v[122:123], v54
	ds_read_b64_tr_b4 v[124:125], v55
	ds_read_b64_tr_b4 v[126:127], v56
	ds_read_b64_tr_b4 v[128:129], v57
	s_waitcnt lgkmcnt(6)
	v_dot8c_i32_i4_e32 v38, v130, v52
	v_dot8c_i32_i4_e32 v39, v130, v50
	v_dot8c_i32_i4_e32 v40, v132, v52
	v_dot8c_i32_i4_e32 v41, v132, v50
	v_dot8c_i32_i4_e32 v42, v134, v52
	v_dot8c_i32_i4_e32 v43, v134, v50
	v_dot8c_i32_i4_e32 v44, v136, v52
	v_dot8c_i32_i4_e32 v45, v136, v50
	v_dot8c_i32_i4_e32 v38, v131, v53
	v_dot8c_i32_i4_e32 v39, v131, v51
	v_dot8c_i32_i4_e32 v40, v133, v53
	v_dot8c_i32_i4_e32 v41, v133, v51
	v_dot8c_i32_i4_e32 v42, v135, v53
	v_dot8c_i32_i4_e32 v43, v135, v51
	v_dot8c_i32_i4_e32 v44, v137, v53
	v_dot8c_i32_i4_e32 v45, v137, v51
	s_nop 3
	s_waitcnt lgkmcnt(15)
; #define LAS __attribute__((address_space(3)))
; __device__ __forceinline__ bf16 f2bf(float f) { return (bf16)f2bfu(f); }
; #define TR4(p_) __builtin_amdgcn_ds_read_tr4_b64_v2i32((LAS v2i*)(p_))
; #define CFENCE() asm volatile("" ::: "memory")
; __device__ __forceinline__ void peer_v_tokens(int j, const LAS unsigned short* EL, const LAS unsigned char* AL  , const LAS float* ASC  , const LAS int* SAL  , ...
;     ...
; #pragma unroll
;         for (int st = 0; st < 16; ++st) {
;             const int p = st >> 2, q = st & 3;
;             if (st < 14) VDMA(st + 2, (st + 2) % 3);
;             if (st < 14) asm volatile("s_waitcnt vmcnt(8)" ::: "memory");
;             else if (st == 14) asm volatile("s_waitcnt vmcnt(4)" ::: "memory");
;             else asm volatile("s_waitcnt vmcnt(0)" ::: "memory");
;             if (q == 0) {
; #pragma unroll
;                 for (int r = 0; r < 4; ++r) { accH[r] = 0; accL[r] = 0; } }
; #pragma unroll
;             for (int tp = 0; tp < 2; ++tp) {
;                 const v2i ao = TR4(ATL + (2 * q + tp) * 128 + 8 * s16), ah = TR4(ATL + 1024 + (2 * q + tp) * 128 + 8 * s16);
; #pragma unroll
;                 for (int r = 0; r < 4; ++r) {
;                     const v2i d = TR4(ldsb + BUF[st % 3] + 2048 * tp + roff[r]);
;                     accH[r] = __builtin_amdgcn_sdot8(d.x, ah.x, accH[r], false); accH[r] = __builtin_amdgcn_sdot8(d.y, ah.y, accH[r], false);
;                     accL[r] = __builtin_amdgcn_sdot8(d.x, ao.x, accL[r], false); accL[r] = __builtin_amdgcn_sdot8(d.y, ao.y, accL[r], false);
;                 }
;             }
;             asm volatile("s_waitcnt lgkmcnt(0)" ::: "memory");
;             if (q == 3) {
; #pragma unroll
;                 for (int r = 0; r < 4; ++r) STASH[256 * p + 16 * (grp + 4 * r) + pc] = f2bf(asc * (float)(2 * ((accH[r] << 4) + accL[r]) + sa));
;             }
;         }
;         CFENCE();
;         {
;             float4 v[4]; float ss = 0.f;
; #pragma unroll
;             for (int jq = 0; jq < 4; ++jq) { typedef unsigned u2v __attribute__((ext_vector_type(2))); const u2v pw = *(const LAS u2v*)(STASH + 4 * lane + 256 * jq); const uint2 hw = hv[jq];
	v_lshlrev_b32_e32 v38, 5, v38
	v_lshlrev_b32_e32 v39, 1, v39
	v_add3_u32 v38, v39, v229, v38
	v_cvt_f32_i32_e32 v38, v38
	v_mul_f32_e32 v38, v228, v38
	v_lshlrev_b32_e32 v40, 5, v40
	v_lshlrev_b32_e32 v41, 1, v41
	v_add3_u32 v40, v41, v229, v40
	v_cvt_f32_i32_e32 v40, v40
	v_mul_f32_e32 v40, v228, v40
	v_lshlrev_b32_e32 v42, 5, v42
	v_lshlrev_b32_e32 v43, 1, v43
	v_add3_u32 v42, v43, v229, v42
	v_cvt_f32_i32_e32 v42, v42
	v_mul_f32_e32 v42, v228, v42
	v_lshlrev_b32_e32 v44, 5, v44
	v_lshlrev_b32_e32 v45, 1, v45
	v_add3_u32 v44, v45, v229, v44
	v_cvt_f32_i32_e32 v44, v44
	v_mul_f32_e32 v44, v228, v44
	v_cvt_pk_bf16_f32 v192, v38, v40
	v_cvt_pk_bf16_f32 v193, v42, v44
	ds_read_b128 v[252:255], v156 offset:1024
	s_add_i32 s44, s40, 8
	s_ashr_i32 s45, s44, 31
	s_lshl_b64 s[44:45], s[44:45], 12
	v_lshl_add_u64 v[80:81], v[36:37], 0, s[44:45]
	s_waitcnt lgkmcnt(0)
	v_mul_f32_e32 v248, v248, v252
	v_mul_f32_e32 v249, v249, v253
	v_mul_f32_e32 v250, v250, v254
	v_mul_f32_e32 v251, v251, v255
	global_store_dwordx4 v[80:81], v[248:251], off offset:3072 nt
	v_add_u32_e32 v147, 8, v140
	v_and_b32_e32 v146, 15, v147
	v_xor_b32_e32 v146, 8, v146
	v_bfe_u32 v148, v147, 4, 4
	v_mul_lo_u32 v146, v146, s92
	v_mul_lo_u32 v148, v148, s92
	v_mov_b32_e32 v147, v146
	v_mov_b32_e32 v149, v148
	ds_write2st64_b64 v77, v[146:147], v[148:149] offset1:2
	v_add_u32_e32 v138, 0x1400, v74
	ds_read_u8 v139, v138
	v_add_u32_e32 v141, 0x1400, v73
	ds_read_u8 v140, v141
	s_add_i32 s43, s67, 128
	v_mov_b32_e32 v138, s43
	ds_read2st64_b32 v[228:229], v138 offset1:1
	ds_read_b128 v[26:29], v227 offset:10240
	ds_read_b128 v[30:33], v227 offset:10256
	v_mov_b32_e32 v38, 0
	v_mov_b32_e32 v39, 0
	v_mov_b32_e32 v40, 0
	v_mov_b32_e32 v41, 0
	v_mov_b32_e32 v42, 0
	v_mov_b32_e32 v43, 0
	v_mov_b32_e32 v44, 0
	v_mov_b32_e32 v45, 0
	v_and_b32_e32 v78, 0xffff, v23
	v_lshrrev_b32_e32 v79, 16, v23
	v_lshl_add_u32 v78, v78, 7, v150
	v_lshl_add_u32 v79, v79, 7, v151
	s_mov_b32 m0, s77
	s_add_i32 s43, s77, 0x400
	global_load_lds_dwordx4 v78, s[50:51]
	s_mov_b32 m0, s43
	s_nop 0
	global_load_lds_dwordx4 v79, s[50:51]
	s_waitcnt vmcnt(9)
	v_add_u32_e32 v54, s79, v59
	v_add_u32_e32 v55, s79, v60
	v_add_u32_e32 v56, s79, v61
	v_add_u32_e32 v57, s79, v62
	ds_read_b64_tr_b4 v[50:51], v160 offset:128
	ds_read_b64_tr_b4 v[52:53], v160 offset:1152
	ds_read_b64_tr_b4 v[130:131], v54
	ds_read_b64_tr_b4 v[132:133], v55
	ds_read_b64_tr_b4 v[134:135], v56
	ds_read_b64_tr_b4 v[136:137], v57
	s_waitcnt lgkmcnt(13)
	v_dot8c_i32_i4_e32 v38, v122, v48
	v_dot8c_i32_i4_e32 v39, v122, v46
	v_dot8c_i32_i4_e32 v40, v124, v48
	v_dot8c_i32_i4_e32 v41, v124, v46
	v_dot8c_i32_i4_e32 v42, v126, v48
	v_dot8c_i32_i4_e32 v43, v126, v46
	v_dot8c_i32_i4_e32 v44, v128, v48
	v_dot8c_i32_i4_e32 v45, v128, v46
	v_dot8c_i32_i4_e32 v38, v123, v49
	v_dot8c_i32_i4_e32 v39, v123, v47
	v_dot8c_i32_i4_e32 v40, v125, v49
	v_dot8c_i32_i4_e32 v41, v125, v47
	v_dot8c_i32_i4_e32 v42, v127, v49
	v_dot8c_i32_i4_e32 v43, v127, v47
	v_dot8c_i32_i4_e32 v44, v129, v49
	v_dot8c_i32_i4_e32 v45, v129, v47
	v_and_b32_e32 v78, 0xffff, v24
	v_lshrrev_b32_e32 v79, 16, v24
	v_lshl_add_u32 v78, v78, 7, v150
	v_lshl_add_u32 v79, v79, 7, v151
	s_mov_b32 m0, s78
	s_add_i32 s43, s78, 0x400
	global_load_lds_dwordx4 v78, s[50:51]
	s_mov_b32 m0, s43
	s_nop 0
	global_load_lds_dwordx4 v79, s[50:51]
	s_waitcnt vmcnt(9)
	v_add_u32_e32 v54, s98, v59
	v_add_u32_e32 v55, s98, v60
	v_add_u32_e32 v56, s98, v61
	v_add_u32_e32 v57, s98, v62
	ds_read_b64_tr_b4 v[46:47], v160 offset:256
	ds_read_b64_tr_b4 v[48:49], v160 offset:1280
	ds_read_b64_tr_b4 v[122:123], v54
	ds_read_b64_tr_b4 v[124:125], v55
	ds_read_b64_tr_b4 v[126:127], v56
	ds_read_b64_tr_b4 v[128:129], v57
	s_waitcnt lgkmcnt(6)
	v_dot8c_i32_i4_e32 v38, v130, v52
	v_dot8c_i32_i4_e32 v39, v130, v50
	v_dot8c_i32_i4_e32 v40, v132, v52
	v_dot8c_i32_i4_e32 v41, v132, v50
	v_dot8c_i32_i4_e32 v42, v134, v52
	v_dot8c_i32_i4_e32 v43, v134, v50
	v_dot8c_i32_i4_e32 v44, v136, v52
	v_dot8c_i32_i4_e32 v45, v136, v50
	v_dot8c_i32_i4_e32 v38, v131, v53
	v_dot8c_i32_i4_e32 v39, v131, v51
	v_dot8c_i32_i4_e32 v40, v133, v53
	v_dot8c_i32_i4_e32 v41, v133, v51
	v_dot8c_i32_i4_e32 v42, v135, v53
	v_dot8c_i32_i4_e32 v43, v135, v51
	v_dot8c_i32_i4_e32 v44, v137, v53
	v_dot8c_i32_i4_e32 v45, v137, v51
	ds_write_b16 v65, v178
	ds_write_b16_d16_hi v65, v178 offset:128
	ds_write_b16 v65, v179 offset:256
	ds_write_b16_d16_hi v65, v179 offset:384
	ds_write_b16 v65, v180 offset:512
	ds_write_b16_d16_hi v65, v180 offset:640
	ds_write_b16 v65, v181 offset:768
	ds_write_b16_d16_hi v65, v181 offset:896
	ds_write_b16 v65, v182 offset:1024
	ds_write_b16_d16_hi v65, v182 offset:1152
	ds_write_b16 v65, v183 offset:1280
	ds_write_b16_d16_hi v65, v183 offset:1408
	ds_write_b16 v65, v184 offset:1536
	ds_write_b16_d16_hi v65, v184 offset:1664
	ds_write_b16 v65, v185 offset:1792
	ds_write_b16_d16_hi v65, v185 offset:1920
	ds_read_b64 v[202:203], v154
	ds_read_b64 v[204:205], v154 offset:512
	ds_read_b64 v[206:207], v154 offset:1024
	ds_read_b64 v[208:209], v154 offset:1536
	v_and_b32_e32 v78, 0xffff, v25
	v_lshrrev_b32_e32 v79, 16, v25
	v_lshl_add_u32 v78, v78, 7, v150
	v_lshl_add_u32 v79, v79, 7, v151
	s_mov_b32 m0, s79
	s_add_i32 s43, s79, 0x400
	global_load_lds_dwordx4 v78, s[50:51]
	s_mov_b32 m0, s43
	s_nop 0
	global_load_lds_dwordx4 v79, s[50:51]
	s_waitcnt vmcnt(9)
	v_add_u32_e32 v54, s99, v59
	v_add_u32_e32 v55, s99, v60
	v_add_u32_e32 v56, s99, v61
	v_add_u32_e32 v57, s99, v62
	ds_read_b64_tr_b4 v[50:51], v160 offset:384
	ds_read_b64_tr_b4 v[52:53], v160 offset:1408
	ds_read_b64_tr_b4 v[130:131], v54
	ds_read_b64_tr_b4 v[132:133], v55
	ds_read_b64_tr_b4 v[134:135], v56
	ds_read_b64_tr_b4 v[136:137], v57
	s_waitcnt lgkmcnt(15)
; #define TR4(p_) __builtin_amdgcn_ds_read_tr4_b64_v2i32((LAS v2i*)(p_))
; #define VDMA(st_, k_) do { _Pragma("unroll") for (int i_ = 0; i_ < 4; ++i_) { \
;         const unsigned off_ = (unsigned)((st_) >> 2) * (16384u * 128u) + (PE_ID(E, 4 * ((st_) & 3) + i_) << 7) + ((i_ & 1) ? cx1 : cx0); \
;         __builtin_amdgcn_global_load_lds((const unsigned*)(V4 + off_), (LAS unsigned*)(ldsb + BUF[k_] + 1024 * i_), 16, 0, 0); } } while (0)
; __device__ __forceinline__ void peer_v_tokens(int j, const LAS unsigned short* EL, const LAS unsigned char* AL  , const LAS float* ASC  , const LAS int* SAL  , ...
;     ...
; #pragma unroll
;         for (int st = 0; st < 16; ++st) {
;             const int p = st >> 2, q = st & 3;
;             if (st < 14) VDMA(st + 2, (st + 2) % 3);
;             if (st < 14) asm volatile("s_waitcnt vmcnt(8)" ::: "memory");
;             else if (st == 14) asm volatile("s_waitcnt vmcnt(4)" ::: "memory");
;             else asm volatile("s_waitcnt vmcnt(0)" ::: "memory");
;             if (q == 0) {
; #pragma unroll
;                 for (int r = 0; r < 4; ++r) { accH[r] = 0; accL[r] = 0; } }
; #pragma unroll
;             for (int tp = 0; tp < 2; ++tp) {
;                 const v2i ao = TR4(ATL + (2 * q + tp) * 128 + 8 * s16), ah = TR4(ATL + 1024 + (2 * q + tp) * 128 + 8 * s16);
; #pragma unroll
;                 for (int r = 0; r < 4; ++r) {
;                     const v2i d = TR4(ldsb + BUF[st % 3] + 2048 * tp + roff[r]);
;                     accH[r] = __builtin_amdgcn_sdot8(d.x, ah.x, accH[r], false); accH[r] = __builtin_amdgcn_sdot8(d.y, ah.y, accH[r], false);
;                     accL[r] = __builtin_amdgcn_sdot8(d.x, ao.x, accL[r], false); accL[r] = __builtin_amdgcn_sdot8(d.y, ao.y, accL[r], false);
;                 }
	v_dot8c_i32_i4_e32 v38, v122, v48
	v_dot8c_i32_i4_e32 v39, v122, v46
	v_dot8c_i32_i4_e32 v40, v124, v48
	v_dot8c_i32_i4_e32 v41, v124, v46
	v_dot8c_i32_i4_e32 v42, v126, v48
	v_dot8c_i32_i4_e32 v43, v126, v46
	v_dot8c_i32_i4_e32 v44, v128, v48
	v_dot8c_i32_i4_e32 v45, v128, v46
	v_dot8c_i32_i4_e32 v38, v123, v49
	v_dot8c_i32_i4_e32 v39, v123, v47
	v_dot8c_i32_i4_e32 v40, v125, v49
	v_dot8c_i32_i4_e32 v41, v125, v47
	v_dot8c_i32_i4_e32 v42, v127, v49
	v_dot8c_i32_i4_e32 v43, v127, v47
	v_dot8c_i32_i4_e32 v44, v129, v49
	v_dot8c_i32_i4_e32 v45, v129, v47
	s_waitcnt lgkmcnt(15)
	v_and_b32_e32 v78, 0xffff, v26
	v_lshrrev_b32_e32 v79, 16, v26
	v_lshl_add_u32 v78, v78, 7, v150
	v_lshl_add_u32 v79, v79, 7, v151
	s_mov_b32 m0, s98
	s_add_i32 s43, s98, 0x400
	global_load_lds_dwordx4 v78, s[50:51]
	s_mov_b32 m0, s43
	s_nop 0
	global_load_lds_dwordx4 v79, s[50:51]
	s_waitcnt vmcnt(9)
	v_add_u32_e32 v54, s76, v59
	v_add_u32_e32 v55, s76, v60
	v_add_u32_e32 v56, s76, v61
	v_add_u32_e32 v57, s76, v62
	ds_read_b64_tr_b4 v[46:47], v160 offset:512
	ds_read_b64_tr_b4 v[48:49], v160 offset:1536
	ds_read_b64_tr_b4 v[122:123], v54
	ds_read_b64_tr_b4 v[124:125], v55
	ds_read_b64_tr_b4 v[126:127], v56
	ds_read_b64_tr_b4 v[128:129], v57
	s_waitcnt lgkmcnt(6)
	v_dot8c_i32_i4_e32 v38, v130, v52
	v_dot8c_i32_i4_e32 v39, v130, v50
	v_dot8c_i32_i4_e32 v40, v132, v52
	v_dot8c_i32_i4_e32 v41, v132, v50
	v_dot8c_i32_i4_e32 v42, v134, v52
	v_dot8c_i32_i4_e32 v43, v134, v50
	v_dot8c_i32_i4_e32 v44, v136, v52
	v_dot8c_i32_i4_e32 v45, v136, v50
	v_dot8c_i32_i4_e32 v38, v131, v53
	v_dot8c_i32_i4_e32 v39, v131, v51
	v_dot8c_i32_i4_e32 v40, v133, v53
	v_dot8c_i32_i4_e32 v41, v133, v51
	v_dot8c_i32_i4_e32 v42, v135, v53
	v_dot8c_i32_i4_e32 v43, v135, v51
	v_dot8c_i32_i4_e32 v44, v137, v53
	v_dot8c_i32_i4_e32 v45, v137, v51
	v_and_b32_e32 v78, 0xffff, v27
	v_lshrrev_b32_e32 v79, 16, v27
	v_lshl_add_u32 v78, v78, 7, v150
	v_lshl_add_u32 v79, v79, 7, v151
	s_mov_b32 m0, s99
	s_add_i32 s43, s99, 0x400
	global_load_lds_dwordx4 v78, s[50:51]
	s_mov_b32 m0, s43
	s_nop 0
	global_load_lds_dwordx4 v79, s[50:51]
	s_waitcnt vmcnt(8)
	v_add_u32_e32 v54, s77, v59
	v_add_u32_e32 v55, s77, v60
	v_add_u32_e32 v56, s77, v61
	v_add_u32_e32 v57, s77, v62
	ds_read_b64_tr_b4 v[50:51], v160 offset:640
	ds_read_b64_tr_b4 v[52:53], v160 offset:1664
	ds_read_b64_tr_b4 v[130:131], v54
	ds_read_b64_tr_b4 v[132:133], v55
	ds_read_b64_tr_b4 v[134:135], v56
	ds_read_b64_tr_b4 v[136:137], v57
	s_waitcnt lgkmcnt(6)
	v_dot8c_i32_i4_e32 v38, v122, v48
	v_dot8c_i32_i4_e32 v39, v122, v46
	v_dot8c_i32_i4_e32 v40, v124, v48
	v_dot8c_i32_i4_e32 v41, v124, v46
	v_dot8c_i32_i4_e32 v42, v126, v48
	v_dot8c_i32_i4_e32 v43, v126, v46
	v_dot8c_i32_i4_e32 v44, v128, v48
	v_dot8c_i32_i4_e32 v45, v128, v46
	v_dot8c_i32_i4_e32 v38, v123, v49
	v_dot8c_i32_i4_e32 v39, v123, v47
	v_dot8c_i32_i4_e32 v40, v125, v49
	v_dot8c_i32_i4_e32 v41, v125, v47
	v_dot8c_i32_i4_e32 v42, v127, v49
	v_dot8c_i32_i4_e32 v43, v127, v47
	v_dot8c_i32_i4_e32 v44, v129, v49
	v_dot8c_i32_i4_e32 v45, v129, v47
	s_waitcnt lgkmcnt(15)
	v_add_u32_e32 v143, 8, v139
	v_and_b32_e32 v142, 15, v143
	v_xor_b32_e32 v142, 8, v142
	v_bfe_u32 v144, v143, 4, 4
	v_mul_lo_u32 v142, v142, s92
	v_mul_lo_u32 v144, v144, s92
	v_mov_b32_e32 v143, v142
	v_mov_b32_e32 v145, v144
	ds_write2st64_b64 v159, v[142:143], v[144:145] offset1:2
	v_and_b32_e32 v78, 0xffff, v28
	v_lshrrev_b32_e32 v79, 16, v28
	v_lshl_add_u32 v78, v78, 7, v150
	v_lshl_add_u32 v79, v79, 7, v151
	s_mov_b32 m0, s76
	s_add_i32 s43, s76, 0x400
	global_load_lds_dwordx4 v78, s[50:51]
	s_mov_b32 m0, s43
	s_nop 0
	global_load_lds_dwordx4 v79, s[50:51]
	s_waitcnt vmcnt(8)
	v_add_u32_e32 v54, s78, v59
	v_add_u32_e32 v55, s78, v60
	v_add_u32_e32 v56, s78, v61
	v_add_u32_e32 v57, s78, v62
	ds_read_b64_tr_b4 v[46:47], v160 offset:768
	ds_read_b64_tr_b4 v[48:49], v160 offset:1792
	ds_read_b64_tr_b4 v[122:123], v54
	ds_read_b64_tr_b4 v[124:125], v55
	ds_read_b64_tr_b4 v[126:127], v56
	ds_read_b64_tr_b4 v[128:129], v57
	s_waitcnt lgkmcnt(7)
	v_dot8c_i32_i4_e32 v38, v130, v52
	v_dot8c_i32_i4_e32 v39, v130, v50
	v_dot8c_i32_i4_e32 v40, v132, v52
	v_dot8c_i32_i4_e32 v41, v132, v50
	v_dot8c_i32_i4_e32 v42, v134, v52
	v_dot8c_i32_i4_e32 v43, v134, v50
	v_dot8c_i32_i4_e32 v44, v136, v52
	v_dot8c_i32_i4_e32 v45, v136, v50
	v_dot8c_i32_i4_e32 v38, v131, v53
	v_dot8c_i32_i4_e32 v39, v131, v51
	v_dot8c_i32_i4_e32 v40, v133, v53
	v_dot8c_i32_i4_e32 v41, v133, v51
	v_dot8c_i32_i4_e32 v42, v135, v53
	v_dot8c_i32_i4_e32 v43, v135, v51
	v_dot8c_i32_i4_e32 v44, v137, v53
	v_dot8c_i32_i4_e32 v45, v137, v51
	v_and_b32_e32 v78, 0xffff, v29
	v_lshrrev_b32_e32 v79, 16, v29
	v_lshl_add_u32 v78, v78, 7, v150
	v_lshl_add_u32 v79, v79, 7, v151
	s_mov_b32 m0, s77
	s_add_i32 s43, s77, 0x400
	global_load_lds_dwordx4 v78, s[50:51]
	s_mov_b32 m0, s43
	s_nop 0
	global_load_lds_dwordx4 v79, s[50:51]
	s_waitcnt vmcnt(8)
	v_add_u32_e32 v54, s79, v59
	v_add_u32_e32 v55, s79, v60
	v_add_u32_e32 v56, s79, v61
	v_add_u32_e32 v57, s79, v62
	ds_read_b64_tr_b4 v[50:51], v160 offset:896
	ds_read_b64_tr_b4 v[52:53], v160 offset:1920
	ds_read_b64_tr_b4 v[130:131], v54
	ds_read_b64_tr_b4 v[132:133], v55
	ds_read_b64_tr_b4 v[134:135], v56
	ds_read_b64_tr_b4 v[136:137], v57
	s_waitcnt lgkmcnt(6)
; #define LAS __attribute__((address_space(3)))
; __device__ __forceinline__ bf16 f2bf(float f) { return (bf16)f2bfu(f); }
; #define CFENCE() asm volatile("" ::: "memory")
; __device__ __forceinline__ void peer_v_tokens(int j, const LAS unsigned short* EL, const LAS unsigned char* AL  , const LAS float* ASC  , const LAS int* SAL  , ...
;     ...
;                 for (int r = 0; r < 4; ++r) STASH[256 * p + 16 * (grp + 4 * r) + pc] = f2bf(asc * (float)(2 * ((accH[r] << 4) + accL[r]) + sa));
;             }
;         }
;         CFENCE();
;         {
;             float4 v[4]; float ss = 0.f;
; #pragma unroll
;             for (int jq = 0; jq < 4; ++jq) { typedef unsigned u2v __attribute__((ext_vector_type(2))); const u2v pw = *(const LAS u2v*)(STASH + 4 * lane + 256 * jq); const uint2 hw = hv[jq];
;                 v[jq] = make_float4(__uint_as_float(hw.x << 16) + __uint_as_float(pw.x << 16), __uint_as_float(hw.x & 0xffff0000u) + __uint_as_float(pw.x & 0xffff0000u),
;                                     __uint_as_float(hw.y << 16) + __uint_as_float(pw.y << 16), __uint_as_float(hw.y & 0xffff0000u) + __uint_as_float(pw.y & 0xffff0000u));
;                 ss += v[jq].x * v[jq].x + v[jq].y * v[jq].y + v[jq].z * v[jq].z + v[jq].w * v[jq].w; }
;             ss = wave_sum(ss);
;             const float r3 = rsqrtf(ss * (1.f / D) + EPS);
	v_dot8c_i32_i4_e32 v38, v122, v48
	v_dot8c_i32_i4_e32 v39, v122, v46
	v_dot8c_i32_i4_e32 v40, v124, v48
	v_dot8c_i32_i4_e32 v41, v124, v46
	v_dot8c_i32_i4_e32 v42, v126, v48
	v_dot8c_i32_i4_e32 v43, v126, v46
	v_dot8c_i32_i4_e32 v44, v128, v48
	v_dot8c_i32_i4_e32 v45, v128, v46
	v_dot8c_i32_i4_e32 v38, v123, v49
	v_dot8c_i32_i4_e32 v39, v123, v47
	v_dot8c_i32_i4_e32 v40, v125, v49
	v_dot8c_i32_i4_e32 v41, v125, v47
	v_dot8c_i32_i4_e32 v42, v127, v49
	v_dot8c_i32_i4_e32 v43, v127, v47
	v_dot8c_i32_i4_e32 v44, v129, v49
	v_dot8c_i32_i4_e32 v45, v129, v47
	v_and_b32_e32 v78, 0xffff, v30
	v_lshrrev_b32_e32 v79, 16, v30
	v_lshl_add_u32 v78, v78, 7, v150
	v_lshl_add_u32 v79, v79, 7, v151
	s_mov_b32 m0, s78
	s_add_i32 s43, s78, 0x400
	global_load_lds_dwordx4 v78, s[50:51]
	s_mov_b32 m0, s43
	s_nop 0
	global_load_lds_dwordx4 v79, s[50:51]
	s_waitcnt vmcnt(8)
	v_add_u32_e32 v54, s98, v59
	v_add_u32_e32 v55, s98, v60
	v_add_u32_e32 v56, s98, v61
	v_add_u32_e32 v57, s98, v62
	ds_read_b64_tr_b4 v[46:47], v160
	ds_read_b64_tr_b4 v[48:49], v160 offset:1024
	ds_read_b64_tr_b4 v[122:123], v54
	ds_read_b64_tr_b4 v[124:125], v55
	ds_read_b64_tr_b4 v[126:127], v56
	ds_read_b64_tr_b4 v[128:129], v57
	s_waitcnt lgkmcnt(6)
	v_dot8c_i32_i4_e32 v38, v130, v52
	v_dot8c_i32_i4_e32 v39, v130, v50
	v_dot8c_i32_i4_e32 v40, v132, v52
	v_dot8c_i32_i4_e32 v41, v132, v50
	v_dot8c_i32_i4_e32 v42, v134, v52
	v_dot8c_i32_i4_e32 v43, v134, v50
	v_dot8c_i32_i4_e32 v44, v136, v52
	v_dot8c_i32_i4_e32 v45, v136, v50
	v_dot8c_i32_i4_e32 v38, v131, v53
	v_dot8c_i32_i4_e32 v39, v131, v51
	v_dot8c_i32_i4_e32 v40, v133, v53
	v_dot8c_i32_i4_e32 v41, v133, v51
	v_dot8c_i32_i4_e32 v42, v135, v53
	v_dot8c_i32_i4_e32 v43, v135, v51
	v_dot8c_i32_i4_e32 v44, v137, v53
	v_dot8c_i32_i4_e32 v45, v137, v51
	s_nop 3
	s_waitcnt lgkmcnt(15)
	v_lshlrev_b32_e32 v38, 5, v38
	v_lshlrev_b32_e32 v39, 1, v39
	v_add3_u32 v38, v39, v229, v38
	v_cvt_f32_i32_e32 v38, v38
	v_mul_f32_e32 v38, v228, v38
	v_lshlrev_b32_e32 v40, 5, v40
	v_lshlrev_b32_e32 v41, 1, v41
	v_add3_u32 v40, v41, v229, v40
	v_cvt_f32_i32_e32 v40, v40
	v_mul_f32_e32 v40, v228, v40
	v_lshlrev_b32_e32 v42, 5, v42
	v_lshlrev_b32_e32 v43, 1, v43
	v_add3_u32 v42, v43, v229, v42
	v_cvt_f32_i32_e32 v42, v42
	v_mul_f32_e32 v42, v228, v42
	v_lshlrev_b32_e32 v44, 5, v44
	v_lshlrev_b32_e32 v45, 1, v45
	v_add3_u32 v44, v45, v229, v44
	v_cvt_f32_i32_e32 v44, v44
	v_mul_f32_e32 v44, v228, v44
	v_cvt_pk_bf16_f32 v162, v38, v40
	v_cvt_pk_bf16_f32 v163, v42, v44
	v_add_u32_e32 v147, 8, v140
	v_and_b32_e32 v146, 15, v147
	v_xor_b32_e32 v146, 8, v146
	v_bfe_u32 v148, v147, 4, 4
	v_mul_lo_u32 v146, v146, s92
	v_mul_lo_u32 v148, v148, s92
	v_mov_b32_e32 v147, v146
	v_mov_b32_e32 v149, v148
	ds_write2st64_b64 v77, v[146:147], v[148:149] offset1:2
	v_add_u32_e32 v138, 0x1000, v74
	ds_read_u8 v139, v138
	v_add_u32_e32 v141, 0x1000, v73
	ds_read_u8 v140, v141
	s_add_i32 s43, s67, 160
	v_mov_b32_e32 v138, s43
	ds_read2st64_b32 v[228:229], v138 offset1:1
	ds_read_b128 v[18:21], v227 offset:8192
	ds_read_b128 v[22:25], v227 offset:8208
	v_add_u32_e32 v152, 0x200000, v63
	v_add_u32_e32 v153, 0x200000, v64
	v_mov_b32_e32 v38, 0
	v_mov_b32_e32 v39, 0
	v_mov_b32_e32 v40, 0
	v_mov_b32_e32 v41, 0
	v_mov_b32_e32 v42, 0
	v_mov_b32_e32 v43, 0
	v_mov_b32_e32 v44, 0
	v_mov_b32_e32 v45, 0
	v_and_b32_e32 v78, 0xffff, v31
	v_lshrrev_b32_e32 v79, 16, v31
	v_lshl_add_u32 v78, v78, 7, v150
	v_lshl_add_u32 v79, v79, 7, v151
	s_mov_b32 m0, s79
	s_add_i32 s43, s79, 0x400
	global_load_lds_dwordx4 v78, s[50:51]
	s_mov_b32 m0, s43
	s_nop 0
	global_load_lds_dwordx4 v79, s[50:51]
	s_waitcnt vmcnt(8)
	v_add_u32_e32 v54, s99, v59
	v_add_u32_e32 v55, s99, v60
	v_add_u32_e32 v56, s99, v61
	v_add_u32_e32 v57, s99, v62
	ds_read_b64_tr_b4 v[50:51], v160 offset:128
	ds_read_b64_tr_b4 v[52:53], v160 offset:1152
	ds_read_b64_tr_b4 v[130:131], v54
	ds_read_b64_tr_b4 v[132:133], v55
	ds_read_b64_tr_b4 v[134:135], v56
	ds_read_b64_tr_b4 v[136:137], v57
	s_waitcnt lgkmcnt(12)
	s_waitcnt vmcnt(35) lgkmcnt(15)
	v_lshlrev_b32_e32 v210, 16, v194
	v_and_b32_e32 v211, 0xffff0000, v194
	v_lshlrev_b32_e32 v142, 16, v202
	v_and_b32_e32 v143, 0xffff0000, v202
	v_add_f32_e32 v210, v210, v142
	v_add_f32_e32 v211, v211, v143
	v_lshlrev_b32_e32 v212, 16, v195
	v_and_b32_e32 v213, 0xffff0000, v195
	v_lshlrev_b32_e32 v142, 16, v203
	v_and_b32_e32 v143, 0xffff0000, v203
	v_add_f32_e32 v212, v212, v142
	v_add_f32_e32 v213, v213, v143
	v_lshlrev_b32_e32 v214, 16, v196
	v_and_b32_e32 v215, 0xffff0000, v196
	v_lshlrev_b32_e32 v142, 16, v204
	v_and_b32_e32 v143, 0xffff0000, v204
	v_add_f32_e32 v214, v214, v142
	v_add_f32_e32 v215, v215, v143
	v_lshlrev_b32_e32 v216, 16, v197
	v_and_b32_e32 v217, 0xffff0000, v197
	v_lshlrev_b32_e32 v142, 16, v205
	v_and_b32_e32 v143, 0xffff0000, v205
	v_add_f32_e32 v216, v216, v142
	v_add_f32_e32 v217, v217, v143
	v_lshlrev_b32_e32 v218, 16, v198
	v_and_b32_e32 v219, 0xffff0000, v198
	v_lshlrev_b32_e32 v142, 16, v206
	v_and_b32_e32 v143, 0xffff0000, v206
	v_add_f32_e32 v218, v218, v142
	v_add_f32_e32 v219, v219, v143
	v_lshlrev_b32_e32 v220, 16, v199
	v_and_b32_e32 v221, 0xffff0000, v199
	v_lshlrev_b32_e32 v142, 16, v207
	v_and_b32_e32 v143, 0xffff0000, v207
	v_add_f32_e32 v220, v220, v142
	v_add_f32_e32 v221, v221, v143
	v_lshlrev_b32_e32 v222, 16, v200
	v_and_b32_e32 v223, 0xffff0000, v200
	v_lshlrev_b32_e32 v142, 16, v208
	v_and_b32_e32 v143, 0xffff0000, v208
	v_add_f32_e32 v222, v222, v142
	v_add_f32_e32 v223, v223, v143
	v_lshlrev_b32_e32 v224, 16, v201
	v_and_b32_e32 v225, 0xffff0000, v201
	v_lshlrev_b32_e32 v142, 16, v209
	v_and_b32_e32 v143, 0xffff0000, v209
	v_add_f32_e32 v224, v224, v142
; #define LAS __attribute__((address_space(3)))
; #define TR4(p_) __builtin_amdgcn_ds_read_tr4_b64_v2i32((LAS v2i*)(p_))
; __device__ __forceinline__ void peer_v_tokens(int j, const LAS unsigned short* EL, const LAS unsigned char* AL  , const LAS float* ASC  , const LAS int* SAL  , ...
;     ...
; #pragma unroll
;         for (int st = 0; st < 16; ++st) {
;             const int p = st >> 2, q = st & 3;
;             if (st < 14) VDMA(st + 2, (st + 2) % 3);
;             if (st < 14) asm volatile("s_waitcnt vmcnt(8)" ::: "memory");
;             else if (st == 14) asm volatile("s_waitcnt vmcnt(4)" ::: "memory");
;             else asm volatile("s_waitcnt vmcnt(0)" ::: "memory");
;             if (q == 0) {
; #pragma unroll
;                 for (int r = 0; r < 4; ++r) { accH[r] = 0; accL[r] = 0; } }
; #pragma unroll
;             for (int tp = 0; tp < 2; ++tp) {
;                 const v2i ao = TR4(ATL + (2 * q + tp) * 128 + 8 * s16), ah = TR4(ATL + 1024 + (2 * q + tp) * 128 + 8 * s16);
; #pragma unroll
;                 for (int r = 0; r < 4; ++r) {
;                     const v2i d = TR4(ldsb + BUF[st % 3] + 2048 * tp + roff[r]);
;                     accH[r] = __builtin_amdgcn_sdot8(d.x, ah.x, accH[r], false); accH[r] = __builtin_amdgcn_sdot8(d.y, ah.y, accH[r], false);
;                     accL[r] = __builtin_amdgcn_sdot8(d.x, ao.x, accL[r], false); accL[r] = __builtin_amdgcn_sdot8(d.y, ao.y, accL[r], false);
;                 }
;     ...
;         {
;             float4 v[4]; float ss = 0.f;
; #pragma unroll
;             for (int jq = 0; jq < 4; ++jq) { typedef unsigned u2v __attribute__((ext_vector_type(2))); const u2v pw = *(const LAS u2v*)(STASH + 4 * lane + 256 * jq); const uint2 hw = hv[jq];
;                 v[jq] = make_float4(__uint_as_float(hw.x << 16) + __uint_as_float(pw.x << 16), __uint_as_float(hw.x & 0xffff0000u) + __uint_as_float(pw.x & 0xffff0000u),
;                                     __uint_as_float(hw.y << 16) + __uint_as_float(pw.y << 16), __uint_as_float(hw.y & 0xffff0000u) + __uint_as_float(pw.y & 0xffff0000u));
;                 ss += v[jq].x * v[jq].x + v[jq].y * v[jq].y + v[jq].z * v[jq].z + v[jq].w * v[jq].w; }
;             ss = wave_sum(ss);
;             const float r3 = rsqrtf(ss * (1.f / D) + EPS);
	v_add_f32_e32 v225, v225, v143
	v_mov_b32_e32 v144, 0
	v_mul_f32_e32 v145, v210, v210
	v_fmac_f32_e32 v145, v211, v211
	v_fmac_f32_e32 v145, v212, v212
	v_fmac_f32_e32 v145, v213, v213
	v_add_f32_e32 v144, v144, v145
	v_mul_f32_e32 v145, v214, v214
	v_fmac_f32_e32 v145, v215, v215
	v_fmac_f32_e32 v145, v216, v216
	v_fmac_f32_e32 v145, v217, v217
	v_add_f32_e32 v144, v144, v145
	v_mul_f32_e32 v145, v218, v218
	v_fmac_f32_e32 v145, v219, v219
	v_fmac_f32_e32 v145, v220, v220
	v_fmac_f32_e32 v145, v221, v221
	v_add_f32_e32 v144, v144, v145
	v_mul_f32_e32 v145, v222, v222
	v_fmac_f32_e32 v145, v223, v223
	v_fmac_f32_e32 v145, v224, v224
	v_fmac_f32_e32 v145, v225, v225
	v_add_f32_e32 v144, v144, v145
	s_nop 1
	v_add_f32_dpp v144, v144, v144 quad_perm:[1,0,3,2] row_mask:0xf bank_mask:0xf bound_ctrl:1
	s_nop 1
	v_add_f32_dpp v144, v144, v144 quad_perm:[2,3,0,1] row_mask:0xf bank_mask:0xf bound_ctrl:1
	s_nop 1
	v_add_f32_dpp v144, v144, v144 row_half_mirror row_mask:0xf bank_mask:0xf bound_ctrl:1
	s_nop 1
	v_add_f32_dpp v144, v144, v144 row_mirror row_mask:0xf bank_mask:0xf bound_ctrl:1
	s_nop 1
	v_readlane_b32 s10, v144, 0
	v_readlane_b32 s11, v144, 16
	v_readlane_b32 s14, v144, 32
	v_readlane_b32 s15, v144, 48
	s_nop 3
	v_mov_b32_e32 v144, s11
	v_mov_b32_e32 v145, s15
	v_add_f32_e32 v144, s10, v144
	v_add_f32_e32 v145, s14, v145
	v_add_f32_e32 v144, v144, v145
	v_fmamk_f32 v144, v144, 0x3a800000, v111
	v_rsq_f32_e32 v144, v144
	s_nop 0
	v_mul_f32_e32 v210, v210, v144
	v_mul_f32_e32 v211, v211, v144
	v_mul_f32_e32 v212, v212, v144
	v_mul_f32_e32 v213, v213, v144
	v_mul_f32_e32 v214, v214, v144
	v_mul_f32_e32 v215, v215, v144
	v_mul_f32_e32 v216, v216, v144
	v_mul_f32_e32 v217, v217, v144
	v_mul_f32_e32 v218, v218, v144
	v_mul_f32_e32 v219, v219, v144
	v_mul_f32_e32 v220, v220, v144
	v_mul_f32_e32 v221, v221, v144
	v_mul_f32_e32 v222, v222, v144
	v_mul_f32_e32 v223, v223, v144
	v_mul_f32_e32 v224, v224, v144
	v_mul_f32_e32 v225, v225, v144
	v_dot8c_i32_i4_e32 v38, v122, v48
	v_dot8c_i32_i4_e32 v39, v122, v46
	v_dot8c_i32_i4_e32 v40, v124, v48
	v_dot8c_i32_i4_e32 v41, v124, v46
	v_dot8c_i32_i4_e32 v42, v126, v48
	v_dot8c_i32_i4_e32 v43, v126, v46
	v_dot8c_i32_i4_e32 v44, v128, v48
	v_dot8c_i32_i4_e32 v45, v128, v46
	v_dot8c_i32_i4_e32 v38, v123, v49
	v_dot8c_i32_i4_e32 v39, v123, v47
	v_dot8c_i32_i4_e32 v40, v125, v49
	v_dot8c_i32_i4_e32 v41, v125, v47
	v_dot8c_i32_i4_e32 v42, v127, v49
	v_dot8c_i32_i4_e32 v43, v127, v47
	v_dot8c_i32_i4_e32 v44, v129, v49
	v_dot8c_i32_i4_e32 v45, v129, v47
	v_and_b32_e32 v78, 0xffff, v32
	v_lshrrev_b32_e32 v79, 16, v32
	v_lshl_add_u32 v78, v78, 7, v150
	v_lshl_add_u32 v79, v79, 7, v151
	s_mov_b32 m0, s98
	s_add_i32 s43, s98, 0x400
	global_load_lds_dwordx4 v78, s[50:51]
	s_mov_b32 m0, s43
	s_nop 0
	global_load_lds_dwordx4 v79, s[50:51]
	s_waitcnt vmcnt(8)
	v_add_u32_e32 v54, s76, v59
	v_add_u32_e32 v55, s76, v60
	v_add_u32_e32 v56, s76, v61
	v_add_u32_e32 v57, s76, v62
	ds_read_b64_tr_b4 v[46:47], v160 offset:256
	ds_read_b64_tr_b4 v[48:49], v160 offset:1280
	ds_read_b64_tr_b4 v[122:123], v54
	ds_read_b64_tr_b4 v[124:125], v55
	ds_read_b64_tr_b4 v[126:127], v56
	ds_read_b64_tr_b4 v[128:129], v57
	s_waitcnt lgkmcnt(6)
	v_dot8c_i32_i4_e32 v38, v130, v52
	v_dot8c_i32_i4_e32 v39, v130, v50
	v_dot8c_i32_i4_e32 v40, v132, v52
	v_dot8c_i32_i4_e32 v41, v132, v50
	v_dot8c_i32_i4_e32 v42, v134, v52
	v_dot8c_i32_i4_e32 v43, v134, v50
	v_dot8c_i32_i4_e32 v44, v136, v52
	v_dot8c_i32_i4_e32 v45, v136, v50
	v_dot8c_i32_i4_e32 v38, v131, v53
	v_dot8c_i32_i4_e32 v39, v131, v51
	v_dot8c_i32_i4_e32 v40, v133, v53
	v_dot8c_i32_i4_e32 v41, v133, v51
	v_dot8c_i32_i4_e32 v42, v135, v53
	v_dot8c_i32_i4_e32 v43, v135, v51
	v_dot8c_i32_i4_e32 v44, v137, v53
	v_dot8c_i32_i4_e32 v45, v137, v51
	v_and_b32_e32 v78, 0xffff, v33
	v_lshrrev_b32_e32 v79, 16, v33
	v_lshl_add_u32 v78, v78, 7, v150
	v_lshl_add_u32 v79, v79, 7, v151
	s_mov_b32 m0, s99
	s_add_i32 s43, s99, 0x400
	global_load_lds_dwordx4 v78, s[50:51]
	s_mov_b32 m0, s43
	s_nop 0
	global_load_lds_dwordx4 v79, s[50:51]
	s_waitcnt vmcnt(8)
	v_add_u32_e32 v54, s77, v59
	v_add_u32_e32 v55, s77, v60
	v_add_u32_e32 v56, s77, v61
	v_add_u32_e32 v57, s77, v62
	ds_read_b64_tr_b4 v[50:51], v160 offset:384
	ds_read_b64_tr_b4 v[52:53], v160 offset:1408
	ds_read_b64_tr_b4 v[130:131], v54
	ds_read_b64_tr_b4 v[132:133], v55
	ds_read_b64_tr_b4 v[134:135], v56
	ds_read_b64_tr_b4 v[136:137], v57
	s_waitcnt lgkmcnt(6)
	v_dot8c_i32_i4_e32 v38, v122, v48
	v_dot8c_i32_i4_e32 v39, v122, v46
	v_dot8c_i32_i4_e32 v40, v124, v48
	v_dot8c_i32_i4_e32 v41, v124, v46
	v_dot8c_i32_i4_e32 v42, v126, v48
	v_dot8c_i32_i4_e32 v43, v126, v46
	v_dot8c_i32_i4_e32 v44, v128, v48
	v_dot8c_i32_i4_e32 v45, v128, v46
	v_dot8c_i32_i4_e32 v38, v123, v49
	v_dot8c_i32_i4_e32 v39, v123, v47
	v_dot8c_i32_i4_e32 v40, v125, v49
	v_dot8c_i32_i4_e32 v41, v125, v47
	v_dot8c_i32_i4_e32 v42, v127, v49
	v_dot8c_i32_i4_e32 v43, v127, v47
	v_dot8c_i32_i4_e32 v44, v129, v49
	v_dot8c_i32_i4_e32 v45, v129, v47
	s_waitcnt lgkmcnt(15)
	v_and_b32_e32 v78, 0xffff, v18
	v_lshrrev_b32_e32 v79, 16, v18
	v_lshl_add_u32 v78, v78, 7, v152
	v_lshl_add_u32 v79, v79, 7, v153
	s_mov_b32 m0, s76
	s_add_i32 s43, s76, 0x400
	global_load_lds_dwordx4 v78, s[50:51]
	s_mov_b32 m0, s43
	s_nop 0
	global_load_lds_dwordx4 v79, s[50:51]
	s_waitcnt vmcnt(8)
	v_add_u32_e32 v54, s78, v59
	v_add_u32_e32 v55, s78, v60
	v_add_u32_e32 v56, s78, v61
	v_add_u32_e32 v57, s78, v62
	ds_read_b64_tr_b4 v[46:47], v160 offset:512
	ds_read_b64_tr_b4 v[48:49], v160 offset:1536
	ds_read_b64_tr_b4 v[122:123], v54
	ds_read_b64_tr_b4 v[124:125], v55
	ds_read_b64_tr_b4 v[126:127], v56
	ds_read_b64_tr_b4 v[128:129], v57
	s_waitcnt lgkmcnt(6)
; #define LAS __attribute__((address_space(3)))
; #define TR4(p_) __builtin_amdgcn_ds_read_tr4_b64_v2i32((LAS v2i*)(p_))
; __device__ __forceinline__ void peer_v_tokens(int j, const LAS unsigned short* EL, const LAS unsigned char* AL  , const LAS float* ASC  , const LAS int* SAL  , ...
;     ...
;         for (int m = 0; m < 2; ++m) {
;             const int idx = lane + 64 * m, tau = idx >> 4, sr = idx & 15, k = 16 * (sr & 7) + 2 * tau + (sr >> 3);
;             const int aq = (int)*(const LAS signed char*)(AL + tl * 128 + k); const int tq = aq + 8;
;             const unsigned lo = (((unsigned)tq & 15u) ^ 8u) * 0x11111111u, hi = ((unsigned)(tq >> 4) & 15u) * 0x11111111u;
;             typedef unsigned u2v __attribute__((ext_vector_type(2)));
;             u2v l2; l2.x = lo; l2.y = lo; u2v h2; h2.x = hi; h2.y = hi;
;             *(LAS u2v*)(ATL + 8 * idx) = l2; *(LAS u2v*)(ATL + 1024 + 8 * idx) = h2;
;         }
;     ...
; #pragma unroll
;         for (int st = 0; st < 16; ++st) {
;             const int p = st >> 2, q = st & 3;
;             if (st < 14) VDMA(st + 2, (st + 2) % 3);
;             if (st < 14) asm volatile("s_waitcnt vmcnt(8)" ::: "memory");
;             else if (st == 14) asm volatile("s_waitcnt vmcnt(4)" ::: "memory");
;             else asm volatile("s_waitcnt vmcnt(0)" ::: "memory");
;             if (q == 0) {
; #pragma unroll
;                 for (int r = 0; r < 4; ++r) { accH[r] = 0; accL[r] = 0; } }
; #pragma unroll
;             for (int tp = 0; tp < 2; ++tp) {
;                 const v2i ao = TR4(ATL + (2 * q + tp) * 128 + 8 * s16), ah = TR4(ATL + 1024 + (2 * q + tp) * 128 + 8 * s16);
; #pragma unroll
;                 for (int r = 0; r < 4; ++r) {
;                     const v2i d = TR4(ldsb + BUF[st % 3] + 2048 * tp + roff[r]);
;                     accH[r] = __builtin_amdgcn_sdot8(d.x, ah.x, accH[r], false); accH[r] = __builtin_amdgcn_sdot8(d.y, ah.y, accH[r], false);
;                     accL[r] = __builtin_amdgcn_sdot8(d.x, ao.x, accL[r], false); accL[r] = __builtin_amdgcn_sdot8(d.y, ao.y, accL[r], false);
;                 }
;             }
;             asm volatile("s_waitcnt lgkmcnt(0)" ::: "memory");
	v_dot8c_i32_i4_e32 v38, v130, v52
	v_dot8c_i32_i4_e32 v39, v130, v50
	v_dot8c_i32_i4_e32 v40, v132, v52
	v_dot8c_i32_i4_e32 v41, v132, v50
	v_dot8c_i32_i4_e32 v42, v134, v52
	v_dot8c_i32_i4_e32 v43, v134, v50
	v_dot8c_i32_i4_e32 v44, v136, v52
	v_dot8c_i32_i4_e32 v45, v136, v50
	v_dot8c_i32_i4_e32 v38, v131, v53
	v_dot8c_i32_i4_e32 v39, v131, v51
	v_dot8c_i32_i4_e32 v40, v133, v53
	v_dot8c_i32_i4_e32 v41, v133, v51
	v_dot8c_i32_i4_e32 v42, v135, v53
	v_dot8c_i32_i4_e32 v43, v135, v51
	v_dot8c_i32_i4_e32 v44, v137, v53
	v_dot8c_i32_i4_e32 v45, v137, v51
	v_and_b32_e32 v78, 0xffff, v19
	v_lshrrev_b32_e32 v79, 16, v19
	v_lshl_add_u32 v78, v78, 7, v152
	v_lshl_add_u32 v79, v79, 7, v153
	s_mov_b32 m0, s77
	s_add_i32 s43, s77, 0x400
	global_load_lds_dwordx4 v78, s[50:51]
	s_mov_b32 m0, s43
	s_nop 0
	global_load_lds_dwordx4 v79, s[50:51]
	s_waitcnt vmcnt(8)
	v_add_u32_e32 v54, s79, v59
	v_add_u32_e32 v55, s79, v60
	v_add_u32_e32 v56, s79, v61
	v_add_u32_e32 v57, s79, v62
	ds_read_b64_tr_b4 v[50:51], v160 offset:640
	ds_read_b64_tr_b4 v[52:53], v160 offset:1664
	ds_read_b64_tr_b4 v[130:131], v54
	ds_read_b64_tr_b4 v[132:133], v55
	ds_read_b64_tr_b4 v[134:135], v56
	ds_read_b64_tr_b4 v[136:137], v57
	s_waitcnt lgkmcnt(6)
	v_dot8c_i32_i4_e32 v38, v122, v48
	v_dot8c_i32_i4_e32 v39, v122, v46
	v_dot8c_i32_i4_e32 v40, v124, v48
	v_dot8c_i32_i4_e32 v41, v124, v46
	v_dot8c_i32_i4_e32 v42, v126, v48
	v_dot8c_i32_i4_e32 v43, v126, v46
	v_dot8c_i32_i4_e32 v44, v128, v48
	v_dot8c_i32_i4_e32 v45, v128, v46
	v_dot8c_i32_i4_e32 v38, v123, v49
	v_dot8c_i32_i4_e32 v39, v123, v47
	v_dot8c_i32_i4_e32 v40, v125, v49
	v_dot8c_i32_i4_e32 v41, v125, v47
	v_dot8c_i32_i4_e32 v42, v127, v49
	v_dot8c_i32_i4_e32 v43, v127, v47
	v_dot8c_i32_i4_e32 v44, v129, v49
	v_dot8c_i32_i4_e32 v45, v129, v47
	s_waitcnt lgkmcnt(15)
	v_add_u32_e32 v143, 8, v139
	v_and_b32_e32 v142, 15, v143
	v_xor_b32_e32 v142, 8, v142
	v_bfe_u32 v144, v143, 4, 4
	v_mul_lo_u32 v142, v142, s92
	v_mul_lo_u32 v144, v144, s92
	v_mov_b32_e32 v143, v142
	v_mov_b32_e32 v145, v144
	ds_write2st64_b64 v159, v[142:143], v[144:145] offset1:2
	v_and_b32_e32 v78, 0xffff, v20
	v_lshrrev_b32_e32 v79, 16, v20
	v_lshl_add_u32 v78, v78, 7, v152
	v_lshl_add_u32 v79, v79, 7, v153
	s_mov_b32 m0, s78
	s_add_i32 s43, s78, 0x400
	global_load_lds_dwordx4 v78, s[50:51]
	s_mov_b32 m0, s43
	s_nop 0
	global_load_lds_dwordx4 v79, s[50:51]
	s_waitcnt vmcnt(8)
	v_add_u32_e32 v54, s98, v59
	v_add_u32_e32 v55, s98, v60
	v_add_u32_e32 v56, s98, v61
	v_add_u32_e32 v57, s98, v62
	ds_read_b64_tr_b4 v[46:47], v160 offset:768
	ds_read_b64_tr_b4 v[48:49], v160 offset:1792
	ds_read_b64_tr_b4 v[122:123], v54
	ds_read_b64_tr_b4 v[124:125], v55
	ds_read_b64_tr_b4 v[126:127], v56
	ds_read_b64_tr_b4 v[128:129], v57
	s_waitcnt lgkmcnt(7)
	v_dot8c_i32_i4_e32 v38, v130, v52
	v_dot8c_i32_i4_e32 v39, v130, v50
	v_dot8c_i32_i4_e32 v40, v132, v52
	v_dot8c_i32_i4_e32 v41, v132, v50
	v_dot8c_i32_i4_e32 v42, v134, v52
	v_dot8c_i32_i4_e32 v43, v134, v50
	v_dot8c_i32_i4_e32 v44, v136, v52
	v_dot8c_i32_i4_e32 v45, v136, v50
	v_dot8c_i32_i4_e32 v38, v131, v53
	v_dot8c_i32_i4_e32 v39, v131, v51
	v_dot8c_i32_i4_e32 v40, v133, v53
	v_dot8c_i32_i4_e32 v41, v133, v51
	v_dot8c_i32_i4_e32 v42, v135, v53
	v_dot8c_i32_i4_e32 v43, v135, v51
	v_dot8c_i32_i4_e32 v44, v137, v53
	v_dot8c_i32_i4_e32 v45, v137, v51
	v_and_b32_e32 v78, 0xffff, v21
	v_lshrrev_b32_e32 v79, 16, v21
	v_lshl_add_u32 v78, v78, 7, v152
	v_lshl_add_u32 v79, v79, 7, v153
	s_mov_b32 m0, s79
	s_add_i32 s43, s79, 0x400
	global_load_lds_dwordx4 v78, s[50:51]
	s_mov_b32 m0, s43
	s_nop 0
	global_load_lds_dwordx4 v79, s[50:51]
	s_waitcnt vmcnt(8)
	v_add_u32_e32 v54, s99, v59
	v_add_u32_e32 v55, s99, v60
	v_add_u32_e32 v56, s99, v61
	v_add_u32_e32 v57, s99, v62
	ds_read_b64_tr_b4 v[50:51], v160 offset:896
	ds_read_b64_tr_b4 v[52:53], v160 offset:1920
	ds_read_b64_tr_b4 v[130:131], v54
	ds_read_b64_tr_b4 v[132:133], v55
	ds_read_b64_tr_b4 v[134:135], v56
	ds_read_b64_tr_b4 v[136:137], v57
	s_waitcnt lgkmcnt(6)
	v_dot8c_i32_i4_e32 v38, v122, v48
	v_dot8c_i32_i4_e32 v39, v122, v46
	v_dot8c_i32_i4_e32 v40, v124, v48
	v_dot8c_i32_i4_e32 v41, v124, v46
	v_dot8c_i32_i4_e32 v42, v126, v48
	v_dot8c_i32_i4_e32 v43, v126, v46
	v_dot8c_i32_i4_e32 v44, v128, v48
	v_dot8c_i32_i4_e32 v45, v128, v46
	v_dot8c_i32_i4_e32 v38, v123, v49
	v_dot8c_i32_i4_e32 v39, v123, v47
	v_dot8c_i32_i4_e32 v40, v125, v49
	v_dot8c_i32_i4_e32 v41, v125, v47
	v_dot8c_i32_i4_e32 v42, v127, v49
	v_dot8c_i32_i4_e32 v43, v127, v47
	v_dot8c_i32_i4_e32 v44, v129, v49
	v_dot8c_i32_i4_e32 v45, v129, v47
	v_and_b32_e32 v78, 0xffff, v22
	v_lshrrev_b32_e32 v79, 16, v22
	v_lshl_add_u32 v78, v78, 7, v152
	v_lshl_add_u32 v79, v79, 7, v153
	s_mov_b32 m0, s98
	s_add_i32 s43, s98, 0x400
	global_load_lds_dwordx4 v78, s[50:51]
	s_mov_b32 m0, s43
	s_nop 0
	global_load_lds_dwordx4 v79, s[50:51]
	s_waitcnt vmcnt(8)
	v_add_u32_e32 v54, s76, v59
	v_add_u32_e32 v55, s76, v60
	v_add_u32_e32 v56, s76, v61
	v_add_u32_e32 v57, s76, v62
	ds_read_b64_tr_b4 v[46:47], v160
	ds_read_b64_tr_b4 v[48:49], v160 offset:1024
	ds_read_b64_tr_b4 v[122:123], v54
	ds_read_b64_tr_b4 v[124:125], v55
	ds_read_b64_tr_b4 v[126:127], v56
	ds_read_b64_tr_b4 v[128:129], v57
	s_waitcnt lgkmcnt(6)
	v_dot8c_i32_i4_e32 v38, v130, v52
	v_dot8c_i32_i4_e32 v39, v130, v50
	v_dot8c_i32_i4_e32 v40, v132, v52
	v_dot8c_i32_i4_e32 v41, v132, v50
	v_dot8c_i32_i4_e32 v42, v134, v52
	v_dot8c_i32_i4_e32 v43, v134, v50
	v_dot8c_i32_i4_e32 v44, v136, v52
	v_dot8c_i32_i4_e32 v45, v136, v50
	v_dot8c_i32_i4_e32 v38, v131, v53
	v_dot8c_i32_i4_e32 v39, v131, v51
	v_dot8c_i32_i4_e32 v40, v133, v53
	v_dot8c_i32_i4_e32 v41, v133, v51
	v_dot8c_i32_i4_e32 v42, v135, v53
	v_dot8c_i32_i4_e32 v43, v135, v51
	v_dot8c_i32_i4_e32 v44, v137, v53
	v_dot8c_i32_i4_e32 v45, v137, v51
	s_nop 3
	s_waitcnt lgkmcnt(15)
; #define LAS __attribute__((address_space(3)))
; __device__ __forceinline__ bf16 f2bf(float f) { return (bf16)f2bfu(f); }
; __device__ __forceinline__ void peer_v_tokens(int j, const LAS unsigned short* EL, const LAS unsigned char* AL  , const LAS float* ASC  , const LAS int* SAL  , ...
;     ...
;         const int tl = it * 8 + wave, t = j * 64 + tl;
;         unsigned E[8];
;         { const LAS v4u* ep = (const LAS v4u*)(EL + tl * 128 + 16 * g); const v4u e0 = ep[0], e1 = ep[1];
;           E[0] = e0.x; E[1] = e0.y; E[2] = e0.z; E[3] = e0.w; E[4] = e1.x; E[5] = e1.y; E[6] = e1.z; E[7] = e1.w; }
;     ...
;         { unsigned ho = (unsigned)t * (D / 4) + (unsigned)lane; asm volatile("" : "+v"(ho)); const uint2* hp = (const uint2*)HB + ho; const float4* gp = (const float4*)fng + lane;
; #pragma unroll
;           for (int jq = 0; jq < 4; ++jq) { hv[jq] = hp[64 * jq]; gv[jq] = gp[64 * jq]; } }
;     ...
;         for (int m = 0; m < 2; ++m) {
;             const int idx = lane + 64 * m, tau = idx >> 4, sr = idx & 15, k = 16 * (sr & 7) + 2 * tau + (sr >> 3);
;             const int aq = (int)*(const LAS signed char*)(AL + tl * 128 + k); const int tq = aq + 8;
;             const unsigned lo = (((unsigned)tq & 15u) ^ 8u) * 0x11111111u, hi = ((unsigned)(tq >> 4) & 15u) * 0x11111111u;
;             typedef unsigned u2v __attribute__((ext_vector_type(2)));
;             u2v l2; l2.x = lo; l2.y = lo; u2v h2; h2.x = hi; h2.y = hi;
;             *(LAS u2v*)(ATL + 8 * idx) = l2; *(LAS u2v*)(ATL + 1024 + 8 * idx) = h2;
;         }
;     ...
;                 for (int r = 0; r < 4; ++r) STASH[256 * p + 16 * (grp + 4 * r) + pc] = f2bf(asc * (float)(2 * ((accH[r] << 4) + accL[r]) + sa));
;     ...
;             for (int jq = 0; jq < 4; ++jq) { typedef float f4v __attribute__((ext_vector_type(4))); f4v o4; o4.x = v[jq].x * r3 * gv[jq].x; o4.y = v[jq].y * r3 * gv[jq].y; o4.z = v[jq].z * r3 * gv[jq].z; o4.w = v[jq].w * r3 * gv[jq].w;
;                 __builtin_nontemporal_store(o4, (f4v*)op + 64 * jq); }
	v_lshlrev_b32_e32 v38, 5, v38
	v_lshlrev_b32_e32 v39, 1, v39
	v_add3_u32 v38, v39, v229, v38
	v_cvt_f32_i32_e32 v38, v38
	v_mul_f32_e32 v38, v228, v38
	v_lshlrev_b32_e32 v40, 5, v40
	v_lshlrev_b32_e32 v41, 1, v41
	v_add3_u32 v40, v41, v229, v40
	v_cvt_f32_i32_e32 v40, v40
	v_mul_f32_e32 v40, v228, v40
	v_lshlrev_b32_e32 v42, 5, v42
	v_lshlrev_b32_e32 v43, 1, v43
	v_add3_u32 v42, v43, v229, v42
	v_cvt_f32_i32_e32 v42, v42
	v_mul_f32_e32 v42, v228, v42
	v_lshlrev_b32_e32 v44, 5, v44
	v_lshlrev_b32_e32 v45, 1, v45
	v_add3_u32 v44, v45, v229, v44
	v_cvt_f32_i32_e32 v44, v44
	v_mul_f32_e32 v44, v228, v44
	v_cvt_pk_bf16_f32 v170, v38, v40
	v_cvt_pk_bf16_f32 v171, v42, v44
	ds_read_b128 v[252:255], v155
	s_add_i32 s44, s40, 16
	s_ashr_i32 s45, s44, 31
	s_lshl_b64 s[44:45], s[44:45], 12
	v_lshl_add_u64 v[80:81], v[36:37], 0, s[44:45]
	s_waitcnt lgkmcnt(0)
	v_mul_f32_e32 v210, v210, v252
	v_mul_f32_e32 v211, v211, v253
	v_mul_f32_e32 v212, v212, v254
	v_mul_f32_e32 v213, v213, v255
	global_store_dwordx4 v[80:81], v[210:213], off nt
	s_add_i32 s43, s40, 24
	s_lshl_b32 s43, s43, 11
	v_add_u32_e32 v138, s43, v66
	global_load_dwordx2 v[194:195], v138, s[70:71]
	global_load_dwordx2 v[196:197], v138, s[70:71] offset:512
	global_load_dwordx2 v[198:199], v138, s[70:71] offset:1024
	global_load_dwordx2 v[200:201], v138, s[70:71] offset:1536
	v_add_u32_e32 v147, 8, v140
	v_and_b32_e32 v146, 15, v147
	v_xor_b32_e32 v146, 8, v146
	v_bfe_u32 v148, v147, 4, 4
	v_mul_lo_u32 v146, v146, s92
	v_mul_lo_u32 v148, v148, s92
	v_mov_b32_e32 v147, v146
	v_mov_b32_e32 v149, v148
	ds_write2st64_b64 v77, v[146:147], v[148:149] offset1:2
	v_add_u32_e32 v138, 0x1400, v74
	ds_read_u8 v139, v138
	v_add_u32_e32 v141, 0x1400, v73
	ds_read_u8 v140, v141
	s_add_i32 s43, s67, 128
	v_mov_b32_e32 v138, s43
	ds_read2st64_b32 v[228:229], v138 offset1:1
	ds_read_b128 v[26:29], v227 offset:10240
	ds_read_b128 v[30:33], v227 offset:10256
	v_mov_b32_e32 v38, 0
	v_mov_b32_e32 v39, 0
	v_mov_b32_e32 v40, 0
	v_mov_b32_e32 v41, 0
	v_mov_b32_e32 v42, 0
	v_mov_b32_e32 v43, 0
	v_mov_b32_e32 v44, 0
	v_mov_b32_e32 v45, 0
	v_and_b32_e32 v78, 0xffff, v23
	v_lshrrev_b32_e32 v79, 16, v23
	v_lshl_add_u32 v78, v78, 7, v152
	v_lshl_add_u32 v79, v79, 7, v153
	s_mov_b32 m0, s99
	s_add_i32 s43, s99, 0x400
	global_load_lds_dwordx4 v78, s[50:51]
	s_mov_b32 m0, s43
	s_nop 0
	global_load_lds_dwordx4 v79, s[50:51]
	s_waitcnt vmcnt(13)
	v_add_u32_e32 v54, s77, v59
	v_add_u32_e32 v55, s77, v60
	v_add_u32_e32 v56, s77, v61
	v_add_u32_e32 v57, s77, v62
	ds_read_b64_tr_b4 v[50:51], v160 offset:128
	ds_read_b64_tr_b4 v[52:53], v160 offset:1152
	ds_read_b64_tr_b4 v[130:131], v54
	ds_read_b64_tr_b4 v[132:133], v55
	ds_read_b64_tr_b4 v[134:135], v56
	ds_read_b64_tr_b4 v[136:137], v57
	s_waitcnt lgkmcnt(13)
	v_dot8c_i32_i4_e32 v38, v122, v48
	v_dot8c_i32_i4_e32 v39, v122, v46
	v_dot8c_i32_i4_e32 v40, v124, v48
	v_dot8c_i32_i4_e32 v41, v124, v46
	v_dot8c_i32_i4_e32 v42, v126, v48
	v_dot8c_i32_i4_e32 v43, v126, v46
	v_dot8c_i32_i4_e32 v44, v128, v48
	v_dot8c_i32_i4_e32 v45, v128, v46
	v_dot8c_i32_i4_e32 v38, v123, v49
	v_dot8c_i32_i4_e32 v39, v123, v47
	v_dot8c_i32_i4_e32 v40, v125, v49
	v_dot8c_i32_i4_e32 v41, v125, v47
	v_dot8c_i32_i4_e32 v42, v127, v49
	v_dot8c_i32_i4_e32 v43, v127, v47
	v_dot8c_i32_i4_e32 v44, v129, v49
	v_dot8c_i32_i4_e32 v45, v129, v47
	v_and_b32_e32 v78, 0xffff, v24
	v_lshrrev_b32_e32 v79, 16, v24
	v_lshl_add_u32 v78, v78, 7, v152
	v_lshl_add_u32 v79, v79, 7, v153
	s_mov_b32 m0, s76
	s_add_i32 s43, s76, 0x400
	global_load_lds_dwordx4 v78, s[50:51]
	s_mov_b32 m0, s43
	s_nop 0
	global_load_lds_dwordx4 v79, s[50:51]
	s_waitcnt vmcnt(13)
	v_add_u32_e32 v54, s78, v59
	v_add_u32_e32 v55, s78, v60
	v_add_u32_e32 v56, s78, v61
	v_add_u32_e32 v57, s78, v62
	ds_read_b64_tr_b4 v[46:47], v160 offset:256
	ds_read_b64_tr_b4 v[48:49], v160 offset:1280
	ds_read_b64_tr_b4 v[122:123], v54
	ds_read_b64_tr_b4 v[124:125], v55
	ds_read_b64_tr_b4 v[126:127], v56
	ds_read_b64_tr_b4 v[128:129], v57
	s_waitcnt lgkmcnt(6)
	v_dot8c_i32_i4_e32 v38, v130, v52
	v_dot8c_i32_i4_e32 v39, v130, v50
	v_dot8c_i32_i4_e32 v40, v132, v52
	v_dot8c_i32_i4_e32 v41, v132, v50
	v_dot8c_i32_i4_e32 v42, v134, v52
	v_dot8c_i32_i4_e32 v43, v134, v50
	v_dot8c_i32_i4_e32 v44, v136, v52
	v_dot8c_i32_i4_e32 v45, v136, v50
	v_dot8c_i32_i4_e32 v38, v131, v53
	v_dot8c_i32_i4_e32 v39, v131, v51
	v_dot8c_i32_i4_e32 v40, v133, v53
	v_dot8c_i32_i4_e32 v41, v133, v51
	v_dot8c_i32_i4_e32 v42, v135, v53
	v_dot8c_i32_i4_e32 v43, v135, v51
	v_dot8c_i32_i4_e32 v44, v137, v53
	v_dot8c_i32_i4_e32 v45, v137, v51
	v_and_b32_e32 v78, 0xffff, v25
	v_lshrrev_b32_e32 v79, 16, v25
	v_lshl_add_u32 v78, v78, 7, v152
	v_lshl_add_u32 v79, v79, 7, v153
	s_mov_b32 m0, s77
	s_add_i32 s43, s77, 0x400
	global_load_lds_dwordx4 v78, s[50:51]
	s_mov_b32 m0, s43
	s_nop 0
	global_load_lds_dwordx4 v79, s[50:51]
	s_waitcnt vmcnt(13)
	v_add_u32_e32 v54, s79, v59
	v_add_u32_e32 v55, s79, v60
	v_add_u32_e32 v56, s79, v61
	v_add_u32_e32 v57, s79, v62
	ds_read_b64_tr_b4 v[50:51], v160 offset:384
	ds_read_b64_tr_b4 v[52:53], v160 offset:1408
	ds_read_b64_tr_b4 v[130:131], v54
	ds_read_b64_tr_b4 v[132:133], v55
	ds_read_b64_tr_b4 v[134:135], v56
	ds_read_b64_tr_b4 v[136:137], v57
	s_waitcnt lgkmcnt(6)
	v_dot8c_i32_i4_e32 v38, v122, v48
	v_dot8c_i32_i4_e32 v39, v122, v46
	v_dot8c_i32_i4_e32 v40, v124, v48
	v_dot8c_i32_i4_e32 v41, v124, v46
	v_dot8c_i32_i4_e32 v42, v126, v48
	v_dot8c_i32_i4_e32 v43, v126, v46
	v_dot8c_i32_i4_e32 v44, v128, v48
	v_dot8c_i32_i4_e32 v45, v128, v46
	v_dot8c_i32_i4_e32 v38, v123, v49
	v_dot8c_i32_i4_e32 v39, v123, v47
	v_dot8c_i32_i4_e32 v40, v125, v49
	v_dot8c_i32_i4_e32 v41, v125, v47
	v_dot8c_i32_i4_e32 v42, v127, v49
	v_dot8c_i32_i4_e32 v43, v127, v47
	v_dot8c_i32_i4_e32 v44, v129, v49
	v_dot8c_i32_i4_e32 v45, v129, v47
	s_waitcnt lgkmcnt(15)
; #define LAS __attribute__((address_space(3)))
; #define TR4(p_) __builtin_amdgcn_ds_read_tr4_b64_v2i32((LAS v2i*)(p_))
; __device__ __forceinline__ void peer_v_tokens(int j, const LAS unsigned short* EL, const LAS unsigned char* AL  , const LAS float* ASC  , const LAS int* SAL  , ...
;     ...
;         for (int m = 0; m < 2; ++m) {
;             const int idx = lane + 64 * m, tau = idx >> 4, sr = idx & 15, k = 16 * (sr & 7) + 2 * tau + (sr >> 3);
;             const int aq = (int)*(const LAS signed char*)(AL + tl * 128 + k); const int tq = aq + 8;
;             const unsigned lo = (((unsigned)tq & 15u) ^ 8u) * 0x11111111u, hi = ((unsigned)(tq >> 4) & 15u) * 0x11111111u;
;             typedef unsigned u2v __attribute__((ext_vector_type(2)));
;             u2v l2; l2.x = lo; l2.y = lo; u2v h2; h2.x = hi; h2.y = hi;
;             *(LAS u2v*)(ATL + 8 * idx) = l2; *(LAS u2v*)(ATL + 1024 + 8 * idx) = h2;
;         }
;     ...
; #pragma unroll
;         for (int st = 0; st < 16; ++st) {
;             const int p = st >> 2, q = st & 3;
;             if (st < 14) VDMA(st + 2, (st + 2) % 3);
;             if (st < 14) asm volatile("s_waitcnt vmcnt(8)" ::: "memory");
;             else if (st == 14) asm volatile("s_waitcnt vmcnt(4)" ::: "memory");
;             else asm volatile("s_waitcnt vmcnt(0)" ::: "memory");
;             if (q == 0) {
; #pragma unroll
;                 for (int r = 0; r < 4; ++r) { accH[r] = 0; accL[r] = 0; } }
; #pragma unroll
;             for (int tp = 0; tp < 2; ++tp) {
;                 const v2i ao = TR4(ATL + (2 * q + tp) * 128 + 8 * s16), ah = TR4(ATL + 1024 + (2 * q + tp) * 128 + 8 * s16);
; #pragma unroll
;                 for (int r = 0; r < 4; ++r) {
;                     const v2i d = TR4(ldsb + BUF[st % 3] + 2048 * tp + roff[r]);
;                     accH[r] = __builtin_amdgcn_sdot8(d.x, ah.x, accH[r], false); accH[r] = __builtin_amdgcn_sdot8(d.y, ah.y, accH[r], false);
;                     accL[r] = __builtin_amdgcn_sdot8(d.x, ao.x, accL[r], false); accL[r] = __builtin_amdgcn_sdot8(d.y, ao.y, accL[r], false);
;                 }
;             }
;             asm volatile("s_waitcnt lgkmcnt(0)" ::: "memory");
	v_and_b32_e32 v78, 0xffff, v26
	v_lshrrev_b32_e32 v79, 16, v26
	v_lshl_add_u32 v78, v78, 7, v152
	v_lshl_add_u32 v79, v79, 7, v153
	s_mov_b32 m0, s78
	s_add_i32 s43, s78, 0x400
	global_load_lds_dwordx4 v78, s[50:51]
	s_mov_b32 m0, s43
	s_nop 0
	global_load_lds_dwordx4 v79, s[50:51]
	s_waitcnt vmcnt(13)
	v_add_u32_e32 v54, s98, v59
	v_add_u32_e32 v55, s98, v60
	v_add_u32_e32 v56, s98, v61
	v_add_u32_e32 v57, s98, v62
	ds_read_b64_tr_b4 v[46:47], v160 offset:512
	ds_read_b64_tr_b4 v[48:49], v160 offset:1536
	ds_read_b64_tr_b4 v[122:123], v54
	ds_read_b64_tr_b4 v[124:125], v55
	ds_read_b64_tr_b4 v[126:127], v56
	ds_read_b64_tr_b4 v[128:129], v57
	s_waitcnt lgkmcnt(6)
	v_dot8c_i32_i4_e32 v38, v130, v52
	v_dot8c_i32_i4_e32 v39, v130, v50
	v_dot8c_i32_i4_e32 v40, v132, v52
	v_dot8c_i32_i4_e32 v41, v132, v50
	v_dot8c_i32_i4_e32 v42, v134, v52
	v_dot8c_i32_i4_e32 v43, v134, v50
	v_dot8c_i32_i4_e32 v44, v136, v52
	v_dot8c_i32_i4_e32 v45, v136, v50
	v_dot8c_i32_i4_e32 v38, v131, v53
	v_dot8c_i32_i4_e32 v39, v131, v51
	v_dot8c_i32_i4_e32 v40, v133, v53
	v_dot8c_i32_i4_e32 v41, v133, v51
	v_dot8c_i32_i4_e32 v42, v135, v53
	v_dot8c_i32_i4_e32 v43, v135, v51
	v_dot8c_i32_i4_e32 v44, v137, v53
	v_dot8c_i32_i4_e32 v45, v137, v51
	v_and_b32_e32 v78, 0xffff, v27
	v_lshrrev_b32_e32 v79, 16, v27
	v_lshl_add_u32 v78, v78, 7, v152
	v_lshl_add_u32 v79, v79, 7, v153
	s_mov_b32 m0, s79
	s_add_i32 s43, s79, 0x400
	global_load_lds_dwordx4 v78, s[50:51]
	s_mov_b32 m0, s43
	s_nop 0
	global_load_lds_dwordx4 v79, s[50:51]
	s_waitcnt vmcnt(8)
	v_add_u32_e32 v54, s99, v59
	v_add_u32_e32 v55, s99, v60
	v_add_u32_e32 v56, s99, v61
	v_add_u32_e32 v57, s99, v62
	ds_read_b64_tr_b4 v[50:51], v160 offset:640
	ds_read_b64_tr_b4 v[52:53], v160 offset:1664
	ds_read_b64_tr_b4 v[130:131], v54
	ds_read_b64_tr_b4 v[132:133], v55
	ds_read_b64_tr_b4 v[134:135], v56
	ds_read_b64_tr_b4 v[136:137], v57
	s_waitcnt lgkmcnt(6)
	v_dot8c_i32_i4_e32 v38, v122, v48
	v_dot8c_i32_i4_e32 v39, v122, v46
	v_dot8c_i32_i4_e32 v40, v124, v48
	v_dot8c_i32_i4_e32 v41, v124, v46
	v_dot8c_i32_i4_e32 v42, v126, v48
	v_dot8c_i32_i4_e32 v43, v126, v46
	v_dot8c_i32_i4_e32 v44, v128, v48
	v_dot8c_i32_i4_e32 v45, v128, v46
	v_dot8c_i32_i4_e32 v38, v123, v49
	v_dot8c_i32_i4_e32 v39, v123, v47
	v_dot8c_i32_i4_e32 v40, v125, v49
	v_dot8c_i32_i4_e32 v41, v125, v47
	v_dot8c_i32_i4_e32 v42, v127, v49
	v_dot8c_i32_i4_e32 v43, v127, v47
	v_dot8c_i32_i4_e32 v44, v129, v49
	v_dot8c_i32_i4_e32 v45, v129, v47
	s_waitcnt lgkmcnt(15)
	v_add_u32_e32 v143, 8, v139
	v_and_b32_e32 v142, 15, v143
	v_xor_b32_e32 v142, 8, v142
	v_bfe_u32 v144, v143, 4, 4
	v_mul_lo_u32 v142, v142, s92
	v_mul_lo_u32 v144, v144, s92
	v_mov_b32_e32 v143, v142
	v_mov_b32_e32 v145, v144
	ds_write2st64_b64 v159, v[142:143], v[144:145] offset1:2
	v_and_b32_e32 v78, 0xffff, v28
	v_lshrrev_b32_e32 v79, 16, v28
	v_lshl_add_u32 v78, v78, 7, v152
	v_lshl_add_u32 v79, v79, 7, v153
	s_mov_b32 m0, s98
	s_add_i32 s43, s98, 0x400
	global_load_lds_dwordx4 v78, s[50:51]
	s_mov_b32 m0, s43
	s_nop 0
	global_load_lds_dwordx4 v79, s[50:51]
	s_waitcnt vmcnt(8)
	v_add_u32_e32 v54, s76, v59
	v_add_u32_e32 v55, s76, v60
	v_add_u32_e32 v56, s76, v61
	v_add_u32_e32 v57, s76, v62
	ds_read_b64_tr_b4 v[46:47], v160 offset:768
	ds_read_b64_tr_b4 v[48:49], v160 offset:1792
	ds_read_b64_tr_b4 v[122:123], v54
	ds_read_b64_tr_b4 v[124:125], v55
	ds_read_b64_tr_b4 v[126:127], v56
	ds_read_b64_tr_b4 v[128:129], v57
	s_waitcnt lgkmcnt(7)
	v_dot8c_i32_i4_e32 v38, v130, v52
	v_dot8c_i32_i4_e32 v39, v130, v50
	v_dot8c_i32_i4_e32 v40, v132, v52
	v_dot8c_i32_i4_e32 v41, v132, v50
	v_dot8c_i32_i4_e32 v42, v134, v52
	v_dot8c_i32_i4_e32 v43, v134, v50
	v_dot8c_i32_i4_e32 v44, v136, v52
	v_dot8c_i32_i4_e32 v45, v136, v50
	v_dot8c_i32_i4_e32 v38, v131, v53
	v_dot8c_i32_i4_e32 v39, v131, v51
	v_dot8c_i32_i4_e32 v40, v133, v53
	v_dot8c_i32_i4_e32 v41, v133, v51
	v_dot8c_i32_i4_e32 v42, v135, v53
	v_dot8c_i32_i4_e32 v43, v135, v51
	v_dot8c_i32_i4_e32 v44, v137, v53
	v_dot8c_i32_i4_e32 v45, v137, v51
	v_and_b32_e32 v78, 0xffff, v29
	v_lshrrev_b32_e32 v79, 16, v29
	v_lshl_add_u32 v78, v78, 7, v152
	v_lshl_add_u32 v79, v79, 7, v153
	s_mov_b32 m0, s99
	s_add_i32 s43, s99, 0x400
	global_load_lds_dwordx4 v78, s[50:51]
	s_mov_b32 m0, s43
	s_nop 0
	global_load_lds_dwordx4 v79, s[50:51]
	s_waitcnt vmcnt(8)
	v_add_u32_e32 v54, s77, v59
	v_add_u32_e32 v55, s77, v60
	v_add_u32_e32 v56, s77, v61
	v_add_u32_e32 v57, s77, v62
	ds_read_b64_tr_b4 v[50:51], v160 offset:896
	ds_read_b64_tr_b4 v[52:53], v160 offset:1920
	ds_read_b64_tr_b4 v[130:131], v54
	ds_read_b64_tr_b4 v[132:133], v55
	ds_read_b64_tr_b4 v[134:135], v56
	ds_read_b64_tr_b4 v[136:137], v57
	s_waitcnt lgkmcnt(6)
	v_dot8c_i32_i4_e32 v38, v122, v48
	v_dot8c_i32_i4_e32 v39, v122, v46
	v_dot8c_i32_i4_e32 v40, v124, v48
	v_dot8c_i32_i4_e32 v41, v124, v46
	v_dot8c_i32_i4_e32 v42, v126, v48
	v_dot8c_i32_i4_e32 v43, v126, v46
	v_dot8c_i32_i4_e32 v44, v128, v48
	v_dot8c_i32_i4_e32 v45, v128, v46
	v_dot8c_i32_i4_e32 v38, v123, v49
	v_dot8c_i32_i4_e32 v39, v123, v47
	v_dot8c_i32_i4_e32 v40, v125, v49
	v_dot8c_i32_i4_e32 v41, v125, v47
	v_dot8c_i32_i4_e32 v42, v127, v49
	v_dot8c_i32_i4_e32 v43, v127, v47
	v_dot8c_i32_i4_e32 v44, v129, v49
	v_dot8c_i32_i4_e32 v45, v129, v47
	v_and_b32_e32 v78, 0xffff, v30
	v_lshrrev_b32_e32 v79, 16, v30
	v_lshl_add_u32 v78, v78, 7, v152
	v_lshl_add_u32 v79, v79, 7, v153
	s_mov_b32 m0, s76
	s_add_i32 s43, s76, 0x400
	global_load_lds_dwordx4 v78, s[50:51]
	s_mov_b32 m0, s43
	s_nop 0
	global_load_lds_dwordx4 v79, s[50:51]
	s_waitcnt vmcnt(8)
; #define LAS __attribute__((address_space(3)))
; __device__ __forceinline__ bf16 f2bf(float f) { return (bf16)f2bfu(f); }
; #define TR4(p_) __builtin_amdgcn_ds_read_tr4_b64_v2i32((LAS v2i*)(p_))
; __device__ __forceinline__ void peer_v_tokens(int j, const LAS unsigned short* EL, const LAS unsigned char* AL  , const LAS float* ASC  , const LAS int* SAL  , ...
;     ...
; #pragma unroll
;         for (int st = 0; st < 16; ++st) {
;             const int p = st >> 2, q = st & 3;
;             if (st < 14) VDMA(st + 2, (st + 2) % 3);
;             if (st < 14) asm volatile("s_waitcnt vmcnt(8)" ::: "memory");
;             else if (st == 14) asm volatile("s_waitcnt vmcnt(4)" ::: "memory");
;             else asm volatile("s_waitcnt vmcnt(0)" ::: "memory");
;             if (q == 0) {
; #pragma unroll
;                 for (int r = 0; r < 4; ++r) { accH[r] = 0; accL[r] = 0; } }
; #pragma unroll
;             for (int tp = 0; tp < 2; ++tp) {
;                 const v2i ao = TR4(ATL + (2 * q + tp) * 128 + 8 * s16), ah = TR4(ATL + 1024 + (2 * q + tp) * 128 + 8 * s16);
; #pragma unroll
;                 for (int r = 0; r < 4; ++r) {
;                     const v2i d = TR4(ldsb + BUF[st % 3] + 2048 * tp + roff[r]);
;                     accH[r] = __builtin_amdgcn_sdot8(d.x, ah.x, accH[r], false); accH[r] = __builtin_amdgcn_sdot8(d.y, ah.y, accH[r], false);
;                     accL[r] = __builtin_amdgcn_sdot8(d.x, ao.x, accL[r], false); accL[r] = __builtin_amdgcn_sdot8(d.y, ao.y, accL[r], false);
;                 }
;             }
;             asm volatile("s_waitcnt lgkmcnt(0)" ::: "memory");
;             if (q == 3) {
; #pragma unroll
;                 for (int r = 0; r < 4; ++r) STASH[256 * p + 16 * (grp + 4 * r) + pc] = f2bf(asc * (float)(2 * ((accH[r] << 4) + accL[r]) + sa));
;             }
;         }
;     ...
;         {
;             float4 v[4]; float ss = 0.f;
; #pragma unroll
;             for (int jq = 0; jq < 4; ++jq) { typedef unsigned u2v __attribute__((ext_vector_type(2))); const u2v pw = *(const LAS u2v*)(STASH + 4 * lane + 256 * jq); const uint2 hw = hv[jq];
;                 v[jq] = make_float4(__uint_as_float(hw.x << 16) + __uint_as_float(pw.x << 16), __uint_as_float(hw.x & 0xffff0000u) + __uint_as_float(pw.x & 0xffff0000u),
	v_add_u32_e32 v54, s78, v59
	v_add_u32_e32 v55, s78, v60
	v_add_u32_e32 v56, s78, v61
	v_add_u32_e32 v57, s78, v62
	ds_read_b64_tr_b4 v[46:47], v160
	ds_read_b64_tr_b4 v[48:49], v160 offset:1024
	ds_read_b64_tr_b4 v[122:123], v54
	ds_read_b64_tr_b4 v[124:125], v55
	ds_read_b64_tr_b4 v[126:127], v56
	ds_read_b64_tr_b4 v[128:129], v57
	s_waitcnt lgkmcnt(6)
	v_dot8c_i32_i4_e32 v38, v130, v52
	v_dot8c_i32_i4_e32 v39, v130, v50
	v_dot8c_i32_i4_e32 v40, v132, v52
	v_dot8c_i32_i4_e32 v41, v132, v50
	v_dot8c_i32_i4_e32 v42, v134, v52
	v_dot8c_i32_i4_e32 v43, v134, v50
	v_dot8c_i32_i4_e32 v44, v136, v52
	v_dot8c_i32_i4_e32 v45, v136, v50
	v_dot8c_i32_i4_e32 v38, v131, v53
	v_dot8c_i32_i4_e32 v39, v131, v51
	v_dot8c_i32_i4_e32 v40, v133, v53
	v_dot8c_i32_i4_e32 v41, v133, v51
	v_dot8c_i32_i4_e32 v42, v135, v53
	v_dot8c_i32_i4_e32 v43, v135, v51
	v_dot8c_i32_i4_e32 v44, v137, v53
	v_dot8c_i32_i4_e32 v45, v137, v51
	s_nop 3
	s_waitcnt lgkmcnt(15)
	v_lshlrev_b32_e32 v38, 5, v38
	v_lshlrev_b32_e32 v39, 1, v39
	v_add3_u32 v38, v39, v229, v38
	v_cvt_f32_i32_e32 v38, v38
	v_mul_f32_e32 v38, v228, v38
	v_lshlrev_b32_e32 v40, 5, v40
	v_lshlrev_b32_e32 v41, 1, v41
	v_add3_u32 v40, v41, v229, v40
	v_cvt_f32_i32_e32 v40, v40
	v_mul_f32_e32 v40, v228, v40
	v_lshlrev_b32_e32 v42, 5, v42
	v_lshlrev_b32_e32 v43, 1, v43
	v_add3_u32 v42, v43, v229, v42
	v_cvt_f32_i32_e32 v42, v42
	v_mul_f32_e32 v42, v228, v42
	v_lshlrev_b32_e32 v44, 5, v44
	v_lshlrev_b32_e32 v45, 1, v45
	v_add3_u32 v44, v45, v229, v44
	v_cvt_f32_i32_e32 v44, v44
	v_mul_f32_e32 v44, v228, v44
	v_cvt_pk_bf16_f32 v164, v38, v40
	v_cvt_pk_bf16_f32 v165, v42, v44
	ds_read_b128 v[252:255], v155 offset:1024
	s_add_i32 s44, s40, 16
	s_ashr_i32 s45, s44, 31
	s_lshl_b64 s[44:45], s[44:45], 12
	v_lshl_add_u64 v[80:81], v[36:37], 0, s[44:45]
	s_waitcnt lgkmcnt(0)
	v_mul_f32_e32 v214, v214, v252
	v_mul_f32_e32 v215, v215, v253
	v_mul_f32_e32 v216, v216, v254
	v_mul_f32_e32 v217, v217, v255
	global_store_dwordx4 v[80:81], v[214:217], off offset:1024 nt
	v_add_u32_e32 v147, 8, v140
	v_and_b32_e32 v146, 15, v147
	v_xor_b32_e32 v146, 8, v146
	v_bfe_u32 v148, v147, 4, 4
	v_mul_lo_u32 v146, v146, s92
	v_mul_lo_u32 v148, v148, s92
	v_mov_b32_e32 v147, v146
	v_mov_b32_e32 v149, v148
	ds_write2st64_b64 v77, v[146:147], v[148:149] offset1:2
	v_add_u32_e32 v138, 0x1000, v74
	ds_read_u8 v139, v138
	v_add_u32_e32 v141, 0x1000, v73
	ds_read_u8 v140, v141
	s_add_i32 s43, s67, 160
	v_mov_b32_e32 v138, s43
	ds_read2st64_b32 v[228:229], v138 offset1:1
	ds_read_b128 v[18:21], v227 offset:8192
	ds_read_b128 v[22:25], v227 offset:8208
	v_add_u32_e32 v150, 0x400000, v63
	v_add_u32_e32 v151, 0x400000, v64
	v_mov_b32_e32 v38, 0
	v_mov_b32_e32 v39, 0
	v_mov_b32_e32 v40, 0
	v_mov_b32_e32 v41, 0
	v_mov_b32_e32 v42, 0
	v_mov_b32_e32 v43, 0
	v_mov_b32_e32 v44, 0
	v_mov_b32_e32 v45, 0
	v_and_b32_e32 v78, 0xffff, v31
	v_lshrrev_b32_e32 v79, 16, v31
	v_lshl_add_u32 v78, v78, 7, v152
	v_lshl_add_u32 v79, v79, 7, v153
	s_mov_b32 m0, s77
	s_add_i32 s43, s77, 0x400
	global_load_lds_dwordx4 v78, s[50:51]
	s_mov_b32 m0, s43
	s_nop 0
	global_load_lds_dwordx4 v79, s[50:51]
	s_waitcnt vmcnt(9)
	v_add_u32_e32 v54, s79, v59
	v_add_u32_e32 v55, s79, v60
	v_add_u32_e32 v56, s79, v61
	v_add_u32_e32 v57, s79, v62
	ds_read_b64_tr_b4 v[50:51], v160 offset:128
	ds_read_b64_tr_b4 v[52:53], v160 offset:1152
	ds_read_b64_tr_b4 v[130:131], v54
	ds_read_b64_tr_b4 v[132:133], v55
	ds_read_b64_tr_b4 v[134:135], v56
	ds_read_b64_tr_b4 v[136:137], v57
	s_waitcnt lgkmcnt(13)
	v_dot8c_i32_i4_e32 v38, v122, v48
	v_dot8c_i32_i4_e32 v39, v122, v46
	v_dot8c_i32_i4_e32 v40, v124, v48
	v_dot8c_i32_i4_e32 v41, v124, v46
	v_dot8c_i32_i4_e32 v42, v126, v48
	v_dot8c_i32_i4_e32 v43, v126, v46
	v_dot8c_i32_i4_e32 v44, v128, v48
	v_dot8c_i32_i4_e32 v45, v128, v46
	v_dot8c_i32_i4_e32 v38, v123, v49
	v_dot8c_i32_i4_e32 v39, v123, v47
	v_dot8c_i32_i4_e32 v40, v125, v49
	v_dot8c_i32_i4_e32 v41, v125, v47
	v_dot8c_i32_i4_e32 v42, v127, v49
	v_dot8c_i32_i4_e32 v43, v127, v47
	v_dot8c_i32_i4_e32 v44, v129, v49
	v_dot8c_i32_i4_e32 v45, v129, v47
	v_and_b32_e32 v78, 0xffff, v32
	v_lshrrev_b32_e32 v79, 16, v32
	v_lshl_add_u32 v78, v78, 7, v152
	v_lshl_add_u32 v79, v79, 7, v153
	s_mov_b32 m0, s78
	s_add_i32 s43, s78, 0x400
	global_load_lds_dwordx4 v78, s[50:51]
	s_mov_b32 m0, s43
	s_nop 0
	global_load_lds_dwordx4 v79, s[50:51]
	s_waitcnt vmcnt(9)
	v_add_u32_e32 v54, s98, v59
	v_add_u32_e32 v55, s98, v60
	v_add_u32_e32 v56, s98, v61
	v_add_u32_e32 v57, s98, v62
	ds_read_b64_tr_b4 v[46:47], v160 offset:256
	ds_read_b64_tr_b4 v[48:49], v160 offset:1280
	ds_read_b64_tr_b4 v[122:123], v54
	ds_read_b64_tr_b4 v[124:125], v55
	ds_read_b64_tr_b4 v[126:127], v56
	ds_read_b64_tr_b4 v[128:129], v57
	s_waitcnt lgkmcnt(6)
	v_dot8c_i32_i4_e32 v38, v130, v52
	v_dot8c_i32_i4_e32 v39, v130, v50
	v_dot8c_i32_i4_e32 v40, v132, v52
	v_dot8c_i32_i4_e32 v41, v132, v50
	v_dot8c_i32_i4_e32 v42, v134, v52
	v_dot8c_i32_i4_e32 v43, v134, v50
	v_dot8c_i32_i4_e32 v44, v136, v52
	v_dot8c_i32_i4_e32 v45, v136, v50
	v_dot8c_i32_i4_e32 v38, v131, v53
	v_dot8c_i32_i4_e32 v39, v131, v51
	v_dot8c_i32_i4_e32 v40, v133, v53
	v_dot8c_i32_i4_e32 v41, v133, v51
	v_dot8c_i32_i4_e32 v42, v135, v53
	v_dot8c_i32_i4_e32 v43, v135, v51
	v_dot8c_i32_i4_e32 v44, v137, v53
	v_dot8c_i32_i4_e32 v45, v137, v51
	ds_write_b16 v65, v186
	ds_write_b16_d16_hi v65, v186 offset:128
	ds_write_b16 v65, v187 offset:256
	ds_write_b16_d16_hi v65, v187 offset:384
	ds_write_b16 v65, v188 offset:512
	ds_write_b16_d16_hi v65, v188 offset:640
	ds_write_b16 v65, v189 offset:768
	ds_write_b16_d16_hi v65, v189 offset:896
	ds_write_b16 v65, v190 offset:1024
	ds_write_b16_d16_hi v65, v190 offset:1152
	ds_write_b16 v65, v191 offset:1280
	ds_write_b16_d16_hi v65, v191 offset:1408
	ds_write_b16 v65, v192 offset:1536
	ds_write_b16_d16_hi v65, v192 offset:1664
	ds_write_b16 v65, v193 offset:1792
	ds_write_b16_d16_hi v65, v193 offset:1920
	ds_read_b64 v[202:203], v154
	ds_read_b64 v[204:205], v154 offset:512
	ds_read_b64 v[206:207], v154 offset:1024
	ds_read_b64 v[208:209], v154 offset:1536
	v_and_b32_e32 v78, 0xffff, v33
	v_lshrrev_b32_e32 v79, 16, v33
	v_lshl_add_u32 v78, v78, 7, v152
	v_lshl_add_u32 v79, v79, 7, v153
	s_mov_b32 m0, s79
	s_add_i32 s43, s79, 0x400
	global_load_lds_dwordx4 v78, s[50:51]
	s_mov_b32 m0, s43
	s_nop 0
	global_load_lds_dwordx4 v79, s[50:51]
	s_waitcnt vmcnt(9)
; #define LAS __attribute__((address_space(3)))
; #define TR4(p_) __builtin_amdgcn_ds_read_tr4_b64_v2i32((LAS v2i*)(p_))
; __device__ __forceinline__ void peer_v_tokens(int j, const LAS unsigned short* EL, const LAS unsigned char* AL  , const LAS float* ASC  , const LAS int* SAL  , ...
;     ...
;         for (int m = 0; m < 2; ++m) {
;             const int idx = lane + 64 * m, tau = idx >> 4, sr = idx & 15, k = 16 * (sr & 7) + 2 * tau + (sr >> 3);
;             const int aq = (int)*(const LAS signed char*)(AL + tl * 128 + k); const int tq = aq + 8;
;             const unsigned lo = (((unsigned)tq & 15u) ^ 8u) * 0x11111111u, hi = ((unsigned)(tq >> 4) & 15u) * 0x11111111u;
;             typedef unsigned u2v __attribute__((ext_vector_type(2)));
;             u2v l2; l2.x = lo; l2.y = lo; u2v h2; h2.x = hi; h2.y = hi;
;             *(LAS u2v*)(ATL + 8 * idx) = l2; *(LAS u2v*)(ATL + 1024 + 8 * idx) = h2;
;         }
;     ...
; #pragma unroll
;         for (int st = 0; st < 16; ++st) {
;             const int p = st >> 2, q = st & 3;
;             if (st < 14) VDMA(st + 2, (st + 2) % 3);
;             if (st < 14) asm volatile("s_waitcnt vmcnt(8)" ::: "memory");
;             else if (st == 14) asm volatile("s_waitcnt vmcnt(4)" ::: "memory");
;             else asm volatile("s_waitcnt vmcnt(0)" ::: "memory");
;             if (q == 0) {
; #pragma unroll
;                 for (int r = 0; r < 4; ++r) { accH[r] = 0; accL[r] = 0; } }
; #pragma unroll
;             for (int tp = 0; tp < 2; ++tp) {
;                 const v2i ao = TR4(ATL + (2 * q + tp) * 128 + 8 * s16), ah = TR4(ATL + 1024 + (2 * q + tp) * 128 + 8 * s16);
; #pragma unroll
;                 for (int r = 0; r < 4; ++r) {
;                     const v2i d = TR4(ldsb + BUF[st % 3] + 2048 * tp + roff[r]);
;                     accH[r] = __builtin_amdgcn_sdot8(d.x, ah.x, accH[r], false); accH[r] = __builtin_amdgcn_sdot8(d.y, ah.y, accH[r], false);
;                     accL[r] = __builtin_amdgcn_sdot8(d.x, ao.x, accL[r], false); accL[r] = __builtin_amdgcn_sdot8(d.y, ao.y, accL[r], false);
;                 }
;             }
;             asm volatile("s_waitcnt lgkmcnt(0)" ::: "memory");
	v_add_u32_e32 v54, s99, v59
	v_add_u32_e32 v55, s99, v60
	v_add_u32_e32 v56, s99, v61
	v_add_u32_e32 v57, s99, v62
	ds_read_b64_tr_b4 v[50:51], v160 offset:384
	ds_read_b64_tr_b4 v[52:53], v160 offset:1408
	ds_read_b64_tr_b4 v[130:131], v54
	ds_read_b64_tr_b4 v[132:133], v55
	ds_read_b64_tr_b4 v[134:135], v56
	ds_read_b64_tr_b4 v[136:137], v57
	s_waitcnt lgkmcnt(15)
	v_dot8c_i32_i4_e32 v38, v122, v48
	v_dot8c_i32_i4_e32 v39, v122, v46
	v_dot8c_i32_i4_e32 v40, v124, v48
	v_dot8c_i32_i4_e32 v41, v124, v46
	v_dot8c_i32_i4_e32 v42, v126, v48
	v_dot8c_i32_i4_e32 v43, v126, v46
	v_dot8c_i32_i4_e32 v44, v128, v48
	v_dot8c_i32_i4_e32 v45, v128, v46
	v_dot8c_i32_i4_e32 v38, v123, v49
	v_dot8c_i32_i4_e32 v39, v123, v47
	v_dot8c_i32_i4_e32 v40, v125, v49
	v_dot8c_i32_i4_e32 v41, v125, v47
	v_dot8c_i32_i4_e32 v42, v127, v49
	v_dot8c_i32_i4_e32 v43, v127, v47
	v_dot8c_i32_i4_e32 v44, v129, v49
	v_dot8c_i32_i4_e32 v45, v129, v47
	s_waitcnt lgkmcnt(15)
	v_and_b32_e32 v78, 0xffff, v18
	v_lshrrev_b32_e32 v79, 16, v18
	v_lshl_add_u32 v78, v78, 7, v150
	v_lshl_add_u32 v79, v79, 7, v151
	s_mov_b32 m0, s98
	s_add_i32 s43, s98, 0x400
	global_load_lds_dwordx4 v78, s[50:51]
	s_mov_b32 m0, s43
	s_nop 0
	global_load_lds_dwordx4 v79, s[50:51]
	s_waitcnt vmcnt(9)
	v_add_u32_e32 v54, s76, v59
	v_add_u32_e32 v55, s76, v60
	v_add_u32_e32 v56, s76, v61
	v_add_u32_e32 v57, s76, v62
	ds_read_b64_tr_b4 v[46:47], v160 offset:512
	ds_read_b64_tr_b4 v[48:49], v160 offset:1536
	ds_read_b64_tr_b4 v[122:123], v54
	ds_read_b64_tr_b4 v[124:125], v55
	ds_read_b64_tr_b4 v[126:127], v56
	ds_read_b64_tr_b4 v[128:129], v57
	s_waitcnt lgkmcnt(6)
	v_dot8c_i32_i4_e32 v38, v130, v52
	v_dot8c_i32_i4_e32 v39, v130, v50
	v_dot8c_i32_i4_e32 v40, v132, v52
	v_dot8c_i32_i4_e32 v41, v132, v50
	v_dot8c_i32_i4_e32 v42, v134, v52
	v_dot8c_i32_i4_e32 v43, v134, v50
	v_dot8c_i32_i4_e32 v44, v136, v52
	v_dot8c_i32_i4_e32 v45, v136, v50
	v_dot8c_i32_i4_e32 v38, v131, v53
	v_dot8c_i32_i4_e32 v39, v131, v51
	v_dot8c_i32_i4_e32 v40, v133, v53
	v_dot8c_i32_i4_e32 v41, v133, v51
	v_dot8c_i32_i4_e32 v42, v135, v53
	v_dot8c_i32_i4_e32 v43, v135, v51
	v_dot8c_i32_i4_e32 v44, v137, v53
	v_dot8c_i32_i4_e32 v45, v137, v51
	v_and_b32_e32 v78, 0xffff, v19
	v_lshrrev_b32_e32 v79, 16, v19
	v_lshl_add_u32 v78, v78, 7, v150
	v_lshl_add_u32 v79, v79, 7, v151
	s_mov_b32 m0, s99
	s_add_i32 s43, s99, 0x400
	global_load_lds_dwordx4 v78, s[50:51]
	s_mov_b32 m0, s43
	s_nop 0
	global_load_lds_dwordx4 v79, s[50:51]
	s_waitcnt vmcnt(8)
	v_add_u32_e32 v54, s77, v59
	v_add_u32_e32 v55, s77, v60
	v_add_u32_e32 v56, s77, v61
	v_add_u32_e32 v57, s77, v62
	ds_read_b64_tr_b4 v[50:51], v160 offset:640
	ds_read_b64_tr_b4 v[52:53], v160 offset:1664
	ds_read_b64_tr_b4 v[130:131], v54
	ds_read_b64_tr_b4 v[132:133], v55
	ds_read_b64_tr_b4 v[134:135], v56
	ds_read_b64_tr_b4 v[136:137], v57
	s_waitcnt lgkmcnt(6)
	v_dot8c_i32_i4_e32 v38, v122, v48
	v_dot8c_i32_i4_e32 v39, v122, v46
	v_dot8c_i32_i4_e32 v40, v124, v48
	v_dot8c_i32_i4_e32 v41, v124, v46
	v_dot8c_i32_i4_e32 v42, v126, v48
	v_dot8c_i32_i4_e32 v43, v126, v46
	v_dot8c_i32_i4_e32 v44, v128, v48
	v_dot8c_i32_i4_e32 v45, v128, v46
	v_dot8c_i32_i4_e32 v38, v123, v49
	v_dot8c_i32_i4_e32 v39, v123, v47
	v_dot8c_i32_i4_e32 v40, v125, v49
	v_dot8c_i32_i4_e32 v41, v125, v47
	v_dot8c_i32_i4_e32 v42, v127, v49
	v_dot8c_i32_i4_e32 v43, v127, v47
	v_dot8c_i32_i4_e32 v44, v129, v49
	v_dot8c_i32_i4_e32 v45, v129, v47
	s_waitcnt lgkmcnt(15)
	v_add_u32_e32 v143, 8, v139
	v_and_b32_e32 v142, 15, v143
	v_xor_b32_e32 v142, 8, v142
	v_bfe_u32 v144, v143, 4, 4
	v_mul_lo_u32 v142, v142, s92
	v_mul_lo_u32 v144, v144, s92
	v_mov_b32_e32 v143, v142
	v_mov_b32_e32 v145, v144
	ds_write2st64_b64 v159, v[142:143], v[144:145] offset1:2
	v_and_b32_e32 v78, 0xffff, v20
	v_lshrrev_b32_e32 v79, 16, v20
	v_lshl_add_u32 v78, v78, 7, v150
	v_lshl_add_u32 v79, v79, 7, v151
	s_mov_b32 m0, s76
	s_add_i32 s43, s76, 0x400
	global_load_lds_dwordx4 v78, s[50:51]
	s_mov_b32 m0, s43
	s_nop 0
	global_load_lds_dwordx4 v79, s[50:51]
	s_waitcnt vmcnt(8)
	v_add_u32_e32 v54, s78, v59
	v_add_u32_e32 v55, s78, v60
	v_add_u32_e32 v56, s78, v61
	v_add_u32_e32 v57, s78, v62
	ds_read_b64_tr_b4 v[46:47], v160 offset:768
	ds_read_b64_tr_b4 v[48:49], v160 offset:1792
	ds_read_b64_tr_b4 v[122:123], v54
	ds_read_b64_tr_b4 v[124:125], v55
	ds_read_b64_tr_b4 v[126:127], v56
	ds_read_b64_tr_b4 v[128:129], v57
	s_waitcnt lgkmcnt(7)
	v_dot8c_i32_i4_e32 v38, v130, v52
	v_dot8c_i32_i4_e32 v39, v130, v50
	v_dot8c_i32_i4_e32 v40, v132, v52
	v_dot8c_i32_i4_e32 v41, v132, v50
	v_dot8c_i32_i4_e32 v42, v134, v52
	v_dot8c_i32_i4_e32 v43, v134, v50
	v_dot8c_i32_i4_e32 v44, v136, v52
	v_dot8c_i32_i4_e32 v45, v136, v50
	v_dot8c_i32_i4_e32 v38, v131, v53
	v_dot8c_i32_i4_e32 v39, v131, v51
	v_dot8c_i32_i4_e32 v40, v133, v53
	v_dot8c_i32_i4_e32 v41, v133, v51
	v_dot8c_i32_i4_e32 v42, v135, v53
	v_dot8c_i32_i4_e32 v43, v135, v51
	v_dot8c_i32_i4_e32 v44, v137, v53
	v_dot8c_i32_i4_e32 v45, v137, v51
	v_and_b32_e32 v78, 0xffff, v21
	v_lshrrev_b32_e32 v79, 16, v21
	v_lshl_add_u32 v78, v78, 7, v150
	v_lshl_add_u32 v79, v79, 7, v151
	s_mov_b32 m0, s77
	s_add_i32 s43, s77, 0x400
	global_load_lds_dwordx4 v78, s[50:51]
	s_mov_b32 m0, s43
	s_nop 0
	global_load_lds_dwordx4 v79, s[50:51]
	s_waitcnt vmcnt(8)
	v_add_u32_e32 v54, s79, v59
	v_add_u32_e32 v55, s79, v60
	v_add_u32_e32 v56, s79, v61
	v_add_u32_e32 v57, s79, v62
	ds_read_b64_tr_b4 v[50:51], v160 offset:896
	ds_read_b64_tr_b4 v[52:53], v160 offset:1920
	ds_read_b64_tr_b4 v[130:131], v54
	ds_read_b64_tr_b4 v[132:133], v55
	ds_read_b64_tr_b4 v[134:135], v56
	ds_read_b64_tr_b4 v[136:137], v57
	s_waitcnt lgkmcnt(6)
; #define LAS __attribute__((address_space(3)))
; __device__ __forceinline__ bf16 f2bf(float f) { return (bf16)f2bfu(f); }
; __device__ __forceinline__ void peer_v_tokens(int j, const LAS unsigned short* EL, const LAS unsigned char* AL  , const LAS float* ASC  , const LAS int* SAL  , ...
;     ...
;         const int tl = it * 8 + wave, t = j * 64 + tl;
;         unsigned E[8];
;         { const LAS v4u* ep = (const LAS v4u*)(EL + tl * 128 + 16 * g); const v4u e0 = ep[0], e1 = ep[1];
;           E[0] = e0.x; E[1] = e0.y; E[2] = e0.z; E[3] = e0.w; E[4] = e1.x; E[5] = e1.y; E[6] = e1.z; E[7] = e1.w; }
;     ...
; #pragma unroll
;         for (int st = 0; st < 16; ++st) {
;             const int p = st >> 2, q = st & 3;
;             if (st < 14) VDMA(st + 2, (st + 2) % 3);
;             if (st < 14) asm volatile("s_waitcnt vmcnt(8)" ::: "memory");
;             else if (st == 14) asm volatile("s_waitcnt vmcnt(4)" ::: "memory");
;             else asm volatile("s_waitcnt vmcnt(0)" ::: "memory");
;             if (q == 0) {
; #pragma unroll
;                 for (int r = 0; r < 4; ++r) { accH[r] = 0; accL[r] = 0; } }
; #pragma unroll
;             for (int tp = 0; tp < 2; ++tp) {
;                 const v2i ao = TR4(ATL + (2 * q + tp) * 128 + 8 * s16), ah = TR4(ATL + 1024 + (2 * q + tp) * 128 + 8 * s16);
; #pragma unroll
;                 for (int r = 0; r < 4; ++r) {
;                     const v2i d = TR4(ldsb + BUF[st % 3] + 2048 * tp + roff[r]);
;                     accH[r] = __builtin_amdgcn_sdot8(d.x, ah.x, accH[r], false); accH[r] = __builtin_amdgcn_sdot8(d.y, ah.y, accH[r], false);
;                     accL[r] = __builtin_amdgcn_sdot8(d.x, ao.x, accL[r], false); accL[r] = __builtin_amdgcn_sdot8(d.y, ao.y, accL[r], false);
;                 }
;             }
;             asm volatile("s_waitcnt lgkmcnt(0)" ::: "memory");
;             if (q == 3) {
; #pragma unroll
;                 for (int r = 0; r < 4; ++r) STASH[256 * p + 16 * (grp + 4 * r) + pc] = f2bf(asc * (float)(2 * ((accH[r] << 4) + accL[r]) + sa));
;             }
;         }
;     ...
;             for (int jq = 0; jq < 4; ++jq) { typedef float f4v __attribute__((ext_vector_type(4))); f4v o4; o4.x = v[jq].x * r3 * gv[jq].x; o4.y = v[jq].y * r3 * gv[jq].y; o4.z = v[jq].z * r3 * gv[jq].z; o4.w = v[jq].w * r3 * gv[jq].w;
;                 __builtin_nontemporal_store(o4, (f4v*)op + 64 * jq); }
	v_dot8c_i32_i4_e32 v38, v122, v48
	v_dot8c_i32_i4_e32 v39, v122, v46
	v_dot8c_i32_i4_e32 v40, v124, v48
	v_dot8c_i32_i4_e32 v41, v124, v46
	v_dot8c_i32_i4_e32 v42, v126, v48
	v_dot8c_i32_i4_e32 v43, v126, v46
	v_dot8c_i32_i4_e32 v44, v128, v48
	v_dot8c_i32_i4_e32 v45, v128, v46
	v_dot8c_i32_i4_e32 v38, v123, v49
	v_dot8c_i32_i4_e32 v39, v123, v47
	v_dot8c_i32_i4_e32 v40, v125, v49
	v_dot8c_i32_i4_e32 v41, v125, v47
	v_dot8c_i32_i4_e32 v42, v127, v49
	v_dot8c_i32_i4_e32 v43, v127, v47
	v_dot8c_i32_i4_e32 v44, v129, v49
	v_dot8c_i32_i4_e32 v45, v129, v47
	v_and_b32_e32 v78, 0xffff, v22
	v_lshrrev_b32_e32 v79, 16, v22
	v_lshl_add_u32 v78, v78, 7, v150
	v_lshl_add_u32 v79, v79, 7, v151
	s_mov_b32 m0, s78
	s_add_i32 s43, s78, 0x400
	global_load_lds_dwordx4 v78, s[50:51]
	s_mov_b32 m0, s43
	s_nop 0
	global_load_lds_dwordx4 v79, s[50:51]
	s_waitcnt vmcnt(8)
	v_add_u32_e32 v54, s98, v59
	v_add_u32_e32 v55, s98, v60
	v_add_u32_e32 v56, s98, v61
	v_add_u32_e32 v57, s98, v62
	ds_read_b64_tr_b4 v[46:47], v160
	ds_read_b64_tr_b4 v[48:49], v160 offset:1024
	ds_read_b64_tr_b4 v[122:123], v54
	ds_read_b64_tr_b4 v[124:125], v55
	ds_read_b64_tr_b4 v[126:127], v56
	ds_read_b64_tr_b4 v[128:129], v57
	s_waitcnt lgkmcnt(6)
	v_dot8c_i32_i4_e32 v38, v130, v52
	v_dot8c_i32_i4_e32 v39, v130, v50
	v_dot8c_i32_i4_e32 v40, v132, v52
	v_dot8c_i32_i4_e32 v41, v132, v50
	v_dot8c_i32_i4_e32 v42, v134, v52
	v_dot8c_i32_i4_e32 v43, v134, v50
	v_dot8c_i32_i4_e32 v44, v136, v52
	v_dot8c_i32_i4_e32 v45, v136, v50
	v_dot8c_i32_i4_e32 v38, v131, v53
	v_dot8c_i32_i4_e32 v39, v131, v51
	v_dot8c_i32_i4_e32 v40, v133, v53
	v_dot8c_i32_i4_e32 v41, v133, v51
	v_dot8c_i32_i4_e32 v42, v135, v53
	v_dot8c_i32_i4_e32 v43, v135, v51
	v_dot8c_i32_i4_e32 v44, v137, v53
	v_dot8c_i32_i4_e32 v45, v137, v51
	s_nop 3
	s_waitcnt lgkmcnt(15)
	v_lshlrev_b32_e32 v38, 5, v38
	v_lshlrev_b32_e32 v39, 1, v39
	v_add3_u32 v38, v39, v229, v38
	v_cvt_f32_i32_e32 v38, v38
	v_mul_f32_e32 v38, v228, v38
	v_lshlrev_b32_e32 v40, 5, v40
	v_lshlrev_b32_e32 v41, 1, v41
	v_add3_u32 v40, v41, v229, v40
	v_cvt_f32_i32_e32 v40, v40
	v_mul_f32_e32 v40, v228, v40
	v_lshlrev_b32_e32 v42, 5, v42
	v_lshlrev_b32_e32 v43, 1, v43
	v_add3_u32 v42, v43, v229, v42
	v_cvt_f32_i32_e32 v42, v42
	v_mul_f32_e32 v42, v228, v42
	v_lshlrev_b32_e32 v44, 5, v44
	v_lshlrev_b32_e32 v45, 1, v45
	v_add3_u32 v44, v45, v229, v44
	v_cvt_f32_i32_e32 v44, v44
	v_mul_f32_e32 v44, v228, v44
	v_cvt_pk_bf16_f32 v172, v38, v40
	v_cvt_pk_bf16_f32 v173, v42, v44
	ds_read_b128 v[252:255], v156
	s_add_i32 s44, s40, 16
	s_ashr_i32 s45, s44, 31
	s_lshl_b64 s[44:45], s[44:45], 12
	v_lshl_add_u64 v[80:81], v[36:37], 0, s[44:45]
	s_waitcnt lgkmcnt(0)
	v_mul_f32_e32 v218, v218, v252
	v_mul_f32_e32 v219, v219, v253
	v_mul_f32_e32 v220, v220, v254
	v_mul_f32_e32 v221, v221, v255
	global_store_dwordx4 v[80:81], v[218:221], off offset:2048 nt
	v_add_u32_e32 v147, 8, v140
	v_and_b32_e32 v146, 15, v147
	v_xor_b32_e32 v146, 8, v146
	v_bfe_u32 v148, v147, 4, 4
	v_mul_lo_u32 v146, v146, s92
	v_mul_lo_u32 v148, v148, s92
	v_mov_b32_e32 v147, v146
	v_mov_b32_e32 v149, v148
	ds_write2st64_b64 v77, v[146:147], v[148:149] offset1:2
	v_add_u32_e32 v138, 0x1400, v74
	ds_read_u8 v139, v138
	v_add_u32_e32 v141, 0x1400, v73
	ds_read_u8 v140, v141
	s_add_i32 s43, s67, 128
	v_mov_b32_e32 v138, s43
	ds_read2st64_b32 v[228:229], v138 offset1:1
	ds_read_b128 v[26:29], v227 offset:10240
	ds_read_b128 v[30:33], v227 offset:10256
	v_mov_b32_e32 v38, 0
	v_mov_b32_e32 v39, 0
	v_mov_b32_e32 v40, 0
	v_mov_b32_e32 v41, 0
	v_mov_b32_e32 v42, 0
	v_mov_b32_e32 v43, 0
	v_mov_b32_e32 v44, 0
	v_mov_b32_e32 v45, 0
	v_and_b32_e32 v78, 0xffff, v23
	v_lshrrev_b32_e32 v79, 16, v23
	v_lshl_add_u32 v78, v78, 7, v150
	v_lshl_add_u32 v79, v79, 7, v151
	s_mov_b32 m0, s79
	s_add_i32 s43, s79, 0x400
	global_load_lds_dwordx4 v78, s[50:51]
	s_mov_b32 m0, s43
	s_nop 0
	global_load_lds_dwordx4 v79, s[50:51]
	s_waitcnt vmcnt(9)
	v_add_u32_e32 v54, s99, v59
	v_add_u32_e32 v55, s99, v60
	v_add_u32_e32 v56, s99, v61
	v_add_u32_e32 v57, s99, v62
	ds_read_b64_tr_b4 v[50:51], v160 offset:128
	ds_read_b64_tr_b4 v[52:53], v160 offset:1152
	ds_read_b64_tr_b4 v[130:131], v54
	ds_read_b64_tr_b4 v[132:133], v55
	ds_read_b64_tr_b4 v[134:135], v56
	ds_read_b64_tr_b4 v[136:137], v57
	s_waitcnt lgkmcnt(13)
	s_waitcnt vmcnt(36) lgkmcnt(15)
; #define LAS __attribute__((address_space(3)))
; #define TR4(p_) __builtin_amdgcn_ds_read_tr4_b64_v2i32((LAS v2i*)(p_))
; __device__ __forceinline__ void peer_v_tokens(int j, const LAS unsigned short* EL, const LAS unsigned char* AL  , const LAS float* ASC  , const LAS int* SAL  , ...
;     ...
; #pragma unroll
;         for (int st = 0; st < 16; ++st) {
;             const int p = st >> 2, q = st & 3;
;             if (st < 14) VDMA(st + 2, (st + 2) % 3);
;             if (st < 14) asm volatile("s_waitcnt vmcnt(8)" ::: "memory");
;             else if (st == 14) asm volatile("s_waitcnt vmcnt(4)" ::: "memory");
;             else asm volatile("s_waitcnt vmcnt(0)" ::: "memory");
;             if (q == 0) {
; #pragma unroll
;                 for (int r = 0; r < 4; ++r) { accH[r] = 0; accL[r] = 0; } }
; #pragma unroll
;             for (int tp = 0; tp < 2; ++tp) {
;                 const v2i ao = TR4(ATL + (2 * q + tp) * 128 + 8 * s16), ah = TR4(ATL + 1024 + (2 * q + tp) * 128 + 8 * s16);
; #pragma unroll
;                 for (int r = 0; r < 4; ++r) {
;                     const v2i d = TR4(ldsb + BUF[st % 3] + 2048 * tp + roff[r]);
;                     accH[r] = __builtin_amdgcn_sdot8(d.x, ah.x, accH[r], false); accH[r] = __builtin_amdgcn_sdot8(d.y, ah.y, accH[r], false);
;                     accL[r] = __builtin_amdgcn_sdot8(d.x, ao.x, accL[r], false); accL[r] = __builtin_amdgcn_sdot8(d.y, ao.y, accL[r], false);
;                 }
;             }
;             asm volatile("s_waitcnt lgkmcnt(0)" ::: "memory");
;     ...
;         {
;             float4 v[4]; float ss = 0.f;
; #pragma unroll
;             for (int jq = 0; jq < 4; ++jq) { typedef unsigned u2v __attribute__((ext_vector_type(2))); const u2v pw = *(const LAS u2v*)(STASH + 4 * lane + 256 * jq); const uint2 hw = hv[jq];
;                 v[jq] = make_float4(__uint_as_float(hw.x << 16) + __uint_as_float(pw.x << 16), __uint_as_float(hw.x & 0xffff0000u) + __uint_as_float(pw.x & 0xffff0000u),
;                                     __uint_as_float(hw.y << 16) + __uint_as_float(pw.y << 16), __uint_as_float(hw.y & 0xffff0000u) + __uint_as_float(pw.y & 0xffff0000u));
;                 ss += v[jq].x * v[jq].x + v[jq].y * v[jq].y + v[jq].z * v[jq].z + v[jq].w * v[jq].w; }
;             ss = wave_sum(ss);
;             const float r3 = rsqrtf(ss * (1.f / D) + EPS);
	v_lshlrev_b32_e32 v236, 16, v194
	v_and_b32_e32 v237, 0xffff0000, v194
	v_lshlrev_b32_e32 v142, 16, v202
	v_and_b32_e32 v143, 0xffff0000, v202
	v_add_f32_e32 v236, v236, v142
	v_add_f32_e32 v237, v237, v143
	v_lshlrev_b32_e32 v238, 16, v195
	v_and_b32_e32 v239, 0xffff0000, v195
	v_lshlrev_b32_e32 v142, 16, v203
	v_and_b32_e32 v143, 0xffff0000, v203
	v_add_f32_e32 v238, v238, v142
	v_add_f32_e32 v239, v239, v143
	v_lshlrev_b32_e32 v240, 16, v196
	v_and_b32_e32 v241, 0xffff0000, v196
	v_lshlrev_b32_e32 v142, 16, v204
	v_and_b32_e32 v143, 0xffff0000, v204
	v_add_f32_e32 v240, v240, v142
	v_add_f32_e32 v241, v241, v143
	v_lshlrev_b32_e32 v242, 16, v197
	v_and_b32_e32 v243, 0xffff0000, v197
	v_lshlrev_b32_e32 v142, 16, v205
	v_and_b32_e32 v143, 0xffff0000, v205
	v_add_f32_e32 v242, v242, v142
	v_add_f32_e32 v243, v243, v143
	v_lshlrev_b32_e32 v244, 16, v198
	v_and_b32_e32 v245, 0xffff0000, v198
	v_lshlrev_b32_e32 v142, 16, v206
	v_and_b32_e32 v143, 0xffff0000, v206
	v_add_f32_e32 v244, v244, v142
	v_add_f32_e32 v245, v245, v143
	v_lshlrev_b32_e32 v246, 16, v199
	v_and_b32_e32 v247, 0xffff0000, v199
	v_lshlrev_b32_e32 v142, 16, v207
	v_and_b32_e32 v143, 0xffff0000, v207
	v_add_f32_e32 v246, v246, v142
	v_add_f32_e32 v247, v247, v143
	v_lshlrev_b32_e32 v248, 16, v200
	v_and_b32_e32 v249, 0xffff0000, v200
	v_lshlrev_b32_e32 v142, 16, v208
	v_and_b32_e32 v143, 0xffff0000, v208
	v_add_f32_e32 v248, v248, v142
	v_add_f32_e32 v249, v249, v143
	v_lshlrev_b32_e32 v250, 16, v201
	v_and_b32_e32 v251, 0xffff0000, v201
	v_lshlrev_b32_e32 v142, 16, v209
	v_and_b32_e32 v143, 0xffff0000, v209
	v_add_f32_e32 v250, v250, v142
	v_add_f32_e32 v251, v251, v143
	v_mov_b32_e32 v144, 0
	v_mul_f32_e32 v145, v236, v236
	v_fmac_f32_e32 v145, v237, v237
	v_fmac_f32_e32 v145, v238, v238
	v_fmac_f32_e32 v145, v239, v239
	v_add_f32_e32 v144, v144, v145
	v_mul_f32_e32 v145, v240, v240
	v_fmac_f32_e32 v145, v241, v241
	v_fmac_f32_e32 v145, v242, v242
	v_fmac_f32_e32 v145, v243, v243
	v_add_f32_e32 v144, v144, v145
	v_mul_f32_e32 v145, v244, v244
	v_fmac_f32_e32 v145, v245, v245
	v_fmac_f32_e32 v145, v246, v246
	v_fmac_f32_e32 v145, v247, v247
	v_add_f32_e32 v144, v144, v145
	v_mul_f32_e32 v145, v248, v248
	v_fmac_f32_e32 v145, v249, v249
	v_fmac_f32_e32 v145, v250, v250
	v_fmac_f32_e32 v145, v251, v251
	v_add_f32_e32 v144, v144, v145
	s_nop 1
	v_add_f32_dpp v144, v144, v144 quad_perm:[1,0,3,2] row_mask:0xf bank_mask:0xf bound_ctrl:1
	s_nop 1
	v_add_f32_dpp v144, v144, v144 quad_perm:[2,3,0,1] row_mask:0xf bank_mask:0xf bound_ctrl:1
	s_nop 1
	v_add_f32_dpp v144, v144, v144 row_half_mirror row_mask:0xf bank_mask:0xf bound_ctrl:1
	s_nop 1
	v_add_f32_dpp v144, v144, v144 row_mirror row_mask:0xf bank_mask:0xf bound_ctrl:1
	s_nop 1
	v_readlane_b32 s10, v144, 0
	v_readlane_b32 s11, v144, 16
	v_readlane_b32 s14, v144, 32
	v_readlane_b32 s15, v144, 48
	s_nop 3
	v_mov_b32_e32 v144, s11
	v_mov_b32_e32 v145, s15
	v_add_f32_e32 v144, s10, v144
	v_add_f32_e32 v145, s14, v145
	v_add_f32_e32 v144, v144, v145
	v_fmamk_f32 v144, v144, 0x3a800000, v111
	v_rsq_f32_e32 v144, v144
	s_nop 0
	v_mul_f32_e32 v236, v236, v144
	v_mul_f32_e32 v237, v237, v144
	v_mul_f32_e32 v238, v238, v144
	v_mul_f32_e32 v239, v239, v144
	v_mul_f32_e32 v240, v240, v144
	v_mul_f32_e32 v241, v241, v144
	v_mul_f32_e32 v242, v242, v144
	v_mul_f32_e32 v243, v243, v144
	v_mul_f32_e32 v244, v244, v144
	v_mul_f32_e32 v245, v245, v144
	v_mul_f32_e32 v246, v246, v144
	v_mul_f32_e32 v247, v247, v144
	v_mul_f32_e32 v248, v248, v144
	v_mul_f32_e32 v249, v249, v144
	v_mul_f32_e32 v250, v250, v144
	v_mul_f32_e32 v251, v251, v144
	v_dot8c_i32_i4_e32 v38, v122, v48
	v_dot8c_i32_i4_e32 v39, v122, v46
	v_dot8c_i32_i4_e32 v40, v124, v48
	v_dot8c_i32_i4_e32 v41, v124, v46
	v_dot8c_i32_i4_e32 v42, v126, v48
	v_dot8c_i32_i4_e32 v43, v126, v46
	v_dot8c_i32_i4_e32 v44, v128, v48
	v_dot8c_i32_i4_e32 v45, v128, v46
	v_dot8c_i32_i4_e32 v38, v123, v49
	v_dot8c_i32_i4_e32 v39, v123, v47
	v_dot8c_i32_i4_e32 v40, v125, v49
	v_dot8c_i32_i4_e32 v41, v125, v47
	v_dot8c_i32_i4_e32 v42, v127, v49
	v_dot8c_i32_i4_e32 v43, v127, v47
	v_dot8c_i32_i4_e32 v44, v129, v49
	v_dot8c_i32_i4_e32 v45, v129, v47
	v_and_b32_e32 v78, 0xffff, v24
	v_lshrrev_b32_e32 v79, 16, v24
	v_lshl_add_u32 v78, v78, 7, v150
	v_lshl_add_u32 v79, v79, 7, v151
	s_mov_b32 m0, s98
	s_add_i32 s43, s98, 0x400
	global_load_lds_dwordx4 v78, s[50:51]
	s_mov_b32 m0, s43
	s_nop 0
	global_load_lds_dwordx4 v79, s[50:51]
	s_waitcnt vmcnt(9)
	v_add_u32_e32 v54, s76, v59
	v_add_u32_e32 v55, s76, v60
	v_add_u32_e32 v56, s76, v61
	v_add_u32_e32 v57, s76, v62
	ds_read_b64_tr_b4 v[46:47], v160 offset:256
	ds_read_b64_tr_b4 v[48:49], v160 offset:1280
	ds_read_b64_tr_b4 v[122:123], v54
	ds_read_b64_tr_b4 v[124:125], v55
	ds_read_b64_tr_b4 v[126:127], v56
	ds_read_b64_tr_b4 v[128:129], v57
	s_waitcnt lgkmcnt(6)
	v_dot8c_i32_i4_e32 v38, v130, v52
	v_dot8c_i32_i4_e32 v39, v130, v50
	v_dot8c_i32_i4_e32 v40, v132, v52
	v_dot8c_i32_i4_e32 v41, v132, v50
	v_dot8c_i32_i4_e32 v42, v134, v52
	v_dot8c_i32_i4_e32 v43, v134, v50
	v_dot8c_i32_i4_e32 v44, v136, v52
	v_dot8c_i32_i4_e32 v45, v136, v50
	v_dot8c_i32_i4_e32 v38, v131, v53
	v_dot8c_i32_i4_e32 v39, v131, v51
	v_dot8c_i32_i4_e32 v40, v133, v53
	v_dot8c_i32_i4_e32 v41, v133, v51
	v_dot8c_i32_i4_e32 v42, v135, v53
	v_dot8c_i32_i4_e32 v43, v135, v51
	v_dot8c_i32_i4_e32 v44, v137, v53
	v_dot8c_i32_i4_e32 v45, v137, v51
	v_and_b32_e32 v78, 0xffff, v25
	v_lshrrev_b32_e32 v79, 16, v25
	v_lshl_add_u32 v78, v78, 7, v150
	v_lshl_add_u32 v79, v79, 7, v151
	s_mov_b32 m0, s99
	s_add_i32 s43, s99, 0x400
	global_load_lds_dwordx4 v78, s[50:51]
	s_mov_b32 m0, s43
	s_nop 0
	global_load_lds_dwordx4 v79, s[50:51]
	s_waitcnt vmcnt(9)
; #define LAS __attribute__((address_space(3)))
; #define TR4(p_) __builtin_amdgcn_ds_read_tr4_b64_v2i32((LAS v2i*)(p_))
; __device__ __forceinline__ void peer_v_tokens(int j, const LAS unsigned short* EL, const LAS unsigned char* AL  , const LAS float* ASC  , const LAS int* SAL  , ...
;     ...
;         for (int m = 0; m < 2; ++m) {
;             const int idx = lane + 64 * m, tau = idx >> 4, sr = idx & 15, k = 16 * (sr & 7) + 2 * tau + (sr >> 3);
;             const int aq = (int)*(const LAS signed char*)(AL + tl * 128 + k); const int tq = aq + 8;
;             const unsigned lo = (((unsigned)tq & 15u) ^ 8u) * 0x11111111u, hi = ((unsigned)(tq >> 4) & 15u) * 0x11111111u;
;             typedef unsigned u2v __attribute__((ext_vector_type(2)));
;             u2v l2; l2.x = lo; l2.y = lo; u2v h2; h2.x = hi; h2.y = hi;
;             *(LAS u2v*)(ATL + 8 * idx) = l2; *(LAS u2v*)(ATL + 1024 + 8 * idx) = h2;
;         }
;     ...
; #pragma unroll
;         for (int st = 0; st < 16; ++st) {
;             const int p = st >> 2, q = st & 3;
;             if (st < 14) VDMA(st + 2, (st + 2) % 3);
;             if (st < 14) asm volatile("s_waitcnt vmcnt(8)" ::: "memory");
;             else if (st == 14) asm volatile("s_waitcnt vmcnt(4)" ::: "memory");
;             else asm volatile("s_waitcnt vmcnt(0)" ::: "memory");
;             if (q == 0) {
; #pragma unroll
;                 for (int r = 0; r < 4; ++r) { accH[r] = 0; accL[r] = 0; } }
; #pragma unroll
;             for (int tp = 0; tp < 2; ++tp) {
;                 const v2i ao = TR4(ATL + (2 * q + tp) * 128 + 8 * s16), ah = TR4(ATL + 1024 + (2 * q + tp) * 128 + 8 * s16);
; #pragma unroll
;                 for (int r = 0; r < 4; ++r) {
;                     const v2i d = TR4(ldsb + BUF[st % 3] + 2048 * tp + roff[r]);
;                     accH[r] = __builtin_amdgcn_sdot8(d.x, ah.x, accH[r], false); accH[r] = __builtin_amdgcn_sdot8(d.y, ah.y, accH[r], false);
;                     accL[r] = __builtin_amdgcn_sdot8(d.x, ao.x, accL[r], false); accL[r] = __builtin_amdgcn_sdot8(d.y, ao.y, accL[r], false);
;                 }
;             }
;             asm volatile("s_waitcnt lgkmcnt(0)" ::: "memory");
	v_add_u32_e32 v54, s77, v59
	v_add_u32_e32 v55, s77, v60
	v_add_u32_e32 v56, s77, v61
	v_add_u32_e32 v57, s77, v62
	ds_read_b64_tr_b4 v[50:51], v160 offset:384
	ds_read_b64_tr_b4 v[52:53], v160 offset:1408
	ds_read_b64_tr_b4 v[130:131], v54
	ds_read_b64_tr_b4 v[132:133], v55
	ds_read_b64_tr_b4 v[134:135], v56
	ds_read_b64_tr_b4 v[136:137], v57
	s_waitcnt lgkmcnt(6)
	v_dot8c_i32_i4_e32 v38, v122, v48
	v_dot8c_i32_i4_e32 v39, v122, v46
	v_dot8c_i32_i4_e32 v40, v124, v48
	v_dot8c_i32_i4_e32 v41, v124, v46
	v_dot8c_i32_i4_e32 v42, v126, v48
	v_dot8c_i32_i4_e32 v43, v126, v46
	v_dot8c_i32_i4_e32 v44, v128, v48
	v_dot8c_i32_i4_e32 v45, v128, v46
	v_dot8c_i32_i4_e32 v38, v123, v49
	v_dot8c_i32_i4_e32 v39, v123, v47
	v_dot8c_i32_i4_e32 v40, v125, v49
	v_dot8c_i32_i4_e32 v41, v125, v47
	v_dot8c_i32_i4_e32 v42, v127, v49
	v_dot8c_i32_i4_e32 v43, v127, v47
	v_dot8c_i32_i4_e32 v44, v129, v49
	v_dot8c_i32_i4_e32 v45, v129, v47
	s_waitcnt lgkmcnt(15)
	v_and_b32_e32 v78, 0xffff, v26
	v_lshrrev_b32_e32 v79, 16, v26
	v_lshl_add_u32 v78, v78, 7, v150
	v_lshl_add_u32 v79, v79, 7, v151
	s_mov_b32 m0, s76
	s_add_i32 s43, s76, 0x400
	global_load_lds_dwordx4 v78, s[50:51]
	s_mov_b32 m0, s43
	s_nop 0
	global_load_lds_dwordx4 v79, s[50:51]
	s_waitcnt vmcnt(9)
	v_add_u32_e32 v54, s78, v59
	v_add_u32_e32 v55, s78, v60
	v_add_u32_e32 v56, s78, v61
	v_add_u32_e32 v57, s78, v62
	ds_read_b64_tr_b4 v[46:47], v160 offset:512
	ds_read_b64_tr_b4 v[48:49], v160 offset:1536
	ds_read_b64_tr_b4 v[122:123], v54
	ds_read_b64_tr_b4 v[124:125], v55
	ds_read_b64_tr_b4 v[126:127], v56
	ds_read_b64_tr_b4 v[128:129], v57
	s_waitcnt lgkmcnt(6)
	v_dot8c_i32_i4_e32 v38, v130, v52
	v_dot8c_i32_i4_e32 v39, v130, v50
	v_dot8c_i32_i4_e32 v40, v132, v52
	v_dot8c_i32_i4_e32 v41, v132, v50
	v_dot8c_i32_i4_e32 v42, v134, v52
	v_dot8c_i32_i4_e32 v43, v134, v50
	v_dot8c_i32_i4_e32 v44, v136, v52
	v_dot8c_i32_i4_e32 v45, v136, v50
	v_dot8c_i32_i4_e32 v38, v131, v53
	v_dot8c_i32_i4_e32 v39, v131, v51
	v_dot8c_i32_i4_e32 v40, v133, v53
	v_dot8c_i32_i4_e32 v41, v133, v51
	v_dot8c_i32_i4_e32 v42, v135, v53
	v_dot8c_i32_i4_e32 v43, v135, v51
	v_dot8c_i32_i4_e32 v44, v137, v53
	v_dot8c_i32_i4_e32 v45, v137, v51
	v_and_b32_e32 v78, 0xffff, v27
	v_lshrrev_b32_e32 v79, 16, v27
	v_lshl_add_u32 v78, v78, 7, v150
	v_lshl_add_u32 v79, v79, 7, v151
	s_mov_b32 m0, s77
	s_add_i32 s43, s77, 0x400
	global_load_lds_dwordx4 v78, s[50:51]
	s_mov_b32 m0, s43
	s_nop 0
	global_load_lds_dwordx4 v79, s[50:51]
	s_waitcnt vmcnt(8)
	v_add_u32_e32 v54, s79, v59
	v_add_u32_e32 v55, s79, v60
	v_add_u32_e32 v56, s79, v61
	v_add_u32_e32 v57, s79, v62
	ds_read_b64_tr_b4 v[50:51], v160 offset:640
	ds_read_b64_tr_b4 v[52:53], v160 offset:1664
	ds_read_b64_tr_b4 v[130:131], v54
	ds_read_b64_tr_b4 v[132:133], v55
	ds_read_b64_tr_b4 v[134:135], v56
	ds_read_b64_tr_b4 v[136:137], v57
	s_waitcnt lgkmcnt(6)
	v_dot8c_i32_i4_e32 v38, v122, v48
	v_dot8c_i32_i4_e32 v39, v122, v46
	v_dot8c_i32_i4_e32 v40, v124, v48
	v_dot8c_i32_i4_e32 v41, v124, v46
	v_dot8c_i32_i4_e32 v42, v126, v48
	v_dot8c_i32_i4_e32 v43, v126, v46
	v_dot8c_i32_i4_e32 v44, v128, v48
	v_dot8c_i32_i4_e32 v45, v128, v46
	v_dot8c_i32_i4_e32 v38, v123, v49
	v_dot8c_i32_i4_e32 v39, v123, v47
	v_dot8c_i32_i4_e32 v40, v125, v49
	v_dot8c_i32_i4_e32 v41, v125, v47
	v_dot8c_i32_i4_e32 v42, v127, v49
	v_dot8c_i32_i4_e32 v43, v127, v47
	v_dot8c_i32_i4_e32 v44, v129, v49
	v_dot8c_i32_i4_e32 v45, v129, v47
	s_waitcnt lgkmcnt(15)
	v_add_u32_e32 v143, 8, v139
	v_and_b32_e32 v142, 15, v143
	v_xor_b32_e32 v142, 8, v142
	v_bfe_u32 v144, v143, 4, 4
	v_mul_lo_u32 v142, v142, s92
	v_mul_lo_u32 v144, v144, s92
	v_mov_b32_e32 v143, v142
	v_mov_b32_e32 v145, v144
	ds_write2st64_b64 v159, v[142:143], v[144:145] offset1:2
	v_and_b32_e32 v78, 0xffff, v28
	v_lshrrev_b32_e32 v79, 16, v28
	v_lshl_add_u32 v78, v78, 7, v150
	v_lshl_add_u32 v79, v79, 7, v151
	s_mov_b32 m0, s78
	s_add_i32 s43, s78, 0x400
	global_load_lds_dwordx4 v78, s[50:51]
	s_mov_b32 m0, s43
	s_nop 0
	global_load_lds_dwordx4 v79, s[50:51]
	s_waitcnt vmcnt(8)
	v_add_u32_e32 v54, s98, v59
	v_add_u32_e32 v55, s98, v60
	v_add_u32_e32 v56, s98, v61
	v_add_u32_e32 v57, s98, v62
	ds_read_b64_tr_b4 v[46:47], v160 offset:768
	ds_read_b64_tr_b4 v[48:49], v160 offset:1792
	ds_read_b64_tr_b4 v[122:123], v54
	ds_read_b64_tr_b4 v[124:125], v55
	ds_read_b64_tr_b4 v[126:127], v56
	ds_read_b64_tr_b4 v[128:129], v57
	s_waitcnt lgkmcnt(7)
	v_dot8c_i32_i4_e32 v38, v130, v52
	v_dot8c_i32_i4_e32 v39, v130, v50
	v_dot8c_i32_i4_e32 v40, v132, v52
	v_dot8c_i32_i4_e32 v41, v132, v50
	v_dot8c_i32_i4_e32 v42, v134, v52
	v_dot8c_i32_i4_e32 v43, v134, v50
	v_dot8c_i32_i4_e32 v44, v136, v52
	v_dot8c_i32_i4_e32 v45, v136, v50
	v_dot8c_i32_i4_e32 v38, v131, v53
	v_dot8c_i32_i4_e32 v39, v131, v51
	v_dot8c_i32_i4_e32 v40, v133, v53
	v_dot8c_i32_i4_e32 v41, v133, v51
	v_dot8c_i32_i4_e32 v42, v135, v53
	v_dot8c_i32_i4_e32 v43, v135, v51
	v_dot8c_i32_i4_e32 v44, v137, v53
	v_dot8c_i32_i4_e32 v45, v137, v51
	v_and_b32_e32 v78, 0xffff, v29
	v_lshrrev_b32_e32 v79, 16, v29
	v_lshl_add_u32 v78, v78, 7, v150
	v_lshl_add_u32 v79, v79, 7, v151
	s_mov_b32 m0, s79
	s_add_i32 s43, s79, 0x400
	global_load_lds_dwordx4 v78, s[50:51]
	s_mov_b32 m0, s43
	s_nop 0
	global_load_lds_dwordx4 v79, s[50:51]
	s_waitcnt vmcnt(8)
	v_add_u32_e32 v54, s99, v59
	v_add_u32_e32 v55, s99, v60
	v_add_u32_e32 v56, s99, v61
	v_add_u32_e32 v57, s99, v62
	ds_read_b64_tr_b4 v[50:51], v160 offset:896
	ds_read_b64_tr_b4 v[52:53], v160 offset:1920
	ds_read_b64_tr_b4 v[130:131], v54
	ds_read_b64_tr_b4 v[132:133], v55
	ds_read_b64_tr_b4 v[134:135], v56
	ds_read_b64_tr_b4 v[136:137], v57
	s_waitcnt lgkmcnt(6)
; #define LAS __attribute__((address_space(3)))
; __device__ __forceinline__ void peer_v_tokens(int j, const LAS unsigned short* EL, const LAS unsigned char* AL  , const LAS float* ASC  , const LAS int* SAL  , ...
;     ...
;         const int tl = it * 8 + wave, t = j * 64 + tl;
;         unsigned E[8];
;         { const LAS v4u* ep = (const LAS v4u*)(EL + tl * 128 + 16 * g); const v4u e0 = ep[0], e1 = ep[1];
;           E[0] = e0.x; E[1] = e0.y; E[2] = e0.z; E[3] = e0.w; E[4] = e1.x; E[5] = e1.y; E[6] = e1.z; E[7] = e1.w; }
;     ...
;         for (int m = 0; m < 2; ++m) {
;             const int idx = lane + 64 * m, tau = idx >> 4, sr = idx & 15, k = 16 * (sr & 7) + 2 * tau + (sr >> 3);
;             const int aq = (int)*(const LAS signed char*)(AL + tl * 128 + k); const int tq = aq + 8;
;             const unsigned lo = (((unsigned)tq & 15u) ^ 8u) * 0x11111111u, hi = ((unsigned)(tq >> 4) & 15u) * 0x11111111u;
;             typedef unsigned u2v __attribute__((ext_vector_type(2)));
;             u2v l2; l2.x = lo; l2.y = lo; u2v h2; h2.x = hi; h2.y = hi;
;             *(LAS u2v*)(ATL + 8 * idx) = l2; *(LAS u2v*)(ATL + 1024 + 8 * idx) = h2;
;         }
;     ...
; #pragma unroll
;         for (int st = 0; st < 16; ++st) {
;             const int p = st >> 2, q = st & 3;
;             if (st < 14) VDMA(st + 2, (st + 2) % 3);
;             if (st < 14) asm volatile("s_waitcnt vmcnt(8)" ::: "memory");
;             else if (st == 14) asm volatile("s_waitcnt vmcnt(4)" ::: "memory");
;             else asm volatile("s_waitcnt vmcnt(0)" ::: "memory");
;             if (q == 0) {
; #pragma unroll
;                 for (int r = 0; r < 4; ++r) { accH[r] = 0; accL[r] = 0; } }
; #pragma unroll
;             for (int tp = 0; tp < 2; ++tp) {
;                 const v2i ao = TR4(ATL + (2 * q + tp) * 128 + 8 * s16), ah = TR4(ATL + 1024 + (2 * q + tp) * 128 + 8 * s16);
; #pragma unroll
;                 for (int r = 0; r < 4; ++r) {
;     ...
;                 for (int r = 0; r < 4; ++r) STASH[256 * p + 16 * (grp + 4 * r) + pc] = f2bf(asc * (float)(2 * ((accH[r] << 4) + accL[r]) + sa));
;     ...
;             for (int jq = 0; jq < 4; ++jq) { typedef float f4v __attribute__((ext_vector_type(4))); f4v o4; o4.x = v[jq].x * r3 * gv[jq].x; o4.y = v[jq].y * r3 * gv[jq].y; o4.z = v[jq].z * r3 * gv[jq].z; o4.w = v[jq].w * r3 * gv[jq].w;
;                 __builtin_nontemporal_store(o4, (f4v*)op + 64 * jq); }
	v_dot8c_i32_i4_e32 v38, v122, v48
	v_dot8c_i32_i4_e32 v39, v122, v46
	v_dot8c_i32_i4_e32 v40, v124, v48
	v_dot8c_i32_i4_e32 v41, v124, v46
	v_dot8c_i32_i4_e32 v42, v126, v48
	v_dot8c_i32_i4_e32 v43, v126, v46
	v_dot8c_i32_i4_e32 v44, v128, v48
	v_dot8c_i32_i4_e32 v45, v128, v46
	v_dot8c_i32_i4_e32 v38, v123, v49
	v_dot8c_i32_i4_e32 v39, v123, v47
	v_dot8c_i32_i4_e32 v40, v125, v49
	v_dot8c_i32_i4_e32 v41, v125, v47
	v_dot8c_i32_i4_e32 v42, v127, v49
	v_dot8c_i32_i4_e32 v43, v127, v47
	v_dot8c_i32_i4_e32 v44, v129, v49
	v_dot8c_i32_i4_e32 v45, v129, v47
	v_and_b32_e32 v78, 0xffff, v30
	v_lshrrev_b32_e32 v79, 16, v30
	v_lshl_add_u32 v78, v78, 7, v150
	v_lshl_add_u32 v79, v79, 7, v151
	s_mov_b32 m0, s98
	s_add_i32 s43, s98, 0x400
	global_load_lds_dwordx4 v78, s[50:51]
	s_mov_b32 m0, s43
	s_nop 0
	global_load_lds_dwordx4 v79, s[50:51]
	s_waitcnt vmcnt(8)
	v_add_u32_e32 v54, s76, v59
	v_add_u32_e32 v55, s76, v60
	v_add_u32_e32 v56, s76, v61
	v_add_u32_e32 v57, s76, v62
	ds_read_b64_tr_b4 v[46:47], v160
	ds_read_b64_tr_b4 v[48:49], v160 offset:1024
	ds_read_b64_tr_b4 v[122:123], v54
	ds_read_b64_tr_b4 v[124:125], v55
	ds_read_b64_tr_b4 v[126:127], v56
	ds_read_b64_tr_b4 v[128:129], v57
	s_waitcnt lgkmcnt(6)
	v_dot8c_i32_i4_e32 v38, v130, v52
	v_dot8c_i32_i4_e32 v39, v130, v50
	v_dot8c_i32_i4_e32 v40, v132, v52
	v_dot8c_i32_i4_e32 v41, v132, v50
	v_dot8c_i32_i4_e32 v42, v134, v52
	v_dot8c_i32_i4_e32 v43, v134, v50
	v_dot8c_i32_i4_e32 v44, v136, v52
	v_dot8c_i32_i4_e32 v45, v136, v50
	v_dot8c_i32_i4_e32 v38, v131, v53
	v_dot8c_i32_i4_e32 v39, v131, v51
	v_dot8c_i32_i4_e32 v40, v133, v53
	v_dot8c_i32_i4_e32 v41, v133, v51
	v_dot8c_i32_i4_e32 v42, v135, v53
	v_dot8c_i32_i4_e32 v43, v135, v51
	v_dot8c_i32_i4_e32 v44, v137, v53
	v_dot8c_i32_i4_e32 v45, v137, v51
	s_nop 3
	s_waitcnt lgkmcnt(15)
	v_lshlrev_b32_e32 v38, 5, v38
	v_lshlrev_b32_e32 v39, 1, v39
	v_add3_u32 v38, v39, v229, v38
	v_cvt_f32_i32_e32 v38, v38
	v_mul_f32_e32 v38, v228, v38
	v_lshlrev_b32_e32 v40, 5, v40
	v_lshlrev_b32_e32 v41, 1, v41
	v_add3_u32 v40, v41, v229, v40
	v_cvt_f32_i32_e32 v40, v40
	v_mul_f32_e32 v40, v228, v40
	v_lshlrev_b32_e32 v42, 5, v42
	v_lshlrev_b32_e32 v43, 1, v43
	v_add3_u32 v42, v43, v229, v42
	v_cvt_f32_i32_e32 v42, v42
	v_mul_f32_e32 v42, v228, v42
	v_lshlrev_b32_e32 v44, 5, v44
	v_lshlrev_b32_e32 v45, 1, v45
	v_add3_u32 v44, v45, v229, v44
	v_cvt_f32_i32_e32 v44, v44
	v_mul_f32_e32 v44, v228, v44
	v_cvt_pk_bf16_f32 v166, v38, v40
	v_cvt_pk_bf16_f32 v167, v42, v44
	ds_read_b128 v[252:255], v156 offset:1024
	s_add_i32 s44, s40, 16
	s_ashr_i32 s45, s44, 31
	s_lshl_b64 s[44:45], s[44:45], 12
	v_lshl_add_u64 v[80:81], v[36:37], 0, s[44:45]
	s_waitcnt lgkmcnt(0)
	v_mul_f32_e32 v222, v222, v252
	v_mul_f32_e32 v223, v223, v253
	v_mul_f32_e32 v224, v224, v254
	v_mul_f32_e32 v225, v225, v255
	global_store_dwordx4 v[80:81], v[222:225], off offset:3072 nt
	ds_read_b128 v[252:255], v155
	s_add_i32 s44, s40, 24
	s_ashr_i32 s45, s44, 31
	s_lshl_b64 s[44:45], s[44:45], 12
	v_lshl_add_u64 v[80:81], v[36:37], 0, s[44:45]
	s_waitcnt lgkmcnt(0)
	v_mul_f32_e32 v236, v236, v252
	v_mul_f32_e32 v237, v237, v253
	v_mul_f32_e32 v238, v238, v254
	v_mul_f32_e32 v239, v239, v255
	global_store_dwordx4 v[80:81], v[236:239], off nt
	v_add_u32_e32 v147, 8, v140
	v_and_b32_e32 v146, 15, v147
	v_xor_b32_e32 v146, 8, v146
	v_bfe_u32 v148, v147, 4, 4
	v_mul_lo_u32 v146, v146, s92
	v_mul_lo_u32 v148, v148, s92
	v_mov_b32_e32 v147, v146
	v_mov_b32_e32 v149, v148
	ds_write2st64_b64 v77, v[146:147], v[148:149] offset1:2
	v_add_u32_e32 v138, 0x1000, v74
	ds_read_u8 v139, v138
	v_add_u32_e32 v141, 0x1000, v73
	ds_read_u8 v140, v141
	s_add_i32 s43, s67, 160
	v_mov_b32_e32 v138, s43
	ds_read2st64_b32 v[228:229], v138 offset1:1
	ds_read_b128 v[18:21], v227 offset:8192
	ds_read_b128 v[22:25], v227 offset:8208
	v_add_u32_e32 v152, 0x600000, v63
	v_add_u32_e32 v153, 0x600000, v64
	v_mov_b32_e32 v38, 0
	v_mov_b32_e32 v39, 0
	v_mov_b32_e32 v40, 0
	v_mov_b32_e32 v41, 0
	v_mov_b32_e32 v42, 0
	v_mov_b32_e32 v43, 0
	v_mov_b32_e32 v44, 0
	v_mov_b32_e32 v45, 0
	v_and_b32_e32 v78, 0xffff, v31
	v_lshrrev_b32_e32 v79, 16, v31
	v_lshl_add_u32 v78, v78, 7, v150
	v_lshl_add_u32 v79, v79, 7, v151
	s_mov_b32 m0, s99
	s_add_i32 s43, s99, 0x400
	global_load_lds_dwordx4 v78, s[50:51]
	s_mov_b32 m0, s43
	s_nop 0
	global_load_lds_dwordx4 v79, s[50:51]
	s_waitcnt vmcnt(10)
	v_add_u32_e32 v54, s77, v59
	v_add_u32_e32 v55, s77, v60
	v_add_u32_e32 v56, s77, v61
	v_add_u32_e32 v57, s77, v62
	ds_read_b64_tr_b4 v[50:51], v160 offset:128
	ds_read_b64_tr_b4 v[52:53], v160 offset:1152
	ds_read_b64_tr_b4 v[130:131], v54
	ds_read_b64_tr_b4 v[132:133], v55
	ds_read_b64_tr_b4 v[134:135], v56
	ds_read_b64_tr_b4 v[136:137], v57
	s_waitcnt lgkmcnt(14)
	v_dot8c_i32_i4_e32 v38, v122, v48
	v_dot8c_i32_i4_e32 v39, v122, v46
	v_dot8c_i32_i4_e32 v40, v124, v48
	v_dot8c_i32_i4_e32 v41, v124, v46
	v_dot8c_i32_i4_e32 v42, v126, v48
	v_dot8c_i32_i4_e32 v43, v126, v46
	v_dot8c_i32_i4_e32 v44, v128, v48
	v_dot8c_i32_i4_e32 v45, v128, v46
	v_dot8c_i32_i4_e32 v38, v123, v49
	v_dot8c_i32_i4_e32 v39, v123, v47
	v_dot8c_i32_i4_e32 v40, v125, v49
	v_dot8c_i32_i4_e32 v41, v125, v47
	v_dot8c_i32_i4_e32 v42, v127, v49
	v_dot8c_i32_i4_e32 v43, v127, v47
	v_dot8c_i32_i4_e32 v44, v129, v49
	v_dot8c_i32_i4_e32 v45, v129, v47
	v_and_b32_e32 v78, 0xffff, v32
	v_lshrrev_b32_e32 v79, 16, v32
	v_lshl_add_u32 v78, v78, 7, v150
	v_lshl_add_u32 v79, v79, 7, v151
	s_mov_b32 m0, s76
	s_add_i32 s43, s76, 0x400
	global_load_lds_dwordx4 v78, s[50:51]
	s_mov_b32 m0, s43
	s_nop 0
	global_load_lds_dwordx4 v79, s[50:51]
	s_waitcnt vmcnt(10)
; #define LAS __attribute__((address_space(3)))
; #define TR4(p_) __builtin_amdgcn_ds_read_tr4_b64_v2i32((LAS v2i*)(p_))
; __device__ __forceinline__ void peer_v_tokens(int j, const LAS unsigned short* EL, const LAS unsigned char* AL  , const LAS float* ASC  , const LAS int* SAL  , ...
;     ...
;         for (int m = 0; m < 2; ++m) {
;             const int idx = lane + 64 * m, tau = idx >> 4, sr = idx & 15, k = 16 * (sr & 7) + 2 * tau + (sr >> 3);
;             const int aq = (int)*(const LAS signed char*)(AL + tl * 128 + k); const int tq = aq + 8;
;             const unsigned lo = (((unsigned)tq & 15u) ^ 8u) * 0x11111111u, hi = ((unsigned)(tq >> 4) & 15u) * 0x11111111u;
;             typedef unsigned u2v __attribute__((ext_vector_type(2)));
;             u2v l2; l2.x = lo; l2.y = lo; u2v h2; h2.x = hi; h2.y = hi;
;             *(LAS u2v*)(ATL + 8 * idx) = l2; *(LAS u2v*)(ATL + 1024 + 8 * idx) = h2;
;         }
;     ...
; #pragma unroll
;         for (int st = 0; st < 16; ++st) {
;             const int p = st >> 2, q = st & 3;
;             if (st < 14) VDMA(st + 2, (st + 2) % 3);
;             if (st < 14) asm volatile("s_waitcnt vmcnt(8)" ::: "memory");
;             else if (st == 14) asm volatile("s_waitcnt vmcnt(4)" ::: "memory");
;             else asm volatile("s_waitcnt vmcnt(0)" ::: "memory");
;             if (q == 0) {
; #pragma unroll
;                 for (int r = 0; r < 4; ++r) { accH[r] = 0; accL[r] = 0; } }
; #pragma unroll
;             for (int tp = 0; tp < 2; ++tp) {
;                 const v2i ao = TR4(ATL + (2 * q + tp) * 128 + 8 * s16), ah = TR4(ATL + 1024 + (2 * q + tp) * 128 + 8 * s16);
; #pragma unroll
;                 for (int r = 0; r < 4; ++r) {
;                     const v2i d = TR4(ldsb + BUF[st % 3] + 2048 * tp + roff[r]);
;                     accH[r] = __builtin_amdgcn_sdot8(d.x, ah.x, accH[r], false); accH[r] = __builtin_amdgcn_sdot8(d.y, ah.y, accH[r], false);
;                     accL[r] = __builtin_amdgcn_sdot8(d.x, ao.x, accL[r], false); accL[r] = __builtin_amdgcn_sdot8(d.y, ao.y, accL[r], false);
;                 }
;             }
;             asm volatile("s_waitcnt lgkmcnt(0)" ::: "memory");
	v_add_u32_e32 v54, s78, v59
	v_add_u32_e32 v55, s78, v60
	v_add_u32_e32 v56, s78, v61
	v_add_u32_e32 v57, s78, v62
	ds_read_b64_tr_b4 v[46:47], v160 offset:256
	ds_read_b64_tr_b4 v[48:49], v160 offset:1280
	ds_read_b64_tr_b4 v[122:123], v54
	ds_read_b64_tr_b4 v[124:125], v55
	ds_read_b64_tr_b4 v[126:127], v56
	ds_read_b64_tr_b4 v[128:129], v57
	s_waitcnt lgkmcnt(6)
	v_dot8c_i32_i4_e32 v38, v130, v52
	v_dot8c_i32_i4_e32 v39, v130, v50
	v_dot8c_i32_i4_e32 v40, v132, v52
	v_dot8c_i32_i4_e32 v41, v132, v50
	v_dot8c_i32_i4_e32 v42, v134, v52
	v_dot8c_i32_i4_e32 v43, v134, v50
	v_dot8c_i32_i4_e32 v44, v136, v52
	v_dot8c_i32_i4_e32 v45, v136, v50
	v_dot8c_i32_i4_e32 v38, v131, v53
	v_dot8c_i32_i4_e32 v39, v131, v51
	v_dot8c_i32_i4_e32 v40, v133, v53
	v_dot8c_i32_i4_e32 v41, v133, v51
	v_dot8c_i32_i4_e32 v42, v135, v53
	v_dot8c_i32_i4_e32 v43, v135, v51
	v_dot8c_i32_i4_e32 v44, v137, v53
	v_dot8c_i32_i4_e32 v45, v137, v51
	v_and_b32_e32 v78, 0xffff, v33
	v_lshrrev_b32_e32 v79, 16, v33
	v_lshl_add_u32 v78, v78, 7, v150
	v_lshl_add_u32 v79, v79, 7, v151
	s_mov_b32 m0, s77
	s_add_i32 s43, s77, 0x400
	global_load_lds_dwordx4 v78, s[50:51]
	s_mov_b32 m0, s43
	s_nop 0
	global_load_lds_dwordx4 v79, s[50:51]
	s_waitcnt vmcnt(10)
	v_add_u32_e32 v54, s79, v59
	v_add_u32_e32 v55, s79, v60
	v_add_u32_e32 v56, s79, v61
	v_add_u32_e32 v57, s79, v62
	ds_read_b64_tr_b4 v[50:51], v160 offset:384
	ds_read_b64_tr_b4 v[52:53], v160 offset:1408
	ds_read_b64_tr_b4 v[130:131], v54
	ds_read_b64_tr_b4 v[132:133], v55
	ds_read_b64_tr_b4 v[134:135], v56
	ds_read_b64_tr_b4 v[136:137], v57
	s_waitcnt lgkmcnt(6)
	v_dot8c_i32_i4_e32 v38, v122, v48
	v_dot8c_i32_i4_e32 v39, v122, v46
	v_dot8c_i32_i4_e32 v40, v124, v48
	v_dot8c_i32_i4_e32 v41, v124, v46
	v_dot8c_i32_i4_e32 v42, v126, v48
	v_dot8c_i32_i4_e32 v43, v126, v46
	v_dot8c_i32_i4_e32 v44, v128, v48
	v_dot8c_i32_i4_e32 v45, v128, v46
	v_dot8c_i32_i4_e32 v38, v123, v49
	v_dot8c_i32_i4_e32 v39, v123, v47
	v_dot8c_i32_i4_e32 v40, v125, v49
	v_dot8c_i32_i4_e32 v41, v125, v47
	v_dot8c_i32_i4_e32 v42, v127, v49
	v_dot8c_i32_i4_e32 v43, v127, v47
	v_dot8c_i32_i4_e32 v44, v129, v49
	v_dot8c_i32_i4_e32 v45, v129, v47
	s_waitcnt lgkmcnt(15)
	v_and_b32_e32 v78, 0xffff, v18
	v_lshrrev_b32_e32 v79, 16, v18
	v_lshl_add_u32 v78, v78, 7, v152
	v_lshl_add_u32 v79, v79, 7, v153
	s_mov_b32 m0, s78
	s_add_i32 s43, s78, 0x400
	global_load_lds_dwordx4 v78, s[50:51]
	s_mov_b32 m0, s43
	s_nop 0
	global_load_lds_dwordx4 v79, s[50:51]
	s_waitcnt vmcnt(10)
	v_add_u32_e32 v54, s98, v59
	v_add_u32_e32 v55, s98, v60
	v_add_u32_e32 v56, s98, v61
	v_add_u32_e32 v57, s98, v62
	ds_read_b64_tr_b4 v[46:47], v160 offset:512
	ds_read_b64_tr_b4 v[48:49], v160 offset:1536
	ds_read_b64_tr_b4 v[122:123], v54
	ds_read_b64_tr_b4 v[124:125], v55
	ds_read_b64_tr_b4 v[126:127], v56
	ds_read_b64_tr_b4 v[128:129], v57
	s_waitcnt lgkmcnt(6)
	v_dot8c_i32_i4_e32 v38, v130, v52
	v_dot8c_i32_i4_e32 v39, v130, v50
	v_dot8c_i32_i4_e32 v40, v132, v52
	v_dot8c_i32_i4_e32 v41, v132, v50
	v_dot8c_i32_i4_e32 v42, v134, v52
	v_dot8c_i32_i4_e32 v43, v134, v50
	v_dot8c_i32_i4_e32 v44, v136, v52
	v_dot8c_i32_i4_e32 v45, v136, v50
	v_dot8c_i32_i4_e32 v38, v131, v53
	v_dot8c_i32_i4_e32 v39, v131, v51
	v_dot8c_i32_i4_e32 v40, v133, v53
	v_dot8c_i32_i4_e32 v41, v133, v51
	v_dot8c_i32_i4_e32 v42, v135, v53
	v_dot8c_i32_i4_e32 v43, v135, v51
	v_dot8c_i32_i4_e32 v44, v137, v53
	v_dot8c_i32_i4_e32 v45, v137, v51
	v_and_b32_e32 v78, 0xffff, v19
	v_lshrrev_b32_e32 v79, 16, v19
	v_lshl_add_u32 v78, v78, 7, v152
	v_lshl_add_u32 v79, v79, 7, v153
	s_mov_b32 m0, s79
	s_add_i32 s43, s79, 0x400
	global_load_lds_dwordx4 v78, s[50:51]
	s_mov_b32 m0, s43
	s_nop 0
	global_load_lds_dwordx4 v79, s[50:51]
	s_waitcnt vmcnt(8)
	v_add_u32_e32 v54, s99, v59
	v_add_u32_e32 v55, s99, v60
	v_add_u32_e32 v56, s99, v61
	v_add_u32_e32 v57, s99, v62
	ds_read_b64_tr_b4 v[50:51], v160 offset:640
	ds_read_b64_tr_b4 v[52:53], v160 offset:1664
	ds_read_b64_tr_b4 v[130:131], v54
	ds_read_b64_tr_b4 v[132:133], v55
	ds_read_b64_tr_b4 v[134:135], v56
	ds_read_b64_tr_b4 v[136:137], v57
	s_waitcnt lgkmcnt(6)
	v_dot8c_i32_i4_e32 v38, v122, v48
	v_dot8c_i32_i4_e32 v39, v122, v46
	v_dot8c_i32_i4_e32 v40, v124, v48
	v_dot8c_i32_i4_e32 v41, v124, v46
	v_dot8c_i32_i4_e32 v42, v126, v48
	v_dot8c_i32_i4_e32 v43, v126, v46
	v_dot8c_i32_i4_e32 v44, v128, v48
	v_dot8c_i32_i4_e32 v45, v128, v46
	v_dot8c_i32_i4_e32 v38, v123, v49
	v_dot8c_i32_i4_e32 v39, v123, v47
	v_dot8c_i32_i4_e32 v40, v125, v49
	v_dot8c_i32_i4_e32 v41, v125, v47
	v_dot8c_i32_i4_e32 v42, v127, v49
	v_dot8c_i32_i4_e32 v43, v127, v47
	v_dot8c_i32_i4_e32 v44, v129, v49
	v_dot8c_i32_i4_e32 v45, v129, v47
	s_waitcnt lgkmcnt(15)
	v_add_u32_e32 v143, 8, v139
	v_and_b32_e32 v142, 15, v143
	v_xor_b32_e32 v142, 8, v142
	v_bfe_u32 v144, v143, 4, 4
	v_mul_lo_u32 v142, v142, s92
	v_mul_lo_u32 v144, v144, s92
	v_mov_b32_e32 v143, v142
	v_mov_b32_e32 v145, v144
	ds_write2st64_b64 v159, v[142:143], v[144:145] offset1:2
	v_and_b32_e32 v78, 0xffff, v20
	v_lshrrev_b32_e32 v79, 16, v20
	v_lshl_add_u32 v78, v78, 7, v152
	v_lshl_add_u32 v79, v79, 7, v153
	s_mov_b32 m0, s98
	s_add_i32 s43, s98, 0x400
	global_load_lds_dwordx4 v78, s[50:51]
	s_mov_b32 m0, s43
	s_nop 0
	global_load_lds_dwordx4 v79, s[50:51]
	s_waitcnt vmcnt(8)
	v_add_u32_e32 v54, s76, v59
	v_add_u32_e32 v55, s76, v60
	v_add_u32_e32 v56, s76, v61
	v_add_u32_e32 v57, s76, v62
	ds_read_b64_tr_b4 v[46:47], v160 offset:768
	ds_read_b64_tr_b4 v[48:49], v160 offset:1792
	ds_read_b64_tr_b4 v[122:123], v54
	ds_read_b64_tr_b4 v[124:125], v55
	ds_read_b64_tr_b4 v[126:127], v56
	ds_read_b64_tr_b4 v[128:129], v57
	s_waitcnt lgkmcnt(7)
; #define LAS __attribute__((address_space(3)))
; __device__ __forceinline__ bf16 f2bf(float f) { return (bf16)f2bfu(f); }
; __device__ __forceinline__ void peer_v_tokens(int j, const LAS unsigned short* EL, const LAS unsigned char* AL  , const LAS float* ASC  , const LAS int* SAL  , ...
;     ...
;         const int tl = it * 8 + wave, t = j * 64 + tl;
;         unsigned E[8];
;         { const LAS v4u* ep = (const LAS v4u*)(EL + tl * 128 + 16 * g); const v4u e0 = ep[0], e1 = ep[1];
;           E[0] = e0.x; E[1] = e0.y; E[2] = e0.z; E[3] = e0.w; E[4] = e1.x; E[5] = e1.y; E[6] = e1.z; E[7] = e1.w; }
;     ...
; #pragma unroll
;         for (int st = 0; st < 16; ++st) {
;             const int p = st >> 2, q = st & 3;
;             if (st < 14) VDMA(st + 2, (st + 2) % 3);
;             if (st < 14) asm volatile("s_waitcnt vmcnt(8)" ::: "memory");
;             else if (st == 14) asm volatile("s_waitcnt vmcnt(4)" ::: "memory");
;             else asm volatile("s_waitcnt vmcnt(0)" ::: "memory");
;             if (q == 0) {
; #pragma unroll
;                 for (int r = 0; r < 4; ++r) { accH[r] = 0; accL[r] = 0; } }
; #pragma unroll
;             for (int tp = 0; tp < 2; ++tp) {
;                 const v2i ao = TR4(ATL + (2 * q + tp) * 128 + 8 * s16), ah = TR4(ATL + 1024 + (2 * q + tp) * 128 + 8 * s16);
; #pragma unroll
;                 for (int r = 0; r < 4; ++r) {
;                     const v2i d = TR4(ldsb + BUF[st % 3] + 2048 * tp + roff[r]);
;                     accH[r] = __builtin_amdgcn_sdot8(d.x, ah.x, accH[r], false); accH[r] = __builtin_amdgcn_sdot8(d.y, ah.y, accH[r], false);
;                     accL[r] = __builtin_amdgcn_sdot8(d.x, ao.x, accL[r], false); accL[r] = __builtin_amdgcn_sdot8(d.y, ao.y, accL[r], false);
;                 }
;             }
;             asm volatile("s_waitcnt lgkmcnt(0)" ::: "memory");
;             if (q == 3) {
; #pragma unroll
;                 for (int r = 0; r < 4; ++r) STASH[256 * p + 16 * (grp + 4 * r) + pc] = f2bf(asc * (float)(2 * ((accH[r] << 4) + accL[r]) + sa));
;             }
;         }
;     ...
;             for (int jq = 0; jq < 4; ++jq) { typedef float f4v __attribute__((ext_vector_type(4))); f4v o4; o4.x = v[jq].x * r3 * gv[jq].x; o4.y = v[jq].y * r3 * gv[jq].y; o4.z = v[jq].z * r3 * gv[jq].z; o4.w = v[jq].w * r3 * gv[jq].w;
;                 __builtin_nontemporal_store(o4, (f4v*)op + 64 * jq); }
	v_dot8c_i32_i4_e32 v38, v130, v52
	v_dot8c_i32_i4_e32 v39, v130, v50
	v_dot8c_i32_i4_e32 v40, v132, v52
	v_dot8c_i32_i4_e32 v41, v132, v50
	v_dot8c_i32_i4_e32 v42, v134, v52
	v_dot8c_i32_i4_e32 v43, v134, v50
	v_dot8c_i32_i4_e32 v44, v136, v52
	v_dot8c_i32_i4_e32 v45, v136, v50
	v_dot8c_i32_i4_e32 v38, v131, v53
	v_dot8c_i32_i4_e32 v39, v131, v51
	v_dot8c_i32_i4_e32 v40, v133, v53
	v_dot8c_i32_i4_e32 v41, v133, v51
	v_dot8c_i32_i4_e32 v42, v135, v53
	v_dot8c_i32_i4_e32 v43, v135, v51
	v_dot8c_i32_i4_e32 v44, v137, v53
	v_dot8c_i32_i4_e32 v45, v137, v51
	v_and_b32_e32 v78, 0xffff, v21
	v_lshrrev_b32_e32 v79, 16, v21
	v_lshl_add_u32 v78, v78, 7, v152
	v_lshl_add_u32 v79, v79, 7, v153
	s_mov_b32 m0, s99
	s_add_i32 s43, s99, 0x400
	global_load_lds_dwordx4 v78, s[50:51]
	s_mov_b32 m0, s43
	s_nop 0
	global_load_lds_dwordx4 v79, s[50:51]
	s_waitcnt vmcnt(8)
	v_add_u32_e32 v54, s77, v59
	v_add_u32_e32 v55, s77, v60
	v_add_u32_e32 v56, s77, v61
	v_add_u32_e32 v57, s77, v62
	ds_read_b64_tr_b4 v[50:51], v160 offset:896
	ds_read_b64_tr_b4 v[52:53], v160 offset:1920
	ds_read_b64_tr_b4 v[130:131], v54
	ds_read_b64_tr_b4 v[132:133], v55
	ds_read_b64_tr_b4 v[134:135], v56
	ds_read_b64_tr_b4 v[136:137], v57
	s_waitcnt lgkmcnt(6)
	v_dot8c_i32_i4_e32 v38, v122, v48
	v_dot8c_i32_i4_e32 v39, v122, v46
	v_dot8c_i32_i4_e32 v40, v124, v48
	v_dot8c_i32_i4_e32 v41, v124, v46
	v_dot8c_i32_i4_e32 v42, v126, v48
	v_dot8c_i32_i4_e32 v43, v126, v46
	v_dot8c_i32_i4_e32 v44, v128, v48
	v_dot8c_i32_i4_e32 v45, v128, v46
	v_dot8c_i32_i4_e32 v38, v123, v49
	v_dot8c_i32_i4_e32 v39, v123, v47
	v_dot8c_i32_i4_e32 v40, v125, v49
	v_dot8c_i32_i4_e32 v41, v125, v47
	v_dot8c_i32_i4_e32 v42, v127, v49
	v_dot8c_i32_i4_e32 v43, v127, v47
	v_dot8c_i32_i4_e32 v44, v129, v49
	v_dot8c_i32_i4_e32 v45, v129, v47
	v_and_b32_e32 v78, 0xffff, v22
	v_lshrrev_b32_e32 v79, 16, v22
	v_lshl_add_u32 v78, v78, 7, v152
	v_lshl_add_u32 v79, v79, 7, v153
	s_mov_b32 m0, s76
	s_add_i32 s43, s76, 0x400
	global_load_lds_dwordx4 v78, s[50:51]
	s_mov_b32 m0, s43
	s_nop 0
	global_load_lds_dwordx4 v79, s[50:51]
	s_waitcnt vmcnt(8)
	v_add_u32_e32 v54, s78, v59
	v_add_u32_e32 v55, s78, v60
	v_add_u32_e32 v56, s78, v61
	v_add_u32_e32 v57, s78, v62
	ds_read_b64_tr_b4 v[46:47], v160
	ds_read_b64_tr_b4 v[48:49], v160 offset:1024
	ds_read_b64_tr_b4 v[122:123], v54
	ds_read_b64_tr_b4 v[124:125], v55
	ds_read_b64_tr_b4 v[126:127], v56
	ds_read_b64_tr_b4 v[128:129], v57
	s_waitcnt lgkmcnt(6)
	v_dot8c_i32_i4_e32 v38, v130, v52
	v_dot8c_i32_i4_e32 v39, v130, v50
	v_dot8c_i32_i4_e32 v40, v132, v52
	v_dot8c_i32_i4_e32 v41, v132, v50
	v_dot8c_i32_i4_e32 v42, v134, v52
	v_dot8c_i32_i4_e32 v43, v134, v50
	v_dot8c_i32_i4_e32 v44, v136, v52
	v_dot8c_i32_i4_e32 v45, v136, v50
	v_dot8c_i32_i4_e32 v38, v131, v53
	v_dot8c_i32_i4_e32 v39, v131, v51
	v_dot8c_i32_i4_e32 v40, v133, v53
	v_dot8c_i32_i4_e32 v41, v133, v51
	v_dot8c_i32_i4_e32 v42, v135, v53
	v_dot8c_i32_i4_e32 v43, v135, v51
	v_dot8c_i32_i4_e32 v44, v137, v53
	v_dot8c_i32_i4_e32 v45, v137, v51
	s_nop 3
	s_waitcnt lgkmcnt(15)
	v_lshlrev_b32_e32 v38, 5, v38
	v_lshlrev_b32_e32 v39, 1, v39
	v_add3_u32 v38, v39, v229, v38
	v_cvt_f32_i32_e32 v38, v38
	v_mul_f32_e32 v38, v228, v38
	v_lshlrev_b32_e32 v40, 5, v40
	v_lshlrev_b32_e32 v41, 1, v41
	v_add3_u32 v40, v41, v229, v40
	v_cvt_f32_i32_e32 v40, v40
	v_mul_f32_e32 v40, v228, v40
	v_lshlrev_b32_e32 v42, 5, v42
	v_lshlrev_b32_e32 v43, 1, v43
	v_add3_u32 v42, v43, v229, v42
	v_cvt_f32_i32_e32 v42, v42
	v_mul_f32_e32 v42, v228, v42
	v_lshlrev_b32_e32 v44, 5, v44
	v_lshlrev_b32_e32 v45, 1, v45
	v_add3_u32 v44, v45, v229, v44
	v_cvt_f32_i32_e32 v44, v44
	v_mul_f32_e32 v44, v228, v44
	v_cvt_pk_bf16_f32 v174, v38, v40
	v_cvt_pk_bf16_f32 v175, v42, v44
	ds_read_b128 v[252:255], v155 offset:1024
	s_add_i32 s44, s40, 24
	s_ashr_i32 s45, s44, 31
	s_lshl_b64 s[44:45], s[44:45], 12
	v_lshl_add_u64 v[80:81], v[36:37], 0, s[44:45]
	s_waitcnt lgkmcnt(0)
	v_mul_f32_e32 v240, v240, v252
	v_mul_f32_e32 v241, v241, v253
	v_mul_f32_e32 v242, v242, v254
	v_mul_f32_e32 v243, v243, v255
	global_store_dwordx4 v[80:81], v[240:243], off offset:1024 nt
	v_add_u32_e32 v147, 8, v140
	v_and_b32_e32 v146, 15, v147
	v_xor_b32_e32 v146, 8, v146
	v_bfe_u32 v148, v147, 4, 4
	v_mul_lo_u32 v146, v146, s92
	v_mul_lo_u32 v148, v148, s92
	v_mov_b32_e32 v147, v146
	v_mov_b32_e32 v149, v148
	ds_write2st64_b64 v77, v[146:147], v[148:149] offset1:2
	v_add_u32_e32 v138, 0x1400, v74
	ds_read_u8 v139, v138
	v_add_u32_e32 v141, 0x1400, v73
	ds_read_u8 v140, v141
	s_add_i32 s43, s67, 128
	v_mov_b32_e32 v138, s43
	ds_read2st64_b32 v[228:229], v138 offset1:1
	ds_read_b128 v[26:29], v227 offset:10240
	ds_read_b128 v[30:33], v227 offset:10256
	v_mov_b32_e32 v38, 0
	v_mov_b32_e32 v39, 0
	v_mov_b32_e32 v40, 0
	v_mov_b32_e32 v41, 0
	v_mov_b32_e32 v42, 0
	v_mov_b32_e32 v43, 0
	v_mov_b32_e32 v44, 0
	v_mov_b32_e32 v45, 0
	v_and_b32_e32 v78, 0xffff, v23
	v_lshrrev_b32_e32 v79, 16, v23
	v_lshl_add_u32 v78, v78, 7, v152
	v_lshl_add_u32 v79, v79, 7, v153
	s_mov_b32 m0, s77
	s_add_i32 s43, s77, 0x400
	global_load_lds_dwordx4 v78, s[50:51]
	s_mov_b32 m0, s43
	s_nop 0
	global_load_lds_dwordx4 v79, s[50:51]
	s_waitcnt vmcnt(9)
	v_add_u32_e32 v54, s79, v59
	v_add_u32_e32 v55, s79, v60
	v_add_u32_e32 v56, s79, v61
	v_add_u32_e32 v57, s79, v62
	ds_read_b64_tr_b4 v[50:51], v160 offset:128
	ds_read_b64_tr_b4 v[52:53], v160 offset:1152
	ds_read_b64_tr_b4 v[130:131], v54
	ds_read_b64_tr_b4 v[132:133], v55
	ds_read_b64_tr_b4 v[134:135], v56
	ds_read_b64_tr_b4 v[136:137], v57
	s_waitcnt lgkmcnt(13)
; #define TR4(p_) __builtin_amdgcn_ds_read_tr4_b64_v2i32((LAS v2i*)(p_))
; #define VDMA(st_, k_) do { _Pragma("unroll") for (int i_ = 0; i_ < 4; ++i_) { \
;         const unsigned off_ = (unsigned)((st_) >> 2) * (16384u * 128u) + (PE_ID(E, 4 * ((st_) & 3) + i_) << 7) + ((i_ & 1) ? cx1 : cx0); \
;         __builtin_amdgcn_global_load_lds((const unsigned*)(V4 + off_), (LAS unsigned*)(ldsb + BUF[k_] + 1024 * i_), 16, 0, 0); } } while (0)
; __device__ __forceinline__ void peer_v_tokens(int j, const LAS unsigned short* EL, const LAS unsigned char* AL  , const LAS float* ASC  , const LAS int* SAL  , ...
;     ...
; #pragma unroll
;         for (int st = 0; st < 16; ++st) {
;             const int p = st >> 2, q = st & 3;
;             if (st < 14) VDMA(st + 2, (st + 2) % 3);
;             if (st < 14) asm volatile("s_waitcnt vmcnt(8)" ::: "memory");
;             else if (st == 14) asm volatile("s_waitcnt vmcnt(4)" ::: "memory");
;             else asm volatile("s_waitcnt vmcnt(0)" ::: "memory");
;             if (q == 0) {
; #pragma unroll
;                 for (int r = 0; r < 4; ++r) { accH[r] = 0; accL[r] = 0; } }
; #pragma unroll
;             for (int tp = 0; tp < 2; ++tp) {
;                 const v2i ao = TR4(ATL + (2 * q + tp) * 128 + 8 * s16), ah = TR4(ATL + 1024 + (2 * q + tp) * 128 + 8 * s16);
; #pragma unroll
;                 for (int r = 0; r < 4; ++r) {
;                     const v2i d = TR4(ldsb + BUF[st % 3] + 2048 * tp + roff[r]);
;                     accH[r] = __builtin_amdgcn_sdot8(d.x, ah.x, accH[r], false); accH[r] = __builtin_amdgcn_sdot8(d.y, ah.y, accH[r], false);
;                     accL[r] = __builtin_amdgcn_sdot8(d.x, ao.x, accL[r], false); accL[r] = __builtin_amdgcn_sdot8(d.y, ao.y, accL[r], false);
;                 }
;             }
;             asm volatile("s_waitcnt lgkmcnt(0)" ::: "memory");
	v_dot8c_i32_i4_e32 v38, v122, v48
	v_dot8c_i32_i4_e32 v39, v122, v46
	v_dot8c_i32_i4_e32 v40, v124, v48
	v_dot8c_i32_i4_e32 v41, v124, v46
	v_dot8c_i32_i4_e32 v42, v126, v48
	v_dot8c_i32_i4_e32 v43, v126, v46
	v_dot8c_i32_i4_e32 v44, v128, v48
	v_dot8c_i32_i4_e32 v45, v128, v46
	v_dot8c_i32_i4_e32 v38, v123, v49
	v_dot8c_i32_i4_e32 v39, v123, v47
	v_dot8c_i32_i4_e32 v40, v125, v49
	v_dot8c_i32_i4_e32 v41, v125, v47
	v_dot8c_i32_i4_e32 v42, v127, v49
	v_dot8c_i32_i4_e32 v43, v127, v47
	v_dot8c_i32_i4_e32 v44, v129, v49
	v_dot8c_i32_i4_e32 v45, v129, v47
	v_and_b32_e32 v78, 0xffff, v24
	v_lshrrev_b32_e32 v79, 16, v24
	v_lshl_add_u32 v78, v78, 7, v152
	v_lshl_add_u32 v79, v79, 7, v153
	s_mov_b32 m0, s78
	s_add_i32 s43, s78, 0x400
	global_load_lds_dwordx4 v78, s[50:51]
	s_mov_b32 m0, s43
	s_nop 0
	global_load_lds_dwordx4 v79, s[50:51]
	s_waitcnt vmcnt(9)
	v_add_u32_e32 v54, s98, v59
	v_add_u32_e32 v55, s98, v60
	v_add_u32_e32 v56, s98, v61
	v_add_u32_e32 v57, s98, v62
	ds_read_b64_tr_b4 v[46:47], v160 offset:256
	ds_read_b64_tr_b4 v[48:49], v160 offset:1280
	ds_read_b64_tr_b4 v[122:123], v54
	ds_read_b64_tr_b4 v[124:125], v55
	ds_read_b64_tr_b4 v[126:127], v56
	ds_read_b64_tr_b4 v[128:129], v57
	s_waitcnt lgkmcnt(6)
	v_dot8c_i32_i4_e32 v38, v130, v52
	v_dot8c_i32_i4_e32 v39, v130, v50
	v_dot8c_i32_i4_e32 v40, v132, v52
	v_dot8c_i32_i4_e32 v41, v132, v50
	v_dot8c_i32_i4_e32 v42, v134, v52
	v_dot8c_i32_i4_e32 v43, v134, v50
	v_dot8c_i32_i4_e32 v44, v136, v52
	v_dot8c_i32_i4_e32 v45, v136, v50
	v_dot8c_i32_i4_e32 v38, v131, v53
	v_dot8c_i32_i4_e32 v39, v131, v51
	v_dot8c_i32_i4_e32 v40, v133, v53
	v_dot8c_i32_i4_e32 v41, v133, v51
	v_dot8c_i32_i4_e32 v42, v135, v53
	v_dot8c_i32_i4_e32 v43, v135, v51
	v_dot8c_i32_i4_e32 v44, v137, v53
	v_dot8c_i32_i4_e32 v45, v137, v51
	v_and_b32_e32 v78, 0xffff, v25
	v_lshrrev_b32_e32 v79, 16, v25
	v_lshl_add_u32 v78, v78, 7, v152
	v_lshl_add_u32 v79, v79, 7, v153
	s_mov_b32 m0, s79
	s_add_i32 s43, s79, 0x400
	global_load_lds_dwordx4 v78, s[50:51]
	s_mov_b32 m0, s43
	s_nop 0
	global_load_lds_dwordx4 v79, s[50:51]
	s_waitcnt vmcnt(9)
	v_add_u32_e32 v54, s99, v59
	v_add_u32_e32 v55, s99, v60
	v_add_u32_e32 v56, s99, v61
	v_add_u32_e32 v57, s99, v62
	ds_read_b64_tr_b4 v[50:51], v160 offset:384
	ds_read_b64_tr_b4 v[52:53], v160 offset:1408
	ds_read_b64_tr_b4 v[130:131], v54
	ds_read_b64_tr_b4 v[132:133], v55
	ds_read_b64_tr_b4 v[134:135], v56
	ds_read_b64_tr_b4 v[136:137], v57
	s_waitcnt lgkmcnt(6)
	v_dot8c_i32_i4_e32 v38, v122, v48
	v_dot8c_i32_i4_e32 v39, v122, v46
	v_dot8c_i32_i4_e32 v40, v124, v48
	v_dot8c_i32_i4_e32 v41, v124, v46
	v_dot8c_i32_i4_e32 v42, v126, v48
	v_dot8c_i32_i4_e32 v43, v126, v46
	v_dot8c_i32_i4_e32 v44, v128, v48
	v_dot8c_i32_i4_e32 v45, v128, v46
	v_dot8c_i32_i4_e32 v38, v123, v49
	v_dot8c_i32_i4_e32 v39, v123, v47
	v_dot8c_i32_i4_e32 v40, v125, v49
	v_dot8c_i32_i4_e32 v41, v125, v47
	v_dot8c_i32_i4_e32 v42, v127, v49
	v_dot8c_i32_i4_e32 v43, v127, v47
	v_dot8c_i32_i4_e32 v44, v129, v49
	v_dot8c_i32_i4_e32 v45, v129, v47
	s_waitcnt lgkmcnt(15)
	v_and_b32_e32 v78, 0xffff, v26
	v_lshrrev_b32_e32 v79, 16, v26
	v_lshl_add_u32 v78, v78, 7, v152
	v_lshl_add_u32 v79, v79, 7, v153
	s_mov_b32 m0, s98
	s_add_i32 s43, s98, 0x400
	global_load_lds_dwordx4 v78, s[50:51]
	s_mov_b32 m0, s43
	s_nop 0
	global_load_lds_dwordx4 v79, s[50:51]
	s_waitcnt vmcnt(9)
	v_add_u32_e32 v54, s76, v59
	v_add_u32_e32 v55, s76, v60
	v_add_u32_e32 v56, s76, v61
	v_add_u32_e32 v57, s76, v62
	ds_read_b64_tr_b4 v[46:47], v160 offset:512
	ds_read_b64_tr_b4 v[48:49], v160 offset:1536
	ds_read_b64_tr_b4 v[122:123], v54
	ds_read_b64_tr_b4 v[124:125], v55
	ds_read_b64_tr_b4 v[126:127], v56
	ds_read_b64_tr_b4 v[128:129], v57
	s_waitcnt lgkmcnt(6)
	v_dot8c_i32_i4_e32 v38, v130, v52
	v_dot8c_i32_i4_e32 v39, v130, v50
	v_dot8c_i32_i4_e32 v40, v132, v52
	v_dot8c_i32_i4_e32 v41, v132, v50
	v_dot8c_i32_i4_e32 v42, v134, v52
	v_dot8c_i32_i4_e32 v43, v134, v50
	v_dot8c_i32_i4_e32 v44, v136, v52
	v_dot8c_i32_i4_e32 v45, v136, v50
	v_dot8c_i32_i4_e32 v38, v131, v53
	v_dot8c_i32_i4_e32 v39, v131, v51
	v_dot8c_i32_i4_e32 v40, v133, v53
	v_dot8c_i32_i4_e32 v41, v133, v51
	v_dot8c_i32_i4_e32 v42, v135, v53
	v_dot8c_i32_i4_e32 v43, v135, v51
	v_dot8c_i32_i4_e32 v44, v137, v53
	v_dot8c_i32_i4_e32 v45, v137, v51
	v_and_b32_e32 v78, 0xffff, v27
	v_lshrrev_b32_e32 v79, 16, v27
	v_lshl_add_u32 v78, v78, 7, v152
	v_lshl_add_u32 v79, v79, 7, v153
	s_mov_b32 m0, s99
	s_add_i32 s43, s99, 0x400
	global_load_lds_dwordx4 v78, s[50:51]
	s_mov_b32 m0, s43
	s_nop 0
	global_load_lds_dwordx4 v79, s[50:51]
	s_waitcnt vmcnt(8)
	v_add_u32_e32 v54, s77, v59
	v_add_u32_e32 v55, s77, v60
	v_add_u32_e32 v56, s77, v61
	v_add_u32_e32 v57, s77, v62
	ds_read_b64_tr_b4 v[50:51], v160 offset:640
	ds_read_b64_tr_b4 v[52:53], v160 offset:1664
	ds_read_b64_tr_b4 v[130:131], v54
	ds_read_b64_tr_b4 v[132:133], v55
	ds_read_b64_tr_b4 v[134:135], v56
	ds_read_b64_tr_b4 v[136:137], v57
	s_waitcnt lgkmcnt(6)
	v_dot8c_i32_i4_e32 v38, v122, v48
	v_dot8c_i32_i4_e32 v39, v122, v46
	v_dot8c_i32_i4_e32 v40, v124, v48
	v_dot8c_i32_i4_e32 v41, v124, v46
	v_dot8c_i32_i4_e32 v42, v126, v48
	v_dot8c_i32_i4_e32 v43, v126, v46
	v_dot8c_i32_i4_e32 v44, v128, v48
	v_dot8c_i32_i4_e32 v45, v128, v46
	v_dot8c_i32_i4_e32 v38, v123, v49
	v_dot8c_i32_i4_e32 v39, v123, v47
	v_dot8c_i32_i4_e32 v40, v125, v49
	v_dot8c_i32_i4_e32 v41, v125, v47
	v_dot8c_i32_i4_e32 v42, v127, v49
	v_dot8c_i32_i4_e32 v43, v127, v47
	v_dot8c_i32_i4_e32 v44, v129, v49
	v_dot8c_i32_i4_e32 v45, v129, v47
	s_waitcnt lgkmcnt(15)
; #define LAS __attribute__((address_space(3)))
; __device__ __forceinline__ bf16 f2bf(float f) { return (bf16)f2bfu(f); }
; __device__ __forceinline__ void peer_v_tokens(int j, const LAS unsigned short* EL, const LAS unsigned char* AL  , const LAS float* ASC  , const LAS int* SAL  , ...
;     ...
;         for (int m = 0; m < 2; ++m) {
;             const int idx = lane + 64 * m, tau = idx >> 4, sr = idx & 15, k = 16 * (sr & 7) + 2 * tau + (sr >> 3);
;             const int aq = (int)*(const LAS signed char*)(AL + tl * 128 + k); const int tq = aq + 8;
;             const unsigned lo = (((unsigned)tq & 15u) ^ 8u) * 0x11111111u, hi = ((unsigned)(tq >> 4) & 15u) * 0x11111111u;
;             typedef unsigned u2v __attribute__((ext_vector_type(2)));
;             u2v l2; l2.x = lo; l2.y = lo; u2v h2; h2.x = hi; h2.y = hi;
;             *(LAS u2v*)(ATL + 8 * idx) = l2; *(LAS u2v*)(ATL + 1024 + 8 * idx) = h2;
;         }
;     ...
; #pragma unroll
;         for (int st = 0; st < 16; ++st) {
;             const int p = st >> 2, q = st & 3;
;             if (st < 14) VDMA(st + 2, (st + 2) % 3);
;             if (st < 14) asm volatile("s_waitcnt vmcnt(8)" ::: "memory");
;             else if (st == 14) asm volatile("s_waitcnt vmcnt(4)" ::: "memory");
;             else asm volatile("s_waitcnt vmcnt(0)" ::: "memory");
;             if (q == 0) {
; #pragma unroll
;                 for (int r = 0; r < 4; ++r) { accH[r] = 0; accL[r] = 0; } }
; #pragma unroll
;             for (int tp = 0; tp < 2; ++tp) {
;                 const v2i ao = TR4(ATL + (2 * q + tp) * 128 + 8 * s16), ah = TR4(ATL + 1024 + (2 * q + tp) * 128 + 8 * s16);
; #pragma unroll
;                 for (int r = 0; r < 4; ++r) {
;                     const v2i d = TR4(ldsb + BUF[st % 3] + 2048 * tp + roff[r]);
;                     accH[r] = __builtin_amdgcn_sdot8(d.x, ah.x, accH[r], false); accH[r] = __builtin_amdgcn_sdot8(d.y, ah.y, accH[r], false);
;                     accL[r] = __builtin_amdgcn_sdot8(d.x, ao.x, accL[r], false); accL[r] = __builtin_amdgcn_sdot8(d.y, ao.y, accL[r], false);
;                 }
;             }
;             asm volatile("s_waitcnt lgkmcnt(0)" ::: "memory");
;             if (q == 3) {
; #pragma unroll
;                 for (int r = 0; r < 4; ++r) STASH[256 * p + 16 * (grp + 4 * r) + pc] = f2bf(asc * (float)(2 * ((accH[r] << 4) + accL[r]) + sa));
;             }
;         }
	v_add_u32_e32 v143, 8, v139
	v_and_b32_e32 v142, 15, v143
	v_xor_b32_e32 v142, 8, v142
	v_bfe_u32 v144, v143, 4, 4
	v_mul_lo_u32 v142, v142, s92
	v_mul_lo_u32 v144, v144, s92
	v_mov_b32_e32 v143, v142
	v_mov_b32_e32 v145, v144
	ds_write2st64_b64 v159, v[142:143], v[144:145] offset1:2
	v_and_b32_e32 v78, 0xffff, v28
	v_lshrrev_b32_e32 v79, 16, v28
	v_lshl_add_u32 v78, v78, 7, v152
	v_lshl_add_u32 v79, v79, 7, v153
	s_mov_b32 m0, s76
	s_add_i32 s43, s76, 0x400
	global_load_lds_dwordx4 v78, s[50:51]
	s_mov_b32 m0, s43
	s_nop 0
	global_load_lds_dwordx4 v79, s[50:51]
	s_waitcnt vmcnt(8)
	v_add_u32_e32 v54, s78, v59
	v_add_u32_e32 v55, s78, v60
	v_add_u32_e32 v56, s78, v61
	v_add_u32_e32 v57, s78, v62
	ds_read_b64_tr_b4 v[46:47], v160 offset:768
	ds_read_b64_tr_b4 v[48:49], v160 offset:1792
	ds_read_b64_tr_b4 v[122:123], v54
	ds_read_b64_tr_b4 v[124:125], v55
	ds_read_b64_tr_b4 v[126:127], v56
	ds_read_b64_tr_b4 v[128:129], v57
	s_waitcnt lgkmcnt(7)
	v_dot8c_i32_i4_e32 v38, v130, v52
	v_dot8c_i32_i4_e32 v39, v130, v50
	v_dot8c_i32_i4_e32 v40, v132, v52
	v_dot8c_i32_i4_e32 v41, v132, v50
	v_dot8c_i32_i4_e32 v42, v134, v52
	v_dot8c_i32_i4_e32 v43, v134, v50
	v_dot8c_i32_i4_e32 v44, v136, v52
	v_dot8c_i32_i4_e32 v45, v136, v50
	v_dot8c_i32_i4_e32 v38, v131, v53
	v_dot8c_i32_i4_e32 v39, v131, v51
	v_dot8c_i32_i4_e32 v40, v133, v53
	v_dot8c_i32_i4_e32 v41, v133, v51
	v_dot8c_i32_i4_e32 v42, v135, v53
	v_dot8c_i32_i4_e32 v43, v135, v51
	v_dot8c_i32_i4_e32 v44, v137, v53
	v_dot8c_i32_i4_e32 v45, v137, v51
	v_and_b32_e32 v78, 0xffff, v29
	v_lshrrev_b32_e32 v79, 16, v29
	v_lshl_add_u32 v78, v78, 7, v152
	v_lshl_add_u32 v79, v79, 7, v153
	s_mov_b32 m0, s77
	s_add_i32 s43, s77, 0x400
	global_load_lds_dwordx4 v78, s[50:51]
	s_mov_b32 m0, s43
	s_nop 0
	global_load_lds_dwordx4 v79, s[50:51]
	s_waitcnt vmcnt(8)
	v_add_u32_e32 v54, s79, v59
	v_add_u32_e32 v55, s79, v60
	v_add_u32_e32 v56, s79, v61
	v_add_u32_e32 v57, s79, v62
	ds_read_b64_tr_b4 v[50:51], v160 offset:896
	ds_read_b64_tr_b4 v[52:53], v160 offset:1920
	ds_read_b64_tr_b4 v[130:131], v54
	ds_read_b64_tr_b4 v[132:133], v55
	ds_read_b64_tr_b4 v[134:135], v56
	ds_read_b64_tr_b4 v[136:137], v57
	s_waitcnt lgkmcnt(6)
	v_dot8c_i32_i4_e32 v38, v122, v48
	v_dot8c_i32_i4_e32 v39, v122, v46
	v_dot8c_i32_i4_e32 v40, v124, v48
	v_dot8c_i32_i4_e32 v41, v124, v46
	v_dot8c_i32_i4_e32 v42, v126, v48
	v_dot8c_i32_i4_e32 v43, v126, v46
	v_dot8c_i32_i4_e32 v44, v128, v48
	v_dot8c_i32_i4_e32 v45, v128, v46
	v_dot8c_i32_i4_e32 v38, v123, v49
	v_dot8c_i32_i4_e32 v39, v123, v47
	v_dot8c_i32_i4_e32 v40, v125, v49
	v_dot8c_i32_i4_e32 v41, v125, v47
	v_dot8c_i32_i4_e32 v42, v127, v49
	v_dot8c_i32_i4_e32 v43, v127, v47
	v_dot8c_i32_i4_e32 v44, v129, v49
	v_dot8c_i32_i4_e32 v45, v129, v47
	v_and_b32_e32 v78, 0xffff, v30
	v_lshrrev_b32_e32 v79, 16, v30
	v_lshl_add_u32 v78, v78, 7, v152
	v_lshl_add_u32 v79, v79, 7, v153
	s_mov_b32 m0, s78
	s_add_i32 s43, s78, 0x400
	global_load_lds_dwordx4 v78, s[50:51]
	s_mov_b32 m0, s43
	s_nop 0
	global_load_lds_dwordx4 v79, s[50:51]
	s_waitcnt vmcnt(8)
	v_add_u32_e32 v54, s98, v59
	v_add_u32_e32 v55, s98, v60
	v_add_u32_e32 v56, s98, v61
	v_add_u32_e32 v57, s98, v62
	ds_read_b64_tr_b4 v[46:47], v160
	ds_read_b64_tr_b4 v[48:49], v160 offset:1024
	ds_read_b64_tr_b4 v[122:123], v54
	ds_read_b64_tr_b4 v[124:125], v55
	ds_read_b64_tr_b4 v[126:127], v56
	ds_read_b64_tr_b4 v[128:129], v57
	s_waitcnt lgkmcnt(6)
	v_dot8c_i32_i4_e32 v38, v130, v52
	v_dot8c_i32_i4_e32 v39, v130, v50
	v_dot8c_i32_i4_e32 v40, v132, v52
	v_dot8c_i32_i4_e32 v41, v132, v50
	v_dot8c_i32_i4_e32 v42, v134, v52
	v_dot8c_i32_i4_e32 v43, v134, v50
	v_dot8c_i32_i4_e32 v44, v136, v52
	v_dot8c_i32_i4_e32 v45, v136, v50
	v_dot8c_i32_i4_e32 v38, v131, v53
	v_dot8c_i32_i4_e32 v39, v131, v51
	v_dot8c_i32_i4_e32 v40, v133, v53
	v_dot8c_i32_i4_e32 v41, v133, v51
	v_dot8c_i32_i4_e32 v42, v135, v53
	v_dot8c_i32_i4_e32 v43, v135, v51
	v_dot8c_i32_i4_e32 v44, v137, v53
	v_dot8c_i32_i4_e32 v45, v137, v51
	s_nop 3
	s_waitcnt lgkmcnt(15)
	v_lshlrev_b32_e32 v38, 5, v38
	v_lshlrev_b32_e32 v39, 1, v39
	v_add3_u32 v38, v39, v229, v38
	v_cvt_f32_i32_e32 v38, v38
	v_mul_f32_e32 v38, v228, v38
	v_lshlrev_b32_e32 v40, 5, v40
	v_lshlrev_b32_e32 v41, 1, v41
	v_add3_u32 v40, v41, v229, v40
	v_cvt_f32_i32_e32 v40, v40
	v_mul_f32_e32 v40, v228, v40
	v_lshlrev_b32_e32 v42, 5, v42
	v_lshlrev_b32_e32 v43, 1, v43
	v_add3_u32 v42, v43, v229, v42
	v_cvt_f32_i32_e32 v42, v42
	v_mul_f32_e32 v42, v228, v42
	v_lshlrev_b32_e32 v44, 5, v44
	v_lshlrev_b32_e32 v45, 1, v45
	v_add3_u32 v44, v45, v229, v44
	v_cvt_f32_i32_e32 v44, v44
	v_mul_f32_e32 v44, v228, v44
	v_cvt_pk_bf16_f32 v168, v38, v40
	v_cvt_pk_bf16_f32 v169, v42, v44
	ds_read_b128 v[252:255], v156
	s_add_i32 s44, s40, 24
	s_ashr_i32 s45, s44, 31
	s_lshl_b64 s[44:45], s[44:45], 12
	v_lshl_add_u64 v[80:81], v[36:37], 0, s[44:45]
	s_waitcnt lgkmcnt(0)
; #define LAS __attribute__((address_space(3)))
; __device__ __forceinline__ void peer_v_tokens(int j, const LAS unsigned short* EL, const LAS unsigned char* AL  , const LAS float* ASC  , const LAS int* SAL  , ...
;     ...
;         const int tl = it * 8 + wave, t = j * 64 + tl;
;         unsigned E[8];
;         { const LAS v4u* ep = (const LAS v4u*)(EL + tl * 128 + 16 * g); const v4u e0 = ep[0], e1 = ep[1];
;           E[0] = e0.x; E[1] = e0.y; E[2] = e0.z; E[3] = e0.w; E[4] = e1.x; E[5] = e1.y; E[6] = e1.z; E[7] = e1.w; }
;     ...
;         { unsigned ho = (unsigned)t * (D / 4) + (unsigned)lane; asm volatile("" : "+v"(ho)); const uint2* hp = (const uint2*)HB + ho; const float4* gp = (const float4*)fng + lane;
; #pragma unroll
;           for (int jq = 0; jq < 4; ++jq) { hv[jq] = hp[64 * jq]; gv[jq] = gp[64 * jq]; } }
;     ...
;         for (int m = 0; m < 2; ++m) {
;             const int idx = lane + 64 * m, tau = idx >> 4, sr = idx & 15, k = 16 * (sr & 7) + 2 * tau + (sr >> 3);
;             const int aq = (int)*(const LAS signed char*)(AL + tl * 128 + k); const int tq = aq + 8;
;             const unsigned lo = (((unsigned)tq & 15u) ^ 8u) * 0x11111111u, hi = ((unsigned)(tq >> 4) & 15u) * 0x11111111u;
;             typedef unsigned u2v __attribute__((ext_vector_type(2)));
;             u2v l2; l2.x = lo; l2.y = lo; u2v h2; h2.x = hi; h2.y = hi;
;             *(LAS u2v*)(ATL + 8 * idx) = l2; *(LAS u2v*)(ATL + 1024 + 8 * idx) = h2;
;         }
;     ...
; #pragma unroll
;         for (int st = 0; st < 16; ++st) {
;             const int p = st >> 2, q = st & 3;
;             if (st < 14) VDMA(st + 2, (st + 2) % 3);
;             if (st < 14) asm volatile("s_waitcnt vmcnt(8)" ::: "memory");
;             else if (st == 14) asm volatile("s_waitcnt vmcnt(4)" ::: "memory");
;             else asm volatile("s_waitcnt vmcnt(0)" ::: "memory");
;             if (q == 0) {
; #pragma unroll
;                 for (int r = 0; r < 4; ++r) { accH[r] = 0; accL[r] = 0; } }
; #pragma unroll
;             for (int tp = 0; tp < 2; ++tp) {
;     ...
;             for (int jq = 0; jq < 4; ++jq) { typedef float f4v __attribute__((ext_vector_type(4))); f4v o4; o4.x = v[jq].x * r3 * gv[jq].x; o4.y = v[jq].y * r3 * gv[jq].y; o4.z = v[jq].z * r3 * gv[jq].z; o4.w = v[jq].w * r3 * gv[jq].w;
;                 __builtin_nontemporal_store(o4, (f4v*)op + 64 * jq); }
	v_mul_f32_e32 v244, v244, v252
	v_mul_f32_e32 v245, v245, v253
	v_mul_f32_e32 v246, v246, v254
	v_mul_f32_e32 v247, v247, v255
	global_store_dwordx4 v[80:81], v[244:247], off offset:2048 nt
	s_add_i32 s43, s40, 32
	s_lshl_b32 s43, s43, 11
	v_add_u32_e32 v138, s43, v66
	global_load_dwordx2 v[194:195], v138, s[70:71]
	global_load_dwordx2 v[196:197], v138, s[70:71] offset:512
	global_load_dwordx2 v[198:199], v138, s[70:71] offset:1024
	global_load_dwordx2 v[200:201], v138, s[70:71] offset:1536
	v_add_u32_e32 v147, 8, v140
	v_and_b32_e32 v146, 15, v147
	v_xor_b32_e32 v146, 8, v146
	v_bfe_u32 v148, v147, 4, 4
	v_mul_lo_u32 v146, v146, s92
	v_mul_lo_u32 v148, v148, s92
	v_mov_b32_e32 v147, v146
	v_mov_b32_e32 v149, v148
	ds_write2st64_b64 v77, v[146:147], v[148:149] offset1:2
	v_add_u32_e32 v138, 0x1800, v74
	ds_read_u8 v139, v138
	v_add_u32_e32 v141, 0x1800, v73
	ds_read_u8 v140, v141
	s_add_i32 s43, s67, 160
	v_mov_b32_e32 v138, s43
	ds_read2st64_b32 v[228:229], v138 offset1:1
	ds_read_b128 v[18:21], v227 offset:12288
	ds_read_b128 v[22:25], v227 offset:12304
	v_mov_b32_e32 v150, v63
	v_mov_b32_e32 v151, v64
	v_mov_b32_e32 v38, 0
	v_mov_b32_e32 v39, 0
	v_mov_b32_e32 v40, 0
	v_mov_b32_e32 v41, 0
	v_mov_b32_e32 v42, 0
	v_mov_b32_e32 v43, 0
	v_mov_b32_e32 v44, 0
	v_mov_b32_e32 v45, 0
	v_and_b32_e32 v78, 0xffff, v31
	v_lshrrev_b32_e32 v79, 16, v31
	v_lshl_add_u32 v78, v78, 7, v152
	v_lshl_add_u32 v79, v79, 7, v153
	s_mov_b32 m0, s79
	s_add_i32 s43, s79, 0x400
	global_load_lds_dwordx4 v78, s[50:51]
	s_mov_b32 m0, s43
	s_nop 0
	global_load_lds_dwordx4 v79, s[50:51]
	s_waitcnt vmcnt(13)
	v_add_u32_e32 v54, s99, v59
	v_add_u32_e32 v55, s99, v60
	v_add_u32_e32 v56, s99, v61
	v_add_u32_e32 v57, s99, v62
	ds_read_b64_tr_b4 v[50:51], v160 offset:128
	ds_read_b64_tr_b4 v[52:53], v160 offset:1152
	ds_read_b64_tr_b4 v[130:131], v54
	ds_read_b64_tr_b4 v[132:133], v55
	ds_read_b64_tr_b4 v[134:135], v56
	ds_read_b64_tr_b4 v[136:137], v57
	s_waitcnt lgkmcnt(13)
	v_dot8c_i32_i4_e32 v38, v122, v48
	v_dot8c_i32_i4_e32 v39, v122, v46
	v_dot8c_i32_i4_e32 v40, v124, v48
	v_dot8c_i32_i4_e32 v41, v124, v46
	v_dot8c_i32_i4_e32 v42, v126, v48
	v_dot8c_i32_i4_e32 v43, v126, v46
	v_dot8c_i32_i4_e32 v44, v128, v48
	v_dot8c_i32_i4_e32 v45, v128, v46
	v_dot8c_i32_i4_e32 v38, v123, v49
	v_dot8c_i32_i4_e32 v39, v123, v47
	v_dot8c_i32_i4_e32 v40, v125, v49
	v_dot8c_i32_i4_e32 v41, v125, v47
	v_dot8c_i32_i4_e32 v42, v127, v49
	v_dot8c_i32_i4_e32 v43, v127, v47
	v_dot8c_i32_i4_e32 v44, v129, v49
	v_dot8c_i32_i4_e32 v45, v129, v47
	v_and_b32_e32 v78, 0xffff, v32
	v_lshrrev_b32_e32 v79, 16, v32
	v_lshl_add_u32 v78, v78, 7, v152
	v_lshl_add_u32 v79, v79, 7, v153
	s_mov_b32 m0, s98
	s_add_i32 s43, s98, 0x400
	global_load_lds_dwordx4 v78, s[50:51]
	s_mov_b32 m0, s43
	s_nop 0
	global_load_lds_dwordx4 v79, s[50:51]
	s_waitcnt vmcnt(13)
	v_add_u32_e32 v54, s76, v59
	v_add_u32_e32 v55, s76, v60
	v_add_u32_e32 v56, s76, v61
	v_add_u32_e32 v57, s76, v62
	ds_read_b64_tr_b4 v[46:47], v160 offset:256
	ds_read_b64_tr_b4 v[48:49], v160 offset:1280
	ds_read_b64_tr_b4 v[122:123], v54
	ds_read_b64_tr_b4 v[124:125], v55
	ds_read_b64_tr_b4 v[126:127], v56
	ds_read_b64_tr_b4 v[128:129], v57
	s_waitcnt lgkmcnt(6)
	v_dot8c_i32_i4_e32 v38, v130, v52
	v_dot8c_i32_i4_e32 v39, v130, v50
	v_dot8c_i32_i4_e32 v40, v132, v52
	v_dot8c_i32_i4_e32 v41, v132, v50
	v_dot8c_i32_i4_e32 v42, v134, v52
	v_dot8c_i32_i4_e32 v43, v134, v50
	v_dot8c_i32_i4_e32 v44, v136, v52
	v_dot8c_i32_i4_e32 v45, v136, v50
	v_dot8c_i32_i4_e32 v38, v131, v53
	v_dot8c_i32_i4_e32 v39, v131, v51
	v_dot8c_i32_i4_e32 v40, v133, v53
	v_dot8c_i32_i4_e32 v41, v133, v51
	v_dot8c_i32_i4_e32 v42, v135, v53
	v_dot8c_i32_i4_e32 v43, v135, v51
	v_dot8c_i32_i4_e32 v44, v137, v53
	v_dot8c_i32_i4_e32 v45, v137, v51
	v_and_b32_e32 v78, 0xffff, v33
	v_lshrrev_b32_e32 v79, 16, v33
	v_lshl_add_u32 v78, v78, 7, v152
	v_lshl_add_u32 v79, v79, 7, v153
	s_mov_b32 m0, s99
	s_add_i32 s43, s99, 0x400
	global_load_lds_dwordx4 v78, s[50:51]
	s_mov_b32 m0, s43
	s_nop 0
	global_load_lds_dwordx4 v79, s[50:51]
	s_waitcnt vmcnt(13)
	v_add_u32_e32 v54, s77, v59
	v_add_u32_e32 v55, s77, v60
	v_add_u32_e32 v56, s77, v61
	v_add_u32_e32 v57, s77, v62
	ds_read_b64_tr_b4 v[50:51], v160 offset:384
	ds_read_b64_tr_b4 v[52:53], v160 offset:1408
	ds_read_b64_tr_b4 v[130:131], v54
	ds_read_b64_tr_b4 v[132:133], v55
	ds_read_b64_tr_b4 v[134:135], v56
	ds_read_b64_tr_b4 v[136:137], v57
	s_waitcnt lgkmcnt(6)
	v_dot8c_i32_i4_e32 v38, v122, v48
	v_dot8c_i32_i4_e32 v39, v122, v46
	v_dot8c_i32_i4_e32 v40, v124, v48
	v_dot8c_i32_i4_e32 v41, v124, v46
	v_dot8c_i32_i4_e32 v42, v126, v48
	v_dot8c_i32_i4_e32 v43, v126, v46
	v_dot8c_i32_i4_e32 v44, v128, v48
	v_dot8c_i32_i4_e32 v45, v128, v46
	v_dot8c_i32_i4_e32 v38, v123, v49
	v_dot8c_i32_i4_e32 v39, v123, v47
	v_dot8c_i32_i4_e32 v40, v125, v49
	v_dot8c_i32_i4_e32 v41, v125, v47
	v_dot8c_i32_i4_e32 v42, v127, v49
	v_dot8c_i32_i4_e32 v43, v127, v47
	v_dot8c_i32_i4_e32 v44, v129, v49
	v_dot8c_i32_i4_e32 v45, v129, v47
	s_waitcnt lgkmcnt(15)
	v_and_b32_e32 v78, 0xffff, v18
	v_lshrrev_b32_e32 v79, 16, v18
	v_lshl_add_u32 v78, v78, 7, v150
	v_lshl_add_u32 v79, v79, 7, v151
	s_mov_b32 m0, s76
	s_add_i32 s43, s76, 0x400
	global_load_lds_dwordx4 v78, s[50:51]
	s_mov_b32 m0, s43
	s_nop 0
	global_load_lds_dwordx4 v79, s[50:51]
	s_waitcnt vmcnt(13)
	v_add_u32_e32 v54, s78, v59
	v_add_u32_e32 v55, s78, v60
	v_add_u32_e32 v56, s78, v61
	v_add_u32_e32 v57, s78, v62
	ds_read_b64_tr_b4 v[46:47], v160 offset:512
	ds_read_b64_tr_b4 v[48:49], v160 offset:1536
	ds_read_b64_tr_b4 v[122:123], v54
	ds_read_b64_tr_b4 v[124:125], v55
	ds_read_b64_tr_b4 v[126:127], v56
	ds_read_b64_tr_b4 v[128:129], v57
	s_waitcnt lgkmcnt(6)
; #define LAS __attribute__((address_space(3)))
; #define TR4(p_) __builtin_amdgcn_ds_read_tr4_b64_v2i32((LAS v2i*)(p_))
; __device__ __forceinline__ void peer_v_tokens(int j, const LAS unsigned short* EL, const LAS unsigned char* AL  , const LAS float* ASC  , const LAS int* SAL  , ...
;     ...
;         for (int m = 0; m < 2; ++m) {
;             const int idx = lane + 64 * m, tau = idx >> 4, sr = idx & 15, k = 16 * (sr & 7) + 2 * tau + (sr >> 3);
;             const int aq = (int)*(const LAS signed char*)(AL + tl * 128 + k); const int tq = aq + 8;
;             const unsigned lo = (((unsigned)tq & 15u) ^ 8u) * 0x11111111u, hi = ((unsigned)(tq >> 4) & 15u) * 0x11111111u;
;             typedef unsigned u2v __attribute__((ext_vector_type(2)));
;             u2v l2; l2.x = lo; l2.y = lo; u2v h2; h2.x = hi; h2.y = hi;
;             *(LAS u2v*)(ATL + 8 * idx) = l2; *(LAS u2v*)(ATL + 1024 + 8 * idx) = h2;
;         }
;     ...
; #pragma unroll
;         for (int st = 0; st < 16; ++st) {
;             const int p = st >> 2, q = st & 3;
;             if (st < 14) VDMA(st + 2, (st + 2) % 3);
;             if (st < 14) asm volatile("s_waitcnt vmcnt(8)" ::: "memory");
;             else if (st == 14) asm volatile("s_waitcnt vmcnt(4)" ::: "memory");
;             else asm volatile("s_waitcnt vmcnt(0)" ::: "memory");
;             if (q == 0) {
; #pragma unroll
;                 for (int r = 0; r < 4; ++r) { accH[r] = 0; accL[r] = 0; } }
; #pragma unroll
;             for (int tp = 0; tp < 2; ++tp) {
;                 const v2i ao = TR4(ATL + (2 * q + tp) * 128 + 8 * s16), ah = TR4(ATL + 1024 + (2 * q + tp) * 128 + 8 * s16);
; #pragma unroll
;                 for (int r = 0; r < 4; ++r) {
;                     const v2i d = TR4(ldsb + BUF[st % 3] + 2048 * tp + roff[r]);
;                     accH[r] = __builtin_amdgcn_sdot8(d.x, ah.x, accH[r], false); accH[r] = __builtin_amdgcn_sdot8(d.y, ah.y, accH[r], false);
;                     accL[r] = __builtin_amdgcn_sdot8(d.x, ao.x, accL[r], false); accL[r] = __builtin_amdgcn_sdot8(d.y, ao.y, accL[r], false);
;                 }
;             }
;             asm volatile("s_waitcnt lgkmcnt(0)" ::: "memory");
	v_dot8c_i32_i4_e32 v38, v130, v52
	v_dot8c_i32_i4_e32 v39, v130, v50
	v_dot8c_i32_i4_e32 v40, v132, v52
	v_dot8c_i32_i4_e32 v41, v132, v50
	v_dot8c_i32_i4_e32 v42, v134, v52
	v_dot8c_i32_i4_e32 v43, v134, v50
	v_dot8c_i32_i4_e32 v44, v136, v52
	v_dot8c_i32_i4_e32 v45, v136, v50
	v_dot8c_i32_i4_e32 v38, v131, v53
	v_dot8c_i32_i4_e32 v39, v131, v51
	v_dot8c_i32_i4_e32 v40, v133, v53
	v_dot8c_i32_i4_e32 v41, v133, v51
	v_dot8c_i32_i4_e32 v42, v135, v53
	v_dot8c_i32_i4_e32 v43, v135, v51
	v_dot8c_i32_i4_e32 v44, v137, v53
	v_dot8c_i32_i4_e32 v45, v137, v51
	v_and_b32_e32 v78, 0xffff, v19
	v_lshrrev_b32_e32 v79, 16, v19
	v_lshl_add_u32 v78, v78, 7, v150
	v_lshl_add_u32 v79, v79, 7, v151
	s_mov_b32 m0, s77
	s_add_i32 s43, s77, 0x400
	global_load_lds_dwordx4 v78, s[50:51]
	s_mov_b32 m0, s43
	s_nop 0
	global_load_lds_dwordx4 v79, s[50:51]
	s_waitcnt vmcnt(8)
	v_add_u32_e32 v54, s79, v59
	v_add_u32_e32 v55, s79, v60
	v_add_u32_e32 v56, s79, v61
	v_add_u32_e32 v57, s79, v62
	ds_read_b64_tr_b4 v[50:51], v160 offset:640
	ds_read_b64_tr_b4 v[52:53], v160 offset:1664
	ds_read_b64_tr_b4 v[130:131], v54
	ds_read_b64_tr_b4 v[132:133], v55
	ds_read_b64_tr_b4 v[134:135], v56
	ds_read_b64_tr_b4 v[136:137], v57
	s_waitcnt lgkmcnt(6)
	v_dot8c_i32_i4_e32 v38, v122, v48
	v_dot8c_i32_i4_e32 v39, v122, v46
	v_dot8c_i32_i4_e32 v40, v124, v48
	v_dot8c_i32_i4_e32 v41, v124, v46
	v_dot8c_i32_i4_e32 v42, v126, v48
	v_dot8c_i32_i4_e32 v43, v126, v46
	v_dot8c_i32_i4_e32 v44, v128, v48
	v_dot8c_i32_i4_e32 v45, v128, v46
	v_dot8c_i32_i4_e32 v38, v123, v49
	v_dot8c_i32_i4_e32 v39, v123, v47
	v_dot8c_i32_i4_e32 v40, v125, v49
	v_dot8c_i32_i4_e32 v41, v125, v47
	v_dot8c_i32_i4_e32 v42, v127, v49
	v_dot8c_i32_i4_e32 v43, v127, v47
	v_dot8c_i32_i4_e32 v44, v129, v49
	v_dot8c_i32_i4_e32 v45, v129, v47
	s_waitcnt lgkmcnt(15)
	v_add_u32_e32 v143, 8, v139
	v_and_b32_e32 v142, 15, v143
	v_xor_b32_e32 v142, 8, v142
	v_bfe_u32 v144, v143, 4, 4
	v_mul_lo_u32 v142, v142, s92
	v_mul_lo_u32 v144, v144, s92
	v_mov_b32_e32 v143, v142
	v_mov_b32_e32 v145, v144
	ds_write2st64_b64 v159, v[142:143], v[144:145] offset1:2
	v_and_b32_e32 v78, 0xffff, v20
	v_lshrrev_b32_e32 v79, 16, v20
	v_lshl_add_u32 v78, v78, 7, v150
	v_lshl_add_u32 v79, v79, 7, v151
	s_mov_b32 m0, s78
	s_add_i32 s43, s78, 0x400
	global_load_lds_dwordx4 v78, s[50:51]
	s_mov_b32 m0, s43
	s_nop 0
	global_load_lds_dwordx4 v79, s[50:51]
	s_waitcnt vmcnt(8)
	v_add_u32_e32 v54, s98, v59
	v_add_u32_e32 v55, s98, v60
	v_add_u32_e32 v56, s98, v61
	v_add_u32_e32 v57, s98, v62
	ds_read_b64_tr_b4 v[46:47], v160 offset:768
	ds_read_b64_tr_b4 v[48:49], v160 offset:1792
	ds_read_b64_tr_b4 v[122:123], v54
	ds_read_b64_tr_b4 v[124:125], v55
	ds_read_b64_tr_b4 v[126:127], v56
	ds_read_b64_tr_b4 v[128:129], v57
	s_waitcnt lgkmcnt(7)
	v_dot8c_i32_i4_e32 v38, v130, v52
	v_dot8c_i32_i4_e32 v39, v130, v50
	v_dot8c_i32_i4_e32 v40, v132, v52
	v_dot8c_i32_i4_e32 v41, v132, v50
	v_dot8c_i32_i4_e32 v42, v134, v52
	v_dot8c_i32_i4_e32 v43, v134, v50
	v_dot8c_i32_i4_e32 v44, v136, v52
	v_dot8c_i32_i4_e32 v45, v136, v50
	v_dot8c_i32_i4_e32 v38, v131, v53
	v_dot8c_i32_i4_e32 v39, v131, v51
	v_dot8c_i32_i4_e32 v40, v133, v53
	v_dot8c_i32_i4_e32 v41, v133, v51
	v_dot8c_i32_i4_e32 v42, v135, v53
	v_dot8c_i32_i4_e32 v43, v135, v51
	v_dot8c_i32_i4_e32 v44, v137, v53
	v_dot8c_i32_i4_e32 v45, v137, v51
	v_and_b32_e32 v78, 0xffff, v21
	v_lshrrev_b32_e32 v79, 16, v21
	v_lshl_add_u32 v78, v78, 7, v150
	v_lshl_add_u32 v79, v79, 7, v151
	s_mov_b32 m0, s79
	s_add_i32 s43, s79, 0x400
	global_load_lds_dwordx4 v78, s[50:51]
	s_mov_b32 m0, s43
	s_nop 0
	global_load_lds_dwordx4 v79, s[50:51]
	s_waitcnt vmcnt(8)
	v_add_u32_e32 v54, s99, v59
	v_add_u32_e32 v55, s99, v60
	v_add_u32_e32 v56, s99, v61
	v_add_u32_e32 v57, s99, v62
	ds_read_b64_tr_b4 v[50:51], v160 offset:896
	ds_read_b64_tr_b4 v[52:53], v160 offset:1920
	ds_read_b64_tr_b4 v[130:131], v54
	ds_read_b64_tr_b4 v[132:133], v55
	ds_read_b64_tr_b4 v[134:135], v56
	ds_read_b64_tr_b4 v[136:137], v57
	s_waitcnt lgkmcnt(6)
	v_dot8c_i32_i4_e32 v38, v122, v48
	v_dot8c_i32_i4_e32 v39, v122, v46
	v_dot8c_i32_i4_e32 v40, v124, v48
	v_dot8c_i32_i4_e32 v41, v124, v46
	v_dot8c_i32_i4_e32 v42, v126, v48
	v_dot8c_i32_i4_e32 v43, v126, v46
	v_dot8c_i32_i4_e32 v44, v128, v48
	v_dot8c_i32_i4_e32 v45, v128, v46
	v_dot8c_i32_i4_e32 v38, v123, v49
	v_dot8c_i32_i4_e32 v39, v123, v47
	v_dot8c_i32_i4_e32 v40, v125, v49
	v_dot8c_i32_i4_e32 v41, v125, v47
	v_dot8c_i32_i4_e32 v42, v127, v49
	v_dot8c_i32_i4_e32 v43, v127, v47
	v_dot8c_i32_i4_e32 v44, v129, v49
	v_dot8c_i32_i4_e32 v45, v129, v47
	v_and_b32_e32 v78, 0xffff, v22
	v_lshrrev_b32_e32 v79, 16, v22
	v_lshl_add_u32 v78, v78, 7, v150
	v_lshl_add_u32 v79, v79, 7, v151
	s_mov_b32 m0, s98
	s_add_i32 s43, s98, 0x400
	global_load_lds_dwordx4 v78, s[50:51]
	s_mov_b32 m0, s43
	s_nop 0
	global_load_lds_dwordx4 v79, s[50:51]
	s_waitcnt vmcnt(8)
	v_add_u32_e32 v54, s76, v59
	v_add_u32_e32 v55, s76, v60
	v_add_u32_e32 v56, s76, v61
	v_add_u32_e32 v57, s76, v62
	ds_read_b64_tr_b4 v[46:47], v160
	ds_read_b64_tr_b4 v[48:49], v160 offset:1024
	ds_read_b64_tr_b4 v[122:123], v54
	ds_read_b64_tr_b4 v[124:125], v55
	ds_read_b64_tr_b4 v[126:127], v56
	ds_read_b64_tr_b4 v[128:129], v57
	s_waitcnt lgkmcnt(6)
	v_dot8c_i32_i4_e32 v38, v130, v52
	v_dot8c_i32_i4_e32 v39, v130, v50
	v_dot8c_i32_i4_e32 v40, v132, v52
	v_dot8c_i32_i4_e32 v41, v132, v50
	v_dot8c_i32_i4_e32 v42, v134, v52
	v_dot8c_i32_i4_e32 v43, v134, v50
	v_dot8c_i32_i4_e32 v44, v136, v52
	v_dot8c_i32_i4_e32 v45, v136, v50
	v_dot8c_i32_i4_e32 v38, v131, v53
	v_dot8c_i32_i4_e32 v39, v131, v51
	v_dot8c_i32_i4_e32 v40, v133, v53
	v_dot8c_i32_i4_e32 v41, v133, v51
	v_dot8c_i32_i4_e32 v42, v135, v53
	v_dot8c_i32_i4_e32 v43, v135, v51
	v_dot8c_i32_i4_e32 v44, v137, v53
	v_dot8c_i32_i4_e32 v45, v137, v51
	s_nop 3
	s_waitcnt lgkmcnt(15)
; #define LAS __attribute__((address_space(3)))
; __device__ __forceinline__ void peer_v_tokens(int j, const LAS unsigned short* EL, const LAS unsigned char* AL  , const LAS float* ASC  , const LAS int* SAL  , ...
;     ...
;         const int tl = it * 8 + wave, t = j * 64 + tl;
;         unsigned E[8];
;         { const LAS v4u* ep = (const LAS v4u*)(EL + tl * 128 + 16 * g); const v4u e0 = ep[0], e1 = ep[1];
;           E[0] = e0.x; E[1] = e0.y; E[2] = e0.z; E[3] = e0.w; E[4] = e1.x; E[5] = e1.y; E[6] = e1.z; E[7] = e1.w; }
;     ...
;         for (int m = 0; m < 2; ++m) {
;             const int idx = lane + 64 * m, tau = idx >> 4, sr = idx & 15, k = 16 * (sr & 7) + 2 * tau + (sr >> 3);
;             const int aq = (int)*(const LAS signed char*)(AL + tl * 128 + k); const int tq = aq + 8;
;             const unsigned lo = (((unsigned)tq & 15u) ^ 8u) * 0x11111111u, hi = ((unsigned)(tq >> 4) & 15u) * 0x11111111u;
;             typedef unsigned u2v __attribute__((ext_vector_type(2)));
;             u2v l2; l2.x = lo; l2.y = lo; u2v h2; h2.x = hi; h2.y = hi;
;             *(LAS u2v*)(ATL + 8 * idx) = l2; *(LAS u2v*)(ATL + 1024 + 8 * idx) = h2;
;         }
;     ...
; #pragma unroll
;         for (int st = 0; st < 16; ++st) {
;             const int p = st >> 2, q = st & 3;
;             if (st < 14) VDMA(st + 2, (st + 2) % 3);
;             if (st < 14) asm volatile("s_waitcnt vmcnt(8)" ::: "memory");
;             else if (st == 14) asm volatile("s_waitcnt vmcnt(4)" ::: "memory");
;             else asm volatile("s_waitcnt vmcnt(0)" ::: "memory");
;             if (q == 0) {
; #pragma unroll
;                 for (int r = 0; r < 4; ++r) { accH[r] = 0; accL[r] = 0; } }
; #pragma unroll
;             for (int tp = 0; tp < 2; ++tp) {
;                 const v2i ao = TR4(ATL + (2 * q + tp) * 128 + 8 * s16), ah = TR4(ATL + 1024 + (2 * q + tp) * 128 + 8 * s16);
; #pragma unroll
;                 for (int r = 0; r < 4; ++r) {
;     ...
;                 for (int r = 0; r < 4; ++r) STASH[256 * p + 16 * (grp + 4 * r) + pc] = f2bf(asc * (float)(2 * ((accH[r] << 4) + accL[r]) + sa));
;     ...
;             for (int jq = 0; jq < 4; ++jq) { typedef float f4v __attribute__((ext_vector_type(4))); f4v o4; o4.x = v[jq].x * r3 * gv[jq].x; o4.y = v[jq].y * r3 * gv[jq].y; o4.z = v[jq].z * r3 * gv[jq].z; o4.w = v[jq].w * r3 * gv[jq].w;
;                 __builtin_nontemporal_store(o4, (f4v*)op + 64 * jq); }
	v_lshlrev_b32_e32 v38, 5, v38
	v_lshlrev_b32_e32 v39, 1, v39
	v_add3_u32 v38, v39, v229, v38
	v_cvt_f32_i32_e32 v38, v38
	v_mul_f32_e32 v38, v228, v38
	v_lshlrev_b32_e32 v40, 5, v40
	v_lshlrev_b32_e32 v41, 1, v41
	v_add3_u32 v40, v41, v229, v40
	v_cvt_f32_i32_e32 v40, v40
	v_mul_f32_e32 v40, v228, v40
	v_lshlrev_b32_e32 v42, 5, v42
	v_lshlrev_b32_e32 v43, 1, v43
	v_add3_u32 v42, v43, v229, v42
	v_cvt_f32_i32_e32 v42, v42
	v_mul_f32_e32 v42, v228, v42
	v_lshlrev_b32_e32 v44, 5, v44
	v_lshlrev_b32_e32 v45, 1, v45
	v_add3_u32 v44, v45, v229, v44
	v_cvt_f32_i32_e32 v44, v44
	v_mul_f32_e32 v44, v228, v44
	v_cvt_pk_bf16_f32 v176, v38, v40
	v_cvt_pk_bf16_f32 v177, v42, v44
	ds_read_b128 v[252:255], v156 offset:1024
	s_add_i32 s44, s40, 24
	s_ashr_i32 s45, s44, 31
	s_lshl_b64 s[44:45], s[44:45], 12
	v_lshl_add_u64 v[80:81], v[36:37], 0, s[44:45]
	s_waitcnt lgkmcnt(0)
	v_mul_f32_e32 v248, v248, v252
	v_mul_f32_e32 v249, v249, v253
	v_mul_f32_e32 v250, v250, v254
	v_mul_f32_e32 v251, v251, v255
	global_store_dwordx4 v[80:81], v[248:251], off offset:3072 nt
	v_add_u32_e32 v147, 8, v140
	v_and_b32_e32 v146, 15, v147
	v_xor_b32_e32 v146, 8, v146
	v_bfe_u32 v148, v147, 4, 4
	v_mul_lo_u32 v146, v146, s92
	v_mul_lo_u32 v148, v148, s92
	v_mov_b32_e32 v147, v146
	v_mov_b32_e32 v149, v148
	ds_write2st64_b64 v77, v[146:147], v[148:149] offset1:2
	v_add_u32_e32 v138, 0x1c00, v74
	ds_read_u8 v139, v138
	v_add_u32_e32 v141, 0x1c00, v73
	ds_read_u8 v140, v141
	s_add_i32 s43, s67, 192
	v_mov_b32_e32 v138, s43
	ds_read2st64_b32 v[228:229], v138 offset1:1
	ds_read_b128 v[26:29], v227 offset:14336
	ds_read_b128 v[30:33], v227 offset:14352
	v_mov_b32_e32 v38, 0
	v_mov_b32_e32 v39, 0
	v_mov_b32_e32 v40, 0
	v_mov_b32_e32 v41, 0
	v_mov_b32_e32 v42, 0
	v_mov_b32_e32 v43, 0
	v_mov_b32_e32 v44, 0
	v_mov_b32_e32 v45, 0
	v_and_b32_e32 v78, 0xffff, v23
	v_lshrrev_b32_e32 v79, 16, v23
	v_lshl_add_u32 v78, v78, 7, v150
	v_lshl_add_u32 v79, v79, 7, v151
	s_mov_b32 m0, s99
	s_add_i32 s43, s99, 0x400
	global_load_lds_dwordx4 v78, s[50:51]
	s_mov_b32 m0, s43
	s_nop 0
	global_load_lds_dwordx4 v79, s[50:51]
	s_waitcnt vmcnt(9)
	v_add_u32_e32 v54, s77, v59
	v_add_u32_e32 v55, s77, v60
	v_add_u32_e32 v56, s77, v61
	v_add_u32_e32 v57, s77, v62
	ds_read_b64_tr_b4 v[50:51], v160 offset:128
	ds_read_b64_tr_b4 v[52:53], v160 offset:1152
	ds_read_b64_tr_b4 v[130:131], v54
	ds_read_b64_tr_b4 v[132:133], v55
	ds_read_b64_tr_b4 v[134:135], v56
	ds_read_b64_tr_b4 v[136:137], v57
	s_waitcnt lgkmcnt(13)
	v_dot8c_i32_i4_e32 v38, v122, v48
	v_dot8c_i32_i4_e32 v39, v122, v46
	v_dot8c_i32_i4_e32 v40, v124, v48
	v_dot8c_i32_i4_e32 v41, v124, v46
	v_dot8c_i32_i4_e32 v42, v126, v48
	v_dot8c_i32_i4_e32 v43, v126, v46
	v_dot8c_i32_i4_e32 v44, v128, v48
	v_dot8c_i32_i4_e32 v45, v128, v46
	v_dot8c_i32_i4_e32 v38, v123, v49
	v_dot8c_i32_i4_e32 v39, v123, v47
	v_dot8c_i32_i4_e32 v40, v125, v49
	v_dot8c_i32_i4_e32 v41, v125, v47
	v_dot8c_i32_i4_e32 v42, v127, v49
	v_dot8c_i32_i4_e32 v43, v127, v47
	v_dot8c_i32_i4_e32 v44, v129, v49
	v_dot8c_i32_i4_e32 v45, v129, v47
	v_and_b32_e32 v78, 0xffff, v24
	v_lshrrev_b32_e32 v79, 16, v24
	v_lshl_add_u32 v78, v78, 7, v150
	v_lshl_add_u32 v79, v79, 7, v151
	s_mov_b32 m0, s76
	s_add_i32 s43, s76, 0x400
	global_load_lds_dwordx4 v78, s[50:51]
	s_mov_b32 m0, s43
	s_nop 0
	global_load_lds_dwordx4 v79, s[50:51]
	s_waitcnt vmcnt(9)
	v_add_u32_e32 v54, s78, v59
	v_add_u32_e32 v55, s78, v60
	v_add_u32_e32 v56, s78, v61
	v_add_u32_e32 v57, s78, v62
	ds_read_b64_tr_b4 v[46:47], v160 offset:256
	ds_read_b64_tr_b4 v[48:49], v160 offset:1280
	ds_read_b64_tr_b4 v[122:123], v54
	ds_read_b64_tr_b4 v[124:125], v55
	ds_read_b64_tr_b4 v[126:127], v56
	ds_read_b64_tr_b4 v[128:129], v57
	s_waitcnt lgkmcnt(6)
	v_dot8c_i32_i4_e32 v38, v130, v52
	v_dot8c_i32_i4_e32 v39, v130, v50
	v_dot8c_i32_i4_e32 v40, v132, v52
	v_dot8c_i32_i4_e32 v41, v132, v50
	v_dot8c_i32_i4_e32 v42, v134, v52
	v_dot8c_i32_i4_e32 v43, v134, v50
	v_dot8c_i32_i4_e32 v44, v136, v52
	v_dot8c_i32_i4_e32 v45, v136, v50
	v_dot8c_i32_i4_e32 v38, v131, v53
	v_dot8c_i32_i4_e32 v39, v131, v51
	v_dot8c_i32_i4_e32 v40, v133, v53
	v_dot8c_i32_i4_e32 v41, v133, v51
	v_dot8c_i32_i4_e32 v42, v135, v53
	v_dot8c_i32_i4_e32 v43, v135, v51
	v_dot8c_i32_i4_e32 v44, v137, v53
	v_dot8c_i32_i4_e32 v45, v137, v51
	ds_write_b16 v65, v162
	ds_write_b16_d16_hi v65, v162 offset:128
	ds_write_b16 v65, v163 offset:256
	ds_write_b16_d16_hi v65, v163 offset:384
	ds_write_b16 v65, v164 offset:512
	ds_write_b16_d16_hi v65, v164 offset:640
	ds_write_b16 v65, v165 offset:768
	ds_write_b16_d16_hi v65, v165 offset:896
	ds_write_b16 v65, v166 offset:1024
	ds_write_b16_d16_hi v65, v166 offset:1152
	ds_write_b16 v65, v167 offset:1280
	ds_write_b16_d16_hi v65, v167 offset:1408
	ds_write_b16 v65, v168 offset:1536
	ds_write_b16_d16_hi v65, v168 offset:1664
	ds_write_b16 v65, v169 offset:1792
	ds_write_b16_d16_hi v65, v169 offset:1920
	ds_read_b64 v[202:203], v154
	ds_read_b64 v[204:205], v154 offset:512
	ds_read_b64 v[206:207], v154 offset:1024
	ds_read_b64 v[208:209], v154 offset:1536
	v_and_b32_e32 v78, 0xffff, v25
	v_lshrrev_b32_e32 v79, 16, v25
	v_lshl_add_u32 v78, v78, 7, v150
	v_lshl_add_u32 v79, v79, 7, v151
	s_mov_b32 m0, s77
	s_add_i32 s43, s77, 0x400
	global_load_lds_dwordx4 v78, s[50:51]
	s_mov_b32 m0, s43
	s_nop 0
	global_load_lds_dwordx4 v79, s[50:51]
	s_waitcnt vmcnt(9)
	v_add_u32_e32 v54, s79, v59
	v_add_u32_e32 v55, s79, v60
	v_add_u32_e32 v56, s79, v61
	v_add_u32_e32 v57, s79, v62
	ds_read_b64_tr_b4 v[50:51], v160 offset:384
	ds_read_b64_tr_b4 v[52:53], v160 offset:1408
	ds_read_b64_tr_b4 v[130:131], v54
	ds_read_b64_tr_b4 v[132:133], v55
	ds_read_b64_tr_b4 v[134:135], v56
	ds_read_b64_tr_b4 v[136:137], v57
	s_waitcnt lgkmcnt(15)
; #define LAS __attribute__((address_space(3)))
; #define TR4(p_) __builtin_amdgcn_ds_read_tr4_b64_v2i32((LAS v2i*)(p_))
; __device__ __forceinline__ void peer_v_tokens(int j, const LAS unsigned short* EL, const LAS unsigned char* AL  , const LAS float* ASC  , const LAS int* SAL  , ...
;     ...
;         for (int m = 0; m < 2; ++m) {
;             const int idx = lane + 64 * m, tau = idx >> 4, sr = idx & 15, k = 16 * (sr & 7) + 2 * tau + (sr >> 3);
;             const int aq = (int)*(const LAS signed char*)(AL + tl * 128 + k); const int tq = aq + 8;
;             const unsigned lo = (((unsigned)tq & 15u) ^ 8u) * 0x11111111u, hi = ((unsigned)(tq >> 4) & 15u) * 0x11111111u;
;             typedef unsigned u2v __attribute__((ext_vector_type(2)));
;             u2v l2; l2.x = lo; l2.y = lo; u2v h2; h2.x = hi; h2.y = hi;
;             *(LAS u2v*)(ATL + 8 * idx) = l2; *(LAS u2v*)(ATL + 1024 + 8 * idx) = h2;
;         }
;     ...
; #pragma unroll
;         for (int st = 0; st < 16; ++st) {
;             const int p = st >> 2, q = st & 3;
;             if (st < 14) VDMA(st + 2, (st + 2) % 3);
;             if (st < 14) asm volatile("s_waitcnt vmcnt(8)" ::: "memory");
;             else if (st == 14) asm volatile("s_waitcnt vmcnt(4)" ::: "memory");
;             else asm volatile("s_waitcnt vmcnt(0)" ::: "memory");
;             if (q == 0) {
; #pragma unroll
;                 for (int r = 0; r < 4; ++r) { accH[r] = 0; accL[r] = 0; } }
; #pragma unroll
;             for (int tp = 0; tp < 2; ++tp) {
;                 const v2i ao = TR4(ATL + (2 * q + tp) * 128 + 8 * s16), ah = TR4(ATL + 1024 + (2 * q + tp) * 128 + 8 * s16);
; #pragma unroll
;                 for (int r = 0; r < 4; ++r) {
;                     const v2i d = TR4(ldsb + BUF[st % 3] + 2048 * tp + roff[r]);
;                     accH[r] = __builtin_amdgcn_sdot8(d.x, ah.x, accH[r], false); accH[r] = __builtin_amdgcn_sdot8(d.y, ah.y, accH[r], false);
;                     accL[r] = __builtin_amdgcn_sdot8(d.x, ao.x, accL[r], false); accL[r] = __builtin_amdgcn_sdot8(d.y, ao.y, accL[r], false);
;                 }
;             }
;             asm volatile("s_waitcnt lgkmcnt(0)" ::: "memory");
	v_dot8c_i32_i4_e32 v38, v122, v48
	v_dot8c_i32_i4_e32 v39, v122, v46
	v_dot8c_i32_i4_e32 v40, v124, v48
	v_dot8c_i32_i4_e32 v41, v124, v46
	v_dot8c_i32_i4_e32 v42, v126, v48
	v_dot8c_i32_i4_e32 v43, v126, v46
	v_dot8c_i32_i4_e32 v44, v128, v48
	v_dot8c_i32_i4_e32 v45, v128, v46
	v_dot8c_i32_i4_e32 v38, v123, v49
	v_dot8c_i32_i4_e32 v39, v123, v47
	v_dot8c_i32_i4_e32 v40, v125, v49
	v_dot8c_i32_i4_e32 v41, v125, v47
	v_dot8c_i32_i4_e32 v42, v127, v49
	v_dot8c_i32_i4_e32 v43, v127, v47
	v_dot8c_i32_i4_e32 v44, v129, v49
	v_dot8c_i32_i4_e32 v45, v129, v47
	s_waitcnt lgkmcnt(15)
	v_and_b32_e32 v78, 0xffff, v26
	v_lshrrev_b32_e32 v79, 16, v26
	v_lshl_add_u32 v78, v78, 7, v150
	v_lshl_add_u32 v79, v79, 7, v151
	s_mov_b32 m0, s78
	s_add_i32 s43, s78, 0x400
	global_load_lds_dwordx4 v78, s[50:51]
	s_mov_b32 m0, s43
	s_nop 0
	global_load_lds_dwordx4 v79, s[50:51]
	s_waitcnt vmcnt(9)
	v_add_u32_e32 v54, s98, v59
	v_add_u32_e32 v55, s98, v60
	v_add_u32_e32 v56, s98, v61
	v_add_u32_e32 v57, s98, v62
	ds_read_b64_tr_b4 v[46:47], v160 offset:512
	ds_read_b64_tr_b4 v[48:49], v160 offset:1536
	ds_read_b64_tr_b4 v[122:123], v54
	ds_read_b64_tr_b4 v[124:125], v55
	ds_read_b64_tr_b4 v[126:127], v56
	ds_read_b64_tr_b4 v[128:129], v57
	s_waitcnt lgkmcnt(6)
	v_dot8c_i32_i4_e32 v38, v130, v52
	v_dot8c_i32_i4_e32 v39, v130, v50
	v_dot8c_i32_i4_e32 v40, v132, v52
	v_dot8c_i32_i4_e32 v41, v132, v50
	v_dot8c_i32_i4_e32 v42, v134, v52
	v_dot8c_i32_i4_e32 v43, v134, v50
	v_dot8c_i32_i4_e32 v44, v136, v52
	v_dot8c_i32_i4_e32 v45, v136, v50
	v_dot8c_i32_i4_e32 v38, v131, v53
	v_dot8c_i32_i4_e32 v39, v131, v51
	v_dot8c_i32_i4_e32 v40, v133, v53
	v_dot8c_i32_i4_e32 v41, v133, v51
	v_dot8c_i32_i4_e32 v42, v135, v53
	v_dot8c_i32_i4_e32 v43, v135, v51
	v_dot8c_i32_i4_e32 v44, v137, v53
	v_dot8c_i32_i4_e32 v45, v137, v51
	v_and_b32_e32 v78, 0xffff, v27
	v_lshrrev_b32_e32 v79, 16, v27
	v_lshl_add_u32 v78, v78, 7, v150
	v_lshl_add_u32 v79, v79, 7, v151
	s_mov_b32 m0, s79
	s_add_i32 s43, s79, 0x400
	global_load_lds_dwordx4 v78, s[50:51]
	s_mov_b32 m0, s43
	s_nop 0
	global_load_lds_dwordx4 v79, s[50:51]
	s_waitcnt vmcnt(8)
	v_add_u32_e32 v54, s99, v59
	v_add_u32_e32 v55, s99, v60
	v_add_u32_e32 v56, s99, v61
	v_add_u32_e32 v57, s99, v62
	ds_read_b64_tr_b4 v[50:51], v160 offset:640
	ds_read_b64_tr_b4 v[52:53], v160 offset:1664
	ds_read_b64_tr_b4 v[130:131], v54
	ds_read_b64_tr_b4 v[132:133], v55
	ds_read_b64_tr_b4 v[134:135], v56
	ds_read_b64_tr_b4 v[136:137], v57
	s_waitcnt lgkmcnt(6)
	v_dot8c_i32_i4_e32 v38, v122, v48
	v_dot8c_i32_i4_e32 v39, v122, v46
	v_dot8c_i32_i4_e32 v40, v124, v48
	v_dot8c_i32_i4_e32 v41, v124, v46
	v_dot8c_i32_i4_e32 v42, v126, v48
	v_dot8c_i32_i4_e32 v43, v126, v46
	v_dot8c_i32_i4_e32 v44, v128, v48
	v_dot8c_i32_i4_e32 v45, v128, v46
	v_dot8c_i32_i4_e32 v38, v123, v49
	v_dot8c_i32_i4_e32 v39, v123, v47
	v_dot8c_i32_i4_e32 v40, v125, v49
	v_dot8c_i32_i4_e32 v41, v125, v47
	v_dot8c_i32_i4_e32 v42, v127, v49
	v_dot8c_i32_i4_e32 v43, v127, v47
	v_dot8c_i32_i4_e32 v44, v129, v49
	v_dot8c_i32_i4_e32 v45, v129, v47
	s_waitcnt lgkmcnt(15)
	v_add_u32_e32 v143, 8, v139
	v_and_b32_e32 v142, 15, v143
	v_xor_b32_e32 v142, 8, v142
	v_bfe_u32 v144, v143, 4, 4
	v_mul_lo_u32 v142, v142, s92
	v_mul_lo_u32 v144, v144, s92
	v_mov_b32_e32 v143, v142
	v_mov_b32_e32 v145, v144
	ds_write2st64_b64 v159, v[142:143], v[144:145] offset1:2
	v_and_b32_e32 v78, 0xffff, v28
	v_lshrrev_b32_e32 v79, 16, v28
	v_lshl_add_u32 v78, v78, 7, v150
	v_lshl_add_u32 v79, v79, 7, v151
	s_mov_b32 m0, s98
	s_add_i32 s43, s98, 0x400
	global_load_lds_dwordx4 v78, s[50:51]
	s_mov_b32 m0, s43
	s_nop 0
	global_load_lds_dwordx4 v79, s[50:51]
	s_waitcnt vmcnt(8)
	v_add_u32_e32 v54, s76, v59
	v_add_u32_e32 v55, s76, v60
	v_add_u32_e32 v56, s76, v61
	v_add_u32_e32 v57, s76, v62
	ds_read_b64_tr_b4 v[46:47], v160 offset:768
	ds_read_b64_tr_b4 v[48:49], v160 offset:1792
	ds_read_b64_tr_b4 v[122:123], v54
	ds_read_b64_tr_b4 v[124:125], v55
	ds_read_b64_tr_b4 v[126:127], v56
	ds_read_b64_tr_b4 v[128:129], v57
	s_waitcnt lgkmcnt(7)
	v_dot8c_i32_i4_e32 v38, v130, v52
	v_dot8c_i32_i4_e32 v39, v130, v50
	v_dot8c_i32_i4_e32 v40, v132, v52
	v_dot8c_i32_i4_e32 v41, v132, v50
	v_dot8c_i32_i4_e32 v42, v134, v52
	v_dot8c_i32_i4_e32 v43, v134, v50
	v_dot8c_i32_i4_e32 v44, v136, v52
	v_dot8c_i32_i4_e32 v45, v136, v50
	v_dot8c_i32_i4_e32 v38, v131, v53
	v_dot8c_i32_i4_e32 v39, v131, v51
	v_dot8c_i32_i4_e32 v40, v133, v53
	v_dot8c_i32_i4_e32 v41, v133, v51
	v_dot8c_i32_i4_e32 v42, v135, v53
	v_dot8c_i32_i4_e32 v43, v135, v51
	v_dot8c_i32_i4_e32 v44, v137, v53
	v_dot8c_i32_i4_e32 v45, v137, v51
	v_and_b32_e32 v78, 0xffff, v29
	v_lshrrev_b32_e32 v79, 16, v29
	v_lshl_add_u32 v78, v78, 7, v150
	v_lshl_add_u32 v79, v79, 7, v151
	s_mov_b32 m0, s99
	s_add_i32 s43, s99, 0x400
	global_load_lds_dwordx4 v78, s[50:51]
	s_mov_b32 m0, s43
	s_nop 0
	global_load_lds_dwordx4 v79, s[50:51]
	s_waitcnt vmcnt(8)
	v_add_u32_e32 v54, s77, v59
	v_add_u32_e32 v55, s77, v60
	v_add_u32_e32 v56, s77, v61
	v_add_u32_e32 v57, s77, v62
	ds_read_b64_tr_b4 v[50:51], v160 offset:896
	ds_read_b64_tr_b4 v[52:53], v160 offset:1920
	ds_read_b64_tr_b4 v[130:131], v54
	ds_read_b64_tr_b4 v[132:133], v55
	ds_read_b64_tr_b4 v[134:135], v56
	ds_read_b64_tr_b4 v[136:137], v57
	s_waitcnt lgkmcnt(6)
; #define LAS __attribute__((address_space(3)))
; __device__ __forceinline__ void peer_v_tokens(int j, const LAS unsigned short* EL, const LAS unsigned char* AL  , const LAS float* ASC  , const LAS int* SAL  , ...
;     ...
;         const int tl = it * 8 + wave, t = j * 64 + tl;
;         unsigned E[8];
;     ...
;         for (int m = 0; m < 2; ++m) {
;             const int idx = lane + 64 * m, tau = idx >> 4, sr = idx & 15, k = 16 * (sr & 7) + 2 * tau + (sr >> 3);
;             const int aq = (int)*(const LAS signed char*)(AL + tl * 128 + k); const int tq = aq + 8;
;             const unsigned lo = (((unsigned)tq & 15u) ^ 8u) * 0x11111111u, hi = ((unsigned)(tq >> 4) & 15u) * 0x11111111u;
;             typedef unsigned u2v __attribute__((ext_vector_type(2)));
;             u2v l2; l2.x = lo; l2.y = lo; u2v h2; h2.x = hi; h2.y = hi;
;             *(LAS u2v*)(ATL + 8 * idx) = l2; *(LAS u2v*)(ATL + 1024 + 8 * idx) = h2;
;         }
;     ...
; #pragma unroll
;         for (int st = 0; st < 16; ++st) {
;             const int p = st >> 2, q = st & 3;
;             if (st < 14) VDMA(st + 2, (st + 2) % 3);
;             if (st < 14) asm volatile("s_waitcnt vmcnt(8)" ::: "memory");
;             else if (st == 14) asm volatile("s_waitcnt vmcnt(4)" ::: "memory");
;             else asm volatile("s_waitcnt vmcnt(0)" ::: "memory");
;             if (q == 0) {
; #pragma unroll
;                 for (int r = 0; r < 4; ++r) { accH[r] = 0; accL[r] = 0; } }
; #pragma unroll
;             for (int tp = 0; tp < 2; ++tp) {
;                 const v2i ao = TR4(ATL + (2 * q + tp) * 128 + 8 * s16), ah = TR4(ATL + 1024 + (2 * q + tp) * 128 + 8 * s16);
; #pragma unroll
;                 for (int r = 0; r < 4; ++r) {
;                     const v2i d = TR4(ldsb + BUF[st % 3] + 2048 * tp + roff[r]);
;                     accH[r] = __builtin_amdgcn_sdot8(d.x, ah.x, accH[r], false); accH[r] = __builtin_amdgcn_sdot8(d.y, ah.y, accH[r], false);
;                     accL[r] = __builtin_amdgcn_sdot8(d.x, ao.x, accL[r], false); accL[r] = __builtin_amdgcn_sdot8(d.y, ao.y, accL[r], false);
;                 }
;             }
;             asm volatile("s_waitcnt lgkmcnt(0)" ::: "memory");
;             if (q == 3) {
; #pragma unroll
;                 for (int r = 0; r < 4; ++r) STASH[256 * p + 16 * (grp + 4 * r) + pc] = f2bf(asc * (float)(2 * ((accH[r] << 4) + accL[r]) + sa));
;             }
;         }
	v_dot8c_i32_i4_e32 v38, v122, v48
	v_dot8c_i32_i4_e32 v39, v122, v46
	v_dot8c_i32_i4_e32 v40, v124, v48
	v_dot8c_i32_i4_e32 v41, v124, v46
	v_dot8c_i32_i4_e32 v42, v126, v48
	v_dot8c_i32_i4_e32 v43, v126, v46
	v_dot8c_i32_i4_e32 v44, v128, v48
	v_dot8c_i32_i4_e32 v45, v128, v46
	v_dot8c_i32_i4_e32 v38, v123, v49
	v_dot8c_i32_i4_e32 v39, v123, v47
	v_dot8c_i32_i4_e32 v40, v125, v49
	v_dot8c_i32_i4_e32 v41, v125, v47
	v_dot8c_i32_i4_e32 v42, v127, v49
	v_dot8c_i32_i4_e32 v43, v127, v47
	v_dot8c_i32_i4_e32 v44, v129, v49
	v_dot8c_i32_i4_e32 v45, v129, v47
	v_and_b32_e32 v78, 0xffff, v30
	v_lshrrev_b32_e32 v79, 16, v30
	v_lshl_add_u32 v78, v78, 7, v150
	v_lshl_add_u32 v79, v79, 7, v151
	s_mov_b32 m0, s76
	s_add_i32 s43, s76, 0x400
	global_load_lds_dwordx4 v78, s[50:51]
	s_mov_b32 m0, s43
	s_nop 0
	global_load_lds_dwordx4 v79, s[50:51]
	s_waitcnt vmcnt(8)
	v_add_u32_e32 v54, s78, v59
	v_add_u32_e32 v55, s78, v60
	v_add_u32_e32 v56, s78, v61
	v_add_u32_e32 v57, s78, v62
	ds_read_b64_tr_b4 v[46:47], v160
	ds_read_b64_tr_b4 v[48:49], v160 offset:1024
	ds_read_b64_tr_b4 v[122:123], v54
	ds_read_b64_tr_b4 v[124:125], v55
	ds_read_b64_tr_b4 v[126:127], v56
	ds_read_b64_tr_b4 v[128:129], v57
	s_waitcnt lgkmcnt(6)
	v_dot8c_i32_i4_e32 v38, v130, v52
	v_dot8c_i32_i4_e32 v39, v130, v50
	v_dot8c_i32_i4_e32 v40, v132, v52
	v_dot8c_i32_i4_e32 v41, v132, v50
	v_dot8c_i32_i4_e32 v42, v134, v52
	v_dot8c_i32_i4_e32 v43, v134, v50
	v_dot8c_i32_i4_e32 v44, v136, v52
	v_dot8c_i32_i4_e32 v45, v136, v50
	v_dot8c_i32_i4_e32 v38, v131, v53
	v_dot8c_i32_i4_e32 v39, v131, v51
	v_dot8c_i32_i4_e32 v40, v133, v53
	v_dot8c_i32_i4_e32 v41, v133, v51
	v_dot8c_i32_i4_e32 v42, v135, v53
	v_dot8c_i32_i4_e32 v43, v135, v51
	v_dot8c_i32_i4_e32 v44, v137, v53
	v_dot8c_i32_i4_e32 v45, v137, v51
	s_nop 3
	s_waitcnt lgkmcnt(15)
	v_lshlrev_b32_e32 v38, 5, v38
	v_lshlrev_b32_e32 v39, 1, v39
	v_add3_u32 v38, v39, v229, v38
	v_cvt_f32_i32_e32 v38, v38
	v_mul_f32_e32 v38, v228, v38
	v_lshlrev_b32_e32 v40, 5, v40
	v_lshlrev_b32_e32 v41, 1, v41
	v_add3_u32 v40, v41, v229, v40
	v_cvt_f32_i32_e32 v40, v40
	v_mul_f32_e32 v40, v228, v40
	v_lshlrev_b32_e32 v42, 5, v42
	v_lshlrev_b32_e32 v43, 1, v43
	v_add3_u32 v42, v43, v229, v42
	v_cvt_f32_i32_e32 v42, v42
	v_mul_f32_e32 v42, v228, v42
	v_lshlrev_b32_e32 v44, 5, v44
	v_lshlrev_b32_e32 v45, 1, v45
	v_add3_u32 v44, v45, v229, v44
	v_cvt_f32_i32_e32 v44, v44
	v_mul_f32_e32 v44, v228, v44
	v_cvt_pk_bf16_f32 v178, v38, v40
	v_cvt_pk_bf16_f32 v179, v42, v44
	v_add_u32_e32 v147, 8, v140
	v_and_b32_e32 v146, 15, v147
	v_xor_b32_e32 v146, 8, v146
	v_bfe_u32 v148, v147, 4, 4
	v_mul_lo_u32 v146, v146, s92
	v_mul_lo_u32 v148, v148, s92
	v_mov_b32_e32 v147, v146
	v_mov_b32_e32 v149, v148
	ds_write2st64_b64 v77, v[146:147], v[148:149] offset1:2
	v_add_u32_e32 v138, 0x1800, v74
	ds_read_u8 v139, v138
	v_add_u32_e32 v141, 0x1800, v73
	ds_read_u8 v140, v141
	s_add_i32 s43, s67, 224
	v_mov_b32_e32 v138, s43
	ds_read2st64_b32 v[228:229], v138 offset1:1
	ds_read_b128 v[18:21], v227 offset:12288
	ds_read_b128 v[22:25], v227 offset:12304
	v_add_u32_e32 v152, 0x200000, v63
	v_add_u32_e32 v153, 0x200000, v64
	v_mov_b32_e32 v38, 0
	v_mov_b32_e32 v39, 0
	v_mov_b32_e32 v40, 0
	v_mov_b32_e32 v41, 0
	v_mov_b32_e32 v42, 0
	v_mov_b32_e32 v43, 0
	v_mov_b32_e32 v44, 0
	v_mov_b32_e32 v45, 0
	v_and_b32_e32 v78, 0xffff, v31
	v_lshrrev_b32_e32 v79, 16, v31
	v_lshl_add_u32 v78, v78, 7, v150
	v_lshl_add_u32 v79, v79, 7, v151
	s_mov_b32 m0, s77
	s_add_i32 s43, s77, 0x400
	global_load_lds_dwordx4 v78, s[50:51]
	s_mov_b32 m0, s43
	s_nop 0
	global_load_lds_dwordx4 v79, s[50:51]
	s_waitcnt vmcnt(8)
	v_add_u32_e32 v54, s79, v59
	v_add_u32_e32 v55, s79, v60
	v_add_u32_e32 v56, s79, v61
	v_add_u32_e32 v57, s79, v62
	ds_read_b64_tr_b4 v[50:51], v160 offset:128
	ds_read_b64_tr_b4 v[52:53], v160 offset:1152
	ds_read_b64_tr_b4 v[130:131], v54
	ds_read_b64_tr_b4 v[132:133], v55
	ds_read_b64_tr_b4 v[134:135], v56
	ds_read_b64_tr_b4 v[136:137], v57
	s_waitcnt lgkmcnt(12)
	s_waitcnt vmcnt(35) lgkmcnt(15)
	v_lshlrev_b32_e32 v210, 16, v194
	v_and_b32_e32 v211, 0xffff0000, v194
	v_lshlrev_b32_e32 v142, 16, v202
	v_and_b32_e32 v143, 0xffff0000, v202
	v_add_f32_e32 v210, v210, v142
	v_add_f32_e32 v211, v211, v143
	v_lshlrev_b32_e32 v212, 16, v195
	v_and_b32_e32 v213, 0xffff0000, v195
	v_lshlrev_b32_e32 v142, 16, v203
	v_and_b32_e32 v143, 0xffff0000, v203
	v_add_f32_e32 v212, v212, v142
	v_add_f32_e32 v213, v213, v143
	v_lshlrev_b32_e32 v214, 16, v196
	v_and_b32_e32 v215, 0xffff0000, v196
	v_lshlrev_b32_e32 v142, 16, v204
	v_and_b32_e32 v143, 0xffff0000, v204
	v_add_f32_e32 v214, v214, v142
	v_add_f32_e32 v215, v215, v143
	v_lshlrev_b32_e32 v216, 16, v197
	v_and_b32_e32 v217, 0xffff0000, v197
	v_lshlrev_b32_e32 v142, 16, v205
	v_and_b32_e32 v143, 0xffff0000, v205
	v_add_f32_e32 v216, v216, v142
	v_add_f32_e32 v217, v217, v143
	v_lshlrev_b32_e32 v218, 16, v198
	v_and_b32_e32 v219, 0xffff0000, v198
	v_lshlrev_b32_e32 v142, 16, v206
	v_and_b32_e32 v143, 0xffff0000, v206
	v_add_f32_e32 v218, v218, v142
	v_add_f32_e32 v219, v219, v143
	v_lshlrev_b32_e32 v220, 16, v199
	v_and_b32_e32 v221, 0xffff0000, v199
	v_lshlrev_b32_e32 v142, 16, v207
	v_and_b32_e32 v143, 0xffff0000, v207
	v_add_f32_e32 v220, v220, v142
	v_add_f32_e32 v221, v221, v143
	v_lshlrev_b32_e32 v222, 16, v200
	v_and_b32_e32 v223, 0xffff0000, v200
	v_lshlrev_b32_e32 v142, 16, v208
	v_and_b32_e32 v143, 0xffff0000, v208
	v_add_f32_e32 v222, v222, v142
	v_add_f32_e32 v223, v223, v143
	v_lshlrev_b32_e32 v224, 16, v201
	v_and_b32_e32 v225, 0xffff0000, v201
	v_lshlrev_b32_e32 v142, 16, v209
	v_and_b32_e32 v143, 0xffff0000, v209
	v_add_f32_e32 v224, v224, v142
; #define TR4(p_) __builtin_amdgcn_ds_read_tr4_b64_v2i32((LAS v2i*)(p_))
; #define VDMA(st_, k_) do { _Pragma("unroll") for (int i_ = 0; i_ < 4; ++i_) { \
;         const unsigned off_ = (unsigned)((st_) >> 2) * (16384u * 128u) + (PE_ID(E, 4 * ((st_) & 3) + i_) << 7) + ((i_ & 1) ? cx1 : cx0); \
;         __builtin_amdgcn_global_load_lds((const unsigned*)(V4 + off_), (LAS unsigned*)(ldsb + BUF[k_] + 1024 * i_), 16, 0, 0); } } while (0)
; __device__ __forceinline__ void peer_v_tokens(int j, const LAS unsigned short* EL, const LAS unsigned char* AL  , const LAS float* ASC  , const LAS int* SAL  , ...
;     ...
; #pragma unroll
;         for (int st = 0; st < 16; ++st) {
;             const int p = st >> 2, q = st & 3;
;             if (st < 14) VDMA(st + 2, (st + 2) % 3);
;             if (st < 14) asm volatile("s_waitcnt vmcnt(8)" ::: "memory");
;             else if (st == 14) asm volatile("s_waitcnt vmcnt(4)" ::: "memory");
;             else asm volatile("s_waitcnt vmcnt(0)" ::: "memory");
;             if (q == 0) {
; #pragma unroll
;                 for (int r = 0; r < 4; ++r) { accH[r] = 0; accL[r] = 0; } }
; #pragma unroll
;             for (int tp = 0; tp < 2; ++tp) {
;                 const v2i ao = TR4(ATL + (2 * q + tp) * 128 + 8 * s16), ah = TR4(ATL + 1024 + (2 * q + tp) * 128 + 8 * s16);
; #pragma unroll
;                 for (int r = 0; r < 4; ++r) {
;                     const v2i d = TR4(ldsb + BUF[st % 3] + 2048 * tp + roff[r]);
;                     accH[r] = __builtin_amdgcn_sdot8(d.x, ah.x, accH[r], false); accH[r] = __builtin_amdgcn_sdot8(d.y, ah.y, accH[r], false);
;                     accL[r] = __builtin_amdgcn_sdot8(d.x, ao.x, accL[r], false); accL[r] = __builtin_amdgcn_sdot8(d.y, ao.y, accL[r], false);
;                 }
;             }
;             asm volatile("s_waitcnt lgkmcnt(0)" ::: "memory");
;     ...
;                 v[jq] = make_float4(__uint_as_float(hw.x << 16) + __uint_as_float(pw.x << 16), __uint_as_float(hw.x & 0xffff0000u) + __uint_as_float(pw.x & 0xffff0000u),
;                                     __uint_as_float(hw.y << 16) + __uint_as_float(pw.y << 16), __uint_as_float(hw.y & 0xffff0000u) + __uint_as_float(pw.y & 0xffff0000u));
;                 ss += v[jq].x * v[jq].x + v[jq].y * v[jq].y + v[jq].z * v[jq].z + v[jq].w * v[jq].w; }
;             ss = wave_sum(ss);
;             const float r3 = rsqrtf(ss * (1.f / D) + EPS);
	v_add_f32_e32 v225, v225, v143
	v_mov_b32_e32 v144, 0
	v_mul_f32_e32 v145, v210, v210
	v_fmac_f32_e32 v145, v211, v211
	v_fmac_f32_e32 v145, v212, v212
	v_fmac_f32_e32 v145, v213, v213
	v_add_f32_e32 v144, v144, v145
	v_mul_f32_e32 v145, v214, v214
	v_fmac_f32_e32 v145, v215, v215
	v_fmac_f32_e32 v145, v216, v216
	v_fmac_f32_e32 v145, v217, v217
	v_add_f32_e32 v144, v144, v145
	v_mul_f32_e32 v145, v218, v218
	v_fmac_f32_e32 v145, v219, v219
	v_fmac_f32_e32 v145, v220, v220
	v_fmac_f32_e32 v145, v221, v221
	v_add_f32_e32 v144, v144, v145
	v_mul_f32_e32 v145, v222, v222
	v_fmac_f32_e32 v145, v223, v223
	v_fmac_f32_e32 v145, v224, v224
	v_fmac_f32_e32 v145, v225, v225
	v_add_f32_e32 v144, v144, v145
	s_nop 1
	v_add_f32_dpp v144, v144, v144 quad_perm:[1,0,3,2] row_mask:0xf bank_mask:0xf bound_ctrl:1
	s_nop 1
	v_add_f32_dpp v144, v144, v144 quad_perm:[2,3,0,1] row_mask:0xf bank_mask:0xf bound_ctrl:1
	s_nop 1
	v_add_f32_dpp v144, v144, v144 row_half_mirror row_mask:0xf bank_mask:0xf bound_ctrl:1
	s_nop 1
	v_add_f32_dpp v144, v144, v144 row_mirror row_mask:0xf bank_mask:0xf bound_ctrl:1
	s_nop 1
	v_readlane_b32 s10, v144, 0
	v_readlane_b32 s11, v144, 16
	v_readlane_b32 s14, v144, 32
	v_readlane_b32 s15, v144, 48
	s_nop 3
	v_mov_b32_e32 v144, s11
	v_mov_b32_e32 v145, s15
	v_add_f32_e32 v144, s10, v144
	v_add_f32_e32 v145, s14, v145
	v_add_f32_e32 v144, v144, v145
	v_fmamk_f32 v144, v144, 0x3a800000, v111
	v_rsq_f32_e32 v144, v144
	s_nop 0
	v_mul_f32_e32 v210, v210, v144
	v_mul_f32_e32 v211, v211, v144
	v_mul_f32_e32 v212, v212, v144
	v_mul_f32_e32 v213, v213, v144
	v_mul_f32_e32 v214, v214, v144
	v_mul_f32_e32 v215, v215, v144
	v_mul_f32_e32 v216, v216, v144
	v_mul_f32_e32 v217, v217, v144
	v_mul_f32_e32 v218, v218, v144
	v_mul_f32_e32 v219, v219, v144
	v_mul_f32_e32 v220, v220, v144
	v_mul_f32_e32 v221, v221, v144
	v_mul_f32_e32 v222, v222, v144
	v_mul_f32_e32 v223, v223, v144
	v_mul_f32_e32 v224, v224, v144
	v_mul_f32_e32 v225, v225, v144
	v_dot8c_i32_i4_e32 v38, v122, v48
	v_dot8c_i32_i4_e32 v39, v122, v46
	v_dot8c_i32_i4_e32 v40, v124, v48
	v_dot8c_i32_i4_e32 v41, v124, v46
	v_dot8c_i32_i4_e32 v42, v126, v48
	v_dot8c_i32_i4_e32 v43, v126, v46
	v_dot8c_i32_i4_e32 v44, v128, v48
	v_dot8c_i32_i4_e32 v45, v128, v46
	v_dot8c_i32_i4_e32 v38, v123, v49
	v_dot8c_i32_i4_e32 v39, v123, v47
	v_dot8c_i32_i4_e32 v40, v125, v49
	v_dot8c_i32_i4_e32 v41, v125, v47
	v_dot8c_i32_i4_e32 v42, v127, v49
	v_dot8c_i32_i4_e32 v43, v127, v47
	v_dot8c_i32_i4_e32 v44, v129, v49
	v_dot8c_i32_i4_e32 v45, v129, v47
	v_and_b32_e32 v78, 0xffff, v32
	v_lshrrev_b32_e32 v79, 16, v32
	v_lshl_add_u32 v78, v78, 7, v150
	v_lshl_add_u32 v79, v79, 7, v151
	s_mov_b32 m0, s78
	s_add_i32 s43, s78, 0x400
	global_load_lds_dwordx4 v78, s[50:51]
	s_mov_b32 m0, s43
	s_nop 0
	global_load_lds_dwordx4 v79, s[50:51]
	s_waitcnt vmcnt(8)
	v_add_u32_e32 v54, s98, v59
	v_add_u32_e32 v55, s98, v60
	v_add_u32_e32 v56, s98, v61
	v_add_u32_e32 v57, s98, v62
	ds_read_b64_tr_b4 v[46:47], v160 offset:256
	ds_read_b64_tr_b4 v[48:49], v160 offset:1280
	ds_read_b64_tr_b4 v[122:123], v54
	ds_read_b64_tr_b4 v[124:125], v55
	ds_read_b64_tr_b4 v[126:127], v56
	ds_read_b64_tr_b4 v[128:129], v57
	s_waitcnt lgkmcnt(6)
	v_dot8c_i32_i4_e32 v38, v130, v52
	v_dot8c_i32_i4_e32 v39, v130, v50
	v_dot8c_i32_i4_e32 v40, v132, v52
	v_dot8c_i32_i4_e32 v41, v132, v50
	v_dot8c_i32_i4_e32 v42, v134, v52
	v_dot8c_i32_i4_e32 v43, v134, v50
	v_dot8c_i32_i4_e32 v44, v136, v52
	v_dot8c_i32_i4_e32 v45, v136, v50
	v_dot8c_i32_i4_e32 v38, v131, v53
	v_dot8c_i32_i4_e32 v39, v131, v51
	v_dot8c_i32_i4_e32 v40, v133, v53
	v_dot8c_i32_i4_e32 v41, v133, v51
	v_dot8c_i32_i4_e32 v42, v135, v53
	v_dot8c_i32_i4_e32 v43, v135, v51
	v_dot8c_i32_i4_e32 v44, v137, v53
	v_dot8c_i32_i4_e32 v45, v137, v51
	v_and_b32_e32 v78, 0xffff, v33
	v_lshrrev_b32_e32 v79, 16, v33
	v_lshl_add_u32 v78, v78, 7, v150
	v_lshl_add_u32 v79, v79, 7, v151
	s_mov_b32 m0, s79
	s_add_i32 s43, s79, 0x400
	global_load_lds_dwordx4 v78, s[50:51]
	s_mov_b32 m0, s43
	s_nop 0
	global_load_lds_dwordx4 v79, s[50:51]
	s_waitcnt vmcnt(8)
	v_add_u32_e32 v54, s99, v59
	v_add_u32_e32 v55, s99, v60
	v_add_u32_e32 v56, s99, v61
	v_add_u32_e32 v57, s99, v62
	ds_read_b64_tr_b4 v[50:51], v160 offset:384
	ds_read_b64_tr_b4 v[52:53], v160 offset:1408
	ds_read_b64_tr_b4 v[130:131], v54
	ds_read_b64_tr_b4 v[132:133], v55
	ds_read_b64_tr_b4 v[134:135], v56
	ds_read_b64_tr_b4 v[136:137], v57
	s_waitcnt lgkmcnt(6)
	v_dot8c_i32_i4_e32 v38, v122, v48
	v_dot8c_i32_i4_e32 v39, v122, v46
	v_dot8c_i32_i4_e32 v40, v124, v48
	v_dot8c_i32_i4_e32 v41, v124, v46
	v_dot8c_i32_i4_e32 v42, v126, v48
	v_dot8c_i32_i4_e32 v43, v126, v46
	v_dot8c_i32_i4_e32 v44, v128, v48
	v_dot8c_i32_i4_e32 v45, v128, v46
	v_dot8c_i32_i4_e32 v38, v123, v49
	v_dot8c_i32_i4_e32 v39, v123, v47
	v_dot8c_i32_i4_e32 v40, v125, v49
	v_dot8c_i32_i4_e32 v41, v125, v47
	v_dot8c_i32_i4_e32 v42, v127, v49
	v_dot8c_i32_i4_e32 v43, v127, v47
	v_dot8c_i32_i4_e32 v44, v129, v49
	v_dot8c_i32_i4_e32 v45, v129, v47
	s_waitcnt lgkmcnt(15)
	v_and_b32_e32 v78, 0xffff, v18
	v_lshrrev_b32_e32 v79, 16, v18
	v_lshl_add_u32 v78, v78, 7, v152
	v_lshl_add_u32 v79, v79, 7, v153
	s_mov_b32 m0, s98
	s_add_i32 s43, s98, 0x400
	global_load_lds_dwordx4 v78, s[50:51]
	s_mov_b32 m0, s43
	s_nop 0
	global_load_lds_dwordx4 v79, s[50:51]
	s_waitcnt vmcnt(8)
	v_add_u32_e32 v54, s76, v59
	v_add_u32_e32 v55, s76, v60
	v_add_u32_e32 v56, s76, v61
	v_add_u32_e32 v57, s76, v62
	ds_read_b64_tr_b4 v[46:47], v160 offset:512
	ds_read_b64_tr_b4 v[48:49], v160 offset:1536
	ds_read_b64_tr_b4 v[122:123], v54
	ds_read_b64_tr_b4 v[124:125], v55
	ds_read_b64_tr_b4 v[126:127], v56
	ds_read_b64_tr_b4 v[128:129], v57
	s_waitcnt lgkmcnt(6)
; #define LAS __attribute__((address_space(3)))
; #define TR4(p_) __builtin_amdgcn_ds_read_tr4_b64_v2i32((LAS v2i*)(p_))
; __device__ __forceinline__ void peer_v_tokens(int j, const LAS unsigned short* EL, const LAS unsigned char* AL  , const LAS float* ASC  , const LAS int* SAL  , ...
;     ...
;         for (int m = 0; m < 2; ++m) {
;             const int idx = lane + 64 * m, tau = idx >> 4, sr = idx & 15, k = 16 * (sr & 7) + 2 * tau + (sr >> 3);
;             const int aq = (int)*(const LAS signed char*)(AL + tl * 128 + k); const int tq = aq + 8;
;             const unsigned lo = (((unsigned)tq & 15u) ^ 8u) * 0x11111111u, hi = ((unsigned)(tq >> 4) & 15u) * 0x11111111u;
;             typedef unsigned u2v __attribute__((ext_vector_type(2)));
;             u2v l2; l2.x = lo; l2.y = lo; u2v h2; h2.x = hi; h2.y = hi;
;             *(LAS u2v*)(ATL + 8 * idx) = l2; *(LAS u2v*)(ATL + 1024 + 8 * idx) = h2;
;         }
;     ...
; #pragma unroll
;         for (int st = 0; st < 16; ++st) {
;             const int p = st >> 2, q = st & 3;
;             if (st < 14) VDMA(st + 2, (st + 2) % 3);
;             if (st < 14) asm volatile("s_waitcnt vmcnt(8)" ::: "memory");
;             else if (st == 14) asm volatile("s_waitcnt vmcnt(4)" ::: "memory");
;             else asm volatile("s_waitcnt vmcnt(0)" ::: "memory");
;             if (q == 0) {
; #pragma unroll
;                 for (int r = 0; r < 4; ++r) { accH[r] = 0; accL[r] = 0; } }
; #pragma unroll
;             for (int tp = 0; tp < 2; ++tp) {
;                 const v2i ao = TR4(ATL + (2 * q + tp) * 128 + 8 * s16), ah = TR4(ATL + 1024 + (2 * q + tp) * 128 + 8 * s16);
; #pragma unroll
;                 for (int r = 0; r < 4; ++r) {
;                     const v2i d = TR4(ldsb + BUF[st % 3] + 2048 * tp + roff[r]);
;                     accH[r] = __builtin_amdgcn_sdot8(d.x, ah.x, accH[r], false); accH[r] = __builtin_amdgcn_sdot8(d.y, ah.y, accH[r], false);
;                     accL[r] = __builtin_amdgcn_sdot8(d.x, ao.x, accL[r], false); accL[r] = __builtin_amdgcn_sdot8(d.y, ao.y, accL[r], false);
;                 }
;             }
;             asm volatile("s_waitcnt lgkmcnt(0)" ::: "memory");
	v_dot8c_i32_i4_e32 v38, v130, v52
	v_dot8c_i32_i4_e32 v39, v130, v50
	v_dot8c_i32_i4_e32 v40, v132, v52
	v_dot8c_i32_i4_e32 v41, v132, v50
	v_dot8c_i32_i4_e32 v42, v134, v52
	v_dot8c_i32_i4_e32 v43, v134, v50
	v_dot8c_i32_i4_e32 v44, v136, v52
	v_dot8c_i32_i4_e32 v45, v136, v50
	v_dot8c_i32_i4_e32 v38, v131, v53
	v_dot8c_i32_i4_e32 v39, v131, v51
	v_dot8c_i32_i4_e32 v40, v133, v53
	v_dot8c_i32_i4_e32 v41, v133, v51
	v_dot8c_i32_i4_e32 v42, v135, v53
	v_dot8c_i32_i4_e32 v43, v135, v51
	v_dot8c_i32_i4_e32 v44, v137, v53
	v_dot8c_i32_i4_e32 v45, v137, v51
	v_and_b32_e32 v78, 0xffff, v19
	v_lshrrev_b32_e32 v79, 16, v19
	v_lshl_add_u32 v78, v78, 7, v152
	v_lshl_add_u32 v79, v79, 7, v153
	s_mov_b32 m0, s99
	s_add_i32 s43, s99, 0x400
	global_load_lds_dwordx4 v78, s[50:51]
	s_mov_b32 m0, s43
	s_nop 0
	global_load_lds_dwordx4 v79, s[50:51]
	s_waitcnt vmcnt(8)
	v_add_u32_e32 v54, s77, v59
	v_add_u32_e32 v55, s77, v60
	v_add_u32_e32 v56, s77, v61
	v_add_u32_e32 v57, s77, v62
	ds_read_b64_tr_b4 v[50:51], v160 offset:640
	ds_read_b64_tr_b4 v[52:53], v160 offset:1664
	ds_read_b64_tr_b4 v[130:131], v54
	ds_read_b64_tr_b4 v[132:133], v55
	ds_read_b64_tr_b4 v[134:135], v56
	ds_read_b64_tr_b4 v[136:137], v57
	s_waitcnt lgkmcnt(6)
	v_dot8c_i32_i4_e32 v38, v122, v48
	v_dot8c_i32_i4_e32 v39, v122, v46
	v_dot8c_i32_i4_e32 v40, v124, v48
	v_dot8c_i32_i4_e32 v41, v124, v46
	v_dot8c_i32_i4_e32 v42, v126, v48
	v_dot8c_i32_i4_e32 v43, v126, v46
	v_dot8c_i32_i4_e32 v44, v128, v48
	v_dot8c_i32_i4_e32 v45, v128, v46
	v_dot8c_i32_i4_e32 v38, v123, v49
	v_dot8c_i32_i4_e32 v39, v123, v47
	v_dot8c_i32_i4_e32 v40, v125, v49
	v_dot8c_i32_i4_e32 v41, v125, v47
	v_dot8c_i32_i4_e32 v42, v127, v49
	v_dot8c_i32_i4_e32 v43, v127, v47
	v_dot8c_i32_i4_e32 v44, v129, v49
	v_dot8c_i32_i4_e32 v45, v129, v47
	s_waitcnt lgkmcnt(15)
	v_add_u32_e32 v143, 8, v139
	v_and_b32_e32 v142, 15, v143
	v_xor_b32_e32 v142, 8, v142
	v_bfe_u32 v144, v143, 4, 4
	v_mul_lo_u32 v142, v142, s92
	v_mul_lo_u32 v144, v144, s92
	v_mov_b32_e32 v143, v142
	v_mov_b32_e32 v145, v144
	ds_write2st64_b64 v159, v[142:143], v[144:145] offset1:2
	v_and_b32_e32 v78, 0xffff, v20
	v_lshrrev_b32_e32 v79, 16, v20
	v_lshl_add_u32 v78, v78, 7, v152
	v_lshl_add_u32 v79, v79, 7, v153
	s_mov_b32 m0, s76
	s_add_i32 s43, s76, 0x400
	global_load_lds_dwordx4 v78, s[50:51]
	s_mov_b32 m0, s43
	s_nop 0
	global_load_lds_dwordx4 v79, s[50:51]
	s_waitcnt vmcnt(8)
	v_add_u32_e32 v54, s78, v59
	v_add_u32_e32 v55, s78, v60
	v_add_u32_e32 v56, s78, v61
	v_add_u32_e32 v57, s78, v62
	ds_read_b64_tr_b4 v[46:47], v160 offset:768
	ds_read_b64_tr_b4 v[48:49], v160 offset:1792
	ds_read_b64_tr_b4 v[122:123], v54
	ds_read_b64_tr_b4 v[124:125], v55
	ds_read_b64_tr_b4 v[126:127], v56
	ds_read_b64_tr_b4 v[128:129], v57
	s_waitcnt lgkmcnt(7)
	v_dot8c_i32_i4_e32 v38, v130, v52
	v_dot8c_i32_i4_e32 v39, v130, v50
	v_dot8c_i32_i4_e32 v40, v132, v52
	v_dot8c_i32_i4_e32 v41, v132, v50
	v_dot8c_i32_i4_e32 v42, v134, v52
	v_dot8c_i32_i4_e32 v43, v134, v50
	v_dot8c_i32_i4_e32 v44, v136, v52
	v_dot8c_i32_i4_e32 v45, v136, v50
	v_dot8c_i32_i4_e32 v38, v131, v53
	v_dot8c_i32_i4_e32 v39, v131, v51
	v_dot8c_i32_i4_e32 v40, v133, v53
	v_dot8c_i32_i4_e32 v41, v133, v51
	v_dot8c_i32_i4_e32 v42, v135, v53
	v_dot8c_i32_i4_e32 v43, v135, v51
	v_dot8c_i32_i4_e32 v44, v137, v53
	v_dot8c_i32_i4_e32 v45, v137, v51
	v_and_b32_e32 v78, 0xffff, v21
	v_lshrrev_b32_e32 v79, 16, v21
	v_lshl_add_u32 v78, v78, 7, v152
	v_lshl_add_u32 v79, v79, 7, v153
	s_mov_b32 m0, s77
	s_add_i32 s43, s77, 0x400
	global_load_lds_dwordx4 v78, s[50:51]
	s_mov_b32 m0, s43
	s_nop 0
	global_load_lds_dwordx4 v79, s[50:51]
	s_waitcnt vmcnt(8)
	v_add_u32_e32 v54, s79, v59
	v_add_u32_e32 v55, s79, v60
	v_add_u32_e32 v56, s79, v61
	v_add_u32_e32 v57, s79, v62
	ds_read_b64_tr_b4 v[50:51], v160 offset:896
	ds_read_b64_tr_b4 v[52:53], v160 offset:1920
	ds_read_b64_tr_b4 v[130:131], v54
	ds_read_b64_tr_b4 v[132:133], v55
	ds_read_b64_tr_b4 v[134:135], v56
	ds_read_b64_tr_b4 v[136:137], v57
	s_waitcnt lgkmcnt(6)
	v_dot8c_i32_i4_e32 v38, v122, v48
	v_dot8c_i32_i4_e32 v39, v122, v46
	v_dot8c_i32_i4_e32 v40, v124, v48
	v_dot8c_i32_i4_e32 v41, v124, v46
	v_dot8c_i32_i4_e32 v42, v126, v48
	v_dot8c_i32_i4_e32 v43, v126, v46
	v_dot8c_i32_i4_e32 v44, v128, v48
	v_dot8c_i32_i4_e32 v45, v128, v46
	v_dot8c_i32_i4_e32 v38, v123, v49
	v_dot8c_i32_i4_e32 v39, v123, v47
	v_dot8c_i32_i4_e32 v40, v125, v49
	v_dot8c_i32_i4_e32 v41, v125, v47
	v_dot8c_i32_i4_e32 v42, v127, v49
	v_dot8c_i32_i4_e32 v43, v127, v47
	v_dot8c_i32_i4_e32 v44, v129, v49
	v_dot8c_i32_i4_e32 v45, v129, v47
	v_and_b32_e32 v78, 0xffff, v22
	v_lshrrev_b32_e32 v79, 16, v22
	v_lshl_add_u32 v78, v78, 7, v152
	v_lshl_add_u32 v79, v79, 7, v153
	s_mov_b32 m0, s78
	s_add_i32 s43, s78, 0x400
	global_load_lds_dwordx4 v78, s[50:51]
	s_mov_b32 m0, s43
	s_nop 0
	global_load_lds_dwordx4 v79, s[50:51]
	s_waitcnt vmcnt(8)
	v_add_u32_e32 v54, s98, v59
	v_add_u32_e32 v55, s98, v60
	v_add_u32_e32 v56, s98, v61
	v_add_u32_e32 v57, s98, v62
	ds_read_b64_tr_b4 v[46:47], v160
	ds_read_b64_tr_b4 v[48:49], v160 offset:1024
	ds_read_b64_tr_b4 v[122:123], v54
	ds_read_b64_tr_b4 v[124:125], v55
	ds_read_b64_tr_b4 v[126:127], v56
	ds_read_b64_tr_b4 v[128:129], v57
	s_waitcnt lgkmcnt(6)
	v_dot8c_i32_i4_e32 v38, v130, v52
	v_dot8c_i32_i4_e32 v39, v130, v50
	v_dot8c_i32_i4_e32 v40, v132, v52
	v_dot8c_i32_i4_e32 v41, v132, v50
	v_dot8c_i32_i4_e32 v42, v134, v52
	v_dot8c_i32_i4_e32 v43, v134, v50
	v_dot8c_i32_i4_e32 v44, v136, v52
	v_dot8c_i32_i4_e32 v45, v136, v50
	v_dot8c_i32_i4_e32 v38, v131, v53
	v_dot8c_i32_i4_e32 v39, v131, v51
	v_dot8c_i32_i4_e32 v40, v133, v53
	v_dot8c_i32_i4_e32 v41, v133, v51
	v_dot8c_i32_i4_e32 v42, v135, v53
	v_dot8c_i32_i4_e32 v43, v135, v51
	v_dot8c_i32_i4_e32 v44, v137, v53
	v_dot8c_i32_i4_e32 v45, v137, v51
	s_nop 3
	s_waitcnt lgkmcnt(15)
; __device__ __forceinline__ void peer_v_tokens(int j, const LAS unsigned short* EL, const LAS unsigned char* AL  , const LAS float* ASC  , const LAS int* SAL  , ...
;     ...
;         const int tl = it * 8 + wave, t = j * 64 + tl;
;         unsigned E[8];
;         { const LAS v4u* ep = (const LAS v4u*)(EL + tl * 128 + 16 * g); const v4u e0 = ep[0], e1 = ep[1];
;           E[0] = e0.x; E[1] = e0.y; E[2] = e0.z; E[3] = e0.w; E[4] = e1.x; E[5] = e1.y; E[6] = e1.z; E[7] = e1.w; }
;     ...
;         { unsigned ho = (unsigned)t * (D / 4) + (unsigned)lane; asm volatile("" : "+v"(ho)); const uint2* hp = (const uint2*)HB + ho; const float4* gp = (const float4*)fng + lane;
; #pragma unroll
;           for (int jq = 0; jq < 4; ++jq) { hv[jq] = hp[64 * jq]; gv[jq] = gp[64 * jq]; } }
;     ...
;         for (int m = 0; m < 2; ++m) {
;             const int idx = lane + 64 * m, tau = idx >> 4, sr = idx & 15, k = 16 * (sr & 7) + 2 * tau + (sr >> 3);
;             const int aq = (int)*(const LAS signed char*)(AL + tl * 128 + k); const int tq = aq + 8;
;             const unsigned lo = (((unsigned)tq & 15u) ^ 8u) * 0x11111111u, hi = ((unsigned)(tq >> 4) & 15u) * 0x11111111u;
;             typedef unsigned u2v __attribute__((ext_vector_type(2)));
;             u2v l2; l2.x = lo; l2.y = lo; u2v h2; h2.x = hi; h2.y = hi;
;             *(LAS u2v*)(ATL + 8 * idx) = l2; *(LAS u2v*)(ATL + 1024 + 8 * idx) = h2;
;         }
;     ...
; #pragma unroll
;         for (int st = 0; st < 16; ++st) {
;             const int p = st >> 2, q = st & 3;
;             if (st < 14) VDMA(st + 2, (st + 2) % 3);
;             if (st < 14) asm volatile("s_waitcnt vmcnt(8)" ::: "memory");
;             else if (st == 14) asm volatile("s_waitcnt vmcnt(4)" ::: "memory");
;             else asm volatile("s_waitcnt vmcnt(0)" ::: "memory");
;             if (q == 0) {
; #pragma unroll
;                 for (int r = 0; r < 4; ++r) { accH[r] = 0; accL[r] = 0; } }
; #pragma unroll
;     ...
;                 for (int r = 0; r < 4; ++r) STASH[256 * p + 16 * (grp + 4 * r) + pc] = f2bf(asc * (float)(2 * ((accH[r] << 4) + accL[r]) + sa));
;     ...
;             for (int jq = 0; jq < 4; ++jq) { typedef float f4v __attribute__((ext_vector_type(4))); f4v o4; o4.x = v[jq].x * r3 * gv[jq].x; o4.y = v[jq].y * r3 * gv[jq].y; o4.z = v[jq].z * r3 * gv[jq].z; o4.w = v[jq].w * r3 * gv[jq].w;
;                 __builtin_nontemporal_store(o4, (f4v*)op + 64 * jq); }
	v_lshlrev_b32_e32 v38, 5, v38
	v_lshlrev_b32_e32 v39, 1, v39
	v_add3_u32 v38, v39, v229, v38
	v_cvt_f32_i32_e32 v38, v38
	v_mul_f32_e32 v38, v228, v38
	v_lshlrev_b32_e32 v40, 5, v40
	v_lshlrev_b32_e32 v41, 1, v41
	v_add3_u32 v40, v41, v229, v40
	v_cvt_f32_i32_e32 v40, v40
	v_mul_f32_e32 v40, v228, v40
	v_lshlrev_b32_e32 v42, 5, v42
	v_lshlrev_b32_e32 v43, 1, v43
	v_add3_u32 v42, v43, v229, v42
	v_cvt_f32_i32_e32 v42, v42
	v_mul_f32_e32 v42, v228, v42
	v_lshlrev_b32_e32 v44, 5, v44
	v_lshlrev_b32_e32 v45, 1, v45
	v_add3_u32 v44, v45, v229, v44
	v_cvt_f32_i32_e32 v44, v44
	v_mul_f32_e32 v44, v228, v44
	v_cvt_pk_bf16_f32 v186, v38, v40
	v_cvt_pk_bf16_f32 v187, v42, v44
	ds_read_b128 v[252:255], v155
	s_add_i32 s44, s40, 32
	s_ashr_i32 s45, s44, 31
	s_lshl_b64 s[44:45], s[44:45], 12
	v_lshl_add_u64 v[80:81], v[36:37], 0, s[44:45]
	s_waitcnt lgkmcnt(0)
	v_mul_f32_e32 v210, v210, v252
	v_mul_f32_e32 v211, v211, v253
	v_mul_f32_e32 v212, v212, v254
	v_mul_f32_e32 v213, v213, v255
	global_store_dwordx4 v[80:81], v[210:213], off nt
	s_add_i32 s43, s40, 40
	s_lshl_b32 s43, s43, 11
	v_add_u32_e32 v138, s43, v66
	global_load_dwordx2 v[194:195], v138, s[70:71]
	global_load_dwordx2 v[196:197], v138, s[70:71] offset:512
	global_load_dwordx2 v[198:199], v138, s[70:71] offset:1024
	global_load_dwordx2 v[200:201], v138, s[70:71] offset:1536
	v_add_u32_e32 v147, 8, v140
	v_and_b32_e32 v146, 15, v147
	v_xor_b32_e32 v146, 8, v146
	v_bfe_u32 v148, v147, 4, 4
	v_mul_lo_u32 v146, v146, s92
	v_mul_lo_u32 v148, v148, s92
	v_mov_b32_e32 v147, v146
	v_mov_b32_e32 v149, v148
	ds_write2st64_b64 v77, v[146:147], v[148:149] offset1:2
	v_add_u32_e32 v138, 0x1c00, v74
	ds_read_u8 v139, v138
	v_add_u32_e32 v141, 0x1c00, v73
	ds_read_u8 v140, v141
	s_add_i32 s43, s67, 192
	v_mov_b32_e32 v138, s43
	ds_read2st64_b32 v[228:229], v138 offset1:1
	ds_read_b128 v[26:29], v227 offset:14336
	ds_read_b128 v[30:33], v227 offset:14352
	v_mov_b32_e32 v38, 0
	v_mov_b32_e32 v39, 0
	v_mov_b32_e32 v40, 0
	v_mov_b32_e32 v41, 0
	v_mov_b32_e32 v42, 0
	v_mov_b32_e32 v43, 0
	v_mov_b32_e32 v44, 0
	v_mov_b32_e32 v45, 0
	v_and_b32_e32 v78, 0xffff, v23
	v_lshrrev_b32_e32 v79, 16, v23
	v_lshl_add_u32 v78, v78, 7, v152
	v_lshl_add_u32 v79, v79, 7, v153
	s_mov_b32 m0, s79
	s_add_i32 s43, s79, 0x400
	global_load_lds_dwordx4 v78, s[50:51]
	s_mov_b32 m0, s43
	s_nop 0
	global_load_lds_dwordx4 v79, s[50:51]
	s_waitcnt vmcnt(13)
	v_add_u32_e32 v54, s99, v59
	v_add_u32_e32 v55, s99, v60
	v_add_u32_e32 v56, s99, v61
	v_add_u32_e32 v57, s99, v62
	ds_read_b64_tr_b4 v[50:51], v160 offset:128
	ds_read_b64_tr_b4 v[52:53], v160 offset:1152
	ds_read_b64_tr_b4 v[130:131], v54
	ds_read_b64_tr_b4 v[132:133], v55
	ds_read_b64_tr_b4 v[134:135], v56
	ds_read_b64_tr_b4 v[136:137], v57
	s_waitcnt lgkmcnt(13)
	v_dot8c_i32_i4_e32 v38, v122, v48
	v_dot8c_i32_i4_e32 v39, v122, v46
	v_dot8c_i32_i4_e32 v40, v124, v48
	v_dot8c_i32_i4_e32 v41, v124, v46
	v_dot8c_i32_i4_e32 v42, v126, v48
	v_dot8c_i32_i4_e32 v43, v126, v46
	v_dot8c_i32_i4_e32 v44, v128, v48
	v_dot8c_i32_i4_e32 v45, v128, v46
	v_dot8c_i32_i4_e32 v38, v123, v49
	v_dot8c_i32_i4_e32 v39, v123, v47
	v_dot8c_i32_i4_e32 v40, v125, v49
	v_dot8c_i32_i4_e32 v41, v125, v47
	v_dot8c_i32_i4_e32 v42, v127, v49
	v_dot8c_i32_i4_e32 v43, v127, v47
	v_dot8c_i32_i4_e32 v44, v129, v49
	v_dot8c_i32_i4_e32 v45, v129, v47
	v_and_b32_e32 v78, 0xffff, v24
	v_lshrrev_b32_e32 v79, 16, v24
	v_lshl_add_u32 v78, v78, 7, v152
	v_lshl_add_u32 v79, v79, 7, v153
	s_mov_b32 m0, s98
	s_add_i32 s43, s98, 0x400
	global_load_lds_dwordx4 v78, s[50:51]
	s_mov_b32 m0, s43
	s_nop 0
	global_load_lds_dwordx4 v79, s[50:51]
	s_waitcnt vmcnt(13)
	v_add_u32_e32 v54, s76, v59
	v_add_u32_e32 v55, s76, v60
	v_add_u32_e32 v56, s76, v61
	v_add_u32_e32 v57, s76, v62
	ds_read_b64_tr_b4 v[46:47], v160 offset:256
	ds_read_b64_tr_b4 v[48:49], v160 offset:1280
	ds_read_b64_tr_b4 v[122:123], v54
	ds_read_b64_tr_b4 v[124:125], v55
	ds_read_b64_tr_b4 v[126:127], v56
	ds_read_b64_tr_b4 v[128:129], v57
	s_waitcnt lgkmcnt(6)
	v_dot8c_i32_i4_e32 v38, v130, v52
	v_dot8c_i32_i4_e32 v39, v130, v50
	v_dot8c_i32_i4_e32 v40, v132, v52
	v_dot8c_i32_i4_e32 v41, v132, v50
	v_dot8c_i32_i4_e32 v42, v134, v52
	v_dot8c_i32_i4_e32 v43, v134, v50
	v_dot8c_i32_i4_e32 v44, v136, v52
	v_dot8c_i32_i4_e32 v45, v136, v50
	v_dot8c_i32_i4_e32 v38, v131, v53
	v_dot8c_i32_i4_e32 v39, v131, v51
	v_dot8c_i32_i4_e32 v40, v133, v53
	v_dot8c_i32_i4_e32 v41, v133, v51
	v_dot8c_i32_i4_e32 v42, v135, v53
	v_dot8c_i32_i4_e32 v43, v135, v51
	v_dot8c_i32_i4_e32 v44, v137, v53
	v_dot8c_i32_i4_e32 v45, v137, v51
	v_and_b32_e32 v78, 0xffff, v25
	v_lshrrev_b32_e32 v79, 16, v25
	v_lshl_add_u32 v78, v78, 7, v152
	v_lshl_add_u32 v79, v79, 7, v153
	s_mov_b32 m0, s99
	s_add_i32 s43, s99, 0x400
	global_load_lds_dwordx4 v78, s[50:51]
	s_mov_b32 m0, s43
	s_nop 0
	global_load_lds_dwordx4 v79, s[50:51]
	s_waitcnt vmcnt(13)
	v_add_u32_e32 v54, s77, v59
	v_add_u32_e32 v55, s77, v60
	v_add_u32_e32 v56, s77, v61
	v_add_u32_e32 v57, s77, v62
	ds_read_b64_tr_b4 v[50:51], v160 offset:384
	ds_read_b64_tr_b4 v[52:53], v160 offset:1408
	ds_read_b64_tr_b4 v[130:131], v54
	ds_read_b64_tr_b4 v[132:133], v55
	ds_read_b64_tr_b4 v[134:135], v56
	ds_read_b64_tr_b4 v[136:137], v57
	s_waitcnt lgkmcnt(6)
	v_dot8c_i32_i4_e32 v38, v122, v48
	v_dot8c_i32_i4_e32 v39, v122, v46
	v_dot8c_i32_i4_e32 v40, v124, v48
	v_dot8c_i32_i4_e32 v41, v124, v46
	v_dot8c_i32_i4_e32 v42, v126, v48
	v_dot8c_i32_i4_e32 v43, v126, v46
	v_dot8c_i32_i4_e32 v44, v128, v48
	v_dot8c_i32_i4_e32 v45, v128, v46
	v_dot8c_i32_i4_e32 v38, v123, v49
	v_dot8c_i32_i4_e32 v39, v123, v47
	v_dot8c_i32_i4_e32 v40, v125, v49
	v_dot8c_i32_i4_e32 v41, v125, v47
	v_dot8c_i32_i4_e32 v42, v127, v49
	v_dot8c_i32_i4_e32 v43, v127, v47
	v_dot8c_i32_i4_e32 v44, v129, v49
	v_dot8c_i32_i4_e32 v45, v129, v47
	s_waitcnt lgkmcnt(15)
; #define LAS __attribute__((address_space(3)))
; #define TR4(p_) __builtin_amdgcn_ds_read_tr4_b64_v2i32((LAS v2i*)(p_))
; __device__ __forceinline__ void peer_v_tokens(int j, const LAS unsigned short* EL, const LAS unsigned char* AL  , const LAS float* ASC  , const LAS int* SAL  , ...
;     ...
;         for (int m = 0; m < 2; ++m) {
;             const int idx = lane + 64 * m, tau = idx >> 4, sr = idx & 15, k = 16 * (sr & 7) + 2 * tau + (sr >> 3);
;             const int aq = (int)*(const LAS signed char*)(AL + tl * 128 + k); const int tq = aq + 8;
;             const unsigned lo = (((unsigned)tq & 15u) ^ 8u) * 0x11111111u, hi = ((unsigned)(tq >> 4) & 15u) * 0x11111111u;
;             typedef unsigned u2v __attribute__((ext_vector_type(2)));
;             u2v l2; l2.x = lo; l2.y = lo; u2v h2; h2.x = hi; h2.y = hi;
;             *(LAS u2v*)(ATL + 8 * idx) = l2; *(LAS u2v*)(ATL + 1024 + 8 * idx) = h2;
;         }
;     ...
; #pragma unroll
;         for (int st = 0; st < 16; ++st) {
;             const int p = st >> 2, q = st & 3;
;             if (st < 14) VDMA(st + 2, (st + 2) % 3);
;             if (st < 14) asm volatile("s_waitcnt vmcnt(8)" ::: "memory");
;             else if (st == 14) asm volatile("s_waitcnt vmcnt(4)" ::: "memory");
;             else asm volatile("s_waitcnt vmcnt(0)" ::: "memory");
;             if (q == 0) {
; #pragma unroll
;                 for (int r = 0; r < 4; ++r) { accH[r] = 0; accL[r] = 0; } }
; #pragma unroll
;             for (int tp = 0; tp < 2; ++tp) {
;                 const v2i ao = TR4(ATL + (2 * q + tp) * 128 + 8 * s16), ah = TR4(ATL + 1024 + (2 * q + tp) * 128 + 8 * s16);
; #pragma unroll
;                 for (int r = 0; r < 4; ++r) {
;                     const v2i d = TR4(ldsb + BUF[st % 3] + 2048 * tp + roff[r]);
;                     accH[r] = __builtin_amdgcn_sdot8(d.x, ah.x, accH[r], false); accH[r] = __builtin_amdgcn_sdot8(d.y, ah.y, accH[r], false);
;                     accL[r] = __builtin_amdgcn_sdot8(d.x, ao.x, accL[r], false); accL[r] = __builtin_amdgcn_sdot8(d.y, ao.y, accL[r], false);
;                 }
;             }
;             asm volatile("s_waitcnt lgkmcnt(0)" ::: "memory");
	v_and_b32_e32 v78, 0xffff, v26
	v_lshrrev_b32_e32 v79, 16, v26
	v_lshl_add_u32 v78, v78, 7, v152
	v_lshl_add_u32 v79, v79, 7, v153
	s_mov_b32 m0, s76
	s_add_i32 s43, s76, 0x400
	global_load_lds_dwordx4 v78, s[50:51]
	s_mov_b32 m0, s43
	s_nop 0
	global_load_lds_dwordx4 v79, s[50:51]
	s_waitcnt vmcnt(13)
	v_add_u32_e32 v54, s78, v59
	v_add_u32_e32 v55, s78, v60
	v_add_u32_e32 v56, s78, v61
	v_add_u32_e32 v57, s78, v62
	ds_read_b64_tr_b4 v[46:47], v160 offset:512
	ds_read_b64_tr_b4 v[48:49], v160 offset:1536
	ds_read_b64_tr_b4 v[122:123], v54
	ds_read_b64_tr_b4 v[124:125], v55
	ds_read_b64_tr_b4 v[126:127], v56
	ds_read_b64_tr_b4 v[128:129], v57
	s_waitcnt lgkmcnt(6)
	v_dot8c_i32_i4_e32 v38, v130, v52
	v_dot8c_i32_i4_e32 v39, v130, v50
	v_dot8c_i32_i4_e32 v40, v132, v52
	v_dot8c_i32_i4_e32 v41, v132, v50
	v_dot8c_i32_i4_e32 v42, v134, v52
	v_dot8c_i32_i4_e32 v43, v134, v50
	v_dot8c_i32_i4_e32 v44, v136, v52
	v_dot8c_i32_i4_e32 v45, v136, v50
	v_dot8c_i32_i4_e32 v38, v131, v53
	v_dot8c_i32_i4_e32 v39, v131, v51
	v_dot8c_i32_i4_e32 v40, v133, v53
	v_dot8c_i32_i4_e32 v41, v133, v51
	v_dot8c_i32_i4_e32 v42, v135, v53
	v_dot8c_i32_i4_e32 v43, v135, v51
	v_dot8c_i32_i4_e32 v44, v137, v53
	v_dot8c_i32_i4_e32 v45, v137, v51
	v_and_b32_e32 v78, 0xffff, v27
	v_lshrrev_b32_e32 v79, 16, v27
	v_lshl_add_u32 v78, v78, 7, v152
	v_lshl_add_u32 v79, v79, 7, v153
	s_mov_b32 m0, s77
	s_add_i32 s43, s77, 0x400
	global_load_lds_dwordx4 v78, s[50:51]
	s_mov_b32 m0, s43
	s_nop 0
	global_load_lds_dwordx4 v79, s[50:51]
	s_waitcnt vmcnt(8)
	v_add_u32_e32 v54, s79, v59
	v_add_u32_e32 v55, s79, v60
	v_add_u32_e32 v56, s79, v61
	v_add_u32_e32 v57, s79, v62
	ds_read_b64_tr_b4 v[50:51], v160 offset:640
	ds_read_b64_tr_b4 v[52:53], v160 offset:1664
	ds_read_b64_tr_b4 v[130:131], v54
	ds_read_b64_tr_b4 v[132:133], v55
	ds_read_b64_tr_b4 v[134:135], v56
	ds_read_b64_tr_b4 v[136:137], v57
	s_waitcnt lgkmcnt(6)
	v_dot8c_i32_i4_e32 v38, v122, v48
	v_dot8c_i32_i4_e32 v39, v122, v46
	v_dot8c_i32_i4_e32 v40, v124, v48
	v_dot8c_i32_i4_e32 v41, v124, v46
	v_dot8c_i32_i4_e32 v42, v126, v48
	v_dot8c_i32_i4_e32 v43, v126, v46
	v_dot8c_i32_i4_e32 v44, v128, v48
	v_dot8c_i32_i4_e32 v45, v128, v46
	v_dot8c_i32_i4_e32 v38, v123, v49
	v_dot8c_i32_i4_e32 v39, v123, v47
	v_dot8c_i32_i4_e32 v40, v125, v49
	v_dot8c_i32_i4_e32 v41, v125, v47
	v_dot8c_i32_i4_e32 v42, v127, v49
	v_dot8c_i32_i4_e32 v43, v127, v47
	v_dot8c_i32_i4_e32 v44, v129, v49
	v_dot8c_i32_i4_e32 v45, v129, v47
	s_waitcnt lgkmcnt(15)
	v_add_u32_e32 v143, 8, v139
	v_and_b32_e32 v142, 15, v143
	v_xor_b32_e32 v142, 8, v142
	v_bfe_u32 v144, v143, 4, 4
	v_mul_lo_u32 v142, v142, s92
	v_mul_lo_u32 v144, v144, s92
	v_mov_b32_e32 v143, v142
	v_mov_b32_e32 v145, v144
	ds_write2st64_b64 v159, v[142:143], v[144:145] offset1:2
	v_and_b32_e32 v78, 0xffff, v28
	v_lshrrev_b32_e32 v79, 16, v28
	v_lshl_add_u32 v78, v78, 7, v152
	v_lshl_add_u32 v79, v79, 7, v153
	s_mov_b32 m0, s78
	s_add_i32 s43, s78, 0x400
	global_load_lds_dwordx4 v78, s[50:51]
	s_mov_b32 m0, s43
	s_nop 0
	global_load_lds_dwordx4 v79, s[50:51]
	s_waitcnt vmcnt(8)
	v_add_u32_e32 v54, s98, v59
	v_add_u32_e32 v55, s98, v60
	v_add_u32_e32 v56, s98, v61
	v_add_u32_e32 v57, s98, v62
	ds_read_b64_tr_b4 v[46:47], v160 offset:768
	ds_read_b64_tr_b4 v[48:49], v160 offset:1792
	ds_read_b64_tr_b4 v[122:123], v54
	ds_read_b64_tr_b4 v[124:125], v55
	ds_read_b64_tr_b4 v[126:127], v56
	ds_read_b64_tr_b4 v[128:129], v57
	s_waitcnt lgkmcnt(7)
	v_dot8c_i32_i4_e32 v38, v130, v52
	v_dot8c_i32_i4_e32 v39, v130, v50
	v_dot8c_i32_i4_e32 v40, v132, v52
	v_dot8c_i32_i4_e32 v41, v132, v50
	v_dot8c_i32_i4_e32 v42, v134, v52
	v_dot8c_i32_i4_e32 v43, v134, v50
	v_dot8c_i32_i4_e32 v44, v136, v52
	v_dot8c_i32_i4_e32 v45, v136, v50
	v_dot8c_i32_i4_e32 v38, v131, v53
	v_dot8c_i32_i4_e32 v39, v131, v51
	v_dot8c_i32_i4_e32 v40, v133, v53
	v_dot8c_i32_i4_e32 v41, v133, v51
	v_dot8c_i32_i4_e32 v42, v135, v53
	v_dot8c_i32_i4_e32 v43, v135, v51
	v_dot8c_i32_i4_e32 v44, v137, v53
	v_dot8c_i32_i4_e32 v45, v137, v51
	v_and_b32_e32 v78, 0xffff, v29
	v_lshrrev_b32_e32 v79, 16, v29
	v_lshl_add_u32 v78, v78, 7, v152
	v_lshl_add_u32 v79, v79, 7, v153
	s_mov_b32 m0, s79
	s_add_i32 s43, s79, 0x400
	global_load_lds_dwordx4 v78, s[50:51]
	s_mov_b32 m0, s43
	s_nop 0
	global_load_lds_dwordx4 v79, s[50:51]
	s_waitcnt vmcnt(8)
	v_add_u32_e32 v54, s99, v59
	v_add_u32_e32 v55, s99, v60
	v_add_u32_e32 v56, s99, v61
	v_add_u32_e32 v57, s99, v62
	ds_read_b64_tr_b4 v[50:51], v160 offset:896
	ds_read_b64_tr_b4 v[52:53], v160 offset:1920
	ds_read_b64_tr_b4 v[130:131], v54
	ds_read_b64_tr_b4 v[132:133], v55
	ds_read_b64_tr_b4 v[134:135], v56
	ds_read_b64_tr_b4 v[136:137], v57
	s_waitcnt lgkmcnt(6)
	v_dot8c_i32_i4_e32 v38, v122, v48
	v_dot8c_i32_i4_e32 v39, v122, v46
	v_dot8c_i32_i4_e32 v40, v124, v48
	v_dot8c_i32_i4_e32 v41, v124, v46
	v_dot8c_i32_i4_e32 v42, v126, v48
	v_dot8c_i32_i4_e32 v43, v126, v46
	v_dot8c_i32_i4_e32 v44, v128, v48
	v_dot8c_i32_i4_e32 v45, v128, v46
	v_dot8c_i32_i4_e32 v38, v123, v49
	v_dot8c_i32_i4_e32 v39, v123, v47
	v_dot8c_i32_i4_e32 v40, v125, v49
	v_dot8c_i32_i4_e32 v41, v125, v47
	v_dot8c_i32_i4_e32 v42, v127, v49
	v_dot8c_i32_i4_e32 v43, v127, v47
	v_dot8c_i32_i4_e32 v44, v129, v49
	v_dot8c_i32_i4_e32 v45, v129, v47
	v_and_b32_e32 v78, 0xffff, v30
	v_lshrrev_b32_e32 v79, 16, v30
	v_lshl_add_u32 v78, v78, 7, v152
	v_lshl_add_u32 v79, v79, 7, v153
	s_mov_b32 m0, s98
	s_add_i32 s43, s98, 0x400
	global_load_lds_dwordx4 v78, s[50:51]
	s_mov_b32 m0, s43
	s_nop 0
	global_load_lds_dwordx4 v79, s[50:51]
	s_waitcnt vmcnt(8)
; #define LAS __attribute__((address_space(3)))
; __device__ __forceinline__ bf16 f2bf(float f) { return (bf16)f2bfu(f); }
; __device__ __forceinline__ void peer_v_tokens(int j, const LAS unsigned short* EL, const LAS unsigned char* AL  , const LAS float* ASC  , const LAS int* SAL  , ...
;     ...
; #pragma unroll
;         for (int m = 0; m < 2; ++m) {
;             const int idx = lane + 64 * m, tau = idx >> 4, sr = idx & 15, k = 16 * (sr & 7) + 2 * tau + (sr >> 3);
;             const int aq = (int)*(const LAS signed char*)(AL + tl * 128 + k); const int tq = aq + 8;
;             const unsigned lo = (((unsigned)tq & 15u) ^ 8u) * 0x11111111u, hi = ((unsigned)(tq >> 4) & 15u) * 0x11111111u;
;             typedef unsigned u2v __attribute__((ext_vector_type(2)));
;             u2v l2; l2.x = lo; l2.y = lo; u2v h2; h2.x = hi; h2.y = hi;
;             *(LAS u2v*)(ATL + 8 * idx) = l2; *(LAS u2v*)(ATL + 1024 + 8 * idx) = h2;
;         }
;     ...
;         for (int st = 0; st < 16; ++st) {
;             const int p = st >> 2, q = st & 3;
;             if (st < 14) VDMA(st + 2, (st + 2) % 3);
;             if (st < 14) asm volatile("s_waitcnt vmcnt(8)" ::: "memory");
;             else if (st == 14) asm volatile("s_waitcnt vmcnt(4)" ::: "memory");
;             else asm volatile("s_waitcnt vmcnt(0)" ::: "memory");
;             if (q == 0) {
; #pragma unroll
;                 for (int r = 0; r < 4; ++r) { accH[r] = 0; accL[r] = 0; } }
; #pragma unroll
;             for (int tp = 0; tp < 2; ++tp) {
;                 const v2i ao = TR4(ATL + (2 * q + tp) * 128 + 8 * s16), ah = TR4(ATL + 1024 + (2 * q + tp) * 128 + 8 * s16);
; #pragma unroll
;                 for (int r = 0; r < 4; ++r) {
;                     const v2i d = TR4(ldsb + BUF[st % 3] + 2048 * tp + roff[r]);
;                     accH[r] = __builtin_amdgcn_sdot8(d.x, ah.x, accH[r], false); accH[r] = __builtin_amdgcn_sdot8(d.y, ah.y, accH[r], false);
;                     accL[r] = __builtin_amdgcn_sdot8(d.x, ao.x, accL[r], false); accL[r] = __builtin_amdgcn_sdot8(d.y, ao.y, accL[r], false);
;                 }
;             }
;             asm volatile("s_waitcnt lgkmcnt(0)" ::: "memory");
;             if (q == 3) {
; #pragma unroll
;                 for (int r = 0; r < 4; ++r) STASH[256 * p + 16 * (grp + 4 * r) + pc] = f2bf(asc * (float)(2 * ((accH[r] << 4) + accL[r]) + sa));
;             }
;         }
	v_add_u32_e32 v54, s76, v59
	v_add_u32_e32 v55, s76, v60
	v_add_u32_e32 v56, s76, v61
	v_add_u32_e32 v57, s76, v62
	ds_read_b64_tr_b4 v[46:47], v160
	ds_read_b64_tr_b4 v[48:49], v160 offset:1024
	ds_read_b64_tr_b4 v[122:123], v54
	ds_read_b64_tr_b4 v[124:125], v55
	ds_read_b64_tr_b4 v[126:127], v56
	ds_read_b64_tr_b4 v[128:129], v57
	s_waitcnt lgkmcnt(6)
	v_dot8c_i32_i4_e32 v38, v130, v52
	v_dot8c_i32_i4_e32 v39, v130, v50
	v_dot8c_i32_i4_e32 v40, v132, v52
	v_dot8c_i32_i4_e32 v41, v132, v50
	v_dot8c_i32_i4_e32 v42, v134, v52
	v_dot8c_i32_i4_e32 v43, v134, v50
	v_dot8c_i32_i4_e32 v44, v136, v52
	v_dot8c_i32_i4_e32 v45, v136, v50
	v_dot8c_i32_i4_e32 v38, v131, v53
	v_dot8c_i32_i4_e32 v39, v131, v51
	v_dot8c_i32_i4_e32 v40, v133, v53
	v_dot8c_i32_i4_e32 v41, v133, v51
	v_dot8c_i32_i4_e32 v42, v135, v53
	v_dot8c_i32_i4_e32 v43, v135, v51
	v_dot8c_i32_i4_e32 v44, v137, v53
	v_dot8c_i32_i4_e32 v45, v137, v51
	s_nop 3
	s_waitcnt lgkmcnt(15)
	v_lshlrev_b32_e32 v38, 5, v38
	v_lshlrev_b32_e32 v39, 1, v39
	v_add3_u32 v38, v39, v229, v38
	v_cvt_f32_i32_e32 v38, v38
	v_mul_f32_e32 v38, v228, v38
	v_lshlrev_b32_e32 v40, 5, v40
	v_lshlrev_b32_e32 v41, 1, v41
	v_add3_u32 v40, v41, v229, v40
	v_cvt_f32_i32_e32 v40, v40
	v_mul_f32_e32 v40, v228, v40
	v_lshlrev_b32_e32 v42, 5, v42
	v_lshlrev_b32_e32 v43, 1, v43
	v_add3_u32 v42, v43, v229, v42
	v_cvt_f32_i32_e32 v42, v42
	v_mul_f32_e32 v42, v228, v42
	v_lshlrev_b32_e32 v44, 5, v44
	v_lshlrev_b32_e32 v45, 1, v45
	v_add3_u32 v44, v45, v229, v44
	v_cvt_f32_i32_e32 v44, v44
	v_mul_f32_e32 v44, v228, v44
	v_cvt_pk_bf16_f32 v180, v38, v40
	v_cvt_pk_bf16_f32 v181, v42, v44
	ds_read_b128 v[252:255], v155 offset:1024
	s_add_i32 s44, s40, 32
	s_ashr_i32 s45, s44, 31
	s_lshl_b64 s[44:45], s[44:45], 12
	v_lshl_add_u64 v[80:81], v[36:37], 0, s[44:45]
	s_waitcnt lgkmcnt(0)
	v_mul_f32_e32 v214, v214, v252
	v_mul_f32_e32 v215, v215, v253
	v_mul_f32_e32 v216, v216, v254
	v_mul_f32_e32 v217, v217, v255
	global_store_dwordx4 v[80:81], v[214:217], off offset:1024 nt
	v_add_u32_e32 v147, 8, v140
	v_and_b32_e32 v146, 15, v147
	v_xor_b32_e32 v146, 8, v146
	v_bfe_u32 v148, v147, 4, 4
	v_mul_lo_u32 v146, v146, s92
	v_mul_lo_u32 v148, v148, s92
	v_mov_b32_e32 v147, v146
	v_mov_b32_e32 v149, v148
	ds_write2st64_b64 v77, v[146:147], v[148:149] offset1:2
	v_add_u32_e32 v138, 0x1800, v74
	ds_read_u8 v139, v138
	v_add_u32_e32 v141, 0x1800, v73
	ds_read_u8 v140, v141
	s_add_i32 s43, s67, 224
	v_mov_b32_e32 v138, s43
	ds_read2st64_b32 v[228:229], v138 offset1:1
	ds_read_b128 v[18:21], v227 offset:12288
	ds_read_b128 v[22:25], v227 offset:12304
	v_add_u32_e32 v150, 0x400000, v63
	v_add_u32_e32 v151, 0x400000, v64
	v_mov_b32_e32 v38, 0
	v_mov_b32_e32 v39, 0
	v_mov_b32_e32 v40, 0
	v_mov_b32_e32 v41, 0
	v_mov_b32_e32 v42, 0
	v_mov_b32_e32 v43, 0
	v_mov_b32_e32 v44, 0
	v_mov_b32_e32 v45, 0
	v_and_b32_e32 v78, 0xffff, v31
	v_lshrrev_b32_e32 v79, 16, v31
	v_lshl_add_u32 v78, v78, 7, v152
	v_lshl_add_u32 v79, v79, 7, v153
	s_mov_b32 m0, s99
	s_add_i32 s43, s99, 0x400
	global_load_lds_dwordx4 v78, s[50:51]
	s_mov_b32 m0, s43
	s_nop 0
	global_load_lds_dwordx4 v79, s[50:51]
	s_waitcnt vmcnt(9)
	v_add_u32_e32 v54, s77, v59
	v_add_u32_e32 v55, s77, v60
	v_add_u32_e32 v56, s77, v61
	v_add_u32_e32 v57, s77, v62
	ds_read_b64_tr_b4 v[50:51], v160 offset:128
	ds_read_b64_tr_b4 v[52:53], v160 offset:1152
	ds_read_b64_tr_b4 v[130:131], v54
	ds_read_b64_tr_b4 v[132:133], v55
	ds_read_b64_tr_b4 v[134:135], v56
	ds_read_b64_tr_b4 v[136:137], v57
	s_waitcnt lgkmcnt(13)
	v_dot8c_i32_i4_e32 v38, v122, v48
	v_dot8c_i32_i4_e32 v39, v122, v46
	v_dot8c_i32_i4_e32 v40, v124, v48
	v_dot8c_i32_i4_e32 v41, v124, v46
	v_dot8c_i32_i4_e32 v42, v126, v48
	v_dot8c_i32_i4_e32 v43, v126, v46
	v_dot8c_i32_i4_e32 v44, v128, v48
	v_dot8c_i32_i4_e32 v45, v128, v46
	v_dot8c_i32_i4_e32 v38, v123, v49
	v_dot8c_i32_i4_e32 v39, v123, v47
	v_dot8c_i32_i4_e32 v40, v125, v49
	v_dot8c_i32_i4_e32 v41, v125, v47
	v_dot8c_i32_i4_e32 v42, v127, v49
	v_dot8c_i32_i4_e32 v43, v127, v47
	v_dot8c_i32_i4_e32 v44, v129, v49
	v_dot8c_i32_i4_e32 v45, v129, v47
	v_and_b32_e32 v78, 0xffff, v32
	v_lshrrev_b32_e32 v79, 16, v32
	v_lshl_add_u32 v78, v78, 7, v152
	v_lshl_add_u32 v79, v79, 7, v153
	s_mov_b32 m0, s76
	s_add_i32 s43, s76, 0x400
	global_load_lds_dwordx4 v78, s[50:51]
	s_mov_b32 m0, s43
	s_nop 0
	global_load_lds_dwordx4 v79, s[50:51]
	s_waitcnt vmcnt(9)
	v_add_u32_e32 v54, s78, v59
	v_add_u32_e32 v55, s78, v60
	v_add_u32_e32 v56, s78, v61
	v_add_u32_e32 v57, s78, v62
	ds_read_b64_tr_b4 v[46:47], v160 offset:256
	ds_read_b64_tr_b4 v[48:49], v160 offset:1280
	ds_read_b64_tr_b4 v[122:123], v54
	ds_read_b64_tr_b4 v[124:125], v55
	ds_read_b64_tr_b4 v[126:127], v56
	ds_read_b64_tr_b4 v[128:129], v57
	s_waitcnt lgkmcnt(6)
	v_dot8c_i32_i4_e32 v38, v130, v52
	v_dot8c_i32_i4_e32 v39, v130, v50
	v_dot8c_i32_i4_e32 v40, v132, v52
	v_dot8c_i32_i4_e32 v41, v132, v50
	v_dot8c_i32_i4_e32 v42, v134, v52
	v_dot8c_i32_i4_e32 v43, v134, v50
	v_dot8c_i32_i4_e32 v44, v136, v52
	v_dot8c_i32_i4_e32 v45, v136, v50
	v_dot8c_i32_i4_e32 v38, v131, v53
	v_dot8c_i32_i4_e32 v39, v131, v51
	v_dot8c_i32_i4_e32 v40, v133, v53
	v_dot8c_i32_i4_e32 v41, v133, v51
	v_dot8c_i32_i4_e32 v42, v135, v53
	v_dot8c_i32_i4_e32 v43, v135, v51
	v_dot8c_i32_i4_e32 v44, v137, v53
	v_dot8c_i32_i4_e32 v45, v137, v51
	ds_write_b16 v65, v170
	ds_write_b16_d16_hi v65, v170 offset:128
	ds_write_b16 v65, v171 offset:256
	ds_write_b16_d16_hi v65, v171 offset:384
	ds_write_b16 v65, v172 offset:512
	ds_write_b16_d16_hi v65, v172 offset:640
	ds_write_b16 v65, v173 offset:768
	ds_write_b16_d16_hi v65, v173 offset:896
	ds_write_b16 v65, v174 offset:1024
	ds_write_b16_d16_hi v65, v174 offset:1152
	ds_write_b16 v65, v175 offset:1280
	ds_write_b16_d16_hi v65, v175 offset:1408
	ds_write_b16 v65, v176 offset:1536
	ds_write_b16_d16_hi v65, v176 offset:1664
	ds_write_b16 v65, v177 offset:1792
	ds_write_b16_d16_hi v65, v177 offset:1920
	ds_read_b64 v[202:203], v154
	ds_read_b64 v[204:205], v154 offset:512
	ds_read_b64 v[206:207], v154 offset:1024
	ds_read_b64 v[208:209], v154 offset:1536
	v_and_b32_e32 v78, 0xffff, v33
	v_lshrrev_b32_e32 v79, 16, v33
	v_lshl_add_u32 v78, v78, 7, v152
	v_lshl_add_u32 v79, v79, 7, v153
	s_mov_b32 m0, s77
	s_add_i32 s43, s77, 0x400
	global_load_lds_dwordx4 v78, s[50:51]
	s_mov_b32 m0, s43
	s_nop 0
	global_load_lds_dwordx4 v79, s[50:51]
	s_waitcnt vmcnt(9)
; #define LAS __attribute__((address_space(3)))
; #define TR4(p_) __builtin_amdgcn_ds_read_tr4_b64_v2i32((LAS v2i*)(p_))
; __device__ __forceinline__ void peer_v_tokens(int j, const LAS unsigned short* EL, const LAS unsigned char* AL  , const LAS float* ASC  , const LAS int* SAL  , ...
;     ...
; #pragma unroll
;         for (int m = 0; m < 2; ++m) {
;             const int idx = lane + 64 * m, tau = idx >> 4, sr = idx & 15, k = 16 * (sr & 7) + 2 * tau + (sr >> 3);
;             const int aq = (int)*(const LAS signed char*)(AL + tl * 128 + k); const int tq = aq + 8;
;             const unsigned lo = (((unsigned)tq & 15u) ^ 8u) * 0x11111111u, hi = ((unsigned)(tq >> 4) & 15u) * 0x11111111u;
;             typedef unsigned u2v __attribute__((ext_vector_type(2)));
;             u2v l2; l2.x = lo; l2.y = lo; u2v h2; h2.x = hi; h2.y = hi;
;             *(LAS u2v*)(ATL + 8 * idx) = l2; *(LAS u2v*)(ATL + 1024 + 8 * idx) = h2;
;         }
;     ...
;         for (int st = 0; st < 16; ++st) {
;             const int p = st >> 2, q = st & 3;
;             if (st < 14) VDMA(st + 2, (st + 2) % 3);
;             if (st < 14) asm volatile("s_waitcnt vmcnt(8)" ::: "memory");
;             else if (st == 14) asm volatile("s_waitcnt vmcnt(4)" ::: "memory");
;             else asm volatile("s_waitcnt vmcnt(0)" ::: "memory");
;             if (q == 0) {
; #pragma unroll
;                 for (int r = 0; r < 4; ++r) { accH[r] = 0; accL[r] = 0; } }
; #pragma unroll
;             for (int tp = 0; tp < 2; ++tp) {
;                 const v2i ao = TR4(ATL + (2 * q + tp) * 128 + 8 * s16), ah = TR4(ATL + 1024 + (2 * q + tp) * 128 + 8 * s16);
; #pragma unroll
;                 for (int r = 0; r < 4; ++r) {
;                     const v2i d = TR4(ldsb + BUF[st % 3] + 2048 * tp + roff[r]);
;                     accH[r] = __builtin_amdgcn_sdot8(d.x, ah.x, accH[r], false); accH[r] = __builtin_amdgcn_sdot8(d.y, ah.y, accH[r], false);
;                     accL[r] = __builtin_amdgcn_sdot8(d.x, ao.x, accL[r], false); accL[r] = __builtin_amdgcn_sdot8(d.y, ao.y, accL[r], false);
;                 }
;             }
;             asm volatile("s_waitcnt lgkmcnt(0)" ::: "memory");
	v_add_u32_e32 v54, s79, v59
	v_add_u32_e32 v55, s79, v60
	v_add_u32_e32 v56, s79, v61
	v_add_u32_e32 v57, s79, v62
	ds_read_b64_tr_b4 v[50:51], v160 offset:384
	ds_read_b64_tr_b4 v[52:53], v160 offset:1408
	ds_read_b64_tr_b4 v[130:131], v54
	ds_read_b64_tr_b4 v[132:133], v55
	ds_read_b64_tr_b4 v[134:135], v56
	ds_read_b64_tr_b4 v[136:137], v57
	s_waitcnt lgkmcnt(15)
	v_dot8c_i32_i4_e32 v38, v122, v48
	v_dot8c_i32_i4_e32 v39, v122, v46
	v_dot8c_i32_i4_e32 v40, v124, v48
	v_dot8c_i32_i4_e32 v41, v124, v46
	v_dot8c_i32_i4_e32 v42, v126, v48
	v_dot8c_i32_i4_e32 v43, v126, v46
	v_dot8c_i32_i4_e32 v44, v128, v48
	v_dot8c_i32_i4_e32 v45, v128, v46
	v_dot8c_i32_i4_e32 v38, v123, v49
	v_dot8c_i32_i4_e32 v39, v123, v47
	v_dot8c_i32_i4_e32 v40, v125, v49
	v_dot8c_i32_i4_e32 v41, v125, v47
	v_dot8c_i32_i4_e32 v42, v127, v49
	v_dot8c_i32_i4_e32 v43, v127, v47
	v_dot8c_i32_i4_e32 v44, v129, v49
	v_dot8c_i32_i4_e32 v45, v129, v47
	s_waitcnt lgkmcnt(15)
	v_and_b32_e32 v78, 0xffff, v18
	v_lshrrev_b32_e32 v79, 16, v18
	v_lshl_add_u32 v78, v78, 7, v150
	v_lshl_add_u32 v79, v79, 7, v151
	s_mov_b32 m0, s78
	s_add_i32 s43, s78, 0x400
	global_load_lds_dwordx4 v78, s[50:51]
	s_mov_b32 m0, s43
	s_nop 0
	global_load_lds_dwordx4 v79, s[50:51]
	s_waitcnt vmcnt(9)
	v_add_u32_e32 v54, s98, v59
	v_add_u32_e32 v55, s98, v60
	v_add_u32_e32 v56, s98, v61
	v_add_u32_e32 v57, s98, v62
	ds_read_b64_tr_b4 v[46:47], v160 offset:512
	ds_read_b64_tr_b4 v[48:49], v160 offset:1536
	ds_read_b64_tr_b4 v[122:123], v54
	ds_read_b64_tr_b4 v[124:125], v55
	ds_read_b64_tr_b4 v[126:127], v56
	ds_read_b64_tr_b4 v[128:129], v57
	s_waitcnt lgkmcnt(6)
	v_dot8c_i32_i4_e32 v38, v130, v52
	v_dot8c_i32_i4_e32 v39, v130, v50
	v_dot8c_i32_i4_e32 v40, v132, v52
	v_dot8c_i32_i4_e32 v41, v132, v50
	v_dot8c_i32_i4_e32 v42, v134, v52
	v_dot8c_i32_i4_e32 v43, v134, v50
	v_dot8c_i32_i4_e32 v44, v136, v52
	v_dot8c_i32_i4_e32 v45, v136, v50
	v_dot8c_i32_i4_e32 v38, v131, v53
	v_dot8c_i32_i4_e32 v39, v131, v51
	v_dot8c_i32_i4_e32 v40, v133, v53
	v_dot8c_i32_i4_e32 v41, v133, v51
	v_dot8c_i32_i4_e32 v42, v135, v53
	v_dot8c_i32_i4_e32 v43, v135, v51
	v_dot8c_i32_i4_e32 v44, v137, v53
	v_dot8c_i32_i4_e32 v45, v137, v51
	v_and_b32_e32 v78, 0xffff, v19
	v_lshrrev_b32_e32 v79, 16, v19
	v_lshl_add_u32 v78, v78, 7, v150
	v_lshl_add_u32 v79, v79, 7, v151
	s_mov_b32 m0, s79
	s_add_i32 s43, s79, 0x400
	global_load_lds_dwordx4 v78, s[50:51]
	s_mov_b32 m0, s43
	s_nop 0
	global_load_lds_dwordx4 v79, s[50:51]
	s_waitcnt vmcnt(8)
	v_add_u32_e32 v54, s99, v59
	v_add_u32_e32 v55, s99, v60
	v_add_u32_e32 v56, s99, v61
	v_add_u32_e32 v57, s99, v62
	ds_read_b64_tr_b4 v[50:51], v160 offset:640
	ds_read_b64_tr_b4 v[52:53], v160 offset:1664
	ds_read_b64_tr_b4 v[130:131], v54
	ds_read_b64_tr_b4 v[132:133], v55
	ds_read_b64_tr_b4 v[134:135], v56
	ds_read_b64_tr_b4 v[136:137], v57
	s_waitcnt lgkmcnt(6)
	v_dot8c_i32_i4_e32 v38, v122, v48
	v_dot8c_i32_i4_e32 v39, v122, v46
	v_dot8c_i32_i4_e32 v40, v124, v48
	v_dot8c_i32_i4_e32 v41, v124, v46
	v_dot8c_i32_i4_e32 v42, v126, v48
	v_dot8c_i32_i4_e32 v43, v126, v46
	v_dot8c_i32_i4_e32 v44, v128, v48
	v_dot8c_i32_i4_e32 v45, v128, v46
	v_dot8c_i32_i4_e32 v38, v123, v49
	v_dot8c_i32_i4_e32 v39, v123, v47
	v_dot8c_i32_i4_e32 v40, v125, v49
	v_dot8c_i32_i4_e32 v41, v125, v47
	v_dot8c_i32_i4_e32 v42, v127, v49
	v_dot8c_i32_i4_e32 v43, v127, v47
	v_dot8c_i32_i4_e32 v44, v129, v49
	v_dot8c_i32_i4_e32 v45, v129, v47
	s_waitcnt lgkmcnt(15)
	v_add_u32_e32 v143, 8, v139
	v_and_b32_e32 v142, 15, v143
	v_xor_b32_e32 v142, 8, v142
	v_bfe_u32 v144, v143, 4, 4
	v_mul_lo_u32 v142, v142, s92
	v_mul_lo_u32 v144, v144, s92
	v_mov_b32_e32 v143, v142
	v_mov_b32_e32 v145, v144
	ds_write2st64_b64 v159, v[142:143], v[144:145] offset1:2
	v_and_b32_e32 v78, 0xffff, v20
	v_lshrrev_b32_e32 v79, 16, v20
	v_lshl_add_u32 v78, v78, 7, v150
	v_lshl_add_u32 v79, v79, 7, v151
	s_mov_b32 m0, s98
	s_add_i32 s43, s98, 0x400
	global_load_lds_dwordx4 v78, s[50:51]
	s_mov_b32 m0, s43
	s_nop 0
	global_load_lds_dwordx4 v79, s[50:51]
	s_waitcnt vmcnt(8)
	v_add_u32_e32 v54, s76, v59
	v_add_u32_e32 v55, s76, v60
	v_add_u32_e32 v56, s76, v61
	v_add_u32_e32 v57, s76, v62
	ds_read_b64_tr_b4 v[46:47], v160 offset:768
	ds_read_b64_tr_b4 v[48:49], v160 offset:1792
	ds_read_b64_tr_b4 v[122:123], v54
	ds_read_b64_tr_b4 v[124:125], v55
	ds_read_b64_tr_b4 v[126:127], v56
	ds_read_b64_tr_b4 v[128:129], v57
	s_waitcnt lgkmcnt(7)
	v_dot8c_i32_i4_e32 v38, v130, v52
	v_dot8c_i32_i4_e32 v39, v130, v50
	v_dot8c_i32_i4_e32 v40, v132, v52
	v_dot8c_i32_i4_e32 v41, v132, v50
	v_dot8c_i32_i4_e32 v42, v134, v52
	v_dot8c_i32_i4_e32 v43, v134, v50
	v_dot8c_i32_i4_e32 v44, v136, v52
	v_dot8c_i32_i4_e32 v45, v136, v50
	v_dot8c_i32_i4_e32 v38, v131, v53
	v_dot8c_i32_i4_e32 v39, v131, v51
	v_dot8c_i32_i4_e32 v40, v133, v53
	v_dot8c_i32_i4_e32 v41, v133, v51
	v_dot8c_i32_i4_e32 v42, v135, v53
	v_dot8c_i32_i4_e32 v43, v135, v51
	v_dot8c_i32_i4_e32 v44, v137, v53
	v_dot8c_i32_i4_e32 v45, v137, v51
	v_and_b32_e32 v78, 0xffff, v21
	v_lshrrev_b32_e32 v79, 16, v21
	v_lshl_add_u32 v78, v78, 7, v150
	v_lshl_add_u32 v79, v79, 7, v151
	s_mov_b32 m0, s99
	s_add_i32 s43, s99, 0x400
	global_load_lds_dwordx4 v78, s[50:51]
	s_mov_b32 m0, s43
	s_nop 0
	global_load_lds_dwordx4 v79, s[50:51]
	s_waitcnt vmcnt(8)
	v_add_u32_e32 v54, s77, v59
	v_add_u32_e32 v55, s77, v60
	v_add_u32_e32 v56, s77, v61
	v_add_u32_e32 v57, s77, v62
	ds_read_b64_tr_b4 v[50:51], v160 offset:896
	ds_read_b64_tr_b4 v[52:53], v160 offset:1920
	ds_read_b64_tr_b4 v[130:131], v54
	ds_read_b64_tr_b4 v[132:133], v55
	ds_read_b64_tr_b4 v[134:135], v56
	ds_read_b64_tr_b4 v[136:137], v57
	s_waitcnt lgkmcnt(6)
; #define LAS __attribute__((address_space(3)))
; __device__ __forceinline__ void peer_v_tokens(int j, const LAS unsigned short* EL, const LAS unsigned char* AL  , const LAS float* ASC  , const LAS int* SAL  , ...
;     ...
;         const int tl = it * 8 + wave, t = j * 64 + tl;
;         unsigned E[8];
;         { const LAS v4u* ep = (const LAS v4u*)(EL + tl * 128 + 16 * g); const v4u e0 = ep[0], e1 = ep[1];
;           E[0] = e0.x; E[1] = e0.y; E[2] = e0.z; E[3] = e0.w; E[4] = e1.x; E[5] = e1.y; E[6] = e1.z; E[7] = e1.w; }
;         uint2 hv[4]; float4 gv[4];
;         { unsigned ho = (unsigned)t * (D / 4) + (unsigned)lane; asm volatile("" : "+v"(ho)); const uint2* hp = (const uint2*)HB + ho; const float4* gp = (const float4*)fng + lane;
; #pragma unroll
;           for (int jq = 0; jq < 4; ++jq) { hv[jq] = hp[64 * jq]; gv[jq] = gp[64 * jq]; } }
;         VDMA(0, 0); VDMA(1, 1);
; #pragma unroll
;         for (int m = 0; m < 2; ++m) {
;     ...
;         for (int st = 0; st < 16; ++st) {
;             const int p = st >> 2, q = st & 3;
;             if (st < 14) VDMA(st + 2, (st + 2) % 3);
;             if (st < 14) asm volatile("s_waitcnt vmcnt(8)" ::: "memory");
;             else if (st == 14) asm volatile("s_waitcnt vmcnt(4)" ::: "memory");
;             else asm volatile("s_waitcnt vmcnt(0)" ::: "memory");
;             if (q == 0) {
; #pragma unroll
;                 for (int r = 0; r < 4; ++r) { accH[r] = 0; accL[r] = 0; } }
; #pragma unroll
;             for (int tp = 0; tp < 2; ++tp) {
;                 const v2i ao = TR4(ATL + (2 * q + tp) * 128 + 8 * s16), ah = TR4(ATL + 1024 + (2 * q + tp) * 128 + 8 * s16);
; #pragma unroll
;                 for (int r = 0; r < 4; ++r) {
;                     const v2i d = TR4(ldsb + BUF[st % 3] + 2048 * tp + roff[r]);
;                     accH[r] = __builtin_amdgcn_sdot8(d.x, ah.x, accH[r], false); accH[r] = __builtin_amdgcn_sdot8(d.y, ah.y, accH[r], false);
;                     accL[r] = __builtin_amdgcn_sdot8(d.x, ao.x, accL[r], false); accL[r] = __builtin_amdgcn_sdot8(d.y, ao.y, accL[r], false);
;                 }
;             }
;             asm volatile("s_waitcnt lgkmcnt(0)" ::: "memory");
;             if (q == 3) {
; #pragma unroll
;                 for (int r = 0; r < 4; ++r) STASH[256 * p + 16 * (grp + 4 * r) + pc] = f2bf(asc * (float)(2 * ((accH[r] << 4) + accL[r]) + sa));
;             }
;         }
	v_dot8c_i32_i4_e32 v38, v122, v48
	v_dot8c_i32_i4_e32 v39, v122, v46
	v_dot8c_i32_i4_e32 v40, v124, v48
	v_dot8c_i32_i4_e32 v41, v124, v46
	v_dot8c_i32_i4_e32 v42, v126, v48
	v_dot8c_i32_i4_e32 v43, v126, v46
	v_dot8c_i32_i4_e32 v44, v128, v48
	v_dot8c_i32_i4_e32 v45, v128, v46
	v_dot8c_i32_i4_e32 v38, v123, v49
	v_dot8c_i32_i4_e32 v39, v123, v47
	v_dot8c_i32_i4_e32 v40, v125, v49
	v_dot8c_i32_i4_e32 v41, v125, v47
	v_dot8c_i32_i4_e32 v42, v127, v49
	v_dot8c_i32_i4_e32 v43, v127, v47
	v_dot8c_i32_i4_e32 v44, v129, v49
	v_dot8c_i32_i4_e32 v45, v129, v47
	v_and_b32_e32 v78, 0xffff, v22
	v_lshrrev_b32_e32 v79, 16, v22
	v_lshl_add_u32 v78, v78, 7, v150
	v_lshl_add_u32 v79, v79, 7, v151
	s_mov_b32 m0, s76
	s_add_i32 s43, s76, 0x400
	global_load_lds_dwordx4 v78, s[50:51]
	s_mov_b32 m0, s43
	s_nop 0
	global_load_lds_dwordx4 v79, s[50:51]
	s_waitcnt vmcnt(8)
	v_add_u32_e32 v54, s78, v59
	v_add_u32_e32 v55, s78, v60
	v_add_u32_e32 v56, s78, v61
	v_add_u32_e32 v57, s78, v62
	ds_read_b64_tr_b4 v[46:47], v160
	ds_read_b64_tr_b4 v[48:49], v160 offset:1024
	ds_read_b64_tr_b4 v[122:123], v54
	ds_read_b64_tr_b4 v[124:125], v55
	ds_read_b64_tr_b4 v[126:127], v56
	ds_read_b64_tr_b4 v[128:129], v57
	s_waitcnt lgkmcnt(6)
	v_dot8c_i32_i4_e32 v38, v130, v52
	v_dot8c_i32_i4_e32 v39, v130, v50
	v_dot8c_i32_i4_e32 v40, v132, v52
	v_dot8c_i32_i4_e32 v41, v132, v50
	v_dot8c_i32_i4_e32 v42, v134, v52
	v_dot8c_i32_i4_e32 v43, v134, v50
	v_dot8c_i32_i4_e32 v44, v136, v52
	v_dot8c_i32_i4_e32 v45, v136, v50
	v_dot8c_i32_i4_e32 v38, v131, v53
	v_dot8c_i32_i4_e32 v39, v131, v51
	v_dot8c_i32_i4_e32 v40, v133, v53
	v_dot8c_i32_i4_e32 v41, v133, v51
	v_dot8c_i32_i4_e32 v42, v135, v53
	v_dot8c_i32_i4_e32 v43, v135, v51
	v_dot8c_i32_i4_e32 v44, v137, v53
	v_dot8c_i32_i4_e32 v45, v137, v51
	s_nop 3
	s_waitcnt lgkmcnt(15)
	v_lshlrev_b32_e32 v38, 5, v38
	v_lshlrev_b32_e32 v39, 1, v39
	v_add3_u32 v38, v39, v229, v38
	v_cvt_f32_i32_e32 v38, v38
	v_mul_f32_e32 v38, v228, v38
	v_lshlrev_b32_e32 v40, 5, v40
	v_lshlrev_b32_e32 v41, 1, v41
	v_add3_u32 v40, v41, v229, v40
	v_cvt_f32_i32_e32 v40, v40
	v_mul_f32_e32 v40, v228, v40
	v_lshlrev_b32_e32 v42, 5, v42
	v_lshlrev_b32_e32 v43, 1, v43
	v_add3_u32 v42, v43, v229, v42
	v_cvt_f32_i32_e32 v42, v42
	v_mul_f32_e32 v42, v228, v42
	v_lshlrev_b32_e32 v44, 5, v44
	v_lshlrev_b32_e32 v45, 1, v45
	v_add3_u32 v44, v45, v229, v44
	v_cvt_f32_i32_e32 v44, v44
	v_mul_f32_e32 v44, v228, v44
	v_cvt_pk_bf16_f32 v188, v38, v40
	v_cvt_pk_bf16_f32 v189, v42, v44
	ds_read_b128 v[252:255], v156
	s_add_i32 s44, s40, 32
	s_ashr_i32 s45, s44, 31
	s_lshl_b64 s[44:45], s[44:45], 12
	v_lshl_add_u64 v[80:81], v[36:37], 0, s[44:45]
	s_waitcnt lgkmcnt(0)
	v_mul_f32_e32 v218, v218, v252
	v_mul_f32_e32 v219, v219, v253
	v_mul_f32_e32 v220, v220, v254
	v_mul_f32_e32 v221, v221, v255
	global_store_dwordx4 v[80:81], v[218:221], off offset:2048 nt
	v_add_u32_e32 v147, 8, v140
	v_and_b32_e32 v146, 15, v147
	v_xor_b32_e32 v146, 8, v146
	v_bfe_u32 v148, v147, 4, 4
	v_mul_lo_u32 v146, v146, s92
	v_mul_lo_u32 v148, v148, s92
	v_mov_b32_e32 v147, v146
	v_mov_b32_e32 v149, v148
	ds_write2st64_b64 v77, v[146:147], v[148:149] offset1:2
	v_add_u32_e32 v138, 0x1c00, v74
	ds_read_u8 v139, v138
	v_add_u32_e32 v141, 0x1c00, v73
	ds_read_u8 v140, v141
	s_add_i32 s43, s67, 192
	v_mov_b32_e32 v138, s43
	ds_read2st64_b32 v[228:229], v138 offset1:1
	ds_read_b128 v[26:29], v227 offset:14336
	ds_read_b128 v[30:33], v227 offset:14352
	v_mov_b32_e32 v38, 0
	v_mov_b32_e32 v39, 0
	v_mov_b32_e32 v40, 0
	v_mov_b32_e32 v41, 0
	v_mov_b32_e32 v42, 0
	v_mov_b32_e32 v43, 0
	v_mov_b32_e32 v44, 0
	v_mov_b32_e32 v45, 0
	v_and_b32_e32 v78, 0xffff, v23
	v_lshrrev_b32_e32 v79, 16, v23
	v_lshl_add_u32 v78, v78, 7, v150
	v_lshl_add_u32 v79, v79, 7, v151
	s_mov_b32 m0, s77
	s_add_i32 s43, s77, 0x400
	global_load_lds_dwordx4 v78, s[50:51]
	s_mov_b32 m0, s43
	s_nop 0
	global_load_lds_dwordx4 v79, s[50:51]
	s_waitcnt vmcnt(9)
	v_add_u32_e32 v54, s79, v59
	v_add_u32_e32 v55, s79, v60
	v_add_u32_e32 v56, s79, v61
	v_add_u32_e32 v57, s79, v62
	ds_read_b64_tr_b4 v[50:51], v160 offset:128
	ds_read_b64_tr_b4 v[52:53], v160 offset:1152
	ds_read_b64_tr_b4 v[130:131], v54
	ds_read_b64_tr_b4 v[132:133], v55
	ds_read_b64_tr_b4 v[134:135], v56
	ds_read_b64_tr_b4 v[136:137], v57
	s_waitcnt lgkmcnt(13)
	s_waitcnt vmcnt(36) lgkmcnt(15)
; #define LAS __attribute__((address_space(3)))
; #define TR4(p_) __builtin_amdgcn_ds_read_tr4_b64_v2i32((LAS v2i*)(p_))
; __device__ __forceinline__ void peer_v_tokens(int j, const LAS unsigned short* EL, const LAS unsigned char* AL  , const LAS float* ASC  , const LAS int* SAL  , ...
;     ...
;         for (int st = 0; st < 16; ++st) {
;             const int p = st >> 2, q = st & 3;
;             if (st < 14) VDMA(st + 2, (st + 2) % 3);
;             if (st < 14) asm volatile("s_waitcnt vmcnt(8)" ::: "memory");
;             else if (st == 14) asm volatile("s_waitcnt vmcnt(4)" ::: "memory");
;             else asm volatile("s_waitcnt vmcnt(0)" ::: "memory");
;             if (q == 0) {
; #pragma unroll
;                 for (int r = 0; r < 4; ++r) { accH[r] = 0; accL[r] = 0; } }
; #pragma unroll
;             for (int tp = 0; tp < 2; ++tp) {
;                 const v2i ao = TR4(ATL + (2 * q + tp) * 128 + 8 * s16), ah = TR4(ATL + 1024 + (2 * q + tp) * 128 + 8 * s16);
; #pragma unroll
;                 for (int r = 0; r < 4; ++r) {
;                     const v2i d = TR4(ldsb + BUF[st % 3] + 2048 * tp + roff[r]);
;                     accH[r] = __builtin_amdgcn_sdot8(d.x, ah.x, accH[r], false); accH[r] = __builtin_amdgcn_sdot8(d.y, ah.y, accH[r], false);
;                     accL[r] = __builtin_amdgcn_sdot8(d.x, ao.x, accL[r], false); accL[r] = __builtin_amdgcn_sdot8(d.y, ao.y, accL[r], false);
;                 }
;             }
;             asm volatile("s_waitcnt lgkmcnt(0)" ::: "memory");
;     ...
;         {
;             float4 v[4]; float ss = 0.f;
; #pragma unroll
;             for (int jq = 0; jq < 4; ++jq) { typedef unsigned u2v __attribute__((ext_vector_type(2))); const u2v pw = *(const LAS u2v*)(STASH + 4 * lane + 256 * jq); const uint2 hw = hv[jq];
;                 v[jq] = make_float4(__uint_as_float(hw.x << 16) + __uint_as_float(pw.x << 16), __uint_as_float(hw.x & 0xffff0000u) + __uint_as_float(pw.x & 0xffff0000u),
;                                     __uint_as_float(hw.y << 16) + __uint_as_float(pw.y << 16), __uint_as_float(hw.y & 0xffff0000u) + __uint_as_float(pw.y & 0xffff0000u));
;                 ss += v[jq].x * v[jq].x + v[jq].y * v[jq].y + v[jq].z * v[jq].z + v[jq].w * v[jq].w; }
;             ss = wave_sum(ss);
;             const float r3 = rsqrtf(ss * (1.f / D) + EPS);
	v_lshlrev_b32_e32 v236, 16, v194
	v_and_b32_e32 v237, 0xffff0000, v194
	v_lshlrev_b32_e32 v142, 16, v202
	v_and_b32_e32 v143, 0xffff0000, v202
	v_add_f32_e32 v236, v236, v142
	v_add_f32_e32 v237, v237, v143
	v_lshlrev_b32_e32 v238, 16, v195
	v_and_b32_e32 v239, 0xffff0000, v195
	v_lshlrev_b32_e32 v142, 16, v203
	v_and_b32_e32 v143, 0xffff0000, v203
	v_add_f32_e32 v238, v238, v142
	v_add_f32_e32 v239, v239, v143
	v_lshlrev_b32_e32 v240, 16, v196
	v_and_b32_e32 v241, 0xffff0000, v196
	v_lshlrev_b32_e32 v142, 16, v204
	v_and_b32_e32 v143, 0xffff0000, v204
	v_add_f32_e32 v240, v240, v142
	v_add_f32_e32 v241, v241, v143
	v_lshlrev_b32_e32 v242, 16, v197
	v_and_b32_e32 v243, 0xffff0000, v197
	v_lshlrev_b32_e32 v142, 16, v205
	v_and_b32_e32 v143, 0xffff0000, v205
	v_add_f32_e32 v242, v242, v142
	v_add_f32_e32 v243, v243, v143
	v_lshlrev_b32_e32 v244, 16, v198
	v_and_b32_e32 v245, 0xffff0000, v198
	v_lshlrev_b32_e32 v142, 16, v206
	v_and_b32_e32 v143, 0xffff0000, v206
	v_add_f32_e32 v244, v244, v142
	v_add_f32_e32 v245, v245, v143
	v_lshlrev_b32_e32 v246, 16, v199
	v_and_b32_e32 v247, 0xffff0000, v199
	v_lshlrev_b32_e32 v142, 16, v207
	v_and_b32_e32 v143, 0xffff0000, v207
	v_add_f32_e32 v246, v246, v142
	v_add_f32_e32 v247, v247, v143
	v_lshlrev_b32_e32 v248, 16, v200
	v_and_b32_e32 v249, 0xffff0000, v200
	v_lshlrev_b32_e32 v142, 16, v208
	v_and_b32_e32 v143, 0xffff0000, v208
	v_add_f32_e32 v248, v248, v142
	v_add_f32_e32 v249, v249, v143
	v_lshlrev_b32_e32 v250, 16, v201
	v_and_b32_e32 v251, 0xffff0000, v201
	v_lshlrev_b32_e32 v142, 16, v209
	v_and_b32_e32 v143, 0xffff0000, v209
	v_add_f32_e32 v250, v250, v142
	v_add_f32_e32 v251, v251, v143
	v_mov_b32_e32 v144, 0
	v_mul_f32_e32 v145, v236, v236
	v_fmac_f32_e32 v145, v237, v237
	v_fmac_f32_e32 v145, v238, v238
	v_fmac_f32_e32 v145, v239, v239
	v_add_f32_e32 v144, v144, v145
	v_mul_f32_e32 v145, v240, v240
	v_fmac_f32_e32 v145, v241, v241
	v_fmac_f32_e32 v145, v242, v242
	v_fmac_f32_e32 v145, v243, v243
	v_add_f32_e32 v144, v144, v145
	v_mul_f32_e32 v145, v244, v244
	v_fmac_f32_e32 v145, v245, v245
	v_fmac_f32_e32 v145, v246, v246
	v_fmac_f32_e32 v145, v247, v247
	v_add_f32_e32 v144, v144, v145
	v_mul_f32_e32 v145, v248, v248
	v_fmac_f32_e32 v145, v249, v249
	v_fmac_f32_e32 v145, v250, v250
	v_fmac_f32_e32 v145, v251, v251
	v_add_f32_e32 v144, v144, v145
	s_nop 1
	v_add_f32_dpp v144, v144, v144 quad_perm:[1,0,3,2] row_mask:0xf bank_mask:0xf bound_ctrl:1
	s_nop 1
	v_add_f32_dpp v144, v144, v144 quad_perm:[2,3,0,1] row_mask:0xf bank_mask:0xf bound_ctrl:1
	s_nop 1
	v_add_f32_dpp v144, v144, v144 row_half_mirror row_mask:0xf bank_mask:0xf bound_ctrl:1
	s_nop 1
	v_add_f32_dpp v144, v144, v144 row_mirror row_mask:0xf bank_mask:0xf bound_ctrl:1
	s_nop 1
	v_readlane_b32 s10, v144, 0
	v_readlane_b32 s11, v144, 16
	v_readlane_b32 s14, v144, 32
	v_readlane_b32 s15, v144, 48
	s_nop 3
	v_mov_b32_e32 v144, s11
	v_mov_b32_e32 v145, s15
	v_add_f32_e32 v144, s10, v144
	v_add_f32_e32 v145, s14, v145
	v_add_f32_e32 v144, v144, v145
	v_fmamk_f32 v144, v144, 0x3a800000, v111
	v_rsq_f32_e32 v144, v144
	s_nop 0
	v_mul_f32_e32 v236, v236, v144
	v_mul_f32_e32 v237, v237, v144
	v_mul_f32_e32 v238, v238, v144
	v_mul_f32_e32 v239, v239, v144
	v_mul_f32_e32 v240, v240, v144
	v_mul_f32_e32 v241, v241, v144
	v_mul_f32_e32 v242, v242, v144
	v_mul_f32_e32 v243, v243, v144
	v_mul_f32_e32 v244, v244, v144
	v_mul_f32_e32 v245, v245, v144
	v_mul_f32_e32 v246, v246, v144
	v_mul_f32_e32 v247, v247, v144
	v_mul_f32_e32 v248, v248, v144
	v_mul_f32_e32 v249, v249, v144
	v_mul_f32_e32 v250, v250, v144
	v_mul_f32_e32 v251, v251, v144
	v_dot8c_i32_i4_e32 v38, v122, v48
	v_dot8c_i32_i4_e32 v39, v122, v46
	v_dot8c_i32_i4_e32 v40, v124, v48
	v_dot8c_i32_i4_e32 v41, v124, v46
	v_dot8c_i32_i4_e32 v42, v126, v48
	v_dot8c_i32_i4_e32 v43, v126, v46
	v_dot8c_i32_i4_e32 v44, v128, v48
	v_dot8c_i32_i4_e32 v45, v128, v46
	v_dot8c_i32_i4_e32 v38, v123, v49
	v_dot8c_i32_i4_e32 v39, v123, v47
	v_dot8c_i32_i4_e32 v40, v125, v49
	v_dot8c_i32_i4_e32 v41, v125, v47
	v_dot8c_i32_i4_e32 v42, v127, v49
	v_dot8c_i32_i4_e32 v43, v127, v47
	v_dot8c_i32_i4_e32 v44, v129, v49
	v_dot8c_i32_i4_e32 v45, v129, v47
	v_and_b32_e32 v78, 0xffff, v24
	v_lshrrev_b32_e32 v79, 16, v24
	v_lshl_add_u32 v78, v78, 7, v150
	v_lshl_add_u32 v79, v79, 7, v151
	s_mov_b32 m0, s78
	s_add_i32 s43, s78, 0x400
	global_load_lds_dwordx4 v78, s[50:51]
	s_mov_b32 m0, s43
	s_nop 0
	global_load_lds_dwordx4 v79, s[50:51]
	s_waitcnt vmcnt(9)
	v_add_u32_e32 v54, s98, v59
	v_add_u32_e32 v55, s98, v60
	v_add_u32_e32 v56, s98, v61
	v_add_u32_e32 v57, s98, v62
	ds_read_b64_tr_b4 v[46:47], v160 offset:256
	ds_read_b64_tr_b4 v[48:49], v160 offset:1280
	ds_read_b64_tr_b4 v[122:123], v54
	ds_read_b64_tr_b4 v[124:125], v55
	ds_read_b64_tr_b4 v[126:127], v56
	ds_read_b64_tr_b4 v[128:129], v57
	s_waitcnt lgkmcnt(6)
	v_dot8c_i32_i4_e32 v38, v130, v52
	v_dot8c_i32_i4_e32 v39, v130, v50
	v_dot8c_i32_i4_e32 v40, v132, v52
	v_dot8c_i32_i4_e32 v41, v132, v50
	v_dot8c_i32_i4_e32 v42, v134, v52
	v_dot8c_i32_i4_e32 v43, v134, v50
	v_dot8c_i32_i4_e32 v44, v136, v52
	v_dot8c_i32_i4_e32 v45, v136, v50
	v_dot8c_i32_i4_e32 v38, v131, v53
	v_dot8c_i32_i4_e32 v39, v131, v51
	v_dot8c_i32_i4_e32 v40, v133, v53
	v_dot8c_i32_i4_e32 v41, v133, v51
	v_dot8c_i32_i4_e32 v42, v135, v53
	v_dot8c_i32_i4_e32 v43, v135, v51
	v_dot8c_i32_i4_e32 v44, v137, v53
	v_dot8c_i32_i4_e32 v45, v137, v51
	v_and_b32_e32 v78, 0xffff, v25
	v_lshrrev_b32_e32 v79, 16, v25
	v_lshl_add_u32 v78, v78, 7, v150
	v_lshl_add_u32 v79, v79, 7, v151
	s_mov_b32 m0, s79
	s_add_i32 s43, s79, 0x400
	global_load_lds_dwordx4 v78, s[50:51]
	s_mov_b32 m0, s43
	s_nop 0
	global_load_lds_dwordx4 v79, s[50:51]
	s_waitcnt vmcnt(9)
; #define LAS __attribute__((address_space(3)))
; #define TR4(p_) __builtin_amdgcn_ds_read_tr4_b64_v2i32((LAS v2i*)(p_))
; __device__ __forceinline__ void peer_v_tokens(int j, const LAS unsigned short* EL, const LAS unsigned char* AL  , const LAS float* ASC  , const LAS int* SAL  , ...
;     ...
; #pragma unroll
;         for (int m = 0; m < 2; ++m) {
;             const int idx = lane + 64 * m, tau = idx >> 4, sr = idx & 15, k = 16 * (sr & 7) + 2 * tau + (sr >> 3);
;             const int aq = (int)*(const LAS signed char*)(AL + tl * 128 + k); const int tq = aq + 8;
;             const unsigned lo = (((unsigned)tq & 15u) ^ 8u) * 0x11111111u, hi = ((unsigned)(tq >> 4) & 15u) * 0x11111111u;
;             typedef unsigned u2v __attribute__((ext_vector_type(2)));
;             u2v l2; l2.x = lo; l2.y = lo; u2v h2; h2.x = hi; h2.y = hi;
;             *(LAS u2v*)(ATL + 8 * idx) = l2; *(LAS u2v*)(ATL + 1024 + 8 * idx) = h2;
;         }
;     ...
;         for (int st = 0; st < 16; ++st) {
;             const int p = st >> 2, q = st & 3;
;             if (st < 14) VDMA(st + 2, (st + 2) % 3);
;             if (st < 14) asm volatile("s_waitcnt vmcnt(8)" ::: "memory");
;             else if (st == 14) asm volatile("s_waitcnt vmcnt(4)" ::: "memory");
;             else asm volatile("s_waitcnt vmcnt(0)" ::: "memory");
;             if (q == 0) {
; #pragma unroll
;                 for (int r = 0; r < 4; ++r) { accH[r] = 0; accL[r] = 0; } }
; #pragma unroll
;             for (int tp = 0; tp < 2; ++tp) {
;                 const v2i ao = TR4(ATL + (2 * q + tp) * 128 + 8 * s16), ah = TR4(ATL + 1024 + (2 * q + tp) * 128 + 8 * s16);
; #pragma unroll
;                 for (int r = 0; r < 4; ++r) {
;                     const v2i d = TR4(ldsb + BUF[st % 3] + 2048 * tp + roff[r]);
;                     accH[r] = __builtin_amdgcn_sdot8(d.x, ah.x, accH[r], false); accH[r] = __builtin_amdgcn_sdot8(d.y, ah.y, accH[r], false);
;                     accL[r] = __builtin_amdgcn_sdot8(d.x, ao.x, accL[r], false); accL[r] = __builtin_amdgcn_sdot8(d.y, ao.y, accL[r], false);
;                 }
;             }
;             asm volatile("s_waitcnt lgkmcnt(0)" ::: "memory");
	v_add_u32_e32 v54, s99, v59
	v_add_u32_e32 v55, s99, v60
	v_add_u32_e32 v56, s99, v61
	v_add_u32_e32 v57, s99, v62
	ds_read_b64_tr_b4 v[50:51], v160 offset:384
	ds_read_b64_tr_b4 v[52:53], v160 offset:1408
	ds_read_b64_tr_b4 v[130:131], v54
	ds_read_b64_tr_b4 v[132:133], v55
	ds_read_b64_tr_b4 v[134:135], v56
	ds_read_b64_tr_b4 v[136:137], v57
	s_waitcnt lgkmcnt(6)
	v_dot8c_i32_i4_e32 v38, v122, v48
	v_dot8c_i32_i4_e32 v39, v122, v46
	v_dot8c_i32_i4_e32 v40, v124, v48
	v_dot8c_i32_i4_e32 v41, v124, v46
	v_dot8c_i32_i4_e32 v42, v126, v48
	v_dot8c_i32_i4_e32 v43, v126, v46
	v_dot8c_i32_i4_e32 v44, v128, v48
	v_dot8c_i32_i4_e32 v45, v128, v46
	v_dot8c_i32_i4_e32 v38, v123, v49
	v_dot8c_i32_i4_e32 v39, v123, v47
	v_dot8c_i32_i4_e32 v40, v125, v49
	v_dot8c_i32_i4_e32 v41, v125, v47
	v_dot8c_i32_i4_e32 v42, v127, v49
	v_dot8c_i32_i4_e32 v43, v127, v47
	v_dot8c_i32_i4_e32 v44, v129, v49
	v_dot8c_i32_i4_e32 v45, v129, v47
	s_waitcnt lgkmcnt(15)
	v_and_b32_e32 v78, 0xffff, v26
	v_lshrrev_b32_e32 v79, 16, v26
	v_lshl_add_u32 v78, v78, 7, v150
	v_lshl_add_u32 v79, v79, 7, v151
	s_mov_b32 m0, s98
	s_add_i32 s43, s98, 0x400
	global_load_lds_dwordx4 v78, s[50:51]
	s_mov_b32 m0, s43
	s_nop 0
	global_load_lds_dwordx4 v79, s[50:51]
	s_waitcnt vmcnt(9)
	v_add_u32_e32 v54, s76, v59
	v_add_u32_e32 v55, s76, v60
	v_add_u32_e32 v56, s76, v61
	v_add_u32_e32 v57, s76, v62
	ds_read_b64_tr_b4 v[46:47], v160 offset:512
	ds_read_b64_tr_b4 v[48:49], v160 offset:1536
	ds_read_b64_tr_b4 v[122:123], v54
	ds_read_b64_tr_b4 v[124:125], v55
	ds_read_b64_tr_b4 v[126:127], v56
	ds_read_b64_tr_b4 v[128:129], v57
	s_waitcnt lgkmcnt(6)
	v_dot8c_i32_i4_e32 v38, v130, v52
	v_dot8c_i32_i4_e32 v39, v130, v50
	v_dot8c_i32_i4_e32 v40, v132, v52
	v_dot8c_i32_i4_e32 v41, v132, v50
	v_dot8c_i32_i4_e32 v42, v134, v52
	v_dot8c_i32_i4_e32 v43, v134, v50
	v_dot8c_i32_i4_e32 v44, v136, v52
	v_dot8c_i32_i4_e32 v45, v136, v50
	v_dot8c_i32_i4_e32 v38, v131, v53
	v_dot8c_i32_i4_e32 v39, v131, v51
	v_dot8c_i32_i4_e32 v40, v133, v53
	v_dot8c_i32_i4_e32 v41, v133, v51
	v_dot8c_i32_i4_e32 v42, v135, v53
	v_dot8c_i32_i4_e32 v43, v135, v51
	v_dot8c_i32_i4_e32 v44, v137, v53
	v_dot8c_i32_i4_e32 v45, v137, v51
	v_and_b32_e32 v78, 0xffff, v27
	v_lshrrev_b32_e32 v79, 16, v27
	v_lshl_add_u32 v78, v78, 7, v150
	v_lshl_add_u32 v79, v79, 7, v151
	s_mov_b32 m0, s99
	s_add_i32 s43, s99, 0x400
	global_load_lds_dwordx4 v78, s[50:51]
	s_mov_b32 m0, s43
	s_nop 0
	global_load_lds_dwordx4 v79, s[50:51]
	s_waitcnt vmcnt(8)
	v_add_u32_e32 v54, s77, v59
	v_add_u32_e32 v55, s77, v60
	v_add_u32_e32 v56, s77, v61
	v_add_u32_e32 v57, s77, v62
	ds_read_b64_tr_b4 v[50:51], v160 offset:640
	ds_read_b64_tr_b4 v[52:53], v160 offset:1664
	ds_read_b64_tr_b4 v[130:131], v54
	ds_read_b64_tr_b4 v[132:133], v55
	ds_read_b64_tr_b4 v[134:135], v56
	ds_read_b64_tr_b4 v[136:137], v57
	s_waitcnt lgkmcnt(6)
	v_dot8c_i32_i4_e32 v38, v122, v48
	v_dot8c_i32_i4_e32 v39, v122, v46
	v_dot8c_i32_i4_e32 v40, v124, v48
	v_dot8c_i32_i4_e32 v41, v124, v46
	v_dot8c_i32_i4_e32 v42, v126, v48
	v_dot8c_i32_i4_e32 v43, v126, v46
	v_dot8c_i32_i4_e32 v44, v128, v48
	v_dot8c_i32_i4_e32 v45, v128, v46
	v_dot8c_i32_i4_e32 v38, v123, v49
	v_dot8c_i32_i4_e32 v39, v123, v47
	v_dot8c_i32_i4_e32 v40, v125, v49
	v_dot8c_i32_i4_e32 v41, v125, v47
	v_dot8c_i32_i4_e32 v42, v127, v49
	v_dot8c_i32_i4_e32 v43, v127, v47
	v_dot8c_i32_i4_e32 v44, v129, v49
	v_dot8c_i32_i4_e32 v45, v129, v47
	s_waitcnt lgkmcnt(15)
	v_add_u32_e32 v143, 8, v139
	v_and_b32_e32 v142, 15, v143
	v_xor_b32_e32 v142, 8, v142
	v_bfe_u32 v144, v143, 4, 4
	v_mul_lo_u32 v142, v142, s92
	v_mul_lo_u32 v144, v144, s92
	v_mov_b32_e32 v143, v142
	v_mov_b32_e32 v145, v144
	ds_write2st64_b64 v159, v[142:143], v[144:145] offset1:2
	v_and_b32_e32 v78, 0xffff, v28
	v_lshrrev_b32_e32 v79, 16, v28
	v_lshl_add_u32 v78, v78, 7, v150
	v_lshl_add_u32 v79, v79, 7, v151
	s_mov_b32 m0, s76
	s_add_i32 s43, s76, 0x400
	global_load_lds_dwordx4 v78, s[50:51]
	s_mov_b32 m0, s43
	s_nop 0
	global_load_lds_dwordx4 v79, s[50:51]
	s_waitcnt vmcnt(8)
	v_add_u32_e32 v54, s78, v59
	v_add_u32_e32 v55, s78, v60
	v_add_u32_e32 v56, s78, v61
	v_add_u32_e32 v57, s78, v62
	ds_read_b64_tr_b4 v[46:47], v160 offset:768
	ds_read_b64_tr_b4 v[48:49], v160 offset:1792
	ds_read_b64_tr_b4 v[122:123], v54
	ds_read_b64_tr_b4 v[124:125], v55
	ds_read_b64_tr_b4 v[126:127], v56
	ds_read_b64_tr_b4 v[128:129], v57
	s_waitcnt lgkmcnt(7)
	v_dot8c_i32_i4_e32 v38, v130, v52
	v_dot8c_i32_i4_e32 v39, v130, v50
	v_dot8c_i32_i4_e32 v40, v132, v52
	v_dot8c_i32_i4_e32 v41, v132, v50
	v_dot8c_i32_i4_e32 v42, v134, v52
	v_dot8c_i32_i4_e32 v43, v134, v50
	v_dot8c_i32_i4_e32 v44, v136, v52
	v_dot8c_i32_i4_e32 v45, v136, v50
	v_dot8c_i32_i4_e32 v38, v131, v53
	v_dot8c_i32_i4_e32 v39, v131, v51
	v_dot8c_i32_i4_e32 v40, v133, v53
	v_dot8c_i32_i4_e32 v41, v133, v51
	v_dot8c_i32_i4_e32 v42, v135, v53
	v_dot8c_i32_i4_e32 v43, v135, v51
	v_dot8c_i32_i4_e32 v44, v137, v53
	v_dot8c_i32_i4_e32 v45, v137, v51
	v_and_b32_e32 v78, 0xffff, v29
	v_lshrrev_b32_e32 v79, 16, v29
	v_lshl_add_u32 v78, v78, 7, v150
	v_lshl_add_u32 v79, v79, 7, v151
	s_mov_b32 m0, s77
	s_add_i32 s43, s77, 0x400
	global_load_lds_dwordx4 v78, s[50:51]
	s_mov_b32 m0, s43
	s_nop 0
	global_load_lds_dwordx4 v79, s[50:51]
	s_waitcnt vmcnt(8)
	v_add_u32_e32 v54, s79, v59
	v_add_u32_e32 v55, s79, v60
	v_add_u32_e32 v56, s79, v61
	v_add_u32_e32 v57, s79, v62
	ds_read_b64_tr_b4 v[50:51], v160 offset:896
	ds_read_b64_tr_b4 v[52:53], v160 offset:1920
	ds_read_b64_tr_b4 v[130:131], v54
	ds_read_b64_tr_b4 v[132:133], v55
	ds_read_b64_tr_b4 v[134:135], v56
	ds_read_b64_tr_b4 v[136:137], v57
	s_waitcnt lgkmcnt(6)
; __device__ __forceinline__ bf16 f2bf(float f) { return (bf16)f2bfu(f); }
; #define TR4(p_) __builtin_amdgcn_ds_read_tr4_b64_v2i32((LAS v2i*)(p_))
; __device__ __forceinline__ void peer_v_tokens(int j, const LAS unsigned short* EL, const LAS unsigned char* AL  , const LAS float* ASC  , const LAS int* SAL  , ...
;     ...
;         for (int st = 0; st < 16; ++st) {
;             const int p = st >> 2, q = st & 3;
;             if (st < 14) VDMA(st + 2, (st + 2) % 3);
;             if (st < 14) asm volatile("s_waitcnt vmcnt(8)" ::: "memory");
;             else if (st == 14) asm volatile("s_waitcnt vmcnt(4)" ::: "memory");
;             else asm volatile("s_waitcnt vmcnt(0)" ::: "memory");
;             if (q == 0) {
; #pragma unroll
;                 for (int r = 0; r < 4; ++r) { accH[r] = 0; accL[r] = 0; } }
; #pragma unroll
;             for (int tp = 0; tp < 2; ++tp) {
;                 const v2i ao = TR4(ATL + (2 * q + tp) * 128 + 8 * s16), ah = TR4(ATL + 1024 + (2 * q + tp) * 128 + 8 * s16);
; #pragma unroll
;                 for (int r = 0; r < 4; ++r) {
;                     const v2i d = TR4(ldsb + BUF[st % 3] + 2048 * tp + roff[r]);
;                     accH[r] = __builtin_amdgcn_sdot8(d.x, ah.x, accH[r], false); accH[r] = __builtin_amdgcn_sdot8(d.y, ah.y, accH[r], false);
;                     accL[r] = __builtin_amdgcn_sdot8(d.x, ao.x, accL[r], false); accL[r] = __builtin_amdgcn_sdot8(d.y, ao.y, accL[r], false);
;                 }
;             }
;             asm volatile("s_waitcnt lgkmcnt(0)" ::: "memory");
;             if (q == 3) {
; #pragma unroll
;                 for (int r = 0; r < 4; ++r) STASH[256 * p + 16 * (grp + 4 * r) + pc] = f2bf(asc * (float)(2 * ((accH[r] << 4) + accL[r]) + sa));
;             }
;         }
;     ...
;             float4* op = (float4*)(outp + (size_t)t * D) + lane;
; #pragma unroll
;             for (int jq = 0; jq < 4; ++jq) { typedef float f4v __attribute__((ext_vector_type(4))); f4v o4; o4.x = v[jq].x * r3 * gv[jq].x; o4.y = v[jq].y * r3 * gv[jq].y; o4.z = v[jq].z * r3 * gv[jq].z; o4.w = v[jq].w * r3 * gv[jq].w;
;                 __builtin_nontemporal_store(o4, (f4v*)op + 64 * jq); }
	v_dot8c_i32_i4_e32 v38, v122, v48
	v_dot8c_i32_i4_e32 v39, v122, v46
	v_dot8c_i32_i4_e32 v40, v124, v48
	v_dot8c_i32_i4_e32 v41, v124, v46
	v_dot8c_i32_i4_e32 v42, v126, v48
	v_dot8c_i32_i4_e32 v43, v126, v46
	v_dot8c_i32_i4_e32 v44, v128, v48
	v_dot8c_i32_i4_e32 v45, v128, v46
	v_dot8c_i32_i4_e32 v38, v123, v49
	v_dot8c_i32_i4_e32 v39, v123, v47
	v_dot8c_i32_i4_e32 v40, v125, v49
	v_dot8c_i32_i4_e32 v41, v125, v47
	v_dot8c_i32_i4_e32 v42, v127, v49
	v_dot8c_i32_i4_e32 v43, v127, v47
	v_dot8c_i32_i4_e32 v44, v129, v49
	v_dot8c_i32_i4_e32 v45, v129, v47
	v_and_b32_e32 v78, 0xffff, v30
	v_lshrrev_b32_e32 v79, 16, v30
	v_lshl_add_u32 v78, v78, 7, v150
	v_lshl_add_u32 v79, v79, 7, v151
	s_mov_b32 m0, s78
	s_add_i32 s43, s78, 0x400
	global_load_lds_dwordx4 v78, s[50:51]
	s_mov_b32 m0, s43
	s_nop 0
	global_load_lds_dwordx4 v79, s[50:51]
	s_waitcnt vmcnt(8)
	v_add_u32_e32 v54, s98, v59
	v_add_u32_e32 v55, s98, v60
	v_add_u32_e32 v56, s98, v61
	v_add_u32_e32 v57, s98, v62
	ds_read_b64_tr_b4 v[46:47], v160
	ds_read_b64_tr_b4 v[48:49], v160 offset:1024
	ds_read_b64_tr_b4 v[122:123], v54
	ds_read_b64_tr_b4 v[124:125], v55
	ds_read_b64_tr_b4 v[126:127], v56
	ds_read_b64_tr_b4 v[128:129], v57
	s_waitcnt lgkmcnt(6)
	v_dot8c_i32_i4_e32 v38, v130, v52
	v_dot8c_i32_i4_e32 v39, v130, v50
	v_dot8c_i32_i4_e32 v40, v132, v52
	v_dot8c_i32_i4_e32 v41, v132, v50
	v_dot8c_i32_i4_e32 v42, v134, v52
	v_dot8c_i32_i4_e32 v43, v134, v50
	v_dot8c_i32_i4_e32 v44, v136, v52
	v_dot8c_i32_i4_e32 v45, v136, v50
	v_dot8c_i32_i4_e32 v38, v131, v53
	v_dot8c_i32_i4_e32 v39, v131, v51
	v_dot8c_i32_i4_e32 v40, v133, v53
	v_dot8c_i32_i4_e32 v41, v133, v51
	v_dot8c_i32_i4_e32 v42, v135, v53
	v_dot8c_i32_i4_e32 v43, v135, v51
	v_dot8c_i32_i4_e32 v44, v137, v53
	v_dot8c_i32_i4_e32 v45, v137, v51
	s_nop 3
	s_waitcnt lgkmcnt(15)
	v_lshlrev_b32_e32 v38, 5, v38
	v_lshlrev_b32_e32 v39, 1, v39
	v_add3_u32 v38, v39, v229, v38
	v_cvt_f32_i32_e32 v38, v38
	v_mul_f32_e32 v38, v228, v38
	v_lshlrev_b32_e32 v40, 5, v40
	v_lshlrev_b32_e32 v41, 1, v41
	v_add3_u32 v40, v41, v229, v40
	v_cvt_f32_i32_e32 v40, v40
	v_mul_f32_e32 v40, v228, v40
	v_lshlrev_b32_e32 v42, 5, v42
	v_lshlrev_b32_e32 v43, 1, v43
	v_add3_u32 v42, v43, v229, v42
	v_cvt_f32_i32_e32 v42, v42
	v_mul_f32_e32 v42, v228, v42
	v_lshlrev_b32_e32 v44, 5, v44
	v_lshlrev_b32_e32 v45, 1, v45
	v_add3_u32 v44, v45, v229, v44
	v_cvt_f32_i32_e32 v44, v44
	v_mul_f32_e32 v44, v228, v44
	v_cvt_pk_bf16_f32 v182, v38, v40
	v_cvt_pk_bf16_f32 v183, v42, v44
	ds_read_b128 v[252:255], v156 offset:1024
	s_add_i32 s44, s40, 32
	s_ashr_i32 s45, s44, 31
	s_lshl_b64 s[44:45], s[44:45], 12
	v_lshl_add_u64 v[80:81], v[36:37], 0, s[44:45]
	s_waitcnt lgkmcnt(0)
	v_mul_f32_e32 v222, v222, v252
	v_mul_f32_e32 v223, v223, v253
	v_mul_f32_e32 v224, v224, v254
	v_mul_f32_e32 v225, v225, v255
	global_store_dwordx4 v[80:81], v[222:225], off offset:3072 nt
	ds_read_b128 v[252:255], v155
	s_add_i32 s44, s40, 40
	s_ashr_i32 s45, s44, 31
	s_lshl_b64 s[44:45], s[44:45], 12
	v_lshl_add_u64 v[80:81], v[36:37], 0, s[44:45]
	s_waitcnt lgkmcnt(0)
	v_mul_f32_e32 v236, v236, v252
	v_mul_f32_e32 v237, v237, v253
	v_mul_f32_e32 v238, v238, v254
	v_mul_f32_e32 v239, v239, v255
	global_store_dwordx4 v[80:81], v[236:239], off nt
	v_add_u32_e32 v147, 8, v140
	v_and_b32_e32 v146, 15, v147
	v_xor_b32_e32 v146, 8, v146
	v_bfe_u32 v148, v147, 4, 4
	v_mul_lo_u32 v146, v146, s92
	v_mul_lo_u32 v148, v148, s92
	v_mov_b32_e32 v147, v146
	v_mov_b32_e32 v149, v148
	ds_write2st64_b64 v77, v[146:147], v[148:149] offset1:2
	v_add_u32_e32 v138, 0x1800, v74
	ds_read_u8 v139, v138
	v_add_u32_e32 v141, 0x1800, v73
	ds_read_u8 v140, v141
	s_add_i32 s43, s67, 224
	v_mov_b32_e32 v138, s43
	ds_read2st64_b32 v[228:229], v138 offset1:1
	ds_read_b128 v[18:21], v227 offset:12288
	ds_read_b128 v[22:25], v227 offset:12304
	v_add_u32_e32 v152, 0x600000, v63
	v_add_u32_e32 v153, 0x600000, v64
	v_mov_b32_e32 v38, 0
	v_mov_b32_e32 v39, 0
	v_mov_b32_e32 v40, 0
	v_mov_b32_e32 v41, 0
	v_mov_b32_e32 v42, 0
	v_mov_b32_e32 v43, 0
	v_mov_b32_e32 v44, 0
	v_mov_b32_e32 v45, 0
	v_and_b32_e32 v78, 0xffff, v31
	v_lshrrev_b32_e32 v79, 16, v31
	v_lshl_add_u32 v78, v78, 7, v150
	v_lshl_add_u32 v79, v79, 7, v151
	s_mov_b32 m0, s79
	s_add_i32 s43, s79, 0x400
	global_load_lds_dwordx4 v78, s[50:51]
	s_mov_b32 m0, s43
	s_nop 0
	global_load_lds_dwordx4 v79, s[50:51]
	s_waitcnt vmcnt(10)
	v_add_u32_e32 v54, s99, v59
	v_add_u32_e32 v55, s99, v60
	v_add_u32_e32 v56, s99, v61
	v_add_u32_e32 v57, s99, v62
	ds_read_b64_tr_b4 v[50:51], v160 offset:128
	ds_read_b64_tr_b4 v[52:53], v160 offset:1152
	ds_read_b64_tr_b4 v[130:131], v54
	ds_read_b64_tr_b4 v[132:133], v55
	ds_read_b64_tr_b4 v[134:135], v56
	ds_read_b64_tr_b4 v[136:137], v57
	s_waitcnt lgkmcnt(14)
	v_dot8c_i32_i4_e32 v38, v122, v48
	v_dot8c_i32_i4_e32 v39, v122, v46
	v_dot8c_i32_i4_e32 v40, v124, v48
	v_dot8c_i32_i4_e32 v41, v124, v46
	v_dot8c_i32_i4_e32 v42, v126, v48
	v_dot8c_i32_i4_e32 v43, v126, v46
	v_dot8c_i32_i4_e32 v44, v128, v48
	v_dot8c_i32_i4_e32 v45, v128, v46
	v_dot8c_i32_i4_e32 v38, v123, v49
	v_dot8c_i32_i4_e32 v39, v123, v47
	v_dot8c_i32_i4_e32 v40, v125, v49
	v_dot8c_i32_i4_e32 v41, v125, v47
	v_dot8c_i32_i4_e32 v42, v127, v49
	v_dot8c_i32_i4_e32 v43, v127, v47
	v_dot8c_i32_i4_e32 v44, v129, v49
	v_dot8c_i32_i4_e32 v45, v129, v47
	v_and_b32_e32 v78, 0xffff, v32
	v_lshrrev_b32_e32 v79, 16, v32
	v_lshl_add_u32 v78, v78, 7, v150
	v_lshl_add_u32 v79, v79, 7, v151
	s_mov_b32 m0, s98
	s_add_i32 s43, s98, 0x400
	global_load_lds_dwordx4 v78, s[50:51]
	s_mov_b32 m0, s43
	s_nop 0
	global_load_lds_dwordx4 v79, s[50:51]
	s_waitcnt vmcnt(10)
; #define TR4(p_) __builtin_amdgcn_ds_read_tr4_b64_v2i32((LAS v2i*)(p_))
; #define VDMA(st_, k_) do { _Pragma("unroll") for (int i_ = 0; i_ < 4; ++i_) { \
;         const unsigned off_ = (unsigned)((st_) >> 2) * (16384u * 128u) + (PE_ID(E, 4 * ((st_) & 3) + i_) << 7) + ((i_ & 1) ? cx1 : cx0); \
;         __builtin_amdgcn_global_load_lds((const unsigned*)(V4 + off_), (LAS unsigned*)(ldsb + BUF[k_] + 1024 * i_), 16, 0, 0); } } while (0)
; __device__ __forceinline__ void peer_v_tokens(int j, const LAS unsigned short* EL, const LAS unsigned char* AL  , const LAS float* ASC  , const LAS int* SAL  , ...
;     ...
;         for (int st = 0; st < 16; ++st) {
;             const int p = st >> 2, q = st & 3;
;             if (st < 14) VDMA(st + 2, (st + 2) % 3);
;             if (st < 14) asm volatile("s_waitcnt vmcnt(8)" ::: "memory");
;             else if (st == 14) asm volatile("s_waitcnt vmcnt(4)" ::: "memory");
;             else asm volatile("s_waitcnt vmcnt(0)" ::: "memory");
;             if (q == 0) {
; #pragma unroll
;                 for (int r = 0; r < 4; ++r) { accH[r] = 0; accL[r] = 0; } }
; #pragma unroll
;             for (int tp = 0; tp < 2; ++tp) {
;                 const v2i ao = TR4(ATL + (2 * q + tp) * 128 + 8 * s16), ah = TR4(ATL + 1024 + (2 * q + tp) * 128 + 8 * s16);
; #pragma unroll
;                 for (int r = 0; r < 4; ++r) {
;                     const v2i d = TR4(ldsb + BUF[st % 3] + 2048 * tp + roff[r]);
;                     accH[r] = __builtin_amdgcn_sdot8(d.x, ah.x, accH[r], false); accH[r] = __builtin_amdgcn_sdot8(d.y, ah.y, accH[r], false);
;                     accL[r] = __builtin_amdgcn_sdot8(d.x, ao.x, accL[r], false); accL[r] = __builtin_amdgcn_sdot8(d.y, ao.y, accL[r], false);
;                 }
;             }
;             asm volatile("s_waitcnt lgkmcnt(0)" ::: "memory");
	v_add_u32_e32 v54, s76, v59
	v_add_u32_e32 v55, s76, v60
	v_add_u32_e32 v56, s76, v61
	v_add_u32_e32 v57, s76, v62
	ds_read_b64_tr_b4 v[46:47], v160 offset:256
	ds_read_b64_tr_b4 v[48:49], v160 offset:1280
	ds_read_b64_tr_b4 v[122:123], v54
	ds_read_b64_tr_b4 v[124:125], v55
	ds_read_b64_tr_b4 v[126:127], v56
	ds_read_b64_tr_b4 v[128:129], v57
	s_waitcnt lgkmcnt(6)
	v_dot8c_i32_i4_e32 v38, v130, v52
	v_dot8c_i32_i4_e32 v39, v130, v50
	v_dot8c_i32_i4_e32 v40, v132, v52
	v_dot8c_i32_i4_e32 v41, v132, v50
	v_dot8c_i32_i4_e32 v42, v134, v52
	v_dot8c_i32_i4_e32 v43, v134, v50
	v_dot8c_i32_i4_e32 v44, v136, v52
	v_dot8c_i32_i4_e32 v45, v136, v50
	v_dot8c_i32_i4_e32 v38, v131, v53
	v_dot8c_i32_i4_e32 v39, v131, v51
	v_dot8c_i32_i4_e32 v40, v133, v53
	v_dot8c_i32_i4_e32 v41, v133, v51
	v_dot8c_i32_i4_e32 v42, v135, v53
	v_dot8c_i32_i4_e32 v43, v135, v51
	v_dot8c_i32_i4_e32 v44, v137, v53
	v_dot8c_i32_i4_e32 v45, v137, v51
	v_and_b32_e32 v78, 0xffff, v33
	v_lshrrev_b32_e32 v79, 16, v33
	v_lshl_add_u32 v78, v78, 7, v150
	v_lshl_add_u32 v79, v79, 7, v151
	s_mov_b32 m0, s99
	s_add_i32 s43, s99, 0x400
	global_load_lds_dwordx4 v78, s[50:51]
	s_mov_b32 m0, s43
	s_nop 0
	global_load_lds_dwordx4 v79, s[50:51]
	s_waitcnt vmcnt(10)
	v_add_u32_e32 v54, s77, v59
	v_add_u32_e32 v55, s77, v60
	v_add_u32_e32 v56, s77, v61
	v_add_u32_e32 v57, s77, v62
	ds_read_b64_tr_b4 v[50:51], v160 offset:384
	ds_read_b64_tr_b4 v[52:53], v160 offset:1408
	ds_read_b64_tr_b4 v[130:131], v54
	ds_read_b64_tr_b4 v[132:133], v55
	ds_read_b64_tr_b4 v[134:135], v56
	ds_read_b64_tr_b4 v[136:137], v57
	s_waitcnt lgkmcnt(6)
	v_dot8c_i32_i4_e32 v38, v122, v48
	v_dot8c_i32_i4_e32 v39, v122, v46
	v_dot8c_i32_i4_e32 v40, v124, v48
	v_dot8c_i32_i4_e32 v41, v124, v46
	v_dot8c_i32_i4_e32 v42, v126, v48
	v_dot8c_i32_i4_e32 v43, v126, v46
	v_dot8c_i32_i4_e32 v44, v128, v48
	v_dot8c_i32_i4_e32 v45, v128, v46
	v_dot8c_i32_i4_e32 v38, v123, v49
	v_dot8c_i32_i4_e32 v39, v123, v47
	v_dot8c_i32_i4_e32 v40, v125, v49
	v_dot8c_i32_i4_e32 v41, v125, v47
	v_dot8c_i32_i4_e32 v42, v127, v49
	v_dot8c_i32_i4_e32 v43, v127, v47
	v_dot8c_i32_i4_e32 v44, v129, v49
	v_dot8c_i32_i4_e32 v45, v129, v47
	s_waitcnt lgkmcnt(15)
	v_and_b32_e32 v78, 0xffff, v18
	v_lshrrev_b32_e32 v79, 16, v18
	v_lshl_add_u32 v78, v78, 7, v152
	v_lshl_add_u32 v79, v79, 7, v153
	s_mov_b32 m0, s76
	s_add_i32 s43, s76, 0x400
	global_load_lds_dwordx4 v78, s[50:51]
	s_mov_b32 m0, s43
	s_nop 0
	global_load_lds_dwordx4 v79, s[50:51]
	s_waitcnt vmcnt(10)
	v_add_u32_e32 v54, s78, v59
	v_add_u32_e32 v55, s78, v60
	v_add_u32_e32 v56, s78, v61
	v_add_u32_e32 v57, s78, v62
	ds_read_b64_tr_b4 v[46:47], v160 offset:512
	ds_read_b64_tr_b4 v[48:49], v160 offset:1536
	ds_read_b64_tr_b4 v[122:123], v54
	ds_read_b64_tr_b4 v[124:125], v55
	ds_read_b64_tr_b4 v[126:127], v56
	ds_read_b64_tr_b4 v[128:129], v57
	s_waitcnt lgkmcnt(6)
	v_dot8c_i32_i4_e32 v38, v130, v52
	v_dot8c_i32_i4_e32 v39, v130, v50
	v_dot8c_i32_i4_e32 v40, v132, v52
	v_dot8c_i32_i4_e32 v41, v132, v50
	v_dot8c_i32_i4_e32 v42, v134, v52
	v_dot8c_i32_i4_e32 v43, v134, v50
	v_dot8c_i32_i4_e32 v44, v136, v52
	v_dot8c_i32_i4_e32 v45, v136, v50
	v_dot8c_i32_i4_e32 v38, v131, v53
	v_dot8c_i32_i4_e32 v39, v131, v51
	v_dot8c_i32_i4_e32 v40, v133, v53
	v_dot8c_i32_i4_e32 v41, v133, v51
	v_dot8c_i32_i4_e32 v42, v135, v53
	v_dot8c_i32_i4_e32 v43, v135, v51
	v_dot8c_i32_i4_e32 v44, v137, v53
	v_dot8c_i32_i4_e32 v45, v137, v51
	v_and_b32_e32 v78, 0xffff, v19
	v_lshrrev_b32_e32 v79, 16, v19
	v_lshl_add_u32 v78, v78, 7, v152
	v_lshl_add_u32 v79, v79, 7, v153
	s_mov_b32 m0, s77
	s_add_i32 s43, s77, 0x400
	global_load_lds_dwordx4 v78, s[50:51]
	s_mov_b32 m0, s43
	s_nop 0
	global_load_lds_dwordx4 v79, s[50:51]
	s_waitcnt vmcnt(8)
	v_add_u32_e32 v54, s79, v59
	v_add_u32_e32 v55, s79, v60
	v_add_u32_e32 v56, s79, v61
	v_add_u32_e32 v57, s79, v62
	ds_read_b64_tr_b4 v[50:51], v160 offset:640
	ds_read_b64_tr_b4 v[52:53], v160 offset:1664
	ds_read_b64_tr_b4 v[130:131], v54
	ds_read_b64_tr_b4 v[132:133], v55
	ds_read_b64_tr_b4 v[134:135], v56
	ds_read_b64_tr_b4 v[136:137], v57
	s_waitcnt lgkmcnt(6)
	v_dot8c_i32_i4_e32 v38, v122, v48
	v_dot8c_i32_i4_e32 v39, v122, v46
	v_dot8c_i32_i4_e32 v40, v124, v48
	v_dot8c_i32_i4_e32 v41, v124, v46
	v_dot8c_i32_i4_e32 v42, v126, v48
	v_dot8c_i32_i4_e32 v43, v126, v46
	v_dot8c_i32_i4_e32 v44, v128, v48
	v_dot8c_i32_i4_e32 v45, v128, v46
	v_dot8c_i32_i4_e32 v38, v123, v49
	v_dot8c_i32_i4_e32 v39, v123, v47
	v_dot8c_i32_i4_e32 v40, v125, v49
	v_dot8c_i32_i4_e32 v41, v125, v47
	v_dot8c_i32_i4_e32 v42, v127, v49
	v_dot8c_i32_i4_e32 v43, v127, v47
	v_dot8c_i32_i4_e32 v44, v129, v49
	v_dot8c_i32_i4_e32 v45, v129, v47
	s_waitcnt lgkmcnt(15)
	v_add_u32_e32 v143, 8, v139
	v_and_b32_e32 v142, 15, v143
	v_xor_b32_e32 v142, 8, v142
	v_bfe_u32 v144, v143, 4, 4
	v_mul_lo_u32 v142, v142, s92
	v_mul_lo_u32 v144, v144, s92
	v_mov_b32_e32 v143, v142
	v_mov_b32_e32 v145, v144
	ds_write2st64_b64 v159, v[142:143], v[144:145] offset1:2
	v_and_b32_e32 v78, 0xffff, v20
	v_lshrrev_b32_e32 v79, 16, v20
	v_lshl_add_u32 v78, v78, 7, v152
	v_lshl_add_u32 v79, v79, 7, v153
	s_mov_b32 m0, s78
	s_add_i32 s43, s78, 0x400
	global_load_lds_dwordx4 v78, s[50:51]
	s_mov_b32 m0, s43
	s_nop 0
	global_load_lds_dwordx4 v79, s[50:51]
	s_waitcnt vmcnt(8)
	v_add_u32_e32 v54, s98, v59
	v_add_u32_e32 v55, s98, v60
	v_add_u32_e32 v56, s98, v61
	v_add_u32_e32 v57, s98, v62
	ds_read_b64_tr_b4 v[46:47], v160 offset:768
	ds_read_b64_tr_b4 v[48:49], v160 offset:1792
	ds_read_b64_tr_b4 v[122:123], v54
	ds_read_b64_tr_b4 v[124:125], v55
	ds_read_b64_tr_b4 v[126:127], v56
	ds_read_b64_tr_b4 v[128:129], v57
	s_waitcnt lgkmcnt(7)
; __device__ __forceinline__ bf16 f2bf(float f) { return (bf16)f2bfu(f); }
; #define TR4(p_) __builtin_amdgcn_ds_read_tr4_b64_v2i32((LAS v2i*)(p_))
; __device__ __forceinline__ void peer_v_tokens(int j, const LAS unsigned short* EL, const LAS unsigned char* AL  , const LAS float* ASC  , const LAS int* SAL  , ...
;     ...
;         for (int st = 0; st < 16; ++st) {
;             const int p = st >> 2, q = st & 3;
;             if (st < 14) VDMA(st + 2, (st + 2) % 3);
;             if (st < 14) asm volatile("s_waitcnt vmcnt(8)" ::: "memory");
;             else if (st == 14) asm volatile("s_waitcnt vmcnt(4)" ::: "memory");
;             else asm volatile("s_waitcnt vmcnt(0)" ::: "memory");
;             if (q == 0) {
; #pragma unroll
;                 for (int r = 0; r < 4; ++r) { accH[r] = 0; accL[r] = 0; } }
; #pragma unroll
;             for (int tp = 0; tp < 2; ++tp) {
;                 const v2i ao = TR4(ATL + (2 * q + tp) * 128 + 8 * s16), ah = TR4(ATL + 1024 + (2 * q + tp) * 128 + 8 * s16);
; #pragma unroll
;                 for (int r = 0; r < 4; ++r) {
;                     const v2i d = TR4(ldsb + BUF[st % 3] + 2048 * tp + roff[r]);
;                     accH[r] = __builtin_amdgcn_sdot8(d.x, ah.x, accH[r], false); accH[r] = __builtin_amdgcn_sdot8(d.y, ah.y, accH[r], false);
;                     accL[r] = __builtin_amdgcn_sdot8(d.x, ao.x, accL[r], false); accL[r] = __builtin_amdgcn_sdot8(d.y, ao.y, accL[r], false);
;                 }
;             }
;             asm volatile("s_waitcnt lgkmcnt(0)" ::: "memory");
;             if (q == 3) {
; #pragma unroll
;                 for (int r = 0; r < 4; ++r) STASH[256 * p + 16 * (grp + 4 * r) + pc] = f2bf(asc * (float)(2 * ((accH[r] << 4) + accL[r]) + sa));
;             }
;         }
;     ...
;             float4* op = (float4*)(outp + (size_t)t * D) + lane;
; #pragma unroll
;             for (int jq = 0; jq < 4; ++jq) { typedef float f4v __attribute__((ext_vector_type(4))); f4v o4; o4.x = v[jq].x * r3 * gv[jq].x; o4.y = v[jq].y * r3 * gv[jq].y; o4.z = v[jq].z * r3 * gv[jq].z; o4.w = v[jq].w * r3 * gv[jq].w;
;                 __builtin_nontemporal_store(o4, (f4v*)op + 64 * jq); }
	v_dot8c_i32_i4_e32 v38, v130, v52
	v_dot8c_i32_i4_e32 v39, v130, v50
	v_dot8c_i32_i4_e32 v40, v132, v52
	v_dot8c_i32_i4_e32 v41, v132, v50
	v_dot8c_i32_i4_e32 v42, v134, v52
	v_dot8c_i32_i4_e32 v43, v134, v50
	v_dot8c_i32_i4_e32 v44, v136, v52
	v_dot8c_i32_i4_e32 v45, v136, v50
	v_dot8c_i32_i4_e32 v38, v131, v53
	v_dot8c_i32_i4_e32 v39, v131, v51
	v_dot8c_i32_i4_e32 v40, v133, v53
	v_dot8c_i32_i4_e32 v41, v133, v51
	v_dot8c_i32_i4_e32 v42, v135, v53
	v_dot8c_i32_i4_e32 v43, v135, v51
	v_dot8c_i32_i4_e32 v44, v137, v53
	v_dot8c_i32_i4_e32 v45, v137, v51
	v_and_b32_e32 v78, 0xffff, v21
	v_lshrrev_b32_e32 v79, 16, v21
	v_lshl_add_u32 v78, v78, 7, v152
	v_lshl_add_u32 v79, v79, 7, v153
	s_mov_b32 m0, s79
	s_add_i32 s43, s79, 0x400
	global_load_lds_dwordx4 v78, s[50:51]
	s_mov_b32 m0, s43
	s_nop 0
	global_load_lds_dwordx4 v79, s[50:51]
	s_waitcnt vmcnt(8)
	v_add_u32_e32 v54, s99, v59
	v_add_u32_e32 v55, s99, v60
	v_add_u32_e32 v56, s99, v61
	v_add_u32_e32 v57, s99, v62
	ds_read_b64_tr_b4 v[50:51], v160 offset:896
	ds_read_b64_tr_b4 v[52:53], v160 offset:1920
	ds_read_b64_tr_b4 v[130:131], v54
	ds_read_b64_tr_b4 v[132:133], v55
	ds_read_b64_tr_b4 v[134:135], v56
	ds_read_b64_tr_b4 v[136:137], v57
	s_waitcnt lgkmcnt(6)
	v_dot8c_i32_i4_e32 v38, v122, v48
	v_dot8c_i32_i4_e32 v39, v122, v46
	v_dot8c_i32_i4_e32 v40, v124, v48
	v_dot8c_i32_i4_e32 v41, v124, v46
	v_dot8c_i32_i4_e32 v42, v126, v48
	v_dot8c_i32_i4_e32 v43, v126, v46
	v_dot8c_i32_i4_e32 v44, v128, v48
	v_dot8c_i32_i4_e32 v45, v128, v46
	v_dot8c_i32_i4_e32 v38, v123, v49
	v_dot8c_i32_i4_e32 v39, v123, v47
	v_dot8c_i32_i4_e32 v40, v125, v49
	v_dot8c_i32_i4_e32 v41, v125, v47
	v_dot8c_i32_i4_e32 v42, v127, v49
	v_dot8c_i32_i4_e32 v43, v127, v47
	v_dot8c_i32_i4_e32 v44, v129, v49
	v_dot8c_i32_i4_e32 v45, v129, v47
	v_and_b32_e32 v78, 0xffff, v22
	v_lshrrev_b32_e32 v79, 16, v22
	v_lshl_add_u32 v78, v78, 7, v152
	v_lshl_add_u32 v79, v79, 7, v153
	s_mov_b32 m0, s98
	s_add_i32 s43, s98, 0x400
	global_load_lds_dwordx4 v78, s[50:51]
	s_mov_b32 m0, s43
	s_nop 0
	global_load_lds_dwordx4 v79, s[50:51]
	s_waitcnt vmcnt(8)
	v_add_u32_e32 v54, s76, v59
	v_add_u32_e32 v55, s76, v60
	v_add_u32_e32 v56, s76, v61
	v_add_u32_e32 v57, s76, v62
	ds_read_b64_tr_b4 v[46:47], v160
	ds_read_b64_tr_b4 v[48:49], v160 offset:1024
	ds_read_b64_tr_b4 v[122:123], v54
	ds_read_b64_tr_b4 v[124:125], v55
	ds_read_b64_tr_b4 v[126:127], v56
	ds_read_b64_tr_b4 v[128:129], v57
	s_waitcnt lgkmcnt(6)
	v_dot8c_i32_i4_e32 v38, v130, v52
	v_dot8c_i32_i4_e32 v39, v130, v50
	v_dot8c_i32_i4_e32 v40, v132, v52
	v_dot8c_i32_i4_e32 v41, v132, v50
	v_dot8c_i32_i4_e32 v42, v134, v52
	v_dot8c_i32_i4_e32 v43, v134, v50
	v_dot8c_i32_i4_e32 v44, v136, v52
	v_dot8c_i32_i4_e32 v45, v136, v50
	v_dot8c_i32_i4_e32 v38, v131, v53
	v_dot8c_i32_i4_e32 v39, v131, v51
	v_dot8c_i32_i4_e32 v40, v133, v53
	v_dot8c_i32_i4_e32 v41, v133, v51
	v_dot8c_i32_i4_e32 v42, v135, v53
	v_dot8c_i32_i4_e32 v43, v135, v51
	v_dot8c_i32_i4_e32 v44, v137, v53
	v_dot8c_i32_i4_e32 v45, v137, v51
	s_nop 3
	s_waitcnt lgkmcnt(15)
	v_lshlrev_b32_e32 v38, 5, v38
	v_lshlrev_b32_e32 v39, 1, v39
	v_add3_u32 v38, v39, v229, v38
	v_cvt_f32_i32_e32 v38, v38
	v_mul_f32_e32 v38, v228, v38
	v_lshlrev_b32_e32 v40, 5, v40
	v_lshlrev_b32_e32 v41, 1, v41
	v_add3_u32 v40, v41, v229, v40
	v_cvt_f32_i32_e32 v40, v40
	v_mul_f32_e32 v40, v228, v40
	v_lshlrev_b32_e32 v42, 5, v42
	v_lshlrev_b32_e32 v43, 1, v43
	v_add3_u32 v42, v43, v229, v42
	v_cvt_f32_i32_e32 v42, v42
	v_mul_f32_e32 v42, v228, v42
	v_lshlrev_b32_e32 v44, 5, v44
	v_lshlrev_b32_e32 v45, 1, v45
	v_add3_u32 v44, v45, v229, v44
	v_cvt_f32_i32_e32 v44, v44
	v_mul_f32_e32 v44, v228, v44
	v_cvt_pk_bf16_f32 v190, v38, v40
	v_cvt_pk_bf16_f32 v191, v42, v44
	ds_read_b128 v[252:255], v155 offset:1024
	s_add_i32 s44, s40, 40
	s_ashr_i32 s45, s44, 31
	s_lshl_b64 s[44:45], s[44:45], 12
	v_lshl_add_u64 v[80:81], v[36:37], 0, s[44:45]
	s_waitcnt lgkmcnt(0)
	v_mul_f32_e32 v240, v240, v252
	v_mul_f32_e32 v241, v241, v253
	v_mul_f32_e32 v242, v242, v254
	v_mul_f32_e32 v243, v243, v255
	global_store_dwordx4 v[80:81], v[240:243], off offset:1024 nt
	v_add_u32_e32 v147, 8, v140
	v_and_b32_e32 v146, 15, v147
	v_xor_b32_e32 v146, 8, v146
	v_bfe_u32 v148, v147, 4, 4
	v_mul_lo_u32 v146, v146, s92
	v_mul_lo_u32 v148, v148, s92
	v_mov_b32_e32 v147, v146
	v_mov_b32_e32 v149, v148
	ds_write2st64_b64 v77, v[146:147], v[148:149] offset1:2
	v_add_u32_e32 v138, 0x1c00, v74
	ds_read_u8 v139, v138
	v_add_u32_e32 v141, 0x1c00, v73
	ds_read_u8 v140, v141
	s_add_i32 s43, s67, 192
	v_mov_b32_e32 v138, s43
	ds_read2st64_b32 v[228:229], v138 offset1:1
	ds_read_b128 v[26:29], v227 offset:14336
	ds_read_b128 v[30:33], v227 offset:14352
	v_mov_b32_e32 v38, 0
	v_mov_b32_e32 v39, 0
	v_mov_b32_e32 v40, 0
	v_mov_b32_e32 v41, 0
	v_mov_b32_e32 v42, 0
	v_mov_b32_e32 v43, 0
	v_mov_b32_e32 v44, 0
	v_mov_b32_e32 v45, 0
	v_and_b32_e32 v78, 0xffff, v23
	v_lshrrev_b32_e32 v79, 16, v23
	v_lshl_add_u32 v78, v78, 7, v152
	v_lshl_add_u32 v79, v79, 7, v153
	s_mov_b32 m0, s99
	s_add_i32 s43, s99, 0x400
	global_load_lds_dwordx4 v78, s[50:51]
	s_mov_b32 m0, s43
	s_nop 0
	global_load_lds_dwordx4 v79, s[50:51]
	s_waitcnt vmcnt(9)
	v_add_u32_e32 v54, s77, v59
	v_add_u32_e32 v55, s77, v60
	v_add_u32_e32 v56, s77, v61
	v_add_u32_e32 v57, s77, v62
	ds_read_b64_tr_b4 v[50:51], v160 offset:128
	ds_read_b64_tr_b4 v[52:53], v160 offset:1152
	ds_read_b64_tr_b4 v[130:131], v54
	ds_read_b64_tr_b4 v[132:133], v55
	ds_read_b64_tr_b4 v[134:135], v56
	ds_read_b64_tr_b4 v[136:137], v57
	s_waitcnt lgkmcnt(13)
; #define TR4(p_) __builtin_amdgcn_ds_read_tr4_b64_v2i32((LAS v2i*)(p_))
; #define VDMA(st_, k_) do { _Pragma("unroll") for (int i_ = 0; i_ < 4; ++i_) { \
;         const unsigned off_ = (unsigned)((st_) >> 2) * (16384u * 128u) + (PE_ID(E, 4 * ((st_) & 3) + i_) << 7) + ((i_ & 1) ? cx1 : cx0); \
;         __builtin_amdgcn_global_load_lds((const unsigned*)(V4 + off_), (LAS unsigned*)(ldsb + BUF[k_] + 1024 * i_), 16, 0, 0); } } while (0)
; __device__ __forceinline__ void peer_v_tokens(int j, const LAS unsigned short* EL, const LAS unsigned char* AL  , const LAS float* ASC  , const LAS int* SAL  , ...
;     ...
;         for (int st = 0; st < 16; ++st) {
;             const int p = st >> 2, q = st & 3;
;             if (st < 14) VDMA(st + 2, (st + 2) % 3);
;             if (st < 14) asm volatile("s_waitcnt vmcnt(8)" ::: "memory");
;             else if (st == 14) asm volatile("s_waitcnt vmcnt(4)" ::: "memory");
;             else asm volatile("s_waitcnt vmcnt(0)" ::: "memory");
;             if (q == 0) {
; #pragma unroll
;                 for (int r = 0; r < 4; ++r) { accH[r] = 0; accL[r] = 0; } }
; #pragma unroll
;             for (int tp = 0; tp < 2; ++tp) {
;                 const v2i ao = TR4(ATL + (2 * q + tp) * 128 + 8 * s16), ah = TR4(ATL + 1024 + (2 * q + tp) * 128 + 8 * s16);
; #pragma unroll
;                 for (int r = 0; r < 4; ++r) {
;                     const v2i d = TR4(ldsb + BUF[st % 3] + 2048 * tp + roff[r]);
;                     accH[r] = __builtin_amdgcn_sdot8(d.x, ah.x, accH[r], false); accH[r] = __builtin_amdgcn_sdot8(d.y, ah.y, accH[r], false);
;                     accL[r] = __builtin_amdgcn_sdot8(d.x, ao.x, accL[r], false); accL[r] = __builtin_amdgcn_sdot8(d.y, ao.y, accL[r], false);
;                 }
;             }
;             asm volatile("s_waitcnt lgkmcnt(0)" ::: "memory");
	v_dot8c_i32_i4_e32 v38, v122, v48
	v_dot8c_i32_i4_e32 v39, v122, v46
	v_dot8c_i32_i4_e32 v40, v124, v48
	v_dot8c_i32_i4_e32 v41, v124, v46
	v_dot8c_i32_i4_e32 v42, v126, v48
	v_dot8c_i32_i4_e32 v43, v126, v46
	v_dot8c_i32_i4_e32 v44, v128, v48
	v_dot8c_i32_i4_e32 v45, v128, v46
	v_dot8c_i32_i4_e32 v38, v123, v49
	v_dot8c_i32_i4_e32 v39, v123, v47
	v_dot8c_i32_i4_e32 v40, v125, v49
	v_dot8c_i32_i4_e32 v41, v125, v47
	v_dot8c_i32_i4_e32 v42, v127, v49
	v_dot8c_i32_i4_e32 v43, v127, v47
	v_dot8c_i32_i4_e32 v44, v129, v49
	v_dot8c_i32_i4_e32 v45, v129, v47
	v_and_b32_e32 v78, 0xffff, v24
	v_lshrrev_b32_e32 v79, 16, v24
	v_lshl_add_u32 v78, v78, 7, v152
	v_lshl_add_u32 v79, v79, 7, v153
	s_mov_b32 m0, s76
	s_add_i32 s43, s76, 0x400
	global_load_lds_dwordx4 v78, s[50:51]
	s_mov_b32 m0, s43
	s_nop 0
	global_load_lds_dwordx4 v79, s[50:51]
	s_waitcnt vmcnt(9)
	v_add_u32_e32 v54, s78, v59
	v_add_u32_e32 v55, s78, v60
	v_add_u32_e32 v56, s78, v61
	v_add_u32_e32 v57, s78, v62
	ds_read_b64_tr_b4 v[46:47], v160 offset:256
	ds_read_b64_tr_b4 v[48:49], v160 offset:1280
	ds_read_b64_tr_b4 v[122:123], v54
	ds_read_b64_tr_b4 v[124:125], v55
	ds_read_b64_tr_b4 v[126:127], v56
	ds_read_b64_tr_b4 v[128:129], v57
	s_waitcnt lgkmcnt(6)
	v_dot8c_i32_i4_e32 v38, v130, v52
	v_dot8c_i32_i4_e32 v39, v130, v50
	v_dot8c_i32_i4_e32 v40, v132, v52
	v_dot8c_i32_i4_e32 v41, v132, v50
	v_dot8c_i32_i4_e32 v42, v134, v52
	v_dot8c_i32_i4_e32 v43, v134, v50
	v_dot8c_i32_i4_e32 v44, v136, v52
	v_dot8c_i32_i4_e32 v45, v136, v50
	v_dot8c_i32_i4_e32 v38, v131, v53
	v_dot8c_i32_i4_e32 v39, v131, v51
	v_dot8c_i32_i4_e32 v40, v133, v53
	v_dot8c_i32_i4_e32 v41, v133, v51
	v_dot8c_i32_i4_e32 v42, v135, v53
	v_dot8c_i32_i4_e32 v43, v135, v51
	v_dot8c_i32_i4_e32 v44, v137, v53
	v_dot8c_i32_i4_e32 v45, v137, v51
	v_and_b32_e32 v78, 0xffff, v25
	v_lshrrev_b32_e32 v79, 16, v25
	v_lshl_add_u32 v78, v78, 7, v152
	v_lshl_add_u32 v79, v79, 7, v153
	s_mov_b32 m0, s77
	s_add_i32 s43, s77, 0x400
	global_load_lds_dwordx4 v78, s[50:51]
	s_mov_b32 m0, s43
	s_nop 0
	global_load_lds_dwordx4 v79, s[50:51]
	s_waitcnt vmcnt(9)
	v_add_u32_e32 v54, s79, v59
	v_add_u32_e32 v55, s79, v60
	v_add_u32_e32 v56, s79, v61
	v_add_u32_e32 v57, s79, v62
	ds_read_b64_tr_b4 v[50:51], v160 offset:384
	ds_read_b64_tr_b4 v[52:53], v160 offset:1408
	ds_read_b64_tr_b4 v[130:131], v54
	ds_read_b64_tr_b4 v[132:133], v55
	ds_read_b64_tr_b4 v[134:135], v56
	ds_read_b64_tr_b4 v[136:137], v57
	s_waitcnt lgkmcnt(6)
	v_dot8c_i32_i4_e32 v38, v122, v48
	v_dot8c_i32_i4_e32 v39, v122, v46
	v_dot8c_i32_i4_e32 v40, v124, v48
	v_dot8c_i32_i4_e32 v41, v124, v46
	v_dot8c_i32_i4_e32 v42, v126, v48
	v_dot8c_i32_i4_e32 v43, v126, v46
	v_dot8c_i32_i4_e32 v44, v128, v48
	v_dot8c_i32_i4_e32 v45, v128, v46
	v_dot8c_i32_i4_e32 v38, v123, v49
	v_dot8c_i32_i4_e32 v39, v123, v47
	v_dot8c_i32_i4_e32 v40, v125, v49
	v_dot8c_i32_i4_e32 v41, v125, v47
	v_dot8c_i32_i4_e32 v42, v127, v49
	v_dot8c_i32_i4_e32 v43, v127, v47
	v_dot8c_i32_i4_e32 v44, v129, v49
	v_dot8c_i32_i4_e32 v45, v129, v47
	s_waitcnt lgkmcnt(15)
	v_and_b32_e32 v78, 0xffff, v26
	v_lshrrev_b32_e32 v79, 16, v26
	v_lshl_add_u32 v78, v78, 7, v152
	v_lshl_add_u32 v79, v79, 7, v153
	s_mov_b32 m0, s78
	s_add_i32 s43, s78, 0x400
	global_load_lds_dwordx4 v78, s[50:51]
	s_mov_b32 m0, s43
	s_nop 0
	global_load_lds_dwordx4 v79, s[50:51]
	s_waitcnt vmcnt(9)
	v_add_u32_e32 v54, s98, v59
	v_add_u32_e32 v55, s98, v60
	v_add_u32_e32 v56, s98, v61
	v_add_u32_e32 v57, s98, v62
	ds_read_b64_tr_b4 v[46:47], v160 offset:512
	ds_read_b64_tr_b4 v[48:49], v160 offset:1536
	ds_read_b64_tr_b4 v[122:123], v54
	ds_read_b64_tr_b4 v[124:125], v55
	ds_read_b64_tr_b4 v[126:127], v56
	ds_read_b64_tr_b4 v[128:129], v57
	s_waitcnt lgkmcnt(6)
	v_dot8c_i32_i4_e32 v38, v130, v52
	v_dot8c_i32_i4_e32 v39, v130, v50
	v_dot8c_i32_i4_e32 v40, v132, v52
	v_dot8c_i32_i4_e32 v41, v132, v50
	v_dot8c_i32_i4_e32 v42, v134, v52
	v_dot8c_i32_i4_e32 v43, v134, v50
	v_dot8c_i32_i4_e32 v44, v136, v52
	v_dot8c_i32_i4_e32 v45, v136, v50
	v_dot8c_i32_i4_e32 v38, v131, v53
	v_dot8c_i32_i4_e32 v39, v131, v51
	v_dot8c_i32_i4_e32 v40, v133, v53
	v_dot8c_i32_i4_e32 v41, v133, v51
	v_dot8c_i32_i4_e32 v42, v135, v53
	v_dot8c_i32_i4_e32 v43, v135, v51
	v_dot8c_i32_i4_e32 v44, v137, v53
	v_dot8c_i32_i4_e32 v45, v137, v51
	v_and_b32_e32 v78, 0xffff, v27
	v_lshrrev_b32_e32 v79, 16, v27
	v_lshl_add_u32 v78, v78, 7, v152
	v_lshl_add_u32 v79, v79, 7, v153
	s_mov_b32 m0, s79
	s_add_i32 s43, s79, 0x400
	global_load_lds_dwordx4 v78, s[50:51]
	s_mov_b32 m0, s43
	s_nop 0
	global_load_lds_dwordx4 v79, s[50:51]
	s_waitcnt vmcnt(8)
	v_add_u32_e32 v54, s99, v59
	v_add_u32_e32 v55, s99, v60
	v_add_u32_e32 v56, s99, v61
	v_add_u32_e32 v57, s99, v62
	ds_read_b64_tr_b4 v[50:51], v160 offset:640
	ds_read_b64_tr_b4 v[52:53], v160 offset:1664
	ds_read_b64_tr_b4 v[130:131], v54
	ds_read_b64_tr_b4 v[132:133], v55
	ds_read_b64_tr_b4 v[134:135], v56
	ds_read_b64_tr_b4 v[136:137], v57
	s_waitcnt lgkmcnt(6)
	v_dot8c_i32_i4_e32 v38, v122, v48
	v_dot8c_i32_i4_e32 v39, v122, v46
	v_dot8c_i32_i4_e32 v40, v124, v48
	v_dot8c_i32_i4_e32 v41, v124, v46
	v_dot8c_i32_i4_e32 v42, v126, v48
	v_dot8c_i32_i4_e32 v43, v126, v46
	v_dot8c_i32_i4_e32 v44, v128, v48
	v_dot8c_i32_i4_e32 v45, v128, v46
	v_dot8c_i32_i4_e32 v38, v123, v49
	v_dot8c_i32_i4_e32 v39, v123, v47
	v_dot8c_i32_i4_e32 v40, v125, v49
	v_dot8c_i32_i4_e32 v41, v125, v47
	v_dot8c_i32_i4_e32 v42, v127, v49
	v_dot8c_i32_i4_e32 v43, v127, v47
	v_dot8c_i32_i4_e32 v44, v129, v49
	v_dot8c_i32_i4_e32 v45, v129, v47
	s_waitcnt lgkmcnt(15)
; __device__ __forceinline__ void peer_v_tokens(int j, const LAS unsigned short* EL, const LAS unsigned char* AL  , const LAS float* ASC  , const LAS int* SAL  , ...
;     ...
; #pragma unroll
;         for (int m = 0; m < 2; ++m) {
;             const int idx = lane + 64 * m, tau = idx >> 4, sr = idx & 15, k = 16 * (sr & 7) + 2 * tau + (sr >> 3);
;             const int aq = (int)*(const LAS signed char*)(AL + tl * 128 + k); const int tq = aq + 8;
;             const unsigned lo = (((unsigned)tq & 15u) ^ 8u) * 0x11111111u, hi = ((unsigned)(tq >> 4) & 15u) * 0x11111111u;
;             typedef unsigned u2v __attribute__((ext_vector_type(2)));
;             u2v l2; l2.x = lo; l2.y = lo; u2v h2; h2.x = hi; h2.y = hi;
;             *(LAS u2v*)(ATL + 8 * idx) = l2; *(LAS u2v*)(ATL + 1024 + 8 * idx) = h2;
;         }
;         const float asc = ASC[tl]; const int sa = SAL[tl];
;         CFENCE();
;         int accH[4], accL[4];
; #pragma unroll
;         for (int st = 0; st < 16; ++st) {
;             const int p = st >> 2, q = st & 3;
;             if (st < 14) VDMA(st + 2, (st + 2) % 3);
;             if (st < 14) asm volatile("s_waitcnt vmcnt(8)" ::: "memory");
;             else if (st == 14) asm volatile("s_waitcnt vmcnt(4)" ::: "memory");
;             else asm volatile("s_waitcnt vmcnt(0)" ::: "memory");
;             if (q == 0) {
; #pragma unroll
;                 for (int r = 0; r < 4; ++r) { accH[r] = 0; accL[r] = 0; } }
; #pragma unroll
;             for (int tp = 0; tp < 2; ++tp) {
;                 const v2i ao = TR4(ATL + (2 * q + tp) * 128 + 8 * s16), ah = TR4(ATL + 1024 + (2 * q + tp) * 128 + 8 * s16);
; #pragma unroll
;                 for (int r = 0; r < 4; ++r) {
;                     const v2i d = TR4(ldsb + BUF[st % 3] + 2048 * tp + roff[r]);
;                     accH[r] = __builtin_amdgcn_sdot8(d.x, ah.x, accH[r], false); accH[r] = __builtin_amdgcn_sdot8(d.y, ah.y, accH[r], false);
;                     accL[r] = __builtin_amdgcn_sdot8(d.x, ao.x, accL[r], false); accL[r] = __builtin_amdgcn_sdot8(d.y, ao.y, accL[r], false);
;                 }
;             }
;             asm volatile("s_waitcnt lgkmcnt(0)" ::: "memory");
;             if (q == 3) {
; #pragma unroll
;                 for (int r = 0; r < 4; ++r) STASH[256 * p + 16 * (grp + 4 * r) + pc] = f2bf(asc * (float)(2 * ((accH[r] << 4) + accL[r]) + sa));
;             }
;         }
	v_add_u32_e32 v143, 8, v139
	v_and_b32_e32 v142, 15, v143
	v_xor_b32_e32 v142, 8, v142
	v_bfe_u32 v144, v143, 4, 4
	v_mul_lo_u32 v142, v142, s92
	v_mul_lo_u32 v144, v144, s92
	v_mov_b32_e32 v143, v142
	v_mov_b32_e32 v145, v144
	ds_write2st64_b64 v159, v[142:143], v[144:145] offset1:2
	v_and_b32_e32 v78, 0xffff, v28
	v_lshrrev_b32_e32 v79, 16, v28
	v_lshl_add_u32 v78, v78, 7, v152
	v_lshl_add_u32 v79, v79, 7, v153
	s_mov_b32 m0, s98
	s_add_i32 s43, s98, 0x400
	global_load_lds_dwordx4 v78, s[50:51]
	s_mov_b32 m0, s43
	s_nop 0
	global_load_lds_dwordx4 v79, s[50:51]
	s_waitcnt vmcnt(8)
	v_add_u32_e32 v54, s76, v59
	v_add_u32_e32 v55, s76, v60
	v_add_u32_e32 v56, s76, v61
	v_add_u32_e32 v57, s76, v62
	ds_read_b64_tr_b4 v[46:47], v160 offset:768
	ds_read_b64_tr_b4 v[48:49], v160 offset:1792
	ds_read_b64_tr_b4 v[122:123], v54
	ds_read_b64_tr_b4 v[124:125], v55
	ds_read_b64_tr_b4 v[126:127], v56
	ds_read_b64_tr_b4 v[128:129], v57
	s_waitcnt lgkmcnt(7)
	v_dot8c_i32_i4_e32 v38, v130, v52
	v_dot8c_i32_i4_e32 v39, v130, v50
	v_dot8c_i32_i4_e32 v40, v132, v52
	v_dot8c_i32_i4_e32 v41, v132, v50
	v_dot8c_i32_i4_e32 v42, v134, v52
	v_dot8c_i32_i4_e32 v43, v134, v50
	v_dot8c_i32_i4_e32 v44, v136, v52
	v_dot8c_i32_i4_e32 v45, v136, v50
	v_dot8c_i32_i4_e32 v38, v131, v53
	v_dot8c_i32_i4_e32 v39, v131, v51
	v_dot8c_i32_i4_e32 v40, v133, v53
	v_dot8c_i32_i4_e32 v41, v133, v51
	v_dot8c_i32_i4_e32 v42, v135, v53
	v_dot8c_i32_i4_e32 v43, v135, v51
	v_dot8c_i32_i4_e32 v44, v137, v53
	v_dot8c_i32_i4_e32 v45, v137, v51
	v_and_b32_e32 v78, 0xffff, v29
	v_lshrrev_b32_e32 v79, 16, v29
	v_lshl_add_u32 v78, v78, 7, v152
	v_lshl_add_u32 v79, v79, 7, v153
	s_mov_b32 m0, s99
	s_add_i32 s43, s99, 0x400
	global_load_lds_dwordx4 v78, s[50:51]
	s_mov_b32 m0, s43
	s_nop 0
	global_load_lds_dwordx4 v79, s[50:51]
	s_waitcnt vmcnt(8)
	v_add_u32_e32 v54, s77, v59
	v_add_u32_e32 v55, s77, v60
	v_add_u32_e32 v56, s77, v61
	v_add_u32_e32 v57, s77, v62
	ds_read_b64_tr_b4 v[50:51], v160 offset:896
	ds_read_b64_tr_b4 v[52:53], v160 offset:1920
	ds_read_b64_tr_b4 v[130:131], v54
	ds_read_b64_tr_b4 v[132:133], v55
	ds_read_b64_tr_b4 v[134:135], v56
	ds_read_b64_tr_b4 v[136:137], v57
	s_waitcnt lgkmcnt(6)
	v_dot8c_i32_i4_e32 v38, v122, v48
	v_dot8c_i32_i4_e32 v39, v122, v46
	v_dot8c_i32_i4_e32 v40, v124, v48
	v_dot8c_i32_i4_e32 v41, v124, v46
	v_dot8c_i32_i4_e32 v42, v126, v48
	v_dot8c_i32_i4_e32 v43, v126, v46
	v_dot8c_i32_i4_e32 v44, v128, v48
	v_dot8c_i32_i4_e32 v45, v128, v46
	v_dot8c_i32_i4_e32 v38, v123, v49
	v_dot8c_i32_i4_e32 v39, v123, v47
	v_dot8c_i32_i4_e32 v40, v125, v49
	v_dot8c_i32_i4_e32 v41, v125, v47
	v_dot8c_i32_i4_e32 v42, v127, v49
	v_dot8c_i32_i4_e32 v43, v127, v47
	v_dot8c_i32_i4_e32 v44, v129, v49
	v_dot8c_i32_i4_e32 v45, v129, v47
	v_and_b32_e32 v78, 0xffff, v30
	v_lshrrev_b32_e32 v79, 16, v30
	v_lshl_add_u32 v78, v78, 7, v152
	v_lshl_add_u32 v79, v79, 7, v153
	s_mov_b32 m0, s76
	s_add_i32 s43, s76, 0x400
	global_load_lds_dwordx4 v78, s[50:51]
	s_mov_b32 m0, s43
	s_nop 0
	global_load_lds_dwordx4 v79, s[50:51]
	s_waitcnt vmcnt(8)
	v_add_u32_e32 v54, s78, v59
	v_add_u32_e32 v55, s78, v60
	v_add_u32_e32 v56, s78, v61
	v_add_u32_e32 v57, s78, v62
	ds_read_b64_tr_b4 v[46:47], v160
	ds_read_b64_tr_b4 v[48:49], v160 offset:1024
	ds_read_b64_tr_b4 v[122:123], v54
	ds_read_b64_tr_b4 v[124:125], v55
	ds_read_b64_tr_b4 v[126:127], v56
	ds_read_b64_tr_b4 v[128:129], v57
	s_waitcnt lgkmcnt(6)
	v_dot8c_i32_i4_e32 v38, v130, v52
	v_dot8c_i32_i4_e32 v39, v130, v50
	v_dot8c_i32_i4_e32 v40, v132, v52
	v_dot8c_i32_i4_e32 v41, v132, v50
	v_dot8c_i32_i4_e32 v42, v134, v52
	v_dot8c_i32_i4_e32 v43, v134, v50
	v_dot8c_i32_i4_e32 v44, v136, v52
	v_dot8c_i32_i4_e32 v45, v136, v50
	v_dot8c_i32_i4_e32 v38, v131, v53
	v_dot8c_i32_i4_e32 v39, v131, v51
	v_dot8c_i32_i4_e32 v40, v133, v53
	v_dot8c_i32_i4_e32 v41, v133, v51
	v_dot8c_i32_i4_e32 v42, v135, v53
	v_dot8c_i32_i4_e32 v43, v135, v51
	v_dot8c_i32_i4_e32 v44, v137, v53
	v_dot8c_i32_i4_e32 v45, v137, v51
	s_nop 3
	s_waitcnt lgkmcnt(15)
	v_lshlrev_b32_e32 v38, 5, v38
	v_lshlrev_b32_e32 v39, 1, v39
	v_add3_u32 v38, v39, v229, v38
	v_cvt_f32_i32_e32 v38, v38
	v_mul_f32_e32 v38, v228, v38
	v_lshlrev_b32_e32 v40, 5, v40
	v_lshlrev_b32_e32 v41, 1, v41
	v_add3_u32 v40, v41, v229, v40
	v_cvt_f32_i32_e32 v40, v40
	v_mul_f32_e32 v40, v228, v40
	v_lshlrev_b32_e32 v42, 5, v42
	v_lshlrev_b32_e32 v43, 1, v43
	v_add3_u32 v42, v43, v229, v42
	v_cvt_f32_i32_e32 v42, v42
	v_mul_f32_e32 v42, v228, v42
	v_lshlrev_b32_e32 v44, 5, v44
	v_lshlrev_b32_e32 v45, 1, v45
	v_add3_u32 v44, v45, v229, v44
	v_cvt_f32_i32_e32 v44, v44
	v_mul_f32_e32 v44, v228, v44
	v_cvt_pk_bf16_f32 v184, v38, v40
	v_cvt_pk_bf16_f32 v185, v42, v44
	ds_read_b128 v[252:255], v156
	s_add_i32 s44, s40, 40
	s_ashr_i32 s45, s44, 31
	s_lshl_b64 s[44:45], s[44:45], 12
	v_lshl_add_u64 v[80:81], v[36:37], 0, s[44:45]
	s_waitcnt lgkmcnt(0)
; __device__ __forceinline__ void peer_v_tokens(int j, const LAS unsigned short* EL, const LAS unsigned char* AL  , const LAS float* ASC  , const LAS int* SAL  , ...
;     ...
;         const int tl = it * 8 + wave, t = j * 64 + tl;
;         unsigned E[8];
;         { const LAS v4u* ep = (const LAS v4u*)(EL + tl * 128 + 16 * g); const v4u e0 = ep[0], e1 = ep[1];
;           E[0] = e0.x; E[1] = e0.y; E[2] = e0.z; E[3] = e0.w; E[4] = e1.x; E[5] = e1.y; E[6] = e1.z; E[7] = e1.w; }
;         uint2 hv[4]; float4 gv[4];
;         { unsigned ho = (unsigned)t * (D / 4) + (unsigned)lane; asm volatile("" : "+v"(ho)); const uint2* hp = (const uint2*)HB + ho; const float4* gp = (const float4*)fng + lane;
; #pragma unroll
;           for (int jq = 0; jq < 4; ++jq) { hv[jq] = hp[64 * jq]; gv[jq] = gp[64 * jq]; } }
;         VDMA(0, 0); VDMA(1, 1);
; #pragma unroll
;         for (int m = 0; m < 2; ++m) {
;             const int idx = lane + 64 * m, tau = idx >> 4, sr = idx & 15, k = 16 * (sr & 7) + 2 * tau + (sr >> 3);
;             const int aq = (int)*(const LAS signed char*)(AL + tl * 128 + k); const int tq = aq + 8;
;             const unsigned lo = (((unsigned)tq & 15u) ^ 8u) * 0x11111111u, hi = ((unsigned)(tq >> 4) & 15u) * 0x11111111u;
;             typedef unsigned u2v __attribute__((ext_vector_type(2)));
;             u2v l2; l2.x = lo; l2.y = lo; u2v h2; h2.x = hi; h2.y = hi;
;             *(LAS u2v*)(ATL + 8 * idx) = l2; *(LAS u2v*)(ATL + 1024 + 8 * idx) = h2;
;         }
;         const float asc = ASC[tl]; const int sa = SAL[tl];
;         CFENCE();
;         int accH[4], accL[4];
; #pragma unroll
;         for (int st = 0; st < 16; ++st) {
;             const int p = st >> 2, q = st & 3;
;             if (st < 14) VDMA(st + 2, (st + 2) % 3);
;             if (st < 14) asm volatile("s_waitcnt vmcnt(8)" ::: "memory");
;             else if (st == 14) asm volatile("s_waitcnt vmcnt(4)" ::: "memory");
;             else asm volatile("s_waitcnt vmcnt(0)" ::: "memory");
;             if (q == 0) {
; #pragma unroll
;                 for (int r = 0; r < 4; ++r) { accH[r] = 0; accL[r] = 0; } }
; #pragma unroll
;             for (int tp = 0; tp < 2; ++tp) {
;                 const v2i ao = TR4(ATL + (2 * q + tp) * 128 + 8 * s16), ah = TR4(ATL + 1024 + (2 * q + tp) * 128 + 8 * s16);
; #pragma unroll
;                 for (int r = 0; r < 4; ++r) {
	v_mul_f32_e32 v244, v244, v252
	v_mul_f32_e32 v245, v245, v253
	v_mul_f32_e32 v246, v246, v254
	v_mul_f32_e32 v247, v247, v255
	global_store_dwordx4 v[80:81], v[244:247], off offset:2048 nt
	s_add_i32 s43, s40, 48
	s_lshl_b32 s43, s43, 11
	v_add_u32_e32 v138, s43, v66
	global_load_dwordx2 v[194:195], v138, s[70:71]
	global_load_dwordx2 v[196:197], v138, s[70:71] offset:512
	global_load_dwordx2 v[198:199], v138, s[70:71] offset:1024
	global_load_dwordx2 v[200:201], v138, s[70:71] offset:1536
	s_add_i32 s43, s40, 56
	s_lshl_b32 s43, s43, 11
	v_add_u32_e32 v138, s43, v66
	global_load_dwordx2 v[18:19], v138, s[70:71]
	global_load_dwordx2 v[20:21], v138, s[70:71] offset:512
	global_load_dwordx2 v[22:23], v138, s[70:71] offset:1024
	global_load_dwordx2 v[24:25], v138, s[70:71] offset:1536
	v_add_u32_e32 v147, 8, v140
	v_and_b32_e32 v146, 15, v147
	v_xor_b32_e32 v146, 8, v146
	v_bfe_u32 v148, v147, 4, 4
	v_mul_lo_u32 v146, v146, s92
	v_mul_lo_u32 v148, v148, s92
	v_mov_b32_e32 v147, v146
	v_mov_b32_e32 v149, v148
	ds_write2st64_b64 v77, v[146:147], v[148:149] offset1:2
	s_add_i32 s43, s67, 224
	v_mov_b32_e32 v138, s43
	ds_read2st64_b32 v[228:229], v138 offset1:1
	v_mov_b32_e32 v38, 0
	v_mov_b32_e32 v39, 0
	v_mov_b32_e32 v40, 0
	v_mov_b32_e32 v41, 0
	v_mov_b32_e32 v42, 0
	v_mov_b32_e32 v43, 0
	v_mov_b32_e32 v44, 0
	v_mov_b32_e32 v45, 0
	v_and_b32_e32 v78, 0xffff, v31
	v_lshrrev_b32_e32 v79, 16, v31
	v_lshl_add_u32 v78, v78, 7, v152
	v_lshl_add_u32 v79, v79, 7, v153
	s_mov_b32 m0, s77
	s_add_i32 s43, s77, 0x400
	global_load_lds_dwordx4 v78, s[50:51]
	s_mov_b32 m0, s43
	s_nop 0
	global_load_lds_dwordx4 v79, s[50:51]
	s_waitcnt vmcnt(17)
	v_add_u32_e32 v54, s79, v59
	v_add_u32_e32 v55, s79, v60
	v_add_u32_e32 v56, s79, v61
	v_add_u32_e32 v57, s79, v62
	ds_read_b64_tr_b4 v[50:51], v160 offset:128
	ds_read_b64_tr_b4 v[52:53], v160 offset:1152
	ds_read_b64_tr_b4 v[130:131], v54
	ds_read_b64_tr_b4 v[132:133], v55
	ds_read_b64_tr_b4 v[134:135], v56
	ds_read_b64_tr_b4 v[136:137], v57
	s_waitcnt lgkmcnt(9)
	v_dot8c_i32_i4_e32 v38, v122, v48
	v_dot8c_i32_i4_e32 v39, v122, v46
	v_dot8c_i32_i4_e32 v40, v124, v48
	v_dot8c_i32_i4_e32 v41, v124, v46
	v_dot8c_i32_i4_e32 v42, v126, v48
	v_dot8c_i32_i4_e32 v43, v126, v46
	v_dot8c_i32_i4_e32 v44, v128, v48
	v_dot8c_i32_i4_e32 v45, v128, v46
	v_dot8c_i32_i4_e32 v38, v123, v49
	v_dot8c_i32_i4_e32 v39, v123, v47
	v_dot8c_i32_i4_e32 v40, v125, v49
	v_dot8c_i32_i4_e32 v41, v125, v47
	v_dot8c_i32_i4_e32 v42, v127, v49
	v_dot8c_i32_i4_e32 v43, v127, v47
	v_dot8c_i32_i4_e32 v44, v129, v49
	v_dot8c_i32_i4_e32 v45, v129, v47
	v_and_b32_e32 v78, 0xffff, v32
	v_lshrrev_b32_e32 v79, 16, v32
	v_lshl_add_u32 v78, v78, 7, v152
	v_lshl_add_u32 v79, v79, 7, v153
	s_mov_b32 m0, s78
	s_add_i32 s43, s78, 0x400
	global_load_lds_dwordx4 v78, s[50:51]
	s_mov_b32 m0, s43
	s_nop 0
	global_load_lds_dwordx4 v79, s[50:51]
	s_waitcnt vmcnt(17)
	v_add_u32_e32 v54, s98, v59
	v_add_u32_e32 v55, s98, v60
	v_add_u32_e32 v56, s98, v61
	v_add_u32_e32 v57, s98, v62
	ds_read_b64_tr_b4 v[46:47], v160 offset:256
	ds_read_b64_tr_b4 v[48:49], v160 offset:1280
	ds_read_b64_tr_b4 v[122:123], v54
	ds_read_b64_tr_b4 v[124:125], v55
	ds_read_b64_tr_b4 v[126:127], v56
	ds_read_b64_tr_b4 v[128:129], v57
	s_waitcnt lgkmcnt(6)
	v_dot8c_i32_i4_e32 v38, v130, v52
	v_dot8c_i32_i4_e32 v39, v130, v50
	v_dot8c_i32_i4_e32 v40, v132, v52
	v_dot8c_i32_i4_e32 v41, v132, v50
	v_dot8c_i32_i4_e32 v42, v134, v52
	v_dot8c_i32_i4_e32 v43, v134, v50
	v_dot8c_i32_i4_e32 v44, v136, v52
	v_dot8c_i32_i4_e32 v45, v136, v50
	v_dot8c_i32_i4_e32 v38, v131, v53
	v_dot8c_i32_i4_e32 v39, v131, v51
	v_dot8c_i32_i4_e32 v40, v133, v53
	v_dot8c_i32_i4_e32 v41, v133, v51
	v_dot8c_i32_i4_e32 v42, v135, v53
	v_dot8c_i32_i4_e32 v43, v135, v51
	v_dot8c_i32_i4_e32 v44, v137, v53
	v_dot8c_i32_i4_e32 v45, v137, v51
	v_and_b32_e32 v78, 0xffff, v33
	v_lshrrev_b32_e32 v79, 16, v33
	v_lshl_add_u32 v78, v78, 7, v152
	v_lshl_add_u32 v79, v79, 7, v153
	s_mov_b32 m0, s79
	s_add_i32 s43, s79, 0x400
	global_load_lds_dwordx4 v78, s[50:51]
	s_mov_b32 m0, s43
	s_nop 0
	global_load_lds_dwordx4 v79, s[50:51]
	s_waitcnt vmcnt(17)
	v_add_u32_e32 v54, s99, v59
	v_add_u32_e32 v55, s99, v60
	v_add_u32_e32 v56, s99, v61
	v_add_u32_e32 v57, s99, v62
	ds_read_b64_tr_b4 v[50:51], v160 offset:384
	ds_read_b64_tr_b4 v[52:53], v160 offset:1408
	ds_read_b64_tr_b4 v[130:131], v54
	ds_read_b64_tr_b4 v[132:133], v55
	ds_read_b64_tr_b4 v[134:135], v56
	ds_read_b64_tr_b4 v[136:137], v57
	s_waitcnt lgkmcnt(6)
	v_dot8c_i32_i4_e32 v38, v122, v48
	v_dot8c_i32_i4_e32 v39, v122, v46
	v_dot8c_i32_i4_e32 v40, v124, v48
	v_dot8c_i32_i4_e32 v41, v124, v46
	v_dot8c_i32_i4_e32 v42, v126, v48
	v_dot8c_i32_i4_e32 v43, v126, v46
	v_dot8c_i32_i4_e32 v44, v128, v48
	v_dot8c_i32_i4_e32 v45, v128, v46
	v_dot8c_i32_i4_e32 v38, v123, v49
	v_dot8c_i32_i4_e32 v39, v123, v47
	v_dot8c_i32_i4_e32 v40, v125, v49
	v_dot8c_i32_i4_e32 v41, v125, v47
	v_dot8c_i32_i4_e32 v42, v127, v49
	v_dot8c_i32_i4_e32 v43, v127, v47
	v_dot8c_i32_i4_e32 v44, v129, v49
	v_dot8c_i32_i4_e32 v45, v129, v47
	s_waitcnt vmcnt(15)
	v_add_u32_e32 v54, s76, v59
	v_add_u32_e32 v55, s76, v60
	v_add_u32_e32 v56, s76, v61
	v_add_u32_e32 v57, s76, v62
	ds_read_b64_tr_b4 v[46:47], v160 offset:512
	ds_read_b64_tr_b4 v[48:49], v160 offset:1536
	ds_read_b64_tr_b4 v[122:123], v54
	ds_read_b64_tr_b4 v[124:125], v55
	ds_read_b64_tr_b4 v[126:127], v56
	ds_read_b64_tr_b4 v[128:129], v57
	s_waitcnt lgkmcnt(6)
; __device__ __forceinline__ void peer_v_tokens(int j, const LAS unsigned short* EL, const LAS unsigned char* AL  , const LAS float* ASC  , const LAS int* SAL  , ...
;     ...
;         for (int st = 0; st < 16; ++st) {
;             const int p = st >> 2, q = st & 3;
;             if (st < 14) VDMA(st + 2, (st + 2) % 3);
;             if (st < 14) asm volatile("s_waitcnt vmcnt(8)" ::: "memory");
;             else if (st == 14) asm volatile("s_waitcnt vmcnt(4)" ::: "memory");
;             else asm volatile("s_waitcnt vmcnt(0)" ::: "memory");
;             if (q == 0) {
; #pragma unroll
;                 for (int r = 0; r < 4; ++r) { accH[r] = 0; accL[r] = 0; } }
; #pragma unroll
;             for (int tp = 0; tp < 2; ++tp) {
;                 const v2i ao = TR4(ATL + (2 * q + tp) * 128 + 8 * s16), ah = TR4(ATL + 1024 + (2 * q + tp) * 128 + 8 * s16);
; #pragma unroll
;                 for (int r = 0; r < 4; ++r) {
;                     const v2i d = TR4(ldsb + BUF[st % 3] + 2048 * tp + roff[r]);
;                     accH[r] = __builtin_amdgcn_sdot8(d.x, ah.x, accH[r], false); accH[r] = __builtin_amdgcn_sdot8(d.y, ah.y, accH[r], false);
;                     accL[r] = __builtin_amdgcn_sdot8(d.x, ao.x, accL[r], false); accL[r] = __builtin_amdgcn_sdot8(d.y, ao.y, accL[r], false);
;                 }
;             }
;             asm volatile("s_waitcnt lgkmcnt(0)" ::: "memory");
;             if (q == 3) {
; #pragma unroll
;                 for (int r = 0; r < 4; ++r) STASH[256 * p + 16 * (grp + 4 * r) + pc] = f2bf(asc * (float)(2 * ((accH[r] << 4) + accL[r]) + sa));
;             }
;         }
;         CFENCE();
;         {
;             float4 v[4]; float ss = 0.f;
; #pragma unroll
;             for (int jq = 0; jq < 4; ++jq) { typedef unsigned u2v __attribute__((ext_vector_type(2))); const u2v pw = *(const LAS u2v*)(STASH + 4 * lane + 256 * jq); const uint2 hw = hv[jq];
;                 v[jq] = make_float4(__uint_as_float(hw.x << 16) + __uint_as_float(pw.x << 16), __uint_as_float(hw.x & 0xffff0000u) + __uint_as_float(pw.x & 0xffff0000u),
;                                     __uint_as_float(hw.y << 16) + __uint_as_float(pw.y << 16), __uint_as_float(hw.y & 0xffff0000u) + __uint_as_float(pw.y & 0xffff0000u));
;                 ss += v[jq].x * v[jq].x + v[jq].y * v[jq].y + v[jq].z * v[jq].z + v[jq].w * v[jq].w; }
;             ss = wave_sum(ss);
	v_dot8c_i32_i4_e32 v38, v130, v52
	v_dot8c_i32_i4_e32 v39, v130, v50
	v_dot8c_i32_i4_e32 v40, v132, v52
	v_dot8c_i32_i4_e32 v41, v132, v50
	v_dot8c_i32_i4_e32 v42, v134, v52
	v_dot8c_i32_i4_e32 v43, v134, v50
	v_dot8c_i32_i4_e32 v44, v136, v52
	v_dot8c_i32_i4_e32 v45, v136, v50
	v_dot8c_i32_i4_e32 v38, v131, v53
	v_dot8c_i32_i4_e32 v39, v131, v51
	v_dot8c_i32_i4_e32 v40, v133, v53
	v_dot8c_i32_i4_e32 v41, v133, v51
	v_dot8c_i32_i4_e32 v42, v135, v53
	v_dot8c_i32_i4_e32 v43, v135, v51
	v_dot8c_i32_i4_e32 v44, v137, v53
	v_dot8c_i32_i4_e32 v45, v137, v51
	s_waitcnt vmcnt(4)
	v_add_u32_e32 v54, s77, v59
	v_add_u32_e32 v55, s77, v60
	v_add_u32_e32 v56, s77, v61
	v_add_u32_e32 v57, s77, v62
	ds_read_b64_tr_b4 v[50:51], v160 offset:640
	ds_read_b64_tr_b4 v[52:53], v160 offset:1664
	ds_read_b64_tr_b4 v[130:131], v54
	ds_read_b64_tr_b4 v[132:133], v55
	ds_read_b64_tr_b4 v[134:135], v56
	ds_read_b64_tr_b4 v[136:137], v57
	s_waitcnt lgkmcnt(6)
	v_dot8c_i32_i4_e32 v38, v122, v48
	v_dot8c_i32_i4_e32 v39, v122, v46
	v_dot8c_i32_i4_e32 v40, v124, v48
	v_dot8c_i32_i4_e32 v41, v124, v46
	v_dot8c_i32_i4_e32 v42, v126, v48
	v_dot8c_i32_i4_e32 v43, v126, v46
	v_dot8c_i32_i4_e32 v44, v128, v48
	v_dot8c_i32_i4_e32 v45, v128, v46
	v_dot8c_i32_i4_e32 v38, v123, v49
	v_dot8c_i32_i4_e32 v39, v123, v47
	v_dot8c_i32_i4_e32 v40, v125, v49
	v_dot8c_i32_i4_e32 v41, v125, v47
	v_dot8c_i32_i4_e32 v42, v127, v49
	v_dot8c_i32_i4_e32 v43, v127, v47
	v_dot8c_i32_i4_e32 v44, v129, v49
	v_dot8c_i32_i4_e32 v45, v129, v47
	s_waitcnt vmcnt(2)
	v_add_u32_e32 v54, s78, v59
	v_add_u32_e32 v55, s78, v60
	v_add_u32_e32 v56, s78, v61
	v_add_u32_e32 v57, s78, v62
	ds_read_b64_tr_b4 v[46:47], v160 offset:768
	ds_read_b64_tr_b4 v[48:49], v160 offset:1792
	ds_read_b64_tr_b4 v[122:123], v54
	ds_read_b64_tr_b4 v[124:125], v55
	ds_read_b64_tr_b4 v[126:127], v56
	ds_read_b64_tr_b4 v[128:129], v57
	s_waitcnt lgkmcnt(6)
	v_dot8c_i32_i4_e32 v38, v130, v52
	v_dot8c_i32_i4_e32 v39, v130, v50
	v_dot8c_i32_i4_e32 v40, v132, v52
	v_dot8c_i32_i4_e32 v41, v132, v50
	v_dot8c_i32_i4_e32 v42, v134, v52
	v_dot8c_i32_i4_e32 v43, v134, v50
	v_dot8c_i32_i4_e32 v44, v136, v52
	v_dot8c_i32_i4_e32 v45, v136, v50
	v_dot8c_i32_i4_e32 v38, v131, v53
	v_dot8c_i32_i4_e32 v39, v131, v51
	v_dot8c_i32_i4_e32 v40, v133, v53
	v_dot8c_i32_i4_e32 v41, v133, v51
	v_dot8c_i32_i4_e32 v42, v135, v53
	v_dot8c_i32_i4_e32 v43, v135, v51
	v_dot8c_i32_i4_e32 v44, v137, v53
	v_dot8c_i32_i4_e32 v45, v137, v51
	s_waitcnt vmcnt(0)
	v_add_u32_e32 v54, s79, v59
	v_add_u32_e32 v55, s79, v60
	v_add_u32_e32 v56, s79, v61
	v_add_u32_e32 v57, s79, v62
	ds_read_b64_tr_b4 v[50:51], v160 offset:896
	ds_read_b64_tr_b4 v[52:53], v160 offset:1920
	ds_read_b64_tr_b4 v[130:131], v54
	ds_read_b64_tr_b4 v[132:133], v55
	ds_read_b64_tr_b4 v[134:135], v56
	ds_read_b64_tr_b4 v[136:137], v57
	s_waitcnt lgkmcnt(6)
	v_dot8c_i32_i4_e32 v38, v122, v48
	v_dot8c_i32_i4_e32 v39, v122, v46
	v_dot8c_i32_i4_e32 v40, v124, v48
	v_dot8c_i32_i4_e32 v41, v124, v46
	v_dot8c_i32_i4_e32 v42, v126, v48
	v_dot8c_i32_i4_e32 v43, v126, v46
	v_dot8c_i32_i4_e32 v44, v128, v48
	v_dot8c_i32_i4_e32 v45, v128, v46
	v_dot8c_i32_i4_e32 v38, v123, v49
	v_dot8c_i32_i4_e32 v39, v123, v47
	v_dot8c_i32_i4_e32 v40, v125, v49
	v_dot8c_i32_i4_e32 v41, v125, v47
	v_dot8c_i32_i4_e32 v42, v127, v49
	v_dot8c_i32_i4_e32 v43, v127, v47
	v_dot8c_i32_i4_e32 v44, v129, v49
	v_dot8c_i32_i4_e32 v45, v129, v47
	s_waitcnt lgkmcnt(0)
	v_dot8c_i32_i4_e32 v38, v130, v52
	v_dot8c_i32_i4_e32 v39, v130, v50
	v_dot8c_i32_i4_e32 v40, v132, v52
	v_dot8c_i32_i4_e32 v41, v132, v50
	v_dot8c_i32_i4_e32 v42, v134, v52
	v_dot8c_i32_i4_e32 v43, v134, v50
	v_dot8c_i32_i4_e32 v44, v136, v52
	v_dot8c_i32_i4_e32 v45, v136, v50
	v_dot8c_i32_i4_e32 v38, v131, v53
	v_dot8c_i32_i4_e32 v39, v131, v51
	v_dot8c_i32_i4_e32 v40, v133, v53
	v_dot8c_i32_i4_e32 v41, v133, v51
	v_dot8c_i32_i4_e32 v42, v135, v53
	v_dot8c_i32_i4_e32 v43, v135, v51
	v_dot8c_i32_i4_e32 v44, v137, v53
	v_dot8c_i32_i4_e32 v45, v137, v51
	s_nop 3
	s_waitcnt lgkmcnt(15)
	v_lshlrev_b32_e32 v38, 5, v38
	v_lshlrev_b32_e32 v39, 1, v39
	v_add3_u32 v38, v39, v229, v38
	v_cvt_f32_i32_e32 v38, v38
	v_mul_f32_e32 v38, v228, v38
	v_lshlrev_b32_e32 v40, 5, v40
	v_lshlrev_b32_e32 v41, 1, v41
	v_add3_u32 v40, v41, v229, v40
	v_cvt_f32_i32_e32 v40, v40
	v_mul_f32_e32 v40, v228, v40
	v_lshlrev_b32_e32 v42, 5, v42
	v_lshlrev_b32_e32 v43, 1, v43
	v_add3_u32 v42, v43, v229, v42
	v_cvt_f32_i32_e32 v42, v42
	v_mul_f32_e32 v42, v228, v42
	v_lshlrev_b32_e32 v44, 5, v44
	v_lshlrev_b32_e32 v45, 1, v45
	v_add3_u32 v44, v45, v229, v44
	v_cvt_f32_i32_e32 v44, v44
	v_mul_f32_e32 v44, v228, v44
	v_cvt_pk_bf16_f32 v192, v38, v40
	v_cvt_pk_bf16_f32 v193, v42, v44
	ds_read_b128 v[252:255], v156 offset:1024
	s_add_i32 s44, s40, 40
	s_ashr_i32 s45, s44, 31
	s_lshl_b64 s[44:45], s[44:45], 12
	v_lshl_add_u64 v[80:81], v[36:37], 0, s[44:45]
	s_waitcnt lgkmcnt(0)
	v_mul_f32_e32 v248, v248, v252
	v_mul_f32_e32 v249, v249, v253
	v_mul_f32_e32 v250, v250, v254
	v_mul_f32_e32 v251, v251, v255
	global_store_dwordx4 v[80:81], v[248:251], off offset:3072 nt
	ds_write_b16 v65, v178
	ds_write_b16_d16_hi v65, v178 offset:128
	ds_write_b16 v65, v179 offset:256
	ds_write_b16_d16_hi v65, v179 offset:384
	ds_write_b16 v65, v180 offset:512
	ds_write_b16_d16_hi v65, v180 offset:640
	ds_write_b16 v65, v181 offset:768
	ds_write_b16_d16_hi v65, v181 offset:896
	ds_write_b16 v65, v182 offset:1024
	ds_write_b16_d16_hi v65, v182 offset:1152
	ds_write_b16 v65, v183 offset:1280
	ds_write_b16_d16_hi v65, v183 offset:1408
	ds_write_b16 v65, v184 offset:1536
	ds_write_b16_d16_hi v65, v184 offset:1664
	ds_write_b16 v65, v185 offset:1792
	ds_write_b16_d16_hi v65, v185 offset:1920
	ds_read_b64 v[202:203], v154
	ds_read_b64 v[204:205], v154 offset:512
	ds_read_b64 v[206:207], v154 offset:1024
	ds_read_b64 v[208:209], v154 offset:1536
	s_waitcnt vmcnt(11) lgkmcnt(0)
; #define LAS __attribute__((address_space(3)))
; __device__ __forceinline__ void peer_v_tokens(int j, const LAS unsigned short* EL, const LAS unsigned char* AL  , const LAS float* ASC  , const LAS int* SAL  , ...
;     ...
;         {
;             float4 v[4]; float ss = 0.f;
; #pragma unroll
;             for (int jq = 0; jq < 4; ++jq) { typedef unsigned u2v __attribute__((ext_vector_type(2))); const u2v pw = *(const LAS u2v*)(STASH + 4 * lane + 256 * jq); const uint2 hw = hv[jq];
;                 v[jq] = make_float4(__uint_as_float(hw.x << 16) + __uint_as_float(pw.x << 16), __uint_as_float(hw.x & 0xffff0000u) + __uint_as_float(pw.x & 0xffff0000u),
;                                     __uint_as_float(hw.y << 16) + __uint_as_float(pw.y << 16), __uint_as_float(hw.y & 0xffff0000u) + __uint_as_float(pw.y & 0xffff0000u));
;                 ss += v[jq].x * v[jq].x + v[jq].y * v[jq].y + v[jq].z * v[jq].z + v[jq].w * v[jq].w; }
;             ss = wave_sum(ss);
;             const float r3 = rsqrtf(ss * (1.f / D) + EPS);
;             float4* op = (float4*)(outp + (size_t)t * D) + lane;
; #pragma unroll
;             for (int jq = 0; jq < 4; ++jq) { typedef float f4v __attribute__((ext_vector_type(4))); f4v o4; o4.x = v[jq].x * r3 * gv[jq].x; o4.y = v[jq].y * r3 * gv[jq].y; o4.z = v[jq].z * r3 * gv[jq].z; o4.w = v[jq].w * r3 * gv[jq].w;
;                 __builtin_nontemporal_store(o4, (f4v*)op + 64 * jq); }
	v_lshlrev_b32_e32 v210, 16, v194
	v_and_b32_e32 v211, 0xffff0000, v194
	v_lshlrev_b32_e32 v142, 16, v202
	v_and_b32_e32 v143, 0xffff0000, v202
	v_add_f32_e32 v210, v210, v142
	v_add_f32_e32 v211, v211, v143
	v_lshlrev_b32_e32 v212, 16, v195
	v_and_b32_e32 v213, 0xffff0000, v195
	v_lshlrev_b32_e32 v142, 16, v203
	v_and_b32_e32 v143, 0xffff0000, v203
	v_add_f32_e32 v212, v212, v142
	v_add_f32_e32 v213, v213, v143
	v_lshlrev_b32_e32 v214, 16, v196
	v_and_b32_e32 v215, 0xffff0000, v196
	v_lshlrev_b32_e32 v142, 16, v204
	v_and_b32_e32 v143, 0xffff0000, v204
	v_add_f32_e32 v214, v214, v142
	v_add_f32_e32 v215, v215, v143
	v_lshlrev_b32_e32 v216, 16, v197
	v_and_b32_e32 v217, 0xffff0000, v197
	v_lshlrev_b32_e32 v142, 16, v205
	v_and_b32_e32 v143, 0xffff0000, v205
	v_add_f32_e32 v216, v216, v142
	v_add_f32_e32 v217, v217, v143
	v_lshlrev_b32_e32 v218, 16, v198
	v_and_b32_e32 v219, 0xffff0000, v198
	v_lshlrev_b32_e32 v142, 16, v206
	v_and_b32_e32 v143, 0xffff0000, v206
	v_add_f32_e32 v218, v218, v142
	v_add_f32_e32 v219, v219, v143
	v_lshlrev_b32_e32 v220, 16, v199
	v_and_b32_e32 v221, 0xffff0000, v199
	v_lshlrev_b32_e32 v142, 16, v207
	v_and_b32_e32 v143, 0xffff0000, v207
	v_add_f32_e32 v220, v220, v142
	v_add_f32_e32 v221, v221, v143
	v_lshlrev_b32_e32 v222, 16, v200
	v_and_b32_e32 v223, 0xffff0000, v200
	v_lshlrev_b32_e32 v142, 16, v208
	v_and_b32_e32 v143, 0xffff0000, v208
	v_add_f32_e32 v222, v222, v142
	v_add_f32_e32 v223, v223, v143
	v_lshlrev_b32_e32 v224, 16, v201
	v_and_b32_e32 v225, 0xffff0000, v201
	v_lshlrev_b32_e32 v142, 16, v209
	v_and_b32_e32 v143, 0xffff0000, v209
	v_add_f32_e32 v224, v224, v142
	v_add_f32_e32 v225, v225, v143
	v_mov_b32_e32 v144, 0
	v_mul_f32_e32 v145, v210, v210
	v_fmac_f32_e32 v145, v211, v211
	v_fmac_f32_e32 v145, v212, v212
	v_fmac_f32_e32 v145, v213, v213
	v_add_f32_e32 v144, v144, v145
	v_mul_f32_e32 v145, v214, v214
	v_fmac_f32_e32 v145, v215, v215
	v_fmac_f32_e32 v145, v216, v216
	v_fmac_f32_e32 v145, v217, v217
	v_add_f32_e32 v144, v144, v145
	v_mul_f32_e32 v145, v218, v218
	v_fmac_f32_e32 v145, v219, v219
	v_fmac_f32_e32 v145, v220, v220
	v_fmac_f32_e32 v145, v221, v221
	v_add_f32_e32 v144, v144, v145
	v_mul_f32_e32 v145, v222, v222
	v_fmac_f32_e32 v145, v223, v223
	v_fmac_f32_e32 v145, v224, v224
	v_fmac_f32_e32 v145, v225, v225
	v_add_f32_e32 v144, v144, v145
	s_nop 1
	v_add_f32_dpp v144, v144, v144 quad_perm:[1,0,3,2] row_mask:0xf bank_mask:0xf bound_ctrl:1
	s_nop 1
	v_add_f32_dpp v144, v144, v144 quad_perm:[2,3,0,1] row_mask:0xf bank_mask:0xf bound_ctrl:1
	s_nop 1
	v_add_f32_dpp v144, v144, v144 row_half_mirror row_mask:0xf bank_mask:0xf bound_ctrl:1
	s_nop 1
	v_add_f32_dpp v144, v144, v144 row_mirror row_mask:0xf bank_mask:0xf bound_ctrl:1
	s_nop 1
	v_readlane_b32 s10, v144, 0
	v_readlane_b32 s11, v144, 16
	v_readlane_b32 s14, v144, 32
	v_readlane_b32 s15, v144, 48
	s_nop 3
	v_mov_b32_e32 v144, s11
	v_mov_b32_e32 v145, s15
	v_add_f32_e32 v144, s10, v144
	v_add_f32_e32 v145, s14, v145
	v_add_f32_e32 v144, v144, v145
	v_fmamk_f32 v144, v144, 0x3a800000, v111
	v_rsq_f32_e32 v144, v144
	s_nop 0
	v_mul_f32_e32 v210, v210, v144
	v_mul_f32_e32 v211, v211, v144
	v_mul_f32_e32 v212, v212, v144
	v_mul_f32_e32 v213, v213, v144
	v_mul_f32_e32 v214, v214, v144
	v_mul_f32_e32 v215, v215, v144
	v_mul_f32_e32 v216, v216, v144
	v_mul_f32_e32 v217, v217, v144
	v_mul_f32_e32 v218, v218, v144
	v_mul_f32_e32 v219, v219, v144
	v_mul_f32_e32 v220, v220, v144
	v_mul_f32_e32 v221, v221, v144
	v_mul_f32_e32 v222, v222, v144
	v_mul_f32_e32 v223, v223, v144
	v_mul_f32_e32 v224, v224, v144
	v_mul_f32_e32 v225, v225, v144
	ds_read_b128 v[252:255], v155
	s_add_i32 s44, s40, 48
	s_ashr_i32 s45, s44, 31
	s_lshl_b64 s[44:45], s[44:45], 12
	v_lshl_add_u64 v[80:81], v[36:37], 0, s[44:45]
	s_waitcnt lgkmcnt(0)
	v_mul_f32_e32 v210, v210, v252
	v_mul_f32_e32 v211, v211, v253
	v_mul_f32_e32 v212, v212, v254
	v_mul_f32_e32 v213, v213, v255
	global_store_dwordx4 v[80:81], v[210:213], off nt
	ds_read_b128 v[252:255], v155 offset:1024
	s_add_i32 s44, s40, 48
	s_ashr_i32 s45, s44, 31
	s_lshl_b64 s[44:45], s[44:45], 12
	v_lshl_add_u64 v[80:81], v[36:37], 0, s[44:45]
	s_waitcnt lgkmcnt(0)
	v_mul_f32_e32 v214, v214, v252
	v_mul_f32_e32 v215, v215, v253
	v_mul_f32_e32 v216, v216, v254
	v_mul_f32_e32 v217, v217, v255
	global_store_dwordx4 v[80:81], v[214:217], off offset:1024 nt
	ds_read_b128 v[252:255], v156
	s_add_i32 s44, s40, 48
	s_ashr_i32 s45, s44, 31
	s_lshl_b64 s[44:45], s[44:45], 12
	v_lshl_add_u64 v[80:81], v[36:37], 0, s[44:45]
	s_waitcnt lgkmcnt(0)
	v_mul_f32_e32 v218, v218, v252
	v_mul_f32_e32 v219, v219, v253
	v_mul_f32_e32 v220, v220, v254
	v_mul_f32_e32 v221, v221, v255
	global_store_dwordx4 v[80:81], v[218:221], off offset:2048 nt
	ds_read_b128 v[252:255], v156 offset:1024
	s_add_i32 s44, s40, 48
	s_ashr_i32 s45, s44, 31
	s_lshl_b64 s[44:45], s[44:45], 12
	v_lshl_add_u64 v[80:81], v[36:37], 0, s[44:45]
	s_waitcnt lgkmcnt(0)
	v_mul_f32_e32 v222, v222, v252
	v_mul_f32_e32 v223, v223, v253
	v_mul_f32_e32 v224, v224, v254
	v_mul_f32_e32 v225, v225, v255
	global_store_dwordx4 v[80:81], v[222:225], off offset:3072 nt
	ds_write_b16 v65, v186
	ds_write_b16_d16_hi v65, v186 offset:128
	ds_write_b16 v65, v187 offset:256
	ds_write_b16_d16_hi v65, v187 offset:384
	ds_write_b16 v65, v188 offset:512
	ds_write_b16_d16_hi v65, v188 offset:640
	ds_write_b16 v65, v189 offset:768
	ds_write_b16_d16_hi v65, v189 offset:896
	ds_write_b16 v65, v190 offset:1024
	ds_write_b16_d16_hi v65, v190 offset:1152
	ds_write_b16 v65, v191 offset:1280
	ds_write_b16_d16_hi v65, v191 offset:1408
	ds_write_b16 v65, v192 offset:1536
	ds_write_b16_d16_hi v65, v192 offset:1664
	ds_write_b16 v65, v193 offset:1792
	ds_write_b16_d16_hi v65, v193 offset:1920
	ds_read_b64 v[202:203], v154
	ds_read_b64 v[204:205], v154 offset:512
	ds_read_b64 v[206:207], v154 offset:1024
	ds_read_b64 v[208:209], v154 offset:1536
	s_waitcnt vmcnt(11) lgkmcnt(0)
; #define LAS __attribute__((address_space(3)))
; __device__ __forceinline__ void peer_v_tokens(int j, const LAS unsigned short* EL, const LAS unsigned char* AL  , const LAS float* ASC  , const LAS int* SAL  , ...
;     ...
;         {
;             float4 v[4]; float ss = 0.f;
; #pragma unroll
;             for (int jq = 0; jq < 4; ++jq) { typedef unsigned u2v __attribute__((ext_vector_type(2))); const u2v pw = *(const LAS u2v*)(STASH + 4 * lane + 256 * jq); const uint2 hw = hv[jq];
;                 v[jq] = make_float4(__uint_as_float(hw.x << 16) + __uint_as_float(pw.x << 16), __uint_as_float(hw.x & 0xffff0000u) + __uint_as_float(pw.x & 0xffff0000u),
;                                     __uint_as_float(hw.y << 16) + __uint_as_float(pw.y << 16), __uint_as_float(hw.y & 0xffff0000u) + __uint_as_float(pw.y & 0xffff0000u));
;                 ss += v[jq].x * v[jq].x + v[jq].y * v[jq].y + v[jq].z * v[jq].z + v[jq].w * v[jq].w; }
;             ss = wave_sum(ss);
;             const float r3 = rsqrtf(ss * (1.f / D) + EPS);
;             float4* op = (float4*)(outp + (size_t)t * D) + lane;
; #pragma unroll
;             for (int jq = 0; jq < 4; ++jq) { typedef float f4v __attribute__((ext_vector_type(4))); f4v o4; o4.x = v[jq].x * r3 * gv[jq].x; o4.y = v[jq].y * r3 * gv[jq].y; o4.z = v[jq].z * r3 * gv[jq].z; o4.w = v[jq].w * r3 * gv[jq].w;
;                 __builtin_nontemporal_store(o4, (f4v*)op + 64 * jq); }
; __global__ void __launch_bounds__(NTHR, 2) k_main(Args a) {
;     ...
;         for (int j = bid; j < NCHUNK; j += nb) {
	v_lshlrev_b32_e32 v236, 16, v18
	v_and_b32_e32 v237, 0xffff0000, v18
	v_lshlrev_b32_e32 v142, 16, v202
	v_and_b32_e32 v143, 0xffff0000, v202
	v_add_f32_e32 v236, v236, v142
	v_add_f32_e32 v237, v237, v143
	v_lshlrev_b32_e32 v238, 16, v19
	v_and_b32_e32 v239, 0xffff0000, v19
	v_lshlrev_b32_e32 v142, 16, v203
	v_and_b32_e32 v143, 0xffff0000, v203
	v_add_f32_e32 v238, v238, v142
	v_add_f32_e32 v239, v239, v143
	v_lshlrev_b32_e32 v240, 16, v20
	v_and_b32_e32 v241, 0xffff0000, v20
	v_lshlrev_b32_e32 v142, 16, v204
	v_and_b32_e32 v143, 0xffff0000, v204
	v_add_f32_e32 v240, v240, v142
	v_add_f32_e32 v241, v241, v143
	v_lshlrev_b32_e32 v242, 16, v21
	v_and_b32_e32 v243, 0xffff0000, v21
	v_lshlrev_b32_e32 v142, 16, v205
	v_and_b32_e32 v143, 0xffff0000, v205
	v_add_f32_e32 v242, v242, v142
	v_add_f32_e32 v243, v243, v143
	v_lshlrev_b32_e32 v244, 16, v22
	v_and_b32_e32 v245, 0xffff0000, v22
	v_lshlrev_b32_e32 v142, 16, v206
	v_and_b32_e32 v143, 0xffff0000, v206
	v_add_f32_e32 v244, v244, v142
	v_add_f32_e32 v245, v245, v143
	v_lshlrev_b32_e32 v246, 16, v23
	v_and_b32_e32 v247, 0xffff0000, v23
	v_lshlrev_b32_e32 v142, 16, v207
	v_and_b32_e32 v143, 0xffff0000, v207
	v_add_f32_e32 v246, v246, v142
	v_add_f32_e32 v247, v247, v143
	v_lshlrev_b32_e32 v248, 16, v24
	v_and_b32_e32 v249, 0xffff0000, v24
	v_lshlrev_b32_e32 v142, 16, v208
	v_and_b32_e32 v143, 0xffff0000, v208
	v_add_f32_e32 v248, v248, v142
	v_add_f32_e32 v249, v249, v143
	v_lshlrev_b32_e32 v250, 16, v25
	v_and_b32_e32 v251, 0xffff0000, v25
	v_lshlrev_b32_e32 v142, 16, v209
	v_and_b32_e32 v143, 0xffff0000, v209
	v_add_f32_e32 v250, v250, v142
	v_add_f32_e32 v251, v251, v143
	v_mov_b32_e32 v144, 0
	v_mul_f32_e32 v145, v236, v236
	v_fmac_f32_e32 v145, v237, v237
	v_fmac_f32_e32 v145, v238, v238
	v_fmac_f32_e32 v145, v239, v239
	v_add_f32_e32 v144, v144, v145
	v_mul_f32_e32 v145, v240, v240
	v_fmac_f32_e32 v145, v241, v241
	v_fmac_f32_e32 v145, v242, v242
	v_fmac_f32_e32 v145, v243, v243
	v_add_f32_e32 v144, v144, v145
	v_mul_f32_e32 v145, v244, v244
	v_fmac_f32_e32 v145, v245, v245
	v_fmac_f32_e32 v145, v246, v246
	v_fmac_f32_e32 v145, v247, v247
	v_add_f32_e32 v144, v144, v145
	v_mul_f32_e32 v145, v248, v248
	v_fmac_f32_e32 v145, v249, v249
	v_fmac_f32_e32 v145, v250, v250
	v_fmac_f32_e32 v145, v251, v251
	v_add_f32_e32 v144, v144, v145
	s_nop 1
	v_add_f32_dpp v144, v144, v144 quad_perm:[1,0,3,2] row_mask:0xf bank_mask:0xf bound_ctrl:1
	s_nop 1
	v_add_f32_dpp v144, v144, v144 quad_perm:[2,3,0,1] row_mask:0xf bank_mask:0xf bound_ctrl:1
	s_nop 1
	v_add_f32_dpp v144, v144, v144 row_half_mirror row_mask:0xf bank_mask:0xf bound_ctrl:1
	s_nop 1
	v_add_f32_dpp v144, v144, v144 row_mirror row_mask:0xf bank_mask:0xf bound_ctrl:1
	s_nop 1
	v_readlane_b32 s10, v144, 0
	v_readlane_b32 s11, v144, 16
	v_readlane_b32 s14, v144, 32
	v_readlane_b32 s15, v144, 48
	s_nop 3
	v_mov_b32_e32 v144, s11
	v_mov_b32_e32 v145, s15
	v_add_f32_e32 v144, s10, v144
	v_add_f32_e32 v145, s14, v145
	v_add_f32_e32 v144, v144, v145
	v_fmamk_f32 v144, v144, 0x3a800000, v111
	v_rsq_f32_e32 v144, v144
	s_nop 0
	v_mul_f32_e32 v236, v236, v144
	v_mul_f32_e32 v237, v237, v144
	v_mul_f32_e32 v238, v238, v144
	v_mul_f32_e32 v239, v239, v144
	v_mul_f32_e32 v240, v240, v144
	v_mul_f32_e32 v241, v241, v144
	v_mul_f32_e32 v242, v242, v144
	v_mul_f32_e32 v243, v243, v144
	v_mul_f32_e32 v244, v244, v144
	v_mul_f32_e32 v245, v245, v144
	v_mul_f32_e32 v246, v246, v144
	v_mul_f32_e32 v247, v247, v144
	v_mul_f32_e32 v248, v248, v144
	v_mul_f32_e32 v249, v249, v144
	v_mul_f32_e32 v250, v250, v144
	v_mul_f32_e32 v251, v251, v144
	ds_read_b128 v[252:255], v155
	s_add_i32 s44, s40, 56
	s_ashr_i32 s45, s44, 31
	s_lshl_b64 s[44:45], s[44:45], 12
	v_lshl_add_u64 v[80:81], v[36:37], 0, s[44:45]
	s_waitcnt lgkmcnt(0)
	v_mul_f32_e32 v236, v236, v252
	v_mul_f32_e32 v237, v237, v253
	v_mul_f32_e32 v238, v238, v254
	v_mul_f32_e32 v239, v239, v255
	global_store_dwordx4 v[80:81], v[236:239], off nt
	ds_read_b128 v[252:255], v155 offset:1024
	s_add_i32 s44, s40, 56
	s_ashr_i32 s45, s44, 31
	s_lshl_b64 s[44:45], s[44:45], 12
	v_lshl_add_u64 v[80:81], v[36:37], 0, s[44:45]
	s_waitcnt lgkmcnt(0)
	v_mul_f32_e32 v240, v240, v252
	v_mul_f32_e32 v241, v241, v253
	v_mul_f32_e32 v242, v242, v254
	v_mul_f32_e32 v243, v243, v255
	global_store_dwordx4 v[80:81], v[240:243], off offset:1024 nt
	ds_read_b128 v[252:255], v156
	s_add_i32 s44, s40, 56
	s_ashr_i32 s45, s44, 31
	s_lshl_b64 s[44:45], s[44:45], 12
	v_lshl_add_u64 v[80:81], v[36:37], 0, s[44:45]
	s_waitcnt lgkmcnt(0)
	v_mul_f32_e32 v244, v244, v252
	v_mul_f32_e32 v245, v245, v253
	v_mul_f32_e32 v246, v246, v254
	v_mul_f32_e32 v247, v247, v255
	global_store_dwordx4 v[80:81], v[244:247], off offset:2048 nt
	ds_read_b128 v[252:255], v156 offset:1024
	s_add_i32 s44, s40, 56
	s_ashr_i32 s45, s44, 31
	s_lshl_b64 s[44:45], s[44:45], 12
	v_lshl_add_u64 v[80:81], v[36:37], 0, s[44:45]
	s_waitcnt lgkmcnt(0)
	v_mul_f32_e32 v248, v248, v252
	v_mul_f32_e32 v249, v249, v253
	v_mul_f32_e32 v250, v250, v254
	v_mul_f32_e32 v251, v251, v255
	global_store_dwordx4 v[80:81], v[248:251], off offset:3072 nt
	s_add_i32 s2, s2, s33
	s_add_i32 s40, s40, s63
	s_add_i32 s73, s73, s74
	s_cmpk_lt_i32 s2, 0x100
	s_cbranch_scc1 .LBB0_648
